# v25 + removed the redundant s_waitcnt lgkmcnt(0) between each phase barrier and its first MFMA in the GEMM K-loops
# speedup vs baseline: 1.0009x; 1.0009x over previous
; #define PG8_STAGE(bufoff, gbase, voff) do { _Pragma("unroll") for (int _i = 0; _i < 2; ++_i) \
;         __builtin_amdgcn_global_load_lds((const unsigned*)((const char*)(gbase) + (voff)[_i]), (LAS unsigned*)(lds + (bufoff) + ldsw + _i * 8192), 16, 0, 0); } while (0)
; #define PG8_LDA(dst, b, h) do { _Pragma("unroll") for (int m = 0; m < 4; ++m) _Pragma("unroll") for (int k = 0; k < 2; ++k) dst[m][k] = *(const LAS bf16x8*)(lds + PG8_SA(b, h) + aoff + m * 2048 + k * 1024); } while (0)
; #define PG8_LDB(dst, b, h) do { _Pragma("unroll") for (int n = 0; n < 2; ++n) _Pragma("unroll") for (int k = 0; k < 2; ++k) dst[n][k] = *(const LAS bf16x8*)(lds + PG8_SB(b, h) + boff + n * 2048 + k * 1024); } while (0)
; #define PG8_MMA(ai, bj, At, Bt) do { __builtin_amdgcn_s_setprio(1); _Pragma("unroll") for (int m = 0; m < 4; ++m) _Pragma("unroll") for (int n = 0; n < 2; ++n) _Pragma("unroll") for (int k = 0; k < 2; ++k) \
;         acc[ai][bj][m][n] = __builtin_amdgcn_mfma_f32_16x16x32_bf16(Bt[n][k], At[m][k], acc[ai][bj][m][n], 0, 0, 0); __builtin_amdgcn_s_setprio(0); } while (0)
; #define PG8_WAIT_V(n) asm volatile("s_waitcnt vmcnt(" #n ")" ::: "memory")
; #define PG8_WAIT_L(n) asm volatile("s_waitcnt lgkmcnt(" #n ")" ::: "memory")
; #define PG8_BAR __builtin_amdgcn_s_barrier()
; #define PG8_SCHED __builtin_amdgcn_sched_barrier(0)
; template <class Epi, class Sched, bool ALIGN_EPI = false, bool SP2 = false>
; __device__ __forceinline__ void gemm_phase(LAS unsigned char* lds, const Gemm g, const Sched& S, const Epi& E) {
;     ...
;             if constexpr (SP2) {
;             PG8_LDB(B0, 0, 0); PG8_LDB(B1, 0, 1); PG8_SCHED; PG8_LDA(At, 0, 0); PG8_STAGE(PG8_SA(1, 1), a1 + hstep, voffA);
;             PG8_WAIT_V(8); PG8_WAIT_L(0); PG8_BAR; PG8_MMA(0, 0, At, B0); PG8_MMA(0, 1, At, B1); PG8_BAR; PG8_SCHED;
;             PG8_LDA(At, 0, 1); PG8_STAGE(PG8_SB(0, 0), b2, voffB); PG8_STAGE(PG8_SB(0, 1), b2 + hstepB, voffB); PG8_STAGE(PG8_SA(0, 0), a2, voffA);
;             PG8_WAIT_V(8); PG8_WAIT_L(0); PG8_BAR; PG8_MMA(1, 0, At, B0); PG8_MMA(1, 1, At, B1); PG8_BAR; PG8_SCHED;
.Lprio_188:
	ds_read_b128 v[66:69], v174
	ds_read_b128 v[70:73], v174 offset:1024
	ds_read_b128 v[74:77], v174 offset:2048
	ds_read_b128 v[78:81], v174 offset:3072
	ds_read_b128 v[162:165], v175
	ds_read_b128 v[182:185], v175 offset:1024
	ds_read_b128 v[186:189], v175 offset:2048
	ds_read_b128 v[190:193], v175 offset:3072
	s_add_u32 s20, s16, 0xfff80080
	s_addc_u32 s21, s17, -1
	s_cmp_eq_u32 s19, 28
	s_cselect_b32 s53, s3, s21
	s_cselect_b32 s52, s12, s20
	s_cselect_b32 s51, s13, s18
	s_cselect_b32 s50, s14, s15
	v_lshl_add_u64 v[166:167], s[16:17], 0, v[154:155]
	s_add_i32 m0, s33, 0xc000
	ds_read_b128 v[194:197], v176
	ds_read_b128 v[198:201], v176 offset:1024
	ds_read_b128 v[202:205], v176 offset:2048
	ds_read_b128 v[206:209], v176 offset:3072
	ds_read_b128 v[210:213], v176 offset:4096
	ds_read_b128 v[214:217], v176 offset:5120
	ds_read_b128 v[218:221], v176 offset:6144
	ds_read_b128 v[222:225], v176 offset:7168
	global_load_lds_dwordx4 v[166:167], off
	v_lshl_add_u64 v[166:167], s[16:17], 0, v[156:157]
	s_add_i32 m0, s33, 0xe000
	s_nop 0
	global_load_lds_dwordx4 v[166:167], off
	s_waitcnt lgkmcnt(0)
	s_barrier
	v_mfma_f32_16x16x32_bf16 v[142:145], v[66:69], v[194:197], 0
	v_mfma_f32_16x16x32_bf16 v[138:141], v[74:77], v[194:197], 0
	v_mfma_f32_16x16x32_bf16 v[126:129], v[66:69], v[202:205], 0
	v_mfma_f32_16x16x32_bf16 v[122:125], v[74:77], v[202:205], 0
	v_mfma_f32_16x16x32_bf16 v[110:113], v[66:69], v[210:213], 0
	v_mfma_f32_16x16x32_bf16 v[106:109], v[74:77], v[210:213], 0
	v_mfma_f32_16x16x32_bf16 v[94:97], v[66:69], v[218:221], 0
	v_mfma_f32_16x16x32_bf16 v[90:93], v[74:77], v[218:221], 0
	v_mfma_f32_16x16x32_bf16 v[142:145], v[70:73], v[198:201], v[142:145]
	v_mfma_f32_16x16x32_bf16 v[138:141], v[78:81], v[198:201], v[138:141]
	v_mfma_f32_16x16x32_bf16 v[126:129], v[70:73], v[206:209], v[126:129]
	v_mfma_f32_16x16x32_bf16 v[122:125], v[78:81], v[206:209], v[122:125]
	v_mfma_f32_16x16x32_bf16 v[110:113], v[70:73], v[214:217], v[110:113]
	v_mfma_f32_16x16x32_bf16 v[106:109], v[78:81], v[214:217], v[106:109]
	v_mfma_f32_16x16x32_bf16 v[94:97], v[70:73], v[222:225], v[94:97]
	v_mfma_f32_16x16x32_bf16 v[90:93], v[78:81], v[222:225], v[90:93]
	v_mfma_f32_16x16x32_bf16 v[134:137], v[162:165], v[194:197], 0
	v_mfma_f32_16x16x32_bf16 v[130:133], v[186:189], v[194:197], 0
	v_mfma_f32_16x16x32_bf16 v[118:121], v[162:165], v[202:205], 0
	v_mfma_f32_16x16x32_bf16 v[114:117], v[186:189], v[202:205], 0
	v_mfma_f32_16x16x32_bf16 v[102:105], v[162:165], v[210:213], 0
	v_mfma_f32_16x16x32_bf16 v[98:101], v[186:189], v[210:213], 0
	v_mfma_f32_16x16x32_bf16 v[86:89], v[162:165], v[218:221], 0
	v_mfma_f32_16x16x32_bf16 v[82:85], v[186:189], v[218:221], 0
	v_mfma_f32_16x16x32_bf16 v[134:137], v[182:185], v[198:201], v[134:137]
	v_mfma_f32_16x16x32_bf16 v[130:133], v[190:193], v[198:201], v[130:133]
	v_mfma_f32_16x16x32_bf16 v[118:121], v[182:185], v[206:209], v[118:121]
	v_mfma_f32_16x16x32_bf16 v[114:117], v[190:193], v[206:209], v[114:117]
	v_mfma_f32_16x16x32_bf16 v[102:105], v[182:185], v[214:217], v[102:105]
	v_mfma_f32_16x16x32_bf16 v[98:101], v[190:193], v[214:217], v[98:101]
	v_mfma_f32_16x16x32_bf16 v[86:89], v[182:185], v[222:225], v[86:89]
	v_mfma_f32_16x16x32_bf16 v[82:85], v[190:193], v[222:225], v[82:85]
	s_barrier
	s_add_i32 s20, s57, s27
	v_lshl_add_u64 v[166:167], s[50:51], 0, v[150:151]
	s_mov_b32 m0, s20
	ds_read_b128 v[194:197], v176 offset:16384
	ds_read_b128 v[198:201], v176 offset:17408
	ds_read_b128 v[202:205], v176 offset:18432
	ds_read_b128 v[206:209], v176 offset:19456
	ds_read_b128 v[210:213], v176 offset:20480
	ds_read_b128 v[214:217], v176 offset:21504
	ds_read_b128 v[218:221], v176 offset:22528
	ds_read_b128 v[222:225], v176 offset:23552
	global_load_lds_dwordx4 v[166:167], off
	s_add_i32 m0, s20, 0x2000
	s_add_u32 s20, s50, 0x80000
	v_lshl_add_u64 v[226:227], s[50:51], 0, v[146:147]
	s_addc_u32 s21, s51, 0
	s_add_i32 s22, s58, s27
	global_load_lds_dwordx4 v[226:227], off
	v_lshl_add_u64 v[228:229], s[20:21], 0, v[150:151]
	s_mov_b32 m0, s22
	v_lshl_add_u64 v[230:231], s[52:53], 0, v[148:149]
	global_load_lds_dwordx4 v[228:229], off
	v_lshl_add_u64 v[228:229], s[20:21], 0, v[146:147]
	s_add_i32 m0, s22, 0x2000
	s_nop 0
	global_load_lds_dwordx4 v[228:229], off
	v_lshl_add_u64 v[228:229], s[52:53], 0, v[152:153]
	s_mov_b32 m0, s33
	s_nop 0
	global_load_lds_dwordx4 v[228:229], off
	s_mov_b32 m0, s34
	s_nop 0
	global_load_lds_dwordx4 v[230:231], off
	s_waitcnt lgkmcnt(0)
	s_barrier
	v_mfma_f32_16x16x32_bf16 v[62:65], v[66:69], v[194:197], 0
	v_mfma_f32_16x16x32_bf16 v[58:61], v[74:77], v[194:197], 0
	v_mfma_f32_16x16x32_bf16 v[46:49], v[66:69], v[202:205], 0
	v_mfma_f32_16x16x32_bf16 v[42:45], v[74:77], v[202:205], 0
	v_mfma_f32_16x16x32_bf16 v[30:33], v[66:69], v[210:213], 0
	v_mfma_f32_16x16x32_bf16 v[26:29], v[74:77], v[210:213], 0
	v_mfma_f32_16x16x32_bf16 v[14:17], v[66:69], v[218:221], 0
	v_mfma_f32_16x16x32_bf16 v[10:13], v[74:77], v[218:221], 0
	v_mfma_f32_16x16x32_bf16 v[62:65], v[70:73], v[198:201], v[62:65]
	v_mfma_f32_16x16x32_bf16 v[58:61], v[78:81], v[198:201], v[58:61]
	v_mfma_f32_16x16x32_bf16 v[46:49], v[70:73], v[206:209], v[46:49]
	v_mfma_f32_16x16x32_bf16 v[42:45], v[78:81], v[206:209], v[42:45]
	v_mfma_f32_16x16x32_bf16 v[30:33], v[70:73], v[214:217], v[30:33]
	v_mfma_f32_16x16x32_bf16 v[26:29], v[78:81], v[214:217], v[26:29]
	v_mfma_f32_16x16x32_bf16 v[14:17], v[70:73], v[222:225], v[14:17]
	v_mfma_f32_16x16x32_bf16 v[10:13], v[78:81], v[222:225], v[10:13]
	v_mfma_f32_16x16x32_bf16 v[54:57], v[162:165], v[194:197], 0
	v_mfma_f32_16x16x32_bf16 v[50:53], v[186:189], v[194:197], 0
	v_mfma_f32_16x16x32_bf16 v[38:41], v[162:165], v[202:205], 0
	v_mfma_f32_16x16x32_bf16 v[34:37], v[186:189], v[202:205], 0
	v_mfma_f32_16x16x32_bf16 v[22:25], v[162:165], v[210:213], 0
	v_mfma_f32_16x16x32_bf16 v[18:21], v[186:189], v[210:213], 0
	v_mfma_f32_16x16x32_bf16 v[6:9], v[162:165], v[218:221], 0
	v_mfma_f32_16x16x32_bf16 v[2:5], v[186:189], v[218:221], 0
	v_mfma_f32_16x16x32_bf16 v[54:57], v[182:185], v[198:201], v[54:57]
	v_mfma_f32_16x16x32_bf16 v[50:53], v[190:193], v[198:201], v[50:53]
	v_mfma_f32_16x16x32_bf16 v[38:41], v[182:185], v[206:209], v[38:41]
	v_mfma_f32_16x16x32_bf16 v[34:37], v[190:193], v[206:209], v[34:37]
	v_mfma_f32_16x16x32_bf16 v[22:25], v[182:185], v[214:217], v[22:25]
	v_mfma_f32_16x16x32_bf16 v[18:21], v[190:193], v[214:217], v[18:21]
	v_mfma_f32_16x16x32_bf16 v[6:9], v[182:185], v[222:225], v[6:9]
	v_mfma_f32_16x16x32_bf16 v[2:5], v[190:193], v[222:225], v[2:5]
	s_barrier
; #define PG8_STAGE(bufoff, gbase, voff) do { _Pragma("unroll") for (int _i = 0; _i < 2; ++_i) \
;         __builtin_amdgcn_global_load_lds((const unsigned*)((const char*)(gbase) + (voff)[_i]), (LAS unsigned*)(lds + (bufoff) + ldsw + _i * 8192), 16, 0, 0); } while (0)
; #define PG8_LDA(dst, b, h) do { _Pragma("unroll") for (int m = 0; m < 4; ++m) _Pragma("unroll") for (int k = 0; k < 2; ++k) dst[m][k] = *(const LAS bf16x8*)(lds + PG8_SA(b, h) + aoff + m * 2048 + k * 1024); } while (0)
; #define PG8_LDB(dst, b, h) do { _Pragma("unroll") for (int n = 0; n < 2; ++n) _Pragma("unroll") for (int k = 0; k < 2; ++k) dst[n][k] = *(const LAS bf16x8*)(lds + PG8_SB(b, h) + boff + n * 2048 + k * 1024); } while (0)
; #define PG8_MMA(ai, bj, At, Bt) do { __builtin_amdgcn_s_setprio(1); _Pragma("unroll") for (int m = 0; m < 4; ++m) _Pragma("unroll") for (int n = 0; n < 2; ++n) _Pragma("unroll") for (int k = 0; k < 2; ++k) \
;         acc[ai][bj][m][n] = __builtin_amdgcn_mfma_f32_16x16x32_bf16(Bt[n][k], At[m][k], acc[ai][bj][m][n], 0, 0, 0); __builtin_amdgcn_s_setprio(0); } while (0)
; #define PG8_WAIT_V(n) asm volatile("s_waitcnt vmcnt(" #n ")" ::: "memory")
; #define PG8_WAIT_L(n) asm volatile("s_waitcnt lgkmcnt(" #n ")" ::: "memory")
; #define PG8_BAR __builtin_amdgcn_s_barrier()
; #define PG8_SCHED __builtin_amdgcn_sched_barrier(0)
; template <class Epi, class Sched, bool ALIGN_EPI = false, bool SP2 = false>
; __device__ __forceinline__ void gemm_phase(LAS unsigned char* lds, const Gemm g, const Sched& S, const Epi& E) {
;     ...
;         for (int t = 0; t < nt; t += 2) {
;     ...
;             PG8_LDB(B0, 1, 0); PG8_LDB(B1, 1, 1); PG8_SCHED; PG8_LDA(At, 1, 0); PG8_STAGE(PG8_SA(0, 1), a2 + hstep, voffA);
;             PG8_WAIT_V(8); PG8_WAIT_L(0); PG8_BAR; PG8_MMA(0, 0, At, B0); PG8_MMA(0, 1, At, B1); PG8_BAR; PG8_SCHED;
;             PG8_LDA(At, 1, 1); PG8_STAGE(PG8_SB(1, 0), b3, voffB); PG8_STAGE(PG8_SB(1, 1), b3 + hstepB, voffB); PG8_STAGE(PG8_SA(1, 0), a3, voffA);
;             PG8_WAIT_V(8); PG8_WAIT_L(0); PG8_BAR; PG8_MMA(1, 0, At, B0); PG8_MMA(1, 1, At, B1); PG8_BAR; PG8_SCHED;
	s_add_i32 s22, 0, 0x18000
	s_add_i32 s23, 0, 0x1c000
	v_add_u32_e32 v78, s22, v170
	v_add_u32_e32 v168, s23, v170
	ds_read_b128 v[66:69], v78
	ds_read_b128 v[70:73], v78 offset:1024
	ds_read_b128 v[74:77], v78 offset:2048
	ds_read_b128 v[78:81], v78 offset:3072
	ds_read_b128 v[162:165], v168
	ds_read_b128 v[182:185], v168 offset:1024
	ds_read_b128 v[186:189], v168 offset:2048
	ds_read_b128 v[190:193], v168 offset:3072
	s_add_u32 s20, s52, 0x80000
	s_addc_u32 s21, s53, 0
	s_mov_b32 m0, s35
	v_lshl_add_u64 v[232:233], s[20:21], 0, v[152:153]
	ds_read_b128 v[194:197], v176 offset:32768
	ds_read_b128 v[198:201], v176 offset:33792
	ds_read_b128 v[202:205], v176 offset:34816
	ds_read_b128 v[206:209], v176 offset:35840
	ds_read_b128 v[210:213], v176 offset:36864
	ds_read_b128 v[214:217], v176 offset:37888
	ds_read_b128 v[218:221], v176 offset:38912
	ds_read_b128 v[222:225], v176 offset:39936
	global_load_lds_dwordx4 v[232:233], off
	v_lshl_add_u64 v[232:233], s[20:21], 0, v[148:149]
	s_mov_b32 m0, s36
	s_nop 0
	global_load_lds_dwordx4 v[232:233], off
	s_waitcnt vmcnt(8)
	s_waitcnt lgkmcnt(0)
	s_barrier
	v_mfma_f32_16x16x32_bf16 v[142:145], v[66:69], v[194:197], v[142:145]
	v_mfma_f32_16x16x32_bf16 v[138:141], v[74:77], v[194:197], v[138:141]
	v_mfma_f32_16x16x32_bf16 v[126:129], v[66:69], v[202:205], v[126:129]
	v_mfma_f32_16x16x32_bf16 v[122:125], v[74:77], v[202:205], v[122:125]
	v_mfma_f32_16x16x32_bf16 v[110:113], v[66:69], v[210:213], v[110:113]
	v_mfma_f32_16x16x32_bf16 v[106:109], v[74:77], v[210:213], v[106:109]
	v_mfma_f32_16x16x32_bf16 v[94:97], v[66:69], v[218:221], v[94:97]
	v_mfma_f32_16x16x32_bf16 v[90:93], v[74:77], v[218:221], v[90:93]
	v_mfma_f32_16x16x32_bf16 v[142:145], v[70:73], v[198:201], v[142:145]
	v_mfma_f32_16x16x32_bf16 v[138:141], v[78:81], v[198:201], v[138:141]
	v_mfma_f32_16x16x32_bf16 v[126:129], v[70:73], v[206:209], v[126:129]
	v_mfma_f32_16x16x32_bf16 v[122:125], v[78:81], v[206:209], v[122:125]
	v_mfma_f32_16x16x32_bf16 v[110:113], v[70:73], v[214:217], v[110:113]
	v_mfma_f32_16x16x32_bf16 v[106:109], v[78:81], v[214:217], v[106:109]
	v_mfma_f32_16x16x32_bf16 v[94:97], v[70:73], v[222:225], v[94:97]
	v_mfma_f32_16x16x32_bf16 v[90:93], v[78:81], v[222:225], v[90:93]
	v_mfma_f32_16x16x32_bf16 v[134:137], v[162:165], v[194:197], v[134:137]
	v_mfma_f32_16x16x32_bf16 v[130:133], v[186:189], v[194:197], v[130:133]
	v_mfma_f32_16x16x32_bf16 v[118:121], v[162:165], v[202:205], v[118:121]
	v_mfma_f32_16x16x32_bf16 v[114:117], v[186:189], v[202:205], v[114:117]
	v_mfma_f32_16x16x32_bf16 v[102:105], v[162:165], v[210:213], v[102:105]
	v_mfma_f32_16x16x32_bf16 v[98:101], v[186:189], v[210:213], v[98:101]
	v_mfma_f32_16x16x32_bf16 v[86:89], v[162:165], v[218:221], v[86:89]
	v_mfma_f32_16x16x32_bf16 v[82:85], v[186:189], v[218:221], v[82:85]
	v_mfma_f32_16x16x32_bf16 v[134:137], v[182:185], v[198:201], v[134:137]
	v_mfma_f32_16x16x32_bf16 v[130:133], v[190:193], v[198:201], v[130:133]
	v_mfma_f32_16x16x32_bf16 v[118:121], v[182:185], v[206:209], v[118:121]
	v_mfma_f32_16x16x32_bf16 v[114:117], v[190:193], v[206:209], v[114:117]
	v_mfma_f32_16x16x32_bf16 v[102:105], v[182:185], v[214:217], v[102:105]
	v_mfma_f32_16x16x32_bf16 v[98:101], v[190:193], v[214:217], v[98:101]
	v_mfma_f32_16x16x32_bf16 v[86:89], v[182:185], v[222:225], v[86:89]
	v_mfma_f32_16x16x32_bf16 v[82:85], v[190:193], v[222:225], v[82:85]
	s_barrier
	s_add_i32 s20, s22, s27
	v_lshl_add_u64 v[166:167], v[166:167], 0, s[10:11]
	s_mov_b32 m0, s20
	ds_read_b128 v[194:197], v176 offset:49152
	ds_read_b128 v[198:201], v176 offset:50176
	ds_read_b128 v[202:205], v176 offset:51200
	ds_read_b128 v[206:209], v176 offset:52224
	ds_read_b128 v[210:213], v176 offset:53248
	ds_read_b128 v[214:217], v176 offset:54272
	ds_read_b128 v[218:221], v176 offset:55296
	ds_read_b128 v[222:225], v176 offset:56320
	global_load_lds_dwordx4 v[166:167], off
	s_add_i32 m0, s20, 0x2000
	s_add_u32 s20, s50, 0x80080
	v_lshl_add_u64 v[166:167], v[226:227], 0, s[10:11]
	s_addc_u32 s21, s51, 0
	s_add_i32 s22, s23, s27
	global_load_lds_dwordx4 v[166:167], off
	v_lshl_add_u64 v[166:167], s[20:21], 0, v[150:151]
	s_mov_b32 m0, s22
	s_nop 0
	global_load_lds_dwordx4 v[166:167], off
	v_lshl_add_u64 v[166:167], s[20:21], 0, v[146:147]
	s_add_i32 m0, s22, 0x2000
	s_nop 0
	global_load_lds_dwordx4 v[166:167], off
	v_lshl_add_u64 v[166:167], v[228:229], 0, s[10:11]
	s_mov_b32 m0, s55
	s_nop 0
	global_load_lds_dwordx4 v[166:167], off
	v_lshl_add_u64 v[166:167], v[230:231], 0, s[10:11]
	s_mov_b32 m0, s56
	s_nop 0
	global_load_lds_dwordx4 v[166:167], off
	s_waitcnt vmcnt(8)
	s_waitcnt lgkmcnt(0)
	s_barrier
	v_mfma_f32_16x16x32_bf16 v[62:65], v[66:69], v[194:197], v[62:65]
	v_mfma_f32_16x16x32_bf16 v[58:61], v[74:77], v[194:197], v[58:61]
	v_mfma_f32_16x16x32_bf16 v[46:49], v[66:69], v[202:205], v[46:49]
	v_mfma_f32_16x16x32_bf16 v[42:45], v[74:77], v[202:205], v[42:45]
	v_mfma_f32_16x16x32_bf16 v[30:33], v[66:69], v[210:213], v[30:33]
	v_mfma_f32_16x16x32_bf16 v[26:29], v[74:77], v[210:213], v[26:29]
	v_mfma_f32_16x16x32_bf16 v[14:17], v[66:69], v[218:221], v[14:17]
	v_mfma_f32_16x16x32_bf16 v[10:13], v[74:77], v[218:221], v[10:13]
	v_mfma_f32_16x16x32_bf16 v[62:65], v[70:73], v[198:201], v[62:65]
	v_mfma_f32_16x16x32_bf16 v[58:61], v[78:81], v[198:201], v[58:61]
	v_mfma_f32_16x16x32_bf16 v[46:49], v[70:73], v[206:209], v[46:49]
	v_mfma_f32_16x16x32_bf16 v[42:45], v[78:81], v[206:209], v[42:45]
	v_mfma_f32_16x16x32_bf16 v[30:33], v[70:73], v[214:217], v[30:33]
	v_mfma_f32_16x16x32_bf16 v[26:29], v[78:81], v[214:217], v[26:29]
	v_mfma_f32_16x16x32_bf16 v[14:17], v[70:73], v[222:225], v[14:17]
	v_mfma_f32_16x16x32_bf16 v[10:13], v[78:81], v[222:225], v[10:13]
	v_mfma_f32_16x16x32_bf16 v[54:57], v[162:165], v[194:197], v[54:57]
	v_mfma_f32_16x16x32_bf16 v[50:53], v[186:189], v[194:197], v[50:53]
	v_mfma_f32_16x16x32_bf16 v[38:41], v[162:165], v[202:205], v[38:41]
	v_mfma_f32_16x16x32_bf16 v[34:37], v[186:189], v[202:205], v[34:37]
	v_mfma_f32_16x16x32_bf16 v[22:25], v[162:165], v[210:213], v[22:25]
	v_mfma_f32_16x16x32_bf16 v[18:21], v[186:189], v[210:213], v[18:21]
	v_mfma_f32_16x16x32_bf16 v[6:9], v[162:165], v[218:221], v[6:9]
	v_mfma_f32_16x16x32_bf16 v[2:5], v[186:189], v[218:221], v[2:5]
	v_mfma_f32_16x16x32_bf16 v[54:57], v[182:185], v[198:201], v[54:57]
	v_mfma_f32_16x16x32_bf16 v[50:53], v[190:193], v[198:201], v[50:53]
	v_mfma_f32_16x16x32_bf16 v[38:41], v[182:185], v[206:209], v[38:41]
	v_mfma_f32_16x16x32_bf16 v[34:37], v[190:193], v[206:209], v[34:37]
	v_mfma_f32_16x16x32_bf16 v[22:25], v[182:185], v[214:217], v[22:25]
	v_mfma_f32_16x16x32_bf16 v[18:21], v[190:193], v[214:217], v[18:21]
	v_mfma_f32_16x16x32_bf16 v[6:9], v[182:185], v[222:225], v[6:9]
	v_mfma_f32_16x16x32_bf16 v[2:5], v[190:193], v[222:225], v[2:5]
	s_barrier
	s_add_i32 s19, s19, 2
	s_add_u32 s16, s16, 0x100
	s_addc_u32 s17, s17, 0
	s_add_u32 s15, s15, 0x100
	s_addc_u32 s18, s18, 0
	s_cmp_gt_u32 s19, 29
; #define PG8_STAGE(bufoff, gbase, voff) do { _Pragma("unroll") for (int _i = 0; _i < 2; ++_i) \
;         __builtin_amdgcn_global_load_lds((const unsigned*)((const char*)(gbase) + (voff)[_i]), (LAS unsigned*)(lds + (bufoff) + ldsw + _i * 8192), 16, 0, 0); } while (0)
; #define PG8_LDA(dst, b, h) do { _Pragma("unroll") for (int m = 0; m < 4; ++m) _Pragma("unroll") for (int k = 0; k < 2; ++k) dst[m][k] = *(const LAS bf16x8*)(lds + PG8_SA(b, h) + aoff + m * 2048 + k * 1024); } while (0)
; #define PG8_LDB(dst, b, h) do { _Pragma("unroll") for (int n = 0; n < 2; ++n) _Pragma("unroll") for (int k = 0; k < 2; ++k) dst[n][k] = *(const LAS bf16x8*)(lds + PG8_SB(b, h) + boff + n * 2048 + k * 1024); } while (0)
; #define PG8_MMA(ai, bj, At, Bt) do { __builtin_amdgcn_s_setprio(1); _Pragma("unroll") for (int m = 0; m < 4; ++m) _Pragma("unroll") for (int n = 0; n < 2; ++n) _Pragma("unroll") for (int k = 0; k < 2; ++k) \
;         acc[ai][bj][m][n] = __builtin_amdgcn_mfma_f32_16x16x32_bf16(Bt[n][k], At[m][k], acc[ai][bj][m][n], 0, 0, 0); __builtin_amdgcn_s_setprio(0); } while (0)
; #define PG8_WAIT_V(n) asm volatile("s_waitcnt vmcnt(" #n ")" ::: "memory")
; #define PG8_WAIT_L(n) asm volatile("s_waitcnt lgkmcnt(" #n ")" ::: "memory")
; template <class Epi, class Sched, bool ALIGN_EPI = false, bool SP2 = false>
; __device__ __forceinline__ void gemm_phase(LAS unsigned char* lds, const Gemm g, const Sched& S, const Epi& E) {
;     ...
;         for (int t = 0; t < nt; t += 2) {
;             const bool last = (t == nt - 2);
;             const char* a1 = cA + (size_t)(t + 1) * kstep;
;             const char* a2 = last ? nA : cA + (size_t)(t + 2) * kstep; const char* b2 = last ? nB : cB + (size_t)(t + 2) * kstep;
;             const char* a3 = a2 + kstep; const char* b3 = b2 + kstep;
;             if (last && has_next) S.a_ready(nxt);
;             if constexpr (SP2) {
;             PG8_LDB(B0, 0, 0); PG8_LDB(B1, 0, 1); PG8_SCHED; PG8_LDA(At, 0, 0); PG8_STAGE(PG8_SA(1, 1), a1 + hstep, voffA);
;             PG8_WAIT_V(8); PG8_WAIT_L(0); PG8_BAR; PG8_MMA(0, 0, At, B0); PG8_MMA(0, 1, At, B1); PG8_BAR; PG8_SCHED;
;             PG8_LDA(At, 0, 1); PG8_STAGE(PG8_SB(0, 0), b2, voffB); PG8_STAGE(PG8_SB(0, 1), b2 + hstepB, voffB); PG8_STAGE(PG8_SA(0, 0), a2, voffA);
;             PG8_WAIT_V(8); PG8_WAIT_L(0); PG8_BAR; PG8_MMA(1, 0, At, B0); PG8_MMA(1, 1, At, B1); PG8_BAR; PG8_SCHED;
.LBB0_188:
	ds_read_b128 v[66:69], v174
	ds_read_b128 v[70:73], v174 offset:1024
	ds_read_b128 v[74:77], v174 offset:2048
	ds_read_b128 v[78:81], v174 offset:3072
	ds_read_b128 v[162:165], v175
	ds_read_b128 v[182:185], v175 offset:1024
	ds_read_b128 v[186:189], v175 offset:2048
	ds_read_b128 v[190:193], v175 offset:3072
	s_add_u32 s20, s16, 0xfff80080
	s_addc_u32 s21, s17, -1
	s_cmp_eq_u32 s19, 28
	s_cselect_b32 s53, s3, s21
	s_cselect_b32 s52, s12, s20
	s_cselect_b32 s51, s13, s18
	s_cselect_b32 s50, s14, s15
	v_lshl_add_u64 v[166:167], s[16:17], 0, v[154:155]
	s_add_i32 m0, s33, 0xc000
	ds_read_b128 v[194:197], v176
	ds_read_b128 v[198:201], v176 offset:1024
	ds_read_b128 v[202:205], v176 offset:2048
	ds_read_b128 v[206:209], v176 offset:3072
	ds_read_b128 v[210:213], v176 offset:4096
	ds_read_b128 v[214:217], v176 offset:5120
	ds_read_b128 v[218:221], v176 offset:6144
	ds_read_b128 v[222:225], v176 offset:7168
	global_load_lds_dwordx4 v[166:167], off
	v_lshl_add_u64 v[166:167], s[16:17], 0, v[156:157]
	s_add_i32 m0, s33, 0xe000
	s_nop 0
	global_load_lds_dwordx4 v[166:167], off
	s_waitcnt vmcnt(8)
	s_waitcnt lgkmcnt(0)
	s_barrier
	v_mfma_f32_16x16x32_bf16 v[142:145], v[66:69], v[194:197], v[142:145]
	v_mfma_f32_16x16x32_bf16 v[138:141], v[74:77], v[194:197], v[138:141]
	v_mfma_f32_16x16x32_bf16 v[126:129], v[66:69], v[202:205], v[126:129]
	v_mfma_f32_16x16x32_bf16 v[122:125], v[74:77], v[202:205], v[122:125]
	v_mfma_f32_16x16x32_bf16 v[110:113], v[66:69], v[210:213], v[110:113]
	v_mfma_f32_16x16x32_bf16 v[106:109], v[74:77], v[210:213], v[106:109]
	v_mfma_f32_16x16x32_bf16 v[94:97], v[66:69], v[218:221], v[94:97]
	v_mfma_f32_16x16x32_bf16 v[90:93], v[74:77], v[218:221], v[90:93]
	v_mfma_f32_16x16x32_bf16 v[142:145], v[70:73], v[198:201], v[142:145]
	v_mfma_f32_16x16x32_bf16 v[138:141], v[78:81], v[198:201], v[138:141]
	v_mfma_f32_16x16x32_bf16 v[126:129], v[70:73], v[206:209], v[126:129]
	v_mfma_f32_16x16x32_bf16 v[122:125], v[78:81], v[206:209], v[122:125]
	v_mfma_f32_16x16x32_bf16 v[110:113], v[70:73], v[214:217], v[110:113]
	v_mfma_f32_16x16x32_bf16 v[106:109], v[78:81], v[214:217], v[106:109]
	v_mfma_f32_16x16x32_bf16 v[94:97], v[70:73], v[222:225], v[94:97]
	v_mfma_f32_16x16x32_bf16 v[90:93], v[78:81], v[222:225], v[90:93]
	v_mfma_f32_16x16x32_bf16 v[134:137], v[162:165], v[194:197], v[134:137]
	v_mfma_f32_16x16x32_bf16 v[130:133], v[186:189], v[194:197], v[130:133]
	v_mfma_f32_16x16x32_bf16 v[118:121], v[162:165], v[202:205], v[118:121]
	v_mfma_f32_16x16x32_bf16 v[114:117], v[186:189], v[202:205], v[114:117]
	v_mfma_f32_16x16x32_bf16 v[102:105], v[162:165], v[210:213], v[102:105]
	v_mfma_f32_16x16x32_bf16 v[98:101], v[186:189], v[210:213], v[98:101]
	v_mfma_f32_16x16x32_bf16 v[86:89], v[162:165], v[218:221], v[86:89]
	v_mfma_f32_16x16x32_bf16 v[82:85], v[186:189], v[218:221], v[82:85]
	v_mfma_f32_16x16x32_bf16 v[134:137], v[182:185], v[198:201], v[134:137]
	v_mfma_f32_16x16x32_bf16 v[130:133], v[190:193], v[198:201], v[130:133]
	v_mfma_f32_16x16x32_bf16 v[118:121], v[182:185], v[206:209], v[118:121]
	v_mfma_f32_16x16x32_bf16 v[114:117], v[190:193], v[206:209], v[114:117]
	v_mfma_f32_16x16x32_bf16 v[102:105], v[182:185], v[214:217], v[102:105]
	v_mfma_f32_16x16x32_bf16 v[98:101], v[190:193], v[214:217], v[98:101]
	v_mfma_f32_16x16x32_bf16 v[86:89], v[182:185], v[222:225], v[86:89]
	v_mfma_f32_16x16x32_bf16 v[82:85], v[190:193], v[222:225], v[82:85]
	s_barrier
	s_add_i32 s20, s57, s27
	v_lshl_add_u64 v[166:167], s[50:51], 0, v[150:151]
	s_mov_b32 m0, s20
	ds_read_b128 v[194:197], v176 offset:16384
	ds_read_b128 v[198:201], v176 offset:17408
	ds_read_b128 v[202:205], v176 offset:18432
	ds_read_b128 v[206:209], v176 offset:19456
	ds_read_b128 v[210:213], v176 offset:20480
	ds_read_b128 v[214:217], v176 offset:21504
	ds_read_b128 v[218:221], v176 offset:22528
	ds_read_b128 v[222:225], v176 offset:23552
	global_load_lds_dwordx4 v[166:167], off
	s_add_i32 m0, s20, 0x2000
	s_add_u32 s20, s50, 0x80000
	v_lshl_add_u64 v[226:227], s[50:51], 0, v[146:147]
	s_addc_u32 s21, s51, 0
	s_add_i32 s22, s58, s27
	global_load_lds_dwordx4 v[226:227], off
	v_lshl_add_u64 v[228:229], s[20:21], 0, v[150:151]
	s_mov_b32 m0, s22
	v_lshl_add_u64 v[230:231], s[52:53], 0, v[148:149]
	global_load_lds_dwordx4 v[228:229], off
	v_lshl_add_u64 v[228:229], s[20:21], 0, v[146:147]
	s_add_i32 m0, s22, 0x2000
	s_nop 0
	global_load_lds_dwordx4 v[228:229], off
	v_lshl_add_u64 v[228:229], s[52:53], 0, v[152:153]
	s_mov_b32 m0, s33
	s_nop 0
	global_load_lds_dwordx4 v[228:229], off
	s_mov_b32 m0, s34
	s_nop 0
	global_load_lds_dwordx4 v[230:231], off
	s_waitcnt vmcnt(8)
	s_waitcnt lgkmcnt(0)
	s_barrier
; #define PG8_STAGE(bufoff, gbase, voff) do { _Pragma("unroll") for (int _i = 0; _i < 2; ++_i) \
;         __builtin_amdgcn_global_load_lds((const unsigned*)((const char*)(gbase) + (voff)[_i]), (LAS unsigned*)(lds + (bufoff) + ldsw + _i * 8192), 16, 0, 0); } while (0)
; #define PG8_LDA(dst, b, h) do { _Pragma("unroll") for (int m = 0; m < 4; ++m) _Pragma("unroll") for (int k = 0; k < 2; ++k) dst[m][k] = *(const LAS bf16x8*)(lds + PG8_SA(b, h) + aoff + m * 2048 + k * 1024); } while (0)
; #define PG8_LDB(dst, b, h) do { _Pragma("unroll") for (int n = 0; n < 2; ++n) _Pragma("unroll") for (int k = 0; k < 2; ++k) dst[n][k] = *(const LAS bf16x8*)(lds + PG8_SB(b, h) + boff + n * 2048 + k * 1024); } while (0)
; #define PG8_MMA(ai, bj, At, Bt) do { __builtin_amdgcn_s_setprio(1); _Pragma("unroll") for (int m = 0; m < 4; ++m) _Pragma("unroll") for (int n = 0; n < 2; ++n) _Pragma("unroll") for (int k = 0; k < 2; ++k) \
;         acc[ai][bj][m][n] = __builtin_amdgcn_mfma_f32_16x16x32_bf16(Bt[n][k], At[m][k], acc[ai][bj][m][n], 0, 0, 0); __builtin_amdgcn_s_setprio(0); } while (0)
; #define PG8_WAIT_V(n) asm volatile("s_waitcnt vmcnt(" #n ")" ::: "memory")
; #define PG8_WAIT_L(n) asm volatile("s_waitcnt lgkmcnt(" #n ")" ::: "memory")
; #define PG8_BAR __builtin_amdgcn_s_barrier()
; #define PG8_SCHED __builtin_amdgcn_sched_barrier(0)
; template <class Epi, class Sched, bool ALIGN_EPI = false, bool SP2 = false>
; __device__ __forceinline__ void gemm_phase(LAS unsigned char* lds, const Gemm g, const Sched& S, const Epi& E) {
;     ...
;             PG8_WAIT_V(8); PG8_WAIT_L(0); PG8_BAR; PG8_MMA(1, 0, At, B0); PG8_MMA(1, 1, At, B1); PG8_BAR; PG8_SCHED;
;             PG8_LDB(B0, 1, 0); PG8_LDB(B1, 1, 1); PG8_SCHED; PG8_LDA(At, 1, 0); PG8_STAGE(PG8_SA(0, 1), a2 + hstep, voffA);
;             PG8_WAIT_V(8); PG8_WAIT_L(0); PG8_BAR; PG8_MMA(0, 0, At, B0); PG8_MMA(0, 1, At, B1); PG8_BAR; PG8_SCHED;
	v_mfma_f32_16x16x32_bf16 v[62:65], v[66:69], v[194:197], v[62:65]
	v_mfma_f32_16x16x32_bf16 v[58:61], v[74:77], v[194:197], v[58:61]
	v_mfma_f32_16x16x32_bf16 v[46:49], v[66:69], v[202:205], v[46:49]
	v_mfma_f32_16x16x32_bf16 v[42:45], v[74:77], v[202:205], v[42:45]
	v_mfma_f32_16x16x32_bf16 v[30:33], v[66:69], v[210:213], v[30:33]
	v_mfma_f32_16x16x32_bf16 v[26:29], v[74:77], v[210:213], v[26:29]
	v_mfma_f32_16x16x32_bf16 v[14:17], v[66:69], v[218:221], v[14:17]
	v_mfma_f32_16x16x32_bf16 v[10:13], v[74:77], v[218:221], v[10:13]
	v_mfma_f32_16x16x32_bf16 v[62:65], v[70:73], v[198:201], v[62:65]
	v_mfma_f32_16x16x32_bf16 v[58:61], v[78:81], v[198:201], v[58:61]
	v_mfma_f32_16x16x32_bf16 v[46:49], v[70:73], v[206:209], v[46:49]
	v_mfma_f32_16x16x32_bf16 v[42:45], v[78:81], v[206:209], v[42:45]
	v_mfma_f32_16x16x32_bf16 v[30:33], v[70:73], v[214:217], v[30:33]
	v_mfma_f32_16x16x32_bf16 v[26:29], v[78:81], v[214:217], v[26:29]
	v_mfma_f32_16x16x32_bf16 v[14:17], v[70:73], v[222:225], v[14:17]
	v_mfma_f32_16x16x32_bf16 v[10:13], v[78:81], v[222:225], v[10:13]
	v_mfma_f32_16x16x32_bf16 v[54:57], v[162:165], v[194:197], v[54:57]
	v_mfma_f32_16x16x32_bf16 v[50:53], v[186:189], v[194:197], v[50:53]
	v_mfma_f32_16x16x32_bf16 v[38:41], v[162:165], v[202:205], v[38:41]
	v_mfma_f32_16x16x32_bf16 v[34:37], v[186:189], v[202:205], v[34:37]
	v_mfma_f32_16x16x32_bf16 v[22:25], v[162:165], v[210:213], v[22:25]
	v_mfma_f32_16x16x32_bf16 v[18:21], v[186:189], v[210:213], v[18:21]
	v_mfma_f32_16x16x32_bf16 v[6:9], v[162:165], v[218:221], v[6:9]
	v_mfma_f32_16x16x32_bf16 v[2:5], v[186:189], v[218:221], v[2:5]
	v_mfma_f32_16x16x32_bf16 v[54:57], v[182:185], v[198:201], v[54:57]
	v_mfma_f32_16x16x32_bf16 v[50:53], v[190:193], v[198:201], v[50:53]
	v_mfma_f32_16x16x32_bf16 v[38:41], v[182:185], v[206:209], v[38:41]
	v_mfma_f32_16x16x32_bf16 v[34:37], v[190:193], v[206:209], v[34:37]
	v_mfma_f32_16x16x32_bf16 v[22:25], v[182:185], v[214:217], v[22:25]
	v_mfma_f32_16x16x32_bf16 v[18:21], v[190:193], v[214:217], v[18:21]
	v_mfma_f32_16x16x32_bf16 v[6:9], v[182:185], v[222:225], v[6:9]
	v_mfma_f32_16x16x32_bf16 v[2:5], v[190:193], v[222:225], v[2:5]
	s_barrier
	s_add_i32 s22, 0, 0x18000
	s_add_i32 s23, 0, 0x1c000
	v_add_u32_e32 v78, s22, v170
	v_add_u32_e32 v168, s23, v170
	ds_read_b128 v[66:69], v78
	ds_read_b128 v[70:73], v78 offset:1024
	ds_read_b128 v[74:77], v78 offset:2048
	ds_read_b128 v[78:81], v78 offset:3072
	ds_read_b128 v[162:165], v168
	ds_read_b128 v[182:185], v168 offset:1024
	ds_read_b128 v[186:189], v168 offset:2048
	ds_read_b128 v[190:193], v168 offset:3072
	s_add_u32 s20, s52, 0x80000
	s_addc_u32 s21, s53, 0
	s_mov_b32 m0, s35
	v_lshl_add_u64 v[232:233], s[20:21], 0, v[152:153]
	ds_read_b128 v[194:197], v176 offset:32768
	ds_read_b128 v[198:201], v176 offset:33792
	ds_read_b128 v[202:205], v176 offset:34816
	ds_read_b128 v[206:209], v176 offset:35840
	ds_read_b128 v[210:213], v176 offset:36864
	ds_read_b128 v[214:217], v176 offset:37888
	ds_read_b128 v[218:221], v176 offset:38912
	ds_read_b128 v[222:225], v176 offset:39936
	global_load_lds_dwordx4 v[232:233], off
	v_lshl_add_u64 v[232:233], s[20:21], 0, v[148:149]
	s_mov_b32 m0, s36
	s_nop 0
	global_load_lds_dwordx4 v[232:233], off
	s_waitcnt vmcnt(8)
	s_waitcnt lgkmcnt(0)
	s_barrier
	v_mfma_f32_16x16x32_bf16 v[142:145], v[66:69], v[194:197], v[142:145]
	v_mfma_f32_16x16x32_bf16 v[138:141], v[74:77], v[194:197], v[138:141]
	v_mfma_f32_16x16x32_bf16 v[126:129], v[66:69], v[202:205], v[126:129]
	v_mfma_f32_16x16x32_bf16 v[122:125], v[74:77], v[202:205], v[122:125]
	v_mfma_f32_16x16x32_bf16 v[110:113], v[66:69], v[210:213], v[110:113]
	v_mfma_f32_16x16x32_bf16 v[106:109], v[74:77], v[210:213], v[106:109]
	v_mfma_f32_16x16x32_bf16 v[94:97], v[66:69], v[218:221], v[94:97]
	v_mfma_f32_16x16x32_bf16 v[90:93], v[74:77], v[218:221], v[90:93]
	v_mfma_f32_16x16x32_bf16 v[142:145], v[70:73], v[198:201], v[142:145]
	v_mfma_f32_16x16x32_bf16 v[138:141], v[78:81], v[198:201], v[138:141]
	v_mfma_f32_16x16x32_bf16 v[126:129], v[70:73], v[206:209], v[126:129]
	v_mfma_f32_16x16x32_bf16 v[122:125], v[78:81], v[206:209], v[122:125]
	v_mfma_f32_16x16x32_bf16 v[110:113], v[70:73], v[214:217], v[110:113]
	v_mfma_f32_16x16x32_bf16 v[106:109], v[78:81], v[214:217], v[106:109]
	v_mfma_f32_16x16x32_bf16 v[94:97], v[70:73], v[222:225], v[94:97]
	v_mfma_f32_16x16x32_bf16 v[90:93], v[78:81], v[222:225], v[90:93]
	v_mfma_f32_16x16x32_bf16 v[134:137], v[162:165], v[194:197], v[134:137]
	v_mfma_f32_16x16x32_bf16 v[130:133], v[186:189], v[194:197], v[130:133]
	v_mfma_f32_16x16x32_bf16 v[118:121], v[162:165], v[202:205], v[118:121]
	v_mfma_f32_16x16x32_bf16 v[114:117], v[186:189], v[202:205], v[114:117]
	v_mfma_f32_16x16x32_bf16 v[102:105], v[162:165], v[210:213], v[102:105]
	v_mfma_f32_16x16x32_bf16 v[98:101], v[186:189], v[210:213], v[98:101]
	v_mfma_f32_16x16x32_bf16 v[86:89], v[162:165], v[218:221], v[86:89]
	v_mfma_f32_16x16x32_bf16 v[82:85], v[186:189], v[218:221], v[82:85]
	v_mfma_f32_16x16x32_bf16 v[134:137], v[182:185], v[198:201], v[134:137]
	v_mfma_f32_16x16x32_bf16 v[130:133], v[190:193], v[198:201], v[130:133]
	v_mfma_f32_16x16x32_bf16 v[118:121], v[182:185], v[206:209], v[118:121]
	v_mfma_f32_16x16x32_bf16 v[114:117], v[190:193], v[206:209], v[114:117]
	v_mfma_f32_16x16x32_bf16 v[102:105], v[182:185], v[214:217], v[102:105]
	v_mfma_f32_16x16x32_bf16 v[98:101], v[190:193], v[214:217], v[98:101]
	v_mfma_f32_16x16x32_bf16 v[86:89], v[182:185], v[222:225], v[86:89]
	v_mfma_f32_16x16x32_bf16 v[82:85], v[190:193], v[222:225], v[82:85]
	s_barrier
; #define PG8_STAGE(bufoff, gbase, voff) do { _Pragma("unroll") for (int _i = 0; _i < 2; ++_i) \
;         __builtin_amdgcn_global_load_lds((const unsigned*)((const char*)(gbase) + (voff)[_i]), (LAS unsigned*)(lds + (bufoff) + ldsw + _i * 8192), 16, 0, 0); } while (0)
; #define PG8_LDA(dst, b, h) do { _Pragma("unroll") for (int m = 0; m < 4; ++m) _Pragma("unroll") for (int k = 0; k < 2; ++k) dst[m][k] = *(const LAS bf16x8*)(lds + PG8_SA(b, h) + aoff + m * 2048 + k * 1024); } while (0)
; #define PG8_MMA(ai, bj, At, Bt) do { __builtin_amdgcn_s_setprio(1); _Pragma("unroll") for (int m = 0; m < 4; ++m) _Pragma("unroll") for (int n = 0; n < 2; ++n) _Pragma("unroll") for (int k = 0; k < 2; ++k) \
;         acc[ai][bj][m][n] = __builtin_amdgcn_mfma_f32_16x16x32_bf16(Bt[n][k], At[m][k], acc[ai][bj][m][n], 0, 0, 0); __builtin_amdgcn_s_setprio(0); } while (0)
; #define PG8_WAIT_V(n) asm volatile("s_waitcnt vmcnt(" #n ")" ::: "memory")
; #define PG8_WAIT_L(n) asm volatile("s_waitcnt lgkmcnt(" #n ")" ::: "memory")
; #define PG8_BAR __builtin_amdgcn_s_barrier()
; #define PG8_SCHED __builtin_amdgcn_sched_barrier(0)
; template <class Epi, class Sched, bool ALIGN_EPI = false, bool SP2 = false>
; __device__ __forceinline__ void gemm_phase(LAS unsigned char* lds, const Gemm g, const Sched& S, const Epi& E) {
;     ...
;         for (int t = 0; t < nt; t += 2) {
;     ...
;             PG8_LDA(At, 1, 1); PG8_STAGE(PG8_SB(1, 0), b3, voffB); PG8_STAGE(PG8_SB(1, 1), b3 + hstepB, voffB); PG8_STAGE(PG8_SA(1, 0), a3, voffA);
;             PG8_WAIT_V(8); PG8_WAIT_L(0); PG8_BAR; PG8_MMA(1, 0, At, B0); PG8_MMA(1, 1, At, B1); PG8_BAR; PG8_SCHED;
;     ...
;         if constexpr (ALIGN_EPI) { if (wr == 0) PG8_BAR; }
	s_add_i32 s20, s22, s27
	v_lshl_add_u64 v[166:167], v[166:167], 0, s[10:11]
	s_mov_b32 m0, s20
	ds_read_b128 v[194:197], v176 offset:49152
	ds_read_b128 v[198:201], v176 offset:50176
	ds_read_b128 v[202:205], v176 offset:51200
	ds_read_b128 v[206:209], v176 offset:52224
	ds_read_b128 v[210:213], v176 offset:53248
	ds_read_b128 v[214:217], v176 offset:54272
	ds_read_b128 v[218:221], v176 offset:55296
	ds_read_b128 v[222:225], v176 offset:56320
	global_load_lds_dwordx4 v[166:167], off
	s_add_i32 m0, s20, 0x2000
	s_add_u32 s20, s50, 0x80080
	v_lshl_add_u64 v[166:167], v[226:227], 0, s[10:11]
	s_addc_u32 s21, s51, 0
	s_add_i32 s22, s23, s27
	global_load_lds_dwordx4 v[166:167], off
	v_lshl_add_u64 v[166:167], s[20:21], 0, v[150:151]
	s_mov_b32 m0, s22
	s_nop 0
	global_load_lds_dwordx4 v[166:167], off
	v_lshl_add_u64 v[166:167], s[20:21], 0, v[146:147]
	s_add_i32 m0, s22, 0x2000
	s_nop 0
	global_load_lds_dwordx4 v[166:167], off
	v_lshl_add_u64 v[166:167], v[228:229], 0, s[10:11]
	s_mov_b32 m0, s55
	s_nop 0
	global_load_lds_dwordx4 v[166:167], off
	v_lshl_add_u64 v[166:167], v[230:231], 0, s[10:11]
	s_mov_b32 m0, s56
	s_nop 0
	global_load_lds_dwordx4 v[166:167], off
	s_waitcnt vmcnt(8)
	s_waitcnt lgkmcnt(0)
	s_barrier
	v_mfma_f32_16x16x32_bf16 v[62:65], v[66:69], v[194:197], v[62:65]
	v_mfma_f32_16x16x32_bf16 v[58:61], v[74:77], v[194:197], v[58:61]
	v_mfma_f32_16x16x32_bf16 v[46:49], v[66:69], v[202:205], v[46:49]
	v_mfma_f32_16x16x32_bf16 v[42:45], v[74:77], v[202:205], v[42:45]
	v_mfma_f32_16x16x32_bf16 v[30:33], v[66:69], v[210:213], v[30:33]
	v_mfma_f32_16x16x32_bf16 v[26:29], v[74:77], v[210:213], v[26:29]
	v_mfma_f32_16x16x32_bf16 v[14:17], v[66:69], v[218:221], v[14:17]
	v_mfma_f32_16x16x32_bf16 v[10:13], v[74:77], v[218:221], v[10:13]
	v_mfma_f32_16x16x32_bf16 v[62:65], v[70:73], v[198:201], v[62:65]
	v_mfma_f32_16x16x32_bf16 v[58:61], v[78:81], v[198:201], v[58:61]
	v_mfma_f32_16x16x32_bf16 v[46:49], v[70:73], v[206:209], v[46:49]
	v_mfma_f32_16x16x32_bf16 v[42:45], v[78:81], v[206:209], v[42:45]
	v_mfma_f32_16x16x32_bf16 v[30:33], v[70:73], v[214:217], v[30:33]
	v_mfma_f32_16x16x32_bf16 v[26:29], v[78:81], v[214:217], v[26:29]
	v_mfma_f32_16x16x32_bf16 v[14:17], v[70:73], v[222:225], v[14:17]
	v_mfma_f32_16x16x32_bf16 v[10:13], v[78:81], v[222:225], v[10:13]
	v_mfma_f32_16x16x32_bf16 v[54:57], v[162:165], v[194:197], v[54:57]
	v_mfma_f32_16x16x32_bf16 v[50:53], v[186:189], v[194:197], v[50:53]
	v_mfma_f32_16x16x32_bf16 v[38:41], v[162:165], v[202:205], v[38:41]
	v_mfma_f32_16x16x32_bf16 v[34:37], v[186:189], v[202:205], v[34:37]
	v_mfma_f32_16x16x32_bf16 v[22:25], v[162:165], v[210:213], v[22:25]
	v_mfma_f32_16x16x32_bf16 v[18:21], v[186:189], v[210:213], v[18:21]
	v_mfma_f32_16x16x32_bf16 v[6:9], v[162:165], v[218:221], v[6:9]
	v_mfma_f32_16x16x32_bf16 v[2:5], v[186:189], v[218:221], v[2:5]
	v_mfma_f32_16x16x32_bf16 v[54:57], v[182:185], v[198:201], v[54:57]
	v_mfma_f32_16x16x32_bf16 v[50:53], v[190:193], v[198:201], v[50:53]
	v_mfma_f32_16x16x32_bf16 v[38:41], v[182:185], v[206:209], v[38:41]
	v_mfma_f32_16x16x32_bf16 v[34:37], v[190:193], v[206:209], v[34:37]
	v_mfma_f32_16x16x32_bf16 v[22:25], v[182:185], v[214:217], v[22:25]
	v_mfma_f32_16x16x32_bf16 v[18:21], v[190:193], v[214:217], v[18:21]
	v_mfma_f32_16x16x32_bf16 v[6:9], v[182:185], v[222:225], v[6:9]
	v_mfma_f32_16x16x32_bf16 v[2:5], v[190:193], v[222:225], v[2:5]
	s_barrier
	s_add_i32 s19, s19, 2
	s_add_u32 s16, s16, 0x100
	s_addc_u32 s17, s17, 0
	s_add_u32 s15, s15, 0x100
	s_addc_u32 s18, s18, 0
	s_cmp_gt_u32 s19, 29
	s_cbranch_scc0 .LBB0_188
	s_setprio 0
	s_and_b64 vcc, exec, s[40:41]
	s_cbranch_vccz .LBB0_191
	s_barrier

; #define PG8_STAGE(bufoff, gbase, voff) do { _Pragma("unroll") for (int _i = 0; _i < 2; ++_i) \
;         __builtin_amdgcn_global_load_lds((const unsigned*)((const char*)(gbase) + (voff)[_i]), (LAS unsigned*)(lds + (bufoff) + ldsw + _i * 8192), 16, 0, 0); } while (0)
; #define PG8_LDA(dst, b, h) do { _Pragma("unroll") for (int m = 0; m < 4; ++m) _Pragma("unroll") for (int k = 0; k < 2; ++k) dst[m][k] = *(const LAS bf16x8*)(lds + PG8_SA(b, h) + aoff + m * 2048 + k * 1024); } while (0)
; #define PG8_LDB(dst, b, h) do { _Pragma("unroll") for (int n = 0; n < 2; ++n) _Pragma("unroll") for (int k = 0; k < 2; ++k) dst[n][k] = *(const LAS bf16x8*)(lds + PG8_SB(b, h) + boff + n * 2048 + k * 1024); } while (0)
; #define PG8_MMA(ai, bj, At, Bt) do { __builtin_amdgcn_s_setprio(1); _Pragma("unroll") for (int m = 0; m < 4; ++m) _Pragma("unroll") for (int n = 0; n < 2; ++n) _Pragma("unroll") for (int k = 0; k < 2; ++k) \
;         acc[ai][bj][m][n] = __builtin_amdgcn_mfma_f32_16x16x32_bf16(Bt[n][k], At[m][k], acc[ai][bj][m][n], 0, 0, 0); __builtin_amdgcn_s_setprio(0); } while (0)
; #define PG8_WAIT_V(n) asm volatile("s_waitcnt vmcnt(" #n ")" ::: "memory")
; #define PG8_WAIT_L(n) asm volatile("s_waitcnt lgkmcnt(" #n ")" ::: "memory")
; template <class Epi, class Sched, bool ALIGN_EPI = false, bool SP2 = false>
; __device__ __forceinline__ void gemm_phase(LAS unsigned char* lds, const Gemm g, const Sched& S, const Epi& E) {
;     ...
;         for (int t = 0; t < nt; t += 2) {
;             const bool last = (t == nt - 2);
;             const char* a1 = cA + (size_t)(t + 1) * kstep;
;             const char* a2 = last ? nA : cA + (size_t)(t + 2) * kstep; const char* b2 = last ? nB : cB + (size_t)(t + 2) * kstep;
;             const char* a3 = a2 + kstep; const char* b3 = b2 + kstep;
;             if (last && has_next) S.a_ready(nxt);
;             if constexpr (SP2) {
;             PG8_LDB(B0, 0, 0); PG8_LDB(B1, 0, 1); PG8_SCHED; PG8_LDA(At, 0, 0); PG8_STAGE(PG8_SA(1, 1), a1 + hstep, voffA);
;             PG8_WAIT_V(8); PG8_WAIT_L(0); PG8_BAR; PG8_MMA(0, 0, At, B0); PG8_MMA(0, 1, At, B1); PG8_BAR; PG8_SCHED;
;             PG8_LDA(At, 0, 1); PG8_STAGE(PG8_SB(0, 0), b2, voffB); PG8_STAGE(PG8_SB(0, 1), b2 + hstepB, voffB); PG8_STAGE(PG8_SA(0, 0), a2, voffA);
;             PG8_WAIT_V(8); PG8_WAIT_L(0); PG8_BAR; PG8_MMA(1, 0, At, B0); PG8_MMA(1, 1, At, B1); PG8_BAR; PG8_SCHED;
.LBB0_288:
	ds_read_b128 v[144:147], v135
	ds_read_b128 v[148:151], v135 offset:1024
	ds_read_b128 v[152:155], v135 offset:2048
	ds_read_b128 v[156:159], v135 offset:3072
	ds_read_b128 v[160:163], v140
	ds_read_b128 v[164:167], v140 offset:1024
	ds_read_b128 v[168:171], v140 offset:2048
	ds_read_b128 v[172:175], v140 offset:3072
	s_add_i32 s44, s40, 2
	s_cmp_lg_u32 s24, s40
	s_cselect_b32 s40, s16, 0
	s_cselect_b32 s41, s17, 0
	s_add_u32 s42, s4, s40
	s_addc_u32 s43, s5, s41
	s_add_u32 s40, s2, s40
	s_addc_u32 s41, s3, s41
	v_lshl_add_u64 v[208:209], v[136:137], 0, s[16:17]
	s_mov_b32 m0, s25
	v_lshl_add_u64 v[208:209], v[208:209], 0, s[38:39]
	ds_read_b128 v[176:179], v141
	ds_read_b128 v[180:183], v141 offset:1024
	ds_read_b128 v[184:187], v141 offset:2048
	ds_read_b128 v[188:191], v141 offset:3072
	ds_read_b128 v[192:195], v141 offset:4096
	ds_read_b128 v[196:199], v141 offset:5120
	ds_read_b128 v[200:203], v141 offset:6144
	ds_read_b128 v[204:207], v141 offset:7168
	global_load_lds_dwordx4 v[208:209], off
	v_lshl_add_u64 v[208:209], v[138:139], 0, s[16:17]
	v_lshl_add_u64 v[208:209], v[208:209], 0, s[38:39]
	s_mov_b32 m0, s28
	s_nop 0
	global_load_lds_dwordx4 v[208:209], off
	s_waitcnt vmcnt(8)
	s_waitcnt lgkmcnt(0)
	s_barrier
	s_setprio 1
	v_mfma_f32_16x16x32_bf16 v[126:129], v[144:147], v[176:179], v[126:129]
	v_mfma_f32_16x16x32_bf16 v[94:97], v[152:155], v[176:179], v[94:97]
	v_mfma_f32_16x16x32_bf16 v[122:125], v[144:147], v[184:187], v[122:125]
	v_mfma_f32_16x16x32_bf16 v[90:93], v[152:155], v[184:187], v[90:93]
	v_mfma_f32_16x16x32_bf16 v[118:121], v[144:147], v[192:195], v[118:121]
	v_mfma_f32_16x16x32_bf16 v[86:89], v[152:155], v[192:195], v[86:89]
	v_mfma_f32_16x16x32_bf16 v[114:117], v[144:147], v[200:203], v[114:117]
	v_mfma_f32_16x16x32_bf16 v[82:85], v[152:155], v[200:203], v[82:85]
	v_mfma_f32_16x16x32_bf16 v[126:129], v[148:151], v[180:183], v[126:129]
	v_mfma_f32_16x16x32_bf16 v[94:97], v[156:159], v[180:183], v[94:97]
	v_mfma_f32_16x16x32_bf16 v[122:125], v[148:151], v[188:191], v[122:125]
	v_mfma_f32_16x16x32_bf16 v[90:93], v[156:159], v[188:191], v[90:93]
	v_mfma_f32_16x16x32_bf16 v[118:121], v[148:151], v[196:199], v[118:121]
	v_mfma_f32_16x16x32_bf16 v[86:89], v[156:159], v[196:199], v[86:89]
	v_mfma_f32_16x16x32_bf16 v[114:117], v[148:151], v[204:207], v[114:117]
	v_mfma_f32_16x16x32_bf16 v[82:85], v[156:159], v[204:207], v[82:85]
	s_setprio 0
	s_setprio 1
	v_mfma_f32_16x16x32_bf16 v[70:73], v[160:163], v[176:179], v[70:73]
	v_mfma_f32_16x16x32_bf16 v[42:45], v[168:171], v[176:179], v[42:45]
	v_mfma_f32_16x16x32_bf16 v[62:65], v[160:163], v[184:187], v[62:65]
	v_mfma_f32_16x16x32_bf16 v[34:37], v[168:171], v[184:187], v[34:37]
	v_mfma_f32_16x16x32_bf16 v[54:57], v[160:163], v[192:195], v[54:57]
	v_mfma_f32_16x16x32_bf16 v[26:29], v[168:171], v[192:195], v[26:29]
	v_mfma_f32_16x16x32_bf16 v[50:53], v[160:163], v[200:203], v[50:53]
	v_mfma_f32_16x16x32_bf16 v[18:21], v[168:171], v[200:203], v[18:21]
	v_mfma_f32_16x16x32_bf16 v[70:73], v[164:167], v[180:183], v[70:73]
	v_mfma_f32_16x16x32_bf16 v[42:45], v[172:175], v[180:183], v[42:45]
	v_mfma_f32_16x16x32_bf16 v[62:65], v[164:167], v[188:191], v[62:65]
	v_mfma_f32_16x16x32_bf16 v[34:37], v[172:175], v[188:191], v[34:37]
	v_mfma_f32_16x16x32_bf16 v[54:57], v[164:167], v[196:199], v[54:57]
	v_mfma_f32_16x16x32_bf16 v[26:29], v[172:175], v[196:199], v[26:29]
	v_mfma_f32_16x16x32_bf16 v[50:53], v[164:167], v[204:207], v[50:53]
	v_mfma_f32_16x16x32_bf16 v[18:21], v[172:175], v[204:207], v[18:21]
	s_setprio 0
	s_barrier
	s_mov_b32 m0, s29
	v_lshl_add_u64 v[208:209], s[40:41], 0, v[132:133]
	s_add_u32 s46, s40, 0x160000
	ds_read_b128 v[176:179], v141 offset:16384
	ds_read_b128 v[180:183], v141 offset:17408
	ds_read_b128 v[184:187], v141 offset:18432
	ds_read_b128 v[188:191], v141 offset:19456
	ds_read_b128 v[192:195], v141 offset:20480
	ds_read_b128 v[196:199], v141 offset:21504
	ds_read_b128 v[200:203], v141 offset:22528
	ds_read_b128 v[204:207], v141 offset:23552
	global_load_lds_dwordx4 v[208:209], off
	v_lshl_add_u64 v[210:211], s[40:41], 0, v[130:131]
	s_mov_b32 m0, s30
	s_addc_u32 s47, s41, 0
	global_load_lds_dwordx4 v[210:211], off
	v_lshl_add_u64 v[212:213], s[46:47], 0, v[132:133]
	s_mov_b32 m0, s31
	v_lshl_add_u64 v[214:215], s[42:43], 0, v[130:131]
	global_load_lds_dwordx4 v[212:213], off
	v_lshl_add_u64 v[212:213], s[46:47], 0, v[130:131]
	s_mov_b32 m0, s33
	s_nop 0
	global_load_lds_dwordx4 v[212:213], off
	v_lshl_add_u64 v[212:213], s[42:43], 0, v[132:133]
	s_mov_b32 m0, s14
	s_nop 0
	global_load_lds_dwordx4 v[212:213], off
	s_mov_b32 m0, s18
	s_nop 0
	global_load_lds_dwordx4 v[214:215], off
	s_waitcnt vmcnt(8)
	s_waitcnt lgkmcnt(0)
	s_barrier
; #define PG8_STAGE(bufoff, gbase, voff) do { _Pragma("unroll") for (int _i = 0; _i < 2; ++_i) \
;         __builtin_amdgcn_global_load_lds((const unsigned*)((const char*)(gbase) + (voff)[_i]), (LAS unsigned*)(lds + (bufoff) + ldsw + _i * 8192), 16, 0, 0); } while (0)
; #define PG8_LDA(dst, b, h) do { _Pragma("unroll") for (int m = 0; m < 4; ++m) _Pragma("unroll") for (int k = 0; k < 2; ++k) dst[m][k] = *(const LAS bf16x8*)(lds + PG8_SA(b, h) + aoff + m * 2048 + k * 1024); } while (0)
; #define PG8_LDB(dst, b, h) do { _Pragma("unroll") for (int n = 0; n < 2; ++n) _Pragma("unroll") for (int k = 0; k < 2; ++k) dst[n][k] = *(const LAS bf16x8*)(lds + PG8_SB(b, h) + boff + n * 2048 + k * 1024); } while (0)
; #define PG8_MMA(ai, bj, At, Bt) do { __builtin_amdgcn_s_setprio(1); _Pragma("unroll") for (int m = 0; m < 4; ++m) _Pragma("unroll") for (int n = 0; n < 2; ++n) _Pragma("unroll") for (int k = 0; k < 2; ++k) \
;         acc[ai][bj][m][n] = __builtin_amdgcn_mfma_f32_16x16x32_bf16(Bt[n][k], At[m][k], acc[ai][bj][m][n], 0, 0, 0); __builtin_amdgcn_s_setprio(0); } while (0)
; #define PG8_WAIT_V(n) asm volatile("s_waitcnt vmcnt(" #n ")" ::: "memory")
; #define PG8_WAIT_L(n) asm volatile("s_waitcnt lgkmcnt(" #n ")" ::: "memory")
; #define PG8_BAR __builtin_amdgcn_s_barrier()
; #define PG8_SCHED __builtin_amdgcn_sched_barrier(0)
; template <class Epi, class Sched, bool ALIGN_EPI = false, bool SP2 = false>
; __device__ __forceinline__ void gemm_phase(LAS unsigned char* lds, const Gemm g, const Sched& S, const Epi& E) {
;     ...
;             PG8_WAIT_V(8); PG8_WAIT_L(0); PG8_BAR; PG8_MMA(1, 0, At, B0); PG8_MMA(1, 1, At, B1); PG8_BAR; PG8_SCHED;
;             PG8_LDB(B0, 1, 0); PG8_LDB(B1, 1, 1); PG8_SCHED; PG8_LDA(At, 1, 0); PG8_STAGE(PG8_SA(0, 1), a2 + hstep, voffA);
;             PG8_WAIT_V(8); PG8_WAIT_L(0); PG8_BAR; PG8_MMA(0, 0, At, B0); PG8_MMA(0, 1, At, B1); PG8_BAR; PG8_SCHED;
	s_setprio 1
	v_mfma_f32_16x16x32_bf16 v[110:113], v[144:147], v[176:179], v[110:113]
	v_mfma_f32_16x16x32_bf16 v[78:81], v[152:155], v[176:179], v[78:81]
	v_mfma_f32_16x16x32_bf16 v[106:109], v[144:147], v[184:187], v[106:109]
	v_mfma_f32_16x16x32_bf16 v[74:77], v[152:155], v[184:187], v[74:77]
	v_mfma_f32_16x16x32_bf16 v[102:105], v[144:147], v[192:195], v[102:105]
	v_mfma_f32_16x16x32_bf16 v[66:69], v[152:155], v[192:195], v[66:69]
	v_mfma_f32_16x16x32_bf16 v[98:101], v[144:147], v[200:203], v[98:101]
	v_mfma_f32_16x16x32_bf16 v[58:61], v[152:155], v[200:203], v[58:61]
	v_mfma_f32_16x16x32_bf16 v[110:113], v[148:151], v[180:183], v[110:113]
	v_mfma_f32_16x16x32_bf16 v[78:81], v[156:159], v[180:183], v[78:81]
	v_mfma_f32_16x16x32_bf16 v[106:109], v[148:151], v[188:191], v[106:109]
	v_mfma_f32_16x16x32_bf16 v[74:77], v[156:159], v[188:191], v[74:77]
	v_mfma_f32_16x16x32_bf16 v[102:105], v[148:151], v[196:199], v[102:105]
	v_mfma_f32_16x16x32_bf16 v[66:69], v[156:159], v[196:199], v[66:69]
	v_mfma_f32_16x16x32_bf16 v[98:101], v[148:151], v[204:207], v[98:101]
	v_mfma_f32_16x16x32_bf16 v[58:61], v[156:159], v[204:207], v[58:61]
	s_setprio 0
	s_setprio 1
	v_mfma_f32_16x16x32_bf16 v[46:49], v[160:163], v[176:179], v[46:49]
	v_mfma_f32_16x16x32_bf16 v[14:17], v[168:171], v[176:179], v[14:17]
	v_mfma_f32_16x16x32_bf16 v[38:41], v[160:163], v[184:187], v[38:41]
	v_mfma_f32_16x16x32_bf16 v[10:13], v[168:171], v[184:187], v[10:13]
	v_mfma_f32_16x16x32_bf16 v[30:33], v[160:163], v[192:195], v[30:33]
	v_mfma_f32_16x16x32_bf16 v[6:9], v[168:171], v[192:195], v[6:9]
	v_mfma_f32_16x16x32_bf16 v[22:25], v[160:163], v[200:203], v[22:25]
	v_mfma_f32_16x16x32_bf16 v[2:5], v[168:171], v[200:203], v[2:5]
	v_mfma_f32_16x16x32_bf16 v[46:49], v[164:167], v[180:183], v[46:49]
	v_mfma_f32_16x16x32_bf16 v[14:17], v[172:175], v[180:183], v[14:17]
	v_mfma_f32_16x16x32_bf16 v[38:41], v[164:167], v[188:191], v[38:41]
	v_mfma_f32_16x16x32_bf16 v[10:13], v[172:175], v[188:191], v[10:13]
	v_mfma_f32_16x16x32_bf16 v[30:33], v[164:167], v[196:199], v[30:33]
	v_mfma_f32_16x16x32_bf16 v[6:9], v[172:175], v[196:199], v[6:9]
	v_mfma_f32_16x16x32_bf16 v[22:25], v[164:167], v[204:207], v[22:25]
	v_mfma_f32_16x16x32_bf16 v[2:5], v[172:175], v[204:207], v[2:5]
	s_setprio 0
	s_barrier
	ds_read_b128 v[144:147], v142
	ds_read_b128 v[148:151], v142 offset:1024
	ds_read_b128 v[152:155], v142 offset:2048
	ds_read_b128 v[156:159], v142 offset:3072
	ds_read_b128 v[160:163], v143
	ds_read_b128 v[164:167], v143 offset:1024
	ds_read_b128 v[168:171], v143 offset:2048
	ds_read_b128 v[172:175], v143 offset:3072
	s_add_u32 s42, s42, 0x160000
	s_addc_u32 s43, s43, 0
	s_mov_b32 m0, s19
	v_lshl_add_u64 v[216:217], s[42:43], 0, v[132:133]
	ds_read_b128 v[176:179], v141 offset:32768
	ds_read_b128 v[180:183], v141 offset:33792
	ds_read_b128 v[184:187], v141 offset:34816
	ds_read_b128 v[188:191], v141 offset:35840
	ds_read_b128 v[192:195], v141 offset:36864
	ds_read_b128 v[196:199], v141 offset:37888
	ds_read_b128 v[200:203], v141 offset:38912
	ds_read_b128 v[204:207], v141 offset:39936
	global_load_lds_dwordx4 v[216:217], off
	v_lshl_add_u64 v[216:217], s[42:43], 0, v[130:131]
	s_mov_b32 m0, s20
	s_nop 0
	global_load_lds_dwordx4 v[216:217], off
	s_waitcnt vmcnt(8)
	s_waitcnt lgkmcnt(0)
	s_barrier
	s_setprio 1
	v_mfma_f32_16x16x32_bf16 v[126:129], v[144:147], v[176:179], v[126:129]
	v_mfma_f32_16x16x32_bf16 v[94:97], v[152:155], v[176:179], v[94:97]
	v_mfma_f32_16x16x32_bf16 v[122:125], v[144:147], v[184:187], v[122:125]
	v_mfma_f32_16x16x32_bf16 v[90:93], v[152:155], v[184:187], v[90:93]
	v_mfma_f32_16x16x32_bf16 v[118:121], v[144:147], v[192:195], v[118:121]
	v_mfma_f32_16x16x32_bf16 v[86:89], v[152:155], v[192:195], v[86:89]
	v_mfma_f32_16x16x32_bf16 v[114:117], v[144:147], v[200:203], v[114:117]
	v_mfma_f32_16x16x32_bf16 v[82:85], v[152:155], v[200:203], v[82:85]
	v_mfma_f32_16x16x32_bf16 v[126:129], v[148:151], v[180:183], v[126:129]
	v_mfma_f32_16x16x32_bf16 v[94:97], v[156:159], v[180:183], v[94:97]
	v_mfma_f32_16x16x32_bf16 v[122:125], v[148:151], v[188:191], v[122:125]
	v_mfma_f32_16x16x32_bf16 v[90:93], v[156:159], v[188:191], v[90:93]
	v_mfma_f32_16x16x32_bf16 v[118:121], v[148:151], v[196:199], v[118:121]
	v_mfma_f32_16x16x32_bf16 v[86:89], v[156:159], v[196:199], v[86:89]
	v_mfma_f32_16x16x32_bf16 v[114:117], v[148:151], v[204:207], v[114:117]
	v_mfma_f32_16x16x32_bf16 v[82:85], v[156:159], v[204:207], v[82:85]
	s_setprio 0
	s_setprio 1
	v_mfma_f32_16x16x32_bf16 v[70:73], v[160:163], v[176:179], v[70:73]
	v_mfma_f32_16x16x32_bf16 v[42:45], v[168:171], v[176:179], v[42:45]
	v_mfma_f32_16x16x32_bf16 v[62:65], v[160:163], v[184:187], v[62:65]
	v_mfma_f32_16x16x32_bf16 v[34:37], v[168:171], v[184:187], v[34:37]
	v_mfma_f32_16x16x32_bf16 v[54:57], v[160:163], v[192:195], v[54:57]
	v_mfma_f32_16x16x32_bf16 v[26:29], v[168:171], v[192:195], v[26:29]
	v_mfma_f32_16x16x32_bf16 v[50:53], v[160:163], v[200:203], v[50:53]
	v_mfma_f32_16x16x32_bf16 v[18:21], v[168:171], v[200:203], v[18:21]
	v_mfma_f32_16x16x32_bf16 v[70:73], v[164:167], v[180:183], v[70:73]
	v_mfma_f32_16x16x32_bf16 v[42:45], v[172:175], v[180:183], v[42:45]
	v_mfma_f32_16x16x32_bf16 v[62:65], v[164:167], v[188:191], v[62:65]
	v_mfma_f32_16x16x32_bf16 v[34:37], v[172:175], v[188:191], v[34:37]
	v_mfma_f32_16x16x32_bf16 v[54:57], v[164:167], v[196:199], v[54:57]
	v_mfma_f32_16x16x32_bf16 v[26:29], v[172:175], v[196:199], v[26:29]
	v_mfma_f32_16x16x32_bf16 v[50:53], v[164:167], v[204:207], v[50:53]
	v_mfma_f32_16x16x32_bf16 v[18:21], v[172:175], v[204:207], v[18:21]
	s_setprio 0
	s_barrier
; #define PG8_STAGE(bufoff, gbase, voff) do { _Pragma("unroll") for (int _i = 0; _i < 2; ++_i) \
;         __builtin_amdgcn_global_load_lds((const unsigned*)((const char*)(gbase) + (voff)[_i]), (LAS unsigned*)(lds + (bufoff) + ldsw + _i * 8192), 16, 0, 0); } while (0)
; #define PG8_LDA(dst, b, h) do { _Pragma("unroll") for (int m = 0; m < 4; ++m) _Pragma("unroll") for (int k = 0; k < 2; ++k) dst[m][k] = *(const LAS bf16x8*)(lds + PG8_SA(b, h) + aoff + m * 2048 + k * 1024); } while (0)
; #define PG8_MMA(ai, bj, At, Bt) do { __builtin_amdgcn_s_setprio(1); _Pragma("unroll") for (int m = 0; m < 4; ++m) _Pragma("unroll") for (int n = 0; n < 2; ++n) _Pragma("unroll") for (int k = 0; k < 2; ++k) \
;         acc[ai][bj][m][n] = __builtin_amdgcn_mfma_f32_16x16x32_bf16(Bt[n][k], At[m][k], acc[ai][bj][m][n], 0, 0, 0); __builtin_amdgcn_s_setprio(0); } while (0)
; #define PG8_WAIT_V(n) asm volatile("s_waitcnt vmcnt(" #n ")" ::: "memory")
; #define PG8_WAIT_L(n) asm volatile("s_waitcnt lgkmcnt(" #n ")" ::: "memory")
; #define PG8_BAR __builtin_amdgcn_s_barrier()
; #define PG8_SCHED __builtin_amdgcn_sched_barrier(0)
; template <class Epi, class Sched, bool ALIGN_EPI = false, bool SP2 = false>
; __device__ __forceinline__ void gemm_phase(LAS unsigned char* lds, const Gemm g, const Sched& S, const Epi& E) {
;     ...
;         for (int t = 0; t < nt; t += 2) {
;     ...
;             PG8_LDA(At, 1, 1); PG8_STAGE(PG8_SB(1, 0), b3, voffB); PG8_STAGE(PG8_SB(1, 1), b3 + hstepB, voffB); PG8_STAGE(PG8_SA(1, 0), a3, voffA);
;             PG8_WAIT_V(8); PG8_WAIT_L(0); PG8_BAR; PG8_MMA(1, 0, At, B0); PG8_MMA(1, 1, At, B1); PG8_BAR; PG8_SCHED;
	s_mov_b32 m0, s34
	v_lshl_add_u64 v[208:209], v[208:209], 0, s[10:11]
	s_add_u32 s40, s40, 0x160080
	ds_read_b128 v[176:179], v141 offset:49152
	ds_read_b128 v[180:183], v141 offset:50176
	ds_read_b128 v[184:187], v141 offset:51200
	ds_read_b128 v[188:191], v141 offset:52224
	ds_read_b128 v[192:195], v141 offset:53248
	ds_read_b128 v[196:199], v141 offset:54272
	ds_read_b128 v[200:203], v141 offset:55296
	ds_read_b128 v[204:207], v141 offset:56320
	global_load_lds_dwordx4 v[208:209], off
	v_lshl_add_u64 v[208:209], v[210:211], 0, s[10:11]
	s_mov_b32 m0, s35
	s_addc_u32 s41, s41, 0
	global_load_lds_dwordx4 v[208:209], off
	v_lshl_add_u64 v[208:209], s[40:41], 0, v[132:133]
	s_mov_b32 m0, s36
	s_nop 0
	global_load_lds_dwordx4 v[208:209], off
	v_lshl_add_u64 v[208:209], s[40:41], 0, v[130:131]
	s_mov_b32 m0, s37
	s_nop 0
	global_load_lds_dwordx4 v[208:209], off
	v_lshl_add_u64 v[208:209], v[212:213], 0, s[10:11]
	s_mov_b32 m0, s22
	s_nop 0
	global_load_lds_dwordx4 v[208:209], off
	v_lshl_add_u64 v[208:209], v[214:215], 0, s[10:11]
	s_mov_b32 m0, s23
	s_nop 0
	global_load_lds_dwordx4 v[208:209], off
	s_waitcnt vmcnt(8)
	s_waitcnt lgkmcnt(0)
	s_barrier
	s_setprio 1
	v_mfma_f32_16x16x32_bf16 v[110:113], v[144:147], v[176:179], v[110:113]
	v_mfma_f32_16x16x32_bf16 v[78:81], v[152:155], v[176:179], v[78:81]
	v_mfma_f32_16x16x32_bf16 v[106:109], v[144:147], v[184:187], v[106:109]
	v_mfma_f32_16x16x32_bf16 v[74:77], v[152:155], v[184:187], v[74:77]
	v_mfma_f32_16x16x32_bf16 v[102:105], v[144:147], v[192:195], v[102:105]
	v_mfma_f32_16x16x32_bf16 v[66:69], v[152:155], v[192:195], v[66:69]
	v_mfma_f32_16x16x32_bf16 v[98:101], v[144:147], v[200:203], v[98:101]
	v_mfma_f32_16x16x32_bf16 v[58:61], v[152:155], v[200:203], v[58:61]
	v_mfma_f32_16x16x32_bf16 v[110:113], v[148:151], v[180:183], v[110:113]
	v_mfma_f32_16x16x32_bf16 v[78:81], v[156:159], v[180:183], v[78:81]
	v_mfma_f32_16x16x32_bf16 v[106:109], v[148:151], v[188:191], v[106:109]
	v_mfma_f32_16x16x32_bf16 v[74:77], v[156:159], v[188:191], v[74:77]
	v_mfma_f32_16x16x32_bf16 v[102:105], v[148:151], v[196:199], v[102:105]
	v_mfma_f32_16x16x32_bf16 v[66:69], v[156:159], v[196:199], v[66:69]
	v_mfma_f32_16x16x32_bf16 v[98:101], v[148:151], v[204:207], v[98:101]
	v_mfma_f32_16x16x32_bf16 v[58:61], v[156:159], v[204:207], v[58:61]
	s_setprio 0
	s_setprio 1
	v_mfma_f32_16x16x32_bf16 v[46:49], v[160:163], v[176:179], v[46:49]
	v_mfma_f32_16x16x32_bf16 v[14:17], v[168:171], v[176:179], v[14:17]
	v_mfma_f32_16x16x32_bf16 v[38:41], v[160:163], v[184:187], v[38:41]
	v_mfma_f32_16x16x32_bf16 v[10:13], v[168:171], v[184:187], v[10:13]
	v_mfma_f32_16x16x32_bf16 v[30:33], v[160:163], v[192:195], v[30:33]
	v_mfma_f32_16x16x32_bf16 v[6:9], v[168:171], v[192:195], v[6:9]
	v_mfma_f32_16x16x32_bf16 v[22:25], v[160:163], v[200:203], v[22:25]
	v_mfma_f32_16x16x32_bf16 v[2:5], v[168:171], v[200:203], v[2:5]
	v_mfma_f32_16x16x32_bf16 v[46:49], v[164:167], v[180:183], v[46:49]
	v_mfma_f32_16x16x32_bf16 v[14:17], v[172:175], v[180:183], v[14:17]
	v_mfma_f32_16x16x32_bf16 v[38:41], v[164:167], v[188:191], v[38:41]
	v_mfma_f32_16x16x32_bf16 v[10:13], v[172:175], v[188:191], v[10:13]
	v_mfma_f32_16x16x32_bf16 v[30:33], v[164:167], v[196:199], v[30:33]
	v_mfma_f32_16x16x32_bf16 v[6:9], v[172:175], v[196:199], v[6:9]
	v_mfma_f32_16x16x32_bf16 v[22:25], v[164:167], v[204:207], v[22:25]
	v_mfma_f32_16x16x32_bf16 v[2:5], v[172:175], v[204:207], v[2:5]
	s_setprio 0
	s_barrier
	s_add_u32 s16, s16, 0x100
	s_addc_u32 s17, s17, 0
	s_cmp_ge_u32 s44, s21
	s_mov_b32 s40, s44
	s_cbranch_scc0 .LBB0_288
	v_readlane_b32 s30, v252, 2
	s_cmpk_lt_u32 s13, 0x100
	v_readlane_b32 s31, v252, 3
	s_mov_b64 s[34:35], s[78:79]
	s_cbranch_scc0 .LBB0_291
	s_barrier

; #define PG8_STAGE(bufoff, gbase, voff) do { _Pragma("unroll") for (int _i = 0; _i < 2; ++_i) \
;         __builtin_amdgcn_global_load_lds((const unsigned*)((const char*)(gbase) + (voff)[_i]), (LAS unsigned*)(lds + (bufoff) + ldsw + _i * 8192), 16, 0, 0); } while (0)
; #define PG8_LDA(dst, b, h) do { _Pragma("unroll") for (int m = 0; m < 4; ++m) _Pragma("unroll") for (int k = 0; k < 2; ++k) dst[m][k] = *(const LAS bf16x8*)(lds + PG8_SA(b, h) + aoff + m * 2048 + k * 1024); } while (0)
; #define PG8_LDB(dst, b, h) do { _Pragma("unroll") for (int n = 0; n < 2; ++n) _Pragma("unroll") for (int k = 0; k < 2; ++k) dst[n][k] = *(const LAS bf16x8*)(lds + PG8_SB(b, h) + boff + n * 2048 + k * 1024); } while (0)
; #define PG8_MMA(ai, bj, At, Bt) do { __builtin_amdgcn_s_setprio(1); _Pragma("unroll") for (int m = 0; m < 4; ++m) _Pragma("unroll") for (int n = 0; n < 2; ++n) _Pragma("unroll") for (int k = 0; k < 2; ++k) \
;         acc[ai][bj][m][n] = __builtin_amdgcn_mfma_f32_16x16x32_bf16(Bt[n][k], At[m][k], acc[ai][bj][m][n], 0, 0, 0); __builtin_amdgcn_s_setprio(0); } while (0)
; #define PG8_WAIT_V(n) asm volatile("s_waitcnt vmcnt(" #n ")" ::: "memory")
; #define PG8_WAIT_L(n) asm volatile("s_waitcnt lgkmcnt(" #n ")" ::: "memory")
; #define PG8_BAR __builtin_amdgcn_s_barrier()
; #define PG8_SCHED __builtin_amdgcn_sched_barrier(0)
; template <class Epi, class Sched, bool ALIGN_EPI = false, bool SP2 = false>
; __device__ __forceinline__ void gemm_phase(LAS unsigned char* lds, const Gemm g, const Sched& S, const Epi& E) {
;     ...
;             if constexpr (SP2) {
;             PG8_LDB(B0, 0, 0); PG8_LDB(B1, 0, 1); PG8_SCHED; PG8_LDA(At, 0, 0); PG8_STAGE(PG8_SA(1, 1), a1 + hstep, voffA);
;             PG8_WAIT_V(8); PG8_WAIT_L(0); PG8_BAR; PG8_MMA(0, 0, At, B0); PG8_MMA(0, 1, At, B1); PG8_BAR; PG8_SCHED;
;             PG8_LDA(At, 0, 1); PG8_STAGE(PG8_SB(0, 0), b2, voffB); PG8_STAGE(PG8_SB(0, 1), b2 + hstepB, voffB); PG8_STAGE(PG8_SA(0, 0), a2, voffA);
;             PG8_WAIT_V(8); PG8_WAIT_L(0); PG8_BAR; PG8_MMA(1, 0, At, B0); PG8_MMA(1, 1, At, B1); PG8_BAR; PG8_SCHED;
.Lprio_317:
	ds_read_b128 v[130:133], v196
	ds_read_b128 v[134:137], v196 offset:1024
	ds_read_b128 v[138:141], v196 offset:2048
	ds_read_b128 v[142:145], v196 offset:3072
	ds_read_b128 v[166:169], v197
	ds_read_b128 v[170:173], v197 offset:1024
	ds_read_b128 v[174:177], v197 offset:2048
	ds_read_b128 v[178:181], v197 offset:3072
	s_add_u32 s54, s16, 0x100
	s_addc_u32 s55, s17, 0
	s_cmpk_eq_i32 s13, 0x54
	s_cselect_b32 s59, s3, s55
	s_cselect_b32 s58, s2, s54
	s_cselect_b32 s57, s53, s12
	s_cselect_b32 s56, s52, s5
	v_lshl_add_u64 v[190:191], s[16:17], 0, v[158:159]
	s_add_i32 m0, s29, 0xc000
	ds_read_b128 v[182:185], v198
	ds_read_b128 v[186:189], v198 offset:1024
	ds_read_b128 v[202:205], v198 offset:2048
	ds_read_b128 v[206:209], v198 offset:3072
	ds_read_b128 v[210:213], v198 offset:4096
	ds_read_b128 v[214:217], v198 offset:5120
	ds_read_b128 v[218:221], v198 offset:6144
	ds_read_b128 v[222:225], v198 offset:7168
	global_load_lds_dwordx4 v[190:191], off
	v_lshl_add_u64 v[190:191], s[16:17], 0, v[160:161]
	s_add_i32 m0, s29, 0xe000
	s_nop 0
	global_load_lds_dwordx4 v[190:191], off
	s_waitcnt lgkmcnt(0)
	s_barrier
	v_mfma_f32_16x16x32_bf16 v[126:129], v[130:133], v[182:185], 0
	v_mfma_f32_16x16x32_bf16 v[122:125], v[138:141], v[182:185], 0
	v_mfma_f32_16x16x32_bf16 v[110:113], v[130:133], v[202:205], 0
	v_mfma_f32_16x16x32_bf16 v[106:109], v[138:141], v[202:205], 0
	v_mfma_f32_16x16x32_bf16 v[94:97], v[130:133], v[210:213], 0
	v_mfma_f32_16x16x32_bf16 v[90:93], v[138:141], v[210:213], 0
	v_mfma_f32_16x16x32_bf16 v[78:81], v[130:133], v[218:221], 0
	v_mfma_f32_16x16x32_bf16 v[74:77], v[138:141], v[218:221], 0
	v_mfma_f32_16x16x32_bf16 v[126:129], v[134:137], v[186:189], v[126:129]
	v_mfma_f32_16x16x32_bf16 v[122:125], v[142:145], v[186:189], v[122:125]
	v_mfma_f32_16x16x32_bf16 v[110:113], v[134:137], v[206:209], v[110:113]
	v_mfma_f32_16x16x32_bf16 v[106:109], v[142:145], v[206:209], v[106:109]
	v_mfma_f32_16x16x32_bf16 v[94:97], v[134:137], v[214:217], v[94:97]
	v_mfma_f32_16x16x32_bf16 v[90:93], v[142:145], v[214:217], v[90:93]
	v_mfma_f32_16x16x32_bf16 v[78:81], v[134:137], v[222:225], v[78:81]
	v_mfma_f32_16x16x32_bf16 v[74:77], v[142:145], v[222:225], v[74:77]
	v_mfma_f32_16x16x32_bf16 v[118:121], v[166:169], v[182:185], 0
	v_mfma_f32_16x16x32_bf16 v[114:117], v[174:177], v[182:185], 0
	v_mfma_f32_16x16x32_bf16 v[102:105], v[166:169], v[202:205], 0
	v_mfma_f32_16x16x32_bf16 v[98:101], v[174:177], v[202:205], 0
	v_mfma_f32_16x16x32_bf16 v[86:89], v[166:169], v[210:213], 0
	v_mfma_f32_16x16x32_bf16 v[82:85], v[174:177], v[210:213], 0
	v_mfma_f32_16x16x32_bf16 v[70:73], v[166:169], v[218:221], 0
	v_mfma_f32_16x16x32_bf16 v[66:69], v[174:177], v[218:221], 0
	v_mfma_f32_16x16x32_bf16 v[118:121], v[170:173], v[186:189], v[118:121]
	v_mfma_f32_16x16x32_bf16 v[114:117], v[178:181], v[186:189], v[114:117]
	v_mfma_f32_16x16x32_bf16 v[102:105], v[170:173], v[206:209], v[102:105]
	v_mfma_f32_16x16x32_bf16 v[98:101], v[178:181], v[206:209], v[98:101]
	v_mfma_f32_16x16x32_bf16 v[86:89], v[170:173], v[214:217], v[86:89]
	v_mfma_f32_16x16x32_bf16 v[82:85], v[178:181], v[214:217], v[82:85]
	v_mfma_f32_16x16x32_bf16 v[70:73], v[170:173], v[222:225], v[70:73]
	v_mfma_f32_16x16x32_bf16 v[66:69], v[178:181], v[222:225], v[66:69]
	s_barrier
	s_add_i32 s14, s64, s28
	v_lshl_add_u64 v[190:191], s[56:57], 0, v[148:149]
	s_mov_b32 m0, s14
	ds_read_b128 v[182:185], v198 offset:16384
	ds_read_b128 v[186:189], v198 offset:17408
	ds_read_b128 v[202:205], v198 offset:18432
	ds_read_b128 v[206:209], v198 offset:19456
	ds_read_b128 v[210:213], v198 offset:20480
	ds_read_b128 v[214:217], v198 offset:21504
	ds_read_b128 v[218:221], v198 offset:22528
	ds_read_b128 v[222:225], v198 offset:23552
	global_load_lds_dwordx4 v[190:191], off
	s_add_i32 m0, s14, 0x2000
	s_add_u32 s14, s56, 0x58000
	v_lshl_add_u64 v[226:227], s[56:57], 0, v[152:153]
	s_addc_u32 s15, s57, 0
	s_add_i32 s16, s65, s28
	global_load_lds_dwordx4 v[226:227], off
	v_lshl_add_u64 v[228:229], s[14:15], 0, v[148:149]
	s_mov_b32 m0, s16
	v_lshl_add_u64 v[230:231], s[58:59], 0, v[150:151]
	global_load_lds_dwordx4 v[228:229], off
	v_lshl_add_u64 v[228:229], s[14:15], 0, v[152:153]
	s_add_i32 m0, s16, 0x2000
	s_nop 0
	global_load_lds_dwordx4 v[228:229], off
	v_lshl_add_u64 v[228:229], s[58:59], 0, v[146:147]
	s_mov_b32 m0, s29
	s_nop 0
	global_load_lds_dwordx4 v[228:229], off
	s_mov_b32 m0, s30
	s_nop 0
	global_load_lds_dwordx4 v[230:231], off
	s_waitcnt lgkmcnt(0)
	s_barrier
	v_mfma_f32_16x16x32_bf16 v[62:65], v[130:133], v[182:185], 0
	v_mfma_f32_16x16x32_bf16 v[58:61], v[138:141], v[182:185], 0
	v_mfma_f32_16x16x32_bf16 v[46:49], v[130:133], v[202:205], 0
	v_mfma_f32_16x16x32_bf16 v[42:45], v[138:141], v[202:205], 0
	v_mfma_f32_16x16x32_bf16 v[30:33], v[130:133], v[210:213], 0
	v_mfma_f32_16x16x32_bf16 v[26:29], v[138:141], v[210:213], 0
	v_mfma_f32_16x16x32_bf16 v[14:17], v[130:133], v[218:221], 0
	v_mfma_f32_16x16x32_bf16 v[10:13], v[138:141], v[218:221], 0
	v_mfma_f32_16x16x32_bf16 v[62:65], v[134:137], v[186:189], v[62:65]
	v_mfma_f32_16x16x32_bf16 v[58:61], v[142:145], v[186:189], v[58:61]
	v_mfma_f32_16x16x32_bf16 v[46:49], v[134:137], v[206:209], v[46:49]
	v_mfma_f32_16x16x32_bf16 v[42:45], v[142:145], v[206:209], v[42:45]
	v_mfma_f32_16x16x32_bf16 v[30:33], v[134:137], v[214:217], v[30:33]
	v_mfma_f32_16x16x32_bf16 v[26:29], v[142:145], v[214:217], v[26:29]
	v_mfma_f32_16x16x32_bf16 v[14:17], v[134:137], v[222:225], v[14:17]
	v_mfma_f32_16x16x32_bf16 v[10:13], v[142:145], v[222:225], v[10:13]
	v_mfma_f32_16x16x32_bf16 v[54:57], v[166:169], v[182:185], 0
	v_mfma_f32_16x16x32_bf16 v[50:53], v[174:177], v[182:185], 0
	v_mfma_f32_16x16x32_bf16 v[38:41], v[166:169], v[202:205], 0
	v_mfma_f32_16x16x32_bf16 v[34:37], v[174:177], v[202:205], 0
	v_mfma_f32_16x16x32_bf16 v[22:25], v[166:169], v[210:213], 0
	v_mfma_f32_16x16x32_bf16 v[18:21], v[174:177], v[210:213], 0
	v_mfma_f32_16x16x32_bf16 v[6:9], v[166:169], v[218:221], 0
	v_mfma_f32_16x16x32_bf16 v[2:5], v[174:177], v[218:221], 0
	v_mfma_f32_16x16x32_bf16 v[54:57], v[170:173], v[186:189], v[54:57]
	v_mfma_f32_16x16x32_bf16 v[50:53], v[178:181], v[186:189], v[50:53]
	v_mfma_f32_16x16x32_bf16 v[38:41], v[170:173], v[206:209], v[38:41]
	v_mfma_f32_16x16x32_bf16 v[34:37], v[178:181], v[206:209], v[34:37]
	v_mfma_f32_16x16x32_bf16 v[22:25], v[170:173], v[214:217], v[22:25]
	v_mfma_f32_16x16x32_bf16 v[18:21], v[178:181], v[214:217], v[18:21]
	v_mfma_f32_16x16x32_bf16 v[6:9], v[170:173], v[222:225], v[6:9]
	v_mfma_f32_16x16x32_bf16 v[2:5], v[178:181], v[222:225], v[2:5]
	s_barrier
; #define PG8_STAGE(bufoff, gbase, voff) do { _Pragma("unroll") for (int _i = 0; _i < 2; ++_i) \
;         __builtin_amdgcn_global_load_lds((const unsigned*)((const char*)(gbase) + (voff)[_i]), (LAS unsigned*)(lds + (bufoff) + ldsw + _i * 8192), 16, 0, 0); } while (0)
; #define PG8_LDA(dst, b, h) do { _Pragma("unroll") for (int m = 0; m < 4; ++m) _Pragma("unroll") for (int k = 0; k < 2; ++k) dst[m][k] = *(const LAS bf16x8*)(lds + PG8_SA(b, h) + aoff + m * 2048 + k * 1024); } while (0)
; #define PG8_LDB(dst, b, h) do { _Pragma("unroll") for (int n = 0; n < 2; ++n) _Pragma("unroll") for (int k = 0; k < 2; ++k) dst[n][k] = *(const LAS bf16x8*)(lds + PG8_SB(b, h) + boff + n * 2048 + k * 1024); } while (0)
; #define PG8_MMA(ai, bj, At, Bt) do { __builtin_amdgcn_s_setprio(1); _Pragma("unroll") for (int m = 0; m < 4; ++m) _Pragma("unroll") for (int n = 0; n < 2; ++n) _Pragma("unroll") for (int k = 0; k < 2; ++k) \
;         acc[ai][bj][m][n] = __builtin_amdgcn_mfma_f32_16x16x32_bf16(Bt[n][k], At[m][k], acc[ai][bj][m][n], 0, 0, 0); __builtin_amdgcn_s_setprio(0); } while (0)
; #define PG8_WAIT_V(n) asm volatile("s_waitcnt vmcnt(" #n ")" ::: "memory")
; #define PG8_WAIT_L(n) asm volatile("s_waitcnt lgkmcnt(" #n ")" ::: "memory")
; #define PG8_BAR __builtin_amdgcn_s_barrier()
; #define PG8_SCHED __builtin_amdgcn_sched_barrier(0)
; template <class Epi, class Sched, bool ALIGN_EPI = false, bool SP2 = false>
; __device__ __forceinline__ void gemm_phase(LAS unsigned char* lds, const Gemm g, const Sched& S, const Epi& E) {
;     ...
;         for (int t = 0; t < nt; t += 2) {
;             const bool last = (t == nt - 2);
;             const char* a1 = cA + (size_t)(t + 1) * kstep;
;             const char* a2 = last ? nA : cA + (size_t)(t + 2) * kstep; const char* b2 = last ? nB : cB + (size_t)(t + 2) * kstep;
;     ...
;             PG8_LDB(B0, 1, 0); PG8_LDB(B1, 1, 1); PG8_SCHED; PG8_LDA(At, 1, 0); PG8_STAGE(PG8_SA(0, 1), a2 + hstep, voffA);
;             PG8_WAIT_V(8); PG8_WAIT_L(0); PG8_BAR; PG8_MMA(0, 0, At, B0); PG8_MMA(0, 1, At, B1); PG8_BAR; PG8_SCHED;
;             PG8_LDA(At, 1, 1); PG8_STAGE(PG8_SB(1, 0), b3, voffB); PG8_STAGE(PG8_SB(1, 1), b3 + hstepB, voffB); PG8_STAGE(PG8_SA(1, 0), a3, voffA);
;             PG8_WAIT_V(8); PG8_WAIT_L(0); PG8_BAR; PG8_MMA(1, 0, At, B0); PG8_MMA(1, 1, At, B1); PG8_BAR; PG8_SCHED;
	s_add_i32 s16, 0, 0x18000
	s_add_i32 s17, 0, 0x1c000
	v_add_u32_e32 v142, s16, v1
	v_add_u32_e32 v154, s17, v1
	ds_read_b128 v[130:133], v142
	ds_read_b128 v[134:137], v142 offset:1024
	ds_read_b128 v[138:141], v142 offset:2048
	ds_read_b128 v[142:145], v142 offset:3072
	ds_read_b128 v[166:169], v154
	ds_read_b128 v[170:173], v154 offset:1024
	ds_read_b128 v[174:177], v154 offset:2048
	ds_read_b128 v[178:181], v154 offset:3072
	s_add_u32 s14, s58, 0x160000
	s_addc_u32 s15, s59, 0
	s_mov_b32 m0, s31
	v_lshl_add_u64 v[232:233], s[14:15], 0, v[146:147]
	ds_read_b128 v[182:185], v198 offset:32768
	ds_read_b128 v[186:189], v198 offset:33792
	ds_read_b128 v[202:205], v198 offset:34816
	ds_read_b128 v[206:209], v198 offset:35840
	ds_read_b128 v[210:213], v198 offset:36864
	ds_read_b128 v[214:217], v198 offset:37888
	ds_read_b128 v[218:221], v198 offset:38912
	ds_read_b128 v[222:225], v198 offset:39936
	global_load_lds_dwordx4 v[232:233], off
	v_lshl_add_u64 v[232:233], s[14:15], 0, v[150:151]
	s_mov_b32 m0, s33
	s_nop 0
	global_load_lds_dwordx4 v[232:233], off
	s_waitcnt vmcnt(8)
	s_waitcnt lgkmcnt(0)
	s_barrier
	v_mfma_f32_16x16x32_bf16 v[126:129], v[130:133], v[182:185], v[126:129]
	v_mfma_f32_16x16x32_bf16 v[122:125], v[138:141], v[182:185], v[122:125]
	v_mfma_f32_16x16x32_bf16 v[110:113], v[130:133], v[202:205], v[110:113]
	v_mfma_f32_16x16x32_bf16 v[106:109], v[138:141], v[202:205], v[106:109]
	v_mfma_f32_16x16x32_bf16 v[94:97], v[130:133], v[210:213], v[94:97]
	v_mfma_f32_16x16x32_bf16 v[90:93], v[138:141], v[210:213], v[90:93]
	v_mfma_f32_16x16x32_bf16 v[78:81], v[130:133], v[218:221], v[78:81]
	v_mfma_f32_16x16x32_bf16 v[74:77], v[138:141], v[218:221], v[74:77]
	v_mfma_f32_16x16x32_bf16 v[126:129], v[134:137], v[186:189], v[126:129]
	v_mfma_f32_16x16x32_bf16 v[122:125], v[142:145], v[186:189], v[122:125]
	v_mfma_f32_16x16x32_bf16 v[110:113], v[134:137], v[206:209], v[110:113]
	v_mfma_f32_16x16x32_bf16 v[106:109], v[142:145], v[206:209], v[106:109]
	v_mfma_f32_16x16x32_bf16 v[94:97], v[134:137], v[214:217], v[94:97]
	v_mfma_f32_16x16x32_bf16 v[90:93], v[142:145], v[214:217], v[90:93]
	v_mfma_f32_16x16x32_bf16 v[78:81], v[134:137], v[222:225], v[78:81]
	v_mfma_f32_16x16x32_bf16 v[74:77], v[142:145], v[222:225], v[74:77]
	v_mfma_f32_16x16x32_bf16 v[118:121], v[166:169], v[182:185], v[118:121]
	v_mfma_f32_16x16x32_bf16 v[114:117], v[174:177], v[182:185], v[114:117]
	v_mfma_f32_16x16x32_bf16 v[102:105], v[166:169], v[202:205], v[102:105]
	v_mfma_f32_16x16x32_bf16 v[98:101], v[174:177], v[202:205], v[98:101]
	v_mfma_f32_16x16x32_bf16 v[86:89], v[166:169], v[210:213], v[86:89]
	v_mfma_f32_16x16x32_bf16 v[82:85], v[174:177], v[210:213], v[82:85]
	v_mfma_f32_16x16x32_bf16 v[70:73], v[166:169], v[218:221], v[70:73]
	v_mfma_f32_16x16x32_bf16 v[66:69], v[174:177], v[218:221], v[66:69]
	v_mfma_f32_16x16x32_bf16 v[118:121], v[170:173], v[186:189], v[118:121]
	v_mfma_f32_16x16x32_bf16 v[114:117], v[178:181], v[186:189], v[114:117]
	v_mfma_f32_16x16x32_bf16 v[102:105], v[170:173], v[206:209], v[102:105]
	v_mfma_f32_16x16x32_bf16 v[98:101], v[178:181], v[206:209], v[98:101]
	v_mfma_f32_16x16x32_bf16 v[86:89], v[170:173], v[214:217], v[86:89]
	v_mfma_f32_16x16x32_bf16 v[82:85], v[178:181], v[214:217], v[82:85]
	v_mfma_f32_16x16x32_bf16 v[70:73], v[170:173], v[222:225], v[70:73]
	v_mfma_f32_16x16x32_bf16 v[66:69], v[178:181], v[222:225], v[66:69]
	s_barrier
	s_add_i32 s14, s16, s28
	v_lshl_add_u64 v[190:191], v[190:191], 0, s[48:49]
	s_mov_b32 m0, s14
	ds_read_b128 v[182:185], v198 offset:49152
	ds_read_b128 v[186:189], v198 offset:50176
	ds_read_b128 v[202:205], v198 offset:51200
	ds_read_b128 v[206:209], v198 offset:52224
	ds_read_b128 v[210:213], v198 offset:53248
	ds_read_b128 v[214:217], v198 offset:54272
	ds_read_b128 v[218:221], v198 offset:55296
	ds_read_b128 v[222:225], v198 offset:56320
	global_load_lds_dwordx4 v[190:191], off
	s_add_i32 m0, s14, 0x2000
	s_add_u32 s14, s56, 0x58080
	v_lshl_add_u64 v[190:191], v[226:227], 0, s[48:49]
	s_addc_u32 s15, s57, 0
	s_add_i32 s16, s17, s28
	global_load_lds_dwordx4 v[190:191], off
	v_lshl_add_u64 v[190:191], s[14:15], 0, v[148:149]
	s_mov_b32 m0, s16
	s_nop 0
	global_load_lds_dwordx4 v[190:191], off
	v_lshl_add_u64 v[190:191], s[14:15], 0, v[152:153]
	s_add_i32 m0, s16, 0x2000
	s_nop 0
	global_load_lds_dwordx4 v[190:191], off
	v_lshl_add_u64 v[190:191], v[228:229], 0, s[48:49]
	s_mov_b32 m0, s61
	s_nop 0
	global_load_lds_dwordx4 v[190:191], off
	v_lshl_add_u64 v[190:191], v[230:231], 0, s[48:49]
	s_mov_b32 m0, s62
	s_nop 0
	global_load_lds_dwordx4 v[190:191], off
	s_waitcnt vmcnt(8)
	s_waitcnt lgkmcnt(0)
	s_barrier
	v_mfma_f32_16x16x32_bf16 v[62:65], v[130:133], v[182:185], v[62:65]
	v_mfma_f32_16x16x32_bf16 v[58:61], v[138:141], v[182:185], v[58:61]
	v_mfma_f32_16x16x32_bf16 v[46:49], v[130:133], v[202:205], v[46:49]
	v_mfma_f32_16x16x32_bf16 v[42:45], v[138:141], v[202:205], v[42:45]
	v_mfma_f32_16x16x32_bf16 v[30:33], v[130:133], v[210:213], v[30:33]
	v_mfma_f32_16x16x32_bf16 v[26:29], v[138:141], v[210:213], v[26:29]
	v_mfma_f32_16x16x32_bf16 v[14:17], v[130:133], v[218:221], v[14:17]
	v_mfma_f32_16x16x32_bf16 v[10:13], v[138:141], v[218:221], v[10:13]
	v_mfma_f32_16x16x32_bf16 v[62:65], v[134:137], v[186:189], v[62:65]
	v_mfma_f32_16x16x32_bf16 v[58:61], v[142:145], v[186:189], v[58:61]
	v_mfma_f32_16x16x32_bf16 v[46:49], v[134:137], v[206:209], v[46:49]
	v_mfma_f32_16x16x32_bf16 v[42:45], v[142:145], v[206:209], v[42:45]
	v_mfma_f32_16x16x32_bf16 v[30:33], v[134:137], v[214:217], v[30:33]
	v_mfma_f32_16x16x32_bf16 v[26:29], v[142:145], v[214:217], v[26:29]
	v_mfma_f32_16x16x32_bf16 v[14:17], v[134:137], v[222:225], v[14:17]
	v_mfma_f32_16x16x32_bf16 v[10:13], v[142:145], v[222:225], v[10:13]
	v_mfma_f32_16x16x32_bf16 v[54:57], v[166:169], v[182:185], v[54:57]
	v_mfma_f32_16x16x32_bf16 v[50:53], v[174:177], v[182:185], v[50:53]
	v_mfma_f32_16x16x32_bf16 v[38:41], v[166:169], v[202:205], v[38:41]
	v_mfma_f32_16x16x32_bf16 v[34:37], v[174:177], v[202:205], v[34:37]
	v_mfma_f32_16x16x32_bf16 v[22:25], v[166:169], v[210:213], v[22:25]
	v_mfma_f32_16x16x32_bf16 v[18:21], v[174:177], v[210:213], v[18:21]
	v_mfma_f32_16x16x32_bf16 v[6:9], v[166:169], v[218:221], v[6:9]
	v_mfma_f32_16x16x32_bf16 v[2:5], v[174:177], v[218:221], v[2:5]
	v_mfma_f32_16x16x32_bf16 v[54:57], v[170:173], v[186:189], v[54:57]
	v_mfma_f32_16x16x32_bf16 v[50:53], v[178:181], v[186:189], v[50:53]
	v_mfma_f32_16x16x32_bf16 v[38:41], v[170:173], v[206:209], v[38:41]
	v_mfma_f32_16x16x32_bf16 v[34:37], v[178:181], v[206:209], v[34:37]
	v_mfma_f32_16x16x32_bf16 v[22:25], v[170:173], v[214:217], v[22:25]
	v_mfma_f32_16x16x32_bf16 v[18:21], v[178:181], v[214:217], v[18:21]
	v_mfma_f32_16x16x32_bf16 v[6:9], v[170:173], v[222:225], v[6:9]
	v_mfma_f32_16x16x32_bf16 v[2:5], v[178:181], v[222:225], v[2:5]
	s_barrier
	s_add_i32 s13, s13, 2
	s_add_u32 s5, s5, 0x100
	s_addc_u32 s12, s12, 0
	s_cmpk_gt_u32 s13, 0x55
	s_mov_b64 s[16:17], s[54:55]
; #define PG8_STAGE(bufoff, gbase, voff) do { _Pragma("unroll") for (int _i = 0; _i < 2; ++_i) \
;         __builtin_amdgcn_global_load_lds((const unsigned*)((const char*)(gbase) + (voff)[_i]), (LAS unsigned*)(lds + (bufoff) + ldsw + _i * 8192), 16, 0, 0); } while (0)
; #define PG8_LDA(dst, b, h) do { _Pragma("unroll") for (int m = 0; m < 4; ++m) _Pragma("unroll") for (int k = 0; k < 2; ++k) dst[m][k] = *(const LAS bf16x8*)(lds + PG8_SA(b, h) + aoff + m * 2048 + k * 1024); } while (0)
; #define PG8_LDB(dst, b, h) do { _Pragma("unroll") for (int n = 0; n < 2; ++n) _Pragma("unroll") for (int k = 0; k < 2; ++k) dst[n][k] = *(const LAS bf16x8*)(lds + PG8_SB(b, h) + boff + n * 2048 + k * 1024); } while (0)
; #define PG8_MMA(ai, bj, At, Bt) do { __builtin_amdgcn_s_setprio(1); _Pragma("unroll") for (int m = 0; m < 4; ++m) _Pragma("unroll") for (int n = 0; n < 2; ++n) _Pragma("unroll") for (int k = 0; k < 2; ++k) \
;         acc[ai][bj][m][n] = __builtin_amdgcn_mfma_f32_16x16x32_bf16(Bt[n][k], At[m][k], acc[ai][bj][m][n], 0, 0, 0); __builtin_amdgcn_s_setprio(0); } while (0)
; #define PG8_WAIT_V(n) asm volatile("s_waitcnt vmcnt(" #n ")" ::: "memory")
; #define PG8_WAIT_L(n) asm volatile("s_waitcnt lgkmcnt(" #n ")" ::: "memory")
; template <class Epi, class Sched, bool ALIGN_EPI = false, bool SP2 = false>
; __device__ __forceinline__ void gemm_phase(LAS unsigned char* lds, const Gemm g, const Sched& S, const Epi& E) {
;     ...
;         for (int t = 0; t < nt; t += 2) {
;             const bool last = (t == nt - 2);
;             const char* a1 = cA + (size_t)(t + 1) * kstep;
;             const char* a2 = last ? nA : cA + (size_t)(t + 2) * kstep; const char* b2 = last ? nB : cB + (size_t)(t + 2) * kstep;
;             const char* a3 = a2 + kstep; const char* b3 = b2 + kstep;
;             if (last && has_next) S.a_ready(nxt);
;             if constexpr (SP2) {
;             PG8_LDB(B0, 0, 0); PG8_LDB(B1, 0, 1); PG8_SCHED; PG8_LDA(At, 0, 0); PG8_STAGE(PG8_SA(1, 1), a1 + hstep, voffA);
;             PG8_WAIT_V(8); PG8_WAIT_L(0); PG8_BAR; PG8_MMA(0, 0, At, B0); PG8_MMA(0, 1, At, B1); PG8_BAR; PG8_SCHED;
;             PG8_LDA(At, 0, 1); PG8_STAGE(PG8_SB(0, 0), b2, voffB); PG8_STAGE(PG8_SB(0, 1), b2 + hstepB, voffB); PG8_STAGE(PG8_SA(0, 0), a2, voffA);
;             PG8_WAIT_V(8); PG8_WAIT_L(0); PG8_BAR; PG8_MMA(1, 0, At, B0); PG8_MMA(1, 1, At, B1); PG8_BAR; PG8_SCHED;
.LBB0_317:
	ds_read_b128 v[130:133], v196
	ds_read_b128 v[134:137], v196 offset:1024
	ds_read_b128 v[138:141], v196 offset:2048
	ds_read_b128 v[142:145], v196 offset:3072
	ds_read_b128 v[166:169], v197
	ds_read_b128 v[170:173], v197 offset:1024
	ds_read_b128 v[174:177], v197 offset:2048
	ds_read_b128 v[178:181], v197 offset:3072
	s_add_u32 s54, s16, 0x100
	s_addc_u32 s55, s17, 0
	s_cmpk_eq_i32 s13, 0x54
	s_cselect_b32 s59, s3, s55
	s_cselect_b32 s58, s2, s54
	s_cselect_b32 s57, s53, s12
	s_cselect_b32 s56, s52, s5
	v_lshl_add_u64 v[190:191], s[16:17], 0, v[158:159]
	s_add_i32 m0, s29, 0xc000
	ds_read_b128 v[182:185], v198
	ds_read_b128 v[186:189], v198 offset:1024
	ds_read_b128 v[202:205], v198 offset:2048
	ds_read_b128 v[206:209], v198 offset:3072
	ds_read_b128 v[210:213], v198 offset:4096
	ds_read_b128 v[214:217], v198 offset:5120
	ds_read_b128 v[218:221], v198 offset:6144
	ds_read_b128 v[222:225], v198 offset:7168
	global_load_lds_dwordx4 v[190:191], off
	v_lshl_add_u64 v[190:191], s[16:17], 0, v[160:161]
	s_add_i32 m0, s29, 0xe000
	s_nop 0
	global_load_lds_dwordx4 v[190:191], off
	s_waitcnt vmcnt(8)
	s_waitcnt lgkmcnt(0)
	s_barrier
	v_mfma_f32_16x16x32_bf16 v[126:129], v[130:133], v[182:185], v[126:129]
	v_mfma_f32_16x16x32_bf16 v[122:125], v[138:141], v[182:185], v[122:125]
	v_mfma_f32_16x16x32_bf16 v[110:113], v[130:133], v[202:205], v[110:113]
	v_mfma_f32_16x16x32_bf16 v[106:109], v[138:141], v[202:205], v[106:109]
	v_mfma_f32_16x16x32_bf16 v[94:97], v[130:133], v[210:213], v[94:97]
	v_mfma_f32_16x16x32_bf16 v[90:93], v[138:141], v[210:213], v[90:93]
	v_mfma_f32_16x16x32_bf16 v[78:81], v[130:133], v[218:221], v[78:81]
	v_mfma_f32_16x16x32_bf16 v[74:77], v[138:141], v[218:221], v[74:77]
	v_mfma_f32_16x16x32_bf16 v[126:129], v[134:137], v[186:189], v[126:129]
	v_mfma_f32_16x16x32_bf16 v[122:125], v[142:145], v[186:189], v[122:125]
	v_mfma_f32_16x16x32_bf16 v[110:113], v[134:137], v[206:209], v[110:113]
	v_mfma_f32_16x16x32_bf16 v[106:109], v[142:145], v[206:209], v[106:109]
	v_mfma_f32_16x16x32_bf16 v[94:97], v[134:137], v[214:217], v[94:97]
	v_mfma_f32_16x16x32_bf16 v[90:93], v[142:145], v[214:217], v[90:93]
	v_mfma_f32_16x16x32_bf16 v[78:81], v[134:137], v[222:225], v[78:81]
	v_mfma_f32_16x16x32_bf16 v[74:77], v[142:145], v[222:225], v[74:77]
	v_mfma_f32_16x16x32_bf16 v[118:121], v[166:169], v[182:185], v[118:121]
	v_mfma_f32_16x16x32_bf16 v[114:117], v[174:177], v[182:185], v[114:117]
	v_mfma_f32_16x16x32_bf16 v[102:105], v[166:169], v[202:205], v[102:105]
	v_mfma_f32_16x16x32_bf16 v[98:101], v[174:177], v[202:205], v[98:101]
	v_mfma_f32_16x16x32_bf16 v[86:89], v[166:169], v[210:213], v[86:89]
	v_mfma_f32_16x16x32_bf16 v[82:85], v[174:177], v[210:213], v[82:85]
	v_mfma_f32_16x16x32_bf16 v[70:73], v[166:169], v[218:221], v[70:73]
	v_mfma_f32_16x16x32_bf16 v[66:69], v[174:177], v[218:221], v[66:69]
	v_mfma_f32_16x16x32_bf16 v[118:121], v[170:173], v[186:189], v[118:121]
	v_mfma_f32_16x16x32_bf16 v[114:117], v[178:181], v[186:189], v[114:117]
	v_mfma_f32_16x16x32_bf16 v[102:105], v[170:173], v[206:209], v[102:105]
	v_mfma_f32_16x16x32_bf16 v[98:101], v[178:181], v[206:209], v[98:101]
	v_mfma_f32_16x16x32_bf16 v[86:89], v[170:173], v[214:217], v[86:89]
	v_mfma_f32_16x16x32_bf16 v[82:85], v[178:181], v[214:217], v[82:85]
	v_mfma_f32_16x16x32_bf16 v[70:73], v[170:173], v[222:225], v[70:73]
	v_mfma_f32_16x16x32_bf16 v[66:69], v[178:181], v[222:225], v[66:69]
	s_barrier
	s_add_i32 s14, s64, s28
	v_lshl_add_u64 v[190:191], s[56:57], 0, v[148:149]
	s_mov_b32 m0, s14
	ds_read_b128 v[182:185], v198 offset:16384
	ds_read_b128 v[186:189], v198 offset:17408
	ds_read_b128 v[202:205], v198 offset:18432
	ds_read_b128 v[206:209], v198 offset:19456
	ds_read_b128 v[210:213], v198 offset:20480
	ds_read_b128 v[214:217], v198 offset:21504
	ds_read_b128 v[218:221], v198 offset:22528
	ds_read_b128 v[222:225], v198 offset:23552
	global_load_lds_dwordx4 v[190:191], off
	s_add_i32 m0, s14, 0x2000
	s_add_u32 s14, s56, 0x58000
	v_lshl_add_u64 v[226:227], s[56:57], 0, v[152:153]
	s_addc_u32 s15, s57, 0
	s_add_i32 s16, s65, s28
	global_load_lds_dwordx4 v[226:227], off
	v_lshl_add_u64 v[228:229], s[14:15], 0, v[148:149]
	s_mov_b32 m0, s16
	v_lshl_add_u64 v[230:231], s[58:59], 0, v[150:151]
	global_load_lds_dwordx4 v[228:229], off
	v_lshl_add_u64 v[228:229], s[14:15], 0, v[152:153]
	s_add_i32 m0, s16, 0x2000
	s_nop 0
	global_load_lds_dwordx4 v[228:229], off
	v_lshl_add_u64 v[228:229], s[58:59], 0, v[146:147]
	s_mov_b32 m0, s29
	s_nop 0
	global_load_lds_dwordx4 v[228:229], off
	s_mov_b32 m0, s30
	s_nop 0
	global_load_lds_dwordx4 v[230:231], off
	s_waitcnt vmcnt(8)
	s_waitcnt lgkmcnt(0)
	s_barrier
; #define PG8_STAGE(bufoff, gbase, voff) do { _Pragma("unroll") for (int _i = 0; _i < 2; ++_i) \
;         __builtin_amdgcn_global_load_lds((const unsigned*)((const char*)(gbase) + (voff)[_i]), (LAS unsigned*)(lds + (bufoff) + ldsw + _i * 8192), 16, 0, 0); } while (0)
; #define PG8_LDA(dst, b, h) do { _Pragma("unroll") for (int m = 0; m < 4; ++m) _Pragma("unroll") for (int k = 0; k < 2; ++k) dst[m][k] = *(const LAS bf16x8*)(lds + PG8_SA(b, h) + aoff + m * 2048 + k * 1024); } while (0)
; #define PG8_LDB(dst, b, h) do { _Pragma("unroll") for (int n = 0; n < 2; ++n) _Pragma("unroll") for (int k = 0; k < 2; ++k) dst[n][k] = *(const LAS bf16x8*)(lds + PG8_SB(b, h) + boff + n * 2048 + k * 1024); } while (0)
; #define PG8_MMA(ai, bj, At, Bt) do { __builtin_amdgcn_s_setprio(1); _Pragma("unroll") for (int m = 0; m < 4; ++m) _Pragma("unroll") for (int n = 0; n < 2; ++n) _Pragma("unroll") for (int k = 0; k < 2; ++k) \
;         acc[ai][bj][m][n] = __builtin_amdgcn_mfma_f32_16x16x32_bf16(Bt[n][k], At[m][k], acc[ai][bj][m][n], 0, 0, 0); __builtin_amdgcn_s_setprio(0); } while (0)
; #define PG8_WAIT_V(n) asm volatile("s_waitcnt vmcnt(" #n ")" ::: "memory")
; #define PG8_WAIT_L(n) asm volatile("s_waitcnt lgkmcnt(" #n ")" ::: "memory")
; #define PG8_BAR __builtin_amdgcn_s_barrier()
; template <class Epi, class Sched, bool ALIGN_EPI = false, bool SP2 = false>
; __device__ __forceinline__ void gemm_phase(LAS unsigned char* lds, const Gemm g, const Sched& S, const Epi& E) {
;     ...
;             PG8_WAIT_V(8); PG8_WAIT_L(0); PG8_BAR; PG8_MMA(0, 0, At, B0); PG8_MMA(0, 1, At, B1); PG8_BAR; PG8_SCHED;
;             PG8_LDA(At, 0, 1); PG8_STAGE(PG8_SB(0, 0), b2, voffB); PG8_STAGE(PG8_SB(0, 1), b2 + hstepB, voffB); PG8_STAGE(PG8_SA(0, 0), a2, voffA);
;             PG8_WAIT_V(8); PG8_WAIT_L(0); PG8_BAR; PG8_MMA(1, 0, At, B0); PG8_MMA(1, 1, At, B1); PG8_BAR; PG8_SCHED;
;             PG8_LDB(B0, 1, 0); PG8_LDB(B1, 1, 1); PG8_SCHED; PG8_LDA(At, 1, 0); PG8_STAGE(PG8_SA(0, 1), a2 + hstep, voffA);
;             PG8_WAIT_V(8); PG8_WAIT_L(0); PG8_BAR; PG8_MMA(0, 0, At, B0); PG8_MMA(0, 1, At, B1); PG8_BAR; PG8_SCHED;
;             PG8_LDA(At, 1, 1); PG8_STAGE(PG8_SB(1, 0), b3, voffB); PG8_STAGE(PG8_SB(1, 1), b3 + hstepB, voffB); PG8_STAGE(PG8_SA(1, 0), a3, voffA);
;             PG8_WAIT_V(8); PG8_WAIT_L(0); PG8_BAR; PG8_MMA(1, 0, At, B0); PG8_MMA(1, 1, At, B1); PG8_BAR; PG8_SCHED;
	v_mfma_f32_16x16x32_bf16 v[62:65], v[130:133], v[182:185], v[62:65]
	v_mfma_f32_16x16x32_bf16 v[58:61], v[138:141], v[182:185], v[58:61]
	v_mfma_f32_16x16x32_bf16 v[46:49], v[130:133], v[202:205], v[46:49]
	v_mfma_f32_16x16x32_bf16 v[42:45], v[138:141], v[202:205], v[42:45]
	v_mfma_f32_16x16x32_bf16 v[30:33], v[130:133], v[210:213], v[30:33]
	v_mfma_f32_16x16x32_bf16 v[26:29], v[138:141], v[210:213], v[26:29]
	v_mfma_f32_16x16x32_bf16 v[14:17], v[130:133], v[218:221], v[14:17]
	v_mfma_f32_16x16x32_bf16 v[10:13], v[138:141], v[218:221], v[10:13]
	v_mfma_f32_16x16x32_bf16 v[62:65], v[134:137], v[186:189], v[62:65]
	v_mfma_f32_16x16x32_bf16 v[58:61], v[142:145], v[186:189], v[58:61]
	v_mfma_f32_16x16x32_bf16 v[46:49], v[134:137], v[206:209], v[46:49]
	v_mfma_f32_16x16x32_bf16 v[42:45], v[142:145], v[206:209], v[42:45]
	v_mfma_f32_16x16x32_bf16 v[30:33], v[134:137], v[214:217], v[30:33]
	v_mfma_f32_16x16x32_bf16 v[26:29], v[142:145], v[214:217], v[26:29]
	v_mfma_f32_16x16x32_bf16 v[14:17], v[134:137], v[222:225], v[14:17]
	v_mfma_f32_16x16x32_bf16 v[10:13], v[142:145], v[222:225], v[10:13]
	v_mfma_f32_16x16x32_bf16 v[54:57], v[166:169], v[182:185], v[54:57]
	v_mfma_f32_16x16x32_bf16 v[50:53], v[174:177], v[182:185], v[50:53]
	v_mfma_f32_16x16x32_bf16 v[38:41], v[166:169], v[202:205], v[38:41]
	v_mfma_f32_16x16x32_bf16 v[34:37], v[174:177], v[202:205], v[34:37]
	v_mfma_f32_16x16x32_bf16 v[22:25], v[166:169], v[210:213], v[22:25]
	v_mfma_f32_16x16x32_bf16 v[18:21], v[174:177], v[210:213], v[18:21]
	v_mfma_f32_16x16x32_bf16 v[6:9], v[166:169], v[218:221], v[6:9]
	v_mfma_f32_16x16x32_bf16 v[2:5], v[174:177], v[218:221], v[2:5]
	v_mfma_f32_16x16x32_bf16 v[54:57], v[170:173], v[186:189], v[54:57]
	v_mfma_f32_16x16x32_bf16 v[50:53], v[178:181], v[186:189], v[50:53]
	v_mfma_f32_16x16x32_bf16 v[38:41], v[170:173], v[206:209], v[38:41]
	v_mfma_f32_16x16x32_bf16 v[34:37], v[178:181], v[206:209], v[34:37]
	v_mfma_f32_16x16x32_bf16 v[22:25], v[170:173], v[214:217], v[22:25]
	v_mfma_f32_16x16x32_bf16 v[18:21], v[178:181], v[214:217], v[18:21]
	v_mfma_f32_16x16x32_bf16 v[6:9], v[170:173], v[222:225], v[6:9]
	v_mfma_f32_16x16x32_bf16 v[2:5], v[178:181], v[222:225], v[2:5]
	s_barrier
	s_add_i32 s16, 0, 0x18000
	s_add_i32 s17, 0, 0x1c000
	v_add_u32_e32 v142, s16, v1
	v_add_u32_e32 v154, s17, v1
	ds_read_b128 v[130:133], v142
	ds_read_b128 v[134:137], v142 offset:1024
	ds_read_b128 v[138:141], v142 offset:2048
	ds_read_b128 v[142:145], v142 offset:3072
	ds_read_b128 v[166:169], v154
	ds_read_b128 v[170:173], v154 offset:1024
	ds_read_b128 v[174:177], v154 offset:2048
	ds_read_b128 v[178:181], v154 offset:3072
	s_add_u32 s14, s58, 0x160000
	s_addc_u32 s15, s59, 0
	s_mov_b32 m0, s31
	v_lshl_add_u64 v[232:233], s[14:15], 0, v[146:147]
	ds_read_b128 v[182:185], v198 offset:32768
	ds_read_b128 v[186:189], v198 offset:33792
	ds_read_b128 v[202:205], v198 offset:34816
	ds_read_b128 v[206:209], v198 offset:35840
	ds_read_b128 v[210:213], v198 offset:36864
	ds_read_b128 v[214:217], v198 offset:37888
	ds_read_b128 v[218:221], v198 offset:38912
	ds_read_b128 v[222:225], v198 offset:39936
	global_load_lds_dwordx4 v[232:233], off
	v_lshl_add_u64 v[232:233], s[14:15], 0, v[150:151]
	s_mov_b32 m0, s33
	s_nop 0
	global_load_lds_dwordx4 v[232:233], off
	s_waitcnt vmcnt(8)
	s_waitcnt lgkmcnt(0)
	s_barrier
	v_mfma_f32_16x16x32_bf16 v[126:129], v[130:133], v[182:185], v[126:129]
	v_mfma_f32_16x16x32_bf16 v[122:125], v[138:141], v[182:185], v[122:125]
	v_mfma_f32_16x16x32_bf16 v[110:113], v[130:133], v[202:205], v[110:113]
	v_mfma_f32_16x16x32_bf16 v[106:109], v[138:141], v[202:205], v[106:109]
	v_mfma_f32_16x16x32_bf16 v[94:97], v[130:133], v[210:213], v[94:97]
	v_mfma_f32_16x16x32_bf16 v[90:93], v[138:141], v[210:213], v[90:93]
	v_mfma_f32_16x16x32_bf16 v[78:81], v[130:133], v[218:221], v[78:81]
	v_mfma_f32_16x16x32_bf16 v[74:77], v[138:141], v[218:221], v[74:77]
	v_mfma_f32_16x16x32_bf16 v[126:129], v[134:137], v[186:189], v[126:129]
	v_mfma_f32_16x16x32_bf16 v[122:125], v[142:145], v[186:189], v[122:125]
	v_mfma_f32_16x16x32_bf16 v[110:113], v[134:137], v[206:209], v[110:113]
	v_mfma_f32_16x16x32_bf16 v[106:109], v[142:145], v[206:209], v[106:109]
	v_mfma_f32_16x16x32_bf16 v[94:97], v[134:137], v[214:217], v[94:97]
	v_mfma_f32_16x16x32_bf16 v[90:93], v[142:145], v[214:217], v[90:93]
	v_mfma_f32_16x16x32_bf16 v[78:81], v[134:137], v[222:225], v[78:81]
	v_mfma_f32_16x16x32_bf16 v[74:77], v[142:145], v[222:225], v[74:77]
	v_mfma_f32_16x16x32_bf16 v[118:121], v[166:169], v[182:185], v[118:121]
	v_mfma_f32_16x16x32_bf16 v[114:117], v[174:177], v[182:185], v[114:117]
	v_mfma_f32_16x16x32_bf16 v[102:105], v[166:169], v[202:205], v[102:105]
	v_mfma_f32_16x16x32_bf16 v[98:101], v[174:177], v[202:205], v[98:101]
	v_mfma_f32_16x16x32_bf16 v[86:89], v[166:169], v[210:213], v[86:89]
	v_mfma_f32_16x16x32_bf16 v[82:85], v[174:177], v[210:213], v[82:85]
	v_mfma_f32_16x16x32_bf16 v[70:73], v[166:169], v[218:221], v[70:73]
	v_mfma_f32_16x16x32_bf16 v[66:69], v[174:177], v[218:221], v[66:69]
	v_mfma_f32_16x16x32_bf16 v[118:121], v[170:173], v[186:189], v[118:121]
	v_mfma_f32_16x16x32_bf16 v[114:117], v[178:181], v[186:189], v[114:117]
	v_mfma_f32_16x16x32_bf16 v[102:105], v[170:173], v[206:209], v[102:105]
	v_mfma_f32_16x16x32_bf16 v[98:101], v[178:181], v[206:209], v[98:101]
	v_mfma_f32_16x16x32_bf16 v[86:89], v[170:173], v[214:217], v[86:89]
	v_mfma_f32_16x16x32_bf16 v[82:85], v[178:181], v[214:217], v[82:85]
	v_mfma_f32_16x16x32_bf16 v[70:73], v[170:173], v[222:225], v[70:73]
	v_mfma_f32_16x16x32_bf16 v[66:69], v[178:181], v[222:225], v[66:69]
	s_barrier
; #define PG8_STAGE(bufoff, gbase, voff) do { _Pragma("unroll") for (int _i = 0; _i < 2; ++_i) \
;         __builtin_amdgcn_global_load_lds((const unsigned*)((const char*)(gbase) + (voff)[_i]), (LAS unsigned*)(lds + (bufoff) + ldsw + _i * 8192), 16, 0, 0); } while (0)
; #define PG8_LDA(dst, b, h) do { _Pragma("unroll") for (int m = 0; m < 4; ++m) _Pragma("unroll") for (int k = 0; k < 2; ++k) dst[m][k] = *(const LAS bf16x8*)(lds + PG8_SA(b, h) + aoff + m * 2048 + k * 1024); } while (0)
; #define PG8_MMA(ai, bj, At, Bt) do { __builtin_amdgcn_s_setprio(1); _Pragma("unroll") for (int m = 0; m < 4; ++m) _Pragma("unroll") for (int n = 0; n < 2; ++n) _Pragma("unroll") for (int k = 0; k < 2; ++k) \
;         acc[ai][bj][m][n] = __builtin_amdgcn_mfma_f32_16x16x32_bf16(Bt[n][k], At[m][k], acc[ai][bj][m][n], 0, 0, 0); __builtin_amdgcn_s_setprio(0); } while (0)
; #define PG8_WAIT_V(n) asm volatile("s_waitcnt vmcnt(" #n ")" ::: "memory")
; #define PG8_WAIT_L(n) asm volatile("s_waitcnt lgkmcnt(" #n ")" ::: "memory")
; #define PG8_BAR __builtin_amdgcn_s_barrier()
; #define PG8_SCHED __builtin_amdgcn_sched_barrier(0)
; template <class Epi, class Sched, bool ALIGN_EPI = false, bool SP2 = false>
; __device__ __forceinline__ void gemm_phase(LAS unsigned char* lds, const Gemm g, const Sched& S, const Epi& E) {
;     ...
;             PG8_LDA(At, 1, 1); PG8_STAGE(PG8_SB(1, 0), b3, voffB); PG8_STAGE(PG8_SB(1, 1), b3 + hstepB, voffB); PG8_STAGE(PG8_SA(1, 0), a3, voffA);
;             PG8_WAIT_V(8); PG8_WAIT_L(0); PG8_BAR; PG8_MMA(1, 0, At, B0); PG8_MMA(1, 1, At, B1); PG8_BAR; PG8_SCHED;
;     ...
;         if constexpr (ALIGN_EPI) { if (wr == 0) PG8_BAR; }
	s_add_i32 s14, s16, s28
	v_lshl_add_u64 v[190:191], v[190:191], 0, s[48:49]
	s_mov_b32 m0, s14
	ds_read_b128 v[182:185], v198 offset:49152
	ds_read_b128 v[186:189], v198 offset:50176
	ds_read_b128 v[202:205], v198 offset:51200
	ds_read_b128 v[206:209], v198 offset:52224
	ds_read_b128 v[210:213], v198 offset:53248
	ds_read_b128 v[214:217], v198 offset:54272
	ds_read_b128 v[218:221], v198 offset:55296
	ds_read_b128 v[222:225], v198 offset:56320
	global_load_lds_dwordx4 v[190:191], off
	s_add_i32 m0, s14, 0x2000
	s_add_u32 s14, s56, 0x58080
	v_lshl_add_u64 v[190:191], v[226:227], 0, s[48:49]
	s_addc_u32 s15, s57, 0
	s_add_i32 s16, s17, s28
	global_load_lds_dwordx4 v[190:191], off
	v_lshl_add_u64 v[190:191], s[14:15], 0, v[148:149]
	s_mov_b32 m0, s16
	s_nop 0
	global_load_lds_dwordx4 v[190:191], off
	v_lshl_add_u64 v[190:191], s[14:15], 0, v[152:153]
	s_add_i32 m0, s16, 0x2000
	s_nop 0
	global_load_lds_dwordx4 v[190:191], off
	v_lshl_add_u64 v[190:191], v[228:229], 0, s[48:49]
	s_mov_b32 m0, s61
	s_nop 0
	global_load_lds_dwordx4 v[190:191], off
	v_lshl_add_u64 v[190:191], v[230:231], 0, s[48:49]
	s_mov_b32 m0, s62
	s_nop 0
	global_load_lds_dwordx4 v[190:191], off
	s_waitcnt vmcnt(8)
	s_waitcnt lgkmcnt(0)
	s_barrier
	v_mfma_f32_16x16x32_bf16 v[62:65], v[130:133], v[182:185], v[62:65]
	v_mfma_f32_16x16x32_bf16 v[58:61], v[138:141], v[182:185], v[58:61]
	v_mfma_f32_16x16x32_bf16 v[46:49], v[130:133], v[202:205], v[46:49]
	v_mfma_f32_16x16x32_bf16 v[42:45], v[138:141], v[202:205], v[42:45]
	v_mfma_f32_16x16x32_bf16 v[30:33], v[130:133], v[210:213], v[30:33]
	v_mfma_f32_16x16x32_bf16 v[26:29], v[138:141], v[210:213], v[26:29]
	v_mfma_f32_16x16x32_bf16 v[14:17], v[130:133], v[218:221], v[14:17]
	v_mfma_f32_16x16x32_bf16 v[10:13], v[138:141], v[218:221], v[10:13]
	v_mfma_f32_16x16x32_bf16 v[62:65], v[134:137], v[186:189], v[62:65]
	v_mfma_f32_16x16x32_bf16 v[58:61], v[142:145], v[186:189], v[58:61]
	v_mfma_f32_16x16x32_bf16 v[46:49], v[134:137], v[206:209], v[46:49]
	v_mfma_f32_16x16x32_bf16 v[42:45], v[142:145], v[206:209], v[42:45]
	v_mfma_f32_16x16x32_bf16 v[30:33], v[134:137], v[214:217], v[30:33]
	v_mfma_f32_16x16x32_bf16 v[26:29], v[142:145], v[214:217], v[26:29]
	v_mfma_f32_16x16x32_bf16 v[14:17], v[134:137], v[222:225], v[14:17]
	v_mfma_f32_16x16x32_bf16 v[10:13], v[142:145], v[222:225], v[10:13]
	v_mfma_f32_16x16x32_bf16 v[54:57], v[166:169], v[182:185], v[54:57]
	v_mfma_f32_16x16x32_bf16 v[50:53], v[174:177], v[182:185], v[50:53]
	v_mfma_f32_16x16x32_bf16 v[38:41], v[166:169], v[202:205], v[38:41]
	v_mfma_f32_16x16x32_bf16 v[34:37], v[174:177], v[202:205], v[34:37]
	v_mfma_f32_16x16x32_bf16 v[22:25], v[166:169], v[210:213], v[22:25]
	v_mfma_f32_16x16x32_bf16 v[18:21], v[174:177], v[210:213], v[18:21]
	v_mfma_f32_16x16x32_bf16 v[6:9], v[166:169], v[218:221], v[6:9]
	v_mfma_f32_16x16x32_bf16 v[2:5], v[174:177], v[218:221], v[2:5]
	v_mfma_f32_16x16x32_bf16 v[54:57], v[170:173], v[186:189], v[54:57]
	v_mfma_f32_16x16x32_bf16 v[50:53], v[178:181], v[186:189], v[50:53]
	v_mfma_f32_16x16x32_bf16 v[38:41], v[170:173], v[206:209], v[38:41]
	v_mfma_f32_16x16x32_bf16 v[34:37], v[178:181], v[206:209], v[34:37]
	v_mfma_f32_16x16x32_bf16 v[22:25], v[170:173], v[214:217], v[22:25]
	v_mfma_f32_16x16x32_bf16 v[18:21], v[178:181], v[214:217], v[18:21]
	v_mfma_f32_16x16x32_bf16 v[6:9], v[170:173], v[222:225], v[6:9]
	v_mfma_f32_16x16x32_bf16 v[2:5], v[178:181], v[222:225], v[2:5]
	s_barrier
	s_add_i32 s13, s13, 2
	s_add_u32 s5, s5, 0x100
	s_addc_u32 s12, s12, 0
	s_cmpk_gt_u32 s13, 0x55
	s_mov_b64 s[16:17], s[54:55]
	s_cbranch_scc0 .LBB0_317
	s_setprio 0
	s_and_b64 vcc, exec, s[50:51]
	s_cbranch_vccz .LBB0_320
	s_barrier

; #define PG8_STAGE(bufoff, gbase, voff) do { _Pragma("unroll") for (int _i = 0; _i < 2; ++_i) \
;         __builtin_amdgcn_global_load_lds((const unsigned*)((const char*)(gbase) + (voff)[_i]), (LAS unsigned*)(lds + (bufoff) + ldsw + _i * 8192), 16, 0, 0); } while (0)
; #define PG8_LDA(dst, b, h) do { _Pragma("unroll") for (int m = 0; m < 4; ++m) _Pragma("unroll") for (int k = 0; k < 2; ++k) dst[m][k] = *(const LAS bf16x8*)(lds + PG8_SA(b, h) + aoff + m * 2048 + k * 1024); } while (0)
; #define PG8_LDB(dst, b, h) do { _Pragma("unroll") for (int n = 0; n < 2; ++n) _Pragma("unroll") for (int k = 0; k < 2; ++k) dst[n][k] = *(const LAS bf16x8*)(lds + PG8_SB(b, h) + boff + n * 2048 + k * 1024); } while (0)
; #define PG8_MMA(ai, bj, At, Bt) do { __builtin_amdgcn_s_setprio(1); _Pragma("unroll") for (int m = 0; m < 4; ++m) _Pragma("unroll") for (int n = 0; n < 2; ++n) _Pragma("unroll") for (int k = 0; k < 2; ++k) \
;         acc[ai][bj][m][n] = __builtin_amdgcn_mfma_f32_16x16x32_bf16(Bt[n][k], At[m][k], acc[ai][bj][m][n], 0, 0, 0); __builtin_amdgcn_s_setprio(0); } while (0)
; #define PG8_WAIT_V(n) asm volatile("s_waitcnt vmcnt(" #n ")" ::: "memory")
; #define PG8_WAIT_L(n) asm volatile("s_waitcnt lgkmcnt(" #n ")" ::: "memory")
; template <class Epi, class Sched, bool ALIGN_EPI = false, bool SP2 = false>
; __device__ __forceinline__ void gemm_phase(LAS unsigned char* lds, const Gemm g, const Sched& S, const Epi& E) {
;     ...
;         for (int t = 0; t < nt; t += 2) {
;             const bool last = (t == nt - 2);
;             const char* a1 = cA + (size_t)(t + 1) * kstep;
;             const char* a2 = last ? nA : cA + (size_t)(t + 2) * kstep; const char* b2 = last ? nB : cB + (size_t)(t + 2) * kstep;
;             const char* a3 = a2 + kstep; const char* b3 = b2 + kstep;
;             if (last && has_next) S.a_ready(nxt);
;             if constexpr (SP2) {
;             PG8_LDB(B0, 0, 0); PG8_LDB(B1, 0, 1); PG8_SCHED; PG8_LDA(At, 0, 0); PG8_STAGE(PG8_SA(1, 1), a1 + hstep, voffA);
;             PG8_WAIT_V(8); PG8_WAIT_L(0); PG8_BAR; PG8_MMA(0, 0, At, B0); PG8_MMA(0, 1, At, B1); PG8_BAR; PG8_SCHED;
;             PG8_LDA(At, 0, 1); PG8_STAGE(PG8_SB(0, 0), b2, voffB); PG8_STAGE(PG8_SB(0, 1), b2 + hstepB, voffB); PG8_STAGE(PG8_SA(0, 0), a2, voffA);
;             PG8_WAIT_V(8); PG8_WAIT_L(0); PG8_BAR; PG8_MMA(1, 0, At, B0); PG8_MMA(1, 1, At, B1); PG8_BAR; PG8_SCHED;
.Lprio_535:
	ds_read_b128 v[34:37], v203
	ds_read_b128 v[38:41], v203 offset:1024
	ds_read_b128 v[42:45], v203 offset:2048
	ds_read_b128 v[46:49], v203 offset:3072
	s_waitcnt vmcnt(0)
	ds_read_b128 v[98:101], v204
	ds_read_b128 v[102:105], v204 offset:1024
	ds_read_b128 v[106:109], v204 offset:2048
	ds_read_b128 v[110:113], v204 offset:3072
	s_add_u32 s21, s16, 0xfff80080
	s_addc_u32 s22, s17, -1
	s_cmp_eq_u32 s20, 28
	s_cselect_b32 s59, s0, s22
	s_cselect_b32 s58, s3, s21
	s_cselect_b32 s49, s14, s19
	s_cselect_b32 s48, s15, s18
	v_lshl_add_u64 v[182:183], s[16:17], 0, v[172:173]
	s_add_i32 m0, s30, 0xc000
	ds_read_b128 v[212:215], v205
	ds_read_b128 v[216:219], v205 offset:1024
	ds_read_b128 v[220:223], v205 offset:2048
	ds_read_b128 v[224:227], v205 offset:3072
	ds_read_b128 v[228:231], v205 offset:4096
	ds_read_b128 v[232:235], v205 offset:5120
	ds_read_b128 v[236:239], v205 offset:6144
	ds_read_b128 v[240:243], v205 offset:7168
	global_load_lds_dwordx4 v[182:183], off
	v_lshl_add_u64 v[182:183], s[16:17], 0, v[174:175]
	s_add_i32 m0, s30, 0xe000
	s_nop 0
	global_load_lds_dwordx4 v[182:183], off
	s_waitcnt lgkmcnt(0)
	s_barrier
	v_mfma_f32_16x16x32_bf16 v[158:161], v[34:37], v[212:215], 0
	v_mfma_f32_16x16x32_bf16 v[154:157], v[42:45], v[212:215], 0
	v_mfma_f32_16x16x32_bf16 v[142:145], v[34:37], v[220:223], 0
	v_mfma_f32_16x16x32_bf16 v[138:141], v[42:45], v[220:223], 0
	v_mfma_f32_16x16x32_bf16 v[126:129], v[34:37], v[228:231], 0
	v_mfma_f32_16x16x32_bf16 v[122:125], v[42:45], v[228:231], 0
	v_mfma_f32_16x16x32_bf16 v[94:97], v[34:37], v[236:239], 0
	v_mfma_f32_16x16x32_bf16 v[90:93], v[42:45], v[236:239], 0
	v_mfma_f32_16x16x32_bf16 v[158:161], v[38:41], v[216:219], v[158:161]
	v_mfma_f32_16x16x32_bf16 v[154:157], v[46:49], v[216:219], v[154:157]
	v_mfma_f32_16x16x32_bf16 v[142:145], v[38:41], v[224:227], v[142:145]
	v_mfma_f32_16x16x32_bf16 v[138:141], v[46:49], v[224:227], v[138:141]
	v_mfma_f32_16x16x32_bf16 v[126:129], v[38:41], v[232:235], v[126:129]
	v_mfma_f32_16x16x32_bf16 v[122:125], v[46:49], v[232:235], v[122:125]
	v_mfma_f32_16x16x32_bf16 v[94:97], v[38:41], v[240:243], v[94:97]
	v_mfma_f32_16x16x32_bf16 v[90:93], v[46:49], v[240:243], v[90:93]
	v_mfma_f32_16x16x32_bf16 v[150:153], v[98:101], v[212:215], 0
	v_mfma_f32_16x16x32_bf16 v[146:149], v[106:109], v[212:215], 0
	v_mfma_f32_16x16x32_bf16 v[134:137], v[98:101], v[220:223], 0
	v_mfma_f32_16x16x32_bf16 v[130:133], v[106:109], v[220:223], 0
	v_mfma_f32_16x16x32_bf16 v[118:121], v[98:101], v[228:231], 0
	v_mfma_f32_16x16x32_bf16 v[114:117], v[106:109], v[228:231], 0
	v_mfma_f32_16x16x32_bf16 v[86:89], v[98:101], v[236:239], 0
	v_mfma_f32_16x16x32_bf16 v[82:85], v[106:109], v[236:239], 0
	v_mfma_f32_16x16x32_bf16 v[150:153], v[102:105], v[216:219], v[150:153]
	v_mfma_f32_16x16x32_bf16 v[146:149], v[110:113], v[216:219], v[146:149]
	v_mfma_f32_16x16x32_bf16 v[134:137], v[102:105], v[224:227], v[134:137]
	v_mfma_f32_16x16x32_bf16 v[130:133], v[110:113], v[224:227], v[130:133]
	v_mfma_f32_16x16x32_bf16 v[118:121], v[102:105], v[232:235], v[118:121]
	v_mfma_f32_16x16x32_bf16 v[114:117], v[110:113], v[232:235], v[114:117]
	v_mfma_f32_16x16x32_bf16 v[86:89], v[102:105], v[240:243], v[86:89]
	v_mfma_f32_16x16x32_bf16 v[82:85], v[110:113], v[240:243], v[82:85]
	s_barrier
	s_add_i32 s21, s68, s29
	v_lshl_add_u64 v[182:183], s[48:49], 0, v[164:165]
	s_mov_b32 m0, s21
	ds_read_b128 v[212:215], v205 offset:16384
	ds_read_b128 v[216:219], v205 offset:17408
	ds_read_b128 v[220:223], v205 offset:18432
	ds_read_b128 v[224:227], v205 offset:19456
	ds_read_b128 v[228:231], v205 offset:20480
	ds_read_b128 v[232:235], v205 offset:21504
	ds_read_b128 v[236:239], v205 offset:22528
	ds_read_b128 v[240:243], v205 offset:23552
	global_load_lds_dwordx4 v[182:183], off
	s_add_i32 m0, s21, 0x2000
	s_add_u32 s22, s48, 0x20000
	v_lshl_add_u64 v[244:245], s[48:49], 0, v[168:169]
	s_addc_u32 s23, s49, 0
	s_add_i32 s21, s69, s29
	global_load_lds_dwordx4 v[244:245], off
	v_lshl_add_u64 v[246:247], s[22:23], 0, v[164:165]
	s_mov_b32 m0, s21
	v_lshl_add_u64 v[248:249], s[58:59], 0, v[166:167]
	global_load_lds_dwordx4 v[246:247], off
	v_lshl_add_u64 v[246:247], s[22:23], 0, v[168:169]
	s_add_i32 m0, s21, 0x2000
	s_nop 0
	global_load_lds_dwordx4 v[246:247], off
	v_lshl_add_u64 v[246:247], s[58:59], 0, v[162:163]
	s_mov_b32 m0, s30
	s_nop 0
	global_load_lds_dwordx4 v[246:247], off
	s_mov_b32 m0, s31
	s_nop 0
	global_load_lds_dwordx4 v[248:249], off
	s_waitcnt lgkmcnt(0)
	s_barrier
	v_mfma_f32_16x16x32_bf16 v[78:81], v[34:37], v[212:215], 0
	v_mfma_f32_16x16x32_bf16 v[74:77], v[42:45], v[212:215], 0
	v_mfma_f32_16x16x32_bf16 v[62:65], v[34:37], v[220:223], 0
	v_mfma_f32_16x16x32_bf16 v[58:61], v[42:45], v[220:223], 0
	v_mfma_f32_16x16x32_bf16 v[30:33], v[34:37], v[228:231], 0
	v_mfma_f32_16x16x32_bf16 v[26:29], v[42:45], v[228:231], 0
	v_mfma_f32_16x16x32_bf16 v[14:17], v[34:37], v[236:239], 0
	v_mfma_f32_16x16x32_bf16 v[10:13], v[42:45], v[236:239], 0
	v_mfma_f32_16x16x32_bf16 v[78:81], v[38:41], v[216:219], v[78:81]
	v_mfma_f32_16x16x32_bf16 v[74:77], v[46:49], v[216:219], v[74:77]
	v_mfma_f32_16x16x32_bf16 v[62:65], v[38:41], v[224:227], v[62:65]
	v_mfma_f32_16x16x32_bf16 v[58:61], v[46:49], v[224:227], v[58:61]
	v_mfma_f32_16x16x32_bf16 v[30:33], v[38:41], v[232:235], v[30:33]
	v_mfma_f32_16x16x32_bf16 v[26:29], v[46:49], v[232:235], v[26:29]
	v_mfma_f32_16x16x32_bf16 v[14:17], v[38:41], v[240:243], v[14:17]
	v_mfma_f32_16x16x32_bf16 v[10:13], v[46:49], v[240:243], v[10:13]
	v_mfma_f32_16x16x32_bf16 v[22:25], v[98:101], v[228:231], 0
	v_mfma_f32_16x16x32_bf16 v[18:21], v[106:109], v[228:231], 0
	v_mfma_f32_16x16x32_bf16 v[6:9], v[98:101], v[236:239], 0
	v_mfma_f32_16x16x32_bf16 v[2:5], v[106:109], v[236:239], 0
	v_mfma_f32_16x16x32_bf16 v[34:37], v[98:101], v[212:215], 0
	v_mfma_f32_16x16x32_bf16 v[38:41], v[106:109], v[212:215], 0
	v_mfma_f32_16x16x32_bf16 v[42:45], v[98:101], v[220:223], 0
	v_mfma_f32_16x16x32_bf16 v[46:49], v[106:109], v[220:223], 0
	v_mfma_f32_16x16x32_bf16 v[22:25], v[102:105], v[232:235], v[22:25]
	v_mfma_f32_16x16x32_bf16 v[18:21], v[110:113], v[232:235], v[18:21]
	v_mfma_f32_16x16x32_bf16 v[6:9], v[102:105], v[240:243], v[6:9]
	v_mfma_f32_16x16x32_bf16 v[2:5], v[110:113], v[240:243], v[2:5]
	v_mfma_f32_16x16x32_bf16 v[34:37], v[102:105], v[216:219], v[34:37]
	v_mfma_f32_16x16x32_bf16 v[38:41], v[110:113], v[216:219], v[38:41]
	v_mfma_f32_16x16x32_bf16 v[42:45], v[102:105], v[224:227], v[42:45]
	v_mfma_f32_16x16x32_bf16 v[46:49], v[110:113], v[224:227], v[46:49]
	s_barrier
; #define PG8_STAGE(bufoff, gbase, voff) do { _Pragma("unroll") for (int _i = 0; _i < 2; ++_i) \
;         __builtin_amdgcn_global_load_lds((const unsigned*)((const char*)(gbase) + (voff)[_i]), (LAS unsigned*)(lds + (bufoff) + ldsw + _i * 8192), 16, 0, 0); } while (0)
; #define PG8_LDA(dst, b, h) do { _Pragma("unroll") for (int m = 0; m < 4; ++m) _Pragma("unroll") for (int k = 0; k < 2; ++k) dst[m][k] = *(const LAS bf16x8*)(lds + PG8_SA(b, h) + aoff + m * 2048 + k * 1024); } while (0)
; #define PG8_LDB(dst, b, h) do { _Pragma("unroll") for (int n = 0; n < 2; ++n) _Pragma("unroll") for (int k = 0; k < 2; ++k) dst[n][k] = *(const LAS bf16x8*)(lds + PG8_SB(b, h) + boff + n * 2048 + k * 1024); } while (0)
; #define PG8_MMA(ai, bj, At, Bt) do { __builtin_amdgcn_s_setprio(1); _Pragma("unroll") for (int m = 0; m < 4; ++m) _Pragma("unroll") for (int n = 0; n < 2; ++n) _Pragma("unroll") for (int k = 0; k < 2; ++k) \
;         acc[ai][bj][m][n] = __builtin_amdgcn_mfma_f32_16x16x32_bf16(Bt[n][k], At[m][k], acc[ai][bj][m][n], 0, 0, 0); __builtin_amdgcn_s_setprio(0); } while (0)
; #define PG8_WAIT_V(n) asm volatile("s_waitcnt vmcnt(" #n ")" ::: "memory")
; #define PG8_WAIT_L(n) asm volatile("s_waitcnt lgkmcnt(" #n ")" ::: "memory")
; #define PG8_BAR __builtin_amdgcn_s_barrier()
; #define PG8_SCHED __builtin_amdgcn_sched_barrier(0)
; template <class Epi, class Sched, bool ALIGN_EPI = false, bool SP2 = false>
; __device__ __forceinline__ void gemm_phase(LAS unsigned char* lds, const Gemm g, const Sched& S, const Epi& E) {
;     ...
;             PG8_LDB(B0, 1, 0); PG8_LDB(B1, 1, 1); PG8_SCHED; PG8_LDA(At, 1, 0); PG8_STAGE(PG8_SA(0, 1), a2 + hstep, voffA);
;             PG8_WAIT_V(8); PG8_WAIT_L(0); PG8_BAR; PG8_MMA(0, 0, At, B0); PG8_MMA(0, 1, At, B1); PG8_BAR; PG8_SCHED;
;             PG8_LDA(At, 1, 1); PG8_STAGE(PG8_SB(1, 0), b3, voffB); PG8_STAGE(PG8_SB(1, 1), b3 + hstepB, voffB); PG8_STAGE(PG8_SA(1, 0), a3, voffA);
;             PG8_WAIT_V(8); PG8_WAIT_L(0); PG8_BAR; PG8_MMA(1, 0, At, B0); PG8_MMA(1, 1, At, B1); PG8_BAR; PG8_SCHED;
	s_add_i32 s21, 0, 0x18000
	s_add_i32 s24, 0, 0x1c000
	v_add_u32_e32 v70, s21, v186
	v_add_u32_e32 v110, s24, v186
	ds_read_b128 v[50:53], v70
	ds_read_b128 v[54:57], v70 offset:1024
	ds_read_b128 v[66:69], v70 offset:2048
	ds_read_b128 v[70:73], v70 offset:3072
	ds_read_b128 v[98:101], v110
	ds_read_b128 v[102:105], v110 offset:1024
	ds_read_b128 v[106:109], v110 offset:2048
	ds_read_b128 v[110:113], v110 offset:3072
	s_add_u32 s22, s58, 0x80000
	s_addc_u32 s23, s59, 0
	s_mov_b32 m0, s33
	v_lshl_add_u64 v[250:251], s[22:23], 0, v[162:163]
	ds_read_b128 v[212:215], v205 offset:32768
	ds_read_b128 v[216:219], v205 offset:33792
	ds_read_b128 v[220:223], v205 offset:34816
	ds_read_b128 v[224:227], v205 offset:35840
	ds_read_b128 v[228:231], v205 offset:36864
	ds_read_b128 v[232:235], v205 offset:37888
	ds_read_b128 v[236:239], v205 offset:38912
	ds_read_b128 v[240:243], v205 offset:39936
	global_load_lds_dwordx4 v[250:251], off
	v_lshl_add_u64 v[250:251], s[22:23], 0, v[166:167]
	s_mov_b32 m0, s60
	s_nop 0
	global_load_lds_dwordx4 v[250:251], off
	s_waitcnt vmcnt(8)
	s_waitcnt lgkmcnt(0)
	s_barrier
	v_mfma_f32_16x16x32_bf16 v[158:161], v[50:53], v[212:215], v[158:161]
	v_mfma_f32_16x16x32_bf16 v[154:157], v[66:69], v[212:215], v[154:157]
	v_mfma_f32_16x16x32_bf16 v[142:145], v[50:53], v[220:223], v[142:145]
	v_mfma_f32_16x16x32_bf16 v[138:141], v[66:69], v[220:223], v[138:141]
	v_mfma_f32_16x16x32_bf16 v[126:129], v[50:53], v[228:231], v[126:129]
	v_mfma_f32_16x16x32_bf16 v[122:125], v[66:69], v[228:231], v[122:125]
	v_mfma_f32_16x16x32_bf16 v[94:97], v[50:53], v[236:239], v[94:97]
	v_mfma_f32_16x16x32_bf16 v[90:93], v[66:69], v[236:239], v[90:93]
	v_mfma_f32_16x16x32_bf16 v[158:161], v[54:57], v[216:219], v[158:161]
	v_mfma_f32_16x16x32_bf16 v[154:157], v[70:73], v[216:219], v[154:157]
	v_mfma_f32_16x16x32_bf16 v[142:145], v[54:57], v[224:227], v[142:145]
	v_mfma_f32_16x16x32_bf16 v[138:141], v[70:73], v[224:227], v[138:141]
	v_mfma_f32_16x16x32_bf16 v[126:129], v[54:57], v[232:235], v[126:129]
	v_mfma_f32_16x16x32_bf16 v[122:125], v[70:73], v[232:235], v[122:125]
	v_mfma_f32_16x16x32_bf16 v[94:97], v[54:57], v[240:243], v[94:97]
	v_mfma_f32_16x16x32_bf16 v[90:93], v[70:73], v[240:243], v[90:93]
	v_mfma_f32_16x16x32_bf16 v[150:153], v[98:101], v[212:215], v[150:153]
	v_mfma_f32_16x16x32_bf16 v[146:149], v[106:109], v[212:215], v[146:149]
	v_mfma_f32_16x16x32_bf16 v[134:137], v[98:101], v[220:223], v[134:137]
	v_mfma_f32_16x16x32_bf16 v[130:133], v[106:109], v[220:223], v[130:133]
	v_mfma_f32_16x16x32_bf16 v[118:121], v[98:101], v[228:231], v[118:121]
	v_mfma_f32_16x16x32_bf16 v[114:117], v[106:109], v[228:231], v[114:117]
	v_mfma_f32_16x16x32_bf16 v[86:89], v[98:101], v[236:239], v[86:89]
	v_mfma_f32_16x16x32_bf16 v[82:85], v[106:109], v[236:239], v[82:85]
	v_mfma_f32_16x16x32_bf16 v[150:153], v[102:105], v[216:219], v[150:153]
	v_mfma_f32_16x16x32_bf16 v[146:149], v[110:113], v[216:219], v[146:149]
	v_mfma_f32_16x16x32_bf16 v[134:137], v[102:105], v[224:227], v[134:137]
	v_mfma_f32_16x16x32_bf16 v[130:133], v[110:113], v[224:227], v[130:133]
	v_mfma_f32_16x16x32_bf16 v[118:121], v[102:105], v[232:235], v[118:121]
	v_mfma_f32_16x16x32_bf16 v[114:117], v[110:113], v[232:235], v[114:117]
	v_mfma_f32_16x16x32_bf16 v[86:89], v[102:105], v[240:243], v[86:89]
	v_mfma_f32_16x16x32_bf16 v[82:85], v[110:113], v[240:243], v[82:85]
	s_barrier
	s_add_i32 s21, s21, s29
	v_lshl_add_u64 v[182:183], v[182:183], 0, s[34:35]
	s_mov_b32 m0, s21
	ds_read_b128 v[212:215], v205 offset:49152
	ds_read_b128 v[216:219], v205 offset:50176
	ds_read_b128 v[220:223], v205 offset:51200
	ds_read_b128 v[224:227], v205 offset:52224
	ds_read_b128 v[228:231], v205 offset:53248
	ds_read_b128 v[232:235], v205 offset:54272
	ds_read_b128 v[236:239], v205 offset:55296
	ds_read_b128 v[240:243], v205 offset:56320
	global_load_lds_dwordx4 v[182:183], off
	s_add_i32 m0, s21, 0x2000
	s_add_u32 s22, s48, 0x20080
	v_lshl_add_u64 v[182:183], v[244:245], 0, s[34:35]
	s_addc_u32 s23, s49, 0
	s_add_i32 s21, s24, s29
	global_load_lds_dwordx4 v[182:183], off
	v_lshl_add_u64 v[182:183], s[22:23], 0, v[164:165]
	s_mov_b32 m0, s21
	s_nop 0
	global_load_lds_dwordx4 v[182:183], off
	v_lshl_add_u64 v[182:183], s[22:23], 0, v[168:169]
	s_add_i32 m0, s21, 0x2000
	s_nop 0
	global_load_lds_dwordx4 v[182:183], off
	v_lshl_add_u64 v[182:183], v[246:247], 0, s[34:35]
	s_mov_b32 m0, s65
	s_nop 0
	global_load_lds_dwordx4 v[182:183], off
	v_lshl_add_u64 v[182:183], v[248:249], 0, s[34:35]
	s_mov_b32 m0, s66
	s_nop 0
	global_load_lds_dwordx4 v[182:183], off
	s_waitcnt vmcnt(8)
	s_waitcnt lgkmcnt(0)
	s_barrier
	v_mfma_f32_16x16x32_bf16 v[78:81], v[50:53], v[212:215], v[78:81]
	v_mfma_f32_16x16x32_bf16 v[74:77], v[66:69], v[212:215], v[74:77]
	v_mfma_f32_16x16x32_bf16 v[62:65], v[50:53], v[220:223], v[62:65]
	v_mfma_f32_16x16x32_bf16 v[58:61], v[66:69], v[220:223], v[58:61]
	v_mfma_f32_16x16x32_bf16 v[30:33], v[50:53], v[228:231], v[30:33]
	v_mfma_f32_16x16x32_bf16 v[26:29], v[66:69], v[228:231], v[26:29]
	v_mfma_f32_16x16x32_bf16 v[14:17], v[50:53], v[236:239], v[14:17]
	v_mfma_f32_16x16x32_bf16 v[10:13], v[66:69], v[236:239], v[10:13]
	v_mfma_f32_16x16x32_bf16 v[78:81], v[54:57], v[216:219], v[78:81]
	v_mfma_f32_16x16x32_bf16 v[74:77], v[70:73], v[216:219], v[74:77]
	v_mfma_f32_16x16x32_bf16 v[62:65], v[54:57], v[224:227], v[62:65]
	v_mfma_f32_16x16x32_bf16 v[58:61], v[70:73], v[224:227], v[58:61]
	v_mfma_f32_16x16x32_bf16 v[30:33], v[54:57], v[232:235], v[30:33]
	v_mfma_f32_16x16x32_bf16 v[26:29], v[70:73], v[232:235], v[26:29]
	v_mfma_f32_16x16x32_bf16 v[14:17], v[54:57], v[240:243], v[14:17]
	v_mfma_f32_16x16x32_bf16 v[10:13], v[70:73], v[240:243], v[10:13]
	v_mfma_f32_16x16x32_bf16 v[34:37], v[98:101], v[212:215], v[34:37]
	v_mfma_f32_16x16x32_bf16 v[70:73], v[102:105], v[216:219], v[34:37]
	v_mfma_f32_16x16x32_bf16 v[34:37], v[106:109], v[212:215], v[38:41]
	v_mfma_f32_16x16x32_bf16 v[66:69], v[110:113], v[216:219], v[34:37]
	v_mfma_f32_16x16x32_bf16 v[34:37], v[98:101], v[220:223], v[42:45]
	v_mfma_f32_16x16x32_bf16 v[54:57], v[102:105], v[224:227], v[34:37]
	v_mfma_f32_16x16x32_bf16 v[34:37], v[106:109], v[220:223], v[46:49]
	v_mfma_f32_16x16x32_bf16 v[22:25], v[98:101], v[228:231], v[22:25]
	v_mfma_f32_16x16x32_bf16 v[18:21], v[106:109], v[228:231], v[18:21]
	v_mfma_f32_16x16x32_bf16 v[6:9], v[98:101], v[236:239], v[6:9]
	v_mfma_f32_16x16x32_bf16 v[2:5], v[106:109], v[236:239], v[2:5]
	v_mfma_f32_16x16x32_bf16 v[50:53], v[110:113], v[224:227], v[34:37]
	v_mfma_f32_16x16x32_bf16 v[22:25], v[102:105], v[232:235], v[22:25]
	v_mfma_f32_16x16x32_bf16 v[18:21], v[110:113], v[232:235], v[18:21]
	v_mfma_f32_16x16x32_bf16 v[6:9], v[102:105], v[240:243], v[6:9]
	v_mfma_f32_16x16x32_bf16 v[2:5], v[110:113], v[240:243], v[2:5]
	s_barrier
	s_add_i32 s20, s20, 2
	s_add_u32 s16, s16, 0x100
	s_addc_u32 s17, s17, 0
	s_add_u32 s18, s18, 0x100
	s_addc_u32 s19, s19, 0
	s_cmp_gt_u32 s20, 29
; #define PG8_STAGE(bufoff, gbase, voff) do { _Pragma("unroll") for (int _i = 0; _i < 2; ++_i) \
;         __builtin_amdgcn_global_load_lds((const unsigned*)((const char*)(gbase) + (voff)[_i]), (LAS unsigned*)(lds + (bufoff) + ldsw + _i * 8192), 16, 0, 0); } while (0)
; #define PG8_LDA(dst, b, h) do { _Pragma("unroll") for (int m = 0; m < 4; ++m) _Pragma("unroll") for (int k = 0; k < 2; ++k) dst[m][k] = *(const LAS bf16x8*)(lds + PG8_SA(b, h) + aoff + m * 2048 + k * 1024); } while (0)
; #define PG8_LDB(dst, b, h) do { _Pragma("unroll") for (int n = 0; n < 2; ++n) _Pragma("unroll") for (int k = 0; k < 2; ++k) dst[n][k] = *(const LAS bf16x8*)(lds + PG8_SB(b, h) + boff + n * 2048 + k * 1024); } while (0)
; #define PG8_MMA(ai, bj, At, Bt) do { __builtin_amdgcn_s_setprio(1); _Pragma("unroll") for (int m = 0; m < 4; ++m) _Pragma("unroll") for (int n = 0; n < 2; ++n) _Pragma("unroll") for (int k = 0; k < 2; ++k) \
;         acc[ai][bj][m][n] = __builtin_amdgcn_mfma_f32_16x16x32_bf16(Bt[n][k], At[m][k], acc[ai][bj][m][n], 0, 0, 0); __builtin_amdgcn_s_setprio(0); } while (0)
; #define PG8_WAIT_V(n) asm volatile("s_waitcnt vmcnt(" #n ")" ::: "memory")
; #define PG8_WAIT_L(n) asm volatile("s_waitcnt lgkmcnt(" #n ")" ::: "memory")
; #define PG8_BAR __builtin_amdgcn_s_barrier()
; #define PG8_SCHED __builtin_amdgcn_sched_barrier(0)
; template <class Epi, class Sched, bool ALIGN_EPI = false, bool SP2 = false>
; __device__ __forceinline__ void gemm_phase(LAS unsigned char* lds, const Gemm g, const Sched& S, const Epi& E) {
;     ...
;         for (int t = 0; t < nt; t += 2) {
;             const bool last = (t == nt - 2);
;             const char* a1 = cA + (size_t)(t + 1) * kstep;
;             const char* a2 = last ? nA : cA + (size_t)(t + 2) * kstep; const char* b2 = last ? nB : cB + (size_t)(t + 2) * kstep;
;             const char* a3 = a2 + kstep; const char* b3 = b2 + kstep;
;             if (last && has_next) S.a_ready(nxt);
;             if constexpr (SP2) {
;             PG8_LDB(B0, 0, 0); PG8_LDB(B1, 0, 1); PG8_SCHED; PG8_LDA(At, 0, 0); PG8_STAGE(PG8_SA(1, 1), a1 + hstep, voffA);
;             PG8_WAIT_V(8); PG8_WAIT_L(0); PG8_BAR; PG8_MMA(0, 0, At, B0); PG8_MMA(0, 1, At, B1); PG8_BAR; PG8_SCHED;
;             PG8_LDA(At, 0, 1); PG8_STAGE(PG8_SB(0, 0), b2, voffB); PG8_STAGE(PG8_SB(0, 1), b2 + hstepB, voffB); PG8_STAGE(PG8_SA(0, 0), a2, voffA);
.LBB0_535:
	ds_read_b128 v[34:37], v203
	ds_read_b128 v[38:41], v203 offset:1024
	ds_read_b128 v[42:45], v203 offset:2048
	ds_read_b128 v[46:49], v203 offset:3072
	s_waitcnt vmcnt(0)
	ds_read_b128 v[98:101], v204
	ds_read_b128 v[102:105], v204 offset:1024
	ds_read_b128 v[106:109], v204 offset:2048
	ds_read_b128 v[110:113], v204 offset:3072
	s_add_u32 s21, s16, 0xfff80080
	s_addc_u32 s22, s17, -1
	s_cmp_eq_u32 s20, 28
	s_cselect_b32 s59, s0, s22
	s_cselect_b32 s58, s3, s21
	s_cselect_b32 s49, s14, s19
	s_cselect_b32 s48, s15, s18
	v_lshl_add_u64 v[182:183], s[16:17], 0, v[172:173]
	s_add_i32 m0, s30, 0xc000
	ds_read_b128 v[212:215], v205
	ds_read_b128 v[216:219], v205 offset:1024
	ds_read_b128 v[220:223], v205 offset:2048
	ds_read_b128 v[224:227], v205 offset:3072
	ds_read_b128 v[228:231], v205 offset:4096
	ds_read_b128 v[232:235], v205 offset:5120
	ds_read_b128 v[236:239], v205 offset:6144
	ds_read_b128 v[240:243], v205 offset:7168
	global_load_lds_dwordx4 v[182:183], off
	v_lshl_add_u64 v[182:183], s[16:17], 0, v[174:175]
	s_add_i32 m0, s30, 0xe000
	s_nop 0
	global_load_lds_dwordx4 v[182:183], off
	s_waitcnt vmcnt(8)
	s_waitcnt lgkmcnt(0)
	s_barrier
	v_mfma_f32_16x16x32_bf16 v[158:161], v[34:37], v[212:215], v[158:161]
	v_mfma_f32_16x16x32_bf16 v[154:157], v[42:45], v[212:215], v[154:157]
	v_mfma_f32_16x16x32_bf16 v[142:145], v[34:37], v[220:223], v[142:145]
	v_mfma_f32_16x16x32_bf16 v[138:141], v[42:45], v[220:223], v[138:141]
	v_mfma_f32_16x16x32_bf16 v[126:129], v[34:37], v[228:231], v[126:129]
	v_mfma_f32_16x16x32_bf16 v[122:125], v[42:45], v[228:231], v[122:125]
	v_mfma_f32_16x16x32_bf16 v[94:97], v[34:37], v[236:239], v[94:97]
	v_mfma_f32_16x16x32_bf16 v[90:93], v[42:45], v[236:239], v[90:93]
	v_mfma_f32_16x16x32_bf16 v[158:161], v[38:41], v[216:219], v[158:161]
	v_mfma_f32_16x16x32_bf16 v[154:157], v[46:49], v[216:219], v[154:157]
	v_mfma_f32_16x16x32_bf16 v[142:145], v[38:41], v[224:227], v[142:145]
	v_mfma_f32_16x16x32_bf16 v[138:141], v[46:49], v[224:227], v[138:141]
	v_mfma_f32_16x16x32_bf16 v[126:129], v[38:41], v[232:235], v[126:129]
	v_mfma_f32_16x16x32_bf16 v[122:125], v[46:49], v[232:235], v[122:125]
	v_mfma_f32_16x16x32_bf16 v[94:97], v[38:41], v[240:243], v[94:97]
	v_mfma_f32_16x16x32_bf16 v[90:93], v[46:49], v[240:243], v[90:93]
	v_mfma_f32_16x16x32_bf16 v[150:153], v[98:101], v[212:215], v[150:153]
	v_mfma_f32_16x16x32_bf16 v[146:149], v[106:109], v[212:215], v[146:149]
	v_mfma_f32_16x16x32_bf16 v[134:137], v[98:101], v[220:223], v[134:137]
	v_mfma_f32_16x16x32_bf16 v[130:133], v[106:109], v[220:223], v[130:133]
	v_mfma_f32_16x16x32_bf16 v[118:121], v[98:101], v[228:231], v[118:121]
	v_mfma_f32_16x16x32_bf16 v[114:117], v[106:109], v[228:231], v[114:117]
	v_mfma_f32_16x16x32_bf16 v[86:89], v[98:101], v[236:239], v[86:89]
	v_mfma_f32_16x16x32_bf16 v[82:85], v[106:109], v[236:239], v[82:85]
	v_mfma_f32_16x16x32_bf16 v[150:153], v[102:105], v[216:219], v[150:153]
	v_mfma_f32_16x16x32_bf16 v[146:149], v[110:113], v[216:219], v[146:149]
	v_mfma_f32_16x16x32_bf16 v[134:137], v[102:105], v[224:227], v[134:137]
	v_mfma_f32_16x16x32_bf16 v[130:133], v[110:113], v[224:227], v[130:133]
	v_mfma_f32_16x16x32_bf16 v[118:121], v[102:105], v[232:235], v[118:121]
	v_mfma_f32_16x16x32_bf16 v[114:117], v[110:113], v[232:235], v[114:117]
	v_mfma_f32_16x16x32_bf16 v[86:89], v[102:105], v[240:243], v[86:89]
	v_mfma_f32_16x16x32_bf16 v[82:85], v[110:113], v[240:243], v[82:85]
	s_barrier
	s_add_i32 s21, s68, s29
	v_lshl_add_u64 v[182:183], s[48:49], 0, v[164:165]
	s_mov_b32 m0, s21
	ds_read_b128 v[212:215], v205 offset:16384
	ds_read_b128 v[216:219], v205 offset:17408
	ds_read_b128 v[220:223], v205 offset:18432
	ds_read_b128 v[224:227], v205 offset:19456
	ds_read_b128 v[228:231], v205 offset:20480
	ds_read_b128 v[232:235], v205 offset:21504
	ds_read_b128 v[236:239], v205 offset:22528
	ds_read_b128 v[240:243], v205 offset:23552
	global_load_lds_dwordx4 v[182:183], off
	s_add_i32 m0, s21, 0x2000
	s_add_u32 s22, s48, 0x20000
	v_lshl_add_u64 v[244:245], s[48:49], 0, v[168:169]
	s_addc_u32 s23, s49, 0
	s_add_i32 s21, s69, s29
	global_load_lds_dwordx4 v[244:245], off
	v_lshl_add_u64 v[246:247], s[22:23], 0, v[164:165]
	s_mov_b32 m0, s21
	v_lshl_add_u64 v[248:249], s[58:59], 0, v[166:167]
	global_load_lds_dwordx4 v[246:247], off
	v_lshl_add_u64 v[246:247], s[22:23], 0, v[168:169]
	s_add_i32 m0, s21, 0x2000
	s_nop 0
	global_load_lds_dwordx4 v[246:247], off
	v_lshl_add_u64 v[246:247], s[58:59], 0, v[162:163]
	s_mov_b32 m0, s30
	s_nop 0
	global_load_lds_dwordx4 v[246:247], off
	s_mov_b32 m0, s31
	s_nop 0
	global_load_lds_dwordx4 v[248:249], off
	s_waitcnt vmcnt(8)
	s_waitcnt lgkmcnt(0)
	s_barrier
; #define PG8_STAGE(bufoff, gbase, voff) do { _Pragma("unroll") for (int _i = 0; _i < 2; ++_i) \
;         __builtin_amdgcn_global_load_lds((const unsigned*)((const char*)(gbase) + (voff)[_i]), (LAS unsigned*)(lds + (bufoff) + ldsw + _i * 8192), 16, 0, 0); } while (0)
; #define PG8_LDA(dst, b, h) do { _Pragma("unroll") for (int m = 0; m < 4; ++m) _Pragma("unroll") for (int k = 0; k < 2; ++k) dst[m][k] = *(const LAS bf16x8*)(lds + PG8_SA(b, h) + aoff + m * 2048 + k * 1024); } while (0)
; #define PG8_LDB(dst, b, h) do { _Pragma("unroll") for (int n = 0; n < 2; ++n) _Pragma("unroll") for (int k = 0; k < 2; ++k) dst[n][k] = *(const LAS bf16x8*)(lds + PG8_SB(b, h) + boff + n * 2048 + k * 1024); } while (0)
; #define PG8_MMA(ai, bj, At, Bt) do { __builtin_amdgcn_s_setprio(1); _Pragma("unroll") for (int m = 0; m < 4; ++m) _Pragma("unroll") for (int n = 0; n < 2; ++n) _Pragma("unroll") for (int k = 0; k < 2; ++k) \
;         acc[ai][bj][m][n] = __builtin_amdgcn_mfma_f32_16x16x32_bf16(Bt[n][k], At[m][k], acc[ai][bj][m][n], 0, 0, 0); __builtin_amdgcn_s_setprio(0); } while (0)
; #define PG8_WAIT_V(n) asm volatile("s_waitcnt vmcnt(" #n ")" ::: "memory")
; #define PG8_WAIT_L(n) asm volatile("s_waitcnt lgkmcnt(" #n ")" ::: "memory")
; #define PG8_BAR __builtin_amdgcn_s_barrier()
; #define PG8_SCHED __builtin_amdgcn_sched_barrier(0)
; template <class Epi, class Sched, bool ALIGN_EPI = false, bool SP2 = false>
; __device__ __forceinline__ void gemm_phase(LAS unsigned char* lds, const Gemm g, const Sched& S, const Epi& E) {
;     ...
;             PG8_WAIT_V(8); PG8_WAIT_L(0); PG8_BAR; PG8_MMA(0, 0, At, B0); PG8_MMA(0, 1, At, B1); PG8_BAR; PG8_SCHED;
;             PG8_LDA(At, 0, 1); PG8_STAGE(PG8_SB(0, 0), b2, voffB); PG8_STAGE(PG8_SB(0, 1), b2 + hstepB, voffB); PG8_STAGE(PG8_SA(0, 0), a2, voffA);
;             PG8_WAIT_V(8); PG8_WAIT_L(0); PG8_BAR; PG8_MMA(1, 0, At, B0); PG8_MMA(1, 1, At, B1); PG8_BAR; PG8_SCHED;
;             PG8_LDB(B0, 1, 0); PG8_LDB(B1, 1, 1); PG8_SCHED; PG8_LDA(At, 1, 0); PG8_STAGE(PG8_SA(0, 1), a2 + hstep, voffA);
;             PG8_WAIT_V(8); PG8_WAIT_L(0); PG8_BAR; PG8_MMA(0, 0, At, B0); PG8_MMA(0, 1, At, B1); PG8_BAR; PG8_SCHED;
;             PG8_LDA(At, 1, 1); PG8_STAGE(PG8_SB(1, 0), b3, voffB); PG8_STAGE(PG8_SB(1, 1), b3 + hstepB, voffB); PG8_STAGE(PG8_SA(1, 0), a3, voffA);
	v_mfma_f32_16x16x32_bf16 v[78:81], v[34:37], v[212:215], v[78:81]
	v_mfma_f32_16x16x32_bf16 v[74:77], v[42:45], v[212:215], v[74:77]
	v_mfma_f32_16x16x32_bf16 v[62:65], v[34:37], v[220:223], v[62:65]
	v_mfma_f32_16x16x32_bf16 v[58:61], v[42:45], v[220:223], v[58:61]
	v_mfma_f32_16x16x32_bf16 v[30:33], v[34:37], v[228:231], v[30:33]
	v_mfma_f32_16x16x32_bf16 v[26:29], v[42:45], v[228:231], v[26:29]
	v_mfma_f32_16x16x32_bf16 v[14:17], v[34:37], v[236:239], v[14:17]
	v_mfma_f32_16x16x32_bf16 v[10:13], v[42:45], v[236:239], v[10:13]
	v_mfma_f32_16x16x32_bf16 v[78:81], v[38:41], v[216:219], v[78:81]
	v_mfma_f32_16x16x32_bf16 v[74:77], v[46:49], v[216:219], v[74:77]
	v_mfma_f32_16x16x32_bf16 v[62:65], v[38:41], v[224:227], v[62:65]
	v_mfma_f32_16x16x32_bf16 v[58:61], v[46:49], v[224:227], v[58:61]
	v_mfma_f32_16x16x32_bf16 v[30:33], v[38:41], v[232:235], v[30:33]
	v_mfma_f32_16x16x32_bf16 v[26:29], v[46:49], v[232:235], v[26:29]
	v_mfma_f32_16x16x32_bf16 v[14:17], v[38:41], v[240:243], v[14:17]
	v_mfma_f32_16x16x32_bf16 v[10:13], v[46:49], v[240:243], v[10:13]
	v_mfma_f32_16x16x32_bf16 v[22:25], v[98:101], v[228:231], v[22:25]
	v_mfma_f32_16x16x32_bf16 v[18:21], v[106:109], v[228:231], v[18:21]
	v_mfma_f32_16x16x32_bf16 v[6:9], v[98:101], v[236:239], v[6:9]
	v_mfma_f32_16x16x32_bf16 v[2:5], v[106:109], v[236:239], v[2:5]
	v_mfma_f32_16x16x32_bf16 v[34:37], v[98:101], v[212:215], v[70:73]
	v_mfma_f32_16x16x32_bf16 v[38:41], v[106:109], v[212:215], v[66:69]
	v_mfma_f32_16x16x32_bf16 v[42:45], v[98:101], v[220:223], v[54:57]
	v_mfma_f32_16x16x32_bf16 v[46:49], v[106:109], v[220:223], v[50:53]
	v_mfma_f32_16x16x32_bf16 v[22:25], v[102:105], v[232:235], v[22:25]
	v_mfma_f32_16x16x32_bf16 v[18:21], v[110:113], v[232:235], v[18:21]
	v_mfma_f32_16x16x32_bf16 v[6:9], v[102:105], v[240:243], v[6:9]
	v_mfma_f32_16x16x32_bf16 v[2:5], v[110:113], v[240:243], v[2:5]
	v_mfma_f32_16x16x32_bf16 v[34:37], v[102:105], v[216:219], v[34:37]
	v_mfma_f32_16x16x32_bf16 v[38:41], v[110:113], v[216:219], v[38:41]
	v_mfma_f32_16x16x32_bf16 v[42:45], v[102:105], v[224:227], v[42:45]
	v_mfma_f32_16x16x32_bf16 v[46:49], v[110:113], v[224:227], v[46:49]
	s_barrier
	s_add_i32 s21, 0, 0x18000
	s_add_i32 s24, 0, 0x1c000
	v_add_u32_e32 v70, s21, v186
	v_add_u32_e32 v110, s24, v186
	ds_read_b128 v[50:53], v70
	ds_read_b128 v[54:57], v70 offset:1024
	ds_read_b128 v[66:69], v70 offset:2048
	ds_read_b128 v[70:73], v70 offset:3072
	ds_read_b128 v[98:101], v110
	ds_read_b128 v[102:105], v110 offset:1024
	ds_read_b128 v[106:109], v110 offset:2048
	ds_read_b128 v[110:113], v110 offset:3072
	s_add_u32 s22, s58, 0x80000
	s_addc_u32 s23, s59, 0
	s_mov_b32 m0, s33
	v_lshl_add_u64 v[250:251], s[22:23], 0, v[162:163]
	ds_read_b128 v[212:215], v205 offset:32768
	ds_read_b128 v[216:219], v205 offset:33792
	ds_read_b128 v[220:223], v205 offset:34816
	ds_read_b128 v[224:227], v205 offset:35840
	ds_read_b128 v[228:231], v205 offset:36864
	ds_read_b128 v[232:235], v205 offset:37888
	ds_read_b128 v[236:239], v205 offset:38912
	ds_read_b128 v[240:243], v205 offset:39936
	global_load_lds_dwordx4 v[250:251], off
	v_lshl_add_u64 v[250:251], s[22:23], 0, v[166:167]
	s_mov_b32 m0, s60
	s_nop 0
	global_load_lds_dwordx4 v[250:251], off
	s_waitcnt vmcnt(8)
	s_waitcnt lgkmcnt(0)
	s_barrier
	v_mfma_f32_16x16x32_bf16 v[158:161], v[50:53], v[212:215], v[158:161]
	v_mfma_f32_16x16x32_bf16 v[154:157], v[66:69], v[212:215], v[154:157]
	v_mfma_f32_16x16x32_bf16 v[142:145], v[50:53], v[220:223], v[142:145]
	v_mfma_f32_16x16x32_bf16 v[138:141], v[66:69], v[220:223], v[138:141]
	v_mfma_f32_16x16x32_bf16 v[126:129], v[50:53], v[228:231], v[126:129]
	v_mfma_f32_16x16x32_bf16 v[122:125], v[66:69], v[228:231], v[122:125]
	v_mfma_f32_16x16x32_bf16 v[94:97], v[50:53], v[236:239], v[94:97]
	v_mfma_f32_16x16x32_bf16 v[90:93], v[66:69], v[236:239], v[90:93]
	v_mfma_f32_16x16x32_bf16 v[158:161], v[54:57], v[216:219], v[158:161]
	v_mfma_f32_16x16x32_bf16 v[154:157], v[70:73], v[216:219], v[154:157]
	v_mfma_f32_16x16x32_bf16 v[142:145], v[54:57], v[224:227], v[142:145]
	v_mfma_f32_16x16x32_bf16 v[138:141], v[70:73], v[224:227], v[138:141]
	v_mfma_f32_16x16x32_bf16 v[126:129], v[54:57], v[232:235], v[126:129]
	v_mfma_f32_16x16x32_bf16 v[122:125], v[70:73], v[232:235], v[122:125]
	v_mfma_f32_16x16x32_bf16 v[94:97], v[54:57], v[240:243], v[94:97]
	v_mfma_f32_16x16x32_bf16 v[90:93], v[70:73], v[240:243], v[90:93]
	v_mfma_f32_16x16x32_bf16 v[150:153], v[98:101], v[212:215], v[150:153]
	v_mfma_f32_16x16x32_bf16 v[146:149], v[106:109], v[212:215], v[146:149]
	v_mfma_f32_16x16x32_bf16 v[134:137], v[98:101], v[220:223], v[134:137]
	v_mfma_f32_16x16x32_bf16 v[130:133], v[106:109], v[220:223], v[130:133]
	v_mfma_f32_16x16x32_bf16 v[118:121], v[98:101], v[228:231], v[118:121]
	v_mfma_f32_16x16x32_bf16 v[114:117], v[106:109], v[228:231], v[114:117]
	v_mfma_f32_16x16x32_bf16 v[86:89], v[98:101], v[236:239], v[86:89]
	v_mfma_f32_16x16x32_bf16 v[82:85], v[106:109], v[236:239], v[82:85]
	v_mfma_f32_16x16x32_bf16 v[150:153], v[102:105], v[216:219], v[150:153]
	v_mfma_f32_16x16x32_bf16 v[146:149], v[110:113], v[216:219], v[146:149]
	v_mfma_f32_16x16x32_bf16 v[134:137], v[102:105], v[224:227], v[134:137]
	v_mfma_f32_16x16x32_bf16 v[130:133], v[110:113], v[224:227], v[130:133]
	v_mfma_f32_16x16x32_bf16 v[118:121], v[102:105], v[232:235], v[118:121]
	v_mfma_f32_16x16x32_bf16 v[114:117], v[110:113], v[232:235], v[114:117]
	v_mfma_f32_16x16x32_bf16 v[86:89], v[102:105], v[240:243], v[86:89]
	v_mfma_f32_16x16x32_bf16 v[82:85], v[110:113], v[240:243], v[82:85]
	s_barrier
; #define PG8_STAGE(bufoff, gbase, voff) do { _Pragma("unroll") for (int _i = 0; _i < 2; ++_i) \
;         __builtin_amdgcn_global_load_lds((const unsigned*)((const char*)(gbase) + (voff)[_i]), (LAS unsigned*)(lds + (bufoff) + ldsw + _i * 8192), 16, 0, 0); } while (0)
; #define PG8_LDA(dst, b, h) do { _Pragma("unroll") for (int m = 0; m < 4; ++m) _Pragma("unroll") for (int k = 0; k < 2; ++k) dst[m][k] = *(const LAS bf16x8*)(lds + PG8_SA(b, h) + aoff + m * 2048 + k * 1024); } while (0)
; #define PG8_MMA(ai, bj, At, Bt) do { __builtin_amdgcn_s_setprio(1); _Pragma("unroll") for (int m = 0; m < 4; ++m) _Pragma("unroll") for (int n = 0; n < 2; ++n) _Pragma("unroll") for (int k = 0; k < 2; ++k) \
;         acc[ai][bj][m][n] = __builtin_amdgcn_mfma_f32_16x16x32_bf16(Bt[n][k], At[m][k], acc[ai][bj][m][n], 0, 0, 0); __builtin_amdgcn_s_setprio(0); } while (0)
; #define PG8_WAIT_V(n) asm volatile("s_waitcnt vmcnt(" #n ")" ::: "memory")
; #define PG8_WAIT_L(n) asm volatile("s_waitcnt lgkmcnt(" #n ")" ::: "memory")
; #define PG8_BAR __builtin_amdgcn_s_barrier()
; #define PG8_SCHED __builtin_amdgcn_sched_barrier(0)
; template <class Epi, class Sched, bool ALIGN_EPI = false, bool SP2 = false>
; __device__ __forceinline__ void gemm_phase(LAS unsigned char* lds, const Gemm g, const Sched& S, const Epi& E) {
;     ...
;             PG8_LDA(At, 1, 1); PG8_STAGE(PG8_SB(1, 0), b3, voffB); PG8_STAGE(PG8_SB(1, 1), b3 + hstepB, voffB); PG8_STAGE(PG8_SA(1, 0), a3, voffA);
;             PG8_WAIT_V(8); PG8_WAIT_L(0); PG8_BAR; PG8_MMA(1, 0, At, B0); PG8_MMA(1, 1, At, B1); PG8_BAR; PG8_SCHED;
;     ...
;         if constexpr (ALIGN_EPI) { if (wr == 0) PG8_BAR; }
	s_add_i32 s21, s21, s29
	v_lshl_add_u64 v[182:183], v[182:183], 0, s[34:35]
	s_mov_b32 m0, s21
	ds_read_b128 v[212:215], v205 offset:49152
	ds_read_b128 v[216:219], v205 offset:50176
	ds_read_b128 v[220:223], v205 offset:51200
	ds_read_b128 v[224:227], v205 offset:52224
	ds_read_b128 v[228:231], v205 offset:53248
	ds_read_b128 v[232:235], v205 offset:54272
	ds_read_b128 v[236:239], v205 offset:55296
	ds_read_b128 v[240:243], v205 offset:56320
	global_load_lds_dwordx4 v[182:183], off
	s_add_i32 m0, s21, 0x2000
	s_add_u32 s22, s48, 0x20080
	v_lshl_add_u64 v[182:183], v[244:245], 0, s[34:35]
	s_addc_u32 s23, s49, 0
	s_add_i32 s21, s24, s29
	global_load_lds_dwordx4 v[182:183], off
	v_lshl_add_u64 v[182:183], s[22:23], 0, v[164:165]
	s_mov_b32 m0, s21
	s_nop 0
	global_load_lds_dwordx4 v[182:183], off
	v_lshl_add_u64 v[182:183], s[22:23], 0, v[168:169]
	s_add_i32 m0, s21, 0x2000
	s_nop 0
	global_load_lds_dwordx4 v[182:183], off
	v_lshl_add_u64 v[182:183], v[246:247], 0, s[34:35]
	s_mov_b32 m0, s65
	s_nop 0
	global_load_lds_dwordx4 v[182:183], off
	v_lshl_add_u64 v[182:183], v[248:249], 0, s[34:35]
	s_mov_b32 m0, s66
	s_nop 0
	global_load_lds_dwordx4 v[182:183], off
	s_waitcnt vmcnt(8)
	s_waitcnt lgkmcnt(0)
	s_barrier
	v_mfma_f32_16x16x32_bf16 v[78:81], v[50:53], v[212:215], v[78:81]
	v_mfma_f32_16x16x32_bf16 v[74:77], v[66:69], v[212:215], v[74:77]
	v_mfma_f32_16x16x32_bf16 v[62:65], v[50:53], v[220:223], v[62:65]
	v_mfma_f32_16x16x32_bf16 v[58:61], v[66:69], v[220:223], v[58:61]
	v_mfma_f32_16x16x32_bf16 v[30:33], v[50:53], v[228:231], v[30:33]
	v_mfma_f32_16x16x32_bf16 v[26:29], v[66:69], v[228:231], v[26:29]
	v_mfma_f32_16x16x32_bf16 v[14:17], v[50:53], v[236:239], v[14:17]
	v_mfma_f32_16x16x32_bf16 v[10:13], v[66:69], v[236:239], v[10:13]
	v_mfma_f32_16x16x32_bf16 v[78:81], v[54:57], v[216:219], v[78:81]
	v_mfma_f32_16x16x32_bf16 v[74:77], v[70:73], v[216:219], v[74:77]
	v_mfma_f32_16x16x32_bf16 v[62:65], v[54:57], v[224:227], v[62:65]
	v_mfma_f32_16x16x32_bf16 v[58:61], v[70:73], v[224:227], v[58:61]
	v_mfma_f32_16x16x32_bf16 v[30:33], v[54:57], v[232:235], v[30:33]
	v_mfma_f32_16x16x32_bf16 v[26:29], v[70:73], v[232:235], v[26:29]
	v_mfma_f32_16x16x32_bf16 v[14:17], v[54:57], v[240:243], v[14:17]
	v_mfma_f32_16x16x32_bf16 v[10:13], v[70:73], v[240:243], v[10:13]
	v_mfma_f32_16x16x32_bf16 v[34:37], v[98:101], v[212:215], v[34:37]
	v_mfma_f32_16x16x32_bf16 v[70:73], v[102:105], v[216:219], v[34:37]
	v_mfma_f32_16x16x32_bf16 v[34:37], v[106:109], v[212:215], v[38:41]
	v_mfma_f32_16x16x32_bf16 v[66:69], v[110:113], v[216:219], v[34:37]
	v_mfma_f32_16x16x32_bf16 v[34:37], v[98:101], v[220:223], v[42:45]
	v_mfma_f32_16x16x32_bf16 v[54:57], v[102:105], v[224:227], v[34:37]
	v_mfma_f32_16x16x32_bf16 v[34:37], v[106:109], v[220:223], v[46:49]
	v_mfma_f32_16x16x32_bf16 v[22:25], v[98:101], v[228:231], v[22:25]
	v_mfma_f32_16x16x32_bf16 v[18:21], v[106:109], v[228:231], v[18:21]
	v_mfma_f32_16x16x32_bf16 v[6:9], v[98:101], v[236:239], v[6:9]
	v_mfma_f32_16x16x32_bf16 v[2:5], v[106:109], v[236:239], v[2:5]
	v_mfma_f32_16x16x32_bf16 v[50:53], v[110:113], v[224:227], v[34:37]
	v_mfma_f32_16x16x32_bf16 v[22:25], v[102:105], v[232:235], v[22:25]
	v_mfma_f32_16x16x32_bf16 v[18:21], v[110:113], v[232:235], v[18:21]
	v_mfma_f32_16x16x32_bf16 v[6:9], v[102:105], v[240:243], v[6:9]
	v_mfma_f32_16x16x32_bf16 v[2:5], v[110:113], v[240:243], v[2:5]
	s_barrier
	s_add_i32 s20, s20, 2
	s_add_u32 s16, s16, 0x100
	s_addc_u32 s17, s17, 0
	s_add_u32 s18, s18, 0x100
	s_addc_u32 s19, s19, 0
	s_cmp_gt_u32 s20, 29
	s_cbranch_scc0 .LBB0_535
	s_setprio 0
	s_and_b64 vcc, exec, s[76:77]
	s_cbranch_vccz .LBB0_538
	s_barrier

; #define PG8_STAGE(bufoff, gbase, voff) do { _Pragma("unroll") for (int _i = 0; _i < 2; ++_i) \
;         __builtin_amdgcn_global_load_lds((const unsigned*)((const char*)(gbase) + (voff)[_i]), (LAS unsigned*)(lds + (bufoff) + ldsw + _i * 8192), 16, 0, 0); } while (0)
; #define PG8_LDA(dst, b, h) do { _Pragma("unroll") for (int m = 0; m < 4; ++m) _Pragma("unroll") for (int k = 0; k < 2; ++k) dst[m][k] = *(const LAS bf16x8*)(lds + PG8_SA(b, h) + aoff + m * 2048 + k * 1024); } while (0)
; #define PG8_LDB(dst, b, h) do { _Pragma("unroll") for (int n = 0; n < 2; ++n) _Pragma("unroll") for (int k = 0; k < 2; ++k) dst[n][k] = *(const LAS bf16x8*)(lds + PG8_SB(b, h) + boff + n * 2048 + k * 1024); } while (0)
; #define PG8_MMA(ai, bj, At, Bt) do { __builtin_amdgcn_s_setprio(1); _Pragma("unroll") for (int m = 0; m < 4; ++m) _Pragma("unroll") for (int n = 0; n < 2; ++n) _Pragma("unroll") for (int k = 0; k < 2; ++k) \
;         acc[ai][bj][m][n] = __builtin_amdgcn_mfma_f32_16x16x32_bf16(Bt[n][k], At[m][k], acc[ai][bj][m][n], 0, 0, 0); __builtin_amdgcn_s_setprio(0); } while (0)
; #define PG8_WAIT_V(n) asm volatile("s_waitcnt vmcnt(" #n ")" ::: "memory")
; #define PG8_WAIT_L(n) asm volatile("s_waitcnt lgkmcnt(" #n ")" ::: "memory")
; #define PG8_BAR __builtin_amdgcn_s_barrier()
; #define PG8_SCHED __builtin_amdgcn_sched_barrier(0)
; template <class Epi, class Sched, bool ALIGN_EPI = false, bool SP2 = false>
; __device__ __forceinline__ void gemm_phase(LAS unsigned char* lds, const Gemm g, const Sched& S, const Epi& E) {
;     ...
;         for (int t = 0; t < nt; t += 2) {
;             const bool last = (t == nt - 2);
;             const char* a1 = cA + (size_t)(t + 1) * kstep;
;             const char* a2 = last ? nA : cA + (size_t)(t + 2) * kstep; const char* b2 = last ? nB : cB + (size_t)(t + 2) * kstep;
;             const char* a3 = a2 + kstep; const char* b3 = b2 + kstep;
;             if (last && has_next) S.a_ready(nxt);
;             if constexpr (SP2) {
;             PG8_LDB(B0, 0, 0); PG8_LDB(B1, 0, 1); PG8_SCHED; PG8_LDA(At, 0, 0); PG8_STAGE(PG8_SA(1, 1), a1 + hstep, voffA);
;             PG8_WAIT_V(8); PG8_WAIT_L(0); PG8_BAR; PG8_MMA(0, 0, At, B0); PG8_MMA(0, 1, At, B1); PG8_BAR; PG8_SCHED;
;             PG8_LDA(At, 0, 1); PG8_STAGE(PG8_SB(0, 0), b2, voffB); PG8_STAGE(PG8_SB(0, 1), b2 + hstepB, voffB); PG8_STAGE(PG8_SA(0, 0), a2, voffA);
.LBB0_1225:
	ds_read_b128 v[140:143], v135
	ds_read_b128 v[144:147], v135 offset:1024
	ds_read_b128 v[148:151], v135 offset:2048
	ds_read_b128 v[152:155], v135 offset:3072
	ds_read_b128 v[156:159], v136
	ds_read_b128 v[160:163], v136 offset:1024
	ds_read_b128 v[164:167], v136 offset:2048
	ds_read_b128 v[168:171], v136 offset:3072
	s_add_i32 s16, s18, 2
	s_mov_b32 s17, s13
	s_or_b32 s12, s18, 1
	s_lshl_b64 s[20:21], s[16:17], 7
	s_cmp_lg_u32 s18, s33
	s_cselect_b32 s18, s20, 0
	s_cselect_b32 s17, s21, 0
	s_add_u32 s20, s8, s18
	s_addc_u32 s21, s9, s17
	s_add_u32 s18, s4, s18
	s_addc_u32 s19, s5, s17
	s_lshl_b64 s[44:45], s[12:13], 7
	s_add_u32 s44, s10, s44
	s_addc_u32 s45, s11, s45
	s_mov_b32 m0, s34
	v_lshl_add_u64 v[204:205], s[44:45], 0, v[132:133]
	ds_read_b128 v[172:175], v137
	ds_read_b128 v[176:179], v137 offset:1024
	ds_read_b128 v[180:183], v137 offset:2048
	ds_read_b128 v[184:187], v137 offset:3072
	ds_read_b128 v[188:191], v137 offset:4096
	ds_read_b128 v[192:195], v137 offset:5120
	ds_read_b128 v[196:199], v137 offset:6144
	ds_read_b128 v[200:203], v137 offset:7168
	global_load_lds_dwordx4 v[204:205], off
	v_lshl_add_u64 v[204:205], s[44:45], 0, v[130:131]
	s_mov_b32 m0, s35
	s_nop 0
	global_load_lds_dwordx4 v[204:205], off
	s_waitcnt vmcnt(8)
	s_waitcnt lgkmcnt(0)
	s_barrier
	s_setprio 1
	v_mfma_f32_16x16x32_bf16 v[126:129], v[140:143], v[172:175], v[126:129]
	v_mfma_f32_16x16x32_bf16 v[94:97], v[148:151], v[172:175], v[94:97]
	v_mfma_f32_16x16x32_bf16 v[122:125], v[140:143], v[180:183], v[122:125]
	v_mfma_f32_16x16x32_bf16 v[90:93], v[148:151], v[180:183], v[90:93]
	v_mfma_f32_16x16x32_bf16 v[118:121], v[140:143], v[188:191], v[118:121]
	v_mfma_f32_16x16x32_bf16 v[86:89], v[148:151], v[188:191], v[86:89]
	v_mfma_f32_16x16x32_bf16 v[114:117], v[140:143], v[196:199], v[114:117]
	v_mfma_f32_16x16x32_bf16 v[82:85], v[148:151], v[196:199], v[82:85]
	v_mfma_f32_16x16x32_bf16 v[126:129], v[144:147], v[176:179], v[126:129]
	v_mfma_f32_16x16x32_bf16 v[94:97], v[152:155], v[176:179], v[94:97]
	v_mfma_f32_16x16x32_bf16 v[122:125], v[144:147], v[184:187], v[122:125]
	v_mfma_f32_16x16x32_bf16 v[90:93], v[152:155], v[184:187], v[90:93]
	v_mfma_f32_16x16x32_bf16 v[118:121], v[144:147], v[192:195], v[118:121]
	v_mfma_f32_16x16x32_bf16 v[86:89], v[152:155], v[192:195], v[86:89]
	v_mfma_f32_16x16x32_bf16 v[114:117], v[144:147], v[200:203], v[114:117]
	v_mfma_f32_16x16x32_bf16 v[82:85], v[152:155], v[200:203], v[82:85]
	s_setprio 0
	s_setprio 1
	v_mfma_f32_16x16x32_bf16 v[70:73], v[156:159], v[172:175], v[70:73]
	v_mfma_f32_16x16x32_bf16 v[42:45], v[164:167], v[172:175], v[42:45]
	v_mfma_f32_16x16x32_bf16 v[62:65], v[156:159], v[180:183], v[62:65]
	v_mfma_f32_16x16x32_bf16 v[34:37], v[164:167], v[180:183], v[34:37]
	v_mfma_f32_16x16x32_bf16 v[54:57], v[156:159], v[188:191], v[54:57]
	v_mfma_f32_16x16x32_bf16 v[26:29], v[164:167], v[188:191], v[26:29]
	v_mfma_f32_16x16x32_bf16 v[50:53], v[156:159], v[196:199], v[50:53]
	v_mfma_f32_16x16x32_bf16 v[18:21], v[164:167], v[196:199], v[18:21]
	v_mfma_f32_16x16x32_bf16 v[70:73], v[160:163], v[176:179], v[70:73]
	v_mfma_f32_16x16x32_bf16 v[42:45], v[168:171], v[176:179], v[42:45]
	v_mfma_f32_16x16x32_bf16 v[62:65], v[160:163], v[184:187], v[62:65]
	v_mfma_f32_16x16x32_bf16 v[34:37], v[168:171], v[184:187], v[34:37]
	v_mfma_f32_16x16x32_bf16 v[54:57], v[160:163], v[192:195], v[54:57]
	v_mfma_f32_16x16x32_bf16 v[26:29], v[168:171], v[192:195], v[26:29]
	v_mfma_f32_16x16x32_bf16 v[50:53], v[160:163], v[200:203], v[50:53]
	v_mfma_f32_16x16x32_bf16 v[18:21], v[168:171], v[200:203], v[18:21]
	s_setprio 0
	s_barrier
	s_mov_b32 m0, s36
	v_lshl_add_u64 v[204:205], s[18:19], 0, v[132:133]
	s_add_u32 s44, s18, 0x80000
	ds_read_b128 v[172:175], v137 offset:16384
	ds_read_b128 v[176:179], v137 offset:17408
	ds_read_b128 v[180:183], v137 offset:18432
	ds_read_b128 v[184:187], v137 offset:19456
	ds_read_b128 v[188:191], v137 offset:20480
	ds_read_b128 v[192:195], v137 offset:21504
	ds_read_b128 v[196:199], v137 offset:22528
	ds_read_b128 v[200:203], v137 offset:23552
	global_load_lds_dwordx4 v[204:205], off
	v_lshl_add_u64 v[206:207], s[18:19], 0, v[130:131]
	s_mov_b32 m0, s37
	s_addc_u32 s45, s19, 0
	global_load_lds_dwordx4 v[206:207], off
	v_lshl_add_u64 v[208:209], s[44:45], 0, v[132:133]
	s_mov_b32 m0, s38
	v_lshl_add_u64 v[210:211], s[20:21], 0, v[130:131]
	global_load_lds_dwordx4 v[208:209], off
	v_lshl_add_u64 v[208:209], s[44:45], 0, v[130:131]
	s_mov_b32 m0, s39
	s_nop 0
	global_load_lds_dwordx4 v[208:209], off
	v_lshl_add_u64 v[208:209], s[20:21], 0, v[132:133]
	s_mov_b32 m0, s3
	s_nop 0
	global_load_lds_dwordx4 v[208:209], off
	s_mov_b32 m0, s24
	s_nop 0
	global_load_lds_dwordx4 v[210:211], off
	s_waitcnt vmcnt(8)
	s_waitcnt lgkmcnt(0)
	s_barrier
; #define PG8_STAGE(bufoff, gbase, voff) do { _Pragma("unroll") for (int _i = 0; _i < 2; ++_i) \
;         __builtin_amdgcn_global_load_lds((const unsigned*)((const char*)(gbase) + (voff)[_i]), (LAS unsigned*)(lds + (bufoff) + ldsw + _i * 8192), 16, 0, 0); } while (0)
; #define PG8_LDA(dst, b, h) do { _Pragma("unroll") for (int m = 0; m < 4; ++m) _Pragma("unroll") for (int k = 0; k < 2; ++k) dst[m][k] = *(const LAS bf16x8*)(lds + PG8_SA(b, h) + aoff + m * 2048 + k * 1024); } while (0)
; #define PG8_LDB(dst, b, h) do { _Pragma("unroll") for (int n = 0; n < 2; ++n) _Pragma("unroll") for (int k = 0; k < 2; ++k) dst[n][k] = *(const LAS bf16x8*)(lds + PG8_SB(b, h) + boff + n * 2048 + k * 1024); } while (0)
; #define PG8_MMA(ai, bj, At, Bt) do { __builtin_amdgcn_s_setprio(1); _Pragma("unroll") for (int m = 0; m < 4; ++m) _Pragma("unroll") for (int n = 0; n < 2; ++n) _Pragma("unroll") for (int k = 0; k < 2; ++k) \
;         acc[ai][bj][m][n] = __builtin_amdgcn_mfma_f32_16x16x32_bf16(Bt[n][k], At[m][k], acc[ai][bj][m][n], 0, 0, 0); __builtin_amdgcn_s_setprio(0); } while (0)
; #define PG8_WAIT_V(n) asm volatile("s_waitcnt vmcnt(" #n ")" ::: "memory")
; #define PG8_WAIT_L(n) asm volatile("s_waitcnt lgkmcnt(" #n ")" ::: "memory")
; #define PG8_BAR __builtin_amdgcn_s_barrier()
; #define PG8_SCHED __builtin_amdgcn_sched_barrier(0)
; template <class Epi, class Sched, bool ALIGN_EPI = false, bool SP2 = false>
; __device__ __forceinline__ void gemm_phase(LAS unsigned char* lds, const Gemm g, const Sched& S, const Epi& E) {
;     ...
;             PG8_WAIT_V(8); PG8_WAIT_L(0); PG8_BAR; PG8_MMA(1, 0, At, B0); PG8_MMA(1, 1, At, B1); PG8_BAR; PG8_SCHED;
;             PG8_LDB(B0, 1, 0); PG8_LDB(B1, 1, 1); PG8_SCHED; PG8_LDA(At, 1, 0); PG8_STAGE(PG8_SA(0, 1), a2 + hstep, voffA);
;             PG8_WAIT_V(8); PG8_WAIT_L(0); PG8_BAR; PG8_MMA(0, 0, At, B0); PG8_MMA(0, 1, At, B1); PG8_BAR; PG8_SCHED;
;             PG8_LDA(At, 1, 1); PG8_STAGE(PG8_SB(1, 0), b3, voffB); PG8_STAGE(PG8_SB(1, 1), b3 + hstepB, voffB); PG8_STAGE(PG8_SA(1, 0), a3, voffA);
	s_setprio 1
	v_mfma_f32_16x16x32_bf16 v[110:113], v[140:143], v[172:175], v[110:113]
	v_mfma_f32_16x16x32_bf16 v[78:81], v[148:151], v[172:175], v[78:81]
	v_mfma_f32_16x16x32_bf16 v[106:109], v[140:143], v[180:183], v[106:109]
	v_mfma_f32_16x16x32_bf16 v[74:77], v[148:151], v[180:183], v[74:77]
	v_mfma_f32_16x16x32_bf16 v[102:105], v[140:143], v[188:191], v[102:105]
	v_mfma_f32_16x16x32_bf16 v[66:69], v[148:151], v[188:191], v[66:69]
	v_mfma_f32_16x16x32_bf16 v[98:101], v[140:143], v[196:199], v[98:101]
	v_mfma_f32_16x16x32_bf16 v[58:61], v[148:151], v[196:199], v[58:61]
	v_mfma_f32_16x16x32_bf16 v[110:113], v[144:147], v[176:179], v[110:113]
	v_mfma_f32_16x16x32_bf16 v[78:81], v[152:155], v[176:179], v[78:81]
	v_mfma_f32_16x16x32_bf16 v[106:109], v[144:147], v[184:187], v[106:109]
	v_mfma_f32_16x16x32_bf16 v[74:77], v[152:155], v[184:187], v[74:77]
	v_mfma_f32_16x16x32_bf16 v[102:105], v[144:147], v[192:195], v[102:105]
	v_mfma_f32_16x16x32_bf16 v[66:69], v[152:155], v[192:195], v[66:69]
	v_mfma_f32_16x16x32_bf16 v[98:101], v[144:147], v[200:203], v[98:101]
	v_mfma_f32_16x16x32_bf16 v[58:61], v[152:155], v[200:203], v[58:61]
	s_setprio 0
	s_setprio 1
	v_mfma_f32_16x16x32_bf16 v[46:49], v[156:159], v[172:175], v[46:49]
	v_mfma_f32_16x16x32_bf16 v[14:17], v[164:167], v[172:175], v[14:17]
	v_mfma_f32_16x16x32_bf16 v[38:41], v[156:159], v[180:183], v[38:41]
	v_mfma_f32_16x16x32_bf16 v[10:13], v[164:167], v[180:183], v[10:13]
	v_mfma_f32_16x16x32_bf16 v[30:33], v[156:159], v[188:191], v[30:33]
	v_mfma_f32_16x16x32_bf16 v[6:9], v[164:167], v[188:191], v[6:9]
	v_mfma_f32_16x16x32_bf16 v[22:25], v[156:159], v[196:199], v[22:25]
	v_mfma_f32_16x16x32_bf16 v[2:5], v[164:167], v[196:199], v[2:5]
	v_mfma_f32_16x16x32_bf16 v[46:49], v[160:163], v[176:179], v[46:49]
	v_mfma_f32_16x16x32_bf16 v[14:17], v[168:171], v[176:179], v[14:17]
	v_mfma_f32_16x16x32_bf16 v[38:41], v[160:163], v[184:187], v[38:41]
	v_mfma_f32_16x16x32_bf16 v[10:13], v[168:171], v[184:187], v[10:13]
	v_mfma_f32_16x16x32_bf16 v[30:33], v[160:163], v[192:195], v[30:33]
	v_mfma_f32_16x16x32_bf16 v[6:9], v[168:171], v[192:195], v[6:9]
	v_mfma_f32_16x16x32_bf16 v[22:25], v[160:163], v[200:203], v[22:25]
	v_mfma_f32_16x16x32_bf16 v[2:5], v[168:171], v[200:203], v[2:5]
	s_setprio 0
	s_barrier
	ds_read_b128 v[140:143], v138
	ds_read_b128 v[144:147], v138 offset:1024
	ds_read_b128 v[148:151], v138 offset:2048
	ds_read_b128 v[152:155], v138 offset:3072
	ds_read_b128 v[156:159], v139
	ds_read_b128 v[160:163], v139 offset:1024
	ds_read_b128 v[164:167], v139 offset:2048
	ds_read_b128 v[168:171], v139 offset:3072
	s_add_u32 s20, s20, 0x80000
	s_addc_u32 s21, s21, 0
	s_mov_b32 m0, s25
	v_lshl_add_u64 v[212:213], s[20:21], 0, v[132:133]
	ds_read_b128 v[172:175], v137 offset:32768
	ds_read_b128 v[176:179], v137 offset:33792
	ds_read_b128 v[180:183], v137 offset:34816
	ds_read_b128 v[184:187], v137 offset:35840
	ds_read_b128 v[188:191], v137 offset:36864
	ds_read_b128 v[192:195], v137 offset:37888
	ds_read_b128 v[196:199], v137 offset:38912
	ds_read_b128 v[200:203], v137 offset:39936
	global_load_lds_dwordx4 v[212:213], off
	v_lshl_add_u64 v[212:213], s[20:21], 0, v[130:131]
	s_mov_b32 m0, s28
	s_nop 0
	global_load_lds_dwordx4 v[212:213], off
	s_waitcnt vmcnt(8)
	s_waitcnt lgkmcnt(0)
	s_barrier
	s_setprio 1
	v_mfma_f32_16x16x32_bf16 v[126:129], v[140:143], v[172:175], v[126:129]
	v_mfma_f32_16x16x32_bf16 v[94:97], v[148:151], v[172:175], v[94:97]
	v_mfma_f32_16x16x32_bf16 v[122:125], v[140:143], v[180:183], v[122:125]
	v_mfma_f32_16x16x32_bf16 v[90:93], v[148:151], v[180:183], v[90:93]
	v_mfma_f32_16x16x32_bf16 v[118:121], v[140:143], v[188:191], v[118:121]
	v_mfma_f32_16x16x32_bf16 v[86:89], v[148:151], v[188:191], v[86:89]
	v_mfma_f32_16x16x32_bf16 v[114:117], v[140:143], v[196:199], v[114:117]
	v_mfma_f32_16x16x32_bf16 v[82:85], v[148:151], v[196:199], v[82:85]
	v_mfma_f32_16x16x32_bf16 v[126:129], v[144:147], v[176:179], v[126:129]
	v_mfma_f32_16x16x32_bf16 v[94:97], v[152:155], v[176:179], v[94:97]
	v_mfma_f32_16x16x32_bf16 v[122:125], v[144:147], v[184:187], v[122:125]
	v_mfma_f32_16x16x32_bf16 v[90:93], v[152:155], v[184:187], v[90:93]
	v_mfma_f32_16x16x32_bf16 v[118:121], v[144:147], v[192:195], v[118:121]
	v_mfma_f32_16x16x32_bf16 v[86:89], v[152:155], v[192:195], v[86:89]
	v_mfma_f32_16x16x32_bf16 v[114:117], v[144:147], v[200:203], v[114:117]
	v_mfma_f32_16x16x32_bf16 v[82:85], v[152:155], v[200:203], v[82:85]
	s_setprio 0
	s_setprio 1
	v_mfma_f32_16x16x32_bf16 v[70:73], v[156:159], v[172:175], v[70:73]
	v_mfma_f32_16x16x32_bf16 v[42:45], v[164:167], v[172:175], v[42:45]
	v_mfma_f32_16x16x32_bf16 v[62:65], v[156:159], v[180:183], v[62:65]
	v_mfma_f32_16x16x32_bf16 v[34:37], v[164:167], v[180:183], v[34:37]
	v_mfma_f32_16x16x32_bf16 v[54:57], v[156:159], v[188:191], v[54:57]
	v_mfma_f32_16x16x32_bf16 v[26:29], v[164:167], v[188:191], v[26:29]
	v_mfma_f32_16x16x32_bf16 v[50:53], v[156:159], v[196:199], v[50:53]
	v_mfma_f32_16x16x32_bf16 v[18:21], v[164:167], v[196:199], v[18:21]
	v_mfma_f32_16x16x32_bf16 v[70:73], v[160:163], v[176:179], v[70:73]
	v_mfma_f32_16x16x32_bf16 v[42:45], v[168:171], v[176:179], v[42:45]
	v_mfma_f32_16x16x32_bf16 v[62:65], v[160:163], v[184:187], v[62:65]
	v_mfma_f32_16x16x32_bf16 v[34:37], v[168:171], v[184:187], v[34:37]
	v_mfma_f32_16x16x32_bf16 v[54:57], v[160:163], v[192:195], v[54:57]
	v_mfma_f32_16x16x32_bf16 v[26:29], v[168:171], v[192:195], v[26:29]
	v_mfma_f32_16x16x32_bf16 v[50:53], v[160:163], v[200:203], v[50:53]
	v_mfma_f32_16x16x32_bf16 v[18:21], v[168:171], v[200:203], v[18:21]
	s_setprio 0
	s_barrier
; #define PG8_STAGE(bufoff, gbase, voff) do { _Pragma("unroll") for (int _i = 0; _i < 2; ++_i) \
;         __builtin_amdgcn_global_load_lds((const unsigned*)((const char*)(gbase) + (voff)[_i]), (LAS unsigned*)(lds + (bufoff) + ldsw + _i * 8192), 16, 0, 0); } while (0)
; #define PG8_LDA(dst, b, h) do { _Pragma("unroll") for (int m = 0; m < 4; ++m) _Pragma("unroll") for (int k = 0; k < 2; ++k) dst[m][k] = *(const LAS bf16x8*)(lds + PG8_SA(b, h) + aoff + m * 2048 + k * 1024); } while (0)
; #define PG8_MMA(ai, bj, At, Bt) do { __builtin_amdgcn_s_setprio(1); _Pragma("unroll") for (int m = 0; m < 4; ++m) _Pragma("unroll") for (int n = 0; n < 2; ++n) _Pragma("unroll") for (int k = 0; k < 2; ++k) \
;         acc[ai][bj][m][n] = __builtin_amdgcn_mfma_f32_16x16x32_bf16(Bt[n][k], At[m][k], acc[ai][bj][m][n], 0, 0, 0); __builtin_amdgcn_s_setprio(0); } while (0)
; #define PG8_WAIT_V(n) asm volatile("s_waitcnt vmcnt(" #n ")" ::: "memory")
; #define PG8_WAIT_L(n) asm volatile("s_waitcnt lgkmcnt(" #n ")" ::: "memory")
; #define PG8_BAR __builtin_amdgcn_s_barrier()
; #define PG8_SCHED __builtin_amdgcn_sched_barrier(0)
; template <class Epi, class Sched, bool ALIGN_EPI = false, bool SP2 = false>
; __device__ __forceinline__ void gemm_phase(LAS unsigned char* lds, const Gemm g, const Sched& S, const Epi& E) {
;     ...
;             PG8_LDA(At, 1, 1); PG8_STAGE(PG8_SB(1, 0), b3, voffB); PG8_STAGE(PG8_SB(1, 1), b3 + hstepB, voffB); PG8_STAGE(PG8_SA(1, 0), a3, voffA);
;             PG8_WAIT_V(8); PG8_WAIT_L(0); PG8_BAR; PG8_MMA(1, 0, At, B0); PG8_MMA(1, 1, At, B1); PG8_BAR; PG8_SCHED;
;     ...
;         if constexpr (ALIGN_EPI) { if (wr == 0) PG8_BAR; }
	s_mov_b32 m0, s40
	v_lshl_add_u64 v[204:205], v[204:205], 0, s[14:15]
	s_add_u32 s18, s18, 0x80080
	ds_read_b128 v[172:175], v137 offset:49152
	ds_read_b128 v[176:179], v137 offset:50176
	ds_read_b128 v[180:183], v137 offset:51200
	ds_read_b128 v[184:187], v137 offset:52224
	ds_read_b128 v[188:191], v137 offset:53248
	ds_read_b128 v[192:195], v137 offset:54272
	ds_read_b128 v[196:199], v137 offset:55296
	ds_read_b128 v[200:203], v137 offset:56320
	global_load_lds_dwordx4 v[204:205], off
	v_lshl_add_u64 v[204:205], v[206:207], 0, s[14:15]
	s_mov_b32 m0, s41
	s_addc_u32 s19, s19, 0
	global_load_lds_dwordx4 v[204:205], off
	v_lshl_add_u64 v[204:205], s[18:19], 0, v[132:133]
	s_mov_b32 m0, s42
	s_nop 0
	global_load_lds_dwordx4 v[204:205], off
	v_lshl_add_u64 v[204:205], s[18:19], 0, v[130:131]
	s_mov_b32 m0, s43
	s_nop 0
	global_load_lds_dwordx4 v[204:205], off
	v_lshl_add_u64 v[204:205], v[208:209], 0, s[14:15]
	s_mov_b32 m0, s30
	s_nop 0
	global_load_lds_dwordx4 v[204:205], off
	v_lshl_add_u64 v[204:205], v[210:211], 0, s[14:15]
	s_mov_b32 m0, s31
	s_nop 0
	global_load_lds_dwordx4 v[204:205], off
	s_waitcnt vmcnt(8)
	s_waitcnt lgkmcnt(0)
	s_barrier
	s_setprio 1
	v_mfma_f32_16x16x32_bf16 v[110:113], v[140:143], v[172:175], v[110:113]
	v_mfma_f32_16x16x32_bf16 v[78:81], v[148:151], v[172:175], v[78:81]
	v_mfma_f32_16x16x32_bf16 v[106:109], v[140:143], v[180:183], v[106:109]
	v_mfma_f32_16x16x32_bf16 v[74:77], v[148:151], v[180:183], v[74:77]
	v_mfma_f32_16x16x32_bf16 v[102:105], v[140:143], v[188:191], v[102:105]
	v_mfma_f32_16x16x32_bf16 v[66:69], v[148:151], v[188:191], v[66:69]
	v_mfma_f32_16x16x32_bf16 v[98:101], v[140:143], v[196:199], v[98:101]
	v_mfma_f32_16x16x32_bf16 v[58:61], v[148:151], v[196:199], v[58:61]
	v_mfma_f32_16x16x32_bf16 v[110:113], v[144:147], v[176:179], v[110:113]
	v_mfma_f32_16x16x32_bf16 v[78:81], v[152:155], v[176:179], v[78:81]
	v_mfma_f32_16x16x32_bf16 v[106:109], v[144:147], v[184:187], v[106:109]
	v_mfma_f32_16x16x32_bf16 v[74:77], v[152:155], v[184:187], v[74:77]
	v_mfma_f32_16x16x32_bf16 v[102:105], v[144:147], v[192:195], v[102:105]
	v_mfma_f32_16x16x32_bf16 v[66:69], v[152:155], v[192:195], v[66:69]
	v_mfma_f32_16x16x32_bf16 v[98:101], v[144:147], v[200:203], v[98:101]
	v_mfma_f32_16x16x32_bf16 v[58:61], v[152:155], v[200:203], v[58:61]
	s_setprio 0
	s_setprio 1
	v_mfma_f32_16x16x32_bf16 v[46:49], v[156:159], v[172:175], v[46:49]
	v_mfma_f32_16x16x32_bf16 v[14:17], v[164:167], v[172:175], v[14:17]
	v_mfma_f32_16x16x32_bf16 v[38:41], v[156:159], v[180:183], v[38:41]
	v_mfma_f32_16x16x32_bf16 v[10:13], v[164:167], v[180:183], v[10:13]
	v_mfma_f32_16x16x32_bf16 v[30:33], v[156:159], v[188:191], v[30:33]
	v_mfma_f32_16x16x32_bf16 v[6:9], v[164:167], v[188:191], v[6:9]
	v_mfma_f32_16x16x32_bf16 v[22:25], v[156:159], v[196:199], v[22:25]
	v_mfma_f32_16x16x32_bf16 v[2:5], v[164:167], v[196:199], v[2:5]
	v_mfma_f32_16x16x32_bf16 v[46:49], v[160:163], v[176:179], v[46:49]
	v_mfma_f32_16x16x32_bf16 v[14:17], v[168:171], v[176:179], v[14:17]
	v_mfma_f32_16x16x32_bf16 v[38:41], v[160:163], v[184:187], v[38:41]
	v_mfma_f32_16x16x32_bf16 v[10:13], v[168:171], v[184:187], v[10:13]
	v_mfma_f32_16x16x32_bf16 v[30:33], v[160:163], v[192:195], v[30:33]
	v_mfma_f32_16x16x32_bf16 v[6:9], v[168:171], v[192:195], v[6:9]
	v_mfma_f32_16x16x32_bf16 v[22:25], v[160:163], v[200:203], v[22:25]
	v_mfma_f32_16x16x32_bf16 v[2:5], v[168:171], v[200:203], v[2:5]
	s_setprio 0
	s_barrier
	s_cmp_ge_u32 s16, s29
	s_mov_b32 s18, s16
	s_cbranch_scc0 .LBB0_1225
	v_readlane_b32 s30, v252, 2
	v_readlane_b32 s34, v252, 37
	s_cmpk_lt_u32 s22, 0x100
	v_readlane_b32 s31, v252, 3
	v_readlane_b32 s35, v252, 38
	s_cbranch_scc0 .LBB0_1228
	s_barrier

; #define PG8_STAGE(bufoff, gbase, voff) do { _Pragma("unroll") for (int _i = 0; _i < 2; ++_i) \
;         __builtin_amdgcn_global_load_lds((const unsigned*)((const char*)(gbase) + (voff)[_i]), (LAS unsigned*)(lds + (bufoff) + ldsw + _i * 8192), 16, 0, 0); } while (0)
; #define PG8_LDA(dst, b, h) do { _Pragma("unroll") for (int m = 0; m < 4; ++m) _Pragma("unroll") for (int k = 0; k < 2; ++k) dst[m][k] = *(const LAS bf16x8*)(lds + PG8_SA(b, h) + aoff + m * 2048 + k * 1024); } while (0)
; #define PG8_LDB(dst, b, h) do { _Pragma("unroll") for (int n = 0; n < 2; ++n) _Pragma("unroll") for (int k = 0; k < 2; ++k) dst[n][k] = *(const LAS bf16x8*)(lds + PG8_SB(b, h) + boff + n * 2048 + k * 1024); } while (0)
; #define PG8_MMA(ai, bj, At, Bt) do { __builtin_amdgcn_s_setprio(1); _Pragma("unroll") for (int m = 0; m < 4; ++m) _Pragma("unroll") for (int n = 0; n < 2; ++n) _Pragma("unroll") for (int k = 0; k < 2; ++k) \
;         acc[ai][bj][m][n] = __builtin_amdgcn_mfma_f32_16x16x32_bf16(Bt[n][k], At[m][k], acc[ai][bj][m][n], 0, 0, 0); __builtin_amdgcn_s_setprio(0); } while (0)
; #define PG8_WAIT_V(n) asm volatile("s_waitcnt vmcnt(" #n ")" ::: "memory")
; #define PG8_WAIT_L(n) asm volatile("s_waitcnt lgkmcnt(" #n ")" ::: "memory")
; template <class Epi, class Sched, bool ALIGN_EPI = false, bool SP2 = false>
; __device__ __forceinline__ void gemm_phase(LAS unsigned char* lds, const Gemm g, const Sched& S, const Epi& E) {
;     ...
;         for (int t = 0; t < nt; t += 2) {
;             const bool last = (t == nt - 2);
;             const char* a1 = cA + (size_t)(t + 1) * kstep;
;             const char* a2 = last ? nA : cA + (size_t)(t + 2) * kstep; const char* b2 = last ? nB : cB + (size_t)(t + 2) * kstep;
;             const char* a3 = a2 + kstep; const char* b3 = b2 + kstep;
;             if (last && has_next) S.a_ready(nxt);
;             if constexpr (SP2) {
;             PG8_LDB(B0, 0, 0); PG8_LDB(B1, 0, 1); PG8_SCHED; PG8_LDA(At, 0, 0); PG8_STAGE(PG8_SA(1, 1), a1 + hstep, voffA);
;             PG8_WAIT_V(8); PG8_WAIT_L(0); PG8_BAR; PG8_MMA(0, 0, At, B0); PG8_MMA(0, 1, At, B1); PG8_BAR; PG8_SCHED;
;             PG8_LDA(At, 0, 1); PG8_STAGE(PG8_SB(0, 0), b2, voffB); PG8_STAGE(PG8_SB(0, 1), b2 + hstepB, voffB); PG8_STAGE(PG8_SA(0, 0), a2, voffA);
;             PG8_WAIT_V(8); PG8_WAIT_L(0); PG8_BAR; PG8_MMA(1, 0, At, B0); PG8_MMA(1, 1, At, B1); PG8_BAR; PG8_SCHED;
.Lprio_1250:
	ds_read_b128 v[50:53], v196
	ds_read_b128 v[54:57], v196 offset:1024
	ds_read_b128 v[138:141], v196 offset:2048
	ds_read_b128 v[142:145], v196 offset:3072
	ds_read_b128 v[146:149], v197
	ds_read_b128 v[150:153], v197 offset:1024
	ds_read_b128 v[174:177], v197 offset:2048
	ds_read_b128 v[178:181], v197 offset:3072
	s_add_u32 s48, s16, 0xfff80080
	s_addc_u32 s49, s17, -1
	s_cmp_eq_u32 s47, 28
	s_cselect_b32 s51, s0, s49
	s_cselect_b32 s50, s3, s48
	s_cselect_b32 s49, s15, s25
	s_cselect_b32 s48, s19, s24
	v_lshl_add_u64 v[190:191], s[16:17], 0, v[166:167]
	s_add_i32 m0, s29, 0xc000
	ds_read_b128 v[182:185], v198
	ds_read_b128 v[186:189], v198 offset:1024
	ds_read_b128 v[202:205], v198 offset:2048
	ds_read_b128 v[206:209], v198 offset:3072
	ds_read_b128 v[210:213], v198 offset:4096
	ds_read_b128 v[214:217], v198 offset:5120
	ds_read_b128 v[218:221], v198 offset:6144
	ds_read_b128 v[222:225], v198 offset:7168
	global_load_lds_dwordx4 v[190:191], off
	v_lshl_add_u64 v[190:191], s[16:17], 0, v[168:169]
	s_add_i32 m0, s29, 0xe000
	s_nop 0
	global_load_lds_dwordx4 v[190:191], off
	s_waitcnt lgkmcnt(0)
	s_barrier
	v_mfma_f32_16x16x32_bf16 v[134:137], v[50:53], v[182:185], 0
	v_mfma_f32_16x16x32_bf16 v[130:133], v[138:141], v[182:185], 0
	v_mfma_f32_16x16x32_bf16 v[118:121], v[50:53], v[202:205], 0
	v_mfma_f32_16x16x32_bf16 v[114:117], v[138:141], v[202:205], 0
	v_mfma_f32_16x16x32_bf16 v[102:105], v[50:53], v[210:213], 0
	v_mfma_f32_16x16x32_bf16 v[98:101], v[138:141], v[210:213], 0
	v_mfma_f32_16x16x32_bf16 v[86:89], v[50:53], v[218:221], 0
	v_mfma_f32_16x16x32_bf16 v[82:85], v[138:141], v[218:221], 0
	v_mfma_f32_16x16x32_bf16 v[134:137], v[54:57], v[186:189], v[134:137]
	v_mfma_f32_16x16x32_bf16 v[130:133], v[142:145], v[186:189], v[130:133]
	v_mfma_f32_16x16x32_bf16 v[118:121], v[54:57], v[206:209], v[118:121]
	v_mfma_f32_16x16x32_bf16 v[114:117], v[142:145], v[206:209], v[114:117]
	v_mfma_f32_16x16x32_bf16 v[102:105], v[54:57], v[214:217], v[102:105]
	v_mfma_f32_16x16x32_bf16 v[98:101], v[142:145], v[214:217], v[98:101]
	v_mfma_f32_16x16x32_bf16 v[86:89], v[54:57], v[222:225], v[86:89]
	v_mfma_f32_16x16x32_bf16 v[82:85], v[142:145], v[222:225], v[82:85]
	v_mfma_f32_16x16x32_bf16 v[126:129], v[146:149], v[182:185], 0
	v_mfma_f32_16x16x32_bf16 v[122:125], v[174:177], v[182:185], 0
	v_mfma_f32_16x16x32_bf16 v[110:113], v[146:149], v[202:205], 0
	v_mfma_f32_16x16x32_bf16 v[106:109], v[174:177], v[202:205], 0
	v_mfma_f32_16x16x32_bf16 v[94:97], v[146:149], v[210:213], 0
	v_mfma_f32_16x16x32_bf16 v[90:93], v[174:177], v[210:213], 0
	v_mfma_f32_16x16x32_bf16 v[78:81], v[146:149], v[218:221], 0
	v_mfma_f32_16x16x32_bf16 v[74:77], v[174:177], v[218:221], 0
	v_mfma_f32_16x16x32_bf16 v[126:129], v[150:153], v[186:189], v[126:129]
	v_mfma_f32_16x16x32_bf16 v[122:125], v[178:181], v[186:189], v[122:125]
	v_mfma_f32_16x16x32_bf16 v[110:113], v[150:153], v[206:209], v[110:113]
	v_mfma_f32_16x16x32_bf16 v[106:109], v[178:181], v[206:209], v[106:109]
	v_mfma_f32_16x16x32_bf16 v[94:97], v[150:153], v[214:217], v[94:97]
	v_mfma_f32_16x16x32_bf16 v[90:93], v[178:181], v[214:217], v[90:93]
	v_mfma_f32_16x16x32_bf16 v[78:81], v[150:153], v[222:225], v[78:81]
	v_mfma_f32_16x16x32_bf16 v[74:77], v[178:181], v[222:225], v[74:77]
	s_barrier
	s_add_i32 s58, s56, s28
	v_lshl_add_u64 v[190:191], s[48:49], 0, v[156:157]
	s_mov_b32 m0, s58
	ds_read_b128 v[182:185], v198 offset:16384
	ds_read_b128 v[186:189], v198 offset:17408
	ds_read_b128 v[202:205], v198 offset:18432
	ds_read_b128 v[206:209], v198 offset:19456
	ds_read_b128 v[210:213], v198 offset:20480
	ds_read_b128 v[214:217], v198 offset:21504
	ds_read_b128 v[218:221], v198 offset:22528
	ds_read_b128 v[222:225], v198 offset:23552
	global_load_lds_dwordx4 v[190:191], off
	s_add_i32 m0, s58, 0x2000
	s_add_u32 s58, s48, 0x20000
	v_lshl_add_u64 v[226:227], s[48:49], 0, v[160:161]
	s_addc_u32 s59, s49, 0
	s_add_i32 s60, s57, s28
	global_load_lds_dwordx4 v[226:227], off
	v_lshl_add_u64 v[228:229], s[58:59], 0, v[156:157]
	s_mov_b32 m0, s60
	v_lshl_add_u64 v[230:231], s[50:51], 0, v[158:159]
	global_load_lds_dwordx4 v[228:229], off
	v_lshl_add_u64 v[228:229], s[58:59], 0, v[160:161]
	s_add_i32 m0, s60, 0x2000
	s_nop 0
	global_load_lds_dwordx4 v[228:229], off
	v_lshl_add_u64 v[228:229], s[50:51], 0, v[154:155]
	s_mov_b32 m0, s29
	s_nop 0
	global_load_lds_dwordx4 v[228:229], off
	s_mov_b32 m0, s30
	s_nop 0
	global_load_lds_dwordx4 v[230:231], off
	s_waitcnt lgkmcnt(0)
	s_barrier
	v_mfma_f32_16x16x32_bf16 v[70:73], v[50:53], v[182:185], 0
	v_mfma_f32_16x16x32_bf16 v[66:69], v[138:141], v[182:185], 0
	v_mfma_f32_16x16x32_bf16 v[46:49], v[50:53], v[202:205], 0
	v_mfma_f32_16x16x32_bf16 v[42:45], v[138:141], v[202:205], 0
	v_mfma_f32_16x16x32_bf16 v[30:33], v[50:53], v[210:213], 0
	v_mfma_f32_16x16x32_bf16 v[26:29], v[138:141], v[210:213], 0
	v_mfma_f32_16x16x32_bf16 v[14:17], v[50:53], v[218:221], 0
	v_mfma_f32_16x16x32_bf16 v[10:13], v[138:141], v[218:221], 0
	v_mfma_f32_16x16x32_bf16 v[70:73], v[54:57], v[186:189], v[70:73]
	v_mfma_f32_16x16x32_bf16 v[66:69], v[142:145], v[186:189], v[66:69]
	v_mfma_f32_16x16x32_bf16 v[46:49], v[54:57], v[206:209], v[46:49]
	v_mfma_f32_16x16x32_bf16 v[42:45], v[142:145], v[206:209], v[42:45]
	v_mfma_f32_16x16x32_bf16 v[30:33], v[54:57], v[214:217], v[30:33]
	v_mfma_f32_16x16x32_bf16 v[26:29], v[142:145], v[214:217], v[26:29]
	v_mfma_f32_16x16x32_bf16 v[14:17], v[54:57], v[222:225], v[14:17]
	v_mfma_f32_16x16x32_bf16 v[10:13], v[142:145], v[222:225], v[10:13]
	v_mfma_f32_16x16x32_bf16 v[38:41], v[146:149], v[202:205], 0
	v_mfma_f32_16x16x32_bf16 v[34:37], v[174:177], v[202:205], 0
	v_mfma_f32_16x16x32_bf16 v[22:25], v[146:149], v[210:213], 0
	v_mfma_f32_16x16x32_bf16 v[18:21], v[174:177], v[210:213], 0
	v_mfma_f32_16x16x32_bf16 v[6:9], v[146:149], v[218:221], 0
	v_mfma_f32_16x16x32_bf16 v[2:5], v[174:177], v[218:221], 0
	v_mfma_f32_16x16x32_bf16 v[50:53], v[146:149], v[182:185], 0
	v_mfma_f32_16x16x32_bf16 v[54:57], v[174:177], v[182:185], 0
	v_mfma_f32_16x16x32_bf16 v[38:41], v[150:153], v[206:209], v[38:41]
	v_mfma_f32_16x16x32_bf16 v[34:37], v[178:181], v[206:209], v[34:37]
	v_mfma_f32_16x16x32_bf16 v[22:25], v[150:153], v[214:217], v[22:25]
	v_mfma_f32_16x16x32_bf16 v[18:21], v[178:181], v[214:217], v[18:21]
	v_mfma_f32_16x16x32_bf16 v[6:9], v[150:153], v[222:225], v[6:9]
	v_mfma_f32_16x16x32_bf16 v[2:5], v[178:181], v[222:225], v[2:5]
	v_mfma_f32_16x16x32_bf16 v[50:53], v[150:153], v[186:189], v[50:53]
	v_mfma_f32_16x16x32_bf16 v[54:57], v[178:181], v[186:189], v[54:57]
	s_barrier
; #define PG8_STAGE(bufoff, gbase, voff) do { _Pragma("unroll") for (int _i = 0; _i < 2; ++_i) \
;         __builtin_amdgcn_global_load_lds((const unsigned*)((const char*)(gbase) + (voff)[_i]), (LAS unsigned*)(lds + (bufoff) + ldsw + _i * 8192), 16, 0, 0); } while (0)
; #define PG8_LDA(dst, b, h) do { _Pragma("unroll") for (int m = 0; m < 4; ++m) _Pragma("unroll") for (int k = 0; k < 2; ++k) dst[m][k] = *(const LAS bf16x8*)(lds + PG8_SA(b, h) + aoff + m * 2048 + k * 1024); } while (0)
; #define PG8_LDB(dst, b, h) do { _Pragma("unroll") for (int n = 0; n < 2; ++n) _Pragma("unroll") for (int k = 0; k < 2; ++k) dst[n][k] = *(const LAS bf16x8*)(lds + PG8_SB(b, h) + boff + n * 2048 + k * 1024); } while (0)
; #define PG8_MMA(ai, bj, At, Bt) do { __builtin_amdgcn_s_setprio(1); _Pragma("unroll") for (int m = 0; m < 4; ++m) _Pragma("unroll") for (int n = 0; n < 2; ++n) _Pragma("unroll") for (int k = 0; k < 2; ++k) \
;         acc[ai][bj][m][n] = __builtin_amdgcn_mfma_f32_16x16x32_bf16(Bt[n][k], At[m][k], acc[ai][bj][m][n], 0, 0, 0); __builtin_amdgcn_s_setprio(0); } while (0)
; #define PG8_WAIT_V(n) asm volatile("s_waitcnt vmcnt(" #n ")" ::: "memory")
; #define PG8_WAIT_L(n) asm volatile("s_waitcnt lgkmcnt(" #n ")" ::: "memory")
; #define PG8_BAR __builtin_amdgcn_s_barrier()
; #define PG8_SCHED __builtin_amdgcn_sched_barrier(0)
; template <class Epi, class Sched, bool ALIGN_EPI = false, bool SP2 = false>
; __device__ __forceinline__ void gemm_phase(LAS unsigned char* lds, const Gemm g, const Sched& S, const Epi& E) {
;     ...
;             PG8_LDB(B0, 1, 0); PG8_LDB(B1, 1, 1); PG8_SCHED; PG8_LDA(At, 1, 0); PG8_STAGE(PG8_SA(0, 1), a2 + hstep, voffA);
;             PG8_WAIT_V(8); PG8_WAIT_L(0); PG8_BAR; PG8_MMA(0, 0, At, B0); PG8_MMA(0, 1, At, B1); PG8_BAR; PG8_SCHED;
;             PG8_LDA(At, 1, 1); PG8_STAGE(PG8_SB(1, 0), b3, voffB); PG8_STAGE(PG8_SB(1, 1), b3 + hstepB, voffB); PG8_STAGE(PG8_SA(1, 0), a3, voffA);
;             PG8_WAIT_V(8); PG8_WAIT_L(0); PG8_BAR; PG8_MMA(1, 0, At, B0); PG8_MMA(1, 1, At, B1); PG8_BAR; PG8_SCHED;
	s_add_i32 s58, 0, 0x18000
	s_add_i32 s59, 0, 0x1c000
	v_add_u32_e32 v142, s58, v1
	v_add_u32_e32 v162, s59, v1
	ds_read_b128 v[58:61], v142
	ds_read_b128 v[62:65], v142 offset:1024
	ds_read_b128 v[138:141], v142 offset:2048
	ds_read_b128 v[142:145], v142 offset:3072
	ds_read_b128 v[146:149], v162
	ds_read_b128 v[150:153], v162 offset:1024
	ds_read_b128 v[174:177], v162 offset:2048
	ds_read_b128 v[178:181], v162 offset:3072
	s_add_u32 s50, s50, 0x80000
	s_addc_u32 s51, s51, 0
	s_mov_b32 m0, s31
	v_lshl_add_u64 v[232:233], s[50:51], 0, v[154:155]
	ds_read_b128 v[182:185], v198 offset:32768
	ds_read_b128 v[186:189], v198 offset:33792
	ds_read_b128 v[202:205], v198 offset:34816
	ds_read_b128 v[206:209], v198 offset:35840
	ds_read_b128 v[210:213], v198 offset:36864
	ds_read_b128 v[214:217], v198 offset:37888
	ds_read_b128 v[218:221], v198 offset:38912
	ds_read_b128 v[222:225], v198 offset:39936
	global_load_lds_dwordx4 v[232:233], off
	v_lshl_add_u64 v[232:233], s[50:51], 0, v[158:159]
	s_mov_b32 m0, s33
	s_nop 0
	global_load_lds_dwordx4 v[232:233], off
	s_waitcnt vmcnt(8)
	s_waitcnt lgkmcnt(0)
	s_barrier
	v_mfma_f32_16x16x32_bf16 v[134:137], v[58:61], v[182:185], v[134:137]
	v_mfma_f32_16x16x32_bf16 v[130:133], v[138:141], v[182:185], v[130:133]
	v_mfma_f32_16x16x32_bf16 v[118:121], v[58:61], v[202:205], v[118:121]
	v_mfma_f32_16x16x32_bf16 v[114:117], v[138:141], v[202:205], v[114:117]
	v_mfma_f32_16x16x32_bf16 v[102:105], v[58:61], v[210:213], v[102:105]
	v_mfma_f32_16x16x32_bf16 v[98:101], v[138:141], v[210:213], v[98:101]
	v_mfma_f32_16x16x32_bf16 v[86:89], v[58:61], v[218:221], v[86:89]
	v_mfma_f32_16x16x32_bf16 v[82:85], v[138:141], v[218:221], v[82:85]
	v_mfma_f32_16x16x32_bf16 v[134:137], v[62:65], v[186:189], v[134:137]
	v_mfma_f32_16x16x32_bf16 v[130:133], v[142:145], v[186:189], v[130:133]
	v_mfma_f32_16x16x32_bf16 v[118:121], v[62:65], v[206:209], v[118:121]
	v_mfma_f32_16x16x32_bf16 v[114:117], v[142:145], v[206:209], v[114:117]
	v_mfma_f32_16x16x32_bf16 v[102:105], v[62:65], v[214:217], v[102:105]
	v_mfma_f32_16x16x32_bf16 v[98:101], v[142:145], v[214:217], v[98:101]
	v_mfma_f32_16x16x32_bf16 v[86:89], v[62:65], v[222:225], v[86:89]
	v_mfma_f32_16x16x32_bf16 v[82:85], v[142:145], v[222:225], v[82:85]
	v_mfma_f32_16x16x32_bf16 v[126:129], v[146:149], v[182:185], v[126:129]
	v_mfma_f32_16x16x32_bf16 v[122:125], v[174:177], v[182:185], v[122:125]
	v_mfma_f32_16x16x32_bf16 v[110:113], v[146:149], v[202:205], v[110:113]
	v_mfma_f32_16x16x32_bf16 v[106:109], v[174:177], v[202:205], v[106:109]
	v_mfma_f32_16x16x32_bf16 v[94:97], v[146:149], v[210:213], v[94:97]
	v_mfma_f32_16x16x32_bf16 v[90:93], v[174:177], v[210:213], v[90:93]
	v_mfma_f32_16x16x32_bf16 v[78:81], v[146:149], v[218:221], v[78:81]
	v_mfma_f32_16x16x32_bf16 v[74:77], v[174:177], v[218:221], v[74:77]
	v_mfma_f32_16x16x32_bf16 v[126:129], v[150:153], v[186:189], v[126:129]
	v_mfma_f32_16x16x32_bf16 v[122:125], v[178:181], v[186:189], v[122:125]
	v_mfma_f32_16x16x32_bf16 v[110:113], v[150:153], v[206:209], v[110:113]
	v_mfma_f32_16x16x32_bf16 v[106:109], v[178:181], v[206:209], v[106:109]
	v_mfma_f32_16x16x32_bf16 v[94:97], v[150:153], v[214:217], v[94:97]
	v_mfma_f32_16x16x32_bf16 v[90:93], v[178:181], v[214:217], v[90:93]
	v_mfma_f32_16x16x32_bf16 v[78:81], v[150:153], v[222:225], v[78:81]
	v_mfma_f32_16x16x32_bf16 v[74:77], v[178:181], v[222:225], v[74:77]
	s_barrier
	s_add_i32 s50, s58, s28
	v_lshl_add_u64 v[190:191], v[190:191], 0, s[10:11]
	s_mov_b32 m0, s50
	ds_read_b128 v[182:185], v198 offset:49152
	ds_read_b128 v[186:189], v198 offset:50176
	ds_read_b128 v[202:205], v198 offset:51200
	ds_read_b128 v[206:209], v198 offset:52224
	ds_read_b128 v[210:213], v198 offset:53248
	ds_read_b128 v[214:217], v198 offset:54272
	ds_read_b128 v[218:221], v198 offset:55296
	ds_read_b128 v[222:225], v198 offset:56320
	global_load_lds_dwordx4 v[190:191], off
	s_add_i32 m0, s50, 0x2000
	s_add_u32 s48, s48, 0x20080
	v_lshl_add_u64 v[190:191], v[226:227], 0, s[10:11]
	s_addc_u32 s49, s49, 0
	s_add_i32 s50, s59, s28
	global_load_lds_dwordx4 v[190:191], off
	v_lshl_add_u64 v[190:191], s[48:49], 0, v[156:157]
	s_mov_b32 m0, s50
	s_nop 0
	global_load_lds_dwordx4 v[190:191], off
	v_lshl_add_u64 v[190:191], s[48:49], 0, v[160:161]
	s_add_i32 m0, s50, 0x2000
	s_nop 0
	global_load_lds_dwordx4 v[190:191], off
	v_lshl_add_u64 v[190:191], v[228:229], 0, s[10:11]
	s_mov_b32 m0, s53
	s_nop 0
	global_load_lds_dwordx4 v[190:191], off
	v_lshl_add_u64 v[190:191], v[230:231], 0, s[10:11]
	s_mov_b32 m0, s54
	s_nop 0
	global_load_lds_dwordx4 v[190:191], off
	s_waitcnt vmcnt(8)
	s_waitcnt lgkmcnt(0)
	s_barrier
	v_mfma_f32_16x16x32_bf16 v[70:73], v[58:61], v[182:185], v[70:73]
	v_mfma_f32_16x16x32_bf16 v[66:69], v[138:141], v[182:185], v[66:69]
	v_mfma_f32_16x16x32_bf16 v[46:49], v[58:61], v[202:205], v[46:49]
	v_mfma_f32_16x16x32_bf16 v[42:45], v[138:141], v[202:205], v[42:45]
	v_mfma_f32_16x16x32_bf16 v[30:33], v[58:61], v[210:213], v[30:33]
	v_mfma_f32_16x16x32_bf16 v[26:29], v[138:141], v[210:213], v[26:29]
	v_mfma_f32_16x16x32_bf16 v[14:17], v[58:61], v[218:221], v[14:17]
	v_mfma_f32_16x16x32_bf16 v[10:13], v[138:141], v[218:221], v[10:13]
	v_mfma_f32_16x16x32_bf16 v[70:73], v[62:65], v[186:189], v[70:73]
	v_mfma_f32_16x16x32_bf16 v[66:69], v[142:145], v[186:189], v[66:69]
	v_mfma_f32_16x16x32_bf16 v[46:49], v[62:65], v[206:209], v[46:49]
	v_mfma_f32_16x16x32_bf16 v[42:45], v[142:145], v[206:209], v[42:45]
	v_mfma_f32_16x16x32_bf16 v[30:33], v[62:65], v[214:217], v[30:33]
	v_mfma_f32_16x16x32_bf16 v[26:29], v[142:145], v[214:217], v[26:29]
	v_mfma_f32_16x16x32_bf16 v[14:17], v[62:65], v[222:225], v[14:17]
	v_mfma_f32_16x16x32_bf16 v[10:13], v[142:145], v[222:225], v[10:13]
	v_mfma_f32_16x16x32_bf16 v[50:53], v[146:149], v[182:185], v[50:53]
	v_mfma_f32_16x16x32_bf16 v[62:65], v[150:153], v[186:189], v[50:53]
	v_mfma_f32_16x16x32_bf16 v[50:53], v[174:177], v[182:185], v[54:57]
	v_mfma_f32_16x16x32_bf16 v[38:41], v[146:149], v[202:205], v[38:41]
	v_mfma_f32_16x16x32_bf16 v[34:37], v[174:177], v[202:205], v[34:37]
	v_mfma_f32_16x16x32_bf16 v[22:25], v[146:149], v[210:213], v[22:25]
	v_mfma_f32_16x16x32_bf16 v[18:21], v[174:177], v[210:213], v[18:21]
	v_mfma_f32_16x16x32_bf16 v[6:9], v[146:149], v[218:221], v[6:9]
	v_mfma_f32_16x16x32_bf16 v[2:5], v[174:177], v[218:221], v[2:5]
	v_mfma_f32_16x16x32_bf16 v[58:61], v[178:181], v[186:189], v[50:53]
	v_mfma_f32_16x16x32_bf16 v[38:41], v[150:153], v[206:209], v[38:41]
	v_mfma_f32_16x16x32_bf16 v[34:37], v[178:181], v[206:209], v[34:37]
	v_mfma_f32_16x16x32_bf16 v[22:25], v[150:153], v[214:217], v[22:25]
	v_mfma_f32_16x16x32_bf16 v[18:21], v[178:181], v[214:217], v[18:21]
	v_mfma_f32_16x16x32_bf16 v[6:9], v[150:153], v[222:225], v[6:9]
	v_mfma_f32_16x16x32_bf16 v[2:5], v[178:181], v[222:225], v[2:5]
	s_barrier
	s_add_i32 s47, s47, 2
	s_add_u32 s16, s16, 0x100
	s_addc_u32 s17, s17, 0
	s_add_u32 s24, s24, 0x100
	s_addc_u32 s25, s25, 0
	s_cmp_gt_u32 s47, 29
; #define PG8_STAGE(bufoff, gbase, voff) do { _Pragma("unroll") for (int _i = 0; _i < 2; ++_i) \
;         __builtin_amdgcn_global_load_lds((const unsigned*)((const char*)(gbase) + (voff)[_i]), (LAS unsigned*)(lds + (bufoff) + ldsw + _i * 8192), 16, 0, 0); } while (0)
; #define PG8_LDA(dst, b, h) do { _Pragma("unroll") for (int m = 0; m < 4; ++m) _Pragma("unroll") for (int k = 0; k < 2; ++k) dst[m][k] = *(const LAS bf16x8*)(lds + PG8_SA(b, h) + aoff + m * 2048 + k * 1024); } while (0)
; #define PG8_LDB(dst, b, h) do { _Pragma("unroll") for (int n = 0; n < 2; ++n) _Pragma("unroll") for (int k = 0; k < 2; ++k) dst[n][k] = *(const LAS bf16x8*)(lds + PG8_SB(b, h) + boff + n * 2048 + k * 1024); } while (0)
; #define PG8_MMA(ai, bj, At, Bt) do { __builtin_amdgcn_s_setprio(1); _Pragma("unroll") for (int m = 0; m < 4; ++m) _Pragma("unroll") for (int n = 0; n < 2; ++n) _Pragma("unroll") for (int k = 0; k < 2; ++k) \
;         acc[ai][bj][m][n] = __builtin_amdgcn_mfma_f32_16x16x32_bf16(Bt[n][k], At[m][k], acc[ai][bj][m][n], 0, 0, 0); __builtin_amdgcn_s_setprio(0); } while (0)
; #define PG8_WAIT_V(n) asm volatile("s_waitcnt vmcnt(" #n ")" ::: "memory")
; #define PG8_WAIT_L(n) asm volatile("s_waitcnt lgkmcnt(" #n ")" ::: "memory")
; #define PG8_BAR __builtin_amdgcn_s_barrier()
; #define PG8_SCHED __builtin_amdgcn_sched_barrier(0)
; template <class Epi, class Sched, bool ALIGN_EPI = false, bool SP2 = false>
; __device__ __forceinline__ void gemm_phase(LAS unsigned char* lds, const Gemm g, const Sched& S, const Epi& E) {
;     ...
;         for (int t = 0; t < nt; t += 2) {
;             const bool last = (t == nt - 2);
;             const char* a1 = cA + (size_t)(t + 1) * kstep;
;             const char* a2 = last ? nA : cA + (size_t)(t + 2) * kstep; const char* b2 = last ? nB : cB + (size_t)(t + 2) * kstep;
;             const char* a3 = a2 + kstep; const char* b3 = b2 + kstep;
;             if (last && has_next) S.a_ready(nxt);
;             if constexpr (SP2) {
;             PG8_LDB(B0, 0, 0); PG8_LDB(B1, 0, 1); PG8_SCHED; PG8_LDA(At, 0, 0); PG8_STAGE(PG8_SA(1, 1), a1 + hstep, voffA);
;             PG8_WAIT_V(8); PG8_WAIT_L(0); PG8_BAR; PG8_MMA(0, 0, At, B0); PG8_MMA(0, 1, At, B1); PG8_BAR; PG8_SCHED;
;             PG8_LDA(At, 0, 1); PG8_STAGE(PG8_SB(0, 0), b2, voffB); PG8_STAGE(PG8_SB(0, 1), b2 + hstepB, voffB); PG8_STAGE(PG8_SA(0, 0), a2, voffA);
.LBB0_1250:
	ds_read_b128 v[50:53], v196
	ds_read_b128 v[54:57], v196 offset:1024
	ds_read_b128 v[138:141], v196 offset:2048
	ds_read_b128 v[142:145], v196 offset:3072
	ds_read_b128 v[146:149], v197
	ds_read_b128 v[150:153], v197 offset:1024
	ds_read_b128 v[174:177], v197 offset:2048
	ds_read_b128 v[178:181], v197 offset:3072
	s_add_u32 s48, s16, 0xfff80080
	s_addc_u32 s49, s17, -1
	s_cmp_eq_u32 s47, 28
	s_cselect_b32 s51, s0, s49
	s_cselect_b32 s50, s3, s48
	s_cselect_b32 s49, s15, s25
	s_cselect_b32 s48, s19, s24
	v_lshl_add_u64 v[190:191], s[16:17], 0, v[166:167]
	s_add_i32 m0, s29, 0xc000
	ds_read_b128 v[182:185], v198
	ds_read_b128 v[186:189], v198 offset:1024
	ds_read_b128 v[202:205], v198 offset:2048
	ds_read_b128 v[206:209], v198 offset:3072
	ds_read_b128 v[210:213], v198 offset:4096
	ds_read_b128 v[214:217], v198 offset:5120
	ds_read_b128 v[218:221], v198 offset:6144
	ds_read_b128 v[222:225], v198 offset:7168
	global_load_lds_dwordx4 v[190:191], off
	v_lshl_add_u64 v[190:191], s[16:17], 0, v[168:169]
	s_add_i32 m0, s29, 0xe000
	s_nop 0
	global_load_lds_dwordx4 v[190:191], off
	s_waitcnt vmcnt(8)
	s_waitcnt lgkmcnt(0)
	s_barrier
	v_mfma_f32_16x16x32_bf16 v[134:137], v[50:53], v[182:185], v[134:137]
	v_mfma_f32_16x16x32_bf16 v[130:133], v[138:141], v[182:185], v[130:133]
	v_mfma_f32_16x16x32_bf16 v[118:121], v[50:53], v[202:205], v[118:121]
	v_mfma_f32_16x16x32_bf16 v[114:117], v[138:141], v[202:205], v[114:117]
	v_mfma_f32_16x16x32_bf16 v[102:105], v[50:53], v[210:213], v[102:105]
	v_mfma_f32_16x16x32_bf16 v[98:101], v[138:141], v[210:213], v[98:101]
	v_mfma_f32_16x16x32_bf16 v[86:89], v[50:53], v[218:221], v[86:89]
	v_mfma_f32_16x16x32_bf16 v[82:85], v[138:141], v[218:221], v[82:85]
	v_mfma_f32_16x16x32_bf16 v[134:137], v[54:57], v[186:189], v[134:137]
	v_mfma_f32_16x16x32_bf16 v[130:133], v[142:145], v[186:189], v[130:133]
	v_mfma_f32_16x16x32_bf16 v[118:121], v[54:57], v[206:209], v[118:121]
	v_mfma_f32_16x16x32_bf16 v[114:117], v[142:145], v[206:209], v[114:117]
	v_mfma_f32_16x16x32_bf16 v[102:105], v[54:57], v[214:217], v[102:105]
	v_mfma_f32_16x16x32_bf16 v[98:101], v[142:145], v[214:217], v[98:101]
	v_mfma_f32_16x16x32_bf16 v[86:89], v[54:57], v[222:225], v[86:89]
	v_mfma_f32_16x16x32_bf16 v[82:85], v[142:145], v[222:225], v[82:85]
	v_mfma_f32_16x16x32_bf16 v[126:129], v[146:149], v[182:185], v[126:129]
	v_mfma_f32_16x16x32_bf16 v[122:125], v[174:177], v[182:185], v[122:125]
	v_mfma_f32_16x16x32_bf16 v[110:113], v[146:149], v[202:205], v[110:113]
	v_mfma_f32_16x16x32_bf16 v[106:109], v[174:177], v[202:205], v[106:109]
	v_mfma_f32_16x16x32_bf16 v[94:97], v[146:149], v[210:213], v[94:97]
	v_mfma_f32_16x16x32_bf16 v[90:93], v[174:177], v[210:213], v[90:93]
	v_mfma_f32_16x16x32_bf16 v[78:81], v[146:149], v[218:221], v[78:81]
	v_mfma_f32_16x16x32_bf16 v[74:77], v[174:177], v[218:221], v[74:77]
	v_mfma_f32_16x16x32_bf16 v[126:129], v[150:153], v[186:189], v[126:129]
	v_mfma_f32_16x16x32_bf16 v[122:125], v[178:181], v[186:189], v[122:125]
	v_mfma_f32_16x16x32_bf16 v[110:113], v[150:153], v[206:209], v[110:113]
	v_mfma_f32_16x16x32_bf16 v[106:109], v[178:181], v[206:209], v[106:109]
	v_mfma_f32_16x16x32_bf16 v[94:97], v[150:153], v[214:217], v[94:97]
	v_mfma_f32_16x16x32_bf16 v[90:93], v[178:181], v[214:217], v[90:93]
	v_mfma_f32_16x16x32_bf16 v[78:81], v[150:153], v[222:225], v[78:81]
	v_mfma_f32_16x16x32_bf16 v[74:77], v[178:181], v[222:225], v[74:77]
	s_barrier
	s_add_i32 s58, s56, s28
	v_lshl_add_u64 v[190:191], s[48:49], 0, v[156:157]
	s_mov_b32 m0, s58
	ds_read_b128 v[182:185], v198 offset:16384
	ds_read_b128 v[186:189], v198 offset:17408
	ds_read_b128 v[202:205], v198 offset:18432
	ds_read_b128 v[206:209], v198 offset:19456
	ds_read_b128 v[210:213], v198 offset:20480
	ds_read_b128 v[214:217], v198 offset:21504
	ds_read_b128 v[218:221], v198 offset:22528
	ds_read_b128 v[222:225], v198 offset:23552
	global_load_lds_dwordx4 v[190:191], off
	s_add_i32 m0, s58, 0x2000
	s_add_u32 s58, s48, 0x20000
	v_lshl_add_u64 v[226:227], s[48:49], 0, v[160:161]
	s_addc_u32 s59, s49, 0
	s_add_i32 s60, s57, s28
	global_load_lds_dwordx4 v[226:227], off
	v_lshl_add_u64 v[228:229], s[58:59], 0, v[156:157]
	s_mov_b32 m0, s60
	v_lshl_add_u64 v[230:231], s[50:51], 0, v[158:159]
	global_load_lds_dwordx4 v[228:229], off
	v_lshl_add_u64 v[228:229], s[58:59], 0, v[160:161]
	s_add_i32 m0, s60, 0x2000
	s_nop 0
	global_load_lds_dwordx4 v[228:229], off
	v_lshl_add_u64 v[228:229], s[50:51], 0, v[154:155]
	s_mov_b32 m0, s29
	s_nop 0
	global_load_lds_dwordx4 v[228:229], off
	s_mov_b32 m0, s30
	s_nop 0
	global_load_lds_dwordx4 v[230:231], off
	s_waitcnt vmcnt(8)
	s_waitcnt lgkmcnt(0)
	s_barrier
; #define PG8_STAGE(bufoff, gbase, voff) do { _Pragma("unroll") for (int _i = 0; _i < 2; ++_i) \
;         __builtin_amdgcn_global_load_lds((const unsigned*)((const char*)(gbase) + (voff)[_i]), (LAS unsigned*)(lds + (bufoff) + ldsw + _i * 8192), 16, 0, 0); } while (0)
; #define PG8_LDA(dst, b, h) do { _Pragma("unroll") for (int m = 0; m < 4; ++m) _Pragma("unroll") for (int k = 0; k < 2; ++k) dst[m][k] = *(const LAS bf16x8*)(lds + PG8_SA(b, h) + aoff + m * 2048 + k * 1024); } while (0)
; #define PG8_LDB(dst, b, h) do { _Pragma("unroll") for (int n = 0; n < 2; ++n) _Pragma("unroll") for (int k = 0; k < 2; ++k) dst[n][k] = *(const LAS bf16x8*)(lds + PG8_SB(b, h) + boff + n * 2048 + k * 1024); } while (0)
; #define PG8_MMA(ai, bj, At, Bt) do { __builtin_amdgcn_s_setprio(1); _Pragma("unroll") for (int m = 0; m < 4; ++m) _Pragma("unroll") for (int n = 0; n < 2; ++n) _Pragma("unroll") for (int k = 0; k < 2; ++k) \
;         acc[ai][bj][m][n] = __builtin_amdgcn_mfma_f32_16x16x32_bf16(Bt[n][k], At[m][k], acc[ai][bj][m][n], 0, 0, 0); __builtin_amdgcn_s_setprio(0); } while (0)
; #define PG8_WAIT_V(n) asm volatile("s_waitcnt vmcnt(" #n ")" ::: "memory")
; #define PG8_WAIT_L(n) asm volatile("s_waitcnt lgkmcnt(" #n ")" ::: "memory")
; #define PG8_BAR __builtin_amdgcn_s_barrier()
; #define PG8_SCHED __builtin_amdgcn_sched_barrier(0)
; template <class Epi, class Sched, bool ALIGN_EPI = false, bool SP2 = false>
; __device__ __forceinline__ void gemm_phase(LAS unsigned char* lds, const Gemm g, const Sched& S, const Epi& E) {
;     ...
;             PG8_WAIT_V(8); PG8_WAIT_L(0); PG8_BAR; PG8_MMA(0, 0, At, B0); PG8_MMA(0, 1, At, B1); PG8_BAR; PG8_SCHED;
;             PG8_LDA(At, 0, 1); PG8_STAGE(PG8_SB(0, 0), b2, voffB); PG8_STAGE(PG8_SB(0, 1), b2 + hstepB, voffB); PG8_STAGE(PG8_SA(0, 0), a2, voffA);
;             PG8_WAIT_V(8); PG8_WAIT_L(0); PG8_BAR; PG8_MMA(1, 0, At, B0); PG8_MMA(1, 1, At, B1); PG8_BAR; PG8_SCHED;
;             PG8_LDB(B0, 1, 0); PG8_LDB(B1, 1, 1); PG8_SCHED; PG8_LDA(At, 1, 0); PG8_STAGE(PG8_SA(0, 1), a2 + hstep, voffA);
;             PG8_WAIT_V(8); PG8_WAIT_L(0); PG8_BAR; PG8_MMA(0, 0, At, B0); PG8_MMA(0, 1, At, B1); PG8_BAR; PG8_SCHED;
;             PG8_LDA(At, 1, 1); PG8_STAGE(PG8_SB(1, 0), b3, voffB); PG8_STAGE(PG8_SB(1, 1), b3 + hstepB, voffB); PG8_STAGE(PG8_SA(1, 0), a3, voffA);
	v_mfma_f32_16x16x32_bf16 v[70:73], v[50:53], v[182:185], v[70:73]
	v_mfma_f32_16x16x32_bf16 v[66:69], v[138:141], v[182:185], v[66:69]
	v_mfma_f32_16x16x32_bf16 v[46:49], v[50:53], v[202:205], v[46:49]
	v_mfma_f32_16x16x32_bf16 v[42:45], v[138:141], v[202:205], v[42:45]
	v_mfma_f32_16x16x32_bf16 v[30:33], v[50:53], v[210:213], v[30:33]
	v_mfma_f32_16x16x32_bf16 v[26:29], v[138:141], v[210:213], v[26:29]
	v_mfma_f32_16x16x32_bf16 v[14:17], v[50:53], v[218:221], v[14:17]
	v_mfma_f32_16x16x32_bf16 v[10:13], v[138:141], v[218:221], v[10:13]
	v_mfma_f32_16x16x32_bf16 v[70:73], v[54:57], v[186:189], v[70:73]
	v_mfma_f32_16x16x32_bf16 v[66:69], v[142:145], v[186:189], v[66:69]
	v_mfma_f32_16x16x32_bf16 v[46:49], v[54:57], v[206:209], v[46:49]
	v_mfma_f32_16x16x32_bf16 v[42:45], v[142:145], v[206:209], v[42:45]
	v_mfma_f32_16x16x32_bf16 v[30:33], v[54:57], v[214:217], v[30:33]
	v_mfma_f32_16x16x32_bf16 v[26:29], v[142:145], v[214:217], v[26:29]
	v_mfma_f32_16x16x32_bf16 v[14:17], v[54:57], v[222:225], v[14:17]
	v_mfma_f32_16x16x32_bf16 v[10:13], v[142:145], v[222:225], v[10:13]
	v_mfma_f32_16x16x32_bf16 v[38:41], v[146:149], v[202:205], v[38:41]
	v_mfma_f32_16x16x32_bf16 v[34:37], v[174:177], v[202:205], v[34:37]
	v_mfma_f32_16x16x32_bf16 v[22:25], v[146:149], v[210:213], v[22:25]
	v_mfma_f32_16x16x32_bf16 v[18:21], v[174:177], v[210:213], v[18:21]
	v_mfma_f32_16x16x32_bf16 v[6:9], v[146:149], v[218:221], v[6:9]
	v_mfma_f32_16x16x32_bf16 v[2:5], v[174:177], v[218:221], v[2:5]
	v_mfma_f32_16x16x32_bf16 v[50:53], v[146:149], v[182:185], v[62:65]
	v_mfma_f32_16x16x32_bf16 v[54:57], v[174:177], v[182:185], v[58:61]
	v_mfma_f32_16x16x32_bf16 v[38:41], v[150:153], v[206:209], v[38:41]
	v_mfma_f32_16x16x32_bf16 v[34:37], v[178:181], v[206:209], v[34:37]
	v_mfma_f32_16x16x32_bf16 v[22:25], v[150:153], v[214:217], v[22:25]
	v_mfma_f32_16x16x32_bf16 v[18:21], v[178:181], v[214:217], v[18:21]
	v_mfma_f32_16x16x32_bf16 v[6:9], v[150:153], v[222:225], v[6:9]
	v_mfma_f32_16x16x32_bf16 v[2:5], v[178:181], v[222:225], v[2:5]
	v_mfma_f32_16x16x32_bf16 v[50:53], v[150:153], v[186:189], v[50:53]
	v_mfma_f32_16x16x32_bf16 v[54:57], v[178:181], v[186:189], v[54:57]
	s_barrier
	s_add_i32 s58, 0, 0x18000
	s_add_i32 s59, 0, 0x1c000
	v_add_u32_e32 v142, s58, v1
	v_add_u32_e32 v162, s59, v1
	ds_read_b128 v[58:61], v142
	ds_read_b128 v[62:65], v142 offset:1024
	ds_read_b128 v[138:141], v142 offset:2048
	ds_read_b128 v[142:145], v142 offset:3072
	ds_read_b128 v[146:149], v162
	ds_read_b128 v[150:153], v162 offset:1024
	ds_read_b128 v[174:177], v162 offset:2048
	ds_read_b128 v[178:181], v162 offset:3072
	s_add_u32 s50, s50, 0x80000
	s_addc_u32 s51, s51, 0
	s_mov_b32 m0, s31
	v_lshl_add_u64 v[232:233], s[50:51], 0, v[154:155]
	ds_read_b128 v[182:185], v198 offset:32768
	ds_read_b128 v[186:189], v198 offset:33792
	ds_read_b128 v[202:205], v198 offset:34816
	ds_read_b128 v[206:209], v198 offset:35840
	ds_read_b128 v[210:213], v198 offset:36864
	ds_read_b128 v[214:217], v198 offset:37888
	ds_read_b128 v[218:221], v198 offset:38912
	ds_read_b128 v[222:225], v198 offset:39936
	global_load_lds_dwordx4 v[232:233], off
	v_lshl_add_u64 v[232:233], s[50:51], 0, v[158:159]
	s_mov_b32 m0, s33
	s_nop 0
	global_load_lds_dwordx4 v[232:233], off
	s_waitcnt vmcnt(8)
	s_waitcnt lgkmcnt(0)
	s_barrier
	v_mfma_f32_16x16x32_bf16 v[134:137], v[58:61], v[182:185], v[134:137]
	v_mfma_f32_16x16x32_bf16 v[130:133], v[138:141], v[182:185], v[130:133]
	v_mfma_f32_16x16x32_bf16 v[118:121], v[58:61], v[202:205], v[118:121]
	v_mfma_f32_16x16x32_bf16 v[114:117], v[138:141], v[202:205], v[114:117]
	v_mfma_f32_16x16x32_bf16 v[102:105], v[58:61], v[210:213], v[102:105]
	v_mfma_f32_16x16x32_bf16 v[98:101], v[138:141], v[210:213], v[98:101]
	v_mfma_f32_16x16x32_bf16 v[86:89], v[58:61], v[218:221], v[86:89]
	v_mfma_f32_16x16x32_bf16 v[82:85], v[138:141], v[218:221], v[82:85]
	v_mfma_f32_16x16x32_bf16 v[134:137], v[62:65], v[186:189], v[134:137]
	v_mfma_f32_16x16x32_bf16 v[130:133], v[142:145], v[186:189], v[130:133]
	v_mfma_f32_16x16x32_bf16 v[118:121], v[62:65], v[206:209], v[118:121]
	v_mfma_f32_16x16x32_bf16 v[114:117], v[142:145], v[206:209], v[114:117]
	v_mfma_f32_16x16x32_bf16 v[102:105], v[62:65], v[214:217], v[102:105]
	v_mfma_f32_16x16x32_bf16 v[98:101], v[142:145], v[214:217], v[98:101]
	v_mfma_f32_16x16x32_bf16 v[86:89], v[62:65], v[222:225], v[86:89]
	v_mfma_f32_16x16x32_bf16 v[82:85], v[142:145], v[222:225], v[82:85]
	v_mfma_f32_16x16x32_bf16 v[126:129], v[146:149], v[182:185], v[126:129]
	v_mfma_f32_16x16x32_bf16 v[122:125], v[174:177], v[182:185], v[122:125]
	v_mfma_f32_16x16x32_bf16 v[110:113], v[146:149], v[202:205], v[110:113]
	v_mfma_f32_16x16x32_bf16 v[106:109], v[174:177], v[202:205], v[106:109]
	v_mfma_f32_16x16x32_bf16 v[94:97], v[146:149], v[210:213], v[94:97]
	v_mfma_f32_16x16x32_bf16 v[90:93], v[174:177], v[210:213], v[90:93]
	v_mfma_f32_16x16x32_bf16 v[78:81], v[146:149], v[218:221], v[78:81]
	v_mfma_f32_16x16x32_bf16 v[74:77], v[174:177], v[218:221], v[74:77]
	v_mfma_f32_16x16x32_bf16 v[126:129], v[150:153], v[186:189], v[126:129]
	v_mfma_f32_16x16x32_bf16 v[122:125], v[178:181], v[186:189], v[122:125]
	v_mfma_f32_16x16x32_bf16 v[110:113], v[150:153], v[206:209], v[110:113]
	v_mfma_f32_16x16x32_bf16 v[106:109], v[178:181], v[206:209], v[106:109]
	v_mfma_f32_16x16x32_bf16 v[94:97], v[150:153], v[214:217], v[94:97]
	v_mfma_f32_16x16x32_bf16 v[90:93], v[178:181], v[214:217], v[90:93]
	v_mfma_f32_16x16x32_bf16 v[78:81], v[150:153], v[222:225], v[78:81]
	v_mfma_f32_16x16x32_bf16 v[74:77], v[178:181], v[222:225], v[74:77]
	s_barrier
; #define PG8_STAGE(bufoff, gbase, voff) do { _Pragma("unroll") for (int _i = 0; _i < 2; ++_i) \
;         __builtin_amdgcn_global_load_lds((const unsigned*)((const char*)(gbase) + (voff)[_i]), (LAS unsigned*)(lds + (bufoff) + ldsw + _i * 8192), 16, 0, 0); } while (0)
; #define PG8_LDA(dst, b, h) do { _Pragma("unroll") for (int m = 0; m < 4; ++m) _Pragma("unroll") for (int k = 0; k < 2; ++k) dst[m][k] = *(const LAS bf16x8*)(lds + PG8_SA(b, h) + aoff + m * 2048 + k * 1024); } while (0)
; #define PG8_MMA(ai, bj, At, Bt) do { __builtin_amdgcn_s_setprio(1); _Pragma("unroll") for (int m = 0; m < 4; ++m) _Pragma("unroll") for (int n = 0; n < 2; ++n) _Pragma("unroll") for (int k = 0; k < 2; ++k) \
;         acc[ai][bj][m][n] = __builtin_amdgcn_mfma_f32_16x16x32_bf16(Bt[n][k], At[m][k], acc[ai][bj][m][n], 0, 0, 0); __builtin_amdgcn_s_setprio(0); } while (0)
; #define PG8_WAIT_V(n) asm volatile("s_waitcnt vmcnt(" #n ")" ::: "memory")
; #define PG8_WAIT_L(n) asm volatile("s_waitcnt lgkmcnt(" #n ")" ::: "memory")
; #define PG8_BAR __builtin_amdgcn_s_barrier()
; #define PG8_SCHED __builtin_amdgcn_sched_barrier(0)
; template <class Epi, class Sched, bool ALIGN_EPI = false, bool SP2 = false>
; __device__ __forceinline__ void gemm_phase(LAS unsigned char* lds, const Gemm g, const Sched& S, const Epi& E) {
;     ...
;             PG8_LDA(At, 1, 1); PG8_STAGE(PG8_SB(1, 0), b3, voffB); PG8_STAGE(PG8_SB(1, 1), b3 + hstepB, voffB); PG8_STAGE(PG8_SA(1, 0), a3, voffA);
;             PG8_WAIT_V(8); PG8_WAIT_L(0); PG8_BAR; PG8_MMA(1, 0, At, B0); PG8_MMA(1, 1, At, B1); PG8_BAR; PG8_SCHED;
;     ...
;         if constexpr (ALIGN_EPI) { if (wr == 0) PG8_BAR; }
	s_add_i32 s50, s58, s28
	v_lshl_add_u64 v[190:191], v[190:191], 0, s[10:11]
	s_mov_b32 m0, s50
	ds_read_b128 v[182:185], v198 offset:49152
	ds_read_b128 v[186:189], v198 offset:50176
	ds_read_b128 v[202:205], v198 offset:51200
	ds_read_b128 v[206:209], v198 offset:52224
	ds_read_b128 v[210:213], v198 offset:53248
	ds_read_b128 v[214:217], v198 offset:54272
	ds_read_b128 v[218:221], v198 offset:55296
	ds_read_b128 v[222:225], v198 offset:56320
	global_load_lds_dwordx4 v[190:191], off
	s_add_i32 m0, s50, 0x2000
	s_add_u32 s48, s48, 0x20080
	v_lshl_add_u64 v[190:191], v[226:227], 0, s[10:11]
	s_addc_u32 s49, s49, 0
	s_add_i32 s50, s59, s28
	global_load_lds_dwordx4 v[190:191], off
	v_lshl_add_u64 v[190:191], s[48:49], 0, v[156:157]
	s_mov_b32 m0, s50
	s_nop 0
	global_load_lds_dwordx4 v[190:191], off
	v_lshl_add_u64 v[190:191], s[48:49], 0, v[160:161]
	s_add_i32 m0, s50, 0x2000
	s_nop 0
	global_load_lds_dwordx4 v[190:191], off
	v_lshl_add_u64 v[190:191], v[228:229], 0, s[10:11]
	s_mov_b32 m0, s53
	s_nop 0
	global_load_lds_dwordx4 v[190:191], off
	v_lshl_add_u64 v[190:191], v[230:231], 0, s[10:11]
	s_mov_b32 m0, s54
	s_nop 0
	global_load_lds_dwordx4 v[190:191], off
	s_waitcnt vmcnt(8)
	s_waitcnt lgkmcnt(0)
	s_barrier
	v_mfma_f32_16x16x32_bf16 v[70:73], v[58:61], v[182:185], v[70:73]
	v_mfma_f32_16x16x32_bf16 v[66:69], v[138:141], v[182:185], v[66:69]
	v_mfma_f32_16x16x32_bf16 v[46:49], v[58:61], v[202:205], v[46:49]
	v_mfma_f32_16x16x32_bf16 v[42:45], v[138:141], v[202:205], v[42:45]
	v_mfma_f32_16x16x32_bf16 v[30:33], v[58:61], v[210:213], v[30:33]
	v_mfma_f32_16x16x32_bf16 v[26:29], v[138:141], v[210:213], v[26:29]
	v_mfma_f32_16x16x32_bf16 v[14:17], v[58:61], v[218:221], v[14:17]
	v_mfma_f32_16x16x32_bf16 v[10:13], v[138:141], v[218:221], v[10:13]
	v_mfma_f32_16x16x32_bf16 v[70:73], v[62:65], v[186:189], v[70:73]
	v_mfma_f32_16x16x32_bf16 v[66:69], v[142:145], v[186:189], v[66:69]
	v_mfma_f32_16x16x32_bf16 v[46:49], v[62:65], v[206:209], v[46:49]
	v_mfma_f32_16x16x32_bf16 v[42:45], v[142:145], v[206:209], v[42:45]
	v_mfma_f32_16x16x32_bf16 v[30:33], v[62:65], v[214:217], v[30:33]
	v_mfma_f32_16x16x32_bf16 v[26:29], v[142:145], v[214:217], v[26:29]
	v_mfma_f32_16x16x32_bf16 v[14:17], v[62:65], v[222:225], v[14:17]
	v_mfma_f32_16x16x32_bf16 v[10:13], v[142:145], v[222:225], v[10:13]
	v_mfma_f32_16x16x32_bf16 v[50:53], v[146:149], v[182:185], v[50:53]
	v_mfma_f32_16x16x32_bf16 v[62:65], v[150:153], v[186:189], v[50:53]
	v_mfma_f32_16x16x32_bf16 v[50:53], v[174:177], v[182:185], v[54:57]
	v_mfma_f32_16x16x32_bf16 v[38:41], v[146:149], v[202:205], v[38:41]
	v_mfma_f32_16x16x32_bf16 v[34:37], v[174:177], v[202:205], v[34:37]
	v_mfma_f32_16x16x32_bf16 v[22:25], v[146:149], v[210:213], v[22:25]
	v_mfma_f32_16x16x32_bf16 v[18:21], v[174:177], v[210:213], v[18:21]
	v_mfma_f32_16x16x32_bf16 v[6:9], v[146:149], v[218:221], v[6:9]
	v_mfma_f32_16x16x32_bf16 v[2:5], v[174:177], v[218:221], v[2:5]
	v_mfma_f32_16x16x32_bf16 v[58:61], v[178:181], v[186:189], v[50:53]
	v_mfma_f32_16x16x32_bf16 v[38:41], v[150:153], v[206:209], v[38:41]
	v_mfma_f32_16x16x32_bf16 v[34:37], v[178:181], v[206:209], v[34:37]
	v_mfma_f32_16x16x32_bf16 v[22:25], v[150:153], v[214:217], v[22:25]
	v_mfma_f32_16x16x32_bf16 v[18:21], v[178:181], v[214:217], v[18:21]
	v_mfma_f32_16x16x32_bf16 v[6:9], v[150:153], v[222:225], v[6:9]
	v_mfma_f32_16x16x32_bf16 v[2:5], v[178:181], v[222:225], v[2:5]
	s_barrier
	s_add_i32 s47, s47, 2
	s_add_u32 s16, s16, 0x100
	s_addc_u32 s17, s17, 0
	s_add_u32 s24, s24, 0x100
	s_addc_u32 s25, s25, 0
	s_cmp_gt_u32 s47, 29
	s_cbranch_scc0 .LBB0_1250
	s_setprio 0
	s_and_b64 vcc, exec, s[12:13]
	s_cbranch_vccz .LBB0_1253
	s_barrier

; #define PG8_STAGE(bufoff, gbase, voff) do { _Pragma("unroll") for (int _i = 0; _i < 2; ++_i) \
;         __builtin_amdgcn_global_load_lds((const unsigned*)((const char*)(gbase) + (voff)[_i]), (LAS unsigned*)(lds + (bufoff) + ldsw + _i * 8192), 16, 0, 0); } while (0)
; #define PG8_LDA(dst, b, h) do { _Pragma("unroll") for (int m = 0; m < 4; ++m) _Pragma("unroll") for (int k = 0; k < 2; ++k) dst[m][k] = *(const LAS bf16x8*)(lds + PG8_SA(b, h) + aoff + m * 2048 + k * 1024); } while (0)
; #define PG8_LDB(dst, b, h) do { _Pragma("unroll") for (int n = 0; n < 2; ++n) _Pragma("unroll") for (int k = 0; k < 2; ++k) dst[n][k] = *(const LAS bf16x8*)(lds + PG8_SB(b, h) + boff + n * 2048 + k * 1024); } while (0)
; #define PG8_MMA(ai, bj, At, Bt) do { __builtin_amdgcn_s_setprio(1); _Pragma("unroll") for (int m = 0; m < 4; ++m) _Pragma("unroll") for (int n = 0; n < 2; ++n) _Pragma("unroll") for (int k = 0; k < 2; ++k) \
;         acc[ai][bj][m][n] = __builtin_amdgcn_mfma_f32_16x16x32_bf16(Bt[n][k], At[m][k], acc[ai][bj][m][n], 0, 0, 0); __builtin_amdgcn_s_setprio(0); } while (0)
; #define PG8_WAIT_V(n) asm volatile("s_waitcnt vmcnt(" #n ")" ::: "memory")
; #define PG8_WAIT_L(n) asm volatile("s_waitcnt lgkmcnt(" #n ")" ::: "memory")
; template <class Epi, class Sched, bool ALIGN_EPI = false, bool SP2 = false>
; __device__ __forceinline__ void gemm_phase(LAS unsigned char* lds, const Gemm g, const Sched& S, const Epi& E) {
;     ...
;         for (int t = 0; t < nt; t += 2) {
;             const bool last = (t == nt - 2);
;             const char* a1 = cA + (size_t)(t + 1) * kstep;
;             const char* a2 = last ? nA : cA + (size_t)(t + 2) * kstep; const char* b2 = last ? nB : cB + (size_t)(t + 2) * kstep;
;             const char* a3 = a2 + kstep; const char* b3 = b2 + kstep;
;             if (last && has_next) S.a_ready(nxt);
;             if constexpr (SP2) {
;             PG8_LDB(B0, 0, 0); PG8_LDB(B1, 0, 1); PG8_SCHED; PG8_LDA(At, 0, 0); PG8_STAGE(PG8_SA(1, 1), a1 + hstep, voffA);
;             PG8_WAIT_V(8); PG8_WAIT_L(0); PG8_BAR; PG8_MMA(0, 0, At, B0); PG8_MMA(0, 1, At, B1); PG8_BAR; PG8_SCHED;
;             PG8_LDA(At, 0, 1); PG8_STAGE(PG8_SB(0, 0), b2, voffB); PG8_STAGE(PG8_SB(0, 1), b2 + hstepB, voffB); PG8_STAGE(PG8_SA(0, 0), a2, voffA);
;             PG8_WAIT_V(8); PG8_WAIT_L(0); PG8_BAR; PG8_MMA(1, 0, At, B0); PG8_MMA(1, 1, At, B1); PG8_BAR; PG8_SCHED;
.Lprio_1465:
	ds_read_b128 v[66:69], v174
	ds_read_b128 v[70:73], v174 offset:1024
	ds_read_b128 v[74:77], v174 offset:2048
	ds_read_b128 v[78:81], v174 offset:3072
	ds_read_b128 v[162:165], v175
	ds_read_b128 v[182:185], v175 offset:1024
	ds_read_b128 v[186:189], v175 offset:2048
	ds_read_b128 v[190:193], v175 offset:3072
	s_add_u32 s22, s16, 0xfff80080
	s_addc_u32 s23, s17, -1
	s_cmp_eq_u32 s53, 28
	s_cselect_b32 s41, s3, s23
	s_cselect_b32 s40, s15, s22
	s_cselect_b32 s23, s13, s52
	s_cselect_b32 s22, s24, s25
	v_lshl_add_u64 v[166:167], s[16:17], 0, v[154:155]
	s_add_i32 m0, s33, 0xc000
	ds_read_b128 v[194:197], v176
	ds_read_b128 v[198:201], v176 offset:1024
	ds_read_b128 v[202:205], v176 offset:2048
	ds_read_b128 v[206:209], v176 offset:3072
	ds_read_b128 v[210:213], v176 offset:4096
	ds_read_b128 v[214:217], v176 offset:5120
	ds_read_b128 v[218:221], v176 offset:6144
	ds_read_b128 v[222:225], v176 offset:7168
	global_load_lds_dwordx4 v[166:167], off
	v_lshl_add_u64 v[166:167], s[16:17], 0, v[156:157]
	s_add_i32 m0, s33, 0xe000
	s_nop 0
	global_load_lds_dwordx4 v[166:167], off
	s_waitcnt lgkmcnt(0)
	s_barrier
	v_mfma_f32_16x16x32_bf16 v[142:145], v[66:69], v[194:197], 0
	v_mfma_f32_16x16x32_bf16 v[138:141], v[74:77], v[194:197], 0
	v_mfma_f32_16x16x32_bf16 v[126:129], v[66:69], v[202:205], 0
	v_mfma_f32_16x16x32_bf16 v[122:125], v[74:77], v[202:205], 0
	v_mfma_f32_16x16x32_bf16 v[110:113], v[66:69], v[210:213], 0
	v_mfma_f32_16x16x32_bf16 v[106:109], v[74:77], v[210:213], 0
	v_mfma_f32_16x16x32_bf16 v[94:97], v[66:69], v[218:221], 0
	v_mfma_f32_16x16x32_bf16 v[90:93], v[74:77], v[218:221], 0
	v_mfma_f32_16x16x32_bf16 v[142:145], v[70:73], v[198:201], v[142:145]
	v_mfma_f32_16x16x32_bf16 v[138:141], v[78:81], v[198:201], v[138:141]
	v_mfma_f32_16x16x32_bf16 v[126:129], v[70:73], v[206:209], v[126:129]
	v_mfma_f32_16x16x32_bf16 v[122:125], v[78:81], v[206:209], v[122:125]
	v_mfma_f32_16x16x32_bf16 v[110:113], v[70:73], v[214:217], v[110:113]
	v_mfma_f32_16x16x32_bf16 v[106:109], v[78:81], v[214:217], v[106:109]
	v_mfma_f32_16x16x32_bf16 v[94:97], v[70:73], v[222:225], v[94:97]
	v_mfma_f32_16x16x32_bf16 v[90:93], v[78:81], v[222:225], v[90:93]
	v_mfma_f32_16x16x32_bf16 v[134:137], v[162:165], v[194:197], 0
	v_mfma_f32_16x16x32_bf16 v[130:133], v[186:189], v[194:197], 0
	v_mfma_f32_16x16x32_bf16 v[118:121], v[162:165], v[202:205], 0
	v_mfma_f32_16x16x32_bf16 v[114:117], v[186:189], v[202:205], 0
	v_mfma_f32_16x16x32_bf16 v[102:105], v[162:165], v[210:213], 0
	v_mfma_f32_16x16x32_bf16 v[98:101], v[186:189], v[210:213], 0
	v_mfma_f32_16x16x32_bf16 v[86:89], v[162:165], v[218:221], 0
	v_mfma_f32_16x16x32_bf16 v[82:85], v[186:189], v[218:221], 0
	v_mfma_f32_16x16x32_bf16 v[134:137], v[182:185], v[198:201], v[134:137]
	v_mfma_f32_16x16x32_bf16 v[130:133], v[190:193], v[198:201], v[130:133]
	v_mfma_f32_16x16x32_bf16 v[118:121], v[182:185], v[206:209], v[118:121]
	v_mfma_f32_16x16x32_bf16 v[114:117], v[190:193], v[206:209], v[114:117]
	v_mfma_f32_16x16x32_bf16 v[102:105], v[182:185], v[214:217], v[102:105]
	v_mfma_f32_16x16x32_bf16 v[98:101], v[190:193], v[214:217], v[98:101]
	v_mfma_f32_16x16x32_bf16 v[86:89], v[182:185], v[222:225], v[86:89]
	v_mfma_f32_16x16x32_bf16 v[82:85], v[190:193], v[222:225], v[82:85]
	s_barrier
	s_add_i32 s54, s47, s29
	v_lshl_add_u64 v[166:167], s[22:23], 0, v[150:151]
	s_mov_b32 m0, s54
	ds_read_b128 v[194:197], v176 offset:16384
	ds_read_b128 v[198:201], v176 offset:17408
	ds_read_b128 v[202:205], v176 offset:18432
	ds_read_b128 v[206:209], v176 offset:19456
	ds_read_b128 v[210:213], v176 offset:20480
	ds_read_b128 v[214:217], v176 offset:21504
	ds_read_b128 v[218:221], v176 offset:22528
	ds_read_b128 v[222:225], v176 offset:23552
	global_load_lds_dwordx4 v[166:167], off
	s_add_i32 m0, s54, 0x2000
	s_add_u32 s54, s22, 0x80000
	v_lshl_add_u64 v[226:227], s[22:23], 0, v[146:147]
	s_addc_u32 s55, s23, 0
	s_add_i32 s56, s48, s29
	global_load_lds_dwordx4 v[226:227], off
	v_lshl_add_u64 v[228:229], s[54:55], 0, v[150:151]
	s_mov_b32 m0, s56
	v_lshl_add_u64 v[230:231], s[40:41], 0, v[148:149]
	global_load_lds_dwordx4 v[228:229], off
	v_lshl_add_u64 v[228:229], s[54:55], 0, v[146:147]
	s_add_i32 m0, s56, 0x2000
	s_nop 0
	global_load_lds_dwordx4 v[228:229], off
	v_lshl_add_u64 v[228:229], s[40:41], 0, v[152:153]
	s_mov_b32 m0, s33
	s_nop 0
	global_load_lds_dwordx4 v[228:229], off
	s_mov_b32 m0, s34
	s_nop 0
	global_load_lds_dwordx4 v[230:231], off
	s_waitcnt lgkmcnt(0)
	s_barrier
	v_mfma_f32_16x16x32_bf16 v[62:65], v[66:69], v[194:197], 0
	v_mfma_f32_16x16x32_bf16 v[58:61], v[74:77], v[194:197], 0
	v_mfma_f32_16x16x32_bf16 v[46:49], v[66:69], v[202:205], 0
	v_mfma_f32_16x16x32_bf16 v[42:45], v[74:77], v[202:205], 0
	v_mfma_f32_16x16x32_bf16 v[30:33], v[66:69], v[210:213], 0
	v_mfma_f32_16x16x32_bf16 v[26:29], v[74:77], v[210:213], 0
	v_mfma_f32_16x16x32_bf16 v[14:17], v[66:69], v[218:221], 0
	v_mfma_f32_16x16x32_bf16 v[10:13], v[74:77], v[218:221], 0
	v_mfma_f32_16x16x32_bf16 v[62:65], v[70:73], v[198:201], v[62:65]
	v_mfma_f32_16x16x32_bf16 v[58:61], v[78:81], v[198:201], v[58:61]
	v_mfma_f32_16x16x32_bf16 v[46:49], v[70:73], v[206:209], v[46:49]
	v_mfma_f32_16x16x32_bf16 v[42:45], v[78:81], v[206:209], v[42:45]
	v_mfma_f32_16x16x32_bf16 v[30:33], v[70:73], v[214:217], v[30:33]
	v_mfma_f32_16x16x32_bf16 v[26:29], v[78:81], v[214:217], v[26:29]
	v_mfma_f32_16x16x32_bf16 v[14:17], v[70:73], v[222:225], v[14:17]
	v_mfma_f32_16x16x32_bf16 v[10:13], v[78:81], v[222:225], v[10:13]
	v_mfma_f32_16x16x32_bf16 v[54:57], v[162:165], v[194:197], 0
	v_mfma_f32_16x16x32_bf16 v[50:53], v[186:189], v[194:197], 0
	v_mfma_f32_16x16x32_bf16 v[38:41], v[162:165], v[202:205], 0
	v_mfma_f32_16x16x32_bf16 v[34:37], v[186:189], v[202:205], 0
	v_mfma_f32_16x16x32_bf16 v[22:25], v[162:165], v[210:213], 0
	v_mfma_f32_16x16x32_bf16 v[18:21], v[186:189], v[210:213], 0
	v_mfma_f32_16x16x32_bf16 v[6:9], v[162:165], v[218:221], 0
	v_mfma_f32_16x16x32_bf16 v[2:5], v[186:189], v[218:221], 0
	v_mfma_f32_16x16x32_bf16 v[54:57], v[182:185], v[198:201], v[54:57]
	v_mfma_f32_16x16x32_bf16 v[50:53], v[190:193], v[198:201], v[50:53]
	v_mfma_f32_16x16x32_bf16 v[38:41], v[182:185], v[206:209], v[38:41]
	v_mfma_f32_16x16x32_bf16 v[34:37], v[190:193], v[206:209], v[34:37]
	v_mfma_f32_16x16x32_bf16 v[22:25], v[182:185], v[214:217], v[22:25]
	v_mfma_f32_16x16x32_bf16 v[18:21], v[190:193], v[214:217], v[18:21]
	v_mfma_f32_16x16x32_bf16 v[6:9], v[182:185], v[222:225], v[6:9]
	v_mfma_f32_16x16x32_bf16 v[2:5], v[190:193], v[222:225], v[2:5]
	s_barrier
; #define PG8_STAGE(bufoff, gbase, voff) do { _Pragma("unroll") for (int _i = 0; _i < 2; ++_i) \
;         __builtin_amdgcn_global_load_lds((const unsigned*)((const char*)(gbase) + (voff)[_i]), (LAS unsigned*)(lds + (bufoff) + ldsw + _i * 8192), 16, 0, 0); } while (0)
; #define PG8_LDA(dst, b, h) do { _Pragma("unroll") for (int m = 0; m < 4; ++m) _Pragma("unroll") for (int k = 0; k < 2; ++k) dst[m][k] = *(const LAS bf16x8*)(lds + PG8_SA(b, h) + aoff + m * 2048 + k * 1024); } while (0)
; #define PG8_LDB(dst, b, h) do { _Pragma("unroll") for (int n = 0; n < 2; ++n) _Pragma("unroll") for (int k = 0; k < 2; ++k) dst[n][k] = *(const LAS bf16x8*)(lds + PG8_SB(b, h) + boff + n * 2048 + k * 1024); } while (0)
; #define PG8_MMA(ai, bj, At, Bt) do { __builtin_amdgcn_s_setprio(1); _Pragma("unroll") for (int m = 0; m < 4; ++m) _Pragma("unroll") for (int n = 0; n < 2; ++n) _Pragma("unroll") for (int k = 0; k < 2; ++k) \
;         acc[ai][bj][m][n] = __builtin_amdgcn_mfma_f32_16x16x32_bf16(Bt[n][k], At[m][k], acc[ai][bj][m][n], 0, 0, 0); __builtin_amdgcn_s_setprio(0); } while (0)
; #define PG8_WAIT_V(n) asm volatile("s_waitcnt vmcnt(" #n ")" ::: "memory")
; #define PG8_WAIT_L(n) asm volatile("s_waitcnt lgkmcnt(" #n ")" ::: "memory")
; #define PG8_BAR __builtin_amdgcn_s_barrier()
; #define PG8_SCHED __builtin_amdgcn_sched_barrier(0)
; template <class Epi, class Sched, bool ALIGN_EPI = false, bool SP2 = false>
; __device__ __forceinline__ void gemm_phase(LAS unsigned char* lds, const Gemm g, const Sched& S, const Epi& E) {
;     ...
;             PG8_LDB(B0, 1, 0); PG8_LDB(B1, 1, 1); PG8_SCHED; PG8_LDA(At, 1, 0); PG8_STAGE(PG8_SA(0, 1), a2 + hstep, voffA);
;             PG8_WAIT_V(8); PG8_WAIT_L(0); PG8_BAR; PG8_MMA(0, 0, At, B0); PG8_MMA(0, 1, At, B1); PG8_BAR; PG8_SCHED;
;             PG8_LDA(At, 1, 1); PG8_STAGE(PG8_SB(1, 0), b3, voffB); PG8_STAGE(PG8_SB(1, 1), b3 + hstepB, voffB); PG8_STAGE(PG8_SA(1, 0), a3, voffA);
;             PG8_WAIT_V(8); PG8_WAIT_L(0); PG8_BAR; PG8_MMA(1, 0, At, B0); PG8_MMA(1, 1, At, B1); PG8_BAR; PG8_SCHED;
	s_add_i32 s54, 0, 0x18000
	s_add_i32 s55, 0, 0x1c000
	v_add_u32_e32 v78, s54, v170
	v_add_u32_e32 v168, s55, v170
	ds_read_b128 v[66:69], v78
	ds_read_b128 v[70:73], v78 offset:1024
	ds_read_b128 v[74:77], v78 offset:2048
	ds_read_b128 v[78:81], v78 offset:3072
	ds_read_b128 v[162:165], v168
	ds_read_b128 v[182:185], v168 offset:1024
	ds_read_b128 v[186:189], v168 offset:2048
	ds_read_b128 v[190:193], v168 offset:3072
	s_add_u32 s40, s40, 0x80000
	s_addc_u32 s41, s41, 0
	s_mov_b32 m0, s35
	v_lshl_add_u64 v[232:233], s[40:41], 0, v[152:153]
	ds_read_b128 v[194:197], v176 offset:32768
	ds_read_b128 v[198:201], v176 offset:33792
	ds_read_b128 v[202:205], v176 offset:34816
	ds_read_b128 v[206:209], v176 offset:35840
	ds_read_b128 v[210:213], v176 offset:36864
	ds_read_b128 v[214:217], v176 offset:37888
	ds_read_b128 v[218:221], v176 offset:38912
	ds_read_b128 v[222:225], v176 offset:39936
	global_load_lds_dwordx4 v[232:233], off
	v_lshl_add_u64 v[232:233], s[40:41], 0, v[148:149]
	s_mov_b32 m0, s36
	s_nop 0
	global_load_lds_dwordx4 v[232:233], off
	s_waitcnt vmcnt(8)
	s_waitcnt lgkmcnt(0)
	s_barrier
	v_mfma_f32_16x16x32_bf16 v[142:145], v[66:69], v[194:197], v[142:145]
	v_mfma_f32_16x16x32_bf16 v[138:141], v[74:77], v[194:197], v[138:141]
	v_mfma_f32_16x16x32_bf16 v[126:129], v[66:69], v[202:205], v[126:129]
	v_mfma_f32_16x16x32_bf16 v[122:125], v[74:77], v[202:205], v[122:125]
	v_mfma_f32_16x16x32_bf16 v[110:113], v[66:69], v[210:213], v[110:113]
	v_mfma_f32_16x16x32_bf16 v[106:109], v[74:77], v[210:213], v[106:109]
	v_mfma_f32_16x16x32_bf16 v[94:97], v[66:69], v[218:221], v[94:97]
	v_mfma_f32_16x16x32_bf16 v[90:93], v[74:77], v[218:221], v[90:93]
	v_mfma_f32_16x16x32_bf16 v[142:145], v[70:73], v[198:201], v[142:145]
	v_mfma_f32_16x16x32_bf16 v[138:141], v[78:81], v[198:201], v[138:141]
	v_mfma_f32_16x16x32_bf16 v[126:129], v[70:73], v[206:209], v[126:129]
	v_mfma_f32_16x16x32_bf16 v[122:125], v[78:81], v[206:209], v[122:125]
	v_mfma_f32_16x16x32_bf16 v[110:113], v[70:73], v[214:217], v[110:113]
	v_mfma_f32_16x16x32_bf16 v[106:109], v[78:81], v[214:217], v[106:109]
	v_mfma_f32_16x16x32_bf16 v[94:97], v[70:73], v[222:225], v[94:97]
	v_mfma_f32_16x16x32_bf16 v[90:93], v[78:81], v[222:225], v[90:93]
	v_mfma_f32_16x16x32_bf16 v[134:137], v[162:165], v[194:197], v[134:137]
	v_mfma_f32_16x16x32_bf16 v[130:133], v[186:189], v[194:197], v[130:133]
	v_mfma_f32_16x16x32_bf16 v[118:121], v[162:165], v[202:205], v[118:121]
	v_mfma_f32_16x16x32_bf16 v[114:117], v[186:189], v[202:205], v[114:117]
	v_mfma_f32_16x16x32_bf16 v[102:105], v[162:165], v[210:213], v[102:105]
	v_mfma_f32_16x16x32_bf16 v[98:101], v[186:189], v[210:213], v[98:101]
	v_mfma_f32_16x16x32_bf16 v[86:89], v[162:165], v[218:221], v[86:89]
	v_mfma_f32_16x16x32_bf16 v[82:85], v[186:189], v[218:221], v[82:85]
	v_mfma_f32_16x16x32_bf16 v[134:137], v[182:185], v[198:201], v[134:137]
	v_mfma_f32_16x16x32_bf16 v[130:133], v[190:193], v[198:201], v[130:133]
	v_mfma_f32_16x16x32_bf16 v[118:121], v[182:185], v[206:209], v[118:121]
	v_mfma_f32_16x16x32_bf16 v[114:117], v[190:193], v[206:209], v[114:117]
	v_mfma_f32_16x16x32_bf16 v[102:105], v[182:185], v[214:217], v[102:105]
	v_mfma_f32_16x16x32_bf16 v[98:101], v[190:193], v[214:217], v[98:101]
	v_mfma_f32_16x16x32_bf16 v[86:89], v[182:185], v[222:225], v[86:89]
	v_mfma_f32_16x16x32_bf16 v[82:85], v[190:193], v[222:225], v[82:85]
	s_barrier
	s_add_i32 s40, s54, s29
	v_lshl_add_u64 v[166:167], v[166:167], 0, s[8:9]
	s_mov_b32 m0, s40
	ds_read_b128 v[194:197], v176 offset:49152
	ds_read_b128 v[198:201], v176 offset:50176
	ds_read_b128 v[202:205], v176 offset:51200
	ds_read_b128 v[206:209], v176 offset:52224
	ds_read_b128 v[210:213], v176 offset:53248
	ds_read_b128 v[214:217], v176 offset:54272
	ds_read_b128 v[218:221], v176 offset:55296
	ds_read_b128 v[222:225], v176 offset:56320
	global_load_lds_dwordx4 v[166:167], off
	s_add_i32 m0, s40, 0x2000
	s_add_u32 s22, s22, 0x80080
	v_lshl_add_u64 v[166:167], v[226:227], 0, s[8:9]
	s_addc_u32 s23, s23, 0
	s_add_i32 s40, s55, s29
	global_load_lds_dwordx4 v[166:167], off
	v_lshl_add_u64 v[166:167], s[22:23], 0, v[150:151]
	s_mov_b32 m0, s40
	s_nop 0
	global_load_lds_dwordx4 v[166:167], off
	v_lshl_add_u64 v[166:167], s[22:23], 0, v[146:147]
	s_add_i32 m0, s40, 0x2000
	s_nop 0
	global_load_lds_dwordx4 v[166:167], off
	v_lshl_add_u64 v[166:167], v[228:229], 0, s[8:9]
	s_mov_b32 m0, s45
	s_nop 0
	global_load_lds_dwordx4 v[166:167], off
	v_lshl_add_u64 v[166:167], v[230:231], 0, s[8:9]
	s_mov_b32 m0, s46
	s_nop 0
	global_load_lds_dwordx4 v[166:167], off
	s_waitcnt vmcnt(8)
	s_waitcnt lgkmcnt(0)
	s_barrier
	v_mfma_f32_16x16x32_bf16 v[62:65], v[66:69], v[194:197], v[62:65]
	v_mfma_f32_16x16x32_bf16 v[58:61], v[74:77], v[194:197], v[58:61]
	v_mfma_f32_16x16x32_bf16 v[46:49], v[66:69], v[202:205], v[46:49]
	v_mfma_f32_16x16x32_bf16 v[42:45], v[74:77], v[202:205], v[42:45]
	v_mfma_f32_16x16x32_bf16 v[30:33], v[66:69], v[210:213], v[30:33]
	v_mfma_f32_16x16x32_bf16 v[26:29], v[74:77], v[210:213], v[26:29]
	v_mfma_f32_16x16x32_bf16 v[14:17], v[66:69], v[218:221], v[14:17]
	v_mfma_f32_16x16x32_bf16 v[10:13], v[74:77], v[218:221], v[10:13]
	v_mfma_f32_16x16x32_bf16 v[62:65], v[70:73], v[198:201], v[62:65]
	v_mfma_f32_16x16x32_bf16 v[58:61], v[78:81], v[198:201], v[58:61]
	v_mfma_f32_16x16x32_bf16 v[46:49], v[70:73], v[206:209], v[46:49]
	v_mfma_f32_16x16x32_bf16 v[42:45], v[78:81], v[206:209], v[42:45]
	v_mfma_f32_16x16x32_bf16 v[30:33], v[70:73], v[214:217], v[30:33]
	v_mfma_f32_16x16x32_bf16 v[26:29], v[78:81], v[214:217], v[26:29]
	v_mfma_f32_16x16x32_bf16 v[14:17], v[70:73], v[222:225], v[14:17]
	v_mfma_f32_16x16x32_bf16 v[10:13], v[78:81], v[222:225], v[10:13]
	v_mfma_f32_16x16x32_bf16 v[54:57], v[162:165], v[194:197], v[54:57]
	v_mfma_f32_16x16x32_bf16 v[50:53], v[186:189], v[194:197], v[50:53]
	v_mfma_f32_16x16x32_bf16 v[38:41], v[162:165], v[202:205], v[38:41]
	v_mfma_f32_16x16x32_bf16 v[34:37], v[186:189], v[202:205], v[34:37]
	v_mfma_f32_16x16x32_bf16 v[22:25], v[162:165], v[210:213], v[22:25]
	v_mfma_f32_16x16x32_bf16 v[18:21], v[186:189], v[210:213], v[18:21]
	v_mfma_f32_16x16x32_bf16 v[6:9], v[162:165], v[218:221], v[6:9]
	v_mfma_f32_16x16x32_bf16 v[2:5], v[186:189], v[218:221], v[2:5]
	v_mfma_f32_16x16x32_bf16 v[54:57], v[182:185], v[198:201], v[54:57]
	v_mfma_f32_16x16x32_bf16 v[50:53], v[190:193], v[198:201], v[50:53]
	v_mfma_f32_16x16x32_bf16 v[38:41], v[182:185], v[206:209], v[38:41]
	v_mfma_f32_16x16x32_bf16 v[34:37], v[190:193], v[206:209], v[34:37]
	v_mfma_f32_16x16x32_bf16 v[22:25], v[182:185], v[214:217], v[22:25]
	v_mfma_f32_16x16x32_bf16 v[18:21], v[190:193], v[214:217], v[18:21]
	v_mfma_f32_16x16x32_bf16 v[6:9], v[182:185], v[222:225], v[6:9]
	v_mfma_f32_16x16x32_bf16 v[2:5], v[190:193], v[222:225], v[2:5]
	s_barrier
	s_add_i32 s53, s53, 2
	s_add_u32 s16, s16, 0x100
	s_addc_u32 s17, s17, 0
	s_add_u32 s25, s25, 0x100
	s_addc_u32 s52, s52, 0
	s_cmp_gt_u32 s53, 29
; #define PG8_STAGE(bufoff, gbase, voff) do { _Pragma("unroll") for (int _i = 0; _i < 2; ++_i) \
;         __builtin_amdgcn_global_load_lds((const unsigned*)((const char*)(gbase) + (voff)[_i]), (LAS unsigned*)(lds + (bufoff) + ldsw + _i * 8192), 16, 0, 0); } while (0)
; #define PG8_LDA(dst, b, h) do { _Pragma("unroll") for (int m = 0; m < 4; ++m) _Pragma("unroll") for (int k = 0; k < 2; ++k) dst[m][k] = *(const LAS bf16x8*)(lds + PG8_SA(b, h) + aoff + m * 2048 + k * 1024); } while (0)
; #define PG8_LDB(dst, b, h) do { _Pragma("unroll") for (int n = 0; n < 2; ++n) _Pragma("unroll") for (int k = 0; k < 2; ++k) dst[n][k] = *(const LAS bf16x8*)(lds + PG8_SB(b, h) + boff + n * 2048 + k * 1024); } while (0)
; #define PG8_MMA(ai, bj, At, Bt) do { __builtin_amdgcn_s_setprio(1); _Pragma("unroll") for (int m = 0; m < 4; ++m) _Pragma("unroll") for (int n = 0; n < 2; ++n) _Pragma("unroll") for (int k = 0; k < 2; ++k) \
;         acc[ai][bj][m][n] = __builtin_amdgcn_mfma_f32_16x16x32_bf16(Bt[n][k], At[m][k], acc[ai][bj][m][n], 0, 0, 0); __builtin_amdgcn_s_setprio(0); } while (0)
; #define PG8_WAIT_V(n) asm volatile("s_waitcnt vmcnt(" #n ")" ::: "memory")
; #define PG8_WAIT_L(n) asm volatile("s_waitcnt lgkmcnt(" #n ")" ::: "memory")
; #define PG8_BAR __builtin_amdgcn_s_barrier()
; #define PG8_SCHED __builtin_amdgcn_sched_barrier(0)
; template <class Epi, class Sched, bool ALIGN_EPI = false, bool SP2 = false>
; __device__ __forceinline__ void gemm_phase(LAS unsigned char* lds, const Gemm g, const Sched& S, const Epi& E) {
;     ...
;         for (int t = 0; t < nt; t += 2) {
;             const bool last = (t == nt - 2);
;             const char* a1 = cA + (size_t)(t + 1) * kstep;
;             const char* a2 = last ? nA : cA + (size_t)(t + 2) * kstep; const char* b2 = last ? nB : cB + (size_t)(t + 2) * kstep;
;             const char* a3 = a2 + kstep; const char* b3 = b2 + kstep;
;             if (last && has_next) S.a_ready(nxt);
;             if constexpr (SP2) {
;             PG8_LDB(B0, 0, 0); PG8_LDB(B1, 0, 1); PG8_SCHED; PG8_LDA(At, 0, 0); PG8_STAGE(PG8_SA(1, 1), a1 + hstep, voffA);
;             PG8_WAIT_V(8); PG8_WAIT_L(0); PG8_BAR; PG8_MMA(0, 0, At, B0); PG8_MMA(0, 1, At, B1); PG8_BAR; PG8_SCHED;
;             PG8_LDA(At, 0, 1); PG8_STAGE(PG8_SB(0, 0), b2, voffB); PG8_STAGE(PG8_SB(0, 1), b2 + hstepB, voffB); PG8_STAGE(PG8_SA(0, 0), a2, voffA);
.LBB0_1465:
	ds_read_b128 v[66:69], v174
	ds_read_b128 v[70:73], v174 offset:1024
	ds_read_b128 v[74:77], v174 offset:2048
	ds_read_b128 v[78:81], v174 offset:3072
	ds_read_b128 v[162:165], v175
	ds_read_b128 v[182:185], v175 offset:1024
	ds_read_b128 v[186:189], v175 offset:2048
	ds_read_b128 v[190:193], v175 offset:3072
	s_add_u32 s22, s16, 0xfff80080
	s_addc_u32 s23, s17, -1
	s_cmp_eq_u32 s53, 28
	s_cselect_b32 s41, s3, s23
	s_cselect_b32 s40, s15, s22
	s_cselect_b32 s23, s13, s52
	s_cselect_b32 s22, s24, s25
	v_lshl_add_u64 v[166:167], s[16:17], 0, v[154:155]
	s_add_i32 m0, s33, 0xc000
	ds_read_b128 v[194:197], v176
	ds_read_b128 v[198:201], v176 offset:1024
	ds_read_b128 v[202:205], v176 offset:2048
	ds_read_b128 v[206:209], v176 offset:3072
	ds_read_b128 v[210:213], v176 offset:4096
	ds_read_b128 v[214:217], v176 offset:5120
	ds_read_b128 v[218:221], v176 offset:6144
	ds_read_b128 v[222:225], v176 offset:7168
	global_load_lds_dwordx4 v[166:167], off
	v_lshl_add_u64 v[166:167], s[16:17], 0, v[156:157]
	s_add_i32 m0, s33, 0xe000
	s_nop 0
	global_load_lds_dwordx4 v[166:167], off
	s_waitcnt vmcnt(8)
	s_waitcnt lgkmcnt(0)
	s_barrier
	v_mfma_f32_16x16x32_bf16 v[142:145], v[66:69], v[194:197], v[142:145]
	v_mfma_f32_16x16x32_bf16 v[138:141], v[74:77], v[194:197], v[138:141]
	v_mfma_f32_16x16x32_bf16 v[126:129], v[66:69], v[202:205], v[126:129]
	v_mfma_f32_16x16x32_bf16 v[122:125], v[74:77], v[202:205], v[122:125]
	v_mfma_f32_16x16x32_bf16 v[110:113], v[66:69], v[210:213], v[110:113]
	v_mfma_f32_16x16x32_bf16 v[106:109], v[74:77], v[210:213], v[106:109]
	v_mfma_f32_16x16x32_bf16 v[94:97], v[66:69], v[218:221], v[94:97]
	v_mfma_f32_16x16x32_bf16 v[90:93], v[74:77], v[218:221], v[90:93]
	v_mfma_f32_16x16x32_bf16 v[142:145], v[70:73], v[198:201], v[142:145]
	v_mfma_f32_16x16x32_bf16 v[138:141], v[78:81], v[198:201], v[138:141]
	v_mfma_f32_16x16x32_bf16 v[126:129], v[70:73], v[206:209], v[126:129]
	v_mfma_f32_16x16x32_bf16 v[122:125], v[78:81], v[206:209], v[122:125]
	v_mfma_f32_16x16x32_bf16 v[110:113], v[70:73], v[214:217], v[110:113]
	v_mfma_f32_16x16x32_bf16 v[106:109], v[78:81], v[214:217], v[106:109]
	v_mfma_f32_16x16x32_bf16 v[94:97], v[70:73], v[222:225], v[94:97]
	v_mfma_f32_16x16x32_bf16 v[90:93], v[78:81], v[222:225], v[90:93]
	v_mfma_f32_16x16x32_bf16 v[134:137], v[162:165], v[194:197], v[134:137]
	v_mfma_f32_16x16x32_bf16 v[130:133], v[186:189], v[194:197], v[130:133]
	v_mfma_f32_16x16x32_bf16 v[118:121], v[162:165], v[202:205], v[118:121]
	v_mfma_f32_16x16x32_bf16 v[114:117], v[186:189], v[202:205], v[114:117]
	v_mfma_f32_16x16x32_bf16 v[102:105], v[162:165], v[210:213], v[102:105]
	v_mfma_f32_16x16x32_bf16 v[98:101], v[186:189], v[210:213], v[98:101]
	v_mfma_f32_16x16x32_bf16 v[86:89], v[162:165], v[218:221], v[86:89]
	v_mfma_f32_16x16x32_bf16 v[82:85], v[186:189], v[218:221], v[82:85]
	v_mfma_f32_16x16x32_bf16 v[134:137], v[182:185], v[198:201], v[134:137]
	v_mfma_f32_16x16x32_bf16 v[130:133], v[190:193], v[198:201], v[130:133]
	v_mfma_f32_16x16x32_bf16 v[118:121], v[182:185], v[206:209], v[118:121]
	v_mfma_f32_16x16x32_bf16 v[114:117], v[190:193], v[206:209], v[114:117]
	v_mfma_f32_16x16x32_bf16 v[102:105], v[182:185], v[214:217], v[102:105]
	v_mfma_f32_16x16x32_bf16 v[98:101], v[190:193], v[214:217], v[98:101]
	v_mfma_f32_16x16x32_bf16 v[86:89], v[182:185], v[222:225], v[86:89]
	v_mfma_f32_16x16x32_bf16 v[82:85], v[190:193], v[222:225], v[82:85]
	s_barrier
	s_add_i32 s54, s47, s29
	v_lshl_add_u64 v[166:167], s[22:23], 0, v[150:151]
	s_mov_b32 m0, s54
	ds_read_b128 v[194:197], v176 offset:16384
	ds_read_b128 v[198:201], v176 offset:17408
	ds_read_b128 v[202:205], v176 offset:18432
	ds_read_b128 v[206:209], v176 offset:19456
	ds_read_b128 v[210:213], v176 offset:20480
	ds_read_b128 v[214:217], v176 offset:21504
	ds_read_b128 v[218:221], v176 offset:22528
	ds_read_b128 v[222:225], v176 offset:23552
	global_load_lds_dwordx4 v[166:167], off
	s_add_i32 m0, s54, 0x2000
	s_add_u32 s54, s22, 0x80000
	v_lshl_add_u64 v[226:227], s[22:23], 0, v[146:147]
	s_addc_u32 s55, s23, 0
	s_add_i32 s56, s48, s29
	global_load_lds_dwordx4 v[226:227], off
	v_lshl_add_u64 v[228:229], s[54:55], 0, v[150:151]
	s_mov_b32 m0, s56
	v_lshl_add_u64 v[230:231], s[40:41], 0, v[148:149]
	global_load_lds_dwordx4 v[228:229], off
	v_lshl_add_u64 v[228:229], s[54:55], 0, v[146:147]
	s_add_i32 m0, s56, 0x2000
	s_nop 0
	global_load_lds_dwordx4 v[228:229], off
	v_lshl_add_u64 v[228:229], s[40:41], 0, v[152:153]
	s_mov_b32 m0, s33
	s_nop 0
	global_load_lds_dwordx4 v[228:229], off
	s_mov_b32 m0, s34
	s_nop 0
	global_load_lds_dwordx4 v[230:231], off
	s_waitcnt vmcnt(8)
	s_waitcnt lgkmcnt(0)
	s_barrier
; #define PG8_STAGE(bufoff, gbase, voff) do { _Pragma("unroll") for (int _i = 0; _i < 2; ++_i) \
;         __builtin_amdgcn_global_load_lds((const unsigned*)((const char*)(gbase) + (voff)[_i]), (LAS unsigned*)(lds + (bufoff) + ldsw + _i * 8192), 16, 0, 0); } while (0)
; #define PG8_LDA(dst, b, h) do { _Pragma("unroll") for (int m = 0; m < 4; ++m) _Pragma("unroll") for (int k = 0; k < 2; ++k) dst[m][k] = *(const LAS bf16x8*)(lds + PG8_SA(b, h) + aoff + m * 2048 + k * 1024); } while (0)
; #define PG8_LDB(dst, b, h) do { _Pragma("unroll") for (int n = 0; n < 2; ++n) _Pragma("unroll") for (int k = 0; k < 2; ++k) dst[n][k] = *(const LAS bf16x8*)(lds + PG8_SB(b, h) + boff + n * 2048 + k * 1024); } while (0)
; #define PG8_MMA(ai, bj, At, Bt) do { __builtin_amdgcn_s_setprio(1); _Pragma("unroll") for (int m = 0; m < 4; ++m) _Pragma("unroll") for (int n = 0; n < 2; ++n) _Pragma("unroll") for (int k = 0; k < 2; ++k) \
;         acc[ai][bj][m][n] = __builtin_amdgcn_mfma_f32_16x16x32_bf16(Bt[n][k], At[m][k], acc[ai][bj][m][n], 0, 0, 0); __builtin_amdgcn_s_setprio(0); } while (0)
; #define PG8_WAIT_V(n) asm volatile("s_waitcnt vmcnt(" #n ")" ::: "memory")
; #define PG8_WAIT_L(n) asm volatile("s_waitcnt lgkmcnt(" #n ")" ::: "memory")
; #define PG8_BAR __builtin_amdgcn_s_barrier()
; #define PG8_SCHED __builtin_amdgcn_sched_barrier(0)
; template <class Epi, class Sched, bool ALIGN_EPI = false, bool SP2 = false>
; __device__ __forceinline__ void gemm_phase(LAS unsigned char* lds, const Gemm g, const Sched& S, const Epi& E) {
;     ...
;             PG8_WAIT_V(8); PG8_WAIT_L(0); PG8_BAR; PG8_MMA(0, 0, At, B0); PG8_MMA(0, 1, At, B1); PG8_BAR; PG8_SCHED;
;             PG8_LDA(At, 0, 1); PG8_STAGE(PG8_SB(0, 0), b2, voffB); PG8_STAGE(PG8_SB(0, 1), b2 + hstepB, voffB); PG8_STAGE(PG8_SA(0, 0), a2, voffA);
;             PG8_WAIT_V(8); PG8_WAIT_L(0); PG8_BAR; PG8_MMA(1, 0, At, B0); PG8_MMA(1, 1, At, B1); PG8_BAR; PG8_SCHED;
;             PG8_LDB(B0, 1, 0); PG8_LDB(B1, 1, 1); PG8_SCHED; PG8_LDA(At, 1, 0); PG8_STAGE(PG8_SA(0, 1), a2 + hstep, voffA);
;             PG8_WAIT_V(8); PG8_WAIT_L(0); PG8_BAR; PG8_MMA(0, 0, At, B0); PG8_MMA(0, 1, At, B1); PG8_BAR; PG8_SCHED;
;             PG8_LDA(At, 1, 1); PG8_STAGE(PG8_SB(1, 0), b3, voffB); PG8_STAGE(PG8_SB(1, 1), b3 + hstepB, voffB); PG8_STAGE(PG8_SA(1, 0), a3, voffA);
	v_mfma_f32_16x16x32_bf16 v[62:65], v[66:69], v[194:197], v[62:65]
	v_mfma_f32_16x16x32_bf16 v[58:61], v[74:77], v[194:197], v[58:61]
	v_mfma_f32_16x16x32_bf16 v[46:49], v[66:69], v[202:205], v[46:49]
	v_mfma_f32_16x16x32_bf16 v[42:45], v[74:77], v[202:205], v[42:45]
	v_mfma_f32_16x16x32_bf16 v[30:33], v[66:69], v[210:213], v[30:33]
	v_mfma_f32_16x16x32_bf16 v[26:29], v[74:77], v[210:213], v[26:29]
	v_mfma_f32_16x16x32_bf16 v[14:17], v[66:69], v[218:221], v[14:17]
	v_mfma_f32_16x16x32_bf16 v[10:13], v[74:77], v[218:221], v[10:13]
	v_mfma_f32_16x16x32_bf16 v[62:65], v[70:73], v[198:201], v[62:65]
	v_mfma_f32_16x16x32_bf16 v[58:61], v[78:81], v[198:201], v[58:61]
	v_mfma_f32_16x16x32_bf16 v[46:49], v[70:73], v[206:209], v[46:49]
	v_mfma_f32_16x16x32_bf16 v[42:45], v[78:81], v[206:209], v[42:45]
	v_mfma_f32_16x16x32_bf16 v[30:33], v[70:73], v[214:217], v[30:33]
	v_mfma_f32_16x16x32_bf16 v[26:29], v[78:81], v[214:217], v[26:29]
	v_mfma_f32_16x16x32_bf16 v[14:17], v[70:73], v[222:225], v[14:17]
	v_mfma_f32_16x16x32_bf16 v[10:13], v[78:81], v[222:225], v[10:13]
	v_mfma_f32_16x16x32_bf16 v[54:57], v[162:165], v[194:197], v[54:57]
	v_mfma_f32_16x16x32_bf16 v[50:53], v[186:189], v[194:197], v[50:53]
	v_mfma_f32_16x16x32_bf16 v[38:41], v[162:165], v[202:205], v[38:41]
	v_mfma_f32_16x16x32_bf16 v[34:37], v[186:189], v[202:205], v[34:37]
	v_mfma_f32_16x16x32_bf16 v[22:25], v[162:165], v[210:213], v[22:25]
	v_mfma_f32_16x16x32_bf16 v[18:21], v[186:189], v[210:213], v[18:21]
	v_mfma_f32_16x16x32_bf16 v[6:9], v[162:165], v[218:221], v[6:9]
	v_mfma_f32_16x16x32_bf16 v[2:5], v[186:189], v[218:221], v[2:5]
	v_mfma_f32_16x16x32_bf16 v[54:57], v[182:185], v[198:201], v[54:57]
	v_mfma_f32_16x16x32_bf16 v[50:53], v[190:193], v[198:201], v[50:53]
	v_mfma_f32_16x16x32_bf16 v[38:41], v[182:185], v[206:209], v[38:41]
	v_mfma_f32_16x16x32_bf16 v[34:37], v[190:193], v[206:209], v[34:37]
	v_mfma_f32_16x16x32_bf16 v[22:25], v[182:185], v[214:217], v[22:25]
	v_mfma_f32_16x16x32_bf16 v[18:21], v[190:193], v[214:217], v[18:21]
	v_mfma_f32_16x16x32_bf16 v[6:9], v[182:185], v[222:225], v[6:9]
	v_mfma_f32_16x16x32_bf16 v[2:5], v[190:193], v[222:225], v[2:5]
	s_barrier
	s_add_i32 s54, 0, 0x18000
	s_add_i32 s55, 0, 0x1c000
	v_add_u32_e32 v78, s54, v170
	v_add_u32_e32 v168, s55, v170
	ds_read_b128 v[66:69], v78
	ds_read_b128 v[70:73], v78 offset:1024
	ds_read_b128 v[74:77], v78 offset:2048
	ds_read_b128 v[78:81], v78 offset:3072
	ds_read_b128 v[162:165], v168
	ds_read_b128 v[182:185], v168 offset:1024
	ds_read_b128 v[186:189], v168 offset:2048
	ds_read_b128 v[190:193], v168 offset:3072
	s_add_u32 s40, s40, 0x80000
	s_addc_u32 s41, s41, 0
	s_mov_b32 m0, s35
	v_lshl_add_u64 v[232:233], s[40:41], 0, v[152:153]
	ds_read_b128 v[194:197], v176 offset:32768
	ds_read_b128 v[198:201], v176 offset:33792
	ds_read_b128 v[202:205], v176 offset:34816
	ds_read_b128 v[206:209], v176 offset:35840
	ds_read_b128 v[210:213], v176 offset:36864
	ds_read_b128 v[214:217], v176 offset:37888
	ds_read_b128 v[218:221], v176 offset:38912
	ds_read_b128 v[222:225], v176 offset:39936
	global_load_lds_dwordx4 v[232:233], off
	v_lshl_add_u64 v[232:233], s[40:41], 0, v[148:149]
	s_mov_b32 m0, s36
	s_nop 0
	global_load_lds_dwordx4 v[232:233], off
	s_waitcnt vmcnt(8)
	s_waitcnt lgkmcnt(0)
	s_barrier
	v_mfma_f32_16x16x32_bf16 v[142:145], v[66:69], v[194:197], v[142:145]
	v_mfma_f32_16x16x32_bf16 v[138:141], v[74:77], v[194:197], v[138:141]
	v_mfma_f32_16x16x32_bf16 v[126:129], v[66:69], v[202:205], v[126:129]
	v_mfma_f32_16x16x32_bf16 v[122:125], v[74:77], v[202:205], v[122:125]
	v_mfma_f32_16x16x32_bf16 v[110:113], v[66:69], v[210:213], v[110:113]
	v_mfma_f32_16x16x32_bf16 v[106:109], v[74:77], v[210:213], v[106:109]
	v_mfma_f32_16x16x32_bf16 v[94:97], v[66:69], v[218:221], v[94:97]
	v_mfma_f32_16x16x32_bf16 v[90:93], v[74:77], v[218:221], v[90:93]
	v_mfma_f32_16x16x32_bf16 v[142:145], v[70:73], v[198:201], v[142:145]
	v_mfma_f32_16x16x32_bf16 v[138:141], v[78:81], v[198:201], v[138:141]
	v_mfma_f32_16x16x32_bf16 v[126:129], v[70:73], v[206:209], v[126:129]
	v_mfma_f32_16x16x32_bf16 v[122:125], v[78:81], v[206:209], v[122:125]
	v_mfma_f32_16x16x32_bf16 v[110:113], v[70:73], v[214:217], v[110:113]
	v_mfma_f32_16x16x32_bf16 v[106:109], v[78:81], v[214:217], v[106:109]
	v_mfma_f32_16x16x32_bf16 v[94:97], v[70:73], v[222:225], v[94:97]
	v_mfma_f32_16x16x32_bf16 v[90:93], v[78:81], v[222:225], v[90:93]
	v_mfma_f32_16x16x32_bf16 v[134:137], v[162:165], v[194:197], v[134:137]
	v_mfma_f32_16x16x32_bf16 v[130:133], v[186:189], v[194:197], v[130:133]
	v_mfma_f32_16x16x32_bf16 v[118:121], v[162:165], v[202:205], v[118:121]
	v_mfma_f32_16x16x32_bf16 v[114:117], v[186:189], v[202:205], v[114:117]
	v_mfma_f32_16x16x32_bf16 v[102:105], v[162:165], v[210:213], v[102:105]
	v_mfma_f32_16x16x32_bf16 v[98:101], v[186:189], v[210:213], v[98:101]
	v_mfma_f32_16x16x32_bf16 v[86:89], v[162:165], v[218:221], v[86:89]
	v_mfma_f32_16x16x32_bf16 v[82:85], v[186:189], v[218:221], v[82:85]
	v_mfma_f32_16x16x32_bf16 v[134:137], v[182:185], v[198:201], v[134:137]
	v_mfma_f32_16x16x32_bf16 v[130:133], v[190:193], v[198:201], v[130:133]
	v_mfma_f32_16x16x32_bf16 v[118:121], v[182:185], v[206:209], v[118:121]
	v_mfma_f32_16x16x32_bf16 v[114:117], v[190:193], v[206:209], v[114:117]
	v_mfma_f32_16x16x32_bf16 v[102:105], v[182:185], v[214:217], v[102:105]
	v_mfma_f32_16x16x32_bf16 v[98:101], v[190:193], v[214:217], v[98:101]
	v_mfma_f32_16x16x32_bf16 v[86:89], v[182:185], v[222:225], v[86:89]
	v_mfma_f32_16x16x32_bf16 v[82:85], v[190:193], v[222:225], v[82:85]
	s_barrier
; #define PG8_STAGE(bufoff, gbase, voff) do { _Pragma("unroll") for (int _i = 0; _i < 2; ++_i) \
;         __builtin_amdgcn_global_load_lds((const unsigned*)((const char*)(gbase) + (voff)[_i]), (LAS unsigned*)(lds + (bufoff) + ldsw + _i * 8192), 16, 0, 0); } while (0)
; #define PG8_LDA(dst, b, h) do { _Pragma("unroll") for (int m = 0; m < 4; ++m) _Pragma("unroll") for (int k = 0; k < 2; ++k) dst[m][k] = *(const LAS bf16x8*)(lds + PG8_SA(b, h) + aoff + m * 2048 + k * 1024); } while (0)
; #define PG8_MMA(ai, bj, At, Bt) do { __builtin_amdgcn_s_setprio(1); _Pragma("unroll") for (int m = 0; m < 4; ++m) _Pragma("unroll") for (int n = 0; n < 2; ++n) _Pragma("unroll") for (int k = 0; k < 2; ++k) \
;         acc[ai][bj][m][n] = __builtin_amdgcn_mfma_f32_16x16x32_bf16(Bt[n][k], At[m][k], acc[ai][bj][m][n], 0, 0, 0); __builtin_amdgcn_s_setprio(0); } while (0)
; #define PG8_WAIT_V(n) asm volatile("s_waitcnt vmcnt(" #n ")" ::: "memory")
; #define PG8_WAIT_L(n) asm volatile("s_waitcnt lgkmcnt(" #n ")" ::: "memory")
; #define PG8_BAR __builtin_amdgcn_s_barrier()
; #define PG8_SCHED __builtin_amdgcn_sched_barrier(0)
; template <class Epi, class Sched, bool ALIGN_EPI = false, bool SP2 = false>
; __device__ __forceinline__ void gemm_phase(LAS unsigned char* lds, const Gemm g, const Sched& S, const Epi& E) {
;     ...
;             PG8_LDA(At, 1, 1); PG8_STAGE(PG8_SB(1, 0), b3, voffB); PG8_STAGE(PG8_SB(1, 1), b3 + hstepB, voffB); PG8_STAGE(PG8_SA(1, 0), a3, voffA);
;             PG8_WAIT_V(8); PG8_WAIT_L(0); PG8_BAR; PG8_MMA(1, 0, At, B0); PG8_MMA(1, 1, At, B1); PG8_BAR; PG8_SCHED;
;     ...
;         if constexpr (ALIGN_EPI) { if (wr == 0) PG8_BAR; }
	s_add_i32 s40, s54, s29
	v_lshl_add_u64 v[166:167], v[166:167], 0, s[8:9]
	s_mov_b32 m0, s40
	ds_read_b128 v[194:197], v176 offset:49152
	ds_read_b128 v[198:201], v176 offset:50176
	ds_read_b128 v[202:205], v176 offset:51200
	ds_read_b128 v[206:209], v176 offset:52224
	ds_read_b128 v[210:213], v176 offset:53248
	ds_read_b128 v[214:217], v176 offset:54272
	ds_read_b128 v[218:221], v176 offset:55296
	ds_read_b128 v[222:225], v176 offset:56320
	global_load_lds_dwordx4 v[166:167], off
	s_add_i32 m0, s40, 0x2000
	s_add_u32 s22, s22, 0x80080
	v_lshl_add_u64 v[166:167], v[226:227], 0, s[8:9]
	s_addc_u32 s23, s23, 0
	s_add_i32 s40, s55, s29
	global_load_lds_dwordx4 v[166:167], off
	v_lshl_add_u64 v[166:167], s[22:23], 0, v[150:151]
	s_mov_b32 m0, s40
	s_nop 0
	global_load_lds_dwordx4 v[166:167], off
	v_lshl_add_u64 v[166:167], s[22:23], 0, v[146:147]
	s_add_i32 m0, s40, 0x2000
	s_nop 0
	global_load_lds_dwordx4 v[166:167], off
	v_lshl_add_u64 v[166:167], v[228:229], 0, s[8:9]
	s_mov_b32 m0, s45
	s_nop 0
	global_load_lds_dwordx4 v[166:167], off
	v_lshl_add_u64 v[166:167], v[230:231], 0, s[8:9]
	s_mov_b32 m0, s46
	s_nop 0
	global_load_lds_dwordx4 v[166:167], off
	s_waitcnt vmcnt(8)
	s_waitcnt lgkmcnt(0)
	s_barrier
	v_mfma_f32_16x16x32_bf16 v[62:65], v[66:69], v[194:197], v[62:65]
	v_mfma_f32_16x16x32_bf16 v[58:61], v[74:77], v[194:197], v[58:61]
	v_mfma_f32_16x16x32_bf16 v[46:49], v[66:69], v[202:205], v[46:49]
	v_mfma_f32_16x16x32_bf16 v[42:45], v[74:77], v[202:205], v[42:45]
	v_mfma_f32_16x16x32_bf16 v[30:33], v[66:69], v[210:213], v[30:33]
	v_mfma_f32_16x16x32_bf16 v[26:29], v[74:77], v[210:213], v[26:29]
	v_mfma_f32_16x16x32_bf16 v[14:17], v[66:69], v[218:221], v[14:17]
	v_mfma_f32_16x16x32_bf16 v[10:13], v[74:77], v[218:221], v[10:13]
	v_mfma_f32_16x16x32_bf16 v[62:65], v[70:73], v[198:201], v[62:65]
	v_mfma_f32_16x16x32_bf16 v[58:61], v[78:81], v[198:201], v[58:61]
	v_mfma_f32_16x16x32_bf16 v[46:49], v[70:73], v[206:209], v[46:49]
	v_mfma_f32_16x16x32_bf16 v[42:45], v[78:81], v[206:209], v[42:45]
	v_mfma_f32_16x16x32_bf16 v[30:33], v[70:73], v[214:217], v[30:33]
	v_mfma_f32_16x16x32_bf16 v[26:29], v[78:81], v[214:217], v[26:29]
	v_mfma_f32_16x16x32_bf16 v[14:17], v[70:73], v[222:225], v[14:17]
	v_mfma_f32_16x16x32_bf16 v[10:13], v[78:81], v[222:225], v[10:13]
	v_mfma_f32_16x16x32_bf16 v[54:57], v[162:165], v[194:197], v[54:57]
	v_mfma_f32_16x16x32_bf16 v[50:53], v[186:189], v[194:197], v[50:53]
	v_mfma_f32_16x16x32_bf16 v[38:41], v[162:165], v[202:205], v[38:41]
	v_mfma_f32_16x16x32_bf16 v[34:37], v[186:189], v[202:205], v[34:37]
	v_mfma_f32_16x16x32_bf16 v[22:25], v[162:165], v[210:213], v[22:25]
	v_mfma_f32_16x16x32_bf16 v[18:21], v[186:189], v[210:213], v[18:21]
	v_mfma_f32_16x16x32_bf16 v[6:9], v[162:165], v[218:221], v[6:9]
	v_mfma_f32_16x16x32_bf16 v[2:5], v[186:189], v[218:221], v[2:5]
	v_mfma_f32_16x16x32_bf16 v[54:57], v[182:185], v[198:201], v[54:57]
	v_mfma_f32_16x16x32_bf16 v[50:53], v[190:193], v[198:201], v[50:53]
	v_mfma_f32_16x16x32_bf16 v[38:41], v[182:185], v[206:209], v[38:41]
	v_mfma_f32_16x16x32_bf16 v[34:37], v[190:193], v[206:209], v[34:37]
	v_mfma_f32_16x16x32_bf16 v[22:25], v[182:185], v[214:217], v[22:25]
	v_mfma_f32_16x16x32_bf16 v[18:21], v[190:193], v[214:217], v[18:21]
	v_mfma_f32_16x16x32_bf16 v[6:9], v[182:185], v[222:225], v[6:9]
	v_mfma_f32_16x16x32_bf16 v[2:5], v[190:193], v[222:225], v[2:5]
	s_barrier
	s_add_i32 s53, s53, 2
	s_add_u32 s16, s16, 0x100
	s_addc_u32 s17, s17, 0
	s_add_u32 s25, s25, 0x100
	s_addc_u32 s52, s52, 0
	s_cmp_gt_u32 s53, 29
	s_cbranch_scc0 .LBB0_1465
	s_setprio 0
	s_and_b64 vcc, exec, s[10:11]
	s_cbranch_vccz .LBB0_1468
	s_barrier

; #define PG8_STAGE(bufoff, gbase, voff) do { _Pragma("unroll") for (int _i = 0; _i < 2; ++_i) \
;         __builtin_amdgcn_global_load_lds((const unsigned*)((const char*)(gbase) + (voff)[_i]), (LAS unsigned*)(lds + (bufoff) + ldsw + _i * 8192), 16, 0, 0); } while (0)
; #define PG8_LDA(dst, b, h) do { _Pragma("unroll") for (int m = 0; m < 4; ++m) _Pragma("unroll") for (int k = 0; k < 2; ++k) dst[m][k] = *(const LAS bf16x8*)(lds + PG8_SA(b, h) + aoff + m * 2048 + k * 1024); } while (0)
; #define PG8_LDB(dst, b, h) do { _Pragma("unroll") for (int n = 0; n < 2; ++n) _Pragma("unroll") for (int k = 0; k < 2; ++k) dst[n][k] = *(const LAS bf16x8*)(lds + PG8_SB(b, h) + boff + n * 2048 + k * 1024); } while (0)
; #define PG8_MMA(ai, bj, At, Bt) do { __builtin_amdgcn_s_setprio(1); _Pragma("unroll") for (int m = 0; m < 4; ++m) _Pragma("unroll") for (int n = 0; n < 2; ++n) _Pragma("unroll") for (int k = 0; k < 2; ++k) \
;         acc[ai][bj][m][n] = __builtin_amdgcn_mfma_f32_16x16x32_bf16(Bt[n][k], At[m][k], acc[ai][bj][m][n], 0, 0, 0); __builtin_amdgcn_s_setprio(0); } while (0)
; #define PG8_WAIT_V(n) asm volatile("s_waitcnt vmcnt(" #n ")" ::: "memory")
; #define PG8_WAIT_L(n) asm volatile("s_waitcnt lgkmcnt(" #n ")" ::: "memory")
; #define PG8_BAR __builtin_amdgcn_s_barrier()
; #define PG8_SCHED __builtin_amdgcn_sched_barrier(0)
; template <class Epi, class Sched, bool ALIGN_EPI = false, bool SP2 = false>
; __device__ __forceinline__ void gemm_phase(LAS unsigned char* lds, const Gemm g, const Sched& S, const Epi& E) {
;     ...
;         for (int t = 0; t < nt; t += 2) {
;             const bool last = (t == nt - 2);
;             const char* a1 = cA + (size_t)(t + 1) * kstep;
;             const char* a2 = last ? nA : cA + (size_t)(t + 2) * kstep; const char* b2 = last ? nB : cB + (size_t)(t + 2) * kstep;
;             const char* a3 = a2 + kstep; const char* b3 = b2 + kstep;
;             if (last && has_next) S.a_ready(nxt);
;             if constexpr (SP2) {
;             PG8_LDB(B0, 0, 0); PG8_LDB(B1, 0, 1); PG8_SCHED; PG8_LDA(At, 0, 0); PG8_STAGE(PG8_SA(1, 1), a1 + hstep, voffA);
;             PG8_WAIT_V(8); PG8_WAIT_L(0); PG8_BAR; PG8_MMA(0, 0, At, B0); PG8_MMA(0, 1, At, B1); PG8_BAR; PG8_SCHED;
;             PG8_LDA(At, 0, 1); PG8_STAGE(PG8_SB(0, 0), b2, voffB); PG8_STAGE(PG8_SB(0, 1), b2 + hstepB, voffB); PG8_STAGE(PG8_SA(0, 0), a2, voffA);
.LBB0_1565:
	ds_read_b128 v[144:147], v135
	ds_read_b128 v[148:151], v135 offset:1024
	ds_read_b128 v[152:155], v135 offset:2048
	ds_read_b128 v[156:159], v135 offset:3072
	ds_read_b128 v[160:163], v140
	ds_read_b128 v[164:167], v140 offset:1024
	ds_read_b128 v[168:171], v140 offset:2048
	ds_read_b128 v[172:175], v140 offset:3072
	s_add_i32 s46, s16, 2
	s_cmp_lg_u32 s35, s16
	s_cselect_b32 s16, s12, 0
	s_cselect_b32 s17, s13, 0
	s_add_u32 s18, s8, s16
	s_addc_u32 s19, s9, s17
	s_add_u32 s16, s2, s16
	s_addc_u32 s17, s3, s17
	v_lshl_add_u64 v[208:209], v[136:137], 0, s[12:13]
	s_mov_b32 m0, s36
	v_lshl_add_u64 v[208:209], v[208:209], 0, s[14:15]
	ds_read_b128 v[176:179], v141
	ds_read_b128 v[180:183], v141 offset:1024
	ds_read_b128 v[184:187], v141 offset:2048
	ds_read_b128 v[188:191], v141 offset:3072
	ds_read_b128 v[192:195], v141 offset:4096
	ds_read_b128 v[196:199], v141 offset:5120
	ds_read_b128 v[200:203], v141 offset:6144
	ds_read_b128 v[204:207], v141 offset:7168
	global_load_lds_dwordx4 v[208:209], off
	v_lshl_add_u64 v[208:209], v[138:139], 0, s[12:13]
	v_lshl_add_u64 v[208:209], v[208:209], 0, s[14:15]
	s_mov_b32 m0, s37
	s_nop 0
	global_load_lds_dwordx4 v[208:209], off
	s_waitcnt vmcnt(8)
	s_waitcnt lgkmcnt(0)
	s_barrier
	s_setprio 1
	v_mfma_f32_16x16x32_bf16 v[126:129], v[144:147], v[176:179], v[126:129]
	v_mfma_f32_16x16x32_bf16 v[94:97], v[152:155], v[176:179], v[94:97]
	v_mfma_f32_16x16x32_bf16 v[122:125], v[144:147], v[184:187], v[122:125]
	v_mfma_f32_16x16x32_bf16 v[90:93], v[152:155], v[184:187], v[90:93]
	v_mfma_f32_16x16x32_bf16 v[118:121], v[144:147], v[192:195], v[118:121]
	v_mfma_f32_16x16x32_bf16 v[86:89], v[152:155], v[192:195], v[86:89]
	v_mfma_f32_16x16x32_bf16 v[114:117], v[144:147], v[200:203], v[114:117]
	v_mfma_f32_16x16x32_bf16 v[82:85], v[152:155], v[200:203], v[82:85]
	v_mfma_f32_16x16x32_bf16 v[126:129], v[148:151], v[180:183], v[126:129]
	v_mfma_f32_16x16x32_bf16 v[94:97], v[156:159], v[180:183], v[94:97]
	v_mfma_f32_16x16x32_bf16 v[122:125], v[148:151], v[188:191], v[122:125]
	v_mfma_f32_16x16x32_bf16 v[90:93], v[156:159], v[188:191], v[90:93]
	v_mfma_f32_16x16x32_bf16 v[118:121], v[148:151], v[196:199], v[118:121]
	v_mfma_f32_16x16x32_bf16 v[86:89], v[156:159], v[196:199], v[86:89]
	v_mfma_f32_16x16x32_bf16 v[114:117], v[148:151], v[204:207], v[114:117]
	v_mfma_f32_16x16x32_bf16 v[82:85], v[156:159], v[204:207], v[82:85]
	s_setprio 0
	s_setprio 1
	v_mfma_f32_16x16x32_bf16 v[70:73], v[160:163], v[176:179], v[70:73]
	v_mfma_f32_16x16x32_bf16 v[42:45], v[168:171], v[176:179], v[42:45]
	v_mfma_f32_16x16x32_bf16 v[62:65], v[160:163], v[184:187], v[62:65]
	v_mfma_f32_16x16x32_bf16 v[34:37], v[168:171], v[184:187], v[34:37]
	v_mfma_f32_16x16x32_bf16 v[54:57], v[160:163], v[192:195], v[54:57]
	v_mfma_f32_16x16x32_bf16 v[26:29], v[168:171], v[192:195], v[26:29]
	v_mfma_f32_16x16x32_bf16 v[50:53], v[160:163], v[200:203], v[50:53]
	v_mfma_f32_16x16x32_bf16 v[18:21], v[168:171], v[200:203], v[18:21]
	v_mfma_f32_16x16x32_bf16 v[70:73], v[164:167], v[180:183], v[70:73]
	v_mfma_f32_16x16x32_bf16 v[42:45], v[172:175], v[180:183], v[42:45]
	v_mfma_f32_16x16x32_bf16 v[62:65], v[164:167], v[188:191], v[62:65]
	v_mfma_f32_16x16x32_bf16 v[34:37], v[172:175], v[188:191], v[34:37]
	v_mfma_f32_16x16x32_bf16 v[54:57], v[164:167], v[196:199], v[54:57]
	v_mfma_f32_16x16x32_bf16 v[26:29], v[172:175], v[196:199], v[26:29]
	v_mfma_f32_16x16x32_bf16 v[50:53], v[164:167], v[204:207], v[50:53]
	v_mfma_f32_16x16x32_bf16 v[18:21], v[172:175], v[204:207], v[18:21]
	s_setprio 0
	s_barrier
	s_mov_b32 m0, s38
	v_lshl_add_u64 v[208:209], s[16:17], 0, v[132:133]
	s_add_u32 s48, s16, 0x160000
	ds_read_b128 v[176:179], v141 offset:16384
	ds_read_b128 v[180:183], v141 offset:17408
	ds_read_b128 v[184:187], v141 offset:18432
	ds_read_b128 v[188:191], v141 offset:19456
	ds_read_b128 v[192:195], v141 offset:20480
	ds_read_b128 v[196:199], v141 offset:21504
	ds_read_b128 v[200:203], v141 offset:22528
	ds_read_b128 v[204:207], v141 offset:23552
	global_load_lds_dwordx4 v[208:209], off
	v_lshl_add_u64 v[210:211], s[16:17], 0, v[130:131]
	s_mov_b32 m0, s39
	s_addc_u32 s49, s17, 0
	global_load_lds_dwordx4 v[210:211], off
	v_lshl_add_u64 v[212:213], s[48:49], 0, v[132:133]
	s_mov_b32 m0, s40
	v_lshl_add_u64 v[214:215], s[18:19], 0, v[130:131]
	global_load_lds_dwordx4 v[212:213], off
	v_lshl_add_u64 v[212:213], s[48:49], 0, v[130:131]
	s_mov_b32 m0, s41
	s_nop 0
	global_load_lds_dwordx4 v[212:213], off
	v_lshl_add_u64 v[212:213], s[18:19], 0, v[132:133]
	s_mov_b32 m0, s22
	s_nop 0
	global_load_lds_dwordx4 v[212:213], off
	s_mov_b32 m0, s24
	s_nop 0
	global_load_lds_dwordx4 v[214:215], off
	s_waitcnt vmcnt(8)
	s_waitcnt lgkmcnt(0)
	s_barrier
; #define PG8_STAGE(bufoff, gbase, voff) do { _Pragma("unroll") for (int _i = 0; _i < 2; ++_i) \
;         __builtin_amdgcn_global_load_lds((const unsigned*)((const char*)(gbase) + (voff)[_i]), (LAS unsigned*)(lds + (bufoff) + ldsw + _i * 8192), 16, 0, 0); } while (0)
; #define PG8_LDA(dst, b, h) do { _Pragma("unroll") for (int m = 0; m < 4; ++m) _Pragma("unroll") for (int k = 0; k < 2; ++k) dst[m][k] = *(const LAS bf16x8*)(lds + PG8_SA(b, h) + aoff + m * 2048 + k * 1024); } while (0)
; #define PG8_LDB(dst, b, h) do { _Pragma("unroll") for (int n = 0; n < 2; ++n) _Pragma("unroll") for (int k = 0; k < 2; ++k) dst[n][k] = *(const LAS bf16x8*)(lds + PG8_SB(b, h) + boff + n * 2048 + k * 1024); } while (0)
; #define PG8_MMA(ai, bj, At, Bt) do { __builtin_amdgcn_s_setprio(1); _Pragma("unroll") for (int m = 0; m < 4; ++m) _Pragma("unroll") for (int n = 0; n < 2; ++n) _Pragma("unroll") for (int k = 0; k < 2; ++k) \
;         acc[ai][bj][m][n] = __builtin_amdgcn_mfma_f32_16x16x32_bf16(Bt[n][k], At[m][k], acc[ai][bj][m][n], 0, 0, 0); __builtin_amdgcn_s_setprio(0); } while (0)
; #define PG8_WAIT_V(n) asm volatile("s_waitcnt vmcnt(" #n ")" ::: "memory")
; #define PG8_WAIT_L(n) asm volatile("s_waitcnt lgkmcnt(" #n ")" ::: "memory")
; #define PG8_BAR __builtin_amdgcn_s_barrier()
; #define PG8_SCHED __builtin_amdgcn_sched_barrier(0)
; template <class Epi, class Sched, bool ALIGN_EPI = false, bool SP2 = false>
; __device__ __forceinline__ void gemm_phase(LAS unsigned char* lds, const Gemm g, const Sched& S, const Epi& E) {
;     ...
;             PG8_WAIT_V(8); PG8_WAIT_L(0); PG8_BAR; PG8_MMA(1, 0, At, B0); PG8_MMA(1, 1, At, B1); PG8_BAR; PG8_SCHED;
;             PG8_LDB(B0, 1, 0); PG8_LDB(B1, 1, 1); PG8_SCHED; PG8_LDA(At, 1, 0); PG8_STAGE(PG8_SA(0, 1), a2 + hstep, voffA);
;             PG8_WAIT_V(8); PG8_WAIT_L(0); PG8_BAR; PG8_MMA(0, 0, At, B0); PG8_MMA(0, 1, At, B1); PG8_BAR; PG8_SCHED;
	s_setprio 1
	v_mfma_f32_16x16x32_bf16 v[110:113], v[144:147], v[176:179], v[110:113]
	v_mfma_f32_16x16x32_bf16 v[78:81], v[152:155], v[176:179], v[78:81]
	v_mfma_f32_16x16x32_bf16 v[106:109], v[144:147], v[184:187], v[106:109]
	v_mfma_f32_16x16x32_bf16 v[74:77], v[152:155], v[184:187], v[74:77]
	v_mfma_f32_16x16x32_bf16 v[102:105], v[144:147], v[192:195], v[102:105]
	v_mfma_f32_16x16x32_bf16 v[66:69], v[152:155], v[192:195], v[66:69]
	v_mfma_f32_16x16x32_bf16 v[98:101], v[144:147], v[200:203], v[98:101]
	v_mfma_f32_16x16x32_bf16 v[58:61], v[152:155], v[200:203], v[58:61]
	v_mfma_f32_16x16x32_bf16 v[110:113], v[148:151], v[180:183], v[110:113]
	v_mfma_f32_16x16x32_bf16 v[78:81], v[156:159], v[180:183], v[78:81]
	v_mfma_f32_16x16x32_bf16 v[106:109], v[148:151], v[188:191], v[106:109]
	v_mfma_f32_16x16x32_bf16 v[74:77], v[156:159], v[188:191], v[74:77]
	v_mfma_f32_16x16x32_bf16 v[102:105], v[148:151], v[196:199], v[102:105]
	v_mfma_f32_16x16x32_bf16 v[66:69], v[156:159], v[196:199], v[66:69]
	v_mfma_f32_16x16x32_bf16 v[98:101], v[148:151], v[204:207], v[98:101]
	v_mfma_f32_16x16x32_bf16 v[58:61], v[156:159], v[204:207], v[58:61]
	s_setprio 0
	s_setprio 1
	v_mfma_f32_16x16x32_bf16 v[46:49], v[160:163], v[176:179], v[46:49]
	v_mfma_f32_16x16x32_bf16 v[14:17], v[168:171], v[176:179], v[14:17]
	v_mfma_f32_16x16x32_bf16 v[38:41], v[160:163], v[184:187], v[38:41]
	v_mfma_f32_16x16x32_bf16 v[10:13], v[168:171], v[184:187], v[10:13]
	v_mfma_f32_16x16x32_bf16 v[30:33], v[160:163], v[192:195], v[30:33]
	v_mfma_f32_16x16x32_bf16 v[6:9], v[168:171], v[192:195], v[6:9]
	v_mfma_f32_16x16x32_bf16 v[22:25], v[160:163], v[200:203], v[22:25]
	v_mfma_f32_16x16x32_bf16 v[2:5], v[168:171], v[200:203], v[2:5]
	v_mfma_f32_16x16x32_bf16 v[46:49], v[164:167], v[180:183], v[46:49]
	v_mfma_f32_16x16x32_bf16 v[14:17], v[172:175], v[180:183], v[14:17]
	v_mfma_f32_16x16x32_bf16 v[38:41], v[164:167], v[188:191], v[38:41]
	v_mfma_f32_16x16x32_bf16 v[10:13], v[172:175], v[188:191], v[10:13]
	v_mfma_f32_16x16x32_bf16 v[30:33], v[164:167], v[196:199], v[30:33]
	v_mfma_f32_16x16x32_bf16 v[6:9], v[172:175], v[196:199], v[6:9]
	v_mfma_f32_16x16x32_bf16 v[22:25], v[164:167], v[204:207], v[22:25]
	v_mfma_f32_16x16x32_bf16 v[2:5], v[172:175], v[204:207], v[2:5]
	s_setprio 0
	s_barrier
	ds_read_b128 v[144:147], v142
	ds_read_b128 v[148:151], v142 offset:1024
	ds_read_b128 v[152:155], v142 offset:2048
	ds_read_b128 v[156:159], v142 offset:3072
	ds_read_b128 v[160:163], v143
	ds_read_b128 v[164:167], v143 offset:1024
	ds_read_b128 v[168:171], v143 offset:2048
	ds_read_b128 v[172:175], v143 offset:3072
	s_add_u32 s18, s18, 0x160000
	s_addc_u32 s19, s19, 0
	s_mov_b32 m0, s25
	v_lshl_add_u64 v[216:217], s[18:19], 0, v[132:133]
	ds_read_b128 v[176:179], v141 offset:32768
	ds_read_b128 v[180:183], v141 offset:33792
	ds_read_b128 v[184:187], v141 offset:34816
	ds_read_b128 v[188:191], v141 offset:35840
	ds_read_b128 v[192:195], v141 offset:36864
	ds_read_b128 v[196:199], v141 offset:37888
	ds_read_b128 v[200:203], v141 offset:38912
	ds_read_b128 v[204:207], v141 offset:39936
	global_load_lds_dwordx4 v[216:217], off
	v_lshl_add_u64 v[216:217], s[18:19], 0, v[130:131]
	s_mov_b32 m0, s30
	s_nop 0
	global_load_lds_dwordx4 v[216:217], off
	s_waitcnt vmcnt(8)
	s_waitcnt lgkmcnt(0)
	s_barrier
	s_setprio 1
	v_mfma_f32_16x16x32_bf16 v[126:129], v[144:147], v[176:179], v[126:129]
	v_mfma_f32_16x16x32_bf16 v[94:97], v[152:155], v[176:179], v[94:97]
	v_mfma_f32_16x16x32_bf16 v[122:125], v[144:147], v[184:187], v[122:125]
	v_mfma_f32_16x16x32_bf16 v[90:93], v[152:155], v[184:187], v[90:93]
	v_mfma_f32_16x16x32_bf16 v[118:121], v[144:147], v[192:195], v[118:121]
	v_mfma_f32_16x16x32_bf16 v[86:89], v[152:155], v[192:195], v[86:89]
	v_mfma_f32_16x16x32_bf16 v[114:117], v[144:147], v[200:203], v[114:117]
	v_mfma_f32_16x16x32_bf16 v[82:85], v[152:155], v[200:203], v[82:85]
	v_mfma_f32_16x16x32_bf16 v[126:129], v[148:151], v[180:183], v[126:129]
	v_mfma_f32_16x16x32_bf16 v[94:97], v[156:159], v[180:183], v[94:97]
	v_mfma_f32_16x16x32_bf16 v[122:125], v[148:151], v[188:191], v[122:125]
	v_mfma_f32_16x16x32_bf16 v[90:93], v[156:159], v[188:191], v[90:93]
	v_mfma_f32_16x16x32_bf16 v[118:121], v[148:151], v[196:199], v[118:121]
	v_mfma_f32_16x16x32_bf16 v[86:89], v[156:159], v[196:199], v[86:89]
	v_mfma_f32_16x16x32_bf16 v[114:117], v[148:151], v[204:207], v[114:117]
	v_mfma_f32_16x16x32_bf16 v[82:85], v[156:159], v[204:207], v[82:85]
	s_setprio 0
	s_setprio 1
	v_mfma_f32_16x16x32_bf16 v[70:73], v[160:163], v[176:179], v[70:73]
	v_mfma_f32_16x16x32_bf16 v[42:45], v[168:171], v[176:179], v[42:45]
	v_mfma_f32_16x16x32_bf16 v[62:65], v[160:163], v[184:187], v[62:65]
	v_mfma_f32_16x16x32_bf16 v[34:37], v[168:171], v[184:187], v[34:37]
	v_mfma_f32_16x16x32_bf16 v[54:57], v[160:163], v[192:195], v[54:57]
	v_mfma_f32_16x16x32_bf16 v[26:29], v[168:171], v[192:195], v[26:29]
	v_mfma_f32_16x16x32_bf16 v[50:53], v[160:163], v[200:203], v[50:53]
	v_mfma_f32_16x16x32_bf16 v[18:21], v[168:171], v[200:203], v[18:21]
	v_mfma_f32_16x16x32_bf16 v[70:73], v[164:167], v[180:183], v[70:73]
	v_mfma_f32_16x16x32_bf16 v[42:45], v[172:175], v[180:183], v[42:45]
	v_mfma_f32_16x16x32_bf16 v[62:65], v[164:167], v[188:191], v[62:65]
	v_mfma_f32_16x16x32_bf16 v[34:37], v[172:175], v[188:191], v[34:37]
	v_mfma_f32_16x16x32_bf16 v[54:57], v[164:167], v[196:199], v[54:57]
	v_mfma_f32_16x16x32_bf16 v[26:29], v[172:175], v[196:199], v[26:29]
	v_mfma_f32_16x16x32_bf16 v[50:53], v[164:167], v[204:207], v[50:53]
	v_mfma_f32_16x16x32_bf16 v[18:21], v[172:175], v[204:207], v[18:21]
	s_setprio 0
	s_barrier
; #define PG8_STAGE(bufoff, gbase, voff) do { _Pragma("unroll") for (int _i = 0; _i < 2; ++_i) \
;         __builtin_amdgcn_global_load_lds((const unsigned*)((const char*)(gbase) + (voff)[_i]), (LAS unsigned*)(lds + (bufoff) + ldsw + _i * 8192), 16, 0, 0); } while (0)
; #define PG8_LDA(dst, b, h) do { _Pragma("unroll") for (int m = 0; m < 4; ++m) _Pragma("unroll") for (int k = 0; k < 2; ++k) dst[m][k] = *(const LAS bf16x8*)(lds + PG8_SA(b, h) + aoff + m * 2048 + k * 1024); } while (0)
; #define PG8_MMA(ai, bj, At, Bt) do { __builtin_amdgcn_s_setprio(1); _Pragma("unroll") for (int m = 0; m < 4; ++m) _Pragma("unroll") for (int n = 0; n < 2; ++n) _Pragma("unroll") for (int k = 0; k < 2; ++k) \
;         acc[ai][bj][m][n] = __builtin_amdgcn_mfma_f32_16x16x32_bf16(Bt[n][k], At[m][k], acc[ai][bj][m][n], 0, 0, 0); __builtin_amdgcn_s_setprio(0); } while (0)
; #define PG8_WAIT_V(n) asm volatile("s_waitcnt vmcnt(" #n ")" ::: "memory")
; #define PG8_WAIT_L(n) asm volatile("s_waitcnt lgkmcnt(" #n ")" ::: "memory")
; #define PG8_BAR __builtin_amdgcn_s_barrier()
; #define PG8_SCHED __builtin_amdgcn_sched_barrier(0)
; template <class Epi, class Sched, bool ALIGN_EPI = false, bool SP2 = false>
; __device__ __forceinline__ void gemm_phase(LAS unsigned char* lds, const Gemm g, const Sched& S, const Epi& E) {
;     ...
;             PG8_LDA(At, 1, 1); PG8_STAGE(PG8_SB(1, 0), b3, voffB); PG8_STAGE(PG8_SB(1, 1), b3 + hstepB, voffB); PG8_STAGE(PG8_SA(1, 0), a3, voffA);
;             PG8_WAIT_V(8); PG8_WAIT_L(0); PG8_BAR; PG8_MMA(1, 0, At, B0); PG8_MMA(1, 1, At, B1); PG8_BAR; PG8_SCHED;
;     ...
;         if constexpr (ALIGN_EPI) { if (wr == 0) PG8_BAR; }
	s_mov_b32 m0, s42
	v_lshl_add_u64 v[208:209], v[208:209], 0, s[10:11]
	s_add_u32 s16, s16, 0x160080
	ds_read_b128 v[176:179], v141 offset:49152
	ds_read_b128 v[180:183], v141 offset:50176
	ds_read_b128 v[184:187], v141 offset:51200
	ds_read_b128 v[188:191], v141 offset:52224
	ds_read_b128 v[192:195], v141 offset:53248
	ds_read_b128 v[196:199], v141 offset:54272
	ds_read_b128 v[200:203], v141 offset:55296
	ds_read_b128 v[204:207], v141 offset:56320
	global_load_lds_dwordx4 v[208:209], off
	v_lshl_add_u64 v[208:209], v[210:211], 0, s[10:11]
	s_mov_b32 m0, s43
	s_addc_u32 s17, s17, 0
	global_load_lds_dwordx4 v[208:209], off
	v_lshl_add_u64 v[208:209], s[16:17], 0, v[132:133]
	s_mov_b32 m0, s44
	s_nop 0
	global_load_lds_dwordx4 v[208:209], off
	v_lshl_add_u64 v[208:209], s[16:17], 0, v[130:131]
	s_mov_b32 m0, s45
	s_nop 0
	global_load_lds_dwordx4 v[208:209], off
	v_lshl_add_u64 v[208:209], v[212:213], 0, s[10:11]
	s_mov_b32 m0, s33
	s_nop 0
	global_load_lds_dwordx4 v[208:209], off
	v_lshl_add_u64 v[208:209], v[214:215], 0, s[10:11]
	s_mov_b32 m0, s34
	s_nop 0
	global_load_lds_dwordx4 v[208:209], off
	s_waitcnt vmcnt(8)
	s_waitcnt lgkmcnt(0)
	s_barrier
	s_setprio 1
	v_mfma_f32_16x16x32_bf16 v[110:113], v[144:147], v[176:179], v[110:113]
	v_mfma_f32_16x16x32_bf16 v[78:81], v[152:155], v[176:179], v[78:81]
	v_mfma_f32_16x16x32_bf16 v[106:109], v[144:147], v[184:187], v[106:109]
	v_mfma_f32_16x16x32_bf16 v[74:77], v[152:155], v[184:187], v[74:77]
	v_mfma_f32_16x16x32_bf16 v[102:105], v[144:147], v[192:195], v[102:105]
	v_mfma_f32_16x16x32_bf16 v[66:69], v[152:155], v[192:195], v[66:69]
	v_mfma_f32_16x16x32_bf16 v[98:101], v[144:147], v[200:203], v[98:101]
	v_mfma_f32_16x16x32_bf16 v[58:61], v[152:155], v[200:203], v[58:61]
	v_mfma_f32_16x16x32_bf16 v[110:113], v[148:151], v[180:183], v[110:113]
	v_mfma_f32_16x16x32_bf16 v[78:81], v[156:159], v[180:183], v[78:81]
	v_mfma_f32_16x16x32_bf16 v[106:109], v[148:151], v[188:191], v[106:109]
	v_mfma_f32_16x16x32_bf16 v[74:77], v[156:159], v[188:191], v[74:77]
	v_mfma_f32_16x16x32_bf16 v[102:105], v[148:151], v[196:199], v[102:105]
	v_mfma_f32_16x16x32_bf16 v[66:69], v[156:159], v[196:199], v[66:69]
	v_mfma_f32_16x16x32_bf16 v[98:101], v[148:151], v[204:207], v[98:101]
	v_mfma_f32_16x16x32_bf16 v[58:61], v[156:159], v[204:207], v[58:61]
	s_setprio 0
	s_setprio 1
	v_mfma_f32_16x16x32_bf16 v[46:49], v[160:163], v[176:179], v[46:49]
	v_mfma_f32_16x16x32_bf16 v[14:17], v[168:171], v[176:179], v[14:17]
	v_mfma_f32_16x16x32_bf16 v[38:41], v[160:163], v[184:187], v[38:41]
	v_mfma_f32_16x16x32_bf16 v[10:13], v[168:171], v[184:187], v[10:13]
	v_mfma_f32_16x16x32_bf16 v[30:33], v[160:163], v[192:195], v[30:33]
	v_mfma_f32_16x16x32_bf16 v[6:9], v[168:171], v[192:195], v[6:9]
	v_mfma_f32_16x16x32_bf16 v[22:25], v[160:163], v[200:203], v[22:25]
	v_mfma_f32_16x16x32_bf16 v[2:5], v[168:171], v[200:203], v[2:5]
	v_mfma_f32_16x16x32_bf16 v[46:49], v[164:167], v[180:183], v[46:49]
	v_mfma_f32_16x16x32_bf16 v[14:17], v[172:175], v[180:183], v[14:17]
	v_mfma_f32_16x16x32_bf16 v[38:41], v[164:167], v[188:191], v[38:41]
	v_mfma_f32_16x16x32_bf16 v[10:13], v[172:175], v[188:191], v[10:13]
	v_mfma_f32_16x16x32_bf16 v[30:33], v[164:167], v[196:199], v[30:33]
	v_mfma_f32_16x16x32_bf16 v[6:9], v[172:175], v[196:199], v[6:9]
	v_mfma_f32_16x16x32_bf16 v[22:25], v[164:167], v[204:207], v[22:25]
	v_mfma_f32_16x16x32_bf16 v[2:5], v[172:175], v[204:207], v[2:5]
	s_setprio 0
	s_barrier
	s_add_u32 s12, s12, 0x100
	s_addc_u32 s13, s13, 0
	s_cmp_ge_u32 s46, s31
	s_mov_b32 s16, s46
	s_cbranch_scc0 .LBB0_1565
	s_cmpk_lt_u32 s21, 0x100
	s_cbranch_scc0 .LBB0_1568
	s_barrier

;     __device__ bool next(int i, Unit& u) const { if (i != 0 || c >= 128) return false; const int t = c >> 2; u.pm = t & 3; u.pn = t >> 2; u.koff = koff_bytes; u.q = c & 3; return true; }
; #define PG8_STAGE(bufoff, gbase, voff) do { _Pragma("unroll") for (int _i = 0; _i < 2; ++_i) \
;         __builtin_amdgcn_global_load_lds((const unsigned*)((const char*)(gbase) + (voff)[_i]), (LAS unsigned*)(lds + (bufoff) + ldsw + _i * 8192), 16, 0, 0); } while (0)
; #define PG8_LDA(dst, b, h) do { _Pragma("unroll") for (int m = 0; m < 4; ++m) _Pragma("unroll") for (int k = 0; k < 2; ++k) dst[m][k] = *(const LAS bf16x8*)(lds + PG8_SA(b, h) + aoff + m * 2048 + k * 1024); } while (0)
; #define PG8_LDB(dst, b, h) do { _Pragma("unroll") for (int n = 0; n < 2; ++n) _Pragma("unroll") for (int k = 0; k < 2; ++k) dst[n][k] = *(const LAS bf16x8*)(lds + PG8_SB(b, h) + boff + n * 2048 + k * 1024); } while (0)
; #define PG8_WAIT_V(n) asm volatile("s_waitcnt vmcnt(" #n ")" ::: "memory")
; template <class Epi, class Sched, bool ALIGN_EPI = false, bool SP2 = false>
; __device__ __forceinline__ void gemm_phase(LAS unsigned char* lds, const Gemm g, const Sched& S, const Epi& E) {
;     ...
;         const bool has_next = S.next(ui + 1, nxt);
;         const char* nA = has_next ? (const char*)g.A + (size_t)nxt.pm * tstep + nxt.koff : cA; const char* nB = has_next ? (const char*)g.Bt + (size_t)nxt.pn * tstep + nxt.koff : cB;
;         for (int t = 0; t < nt; t += 2) {
;             const bool last = (t == nt - 2);
;             const char* a1 = cA + (size_t)(t + 1) * kstep;
;             const char* a2 = last ? nA : cA + (size_t)(t + 2) * kstep; const char* b2 = last ? nB : cB + (size_t)(t + 2) * kstep;
;             const char* a3 = a2 + kstep; const char* b3 = b2 + kstep;
;             if (last && has_next) S.a_ready(nxt);
;             if constexpr (SP2) {
;             PG8_LDB(B0, 0, 0); PG8_LDB(B1, 0, 1); PG8_SCHED; PG8_LDA(At, 0, 0); PG8_STAGE(PG8_SA(1, 1), a1 + hstep, voffA);
;             PG8_WAIT_V(8); PG8_WAIT_L(0); PG8_BAR; PG8_MMA(0, 0, At, B0); PG8_MMA(0, 1, At, B1); PG8_BAR; PG8_SCHED;
;             PG8_LDA(At, 0, 1); PG8_STAGE(PG8_SB(0, 0), b2, voffB); PG8_STAGE(PG8_SB(0, 1), b2 + hstepB, voffB); PG8_STAGE(PG8_SA(0, 0), a2, voffA);
;             PG8_WAIT_V(8); PG8_WAIT_L(0); PG8_BAR; PG8_MMA(1, 0, At, B0); PG8_MMA(1, 1, At, B1); PG8_BAR; PG8_SCHED;
.Lprio_1595:
	ds_read_b128 v[130:133], v196
	ds_read_b128 v[134:137], v196 offset:1024
	ds_read_b128 v[138:141], v196 offset:2048
	ds_read_b128 v[142:145], v196 offset:3072
	ds_read_b128 v[166:169], v197
	ds_read_b128 v[170:173], v197 offset:1024
	ds_read_b128 v[174:177], v197 offset:2048
	ds_read_b128 v[178:181], v197 offset:3072
	s_add_u32 s20, s16, 0x100
	s_addc_u32 s21, s17, 0
	s_cmpk_eq_i32 s25, 0x54
	s_cselect_b32 s47, s3, s21
	s_cselect_b32 s46, s2, s20
	s_cselect_b32 s23, s19, s24
	s_cselect_b32 s22, s18, s9
	v_lshl_add_u64 v[190:191], s[16:17], 0, v[158:159]
	s_add_i32 m0, s31, 0xc000
	ds_read_b128 v[182:185], v198
	ds_read_b128 v[186:189], v198 offset:1024
	ds_read_b128 v[202:205], v198 offset:2048
	ds_read_b128 v[206:209], v198 offset:3072
	ds_read_b128 v[210:213], v198 offset:4096
	ds_read_b128 v[214:217], v198 offset:5120
	ds_read_b128 v[218:221], v198 offset:6144
	ds_read_b128 v[222:225], v198 offset:7168
	global_load_lds_dwordx4 v[190:191], off
	v_lshl_add_u64 v[190:191], s[16:17], 0, v[160:161]
	s_add_i32 m0, s31, 0xe000
	s_nop 0
	global_load_lds_dwordx4 v[190:191], off
	s_waitcnt lgkmcnt(0)
	s_barrier
	v_mfma_f32_16x16x32_bf16 v[126:129], v[130:133], v[182:185], 0
	v_mfma_f32_16x16x32_bf16 v[122:125], v[138:141], v[182:185], 0
	v_mfma_f32_16x16x32_bf16 v[110:113], v[130:133], v[202:205], 0
	v_mfma_f32_16x16x32_bf16 v[106:109], v[138:141], v[202:205], 0
	v_mfma_f32_16x16x32_bf16 v[94:97], v[130:133], v[210:213], 0
	v_mfma_f32_16x16x32_bf16 v[90:93], v[138:141], v[210:213], 0
	v_mfma_f32_16x16x32_bf16 v[78:81], v[130:133], v[218:221], 0
	v_mfma_f32_16x16x32_bf16 v[74:77], v[138:141], v[218:221], 0
	v_mfma_f32_16x16x32_bf16 v[126:129], v[134:137], v[186:189], v[126:129]
	v_mfma_f32_16x16x32_bf16 v[122:125], v[142:145], v[186:189], v[122:125]
	v_mfma_f32_16x16x32_bf16 v[110:113], v[134:137], v[206:209], v[110:113]
	v_mfma_f32_16x16x32_bf16 v[106:109], v[142:145], v[206:209], v[106:109]
	v_mfma_f32_16x16x32_bf16 v[94:97], v[134:137], v[214:217], v[94:97]
	v_mfma_f32_16x16x32_bf16 v[90:93], v[142:145], v[214:217], v[90:93]
	v_mfma_f32_16x16x32_bf16 v[78:81], v[134:137], v[222:225], v[78:81]
	v_mfma_f32_16x16x32_bf16 v[74:77], v[142:145], v[222:225], v[74:77]
	v_mfma_f32_16x16x32_bf16 v[118:121], v[166:169], v[182:185], 0
	v_mfma_f32_16x16x32_bf16 v[114:117], v[174:177], v[182:185], 0
	v_mfma_f32_16x16x32_bf16 v[102:105], v[166:169], v[202:205], 0
	v_mfma_f32_16x16x32_bf16 v[98:101], v[174:177], v[202:205], 0
	v_mfma_f32_16x16x32_bf16 v[86:89], v[166:169], v[210:213], 0
	v_mfma_f32_16x16x32_bf16 v[82:85], v[174:177], v[210:213], 0
	v_mfma_f32_16x16x32_bf16 v[70:73], v[166:169], v[218:221], 0
	v_mfma_f32_16x16x32_bf16 v[66:69], v[174:177], v[218:221], 0
	v_mfma_f32_16x16x32_bf16 v[118:121], v[170:173], v[186:189], v[118:121]
	v_mfma_f32_16x16x32_bf16 v[114:117], v[178:181], v[186:189], v[114:117]
	v_mfma_f32_16x16x32_bf16 v[102:105], v[170:173], v[206:209], v[102:105]
	v_mfma_f32_16x16x32_bf16 v[98:101], v[178:181], v[206:209], v[98:101]
	v_mfma_f32_16x16x32_bf16 v[86:89], v[170:173], v[214:217], v[86:89]
	v_mfma_f32_16x16x32_bf16 v[82:85], v[178:181], v[214:217], v[82:85]
	v_mfma_f32_16x16x32_bf16 v[70:73], v[170:173], v[222:225], v[70:73]
	v_mfma_f32_16x16x32_bf16 v[66:69], v[178:181], v[222:225], v[66:69]
	s_barrier
	s_add_i32 s16, s52, s30
	v_lshl_add_u64 v[190:191], s[22:23], 0, v[148:149]
	s_mov_b32 m0, s16
	ds_read_b128 v[182:185], v198 offset:16384
	ds_read_b128 v[186:189], v198 offset:17408
	ds_read_b128 v[202:205], v198 offset:18432
	ds_read_b128 v[206:209], v198 offset:19456
	ds_read_b128 v[210:213], v198 offset:20480
	ds_read_b128 v[214:217], v198 offset:21504
	ds_read_b128 v[218:221], v198 offset:22528
	ds_read_b128 v[222:225], v198 offset:23552
	global_load_lds_dwordx4 v[190:191], off
	s_add_i32 m0, s16, 0x2000
	s_add_u32 s16, s22, 0x58000
	v_lshl_add_u64 v[226:227], s[22:23], 0, v[152:153]
	s_addc_u32 s17, s23, 0
	s_add_i32 s56, s53, s30
	global_load_lds_dwordx4 v[226:227], off
	v_lshl_add_u64 v[228:229], s[16:17], 0, v[148:149]
	s_mov_b32 m0, s56
	v_lshl_add_u64 v[230:231], s[46:47], 0, v[150:151]
	global_load_lds_dwordx4 v[228:229], off
	v_lshl_add_u64 v[228:229], s[16:17], 0, v[152:153]
	s_add_i32 m0, s56, 0x2000
	s_nop 0
	global_load_lds_dwordx4 v[228:229], off
	v_lshl_add_u64 v[228:229], s[46:47], 0, v[146:147]
	s_mov_b32 m0, s31
	s_nop 0
	global_load_lds_dwordx4 v[228:229], off
	s_mov_b32 m0, s33
	s_nop 0
	global_load_lds_dwordx4 v[230:231], off
	s_waitcnt lgkmcnt(0)
	s_barrier
	v_mfma_f32_16x16x32_bf16 v[62:65], v[130:133], v[182:185], 0
	v_mfma_f32_16x16x32_bf16 v[58:61], v[138:141], v[182:185], 0
	v_mfma_f32_16x16x32_bf16 v[46:49], v[130:133], v[202:205], 0
	v_mfma_f32_16x16x32_bf16 v[42:45], v[138:141], v[202:205], 0
	v_mfma_f32_16x16x32_bf16 v[30:33], v[130:133], v[210:213], 0
	v_mfma_f32_16x16x32_bf16 v[26:29], v[138:141], v[210:213], 0
	v_mfma_f32_16x16x32_bf16 v[14:17], v[130:133], v[218:221], 0
	v_mfma_f32_16x16x32_bf16 v[10:13], v[138:141], v[218:221], 0
	v_mfma_f32_16x16x32_bf16 v[62:65], v[134:137], v[186:189], v[62:65]
	v_mfma_f32_16x16x32_bf16 v[58:61], v[142:145], v[186:189], v[58:61]
	v_mfma_f32_16x16x32_bf16 v[46:49], v[134:137], v[206:209], v[46:49]
	v_mfma_f32_16x16x32_bf16 v[42:45], v[142:145], v[206:209], v[42:45]
	v_mfma_f32_16x16x32_bf16 v[30:33], v[134:137], v[214:217], v[30:33]
	v_mfma_f32_16x16x32_bf16 v[26:29], v[142:145], v[214:217], v[26:29]
	v_mfma_f32_16x16x32_bf16 v[14:17], v[134:137], v[222:225], v[14:17]
	v_mfma_f32_16x16x32_bf16 v[10:13], v[142:145], v[222:225], v[10:13]
	v_mfma_f32_16x16x32_bf16 v[54:57], v[166:169], v[182:185], 0
	v_mfma_f32_16x16x32_bf16 v[50:53], v[174:177], v[182:185], 0
	v_mfma_f32_16x16x32_bf16 v[38:41], v[166:169], v[202:205], 0
	v_mfma_f32_16x16x32_bf16 v[34:37], v[174:177], v[202:205], 0
	v_mfma_f32_16x16x32_bf16 v[22:25], v[166:169], v[210:213], 0
	v_mfma_f32_16x16x32_bf16 v[18:21], v[174:177], v[210:213], 0
	v_mfma_f32_16x16x32_bf16 v[6:9], v[166:169], v[218:221], 0
	v_mfma_f32_16x16x32_bf16 v[2:5], v[174:177], v[218:221], 0
	v_mfma_f32_16x16x32_bf16 v[54:57], v[170:173], v[186:189], v[54:57]
	v_mfma_f32_16x16x32_bf16 v[50:53], v[178:181], v[186:189], v[50:53]
	v_mfma_f32_16x16x32_bf16 v[38:41], v[170:173], v[206:209], v[38:41]
	v_mfma_f32_16x16x32_bf16 v[34:37], v[178:181], v[206:209], v[34:37]
	v_mfma_f32_16x16x32_bf16 v[22:25], v[170:173], v[214:217], v[22:25]
	v_mfma_f32_16x16x32_bf16 v[18:21], v[178:181], v[214:217], v[18:21]
	v_mfma_f32_16x16x32_bf16 v[6:9], v[170:173], v[222:225], v[6:9]
	v_mfma_f32_16x16x32_bf16 v[2:5], v[178:181], v[222:225], v[2:5]
	s_barrier
; #define PG8_STAGE(bufoff, gbase, voff) do { _Pragma("unroll") for (int _i = 0; _i < 2; ++_i) \
;         __builtin_amdgcn_global_load_lds((const unsigned*)((const char*)(gbase) + (voff)[_i]), (LAS unsigned*)(lds + (bufoff) + ldsw + _i * 8192), 16, 0, 0); } while (0)
; #define PG8_LDA(dst, b, h) do { _Pragma("unroll") for (int m = 0; m < 4; ++m) _Pragma("unroll") for (int k = 0; k < 2; ++k) dst[m][k] = *(const LAS bf16x8*)(lds + PG8_SA(b, h) + aoff + m * 2048 + k * 1024); } while (0)
; #define PG8_LDB(dst, b, h) do { _Pragma("unroll") for (int n = 0; n < 2; ++n) _Pragma("unroll") for (int k = 0; k < 2; ++k) dst[n][k] = *(const LAS bf16x8*)(lds + PG8_SB(b, h) + boff + n * 2048 + k * 1024); } while (0)
; #define PG8_MMA(ai, bj, At, Bt) do { __builtin_amdgcn_s_setprio(1); _Pragma("unroll") for (int m = 0; m < 4; ++m) _Pragma("unroll") for (int n = 0; n < 2; ++n) _Pragma("unroll") for (int k = 0; k < 2; ++k) \
;         acc[ai][bj][m][n] = __builtin_amdgcn_mfma_f32_16x16x32_bf16(Bt[n][k], At[m][k], acc[ai][bj][m][n], 0, 0, 0); __builtin_amdgcn_s_setprio(0); } while (0)
; #define PG8_WAIT_V(n) asm volatile("s_waitcnt vmcnt(" #n ")" ::: "memory")
; #define PG8_WAIT_L(n) asm volatile("s_waitcnt lgkmcnt(" #n ")" ::: "memory")
; #define PG8_BAR __builtin_amdgcn_s_barrier()
; #define PG8_SCHED __builtin_amdgcn_sched_barrier(0)
; template <class Epi, class Sched, bool ALIGN_EPI = false, bool SP2 = false>
; __device__ __forceinline__ void gemm_phase(LAS unsigned char* lds, const Gemm g, const Sched& S, const Epi& E) {
;     ...
;             PG8_LDB(B0, 1, 0); PG8_LDB(B1, 1, 1); PG8_SCHED; PG8_LDA(At, 1, 0); PG8_STAGE(PG8_SA(0, 1), a2 + hstep, voffA);
;             PG8_WAIT_V(8); PG8_WAIT_L(0); PG8_BAR; PG8_MMA(0, 0, At, B0); PG8_MMA(0, 1, At, B1); PG8_BAR; PG8_SCHED;
;             PG8_LDA(At, 1, 1); PG8_STAGE(PG8_SB(1, 0), b3, voffB); PG8_STAGE(PG8_SB(1, 1), b3 + hstepB, voffB); PG8_STAGE(PG8_SA(1, 0), a3, voffA);
;             PG8_WAIT_V(8); PG8_WAIT_L(0); PG8_BAR; PG8_MMA(1, 0, At, B0); PG8_MMA(1, 1, At, B1); PG8_BAR; PG8_SCHED;
	s_add_i32 s56, 0, 0x18000
	s_add_i32 s57, 0, 0x1c000
	v_add_u32_e32 v142, s56, v1
	v_add_u32_e32 v154, s57, v1
	ds_read_b128 v[130:133], v142
	ds_read_b128 v[134:137], v142 offset:1024
	ds_read_b128 v[138:141], v142 offset:2048
	ds_read_b128 v[142:145], v142 offset:3072
	ds_read_b128 v[166:169], v154
	ds_read_b128 v[170:173], v154 offset:1024
	ds_read_b128 v[174:177], v154 offset:2048
	ds_read_b128 v[178:181], v154 offset:3072
	s_add_u32 s16, s46, 0x160000
	s_addc_u32 s17, s47, 0
	s_mov_b32 m0, s34
	v_lshl_add_u64 v[232:233], s[16:17], 0, v[146:147]
	ds_read_b128 v[182:185], v198 offset:32768
	ds_read_b128 v[186:189], v198 offset:33792
	ds_read_b128 v[202:205], v198 offset:34816
	ds_read_b128 v[206:209], v198 offset:35840
	ds_read_b128 v[210:213], v198 offset:36864
	ds_read_b128 v[214:217], v198 offset:37888
	ds_read_b128 v[218:221], v198 offset:38912
	ds_read_b128 v[222:225], v198 offset:39936
	global_load_lds_dwordx4 v[232:233], off
	v_lshl_add_u64 v[232:233], s[16:17], 0, v[150:151]
	s_mov_b32 m0, s35
	s_nop 0
	global_load_lds_dwordx4 v[232:233], off
	s_waitcnt vmcnt(8)
	s_waitcnt lgkmcnt(0)
	s_barrier
	v_mfma_f32_16x16x32_bf16 v[126:129], v[130:133], v[182:185], v[126:129]
	v_mfma_f32_16x16x32_bf16 v[122:125], v[138:141], v[182:185], v[122:125]
	v_mfma_f32_16x16x32_bf16 v[110:113], v[130:133], v[202:205], v[110:113]
	v_mfma_f32_16x16x32_bf16 v[106:109], v[138:141], v[202:205], v[106:109]
	v_mfma_f32_16x16x32_bf16 v[94:97], v[130:133], v[210:213], v[94:97]
	v_mfma_f32_16x16x32_bf16 v[90:93], v[138:141], v[210:213], v[90:93]
	v_mfma_f32_16x16x32_bf16 v[78:81], v[130:133], v[218:221], v[78:81]
	v_mfma_f32_16x16x32_bf16 v[74:77], v[138:141], v[218:221], v[74:77]
	v_mfma_f32_16x16x32_bf16 v[126:129], v[134:137], v[186:189], v[126:129]
	v_mfma_f32_16x16x32_bf16 v[122:125], v[142:145], v[186:189], v[122:125]
	v_mfma_f32_16x16x32_bf16 v[110:113], v[134:137], v[206:209], v[110:113]
	v_mfma_f32_16x16x32_bf16 v[106:109], v[142:145], v[206:209], v[106:109]
	v_mfma_f32_16x16x32_bf16 v[94:97], v[134:137], v[214:217], v[94:97]
	v_mfma_f32_16x16x32_bf16 v[90:93], v[142:145], v[214:217], v[90:93]
	v_mfma_f32_16x16x32_bf16 v[78:81], v[134:137], v[222:225], v[78:81]
	v_mfma_f32_16x16x32_bf16 v[74:77], v[142:145], v[222:225], v[74:77]
	v_mfma_f32_16x16x32_bf16 v[118:121], v[166:169], v[182:185], v[118:121]
	v_mfma_f32_16x16x32_bf16 v[114:117], v[174:177], v[182:185], v[114:117]
	v_mfma_f32_16x16x32_bf16 v[102:105], v[166:169], v[202:205], v[102:105]
	v_mfma_f32_16x16x32_bf16 v[98:101], v[174:177], v[202:205], v[98:101]
	v_mfma_f32_16x16x32_bf16 v[86:89], v[166:169], v[210:213], v[86:89]
	v_mfma_f32_16x16x32_bf16 v[82:85], v[174:177], v[210:213], v[82:85]
	v_mfma_f32_16x16x32_bf16 v[70:73], v[166:169], v[218:221], v[70:73]
	v_mfma_f32_16x16x32_bf16 v[66:69], v[174:177], v[218:221], v[66:69]
	v_mfma_f32_16x16x32_bf16 v[118:121], v[170:173], v[186:189], v[118:121]
	v_mfma_f32_16x16x32_bf16 v[114:117], v[178:181], v[186:189], v[114:117]
	v_mfma_f32_16x16x32_bf16 v[102:105], v[170:173], v[206:209], v[102:105]
	v_mfma_f32_16x16x32_bf16 v[98:101], v[178:181], v[206:209], v[98:101]
	v_mfma_f32_16x16x32_bf16 v[86:89], v[170:173], v[214:217], v[86:89]
	v_mfma_f32_16x16x32_bf16 v[82:85], v[178:181], v[214:217], v[82:85]
	v_mfma_f32_16x16x32_bf16 v[70:73], v[170:173], v[222:225], v[70:73]
	v_mfma_f32_16x16x32_bf16 v[66:69], v[178:181], v[222:225], v[66:69]
	s_barrier
	s_add_i32 s16, s56, s30
	v_lshl_add_u64 v[190:191], v[190:191], 0, s[12:13]
	s_mov_b32 m0, s16
	ds_read_b128 v[182:185], v198 offset:49152
	ds_read_b128 v[186:189], v198 offset:50176
	ds_read_b128 v[202:205], v198 offset:51200
	ds_read_b128 v[206:209], v198 offset:52224
	ds_read_b128 v[210:213], v198 offset:53248
	ds_read_b128 v[214:217], v198 offset:54272
	ds_read_b128 v[218:221], v198 offset:55296
	ds_read_b128 v[222:225], v198 offset:56320
	global_load_lds_dwordx4 v[190:191], off
	s_add_i32 m0, s16, 0x2000
	s_add_u32 s16, s22, 0x58080
	v_lshl_add_u64 v[190:191], v[226:227], 0, s[12:13]
	s_addc_u32 s17, s23, 0
	s_add_i32 s22, s57, s30
	global_load_lds_dwordx4 v[190:191], off
	v_lshl_add_u64 v[190:191], s[16:17], 0, v[148:149]
	s_mov_b32 m0, s22
	s_nop 0
	global_load_lds_dwordx4 v[190:191], off
	v_lshl_add_u64 v[190:191], s[16:17], 0, v[152:153]
	s_add_i32 m0, s22, 0x2000
	s_nop 0
	global_load_lds_dwordx4 v[190:191], off
	v_lshl_add_u64 v[190:191], v[228:229], 0, s[12:13]
	s_mov_b32 m0, s49
	s_nop 0
	global_load_lds_dwordx4 v[190:191], off
	v_lshl_add_u64 v[190:191], v[230:231], 0, s[12:13]
	s_mov_b32 m0, s50
	s_nop 0
	global_load_lds_dwordx4 v[190:191], off
	s_waitcnt vmcnt(8)
	s_waitcnt lgkmcnt(0)
	s_barrier
	v_mfma_f32_16x16x32_bf16 v[62:65], v[130:133], v[182:185], v[62:65]
	v_mfma_f32_16x16x32_bf16 v[58:61], v[138:141], v[182:185], v[58:61]
	v_mfma_f32_16x16x32_bf16 v[46:49], v[130:133], v[202:205], v[46:49]
	v_mfma_f32_16x16x32_bf16 v[42:45], v[138:141], v[202:205], v[42:45]
	v_mfma_f32_16x16x32_bf16 v[30:33], v[130:133], v[210:213], v[30:33]
	v_mfma_f32_16x16x32_bf16 v[26:29], v[138:141], v[210:213], v[26:29]
	v_mfma_f32_16x16x32_bf16 v[14:17], v[130:133], v[218:221], v[14:17]
	v_mfma_f32_16x16x32_bf16 v[10:13], v[138:141], v[218:221], v[10:13]
	v_mfma_f32_16x16x32_bf16 v[62:65], v[134:137], v[186:189], v[62:65]
	v_mfma_f32_16x16x32_bf16 v[58:61], v[142:145], v[186:189], v[58:61]
	v_mfma_f32_16x16x32_bf16 v[46:49], v[134:137], v[206:209], v[46:49]
	v_mfma_f32_16x16x32_bf16 v[42:45], v[142:145], v[206:209], v[42:45]
	v_mfma_f32_16x16x32_bf16 v[30:33], v[134:137], v[214:217], v[30:33]
	v_mfma_f32_16x16x32_bf16 v[26:29], v[142:145], v[214:217], v[26:29]
	v_mfma_f32_16x16x32_bf16 v[14:17], v[134:137], v[222:225], v[14:17]
	v_mfma_f32_16x16x32_bf16 v[10:13], v[142:145], v[222:225], v[10:13]
	v_mfma_f32_16x16x32_bf16 v[54:57], v[166:169], v[182:185], v[54:57]
	v_mfma_f32_16x16x32_bf16 v[50:53], v[174:177], v[182:185], v[50:53]
	v_mfma_f32_16x16x32_bf16 v[38:41], v[166:169], v[202:205], v[38:41]
	v_mfma_f32_16x16x32_bf16 v[34:37], v[174:177], v[202:205], v[34:37]
	v_mfma_f32_16x16x32_bf16 v[22:25], v[166:169], v[210:213], v[22:25]
	v_mfma_f32_16x16x32_bf16 v[18:21], v[174:177], v[210:213], v[18:21]
	v_mfma_f32_16x16x32_bf16 v[6:9], v[166:169], v[218:221], v[6:9]
	v_mfma_f32_16x16x32_bf16 v[2:5], v[174:177], v[218:221], v[2:5]
	v_mfma_f32_16x16x32_bf16 v[54:57], v[170:173], v[186:189], v[54:57]
	v_mfma_f32_16x16x32_bf16 v[50:53], v[178:181], v[186:189], v[50:53]
	v_mfma_f32_16x16x32_bf16 v[38:41], v[170:173], v[206:209], v[38:41]
	v_mfma_f32_16x16x32_bf16 v[34:37], v[178:181], v[206:209], v[34:37]
	v_mfma_f32_16x16x32_bf16 v[22:25], v[170:173], v[214:217], v[22:25]
	v_mfma_f32_16x16x32_bf16 v[18:21], v[178:181], v[214:217], v[18:21]
	v_mfma_f32_16x16x32_bf16 v[6:9], v[170:173], v[222:225], v[6:9]
	v_mfma_f32_16x16x32_bf16 v[2:5], v[178:181], v[222:225], v[2:5]
	s_barrier
	s_add_i32 s25, s25, 2
	s_add_u32 s9, s9, 0x100
	s_addc_u32 s24, s24, 0
	s_cmpk_gt_u32 s25, 0x55
	s_mov_b64 s[16:17], s[20:21]
; #define PG8_STAGE(bufoff, gbase, voff) do { _Pragma("unroll") for (int _i = 0; _i < 2; ++_i) \
;         __builtin_amdgcn_global_load_lds((const unsigned*)((const char*)(gbase) + (voff)[_i]), (LAS unsigned*)(lds + (bufoff) + ldsw + _i * 8192), 16, 0, 0); } while (0)
; #define PG8_LDA(dst, b, h) do { _Pragma("unroll") for (int m = 0; m < 4; ++m) _Pragma("unroll") for (int k = 0; k < 2; ++k) dst[m][k] = *(const LAS bf16x8*)(lds + PG8_SA(b, h) + aoff + m * 2048 + k * 1024); } while (0)
; #define PG8_LDB(dst, b, h) do { _Pragma("unroll") for (int n = 0; n < 2; ++n) _Pragma("unroll") for (int k = 0; k < 2; ++k) dst[n][k] = *(const LAS bf16x8*)(lds + PG8_SB(b, h) + boff + n * 2048 + k * 1024); } while (0)
; #define PG8_MMA(ai, bj, At, Bt) do { __builtin_amdgcn_s_setprio(1); _Pragma("unroll") for (int m = 0; m < 4; ++m) _Pragma("unroll") for (int n = 0; n < 2; ++n) _Pragma("unroll") for (int k = 0; k < 2; ++k) \
;         acc[ai][bj][m][n] = __builtin_amdgcn_mfma_f32_16x16x32_bf16(Bt[n][k], At[m][k], acc[ai][bj][m][n], 0, 0, 0); __builtin_amdgcn_s_setprio(0); } while (0)
; #define PG8_WAIT_V(n) asm volatile("s_waitcnt vmcnt(" #n ")" ::: "memory")
; #define PG8_WAIT_L(n) asm volatile("s_waitcnt lgkmcnt(" #n ")" ::: "memory")
; #define PG8_BAR __builtin_amdgcn_s_barrier()
; template <class Epi, class Sched, bool ALIGN_EPI = false, bool SP2 = false>
; __device__ __forceinline__ void gemm_phase(LAS unsigned char* lds, const Gemm g, const Sched& S, const Epi& E) {
;     ...
;             const bool last = (t == nt - 2);
;             const char* a1 = cA + (size_t)(t + 1) * kstep;
;             const char* a2 = last ? nA : cA + (size_t)(t + 2) * kstep; const char* b2 = last ? nB : cB + (size_t)(t + 2) * kstep;
;             const char* a3 = a2 + kstep; const char* b3 = b2 + kstep;
;             if (last && has_next) S.a_ready(nxt);
;             if constexpr (SP2) {
;             PG8_LDB(B0, 0, 0); PG8_LDB(B1, 0, 1); PG8_SCHED; PG8_LDA(At, 0, 0); PG8_STAGE(PG8_SA(1, 1), a1 + hstep, voffA);
;             PG8_WAIT_V(8); PG8_WAIT_L(0); PG8_BAR; PG8_MMA(0, 0, At, B0); PG8_MMA(0, 1, At, B1); PG8_BAR; PG8_SCHED;
;             PG8_LDA(At, 0, 1); PG8_STAGE(PG8_SB(0, 0), b2, voffB); PG8_STAGE(PG8_SB(0, 1), b2 + hstepB, voffB); PG8_STAGE(PG8_SA(0, 0), a2, voffA);
;             PG8_WAIT_V(8); PG8_WAIT_L(0); PG8_BAR; PG8_MMA(1, 0, At, B0); PG8_MMA(1, 1, At, B1); PG8_BAR; PG8_SCHED;
.LBB0_1595:
	ds_read_b128 v[130:133], v196
	ds_read_b128 v[134:137], v196 offset:1024
	ds_read_b128 v[138:141], v196 offset:2048
	ds_read_b128 v[142:145], v196 offset:3072
	ds_read_b128 v[166:169], v197
	ds_read_b128 v[170:173], v197 offset:1024
	ds_read_b128 v[174:177], v197 offset:2048
	ds_read_b128 v[178:181], v197 offset:3072
	s_add_u32 s20, s16, 0x100
	s_addc_u32 s21, s17, 0
	s_cmpk_eq_i32 s25, 0x54
	s_cselect_b32 s47, s3, s21
	s_cselect_b32 s46, s2, s20
	s_cselect_b32 s23, s19, s24
	s_cselect_b32 s22, s18, s9
	v_lshl_add_u64 v[190:191], s[16:17], 0, v[158:159]
	s_add_i32 m0, s31, 0xc000
	ds_read_b128 v[182:185], v198
	ds_read_b128 v[186:189], v198 offset:1024
	ds_read_b128 v[202:205], v198 offset:2048
	ds_read_b128 v[206:209], v198 offset:3072
	ds_read_b128 v[210:213], v198 offset:4096
	ds_read_b128 v[214:217], v198 offset:5120
	ds_read_b128 v[218:221], v198 offset:6144
	ds_read_b128 v[222:225], v198 offset:7168
	global_load_lds_dwordx4 v[190:191], off
	v_lshl_add_u64 v[190:191], s[16:17], 0, v[160:161]
	s_add_i32 m0, s31, 0xe000
	s_nop 0
	global_load_lds_dwordx4 v[190:191], off
	s_waitcnt vmcnt(8)
	s_waitcnt lgkmcnt(0)
	s_barrier
	v_mfma_f32_16x16x32_bf16 v[126:129], v[130:133], v[182:185], v[126:129]
	v_mfma_f32_16x16x32_bf16 v[122:125], v[138:141], v[182:185], v[122:125]
	v_mfma_f32_16x16x32_bf16 v[110:113], v[130:133], v[202:205], v[110:113]
	v_mfma_f32_16x16x32_bf16 v[106:109], v[138:141], v[202:205], v[106:109]
	v_mfma_f32_16x16x32_bf16 v[94:97], v[130:133], v[210:213], v[94:97]
	v_mfma_f32_16x16x32_bf16 v[90:93], v[138:141], v[210:213], v[90:93]
	v_mfma_f32_16x16x32_bf16 v[78:81], v[130:133], v[218:221], v[78:81]
	v_mfma_f32_16x16x32_bf16 v[74:77], v[138:141], v[218:221], v[74:77]
	v_mfma_f32_16x16x32_bf16 v[126:129], v[134:137], v[186:189], v[126:129]
	v_mfma_f32_16x16x32_bf16 v[122:125], v[142:145], v[186:189], v[122:125]
	v_mfma_f32_16x16x32_bf16 v[110:113], v[134:137], v[206:209], v[110:113]
	v_mfma_f32_16x16x32_bf16 v[106:109], v[142:145], v[206:209], v[106:109]
	v_mfma_f32_16x16x32_bf16 v[94:97], v[134:137], v[214:217], v[94:97]
	v_mfma_f32_16x16x32_bf16 v[90:93], v[142:145], v[214:217], v[90:93]
	v_mfma_f32_16x16x32_bf16 v[78:81], v[134:137], v[222:225], v[78:81]
	v_mfma_f32_16x16x32_bf16 v[74:77], v[142:145], v[222:225], v[74:77]
	v_mfma_f32_16x16x32_bf16 v[118:121], v[166:169], v[182:185], v[118:121]
	v_mfma_f32_16x16x32_bf16 v[114:117], v[174:177], v[182:185], v[114:117]
	v_mfma_f32_16x16x32_bf16 v[102:105], v[166:169], v[202:205], v[102:105]
	v_mfma_f32_16x16x32_bf16 v[98:101], v[174:177], v[202:205], v[98:101]
	v_mfma_f32_16x16x32_bf16 v[86:89], v[166:169], v[210:213], v[86:89]
	v_mfma_f32_16x16x32_bf16 v[82:85], v[174:177], v[210:213], v[82:85]
	v_mfma_f32_16x16x32_bf16 v[70:73], v[166:169], v[218:221], v[70:73]
	v_mfma_f32_16x16x32_bf16 v[66:69], v[174:177], v[218:221], v[66:69]
	v_mfma_f32_16x16x32_bf16 v[118:121], v[170:173], v[186:189], v[118:121]
	v_mfma_f32_16x16x32_bf16 v[114:117], v[178:181], v[186:189], v[114:117]
	v_mfma_f32_16x16x32_bf16 v[102:105], v[170:173], v[206:209], v[102:105]
	v_mfma_f32_16x16x32_bf16 v[98:101], v[178:181], v[206:209], v[98:101]
	v_mfma_f32_16x16x32_bf16 v[86:89], v[170:173], v[214:217], v[86:89]
	v_mfma_f32_16x16x32_bf16 v[82:85], v[178:181], v[214:217], v[82:85]
	v_mfma_f32_16x16x32_bf16 v[70:73], v[170:173], v[222:225], v[70:73]
	v_mfma_f32_16x16x32_bf16 v[66:69], v[178:181], v[222:225], v[66:69]
	s_barrier
	s_add_i32 s16, s52, s30
	v_lshl_add_u64 v[190:191], s[22:23], 0, v[148:149]
	s_mov_b32 m0, s16
	ds_read_b128 v[182:185], v198 offset:16384
	ds_read_b128 v[186:189], v198 offset:17408
	ds_read_b128 v[202:205], v198 offset:18432
	ds_read_b128 v[206:209], v198 offset:19456
	ds_read_b128 v[210:213], v198 offset:20480
	ds_read_b128 v[214:217], v198 offset:21504
	ds_read_b128 v[218:221], v198 offset:22528
	ds_read_b128 v[222:225], v198 offset:23552
	global_load_lds_dwordx4 v[190:191], off
	s_add_i32 m0, s16, 0x2000
	s_add_u32 s16, s22, 0x58000
	v_lshl_add_u64 v[226:227], s[22:23], 0, v[152:153]
	s_addc_u32 s17, s23, 0
	s_add_i32 s56, s53, s30
	global_load_lds_dwordx4 v[226:227], off
	v_lshl_add_u64 v[228:229], s[16:17], 0, v[148:149]
	s_mov_b32 m0, s56
	v_lshl_add_u64 v[230:231], s[46:47], 0, v[150:151]
	global_load_lds_dwordx4 v[228:229], off
	v_lshl_add_u64 v[228:229], s[16:17], 0, v[152:153]
	s_add_i32 m0, s56, 0x2000
	s_nop 0
	global_load_lds_dwordx4 v[228:229], off
	v_lshl_add_u64 v[228:229], s[46:47], 0, v[146:147]
	s_mov_b32 m0, s31
	s_nop 0
	global_load_lds_dwordx4 v[228:229], off
	s_mov_b32 m0, s33
	s_nop 0
	global_load_lds_dwordx4 v[230:231], off
	s_waitcnt vmcnt(8)
	s_waitcnt lgkmcnt(0)
	s_barrier
; #define PG8_STAGE(bufoff, gbase, voff) do { _Pragma("unroll") for (int _i = 0; _i < 2; ++_i) \
;         __builtin_amdgcn_global_load_lds((const unsigned*)((const char*)(gbase) + (voff)[_i]), (LAS unsigned*)(lds + (bufoff) + ldsw + _i * 8192), 16, 0, 0); } while (0)
; #define PG8_LDA(dst, b, h) do { _Pragma("unroll") for (int m = 0; m < 4; ++m) _Pragma("unroll") for (int k = 0; k < 2; ++k) dst[m][k] = *(const LAS bf16x8*)(lds + PG8_SA(b, h) + aoff + m * 2048 + k * 1024); } while (0)
; #define PG8_LDB(dst, b, h) do { _Pragma("unroll") for (int n = 0; n < 2; ++n) _Pragma("unroll") for (int k = 0; k < 2; ++k) dst[n][k] = *(const LAS bf16x8*)(lds + PG8_SB(b, h) + boff + n * 2048 + k * 1024); } while (0)
; #define PG8_MMA(ai, bj, At, Bt) do { __builtin_amdgcn_s_setprio(1); _Pragma("unroll") for (int m = 0; m < 4; ++m) _Pragma("unroll") for (int n = 0; n < 2; ++n) _Pragma("unroll") for (int k = 0; k < 2; ++k) \
;         acc[ai][bj][m][n] = __builtin_amdgcn_mfma_f32_16x16x32_bf16(Bt[n][k], At[m][k], acc[ai][bj][m][n], 0, 0, 0); __builtin_amdgcn_s_setprio(0); } while (0)
; #define PG8_WAIT_V(n) asm volatile("s_waitcnt vmcnt(" #n ")" ::: "memory")
; #define PG8_WAIT_L(n) asm volatile("s_waitcnt lgkmcnt(" #n ")" ::: "memory")
; #define PG8_BAR __builtin_amdgcn_s_barrier()
; #define PG8_SCHED __builtin_amdgcn_sched_barrier(0)
; template <class Epi, class Sched, bool ALIGN_EPI = false, bool SP2 = false>
; __device__ __forceinline__ void gemm_phase(LAS unsigned char* lds, const Gemm g, const Sched& S, const Epi& E) {
;     ...
;             PG8_WAIT_V(8); PG8_WAIT_L(0); PG8_BAR; PG8_MMA(1, 0, At, B0); PG8_MMA(1, 1, At, B1); PG8_BAR; PG8_SCHED;
;             PG8_LDB(B0, 1, 0); PG8_LDB(B1, 1, 1); PG8_SCHED; PG8_LDA(At, 1, 0); PG8_STAGE(PG8_SA(0, 1), a2 + hstep, voffA);
;             PG8_WAIT_V(8); PG8_WAIT_L(0); PG8_BAR; PG8_MMA(0, 0, At, B0); PG8_MMA(0, 1, At, B1); PG8_BAR; PG8_SCHED;
	v_mfma_f32_16x16x32_bf16 v[62:65], v[130:133], v[182:185], v[62:65]
	v_mfma_f32_16x16x32_bf16 v[58:61], v[138:141], v[182:185], v[58:61]
	v_mfma_f32_16x16x32_bf16 v[46:49], v[130:133], v[202:205], v[46:49]
	v_mfma_f32_16x16x32_bf16 v[42:45], v[138:141], v[202:205], v[42:45]
	v_mfma_f32_16x16x32_bf16 v[30:33], v[130:133], v[210:213], v[30:33]
	v_mfma_f32_16x16x32_bf16 v[26:29], v[138:141], v[210:213], v[26:29]
	v_mfma_f32_16x16x32_bf16 v[14:17], v[130:133], v[218:221], v[14:17]
	v_mfma_f32_16x16x32_bf16 v[10:13], v[138:141], v[218:221], v[10:13]
	v_mfma_f32_16x16x32_bf16 v[62:65], v[134:137], v[186:189], v[62:65]
	v_mfma_f32_16x16x32_bf16 v[58:61], v[142:145], v[186:189], v[58:61]
	v_mfma_f32_16x16x32_bf16 v[46:49], v[134:137], v[206:209], v[46:49]
	v_mfma_f32_16x16x32_bf16 v[42:45], v[142:145], v[206:209], v[42:45]
	v_mfma_f32_16x16x32_bf16 v[30:33], v[134:137], v[214:217], v[30:33]
	v_mfma_f32_16x16x32_bf16 v[26:29], v[142:145], v[214:217], v[26:29]
	v_mfma_f32_16x16x32_bf16 v[14:17], v[134:137], v[222:225], v[14:17]
	v_mfma_f32_16x16x32_bf16 v[10:13], v[142:145], v[222:225], v[10:13]
	v_mfma_f32_16x16x32_bf16 v[54:57], v[166:169], v[182:185], v[54:57]
	v_mfma_f32_16x16x32_bf16 v[50:53], v[174:177], v[182:185], v[50:53]
	v_mfma_f32_16x16x32_bf16 v[38:41], v[166:169], v[202:205], v[38:41]
	v_mfma_f32_16x16x32_bf16 v[34:37], v[174:177], v[202:205], v[34:37]
	v_mfma_f32_16x16x32_bf16 v[22:25], v[166:169], v[210:213], v[22:25]
	v_mfma_f32_16x16x32_bf16 v[18:21], v[174:177], v[210:213], v[18:21]
	v_mfma_f32_16x16x32_bf16 v[6:9], v[166:169], v[218:221], v[6:9]
	v_mfma_f32_16x16x32_bf16 v[2:5], v[174:177], v[218:221], v[2:5]
	v_mfma_f32_16x16x32_bf16 v[54:57], v[170:173], v[186:189], v[54:57]
	v_mfma_f32_16x16x32_bf16 v[50:53], v[178:181], v[186:189], v[50:53]
	v_mfma_f32_16x16x32_bf16 v[38:41], v[170:173], v[206:209], v[38:41]
	v_mfma_f32_16x16x32_bf16 v[34:37], v[178:181], v[206:209], v[34:37]
	v_mfma_f32_16x16x32_bf16 v[22:25], v[170:173], v[214:217], v[22:25]
	v_mfma_f32_16x16x32_bf16 v[18:21], v[178:181], v[214:217], v[18:21]
	v_mfma_f32_16x16x32_bf16 v[6:9], v[170:173], v[222:225], v[6:9]
	v_mfma_f32_16x16x32_bf16 v[2:5], v[178:181], v[222:225], v[2:5]
	s_barrier
	s_add_i32 s56, 0, 0x18000
	s_add_i32 s57, 0, 0x1c000
	v_add_u32_e32 v142, s56, v1
	v_add_u32_e32 v154, s57, v1
	ds_read_b128 v[130:133], v142
	ds_read_b128 v[134:137], v142 offset:1024
	ds_read_b128 v[138:141], v142 offset:2048
	ds_read_b128 v[142:145], v142 offset:3072
	ds_read_b128 v[166:169], v154
	ds_read_b128 v[170:173], v154 offset:1024
	ds_read_b128 v[174:177], v154 offset:2048
	ds_read_b128 v[178:181], v154 offset:3072
	s_add_u32 s16, s46, 0x160000
	s_addc_u32 s17, s47, 0
	s_mov_b32 m0, s34
	v_lshl_add_u64 v[232:233], s[16:17], 0, v[146:147]
	ds_read_b128 v[182:185], v198 offset:32768
	ds_read_b128 v[186:189], v198 offset:33792
	ds_read_b128 v[202:205], v198 offset:34816
	ds_read_b128 v[206:209], v198 offset:35840
	ds_read_b128 v[210:213], v198 offset:36864
	ds_read_b128 v[214:217], v198 offset:37888
	ds_read_b128 v[218:221], v198 offset:38912
	ds_read_b128 v[222:225], v198 offset:39936
	global_load_lds_dwordx4 v[232:233], off
	v_lshl_add_u64 v[232:233], s[16:17], 0, v[150:151]
	s_mov_b32 m0, s35
	s_nop 0
	global_load_lds_dwordx4 v[232:233], off
	s_waitcnt vmcnt(8)
	s_waitcnt lgkmcnt(0)
	s_barrier
	v_mfma_f32_16x16x32_bf16 v[126:129], v[130:133], v[182:185], v[126:129]
	v_mfma_f32_16x16x32_bf16 v[122:125], v[138:141], v[182:185], v[122:125]
	v_mfma_f32_16x16x32_bf16 v[110:113], v[130:133], v[202:205], v[110:113]
	v_mfma_f32_16x16x32_bf16 v[106:109], v[138:141], v[202:205], v[106:109]
	v_mfma_f32_16x16x32_bf16 v[94:97], v[130:133], v[210:213], v[94:97]
	v_mfma_f32_16x16x32_bf16 v[90:93], v[138:141], v[210:213], v[90:93]
	v_mfma_f32_16x16x32_bf16 v[78:81], v[130:133], v[218:221], v[78:81]
	v_mfma_f32_16x16x32_bf16 v[74:77], v[138:141], v[218:221], v[74:77]
	v_mfma_f32_16x16x32_bf16 v[126:129], v[134:137], v[186:189], v[126:129]
	v_mfma_f32_16x16x32_bf16 v[122:125], v[142:145], v[186:189], v[122:125]
	v_mfma_f32_16x16x32_bf16 v[110:113], v[134:137], v[206:209], v[110:113]
	v_mfma_f32_16x16x32_bf16 v[106:109], v[142:145], v[206:209], v[106:109]
	v_mfma_f32_16x16x32_bf16 v[94:97], v[134:137], v[214:217], v[94:97]
	v_mfma_f32_16x16x32_bf16 v[90:93], v[142:145], v[214:217], v[90:93]
	v_mfma_f32_16x16x32_bf16 v[78:81], v[134:137], v[222:225], v[78:81]
	v_mfma_f32_16x16x32_bf16 v[74:77], v[142:145], v[222:225], v[74:77]
	v_mfma_f32_16x16x32_bf16 v[118:121], v[166:169], v[182:185], v[118:121]
	v_mfma_f32_16x16x32_bf16 v[114:117], v[174:177], v[182:185], v[114:117]
	v_mfma_f32_16x16x32_bf16 v[102:105], v[166:169], v[202:205], v[102:105]
	v_mfma_f32_16x16x32_bf16 v[98:101], v[174:177], v[202:205], v[98:101]
	v_mfma_f32_16x16x32_bf16 v[86:89], v[166:169], v[210:213], v[86:89]
	v_mfma_f32_16x16x32_bf16 v[82:85], v[174:177], v[210:213], v[82:85]
	v_mfma_f32_16x16x32_bf16 v[70:73], v[166:169], v[218:221], v[70:73]
	v_mfma_f32_16x16x32_bf16 v[66:69], v[174:177], v[218:221], v[66:69]
	v_mfma_f32_16x16x32_bf16 v[118:121], v[170:173], v[186:189], v[118:121]
	v_mfma_f32_16x16x32_bf16 v[114:117], v[178:181], v[186:189], v[114:117]
	v_mfma_f32_16x16x32_bf16 v[102:105], v[170:173], v[206:209], v[102:105]
	v_mfma_f32_16x16x32_bf16 v[98:101], v[178:181], v[206:209], v[98:101]
	v_mfma_f32_16x16x32_bf16 v[86:89], v[170:173], v[214:217], v[86:89]
	v_mfma_f32_16x16x32_bf16 v[82:85], v[178:181], v[214:217], v[82:85]
	v_mfma_f32_16x16x32_bf16 v[70:73], v[170:173], v[222:225], v[70:73]
	v_mfma_f32_16x16x32_bf16 v[66:69], v[178:181], v[222:225], v[66:69]
	s_barrier
; #define PG8_STAGE(bufoff, gbase, voff) do { _Pragma("unroll") for (int _i = 0; _i < 2; ++_i) \
;         __builtin_amdgcn_global_load_lds((const unsigned*)((const char*)(gbase) + (voff)[_i]), (LAS unsigned*)(lds + (bufoff) + ldsw + _i * 8192), 16, 0, 0); } while (0)
; #define PG8_LDA(dst, b, h) do { _Pragma("unroll") for (int m = 0; m < 4; ++m) _Pragma("unroll") for (int k = 0; k < 2; ++k) dst[m][k] = *(const LAS bf16x8*)(lds + PG8_SA(b, h) + aoff + m * 2048 + k * 1024); } while (0)
; #define PG8_MMA(ai, bj, At, Bt) do { __builtin_amdgcn_s_setprio(1); _Pragma("unroll") for (int m = 0; m < 4; ++m) _Pragma("unroll") for (int n = 0; n < 2; ++n) _Pragma("unroll") for (int k = 0; k < 2; ++k) \
;         acc[ai][bj][m][n] = __builtin_amdgcn_mfma_f32_16x16x32_bf16(Bt[n][k], At[m][k], acc[ai][bj][m][n], 0, 0, 0); __builtin_amdgcn_s_setprio(0); } while (0)
; #define PG8_WAIT_V(n) asm volatile("s_waitcnt vmcnt(" #n ")" ::: "memory")
; #define PG8_WAIT_L(n) asm volatile("s_waitcnt lgkmcnt(" #n ")" ::: "memory")
; #define PG8_BAR __builtin_amdgcn_s_barrier()
; #define PG8_SCHED __builtin_amdgcn_sched_barrier(0)
; template <class Epi, class Sched, bool ALIGN_EPI = false, bool SP2 = false>
; __device__ __forceinline__ void gemm_phase(LAS unsigned char* lds, const Gemm g, const Sched& S, const Epi& E) {
;     ...
;             PG8_LDA(At, 1, 1); PG8_STAGE(PG8_SB(1, 0), b3, voffB); PG8_STAGE(PG8_SB(1, 1), b3 + hstepB, voffB); PG8_STAGE(PG8_SA(1, 0), a3, voffA);
;             PG8_WAIT_V(8); PG8_WAIT_L(0); PG8_BAR; PG8_MMA(1, 0, At, B0); PG8_MMA(1, 1, At, B1); PG8_BAR; PG8_SCHED;
;     ...
;         if constexpr (ALIGN_EPI) { if (wr == 0) PG8_BAR; }
	s_add_i32 s16, s56, s30
	v_lshl_add_u64 v[190:191], v[190:191], 0, s[12:13]
	s_mov_b32 m0, s16
	ds_read_b128 v[182:185], v198 offset:49152
	ds_read_b128 v[186:189], v198 offset:50176
	ds_read_b128 v[202:205], v198 offset:51200
	ds_read_b128 v[206:209], v198 offset:52224
	ds_read_b128 v[210:213], v198 offset:53248
	ds_read_b128 v[214:217], v198 offset:54272
	ds_read_b128 v[218:221], v198 offset:55296
	ds_read_b128 v[222:225], v198 offset:56320
	global_load_lds_dwordx4 v[190:191], off
	s_add_i32 m0, s16, 0x2000
	s_add_u32 s16, s22, 0x58080
	v_lshl_add_u64 v[190:191], v[226:227], 0, s[12:13]
	s_addc_u32 s17, s23, 0
	s_add_i32 s22, s57, s30
	global_load_lds_dwordx4 v[190:191], off
	v_lshl_add_u64 v[190:191], s[16:17], 0, v[148:149]
	s_mov_b32 m0, s22
	s_nop 0
	global_load_lds_dwordx4 v[190:191], off
	v_lshl_add_u64 v[190:191], s[16:17], 0, v[152:153]
	s_add_i32 m0, s22, 0x2000
	s_nop 0
	global_load_lds_dwordx4 v[190:191], off
	v_lshl_add_u64 v[190:191], v[228:229], 0, s[12:13]
	s_mov_b32 m0, s49
	s_nop 0
	global_load_lds_dwordx4 v[190:191], off
	v_lshl_add_u64 v[190:191], v[230:231], 0, s[12:13]
	s_mov_b32 m0, s50
	s_nop 0
	global_load_lds_dwordx4 v[190:191], off
	s_waitcnt vmcnt(8)
	s_waitcnt lgkmcnt(0)
	s_barrier
	v_mfma_f32_16x16x32_bf16 v[62:65], v[130:133], v[182:185], v[62:65]
	v_mfma_f32_16x16x32_bf16 v[58:61], v[138:141], v[182:185], v[58:61]
	v_mfma_f32_16x16x32_bf16 v[46:49], v[130:133], v[202:205], v[46:49]
	v_mfma_f32_16x16x32_bf16 v[42:45], v[138:141], v[202:205], v[42:45]
	v_mfma_f32_16x16x32_bf16 v[30:33], v[130:133], v[210:213], v[30:33]
	v_mfma_f32_16x16x32_bf16 v[26:29], v[138:141], v[210:213], v[26:29]
	v_mfma_f32_16x16x32_bf16 v[14:17], v[130:133], v[218:221], v[14:17]
	v_mfma_f32_16x16x32_bf16 v[10:13], v[138:141], v[218:221], v[10:13]
	v_mfma_f32_16x16x32_bf16 v[62:65], v[134:137], v[186:189], v[62:65]
	v_mfma_f32_16x16x32_bf16 v[58:61], v[142:145], v[186:189], v[58:61]
	v_mfma_f32_16x16x32_bf16 v[46:49], v[134:137], v[206:209], v[46:49]
	v_mfma_f32_16x16x32_bf16 v[42:45], v[142:145], v[206:209], v[42:45]
	v_mfma_f32_16x16x32_bf16 v[30:33], v[134:137], v[214:217], v[30:33]
	v_mfma_f32_16x16x32_bf16 v[26:29], v[142:145], v[214:217], v[26:29]
	v_mfma_f32_16x16x32_bf16 v[14:17], v[134:137], v[222:225], v[14:17]
	v_mfma_f32_16x16x32_bf16 v[10:13], v[142:145], v[222:225], v[10:13]
	v_mfma_f32_16x16x32_bf16 v[54:57], v[166:169], v[182:185], v[54:57]
	v_mfma_f32_16x16x32_bf16 v[50:53], v[174:177], v[182:185], v[50:53]
	v_mfma_f32_16x16x32_bf16 v[38:41], v[166:169], v[202:205], v[38:41]
	v_mfma_f32_16x16x32_bf16 v[34:37], v[174:177], v[202:205], v[34:37]
	v_mfma_f32_16x16x32_bf16 v[22:25], v[166:169], v[210:213], v[22:25]
	v_mfma_f32_16x16x32_bf16 v[18:21], v[174:177], v[210:213], v[18:21]
	v_mfma_f32_16x16x32_bf16 v[6:9], v[166:169], v[218:221], v[6:9]
	v_mfma_f32_16x16x32_bf16 v[2:5], v[174:177], v[218:221], v[2:5]
	v_mfma_f32_16x16x32_bf16 v[54:57], v[170:173], v[186:189], v[54:57]
	v_mfma_f32_16x16x32_bf16 v[50:53], v[178:181], v[186:189], v[50:53]
	v_mfma_f32_16x16x32_bf16 v[38:41], v[170:173], v[206:209], v[38:41]
	v_mfma_f32_16x16x32_bf16 v[34:37], v[178:181], v[206:209], v[34:37]
	v_mfma_f32_16x16x32_bf16 v[22:25], v[170:173], v[214:217], v[22:25]
	v_mfma_f32_16x16x32_bf16 v[18:21], v[178:181], v[214:217], v[18:21]
	v_mfma_f32_16x16x32_bf16 v[6:9], v[170:173], v[222:225], v[6:9]
	v_mfma_f32_16x16x32_bf16 v[2:5], v[178:181], v[222:225], v[2:5]
	s_barrier
	s_add_i32 s25, s25, 2
	s_add_u32 s9, s9, 0x100
	s_addc_u32 s24, s24, 0
	s_cmpk_gt_u32 s25, 0x55
	s_mov_b64 s[16:17], s[20:21]
	s_cbranch_scc0 .LBB0_1595
	s_setprio 0
	s_and_b64 vcc, exec, s[14:15]
	s_cbranch_vccz .LBB0_1598
	s_barrier

;     __device__ bool next(int i, Unit& u) const { if (i != 0 || c >= 128) return false; const int t = c >> 2; u.pm = t & 3; u.pn = t >> 2; u.koff = koff_bytes; u.q = c & 3; return true; }
; #define PG8_STAGE(bufoff, gbase, voff) do { _Pragma("unroll") for (int _i = 0; _i < 2; ++_i) \
;         __builtin_amdgcn_global_load_lds((const unsigned*)((const char*)(gbase) + (voff)[_i]), (LAS unsigned*)(lds + (bufoff) + ldsw + _i * 8192), 16, 0, 0); } while (0)
; #define PG8_LDA(dst, b, h) do { _Pragma("unroll") for (int m = 0; m < 4; ++m) _Pragma("unroll") for (int k = 0; k < 2; ++k) dst[m][k] = *(const LAS bf16x8*)(lds + PG8_SA(b, h) + aoff + m * 2048 + k * 1024); } while (0)
; #define PG8_LDB(dst, b, h) do { _Pragma("unroll") for (int n = 0; n < 2; ++n) _Pragma("unroll") for (int k = 0; k < 2; ++k) dst[n][k] = *(const LAS bf16x8*)(lds + PG8_SB(b, h) + boff + n * 2048 + k * 1024); } while (0)
; #define PG8_WAIT_V(n) asm volatile("s_waitcnt vmcnt(" #n ")" ::: "memory")
; template <class Epi, class Sched, bool ALIGN_EPI = false, bool SP2 = false>
; __device__ __forceinline__ void gemm_phase(LAS unsigned char* lds, const Gemm g, const Sched& S, const Epi& E) {
;     ...
;         const bool has_next = S.next(ui + 1, nxt);
;         const char* nA = has_next ? (const char*)g.A + (size_t)nxt.pm * tstep + nxt.koff : cA; const char* nB = has_next ? (const char*)g.Bt + (size_t)nxt.pn * tstep + nxt.koff : cB;
;         for (int t = 0; t < nt; t += 2) {
;             const bool last = (t == nt - 2);
;             const char* a1 = cA + (size_t)(t + 1) * kstep;
;             const char* a2 = last ? nA : cA + (size_t)(t + 2) * kstep; const char* b2 = last ? nB : cB + (size_t)(t + 2) * kstep;
;             const char* a3 = a2 + kstep; const char* b3 = b2 + kstep;
;             if (last && has_next) S.a_ready(nxt);
;             if constexpr (SP2) {
;             PG8_LDB(B0, 0, 0); PG8_LDB(B1, 0, 1); PG8_SCHED; PG8_LDA(At, 0, 0); PG8_STAGE(PG8_SA(1, 1), a1 + hstep, voffA);
;             PG8_WAIT_V(8); PG8_WAIT_L(0); PG8_BAR; PG8_MMA(0, 0, At, B0); PG8_MMA(0, 1, At, B1); PG8_BAR; PG8_SCHED;
;             PG8_LDA(At, 0, 1); PG8_STAGE(PG8_SB(0, 0), b2, voffB); PG8_STAGE(PG8_SB(0, 1), b2 + hstepB, voffB); PG8_STAGE(PG8_SA(0, 0), a2, voffA);
;             PG8_WAIT_V(8); PG8_WAIT_L(0); PG8_BAR; PG8_MMA(1, 0, At, B0); PG8_MMA(1, 1, At, B1); PG8_BAR; PG8_SCHED;
.Lprio_1822:
	ds_read_b128 v[66:69], v173
	ds_read_b128 v[70:73], v173 offset:1024
	ds_read_b128 v[74:77], v173 offset:2048
	ds_read_b128 v[78:81], v173 offset:3072
	ds_read_b128 v[162:165], v174
	ds_read_b128 v[180:183], v174 offset:1024
	ds_read_b128 v[184:187], v174 offset:2048
	ds_read_b128 v[188:191], v174 offset:3072
	s_add_u32 s22, s16, 0xfff80080
	s_addc_u32 s23, s17, -1
	s_cmp_eq_u32 s50, 28
	s_cselect_b32 s41, s3, s23
	s_cselect_b32 s40, s15, s22
	s_cselect_b32 s23, s13, s49
	s_cselect_b32 s22, s24, s25
	v_lshl_add_u64 v[166:167], s[16:17], 0, v[156:157]
	s_add_i32 m0, s29, 0xc000
	ds_read_b128 v[192:195], v175
	ds_read_b128 v[196:199], v175 offset:1024
	ds_read_b128 v[200:203], v175 offset:2048
	ds_read_b128 v[204:207], v175 offset:3072
	ds_read_b128 v[208:211], v175 offset:4096
	ds_read_b128 v[212:215], v175 offset:5120
	ds_read_b128 v[216:219], v175 offset:6144
	ds_read_b128 v[220:223], v175 offset:7168
	global_load_lds_dwordx4 v[166:167], off
	v_lshl_add_u64 v[166:167], s[16:17], 0, v[154:155]
	s_add_i32 m0, s29, 0xe000
	s_nop 0
	global_load_lds_dwordx4 v[166:167], off
	s_waitcnt lgkmcnt(0)
	s_barrier
	v_mfma_f32_16x16x32_bf16 v[142:145], v[66:69], v[192:195], 0
	v_mfma_f32_16x16x32_bf16 v[138:141], v[74:77], v[192:195], 0
	v_mfma_f32_16x16x32_bf16 v[126:129], v[66:69], v[200:203], 0
	v_mfma_f32_16x16x32_bf16 v[122:125], v[74:77], v[200:203], 0
	v_mfma_f32_16x16x32_bf16 v[110:113], v[66:69], v[208:211], 0
	v_mfma_f32_16x16x32_bf16 v[106:109], v[74:77], v[208:211], 0
	v_mfma_f32_16x16x32_bf16 v[94:97], v[66:69], v[216:219], 0
	v_mfma_f32_16x16x32_bf16 v[90:93], v[74:77], v[216:219], 0
	v_mfma_f32_16x16x32_bf16 v[142:145], v[70:73], v[196:199], v[142:145]
	v_mfma_f32_16x16x32_bf16 v[138:141], v[78:81], v[196:199], v[138:141]
	v_mfma_f32_16x16x32_bf16 v[126:129], v[70:73], v[204:207], v[126:129]
	v_mfma_f32_16x16x32_bf16 v[122:125], v[78:81], v[204:207], v[122:125]
	v_mfma_f32_16x16x32_bf16 v[110:113], v[70:73], v[212:215], v[110:113]
	v_mfma_f32_16x16x32_bf16 v[106:109], v[78:81], v[212:215], v[106:109]
	v_mfma_f32_16x16x32_bf16 v[94:97], v[70:73], v[220:223], v[94:97]
	v_mfma_f32_16x16x32_bf16 v[90:93], v[78:81], v[220:223], v[90:93]
	v_mfma_f32_16x16x32_bf16 v[134:137], v[162:165], v[192:195], 0
	v_mfma_f32_16x16x32_bf16 v[130:133], v[184:187], v[192:195], 0
	v_mfma_f32_16x16x32_bf16 v[118:121], v[162:165], v[200:203], 0
	v_mfma_f32_16x16x32_bf16 v[114:117], v[184:187], v[200:203], 0
	v_mfma_f32_16x16x32_bf16 v[102:105], v[162:165], v[208:211], 0
	v_mfma_f32_16x16x32_bf16 v[98:101], v[184:187], v[208:211], 0
	v_mfma_f32_16x16x32_bf16 v[86:89], v[162:165], v[216:219], 0
	v_mfma_f32_16x16x32_bf16 v[82:85], v[184:187], v[216:219], 0
	v_mfma_f32_16x16x32_bf16 v[134:137], v[180:183], v[196:199], v[134:137]
	v_mfma_f32_16x16x32_bf16 v[130:133], v[188:191], v[196:199], v[130:133]
	v_mfma_f32_16x16x32_bf16 v[118:121], v[180:183], v[204:207], v[118:121]
	v_mfma_f32_16x16x32_bf16 v[114:117], v[188:191], v[204:207], v[114:117]
	v_mfma_f32_16x16x32_bf16 v[102:105], v[180:183], v[212:215], v[102:105]
	v_mfma_f32_16x16x32_bf16 v[98:101], v[188:191], v[212:215], v[98:101]
	v_mfma_f32_16x16x32_bf16 v[86:89], v[180:183], v[220:223], v[86:89]
	v_mfma_f32_16x16x32_bf16 v[82:85], v[188:191], v[220:223], v[82:85]
	s_barrier
	s_add_i32 s51, s44, s26
	v_lshl_add_u64 v[166:167], s[22:23], 0, v[150:151]
	s_mov_b32 m0, s51
	ds_read_b128 v[192:195], v175 offset:16384
	ds_read_b128 v[196:199], v175 offset:17408
	ds_read_b128 v[200:203], v175 offset:18432
	ds_read_b128 v[204:207], v175 offset:19456
	ds_read_b128 v[208:211], v175 offset:20480
	ds_read_b128 v[212:215], v175 offset:21504
	ds_read_b128 v[216:219], v175 offset:22528
	ds_read_b128 v[220:223], v175 offset:23552
	global_load_lds_dwordx4 v[166:167], off
	s_add_i32 m0, s51, 0x2000
	s_add_u32 s52, s22, 0x80000
	v_lshl_add_u64 v[224:225], s[22:23], 0, v[146:147]
	s_addc_u32 s53, s23, 0
	s_add_i32 s51, s45, s26
	global_load_lds_dwordx4 v[224:225], off
	v_lshl_add_u64 v[226:227], s[52:53], 0, v[150:151]
	s_mov_b32 m0, s51
	v_lshl_add_u64 v[228:229], s[40:41], 0, v[148:149]
	global_load_lds_dwordx4 v[226:227], off
	v_lshl_add_u64 v[226:227], s[52:53], 0, v[146:147]
	s_add_i32 m0, s51, 0x2000
	s_nop 0
	global_load_lds_dwordx4 v[226:227], off
	v_lshl_add_u64 v[226:227], s[40:41], 0, v[152:153]
	s_mov_b32 m0, s29
	s_nop 0
	global_load_lds_dwordx4 v[226:227], off
	s_mov_b32 m0, s30
	s_nop 0
	global_load_lds_dwordx4 v[228:229], off
	s_waitcnt lgkmcnt(0)
	s_barrier
	v_mfma_f32_16x16x32_bf16 v[62:65], v[66:69], v[192:195], 0
	v_mfma_f32_16x16x32_bf16 v[58:61], v[74:77], v[192:195], 0
	v_mfma_f32_16x16x32_bf16 v[46:49], v[66:69], v[200:203], 0
	v_mfma_f32_16x16x32_bf16 v[42:45], v[74:77], v[200:203], 0
	v_mfma_f32_16x16x32_bf16 v[30:33], v[66:69], v[208:211], 0
	v_mfma_f32_16x16x32_bf16 v[26:29], v[74:77], v[208:211], 0
	v_mfma_f32_16x16x32_bf16 v[14:17], v[66:69], v[216:219], 0
	v_mfma_f32_16x16x32_bf16 v[10:13], v[74:77], v[216:219], 0
	v_mfma_f32_16x16x32_bf16 v[62:65], v[70:73], v[196:199], v[62:65]
	v_mfma_f32_16x16x32_bf16 v[58:61], v[78:81], v[196:199], v[58:61]
	v_mfma_f32_16x16x32_bf16 v[46:49], v[70:73], v[204:207], v[46:49]
	v_mfma_f32_16x16x32_bf16 v[42:45], v[78:81], v[204:207], v[42:45]
	v_mfma_f32_16x16x32_bf16 v[30:33], v[70:73], v[212:215], v[30:33]
	v_mfma_f32_16x16x32_bf16 v[26:29], v[78:81], v[212:215], v[26:29]
	v_mfma_f32_16x16x32_bf16 v[14:17], v[70:73], v[220:223], v[14:17]
	v_mfma_f32_16x16x32_bf16 v[10:13], v[78:81], v[220:223], v[10:13]
	v_mfma_f32_16x16x32_bf16 v[54:57], v[162:165], v[192:195], 0
	v_mfma_f32_16x16x32_bf16 v[50:53], v[184:187], v[192:195], 0
	v_mfma_f32_16x16x32_bf16 v[38:41], v[162:165], v[200:203], 0
	v_mfma_f32_16x16x32_bf16 v[34:37], v[184:187], v[200:203], 0
	v_mfma_f32_16x16x32_bf16 v[22:25], v[162:165], v[208:211], 0
	v_mfma_f32_16x16x32_bf16 v[18:21], v[184:187], v[208:211], 0
	v_mfma_f32_16x16x32_bf16 v[6:9], v[162:165], v[216:219], 0
	v_mfma_f32_16x16x32_bf16 v[2:5], v[184:187], v[216:219], 0
	v_mfma_f32_16x16x32_bf16 v[54:57], v[180:183], v[196:199], v[54:57]
	v_mfma_f32_16x16x32_bf16 v[50:53], v[188:191], v[196:199], v[50:53]
	v_mfma_f32_16x16x32_bf16 v[38:41], v[180:183], v[204:207], v[38:41]
	v_mfma_f32_16x16x32_bf16 v[34:37], v[188:191], v[204:207], v[34:37]
	v_mfma_f32_16x16x32_bf16 v[22:25], v[180:183], v[212:215], v[22:25]
	v_mfma_f32_16x16x32_bf16 v[18:21], v[188:191], v[212:215], v[18:21]
	v_mfma_f32_16x16x32_bf16 v[6:9], v[180:183], v[220:223], v[6:9]
	v_mfma_f32_16x16x32_bf16 v[2:5], v[188:191], v[220:223], v[2:5]
	s_barrier
; #define PG8_STAGE(bufoff, gbase, voff) do { _Pragma("unroll") for (int _i = 0; _i < 2; ++_i) \
;         __builtin_amdgcn_global_load_lds((const unsigned*)((const char*)(gbase) + (voff)[_i]), (LAS unsigned*)(lds + (bufoff) + ldsw + _i * 8192), 16, 0, 0); } while (0)
; #define PG8_LDA(dst, b, h) do { _Pragma("unroll") for (int m = 0; m < 4; ++m) _Pragma("unroll") for (int k = 0; k < 2; ++k) dst[m][k] = *(const LAS bf16x8*)(lds + PG8_SA(b, h) + aoff + m * 2048 + k * 1024); } while (0)
; #define PG8_LDB(dst, b, h) do { _Pragma("unroll") for (int n = 0; n < 2; ++n) _Pragma("unroll") for (int k = 0; k < 2; ++k) dst[n][k] = *(const LAS bf16x8*)(lds + PG8_SB(b, h) + boff + n * 2048 + k * 1024); } while (0)
; #define PG8_MMA(ai, bj, At, Bt) do { __builtin_amdgcn_s_setprio(1); _Pragma("unroll") for (int m = 0; m < 4; ++m) _Pragma("unroll") for (int n = 0; n < 2; ++n) _Pragma("unroll") for (int k = 0; k < 2; ++k) \
;         acc[ai][bj][m][n] = __builtin_amdgcn_mfma_f32_16x16x32_bf16(Bt[n][k], At[m][k], acc[ai][bj][m][n], 0, 0, 0); __builtin_amdgcn_s_setprio(0); } while (0)
; #define PG8_WAIT_V(n) asm volatile("s_waitcnt vmcnt(" #n ")" ::: "memory")
; #define PG8_WAIT_L(n) asm volatile("s_waitcnt lgkmcnt(" #n ")" ::: "memory")
; #define PG8_BAR __builtin_amdgcn_s_barrier()
; #define PG8_SCHED __builtin_amdgcn_sched_barrier(0)
; template <class Epi, class Sched, bool ALIGN_EPI = false, bool SP2 = false>
; __device__ __forceinline__ void gemm_phase(LAS unsigned char* lds, const Gemm g, const Sched& S, const Epi& E) {
;     ...
;             PG8_LDB(B0, 1, 0); PG8_LDB(B1, 1, 1); PG8_SCHED; PG8_LDA(At, 1, 0); PG8_STAGE(PG8_SA(0, 1), a2 + hstep, voffA);
;             PG8_WAIT_V(8); PG8_WAIT_L(0); PG8_BAR; PG8_MMA(0, 0, At, B0); PG8_MMA(0, 1, At, B1); PG8_BAR; PG8_SCHED;
;             PG8_LDA(At, 1, 1); PG8_STAGE(PG8_SB(1, 0), b3, voffB); PG8_STAGE(PG8_SB(1, 1), b3 + hstepB, voffB); PG8_STAGE(PG8_SA(1, 0), a3, voffA);
;             PG8_WAIT_V(8); PG8_WAIT_L(0); PG8_BAR; PG8_MMA(1, 0, At, B0); PG8_MMA(1, 1, At, B1); PG8_BAR; PG8_SCHED;
	s_add_i32 s51, 0, 0x18000
	s_add_i32 s52, 0, 0x1c000
	v_add_u32_e32 v78, s51, v169
	v_add_u32_e32 v168, s52, v169
	ds_read_b128 v[66:69], v78
	ds_read_b128 v[70:73], v78 offset:1024
	ds_read_b128 v[74:77], v78 offset:2048
	ds_read_b128 v[78:81], v78 offset:3072
	ds_read_b128 v[162:165], v168
	ds_read_b128 v[180:183], v168 offset:1024
	ds_read_b128 v[184:187], v168 offset:2048
	ds_read_b128 v[188:191], v168 offset:3072
	s_add_u32 s40, s40, 0x80000
	s_addc_u32 s41, s41, 0
	s_mov_b32 m0, s31
	v_lshl_add_u64 v[230:231], s[40:41], 0, v[152:153]
	ds_read_b128 v[192:195], v175 offset:32768
	ds_read_b128 v[196:199], v175 offset:33792
	ds_read_b128 v[200:203], v175 offset:34816
	ds_read_b128 v[204:207], v175 offset:35840
	ds_read_b128 v[208:211], v175 offset:36864
	ds_read_b128 v[212:215], v175 offset:37888
	ds_read_b128 v[216:219], v175 offset:38912
	ds_read_b128 v[220:223], v175 offset:39936
	global_load_lds_dwordx4 v[230:231], off
	v_lshl_add_u64 v[230:231], s[40:41], 0, v[148:149]
	s_mov_b32 m0, s33
	s_nop 0
	global_load_lds_dwordx4 v[230:231], off
	s_waitcnt vmcnt(8)
	s_waitcnt lgkmcnt(0)
	s_barrier
	v_mfma_f32_16x16x32_bf16 v[142:145], v[66:69], v[192:195], v[142:145]
	v_mfma_f32_16x16x32_bf16 v[138:141], v[74:77], v[192:195], v[138:141]
	v_mfma_f32_16x16x32_bf16 v[126:129], v[66:69], v[200:203], v[126:129]
	v_mfma_f32_16x16x32_bf16 v[122:125], v[74:77], v[200:203], v[122:125]
	v_mfma_f32_16x16x32_bf16 v[110:113], v[66:69], v[208:211], v[110:113]
	v_mfma_f32_16x16x32_bf16 v[106:109], v[74:77], v[208:211], v[106:109]
	v_mfma_f32_16x16x32_bf16 v[94:97], v[66:69], v[216:219], v[94:97]
	v_mfma_f32_16x16x32_bf16 v[90:93], v[74:77], v[216:219], v[90:93]
	v_mfma_f32_16x16x32_bf16 v[142:145], v[70:73], v[196:199], v[142:145]
	v_mfma_f32_16x16x32_bf16 v[138:141], v[78:81], v[196:199], v[138:141]
	v_mfma_f32_16x16x32_bf16 v[126:129], v[70:73], v[204:207], v[126:129]
	v_mfma_f32_16x16x32_bf16 v[122:125], v[78:81], v[204:207], v[122:125]
	v_mfma_f32_16x16x32_bf16 v[110:113], v[70:73], v[212:215], v[110:113]
	v_mfma_f32_16x16x32_bf16 v[106:109], v[78:81], v[212:215], v[106:109]
	v_mfma_f32_16x16x32_bf16 v[94:97], v[70:73], v[220:223], v[94:97]
	v_mfma_f32_16x16x32_bf16 v[90:93], v[78:81], v[220:223], v[90:93]
	v_mfma_f32_16x16x32_bf16 v[134:137], v[162:165], v[192:195], v[134:137]
	v_mfma_f32_16x16x32_bf16 v[130:133], v[184:187], v[192:195], v[130:133]
	v_mfma_f32_16x16x32_bf16 v[118:121], v[162:165], v[200:203], v[118:121]
	v_mfma_f32_16x16x32_bf16 v[114:117], v[184:187], v[200:203], v[114:117]
	v_mfma_f32_16x16x32_bf16 v[102:105], v[162:165], v[208:211], v[102:105]
	v_mfma_f32_16x16x32_bf16 v[98:101], v[184:187], v[208:211], v[98:101]
	v_mfma_f32_16x16x32_bf16 v[86:89], v[162:165], v[216:219], v[86:89]
	v_mfma_f32_16x16x32_bf16 v[82:85], v[184:187], v[216:219], v[82:85]
	v_mfma_f32_16x16x32_bf16 v[134:137], v[180:183], v[196:199], v[134:137]
	v_mfma_f32_16x16x32_bf16 v[130:133], v[188:191], v[196:199], v[130:133]
	v_mfma_f32_16x16x32_bf16 v[118:121], v[180:183], v[204:207], v[118:121]
	v_mfma_f32_16x16x32_bf16 v[114:117], v[188:191], v[204:207], v[114:117]
	v_mfma_f32_16x16x32_bf16 v[102:105], v[180:183], v[212:215], v[102:105]
	v_mfma_f32_16x16x32_bf16 v[98:101], v[188:191], v[212:215], v[98:101]
	v_mfma_f32_16x16x32_bf16 v[86:89], v[180:183], v[220:223], v[86:89]
	v_mfma_f32_16x16x32_bf16 v[82:85], v[188:191], v[220:223], v[82:85]
	s_barrier
	s_add_i32 s40, s51, s26
	v_lshl_add_u64 v[166:167], v[166:167], 0, s[8:9]
	s_mov_b32 m0, s40
	ds_read_b128 v[192:195], v175 offset:49152
	ds_read_b128 v[196:199], v175 offset:50176
	ds_read_b128 v[200:203], v175 offset:51200
	ds_read_b128 v[204:207], v175 offset:52224
	ds_read_b128 v[208:211], v175 offset:53248
	ds_read_b128 v[212:215], v175 offset:54272
	ds_read_b128 v[216:219], v175 offset:55296
	ds_read_b128 v[220:223], v175 offset:56320
	global_load_lds_dwordx4 v[166:167], off
	s_add_i32 m0, s40, 0x2000
	s_add_u32 s22, s22, 0x80080
	v_lshl_add_u64 v[166:167], v[224:225], 0, s[8:9]
	s_addc_u32 s23, s23, 0
	s_add_i32 s40, s52, s26
	global_load_lds_dwordx4 v[166:167], off
	v_lshl_add_u64 v[166:167], s[22:23], 0, v[150:151]
	s_mov_b32 m0, s40
	s_nop 0
	global_load_lds_dwordx4 v[166:167], off
	v_lshl_add_u64 v[166:167], s[22:23], 0, v[146:147]
	s_add_i32 m0, s40, 0x2000
	s_nop 0
	global_load_lds_dwordx4 v[166:167], off
	v_lshl_add_u64 v[166:167], v[226:227], 0, s[8:9]
	s_mov_b32 m0, s42
	s_nop 0
	global_load_lds_dwordx4 v[166:167], off
	v_lshl_add_u64 v[166:167], v[228:229], 0, s[8:9]
	s_mov_b32 m0, s43
	s_nop 0
	global_load_lds_dwordx4 v[166:167], off
	s_waitcnt vmcnt(8)
	s_waitcnt lgkmcnt(0)
	s_barrier
	v_mfma_f32_16x16x32_bf16 v[62:65], v[66:69], v[192:195], v[62:65]
	v_mfma_f32_16x16x32_bf16 v[58:61], v[74:77], v[192:195], v[58:61]
	v_mfma_f32_16x16x32_bf16 v[46:49], v[66:69], v[200:203], v[46:49]
	v_mfma_f32_16x16x32_bf16 v[42:45], v[74:77], v[200:203], v[42:45]
	v_mfma_f32_16x16x32_bf16 v[30:33], v[66:69], v[208:211], v[30:33]
	v_mfma_f32_16x16x32_bf16 v[26:29], v[74:77], v[208:211], v[26:29]
	v_mfma_f32_16x16x32_bf16 v[14:17], v[66:69], v[216:219], v[14:17]
	v_mfma_f32_16x16x32_bf16 v[10:13], v[74:77], v[216:219], v[10:13]
	v_mfma_f32_16x16x32_bf16 v[62:65], v[70:73], v[196:199], v[62:65]
	v_mfma_f32_16x16x32_bf16 v[58:61], v[78:81], v[196:199], v[58:61]
	v_mfma_f32_16x16x32_bf16 v[46:49], v[70:73], v[204:207], v[46:49]
	v_mfma_f32_16x16x32_bf16 v[42:45], v[78:81], v[204:207], v[42:45]
	v_mfma_f32_16x16x32_bf16 v[30:33], v[70:73], v[212:215], v[30:33]
	v_mfma_f32_16x16x32_bf16 v[26:29], v[78:81], v[212:215], v[26:29]
	v_mfma_f32_16x16x32_bf16 v[14:17], v[70:73], v[220:223], v[14:17]
	v_mfma_f32_16x16x32_bf16 v[10:13], v[78:81], v[220:223], v[10:13]
	v_mfma_f32_16x16x32_bf16 v[54:57], v[162:165], v[192:195], v[54:57]
	v_mfma_f32_16x16x32_bf16 v[50:53], v[184:187], v[192:195], v[50:53]
	v_mfma_f32_16x16x32_bf16 v[38:41], v[162:165], v[200:203], v[38:41]
	v_mfma_f32_16x16x32_bf16 v[34:37], v[184:187], v[200:203], v[34:37]
	v_mfma_f32_16x16x32_bf16 v[22:25], v[162:165], v[208:211], v[22:25]
	v_mfma_f32_16x16x32_bf16 v[18:21], v[184:187], v[208:211], v[18:21]
	v_mfma_f32_16x16x32_bf16 v[6:9], v[162:165], v[216:219], v[6:9]
	v_mfma_f32_16x16x32_bf16 v[2:5], v[184:187], v[216:219], v[2:5]
	v_mfma_f32_16x16x32_bf16 v[54:57], v[180:183], v[196:199], v[54:57]
	v_mfma_f32_16x16x32_bf16 v[50:53], v[188:191], v[196:199], v[50:53]
	v_mfma_f32_16x16x32_bf16 v[38:41], v[180:183], v[204:207], v[38:41]
	v_mfma_f32_16x16x32_bf16 v[34:37], v[188:191], v[204:207], v[34:37]
	v_mfma_f32_16x16x32_bf16 v[22:25], v[180:183], v[212:215], v[22:25]
	v_mfma_f32_16x16x32_bf16 v[18:21], v[188:191], v[212:215], v[18:21]
	v_mfma_f32_16x16x32_bf16 v[6:9], v[180:183], v[220:223], v[6:9]
	v_mfma_f32_16x16x32_bf16 v[2:5], v[188:191], v[220:223], v[2:5]
	s_barrier
	s_add_i32 s50, s50, 2
	s_add_u32 s25, s25, 0x100
	s_addc_u32 s49, s49, 0
	s_add_u32 s16, s16, 0x100
	s_addc_u32 s17, s17, 0
	s_cmp_lt_u32 s50, 30
; #define PG8_STAGE(bufoff, gbase, voff) do { _Pragma("unroll") for (int _i = 0; _i < 2; ++_i) \
;         __builtin_amdgcn_global_load_lds((const unsigned*)((const char*)(gbase) + (voff)[_i]), (LAS unsigned*)(lds + (bufoff) + ldsw + _i * 8192), 16, 0, 0); } while (0)
; #define PG8_LDA(dst, b, h) do { _Pragma("unroll") for (int m = 0; m < 4; ++m) _Pragma("unroll") for (int k = 0; k < 2; ++k) dst[m][k] = *(const LAS bf16x8*)(lds + PG8_SA(b, h) + aoff + m * 2048 + k * 1024); } while (0)
; #define PG8_LDB(dst, b, h) do { _Pragma("unroll") for (int n = 0; n < 2; ++n) _Pragma("unroll") for (int k = 0; k < 2; ++k) dst[n][k] = *(const LAS bf16x8*)(lds + PG8_SB(b, h) + boff + n * 2048 + k * 1024); } while (0)
; #define PG8_MMA(ai, bj, At, Bt) do { __builtin_amdgcn_s_setprio(1); _Pragma("unroll") for (int m = 0; m < 4; ++m) _Pragma("unroll") for (int n = 0; n < 2; ++n) _Pragma("unroll") for (int k = 0; k < 2; ++k) \
;         acc[ai][bj][m][n] = __builtin_amdgcn_mfma_f32_16x16x32_bf16(Bt[n][k], At[m][k], acc[ai][bj][m][n], 0, 0, 0); __builtin_amdgcn_s_setprio(0); } while (0)
; #define PG8_WAIT_V(n) asm volatile("s_waitcnt vmcnt(" #n ")" ::: "memory")
; #define PG8_WAIT_L(n) asm volatile("s_waitcnt lgkmcnt(" #n ")" ::: "memory")
; #define PG8_BAR __builtin_amdgcn_s_barrier()
; template <class Epi, class Sched, bool ALIGN_EPI = false, bool SP2 = false>
; __device__ __forceinline__ void gemm_phase(LAS unsigned char* lds, const Gemm g, const Sched& S, const Epi& E) {
;     ...
;             const bool last = (t == nt - 2);
;             const char* a1 = cA + (size_t)(t + 1) * kstep;
;             const char* a2 = last ? nA : cA + (size_t)(t + 2) * kstep; const char* b2 = last ? nB : cB + (size_t)(t + 2) * kstep;
;             const char* a3 = a2 + kstep; const char* b3 = b2 + kstep;
;             if (last && has_next) S.a_ready(nxt);
;             if constexpr (SP2) {
;             PG8_LDB(B0, 0, 0); PG8_LDB(B1, 0, 1); PG8_SCHED; PG8_LDA(At, 0, 0); PG8_STAGE(PG8_SA(1, 1), a1 + hstep, voffA);
;             PG8_WAIT_V(8); PG8_WAIT_L(0); PG8_BAR; PG8_MMA(0, 0, At, B0); PG8_MMA(0, 1, At, B1); PG8_BAR; PG8_SCHED;
;             PG8_LDA(At, 0, 1); PG8_STAGE(PG8_SB(0, 0), b2, voffB); PG8_STAGE(PG8_SB(0, 1), b2 + hstepB, voffB); PG8_STAGE(PG8_SA(0, 0), a2, voffA);
;             PG8_WAIT_V(8); PG8_WAIT_L(0); PG8_BAR; PG8_MMA(1, 0, At, B0); PG8_MMA(1, 1, At, B1); PG8_BAR; PG8_SCHED;
.LBB0_1822:
	ds_read_b128 v[66:69], v173
	ds_read_b128 v[70:73], v173 offset:1024
	ds_read_b128 v[74:77], v173 offset:2048
	ds_read_b128 v[78:81], v173 offset:3072
	ds_read_b128 v[162:165], v174
	ds_read_b128 v[180:183], v174 offset:1024
	ds_read_b128 v[184:187], v174 offset:2048
	ds_read_b128 v[188:191], v174 offset:3072
	s_add_u32 s22, s16, 0xfff80080
	s_addc_u32 s23, s17, -1
	s_cmp_eq_u32 s50, 28
	s_cselect_b32 s41, s3, s23
	s_cselect_b32 s40, s15, s22
	s_cselect_b32 s23, s13, s49
	s_cselect_b32 s22, s24, s25
	v_lshl_add_u64 v[166:167], s[16:17], 0, v[156:157]
	s_add_i32 m0, s29, 0xc000
	ds_read_b128 v[192:195], v175
	ds_read_b128 v[196:199], v175 offset:1024
	ds_read_b128 v[200:203], v175 offset:2048
	ds_read_b128 v[204:207], v175 offset:3072
	ds_read_b128 v[208:211], v175 offset:4096
	ds_read_b128 v[212:215], v175 offset:5120
	ds_read_b128 v[216:219], v175 offset:6144
	ds_read_b128 v[220:223], v175 offset:7168
	global_load_lds_dwordx4 v[166:167], off
	v_lshl_add_u64 v[166:167], s[16:17], 0, v[154:155]
	s_add_i32 m0, s29, 0xe000
	s_nop 0
	global_load_lds_dwordx4 v[166:167], off
	s_waitcnt vmcnt(8)
	s_waitcnt lgkmcnt(0)
	s_barrier
	v_mfma_f32_16x16x32_bf16 v[142:145], v[66:69], v[192:195], v[142:145]
	v_mfma_f32_16x16x32_bf16 v[138:141], v[74:77], v[192:195], v[138:141]
	v_mfma_f32_16x16x32_bf16 v[126:129], v[66:69], v[200:203], v[126:129]
	v_mfma_f32_16x16x32_bf16 v[122:125], v[74:77], v[200:203], v[122:125]
	v_mfma_f32_16x16x32_bf16 v[110:113], v[66:69], v[208:211], v[110:113]
	v_mfma_f32_16x16x32_bf16 v[106:109], v[74:77], v[208:211], v[106:109]
	v_mfma_f32_16x16x32_bf16 v[94:97], v[66:69], v[216:219], v[94:97]
	v_mfma_f32_16x16x32_bf16 v[90:93], v[74:77], v[216:219], v[90:93]
	v_mfma_f32_16x16x32_bf16 v[142:145], v[70:73], v[196:199], v[142:145]
	v_mfma_f32_16x16x32_bf16 v[138:141], v[78:81], v[196:199], v[138:141]
	v_mfma_f32_16x16x32_bf16 v[126:129], v[70:73], v[204:207], v[126:129]
	v_mfma_f32_16x16x32_bf16 v[122:125], v[78:81], v[204:207], v[122:125]
	v_mfma_f32_16x16x32_bf16 v[110:113], v[70:73], v[212:215], v[110:113]
	v_mfma_f32_16x16x32_bf16 v[106:109], v[78:81], v[212:215], v[106:109]
	v_mfma_f32_16x16x32_bf16 v[94:97], v[70:73], v[220:223], v[94:97]
	v_mfma_f32_16x16x32_bf16 v[90:93], v[78:81], v[220:223], v[90:93]
	v_mfma_f32_16x16x32_bf16 v[134:137], v[162:165], v[192:195], v[134:137]
	v_mfma_f32_16x16x32_bf16 v[130:133], v[184:187], v[192:195], v[130:133]
	v_mfma_f32_16x16x32_bf16 v[118:121], v[162:165], v[200:203], v[118:121]
	v_mfma_f32_16x16x32_bf16 v[114:117], v[184:187], v[200:203], v[114:117]
	v_mfma_f32_16x16x32_bf16 v[102:105], v[162:165], v[208:211], v[102:105]
	v_mfma_f32_16x16x32_bf16 v[98:101], v[184:187], v[208:211], v[98:101]
	v_mfma_f32_16x16x32_bf16 v[86:89], v[162:165], v[216:219], v[86:89]
	v_mfma_f32_16x16x32_bf16 v[82:85], v[184:187], v[216:219], v[82:85]
	v_mfma_f32_16x16x32_bf16 v[134:137], v[180:183], v[196:199], v[134:137]
	v_mfma_f32_16x16x32_bf16 v[130:133], v[188:191], v[196:199], v[130:133]
	v_mfma_f32_16x16x32_bf16 v[118:121], v[180:183], v[204:207], v[118:121]
	v_mfma_f32_16x16x32_bf16 v[114:117], v[188:191], v[204:207], v[114:117]
	v_mfma_f32_16x16x32_bf16 v[102:105], v[180:183], v[212:215], v[102:105]
	v_mfma_f32_16x16x32_bf16 v[98:101], v[188:191], v[212:215], v[98:101]
	v_mfma_f32_16x16x32_bf16 v[86:89], v[180:183], v[220:223], v[86:89]
	v_mfma_f32_16x16x32_bf16 v[82:85], v[188:191], v[220:223], v[82:85]
	s_barrier
	s_add_i32 s51, s44, s26
	v_lshl_add_u64 v[166:167], s[22:23], 0, v[150:151]
	s_mov_b32 m0, s51
	ds_read_b128 v[192:195], v175 offset:16384
	ds_read_b128 v[196:199], v175 offset:17408
	ds_read_b128 v[200:203], v175 offset:18432
	ds_read_b128 v[204:207], v175 offset:19456
	ds_read_b128 v[208:211], v175 offset:20480
	ds_read_b128 v[212:215], v175 offset:21504
	ds_read_b128 v[216:219], v175 offset:22528
	ds_read_b128 v[220:223], v175 offset:23552
	global_load_lds_dwordx4 v[166:167], off
	s_add_i32 m0, s51, 0x2000
	s_add_u32 s52, s22, 0x80000
	v_lshl_add_u64 v[224:225], s[22:23], 0, v[146:147]
	s_addc_u32 s53, s23, 0
	s_add_i32 s51, s45, s26
	global_load_lds_dwordx4 v[224:225], off
	v_lshl_add_u64 v[226:227], s[52:53], 0, v[150:151]
	s_mov_b32 m0, s51
	v_lshl_add_u64 v[228:229], s[40:41], 0, v[148:149]
	global_load_lds_dwordx4 v[226:227], off
	v_lshl_add_u64 v[226:227], s[52:53], 0, v[146:147]
	s_add_i32 m0, s51, 0x2000
	s_nop 0
	global_load_lds_dwordx4 v[226:227], off
	v_lshl_add_u64 v[226:227], s[40:41], 0, v[152:153]
	s_mov_b32 m0, s29
	s_nop 0
	global_load_lds_dwordx4 v[226:227], off
	s_mov_b32 m0, s30
	s_nop 0
	global_load_lds_dwordx4 v[228:229], off
	s_waitcnt vmcnt(8)
	s_waitcnt lgkmcnt(0)
	s_barrier
; #define PG8_STAGE(bufoff, gbase, voff) do { _Pragma("unroll") for (int _i = 0; _i < 2; ++_i) \
;         __builtin_amdgcn_global_load_lds((const unsigned*)((const char*)(gbase) + (voff)[_i]), (LAS unsigned*)(lds + (bufoff) + ldsw + _i * 8192), 16, 0, 0); } while (0)
; #define PG8_LDA(dst, b, h) do { _Pragma("unroll") for (int m = 0; m < 4; ++m) _Pragma("unroll") for (int k = 0; k < 2; ++k) dst[m][k] = *(const LAS bf16x8*)(lds + PG8_SA(b, h) + aoff + m * 2048 + k * 1024); } while (0)
; #define PG8_LDB(dst, b, h) do { _Pragma("unroll") for (int n = 0; n < 2; ++n) _Pragma("unroll") for (int k = 0; k < 2; ++k) dst[n][k] = *(const LAS bf16x8*)(lds + PG8_SB(b, h) + boff + n * 2048 + k * 1024); } while (0)
; #define PG8_MMA(ai, bj, At, Bt) do { __builtin_amdgcn_s_setprio(1); _Pragma("unroll") for (int m = 0; m < 4; ++m) _Pragma("unroll") for (int n = 0; n < 2; ++n) _Pragma("unroll") for (int k = 0; k < 2; ++k) \
;         acc[ai][bj][m][n] = __builtin_amdgcn_mfma_f32_16x16x32_bf16(Bt[n][k], At[m][k], acc[ai][bj][m][n], 0, 0, 0); __builtin_amdgcn_s_setprio(0); } while (0)
; #define PG8_WAIT_V(n) asm volatile("s_waitcnt vmcnt(" #n ")" ::: "memory")
; #define PG8_WAIT_L(n) asm volatile("s_waitcnt lgkmcnt(" #n ")" ::: "memory")
; #define PG8_BAR __builtin_amdgcn_s_barrier()
; #define PG8_SCHED __builtin_amdgcn_sched_barrier(0)
; template <class Epi, class Sched, bool ALIGN_EPI = false, bool SP2 = false>
; __device__ __forceinline__ void gemm_phase(LAS unsigned char* lds, const Gemm g, const Sched& S, const Epi& E) {
;     ...
;             PG8_WAIT_V(8); PG8_WAIT_L(0); PG8_BAR; PG8_MMA(1, 0, At, B0); PG8_MMA(1, 1, At, B1); PG8_BAR; PG8_SCHED;
;             PG8_LDB(B0, 1, 0); PG8_LDB(B1, 1, 1); PG8_SCHED; PG8_LDA(At, 1, 0); PG8_STAGE(PG8_SA(0, 1), a2 + hstep, voffA);
;             PG8_WAIT_V(8); PG8_WAIT_L(0); PG8_BAR; PG8_MMA(0, 0, At, B0); PG8_MMA(0, 1, At, B1); PG8_BAR; PG8_SCHED;
	v_mfma_f32_16x16x32_bf16 v[62:65], v[66:69], v[192:195], v[62:65]
	v_mfma_f32_16x16x32_bf16 v[58:61], v[74:77], v[192:195], v[58:61]
	v_mfma_f32_16x16x32_bf16 v[46:49], v[66:69], v[200:203], v[46:49]
	v_mfma_f32_16x16x32_bf16 v[42:45], v[74:77], v[200:203], v[42:45]
	v_mfma_f32_16x16x32_bf16 v[30:33], v[66:69], v[208:211], v[30:33]
	v_mfma_f32_16x16x32_bf16 v[26:29], v[74:77], v[208:211], v[26:29]
	v_mfma_f32_16x16x32_bf16 v[14:17], v[66:69], v[216:219], v[14:17]
	v_mfma_f32_16x16x32_bf16 v[10:13], v[74:77], v[216:219], v[10:13]
	v_mfma_f32_16x16x32_bf16 v[62:65], v[70:73], v[196:199], v[62:65]
	v_mfma_f32_16x16x32_bf16 v[58:61], v[78:81], v[196:199], v[58:61]
	v_mfma_f32_16x16x32_bf16 v[46:49], v[70:73], v[204:207], v[46:49]
	v_mfma_f32_16x16x32_bf16 v[42:45], v[78:81], v[204:207], v[42:45]
	v_mfma_f32_16x16x32_bf16 v[30:33], v[70:73], v[212:215], v[30:33]
	v_mfma_f32_16x16x32_bf16 v[26:29], v[78:81], v[212:215], v[26:29]
	v_mfma_f32_16x16x32_bf16 v[14:17], v[70:73], v[220:223], v[14:17]
	v_mfma_f32_16x16x32_bf16 v[10:13], v[78:81], v[220:223], v[10:13]
	v_mfma_f32_16x16x32_bf16 v[54:57], v[162:165], v[192:195], v[54:57]
	v_mfma_f32_16x16x32_bf16 v[50:53], v[184:187], v[192:195], v[50:53]
	v_mfma_f32_16x16x32_bf16 v[38:41], v[162:165], v[200:203], v[38:41]
	v_mfma_f32_16x16x32_bf16 v[34:37], v[184:187], v[200:203], v[34:37]
	v_mfma_f32_16x16x32_bf16 v[22:25], v[162:165], v[208:211], v[22:25]
	v_mfma_f32_16x16x32_bf16 v[18:21], v[184:187], v[208:211], v[18:21]
	v_mfma_f32_16x16x32_bf16 v[6:9], v[162:165], v[216:219], v[6:9]
	v_mfma_f32_16x16x32_bf16 v[2:5], v[184:187], v[216:219], v[2:5]
	v_mfma_f32_16x16x32_bf16 v[54:57], v[180:183], v[196:199], v[54:57]
	v_mfma_f32_16x16x32_bf16 v[50:53], v[188:191], v[196:199], v[50:53]
	v_mfma_f32_16x16x32_bf16 v[38:41], v[180:183], v[204:207], v[38:41]
	v_mfma_f32_16x16x32_bf16 v[34:37], v[188:191], v[204:207], v[34:37]
	v_mfma_f32_16x16x32_bf16 v[22:25], v[180:183], v[212:215], v[22:25]
	v_mfma_f32_16x16x32_bf16 v[18:21], v[188:191], v[212:215], v[18:21]
	v_mfma_f32_16x16x32_bf16 v[6:9], v[180:183], v[220:223], v[6:9]
	v_mfma_f32_16x16x32_bf16 v[2:5], v[188:191], v[220:223], v[2:5]
	s_barrier
	s_add_i32 s51, 0, 0x18000
	s_add_i32 s52, 0, 0x1c000
	v_add_u32_e32 v78, s51, v169
	v_add_u32_e32 v168, s52, v169
	ds_read_b128 v[66:69], v78
	ds_read_b128 v[70:73], v78 offset:1024
	ds_read_b128 v[74:77], v78 offset:2048
	ds_read_b128 v[78:81], v78 offset:3072
	ds_read_b128 v[162:165], v168
	ds_read_b128 v[180:183], v168 offset:1024
	ds_read_b128 v[184:187], v168 offset:2048
	ds_read_b128 v[188:191], v168 offset:3072
	s_add_u32 s40, s40, 0x80000
	s_addc_u32 s41, s41, 0
	s_mov_b32 m0, s31
	v_lshl_add_u64 v[230:231], s[40:41], 0, v[152:153]
	ds_read_b128 v[192:195], v175 offset:32768
	ds_read_b128 v[196:199], v175 offset:33792
	ds_read_b128 v[200:203], v175 offset:34816
	ds_read_b128 v[204:207], v175 offset:35840
	ds_read_b128 v[208:211], v175 offset:36864
	ds_read_b128 v[212:215], v175 offset:37888
	ds_read_b128 v[216:219], v175 offset:38912
	ds_read_b128 v[220:223], v175 offset:39936
	global_load_lds_dwordx4 v[230:231], off
	v_lshl_add_u64 v[230:231], s[40:41], 0, v[148:149]
	s_mov_b32 m0, s33
	s_nop 0
	global_load_lds_dwordx4 v[230:231], off
	s_waitcnt vmcnt(8)
	s_waitcnt lgkmcnt(0)
	s_barrier
	v_mfma_f32_16x16x32_bf16 v[142:145], v[66:69], v[192:195], v[142:145]
	v_mfma_f32_16x16x32_bf16 v[138:141], v[74:77], v[192:195], v[138:141]
	v_mfma_f32_16x16x32_bf16 v[126:129], v[66:69], v[200:203], v[126:129]
	v_mfma_f32_16x16x32_bf16 v[122:125], v[74:77], v[200:203], v[122:125]
	v_mfma_f32_16x16x32_bf16 v[110:113], v[66:69], v[208:211], v[110:113]
	v_mfma_f32_16x16x32_bf16 v[106:109], v[74:77], v[208:211], v[106:109]
	v_mfma_f32_16x16x32_bf16 v[94:97], v[66:69], v[216:219], v[94:97]
	v_mfma_f32_16x16x32_bf16 v[90:93], v[74:77], v[216:219], v[90:93]
	v_mfma_f32_16x16x32_bf16 v[142:145], v[70:73], v[196:199], v[142:145]
	v_mfma_f32_16x16x32_bf16 v[138:141], v[78:81], v[196:199], v[138:141]
	v_mfma_f32_16x16x32_bf16 v[126:129], v[70:73], v[204:207], v[126:129]
	v_mfma_f32_16x16x32_bf16 v[122:125], v[78:81], v[204:207], v[122:125]
	v_mfma_f32_16x16x32_bf16 v[110:113], v[70:73], v[212:215], v[110:113]
	v_mfma_f32_16x16x32_bf16 v[106:109], v[78:81], v[212:215], v[106:109]
	v_mfma_f32_16x16x32_bf16 v[94:97], v[70:73], v[220:223], v[94:97]
	v_mfma_f32_16x16x32_bf16 v[90:93], v[78:81], v[220:223], v[90:93]
	v_mfma_f32_16x16x32_bf16 v[134:137], v[162:165], v[192:195], v[134:137]
	v_mfma_f32_16x16x32_bf16 v[130:133], v[184:187], v[192:195], v[130:133]
	v_mfma_f32_16x16x32_bf16 v[118:121], v[162:165], v[200:203], v[118:121]
	v_mfma_f32_16x16x32_bf16 v[114:117], v[184:187], v[200:203], v[114:117]
	v_mfma_f32_16x16x32_bf16 v[102:105], v[162:165], v[208:211], v[102:105]
	v_mfma_f32_16x16x32_bf16 v[98:101], v[184:187], v[208:211], v[98:101]
	v_mfma_f32_16x16x32_bf16 v[86:89], v[162:165], v[216:219], v[86:89]
	v_mfma_f32_16x16x32_bf16 v[82:85], v[184:187], v[216:219], v[82:85]
	v_mfma_f32_16x16x32_bf16 v[134:137], v[180:183], v[196:199], v[134:137]
	v_mfma_f32_16x16x32_bf16 v[130:133], v[188:191], v[196:199], v[130:133]
	v_mfma_f32_16x16x32_bf16 v[118:121], v[180:183], v[204:207], v[118:121]
	v_mfma_f32_16x16x32_bf16 v[114:117], v[188:191], v[204:207], v[114:117]
	v_mfma_f32_16x16x32_bf16 v[102:105], v[180:183], v[212:215], v[102:105]
	v_mfma_f32_16x16x32_bf16 v[98:101], v[188:191], v[212:215], v[98:101]
	v_mfma_f32_16x16x32_bf16 v[86:89], v[180:183], v[220:223], v[86:89]
	v_mfma_f32_16x16x32_bf16 v[82:85], v[188:191], v[220:223], v[82:85]
	s_barrier
; #define PG8_STAGE(bufoff, gbase, voff) do { _Pragma("unroll") for (int _i = 0; _i < 2; ++_i) \
;         __builtin_amdgcn_global_load_lds((const unsigned*)((const char*)(gbase) + (voff)[_i]), (LAS unsigned*)(lds + (bufoff) + ldsw + _i * 8192), 16, 0, 0); } while (0)
; #define PG8_LDA(dst, b, h) do { _Pragma("unroll") for (int m = 0; m < 4; ++m) _Pragma("unroll") for (int k = 0; k < 2; ++k) dst[m][k] = *(const LAS bf16x8*)(lds + PG8_SA(b, h) + aoff + m * 2048 + k * 1024); } while (0)
; #define PG8_MMA(ai, bj, At, Bt) do { __builtin_amdgcn_s_setprio(1); _Pragma("unroll") for (int m = 0; m < 4; ++m) _Pragma("unroll") for (int n = 0; n < 2; ++n) _Pragma("unroll") for (int k = 0; k < 2; ++k) \
;         acc[ai][bj][m][n] = __builtin_amdgcn_mfma_f32_16x16x32_bf16(Bt[n][k], At[m][k], acc[ai][bj][m][n], 0, 0, 0); __builtin_amdgcn_s_setprio(0); } while (0)
; #define PG8_WAIT_V(n) asm volatile("s_waitcnt vmcnt(" #n ")" ::: "memory")
; #define PG8_WAIT_L(n) asm volatile("s_waitcnt lgkmcnt(" #n ")" ::: "memory")
; #define PG8_BAR __builtin_amdgcn_s_barrier()
; #define PG8_SCHED __builtin_amdgcn_sched_barrier(0)
; template <class Epi, class Sched, bool ALIGN_EPI = false, bool SP2 = false>
; __device__ __forceinline__ void gemm_phase(LAS unsigned char* lds, const Gemm g, const Sched& S, const Epi& E) {
;     ...
;             PG8_LDA(At, 1, 1); PG8_STAGE(PG8_SB(1, 0), b3, voffB); PG8_STAGE(PG8_SB(1, 1), b3 + hstepB, voffB); PG8_STAGE(PG8_SA(1, 0), a3, voffA);
;             PG8_WAIT_V(8); PG8_WAIT_L(0); PG8_BAR; PG8_MMA(1, 0, At, B0); PG8_MMA(1, 1, At, B1); PG8_BAR; PG8_SCHED;
;     ...
;         if constexpr (ALIGN_EPI) { if (wr == 0) PG8_BAR; }
	s_add_i32 s40, s51, s26
	v_lshl_add_u64 v[166:167], v[166:167], 0, s[8:9]
	s_mov_b32 m0, s40
	ds_read_b128 v[192:195], v175 offset:49152
	ds_read_b128 v[196:199], v175 offset:50176
	ds_read_b128 v[200:203], v175 offset:51200
	ds_read_b128 v[204:207], v175 offset:52224
	ds_read_b128 v[208:211], v175 offset:53248
	ds_read_b128 v[212:215], v175 offset:54272
	ds_read_b128 v[216:219], v175 offset:55296
	ds_read_b128 v[220:223], v175 offset:56320
	global_load_lds_dwordx4 v[166:167], off
	s_add_i32 m0, s40, 0x2000
	s_add_u32 s22, s22, 0x80080
	v_lshl_add_u64 v[166:167], v[224:225], 0, s[8:9]
	s_addc_u32 s23, s23, 0
	s_add_i32 s40, s52, s26
	global_load_lds_dwordx4 v[166:167], off
	v_lshl_add_u64 v[166:167], s[22:23], 0, v[150:151]
	s_mov_b32 m0, s40
	s_nop 0
	global_load_lds_dwordx4 v[166:167], off
	v_lshl_add_u64 v[166:167], s[22:23], 0, v[146:147]
	s_add_i32 m0, s40, 0x2000
	s_nop 0
	global_load_lds_dwordx4 v[166:167], off
	v_lshl_add_u64 v[166:167], v[226:227], 0, s[8:9]
	s_mov_b32 m0, s42
	s_nop 0
	global_load_lds_dwordx4 v[166:167], off
	v_lshl_add_u64 v[166:167], v[228:229], 0, s[8:9]
	s_mov_b32 m0, s43
	s_nop 0
	global_load_lds_dwordx4 v[166:167], off
	s_waitcnt vmcnt(8)
	s_waitcnt lgkmcnt(0)
	s_barrier
	v_mfma_f32_16x16x32_bf16 v[62:65], v[66:69], v[192:195], v[62:65]
	v_mfma_f32_16x16x32_bf16 v[58:61], v[74:77], v[192:195], v[58:61]
	v_mfma_f32_16x16x32_bf16 v[46:49], v[66:69], v[200:203], v[46:49]
	v_mfma_f32_16x16x32_bf16 v[42:45], v[74:77], v[200:203], v[42:45]
	v_mfma_f32_16x16x32_bf16 v[30:33], v[66:69], v[208:211], v[30:33]
	v_mfma_f32_16x16x32_bf16 v[26:29], v[74:77], v[208:211], v[26:29]
	v_mfma_f32_16x16x32_bf16 v[14:17], v[66:69], v[216:219], v[14:17]
	v_mfma_f32_16x16x32_bf16 v[10:13], v[74:77], v[216:219], v[10:13]
	v_mfma_f32_16x16x32_bf16 v[62:65], v[70:73], v[196:199], v[62:65]
	v_mfma_f32_16x16x32_bf16 v[58:61], v[78:81], v[196:199], v[58:61]
	v_mfma_f32_16x16x32_bf16 v[46:49], v[70:73], v[204:207], v[46:49]
	v_mfma_f32_16x16x32_bf16 v[42:45], v[78:81], v[204:207], v[42:45]
	v_mfma_f32_16x16x32_bf16 v[30:33], v[70:73], v[212:215], v[30:33]
	v_mfma_f32_16x16x32_bf16 v[26:29], v[78:81], v[212:215], v[26:29]
	v_mfma_f32_16x16x32_bf16 v[14:17], v[70:73], v[220:223], v[14:17]
	v_mfma_f32_16x16x32_bf16 v[10:13], v[78:81], v[220:223], v[10:13]
	v_mfma_f32_16x16x32_bf16 v[54:57], v[162:165], v[192:195], v[54:57]
	v_mfma_f32_16x16x32_bf16 v[50:53], v[184:187], v[192:195], v[50:53]
	v_mfma_f32_16x16x32_bf16 v[38:41], v[162:165], v[200:203], v[38:41]
	v_mfma_f32_16x16x32_bf16 v[34:37], v[184:187], v[200:203], v[34:37]
	v_mfma_f32_16x16x32_bf16 v[22:25], v[162:165], v[208:211], v[22:25]
	v_mfma_f32_16x16x32_bf16 v[18:21], v[184:187], v[208:211], v[18:21]
	v_mfma_f32_16x16x32_bf16 v[6:9], v[162:165], v[216:219], v[6:9]
	v_mfma_f32_16x16x32_bf16 v[2:5], v[184:187], v[216:219], v[2:5]
	v_mfma_f32_16x16x32_bf16 v[54:57], v[180:183], v[196:199], v[54:57]
	v_mfma_f32_16x16x32_bf16 v[50:53], v[188:191], v[196:199], v[50:53]
	v_mfma_f32_16x16x32_bf16 v[38:41], v[180:183], v[204:207], v[38:41]
	v_mfma_f32_16x16x32_bf16 v[34:37], v[188:191], v[204:207], v[34:37]
	v_mfma_f32_16x16x32_bf16 v[22:25], v[180:183], v[212:215], v[22:25]
	v_mfma_f32_16x16x32_bf16 v[18:21], v[188:191], v[212:215], v[18:21]
	v_mfma_f32_16x16x32_bf16 v[6:9], v[180:183], v[220:223], v[6:9]
	v_mfma_f32_16x16x32_bf16 v[2:5], v[188:191], v[220:223], v[2:5]
	s_barrier
	s_add_i32 s50, s50, 2
	s_add_u32 s25, s25, 0x100
	s_addc_u32 s49, s49, 0
	s_add_u32 s16, s16, 0x100
	s_addc_u32 s17, s17, 0
	s_cmp_lt_u32 s50, 30
	s_cbranch_scc1 .LBB0_1822
	s_setprio 0
	s_andn2_b64 vcc, exec, s[10:11]
	s_cbranch_vccnz .LBB0_1825
	s_barrier

; #define PG8_STAGE(bufoff, gbase, voff) do { _Pragma("unroll") for (int _i = 0; _i < 2; ++_i) \
;         __builtin_amdgcn_global_load_lds((const unsigned*)((const char*)(gbase) + (voff)[_i]), (LAS unsigned*)(lds + (bufoff) + ldsw + _i * 8192), 16, 0, 0); } while (0)
; #define PG8_LDA(dst, b, h) do { _Pragma("unroll") for (int m = 0; m < 4; ++m) _Pragma("unroll") for (int k = 0; k < 2; ++k) dst[m][k] = *(const LAS bf16x8*)(lds + PG8_SA(b, h) + aoff + m * 2048 + k * 1024); } while (0)
; #define PG8_LDB(dst, b, h) do { _Pragma("unroll") for (int n = 0; n < 2; ++n) _Pragma("unroll") for (int k = 0; k < 2; ++k) dst[n][k] = *(const LAS bf16x8*)(lds + PG8_SB(b, h) + boff + n * 2048 + k * 1024); } while (0)
; #define PG8_MMA(ai, bj, At, Bt) do { __builtin_amdgcn_s_setprio(1); _Pragma("unroll") for (int m = 0; m < 4; ++m) _Pragma("unroll") for (int n = 0; n < 2; ++n) _Pragma("unroll") for (int k = 0; k < 2; ++k) \
;         acc[ai][bj][m][n] = __builtin_amdgcn_mfma_f32_16x16x32_bf16(Bt[n][k], At[m][k], acc[ai][bj][m][n], 0, 0, 0); __builtin_amdgcn_s_setprio(0); } while (0)
; #define PG8_WAIT_V(n) asm volatile("s_waitcnt vmcnt(" #n ")" ::: "memory")
; #define PG8_WAIT_L(n) asm volatile("s_waitcnt lgkmcnt(" #n ")" ::: "memory")
; #define PG8_BAR __builtin_amdgcn_s_barrier()
; template <class Epi, class Sched, bool ALIGN_EPI = false, bool SP2 = false>
; __device__ __forceinline__ void gemm_phase(LAS unsigned char* lds, const Gemm g, const Sched& S, const Epi& E) {
;     ...
;             const bool last = (t == nt - 2);
;             const char* a1 = cA + (size_t)(t + 1) * kstep;
;             const char* a2 = last ? nA : cA + (size_t)(t + 2) * kstep; const char* b2 = last ? nB : cB + (size_t)(t + 2) * kstep;
;             const char* a3 = a2 + kstep; const char* b3 = b2 + kstep;
;             if (last && has_next) S.a_ready(nxt);
;             if constexpr (SP2) {
;             PG8_LDB(B0, 0, 0); PG8_LDB(B1, 0, 1); PG8_SCHED; PG8_LDA(At, 0, 0); PG8_STAGE(PG8_SA(1, 1), a1 + hstep, voffA);
;             PG8_WAIT_V(8); PG8_WAIT_L(0); PG8_BAR; PG8_MMA(0, 0, At, B0); PG8_MMA(0, 1, At, B1); PG8_BAR; PG8_SCHED;
;             PG8_LDA(At, 0, 1); PG8_STAGE(PG8_SB(0, 0), b2, voffB); PG8_STAGE(PG8_SB(0, 1), b2 + hstepB, voffB); PG8_STAGE(PG8_SA(0, 0), a2, voffA);
;             PG8_WAIT_V(8); PG8_WAIT_L(0); PG8_BAR; PG8_MMA(1, 0, At, B0); PG8_MMA(1, 1, At, B1); PG8_BAR; PG8_SCHED;
.LBB0_1896:
	ds_read_b128 v[144:147], v135
	ds_read_b128 v[148:151], v135 offset:1024
	ds_read_b128 v[152:155], v135 offset:2048
	ds_read_b128 v[156:159], v135 offset:3072
	ds_read_b128 v[160:163], v140
	ds_read_b128 v[164:167], v140 offset:1024
	ds_read_b128 v[168:171], v140 offset:2048
	ds_read_b128 v[172:175], v140 offset:3072
	s_add_i32 s40, s14, 2
	s_cmp_lg_u32 s28, s14
	s_cselect_b32 s14, s10, 0
	s_cselect_b32 s15, s11, 0
	s_add_u32 s16, s4, s14
	s_addc_u32 s17, s5, s15
	s_add_u32 s14, s2, s14
	s_addc_u32 s15, s3, s15
	v_lshl_add_u64 v[208:209], v[138:139], 0, s[10:11]
	s_mov_b32 m0, s29
	v_lshl_add_u64 v[208:209], v[208:209], 0, s[12:13]
	ds_read_b128 v[176:179], v141
	ds_read_b128 v[180:183], v141 offset:1024
	ds_read_b128 v[184:187], v141 offset:2048
	ds_read_b128 v[188:191], v141 offset:3072
	ds_read_b128 v[192:195], v141 offset:4096
	ds_read_b128 v[196:199], v141 offset:5120
	ds_read_b128 v[200:203], v141 offset:6144
	ds_read_b128 v[204:207], v141 offset:7168
	global_load_lds_dwordx4 v[208:209], off
	v_lshl_add_u64 v[208:209], v[136:137], 0, s[10:11]
	v_lshl_add_u64 v[208:209], v[208:209], 0, s[12:13]
	s_mov_b32 m0, s30
	s_nop 0
	global_load_lds_dwordx4 v[208:209], off
	s_waitcnt vmcnt(8)
	s_waitcnt lgkmcnt(0)
	s_barrier
	s_setprio 1
	v_mfma_f32_16x16x32_bf16 v[126:129], v[144:147], v[176:179], v[126:129]
	v_mfma_f32_16x16x32_bf16 v[94:97], v[152:155], v[176:179], v[94:97]
	v_mfma_f32_16x16x32_bf16 v[122:125], v[144:147], v[184:187], v[122:125]
	v_mfma_f32_16x16x32_bf16 v[90:93], v[152:155], v[184:187], v[90:93]
	v_mfma_f32_16x16x32_bf16 v[118:121], v[144:147], v[192:195], v[118:121]
	v_mfma_f32_16x16x32_bf16 v[86:89], v[152:155], v[192:195], v[86:89]
	v_mfma_f32_16x16x32_bf16 v[114:117], v[144:147], v[200:203], v[114:117]
	v_mfma_f32_16x16x32_bf16 v[82:85], v[152:155], v[200:203], v[82:85]
	v_mfma_f32_16x16x32_bf16 v[126:129], v[148:151], v[180:183], v[126:129]
	v_mfma_f32_16x16x32_bf16 v[94:97], v[156:159], v[180:183], v[94:97]
	v_mfma_f32_16x16x32_bf16 v[122:125], v[148:151], v[188:191], v[122:125]
	v_mfma_f32_16x16x32_bf16 v[90:93], v[156:159], v[188:191], v[90:93]
	v_mfma_f32_16x16x32_bf16 v[118:121], v[148:151], v[196:199], v[118:121]
	v_mfma_f32_16x16x32_bf16 v[86:89], v[156:159], v[196:199], v[86:89]
	v_mfma_f32_16x16x32_bf16 v[114:117], v[148:151], v[204:207], v[114:117]
	v_mfma_f32_16x16x32_bf16 v[82:85], v[156:159], v[204:207], v[82:85]
	s_setprio 0
	s_setprio 1
	v_mfma_f32_16x16x32_bf16 v[70:73], v[160:163], v[176:179], v[70:73]
	v_mfma_f32_16x16x32_bf16 v[42:45], v[168:171], v[176:179], v[42:45]
	v_mfma_f32_16x16x32_bf16 v[62:65], v[160:163], v[184:187], v[62:65]
	v_mfma_f32_16x16x32_bf16 v[34:37], v[168:171], v[184:187], v[34:37]
	v_mfma_f32_16x16x32_bf16 v[54:57], v[160:163], v[192:195], v[54:57]
	v_mfma_f32_16x16x32_bf16 v[26:29], v[168:171], v[192:195], v[26:29]
	v_mfma_f32_16x16x32_bf16 v[50:53], v[160:163], v[200:203], v[50:53]
	v_mfma_f32_16x16x32_bf16 v[18:21], v[168:171], v[200:203], v[18:21]
	v_mfma_f32_16x16x32_bf16 v[70:73], v[164:167], v[180:183], v[70:73]
	v_mfma_f32_16x16x32_bf16 v[42:45], v[172:175], v[180:183], v[42:45]
	v_mfma_f32_16x16x32_bf16 v[62:65], v[164:167], v[188:191], v[62:65]
	v_mfma_f32_16x16x32_bf16 v[34:37], v[172:175], v[188:191], v[34:37]
	v_mfma_f32_16x16x32_bf16 v[54:57], v[164:167], v[196:199], v[54:57]
	v_mfma_f32_16x16x32_bf16 v[26:29], v[172:175], v[196:199], v[26:29]
	v_mfma_f32_16x16x32_bf16 v[50:53], v[164:167], v[204:207], v[50:53]
	v_mfma_f32_16x16x32_bf16 v[18:21], v[172:175], v[204:207], v[18:21]
	s_setprio 0
	s_barrier
	s_mov_b32 m0, s31
	v_lshl_add_u64 v[208:209], s[14:15], 0, v[132:133]
	s_add_u32 s42, s14, 0x160000
	ds_read_b128 v[176:179], v141 offset:16384
	ds_read_b128 v[180:183], v141 offset:17408
	ds_read_b128 v[184:187], v141 offset:18432
	ds_read_b128 v[188:191], v141 offset:19456
	ds_read_b128 v[192:195], v141 offset:20480
	ds_read_b128 v[196:199], v141 offset:21504
	ds_read_b128 v[200:203], v141 offset:22528
	ds_read_b128 v[204:207], v141 offset:23552
	global_load_lds_dwordx4 v[208:209], off
	v_lshl_add_u64 v[210:211], s[14:15], 0, v[130:131]
	s_mov_b32 m0, s33
	s_addc_u32 s43, s15, 0
	global_load_lds_dwordx4 v[210:211], off
	v_lshl_add_u64 v[212:213], s[42:43], 0, v[132:133]
	s_mov_b32 m0, s34
	v_lshl_add_u64 v[214:215], s[16:17], 0, v[130:131]
	global_load_lds_dwordx4 v[212:213], off
	v_lshl_add_u64 v[212:213], s[42:43], 0, v[130:131]
	s_mov_b32 m0, s35
	s_nop 0
	global_load_lds_dwordx4 v[212:213], off
	v_lshl_add_u64 v[212:213], s[16:17], 0, v[132:133]
	s_mov_b32 m0, s20
	s_nop 0
	global_load_lds_dwordx4 v[212:213], off
	s_mov_b32 m0, s22
	s_nop 0
	global_load_lds_dwordx4 v[214:215], off
	s_waitcnt vmcnt(8)
	s_waitcnt lgkmcnt(0)
	s_barrier
; #define PG8_STAGE(bufoff, gbase, voff) do { _Pragma("unroll") for (int _i = 0; _i < 2; ++_i) \
;         __builtin_amdgcn_global_load_lds((const unsigned*)((const char*)(gbase) + (voff)[_i]), (LAS unsigned*)(lds + (bufoff) + ldsw + _i * 8192), 16, 0, 0); } while (0)
; #define PG8_LDA(dst, b, h) do { _Pragma("unroll") for (int m = 0; m < 4; ++m) _Pragma("unroll") for (int k = 0; k < 2; ++k) dst[m][k] = *(const LAS bf16x8*)(lds + PG8_SA(b, h) + aoff + m * 2048 + k * 1024); } while (0)
; #define PG8_LDB(dst, b, h) do { _Pragma("unroll") for (int n = 0; n < 2; ++n) _Pragma("unroll") for (int k = 0; k < 2; ++k) dst[n][k] = *(const LAS bf16x8*)(lds + PG8_SB(b, h) + boff + n * 2048 + k * 1024); } while (0)
; #define PG8_MMA(ai, bj, At, Bt) do { __builtin_amdgcn_s_setprio(1); _Pragma("unroll") for (int m = 0; m < 4; ++m) _Pragma("unroll") for (int n = 0; n < 2; ++n) _Pragma("unroll") for (int k = 0; k < 2; ++k) \
;         acc[ai][bj][m][n] = __builtin_amdgcn_mfma_f32_16x16x32_bf16(Bt[n][k], At[m][k], acc[ai][bj][m][n], 0, 0, 0); __builtin_amdgcn_s_setprio(0); } while (0)
; #define PG8_WAIT_V(n) asm volatile("s_waitcnt vmcnt(" #n ")" ::: "memory")
; #define PG8_WAIT_L(n) asm volatile("s_waitcnt lgkmcnt(" #n ")" ::: "memory")
; #define PG8_BAR __builtin_amdgcn_s_barrier()
; #define PG8_SCHED __builtin_amdgcn_sched_barrier(0)
; template <class Epi, class Sched, bool ALIGN_EPI = false, bool SP2 = false>
; __device__ __forceinline__ void gemm_phase(LAS unsigned char* lds, const Gemm g, const Sched& S, const Epi& E) {
;     ...
;             PG8_WAIT_V(8); PG8_WAIT_L(0); PG8_BAR; PG8_MMA(1, 0, At, B0); PG8_MMA(1, 1, At, B1); PG8_BAR; PG8_SCHED;
;             PG8_LDB(B0, 1, 0); PG8_LDB(B1, 1, 1); PG8_SCHED; PG8_LDA(At, 1, 0); PG8_STAGE(PG8_SA(0, 1), a2 + hstep, voffA);
;             PG8_WAIT_V(8); PG8_WAIT_L(0); PG8_BAR; PG8_MMA(0, 0, At, B0); PG8_MMA(0, 1, At, B1); PG8_BAR; PG8_SCHED;
	s_setprio 1
	v_mfma_f32_16x16x32_bf16 v[110:113], v[144:147], v[176:179], v[110:113]
	v_mfma_f32_16x16x32_bf16 v[78:81], v[152:155], v[176:179], v[78:81]
	v_mfma_f32_16x16x32_bf16 v[106:109], v[144:147], v[184:187], v[106:109]
	v_mfma_f32_16x16x32_bf16 v[74:77], v[152:155], v[184:187], v[74:77]
	v_mfma_f32_16x16x32_bf16 v[102:105], v[144:147], v[192:195], v[102:105]
	v_mfma_f32_16x16x32_bf16 v[66:69], v[152:155], v[192:195], v[66:69]
	v_mfma_f32_16x16x32_bf16 v[98:101], v[144:147], v[200:203], v[98:101]
	v_mfma_f32_16x16x32_bf16 v[58:61], v[152:155], v[200:203], v[58:61]
	v_mfma_f32_16x16x32_bf16 v[110:113], v[148:151], v[180:183], v[110:113]
	v_mfma_f32_16x16x32_bf16 v[78:81], v[156:159], v[180:183], v[78:81]
	v_mfma_f32_16x16x32_bf16 v[106:109], v[148:151], v[188:191], v[106:109]
	v_mfma_f32_16x16x32_bf16 v[74:77], v[156:159], v[188:191], v[74:77]
	v_mfma_f32_16x16x32_bf16 v[102:105], v[148:151], v[196:199], v[102:105]
	v_mfma_f32_16x16x32_bf16 v[66:69], v[156:159], v[196:199], v[66:69]
	v_mfma_f32_16x16x32_bf16 v[98:101], v[148:151], v[204:207], v[98:101]
	v_mfma_f32_16x16x32_bf16 v[58:61], v[156:159], v[204:207], v[58:61]
	s_setprio 0
	s_setprio 1
	v_mfma_f32_16x16x32_bf16 v[46:49], v[160:163], v[176:179], v[46:49]
	v_mfma_f32_16x16x32_bf16 v[14:17], v[168:171], v[176:179], v[14:17]
	v_mfma_f32_16x16x32_bf16 v[38:41], v[160:163], v[184:187], v[38:41]
	v_mfma_f32_16x16x32_bf16 v[10:13], v[168:171], v[184:187], v[10:13]
	v_mfma_f32_16x16x32_bf16 v[30:33], v[160:163], v[192:195], v[30:33]
	v_mfma_f32_16x16x32_bf16 v[6:9], v[168:171], v[192:195], v[6:9]
	v_mfma_f32_16x16x32_bf16 v[22:25], v[160:163], v[200:203], v[22:25]
	v_mfma_f32_16x16x32_bf16 v[2:5], v[168:171], v[200:203], v[2:5]
	v_mfma_f32_16x16x32_bf16 v[46:49], v[164:167], v[180:183], v[46:49]
	v_mfma_f32_16x16x32_bf16 v[14:17], v[172:175], v[180:183], v[14:17]
	v_mfma_f32_16x16x32_bf16 v[38:41], v[164:167], v[188:191], v[38:41]
	v_mfma_f32_16x16x32_bf16 v[10:13], v[172:175], v[188:191], v[10:13]
	v_mfma_f32_16x16x32_bf16 v[30:33], v[164:167], v[196:199], v[30:33]
	v_mfma_f32_16x16x32_bf16 v[6:9], v[172:175], v[196:199], v[6:9]
	v_mfma_f32_16x16x32_bf16 v[22:25], v[164:167], v[204:207], v[22:25]
	v_mfma_f32_16x16x32_bf16 v[2:5], v[172:175], v[204:207], v[2:5]
	s_setprio 0
	s_barrier
	ds_read_b128 v[144:147], v142
	ds_read_b128 v[148:151], v142 offset:1024
	ds_read_b128 v[152:155], v142 offset:2048
	ds_read_b128 v[156:159], v142 offset:3072
	ds_read_b128 v[160:163], v143
	ds_read_b128 v[164:167], v143 offset:1024
	ds_read_b128 v[168:171], v143 offset:2048
	ds_read_b128 v[172:175], v143 offset:3072
	s_add_u32 s16, s16, 0x160000
	s_addc_u32 s17, s17, 0
	s_mov_b32 m0, s23
	v_lshl_add_u64 v[216:217], s[16:17], 0, v[132:133]
	ds_read_b128 v[176:179], v141 offset:32768
	ds_read_b128 v[180:183], v141 offset:33792
	ds_read_b128 v[184:187], v141 offset:34816
	ds_read_b128 v[188:191], v141 offset:35840
	ds_read_b128 v[192:195], v141 offset:36864
	ds_read_b128 v[196:199], v141 offset:37888
	ds_read_b128 v[200:203], v141 offset:38912
	ds_read_b128 v[204:207], v141 offset:39936
	global_load_lds_dwordx4 v[216:217], off
	v_lshl_add_u64 v[216:217], s[16:17], 0, v[130:131]
	s_mov_b32 m0, s24
	s_nop 0
	global_load_lds_dwordx4 v[216:217], off
	s_waitcnt vmcnt(8)
	s_waitcnt lgkmcnt(0)
	s_barrier
	s_setprio 1
	v_mfma_f32_16x16x32_bf16 v[126:129], v[144:147], v[176:179], v[126:129]
	v_mfma_f32_16x16x32_bf16 v[94:97], v[152:155], v[176:179], v[94:97]
	v_mfma_f32_16x16x32_bf16 v[122:125], v[144:147], v[184:187], v[122:125]
	v_mfma_f32_16x16x32_bf16 v[90:93], v[152:155], v[184:187], v[90:93]
	v_mfma_f32_16x16x32_bf16 v[118:121], v[144:147], v[192:195], v[118:121]
	v_mfma_f32_16x16x32_bf16 v[86:89], v[152:155], v[192:195], v[86:89]
	v_mfma_f32_16x16x32_bf16 v[114:117], v[144:147], v[200:203], v[114:117]
	v_mfma_f32_16x16x32_bf16 v[82:85], v[152:155], v[200:203], v[82:85]
	v_mfma_f32_16x16x32_bf16 v[126:129], v[148:151], v[180:183], v[126:129]
	v_mfma_f32_16x16x32_bf16 v[94:97], v[156:159], v[180:183], v[94:97]
	v_mfma_f32_16x16x32_bf16 v[122:125], v[148:151], v[188:191], v[122:125]
	v_mfma_f32_16x16x32_bf16 v[90:93], v[156:159], v[188:191], v[90:93]
	v_mfma_f32_16x16x32_bf16 v[118:121], v[148:151], v[196:199], v[118:121]
	v_mfma_f32_16x16x32_bf16 v[86:89], v[156:159], v[196:199], v[86:89]
	v_mfma_f32_16x16x32_bf16 v[114:117], v[148:151], v[204:207], v[114:117]
	v_mfma_f32_16x16x32_bf16 v[82:85], v[156:159], v[204:207], v[82:85]
	s_setprio 0
	s_setprio 1
	v_mfma_f32_16x16x32_bf16 v[70:73], v[160:163], v[176:179], v[70:73]
	v_mfma_f32_16x16x32_bf16 v[42:45], v[168:171], v[176:179], v[42:45]
	v_mfma_f32_16x16x32_bf16 v[62:65], v[160:163], v[184:187], v[62:65]
	v_mfma_f32_16x16x32_bf16 v[34:37], v[168:171], v[184:187], v[34:37]
	v_mfma_f32_16x16x32_bf16 v[54:57], v[160:163], v[192:195], v[54:57]
	v_mfma_f32_16x16x32_bf16 v[26:29], v[168:171], v[192:195], v[26:29]
	v_mfma_f32_16x16x32_bf16 v[50:53], v[160:163], v[200:203], v[50:53]
	v_mfma_f32_16x16x32_bf16 v[18:21], v[168:171], v[200:203], v[18:21]
	v_mfma_f32_16x16x32_bf16 v[70:73], v[164:167], v[180:183], v[70:73]
	v_mfma_f32_16x16x32_bf16 v[42:45], v[172:175], v[180:183], v[42:45]
	v_mfma_f32_16x16x32_bf16 v[62:65], v[164:167], v[188:191], v[62:65]
	v_mfma_f32_16x16x32_bf16 v[34:37], v[172:175], v[188:191], v[34:37]
	v_mfma_f32_16x16x32_bf16 v[54:57], v[164:167], v[196:199], v[54:57]
	v_mfma_f32_16x16x32_bf16 v[26:29], v[172:175], v[196:199], v[26:29]
	v_mfma_f32_16x16x32_bf16 v[50:53], v[164:167], v[204:207], v[50:53]
	v_mfma_f32_16x16x32_bf16 v[18:21], v[172:175], v[204:207], v[18:21]
	s_setprio 0
	s_barrier
; #define PG8_STAGE(bufoff, gbase, voff) do { _Pragma("unroll") for (int _i = 0; _i < 2; ++_i) \
;         __builtin_amdgcn_global_load_lds((const unsigned*)((const char*)(gbase) + (voff)[_i]), (LAS unsigned*)(lds + (bufoff) + ldsw + _i * 8192), 16, 0, 0); } while (0)
; #define PG8_LDA(dst, b, h) do { _Pragma("unroll") for (int m = 0; m < 4; ++m) _Pragma("unroll") for (int k = 0; k < 2; ++k) dst[m][k] = *(const LAS bf16x8*)(lds + PG8_SA(b, h) + aoff + m * 2048 + k * 1024); } while (0)
; #define PG8_MMA(ai, bj, At, Bt) do { __builtin_amdgcn_s_setprio(1); _Pragma("unroll") for (int m = 0; m < 4; ++m) _Pragma("unroll") for (int n = 0; n < 2; ++n) _Pragma("unroll") for (int k = 0; k < 2; ++k) \
;         acc[ai][bj][m][n] = __builtin_amdgcn_mfma_f32_16x16x32_bf16(Bt[n][k], At[m][k], acc[ai][bj][m][n], 0, 0, 0); __builtin_amdgcn_s_setprio(0); } while (0)
; #define PG8_WAIT_V(n) asm volatile("s_waitcnt vmcnt(" #n ")" ::: "memory")
; #define PG8_WAIT_L(n) asm volatile("s_waitcnt lgkmcnt(" #n ")" ::: "memory")
; #define PG8_BAR __builtin_amdgcn_s_barrier()
; #define PG8_SCHED __builtin_amdgcn_sched_barrier(0)
; template <class Epi, class Sched, bool ALIGN_EPI = false, bool SP2 = false>
; __device__ __forceinline__ void gemm_phase(LAS unsigned char* lds, const Gemm g, const Sched& S, const Epi& E) {
;     ...
;             PG8_LDA(At, 1, 1); PG8_STAGE(PG8_SB(1, 0), b3, voffB); PG8_STAGE(PG8_SB(1, 1), b3 + hstepB, voffB); PG8_STAGE(PG8_SA(1, 0), a3, voffA);
;             PG8_WAIT_V(8); PG8_WAIT_L(0); PG8_BAR; PG8_MMA(1, 0, At, B0); PG8_MMA(1, 1, At, B1); PG8_BAR; PG8_SCHED;
;     ...
;         if constexpr (ALIGN_EPI) { if (wr == 0) PG8_BAR; }
	s_mov_b32 m0, s36
	v_lshl_add_u64 v[208:209], v[208:209], 0, s[8:9]
	s_add_u32 s14, s14, 0x160080
	ds_read_b128 v[176:179], v141 offset:49152
	ds_read_b128 v[180:183], v141 offset:50176
	ds_read_b128 v[184:187], v141 offset:51200
	ds_read_b128 v[188:191], v141 offset:52224
	ds_read_b128 v[192:195], v141 offset:53248
	ds_read_b128 v[196:199], v141 offset:54272
	ds_read_b128 v[200:203], v141 offset:55296
	ds_read_b128 v[204:207], v141 offset:56320
	global_load_lds_dwordx4 v[208:209], off
	v_lshl_add_u64 v[208:209], v[210:211], 0, s[8:9]
	s_mov_b32 m0, s37
	s_addc_u32 s15, s15, 0
	global_load_lds_dwordx4 v[208:209], off
	v_lshl_add_u64 v[208:209], s[14:15], 0, v[132:133]
	s_mov_b32 m0, s38
	s_nop 0
	global_load_lds_dwordx4 v[208:209], off
	v_lshl_add_u64 v[208:209], s[14:15], 0, v[130:131]
	s_mov_b32 m0, s39
	s_nop 0
	global_load_lds_dwordx4 v[208:209], off
	v_lshl_add_u64 v[208:209], v[212:213], 0, s[8:9]
	s_mov_b32 m0, s26
	s_nop 0
	global_load_lds_dwordx4 v[208:209], off
	v_lshl_add_u64 v[208:209], v[214:215], 0, s[8:9]
	s_mov_b32 m0, s27
	s_nop 0
	global_load_lds_dwordx4 v[208:209], off
	s_waitcnt vmcnt(8)
	s_waitcnt lgkmcnt(0)
	s_barrier
	s_setprio 1
	v_mfma_f32_16x16x32_bf16 v[110:113], v[144:147], v[176:179], v[110:113]
	v_mfma_f32_16x16x32_bf16 v[78:81], v[152:155], v[176:179], v[78:81]
	v_mfma_f32_16x16x32_bf16 v[106:109], v[144:147], v[184:187], v[106:109]
	v_mfma_f32_16x16x32_bf16 v[74:77], v[152:155], v[184:187], v[74:77]
	v_mfma_f32_16x16x32_bf16 v[102:105], v[144:147], v[192:195], v[102:105]
	v_mfma_f32_16x16x32_bf16 v[66:69], v[152:155], v[192:195], v[66:69]
	v_mfma_f32_16x16x32_bf16 v[98:101], v[144:147], v[200:203], v[98:101]
	v_mfma_f32_16x16x32_bf16 v[58:61], v[152:155], v[200:203], v[58:61]
	v_mfma_f32_16x16x32_bf16 v[110:113], v[148:151], v[180:183], v[110:113]
	v_mfma_f32_16x16x32_bf16 v[78:81], v[156:159], v[180:183], v[78:81]
	v_mfma_f32_16x16x32_bf16 v[106:109], v[148:151], v[188:191], v[106:109]
	v_mfma_f32_16x16x32_bf16 v[74:77], v[156:159], v[188:191], v[74:77]
	v_mfma_f32_16x16x32_bf16 v[102:105], v[148:151], v[196:199], v[102:105]
	v_mfma_f32_16x16x32_bf16 v[66:69], v[156:159], v[196:199], v[66:69]
	v_mfma_f32_16x16x32_bf16 v[98:101], v[148:151], v[204:207], v[98:101]
	v_mfma_f32_16x16x32_bf16 v[58:61], v[156:159], v[204:207], v[58:61]
	s_setprio 0
	s_setprio 1
	v_mfma_f32_16x16x32_bf16 v[46:49], v[160:163], v[176:179], v[46:49]
	v_mfma_f32_16x16x32_bf16 v[14:17], v[168:171], v[176:179], v[14:17]
	v_mfma_f32_16x16x32_bf16 v[38:41], v[160:163], v[184:187], v[38:41]
	v_mfma_f32_16x16x32_bf16 v[10:13], v[168:171], v[184:187], v[10:13]
	v_mfma_f32_16x16x32_bf16 v[30:33], v[160:163], v[192:195], v[30:33]
	v_mfma_f32_16x16x32_bf16 v[6:9], v[168:171], v[192:195], v[6:9]
	v_mfma_f32_16x16x32_bf16 v[22:25], v[160:163], v[200:203], v[22:25]
	v_mfma_f32_16x16x32_bf16 v[2:5], v[168:171], v[200:203], v[2:5]
	v_mfma_f32_16x16x32_bf16 v[46:49], v[164:167], v[180:183], v[46:49]
	v_mfma_f32_16x16x32_bf16 v[14:17], v[172:175], v[180:183], v[14:17]
	v_mfma_f32_16x16x32_bf16 v[38:41], v[164:167], v[188:191], v[38:41]
	v_mfma_f32_16x16x32_bf16 v[10:13], v[172:175], v[188:191], v[10:13]
	v_mfma_f32_16x16x32_bf16 v[30:33], v[164:167], v[196:199], v[30:33]
	v_mfma_f32_16x16x32_bf16 v[6:9], v[172:175], v[196:199], v[6:9]
	v_mfma_f32_16x16x32_bf16 v[22:25], v[164:167], v[204:207], v[22:25]
	v_mfma_f32_16x16x32_bf16 v[2:5], v[172:175], v[204:207], v[2:5]
	s_setprio 0
	s_barrier
	s_add_u32 s10, s10, 0x100
	s_addc_u32 s11, s11, 0
	s_cmp_lt_u32 s40, s25
	s_mov_b32 s14, s40
	s_cbranch_scc1 .LBB0_1896
	v_readlane_b32 s30, v252, 2
	v_readlane_b32 s34, v252, 37
	s_cmpk_gt_u32 s19, 0xff
	v_readlane_b32 s31, v252, 3
	v_readlane_b32 s35, v252, 38
	s_cbranch_scc1 .LBB0_1899
	s_barrier

;     __device__ bool next(int i, Unit& u) const { if (i != 0 || c >= 128) return false; const int t = c >> 2; u.pm = t & 3; u.pn = t >> 2; u.koff = koff_bytes; u.q = c & 3; return true; }
; #define PG8_STAGE(bufoff, gbase, voff) do { _Pragma("unroll") for (int _i = 0; _i < 2; ++_i) \
;         __builtin_amdgcn_global_load_lds((const unsigned*)((const char*)(gbase) + (voff)[_i]), (LAS unsigned*)(lds + (bufoff) + ldsw + _i * 8192), 16, 0, 0); } while (0)
; #define PG8_LDA(dst, b, h) do { _Pragma("unroll") for (int m = 0; m < 4; ++m) _Pragma("unroll") for (int k = 0; k < 2; ++k) dst[m][k] = *(const LAS bf16x8*)(lds + PG8_SA(b, h) + aoff + m * 2048 + k * 1024); } while (0)
; #define PG8_LDB(dst, b, h) do { _Pragma("unroll") for (int n = 0; n < 2; ++n) _Pragma("unroll") for (int k = 0; k < 2; ++k) dst[n][k] = *(const LAS bf16x8*)(lds + PG8_SB(b, h) + boff + n * 2048 + k * 1024); } while (0)
; #define PG8_WAIT_V(n) asm volatile("s_waitcnt vmcnt(" #n ")" ::: "memory")
; template <class Epi, class Sched, bool ALIGN_EPI = false, bool SP2 = false>
; __device__ __forceinline__ void gemm_phase(LAS unsigned char* lds, const Gemm g, const Sched& S, const Epi& E) {
;     ...
;         const bool has_next = S.next(ui + 1, nxt);
;         const char* nA = has_next ? (const char*)g.A + (size_t)nxt.pm * tstep + nxt.koff : cA; const char* nB = has_next ? (const char*)g.Bt + (size_t)nxt.pn * tstep + nxt.koff : cB;
;         for (int t = 0; t < nt; t += 2) {
;             const bool last = (t == nt - 2);
;             const char* a1 = cA + (size_t)(t + 1) * kstep;
;             const char* a2 = last ? nA : cA + (size_t)(t + 2) * kstep; const char* b2 = last ? nB : cB + (size_t)(t + 2) * kstep;
;             const char* a3 = a2 + kstep; const char* b3 = b2 + kstep;
;             if (last && has_next) S.a_ready(nxt);
;             if constexpr (SP2) {
;             PG8_LDB(B0, 0, 0); PG8_LDB(B1, 0, 1); PG8_SCHED; PG8_LDA(At, 0, 0); PG8_STAGE(PG8_SA(1, 1), a1 + hstep, voffA);
;             PG8_WAIT_V(8); PG8_WAIT_L(0); PG8_BAR; PG8_MMA(0, 0, At, B0); PG8_MMA(0, 1, At, B1); PG8_BAR; PG8_SCHED;
;             PG8_LDA(At, 0, 1); PG8_STAGE(PG8_SB(0, 0), b2, voffB); PG8_STAGE(PG8_SB(0, 1), b2 + hstepB, voffB); PG8_STAGE(PG8_SA(0, 0), a2, voffA);
;             PG8_WAIT_V(8); PG8_WAIT_L(0); PG8_BAR; PG8_MMA(1, 0, At, B0); PG8_MMA(1, 1, At, B1); PG8_BAR; PG8_SCHED;
.Lprio_1926:
	ds_read_b128 v[130:133], v196
	ds_read_b128 v[134:137], v196 offset:1024
	ds_read_b128 v[138:141], v196 offset:2048
	ds_read_b128 v[142:145], v196 offset:3072
	ds_read_b128 v[166:169], v197
	ds_read_b128 v[170:173], v197 offset:1024
	ds_read_b128 v[174:177], v197 offset:2048
	ds_read_b128 v[178:181], v197 offset:3072
	s_add_u32 s20, s18, 0x100
	s_addc_u32 s21, s19, 0
	s_cmpk_eq_i32 s25, 0x54
	s_cselect_b32 s47, s17, s21
	s_cselect_b32 s46, s16, s20
	s_cselect_b32 s23, s3, s24
	s_cselect_b32 s22, s2, s5
	v_lshl_add_u64 v[190:191], s[18:19], 0, v[160:161]
	s_add_i32 m0, s27, 0xc000
	ds_read_b128 v[182:185], v198
	ds_read_b128 v[186:189], v198 offset:1024
	ds_read_b128 v[202:205], v198 offset:2048
	ds_read_b128 v[206:209], v198 offset:3072
	ds_read_b128 v[210:213], v198 offset:4096
	ds_read_b128 v[214:217], v198 offset:5120
	ds_read_b128 v[218:221], v198 offset:6144
	ds_read_b128 v[222:225], v198 offset:7168
	global_load_lds_dwordx4 v[190:191], off
	v_lshl_add_u64 v[190:191], s[18:19], 0, v[158:159]
	s_add_i32 m0, s27, 0xe000
	s_nop 0
	global_load_lds_dwordx4 v[190:191], off
	s_waitcnt lgkmcnt(0)
	s_barrier
	v_mfma_f32_16x16x32_bf16 v[126:129], v[130:133], v[182:185], 0
	v_mfma_f32_16x16x32_bf16 v[122:125], v[138:141], v[182:185], 0
	v_mfma_f32_16x16x32_bf16 v[110:113], v[130:133], v[202:205], 0
	v_mfma_f32_16x16x32_bf16 v[106:109], v[138:141], v[202:205], 0
	v_mfma_f32_16x16x32_bf16 v[94:97], v[130:133], v[210:213], 0
	v_mfma_f32_16x16x32_bf16 v[90:93], v[138:141], v[210:213], 0
	v_mfma_f32_16x16x32_bf16 v[78:81], v[130:133], v[218:221], 0
	v_mfma_f32_16x16x32_bf16 v[74:77], v[138:141], v[218:221], 0
	v_mfma_f32_16x16x32_bf16 v[126:129], v[134:137], v[186:189], v[126:129]
	v_mfma_f32_16x16x32_bf16 v[122:125], v[142:145], v[186:189], v[122:125]
	v_mfma_f32_16x16x32_bf16 v[110:113], v[134:137], v[206:209], v[110:113]
	v_mfma_f32_16x16x32_bf16 v[106:109], v[142:145], v[206:209], v[106:109]
	v_mfma_f32_16x16x32_bf16 v[94:97], v[134:137], v[214:217], v[94:97]
	v_mfma_f32_16x16x32_bf16 v[90:93], v[142:145], v[214:217], v[90:93]
	v_mfma_f32_16x16x32_bf16 v[78:81], v[134:137], v[222:225], v[78:81]
	v_mfma_f32_16x16x32_bf16 v[74:77], v[142:145], v[222:225], v[74:77]
	v_mfma_f32_16x16x32_bf16 v[118:121], v[166:169], v[182:185], 0
	v_mfma_f32_16x16x32_bf16 v[114:117], v[174:177], v[182:185], 0
	v_mfma_f32_16x16x32_bf16 v[102:105], v[166:169], v[202:205], 0
	v_mfma_f32_16x16x32_bf16 v[98:101], v[174:177], v[202:205], 0
	v_mfma_f32_16x16x32_bf16 v[86:89], v[166:169], v[210:213], 0
	v_mfma_f32_16x16x32_bf16 v[82:85], v[174:177], v[210:213], 0
	v_mfma_f32_16x16x32_bf16 v[70:73], v[166:169], v[218:221], 0
	v_mfma_f32_16x16x32_bf16 v[66:69], v[174:177], v[218:221], 0
	v_mfma_f32_16x16x32_bf16 v[118:121], v[170:173], v[186:189], v[118:121]
	v_mfma_f32_16x16x32_bf16 v[114:117], v[178:181], v[186:189], v[114:117]
	v_mfma_f32_16x16x32_bf16 v[102:105], v[170:173], v[206:209], v[102:105]
	v_mfma_f32_16x16x32_bf16 v[98:101], v[178:181], v[206:209], v[98:101]
	v_mfma_f32_16x16x32_bf16 v[86:89], v[170:173], v[214:217], v[86:89]
	v_mfma_f32_16x16x32_bf16 v[82:85], v[178:181], v[214:217], v[82:85]
	v_mfma_f32_16x16x32_bf16 v[70:73], v[170:173], v[222:225], v[70:73]
	v_mfma_f32_16x16x32_bf16 v[66:69], v[178:181], v[222:225], v[66:69]
	s_barrier
	s_add_i32 s18, s50, s26
	v_lshl_add_u64 v[190:191], s[22:23], 0, v[148:149]
	s_mov_b32 m0, s18
	ds_read_b128 v[182:185], v198 offset:16384
	ds_read_b128 v[186:189], v198 offset:17408
	ds_read_b128 v[202:205], v198 offset:18432
	ds_read_b128 v[206:209], v198 offset:19456
	ds_read_b128 v[210:213], v198 offset:20480
	ds_read_b128 v[214:217], v198 offset:21504
	ds_read_b128 v[218:221], v198 offset:22528
	ds_read_b128 v[222:225], v198 offset:23552
	global_load_lds_dwordx4 v[190:191], off
	s_add_i32 m0, s18, 0x2000
	s_add_u32 s18, s22, 0x58000
	v_lshl_add_u64 v[226:227], s[22:23], 0, v[152:153]
	s_addc_u32 s19, s23, 0
	s_add_i32 s54, s51, s26
	global_load_lds_dwordx4 v[226:227], off
	v_lshl_add_u64 v[228:229], s[18:19], 0, v[148:149]
	s_mov_b32 m0, s54
	v_lshl_add_u64 v[230:231], s[46:47], 0, v[150:151]
	global_load_lds_dwordx4 v[228:229], off
	v_lshl_add_u64 v[228:229], s[18:19], 0, v[152:153]
	s_add_i32 m0, s54, 0x2000
	s_nop 0
	global_load_lds_dwordx4 v[228:229], off
	v_lshl_add_u64 v[228:229], s[46:47], 0, v[146:147]
	s_mov_b32 m0, s27
	s_nop 0
	global_load_lds_dwordx4 v[228:229], off
	s_mov_b32 m0, s28
	s_nop 0
	global_load_lds_dwordx4 v[230:231], off
	s_waitcnt lgkmcnt(0)
	s_barrier
	v_mfma_f32_16x16x32_bf16 v[62:65], v[130:133], v[182:185], 0
	v_mfma_f32_16x16x32_bf16 v[58:61], v[138:141], v[182:185], 0
	v_mfma_f32_16x16x32_bf16 v[46:49], v[130:133], v[202:205], 0
	v_mfma_f32_16x16x32_bf16 v[42:45], v[138:141], v[202:205], 0
	v_mfma_f32_16x16x32_bf16 v[30:33], v[130:133], v[210:213], 0
	v_mfma_f32_16x16x32_bf16 v[26:29], v[138:141], v[210:213], 0
	v_mfma_f32_16x16x32_bf16 v[14:17], v[130:133], v[218:221], 0
	v_mfma_f32_16x16x32_bf16 v[10:13], v[138:141], v[218:221], 0
	v_mfma_f32_16x16x32_bf16 v[62:65], v[134:137], v[186:189], v[62:65]
	v_mfma_f32_16x16x32_bf16 v[58:61], v[142:145], v[186:189], v[58:61]
	v_mfma_f32_16x16x32_bf16 v[46:49], v[134:137], v[206:209], v[46:49]
	v_mfma_f32_16x16x32_bf16 v[42:45], v[142:145], v[206:209], v[42:45]
	v_mfma_f32_16x16x32_bf16 v[30:33], v[134:137], v[214:217], v[30:33]
	v_mfma_f32_16x16x32_bf16 v[26:29], v[142:145], v[214:217], v[26:29]
	v_mfma_f32_16x16x32_bf16 v[14:17], v[134:137], v[222:225], v[14:17]
	v_mfma_f32_16x16x32_bf16 v[10:13], v[142:145], v[222:225], v[10:13]
	v_mfma_f32_16x16x32_bf16 v[54:57], v[166:169], v[182:185], 0
	v_mfma_f32_16x16x32_bf16 v[50:53], v[174:177], v[182:185], 0
	v_mfma_f32_16x16x32_bf16 v[38:41], v[166:169], v[202:205], 0
	v_mfma_f32_16x16x32_bf16 v[34:37], v[174:177], v[202:205], 0
	v_mfma_f32_16x16x32_bf16 v[22:25], v[166:169], v[210:213], 0
	v_mfma_f32_16x16x32_bf16 v[18:21], v[174:177], v[210:213], 0
	v_mfma_f32_16x16x32_bf16 v[6:9], v[166:169], v[218:221], 0
	v_mfma_f32_16x16x32_bf16 v[2:5], v[174:177], v[218:221], 0
	v_mfma_f32_16x16x32_bf16 v[54:57], v[170:173], v[186:189], v[54:57]
	v_mfma_f32_16x16x32_bf16 v[50:53], v[178:181], v[186:189], v[50:53]
	v_mfma_f32_16x16x32_bf16 v[38:41], v[170:173], v[206:209], v[38:41]
	v_mfma_f32_16x16x32_bf16 v[34:37], v[178:181], v[206:209], v[34:37]
	v_mfma_f32_16x16x32_bf16 v[22:25], v[170:173], v[214:217], v[22:25]
	v_mfma_f32_16x16x32_bf16 v[18:21], v[178:181], v[214:217], v[18:21]
	v_mfma_f32_16x16x32_bf16 v[6:9], v[170:173], v[222:225], v[6:9]
	v_mfma_f32_16x16x32_bf16 v[2:5], v[178:181], v[222:225], v[2:5]
	s_barrier
; #define PG8_STAGE(bufoff, gbase, voff) do { _Pragma("unroll") for (int _i = 0; _i < 2; ++_i) \
;         __builtin_amdgcn_global_load_lds((const unsigned*)((const char*)(gbase) + (voff)[_i]), (LAS unsigned*)(lds + (bufoff) + ldsw + _i * 8192), 16, 0, 0); } while (0)
; #define PG8_LDA(dst, b, h) do { _Pragma("unroll") for (int m = 0; m < 4; ++m) _Pragma("unroll") for (int k = 0; k < 2; ++k) dst[m][k] = *(const LAS bf16x8*)(lds + PG8_SA(b, h) + aoff + m * 2048 + k * 1024); } while (0)
; #define PG8_LDB(dst, b, h) do { _Pragma("unroll") for (int n = 0; n < 2; ++n) _Pragma("unroll") for (int k = 0; k < 2; ++k) dst[n][k] = *(const LAS bf16x8*)(lds + PG8_SB(b, h) + boff + n * 2048 + k * 1024); } while (0)
; #define PG8_MMA(ai, bj, At, Bt) do { __builtin_amdgcn_s_setprio(1); _Pragma("unroll") for (int m = 0; m < 4; ++m) _Pragma("unroll") for (int n = 0; n < 2; ++n) _Pragma("unroll") for (int k = 0; k < 2; ++k) \
;         acc[ai][bj][m][n] = __builtin_amdgcn_mfma_f32_16x16x32_bf16(Bt[n][k], At[m][k], acc[ai][bj][m][n], 0, 0, 0); __builtin_amdgcn_s_setprio(0); } while (0)
; #define PG8_WAIT_V(n) asm volatile("s_waitcnt vmcnt(" #n ")" ::: "memory")
; #define PG8_WAIT_L(n) asm volatile("s_waitcnt lgkmcnt(" #n ")" ::: "memory")
; #define PG8_BAR __builtin_amdgcn_s_barrier()
; #define PG8_SCHED __builtin_amdgcn_sched_barrier(0)
; template <class Epi, class Sched, bool ALIGN_EPI = false, bool SP2 = false>
; __device__ __forceinline__ void gemm_phase(LAS unsigned char* lds, const Gemm g, const Sched& S, const Epi& E) {
;     ...
;             PG8_LDB(B0, 1, 0); PG8_LDB(B1, 1, 1); PG8_SCHED; PG8_LDA(At, 1, 0); PG8_STAGE(PG8_SA(0, 1), a2 + hstep, voffA);
;             PG8_WAIT_V(8); PG8_WAIT_L(0); PG8_BAR; PG8_MMA(0, 0, At, B0); PG8_MMA(0, 1, At, B1); PG8_BAR; PG8_SCHED;
;             PG8_LDA(At, 1, 1); PG8_STAGE(PG8_SB(1, 0), b3, voffB); PG8_STAGE(PG8_SB(1, 1), b3 + hstepB, voffB); PG8_STAGE(PG8_SA(1, 0), a3, voffA);
;             PG8_WAIT_V(8); PG8_WAIT_L(0); PG8_BAR; PG8_MMA(1, 0, At, B0); PG8_MMA(1, 1, At, B1); PG8_BAR; PG8_SCHED;
	s_add_i32 s54, 0, 0x18000
	s_add_i32 s55, 0, 0x1c000
	v_add_u32_e32 v142, s54, v1
	v_add_u32_e32 v154, s55, v1
	ds_read_b128 v[130:133], v142
	ds_read_b128 v[134:137], v142 offset:1024
	ds_read_b128 v[138:141], v142 offset:2048
	ds_read_b128 v[142:145], v142 offset:3072
	ds_read_b128 v[166:169], v154
	ds_read_b128 v[170:173], v154 offset:1024
	ds_read_b128 v[174:177], v154 offset:2048
	ds_read_b128 v[178:181], v154 offset:3072
	s_add_u32 s18, s46, 0x160000
	s_addc_u32 s19, s47, 0
	s_mov_b32 m0, s29
	v_lshl_add_u64 v[232:233], s[18:19], 0, v[146:147]
	ds_read_b128 v[182:185], v198 offset:32768
	ds_read_b128 v[186:189], v198 offset:33792
	ds_read_b128 v[202:205], v198 offset:34816
	ds_read_b128 v[206:209], v198 offset:35840
	ds_read_b128 v[210:213], v198 offset:36864
	ds_read_b128 v[214:217], v198 offset:37888
	ds_read_b128 v[218:221], v198 offset:38912
	ds_read_b128 v[222:225], v198 offset:39936
	global_load_lds_dwordx4 v[232:233], off
	v_lshl_add_u64 v[232:233], s[18:19], 0, v[150:151]
	s_mov_b32 m0, s30
	s_nop 0
	global_load_lds_dwordx4 v[232:233], off
	s_waitcnt vmcnt(8)
	s_waitcnt lgkmcnt(0)
	s_barrier
	v_mfma_f32_16x16x32_bf16 v[126:129], v[130:133], v[182:185], v[126:129]
	v_mfma_f32_16x16x32_bf16 v[122:125], v[138:141], v[182:185], v[122:125]
	v_mfma_f32_16x16x32_bf16 v[110:113], v[130:133], v[202:205], v[110:113]
	v_mfma_f32_16x16x32_bf16 v[106:109], v[138:141], v[202:205], v[106:109]
	v_mfma_f32_16x16x32_bf16 v[94:97], v[130:133], v[210:213], v[94:97]
	v_mfma_f32_16x16x32_bf16 v[90:93], v[138:141], v[210:213], v[90:93]
	v_mfma_f32_16x16x32_bf16 v[78:81], v[130:133], v[218:221], v[78:81]
	v_mfma_f32_16x16x32_bf16 v[74:77], v[138:141], v[218:221], v[74:77]
	v_mfma_f32_16x16x32_bf16 v[126:129], v[134:137], v[186:189], v[126:129]
	v_mfma_f32_16x16x32_bf16 v[122:125], v[142:145], v[186:189], v[122:125]
	v_mfma_f32_16x16x32_bf16 v[110:113], v[134:137], v[206:209], v[110:113]
	v_mfma_f32_16x16x32_bf16 v[106:109], v[142:145], v[206:209], v[106:109]
	v_mfma_f32_16x16x32_bf16 v[94:97], v[134:137], v[214:217], v[94:97]
	v_mfma_f32_16x16x32_bf16 v[90:93], v[142:145], v[214:217], v[90:93]
	v_mfma_f32_16x16x32_bf16 v[78:81], v[134:137], v[222:225], v[78:81]
	v_mfma_f32_16x16x32_bf16 v[74:77], v[142:145], v[222:225], v[74:77]
	v_mfma_f32_16x16x32_bf16 v[118:121], v[166:169], v[182:185], v[118:121]
	v_mfma_f32_16x16x32_bf16 v[114:117], v[174:177], v[182:185], v[114:117]
	v_mfma_f32_16x16x32_bf16 v[102:105], v[166:169], v[202:205], v[102:105]
	v_mfma_f32_16x16x32_bf16 v[98:101], v[174:177], v[202:205], v[98:101]
	v_mfma_f32_16x16x32_bf16 v[86:89], v[166:169], v[210:213], v[86:89]
	v_mfma_f32_16x16x32_bf16 v[82:85], v[174:177], v[210:213], v[82:85]
	v_mfma_f32_16x16x32_bf16 v[70:73], v[166:169], v[218:221], v[70:73]
	v_mfma_f32_16x16x32_bf16 v[66:69], v[174:177], v[218:221], v[66:69]
	v_mfma_f32_16x16x32_bf16 v[118:121], v[170:173], v[186:189], v[118:121]
	v_mfma_f32_16x16x32_bf16 v[114:117], v[178:181], v[186:189], v[114:117]
	v_mfma_f32_16x16x32_bf16 v[102:105], v[170:173], v[206:209], v[102:105]
	v_mfma_f32_16x16x32_bf16 v[98:101], v[178:181], v[206:209], v[98:101]
	v_mfma_f32_16x16x32_bf16 v[86:89], v[170:173], v[214:217], v[86:89]
	v_mfma_f32_16x16x32_bf16 v[82:85], v[178:181], v[214:217], v[82:85]
	v_mfma_f32_16x16x32_bf16 v[70:73], v[170:173], v[222:225], v[70:73]
	v_mfma_f32_16x16x32_bf16 v[66:69], v[178:181], v[222:225], v[66:69]
	s_barrier
	s_add_i32 s18, s54, s26
	v_lshl_add_u64 v[190:191], v[190:191], 0, s[12:13]
	s_mov_b32 m0, s18
	ds_read_b128 v[182:185], v198 offset:49152
	ds_read_b128 v[186:189], v198 offset:50176
	ds_read_b128 v[202:205], v198 offset:51200
	ds_read_b128 v[206:209], v198 offset:52224
	ds_read_b128 v[210:213], v198 offset:53248
	ds_read_b128 v[214:217], v198 offset:54272
	ds_read_b128 v[218:221], v198 offset:55296
	ds_read_b128 v[222:225], v198 offset:56320
	global_load_lds_dwordx4 v[190:191], off
	s_add_i32 m0, s18, 0x2000
	s_add_u32 s18, s22, 0x58080
	v_lshl_add_u64 v[190:191], v[226:227], 0, s[12:13]
	s_addc_u32 s19, s23, 0
	s_add_i32 s22, s55, s26
	global_load_lds_dwordx4 v[190:191], off
	v_lshl_add_u64 v[190:191], s[18:19], 0, v[148:149]
	s_mov_b32 m0, s22
	s_nop 0
	global_load_lds_dwordx4 v[190:191], off
	v_lshl_add_u64 v[190:191], s[18:19], 0, v[152:153]
	s_add_i32 m0, s22, 0x2000
	s_nop 0
	global_load_lds_dwordx4 v[190:191], off
	v_lshl_add_u64 v[190:191], v[228:229], 0, s[12:13]
	s_mov_b32 m0, s37
	s_nop 0
	global_load_lds_dwordx4 v[190:191], off
	v_lshl_add_u64 v[190:191], v[230:231], 0, s[12:13]
	s_mov_b32 m0, s48
	s_nop 0
	global_load_lds_dwordx4 v[190:191], off
	s_waitcnt vmcnt(8)
	s_waitcnt lgkmcnt(0)
	s_barrier
	v_mfma_f32_16x16x32_bf16 v[62:65], v[130:133], v[182:185], v[62:65]
	v_mfma_f32_16x16x32_bf16 v[58:61], v[138:141], v[182:185], v[58:61]
	v_mfma_f32_16x16x32_bf16 v[46:49], v[130:133], v[202:205], v[46:49]
	v_mfma_f32_16x16x32_bf16 v[42:45], v[138:141], v[202:205], v[42:45]
	v_mfma_f32_16x16x32_bf16 v[30:33], v[130:133], v[210:213], v[30:33]
	v_mfma_f32_16x16x32_bf16 v[26:29], v[138:141], v[210:213], v[26:29]
	v_mfma_f32_16x16x32_bf16 v[14:17], v[130:133], v[218:221], v[14:17]
	v_mfma_f32_16x16x32_bf16 v[10:13], v[138:141], v[218:221], v[10:13]
	v_mfma_f32_16x16x32_bf16 v[62:65], v[134:137], v[186:189], v[62:65]
	v_mfma_f32_16x16x32_bf16 v[58:61], v[142:145], v[186:189], v[58:61]
	v_mfma_f32_16x16x32_bf16 v[46:49], v[134:137], v[206:209], v[46:49]
	v_mfma_f32_16x16x32_bf16 v[42:45], v[142:145], v[206:209], v[42:45]
	v_mfma_f32_16x16x32_bf16 v[30:33], v[134:137], v[214:217], v[30:33]
	v_mfma_f32_16x16x32_bf16 v[26:29], v[142:145], v[214:217], v[26:29]
	v_mfma_f32_16x16x32_bf16 v[14:17], v[134:137], v[222:225], v[14:17]
	v_mfma_f32_16x16x32_bf16 v[10:13], v[142:145], v[222:225], v[10:13]
	v_mfma_f32_16x16x32_bf16 v[54:57], v[166:169], v[182:185], v[54:57]
	v_mfma_f32_16x16x32_bf16 v[50:53], v[174:177], v[182:185], v[50:53]
	v_mfma_f32_16x16x32_bf16 v[38:41], v[166:169], v[202:205], v[38:41]
	v_mfma_f32_16x16x32_bf16 v[34:37], v[174:177], v[202:205], v[34:37]
	v_mfma_f32_16x16x32_bf16 v[22:25], v[166:169], v[210:213], v[22:25]
	v_mfma_f32_16x16x32_bf16 v[18:21], v[174:177], v[210:213], v[18:21]
	v_mfma_f32_16x16x32_bf16 v[6:9], v[166:169], v[218:221], v[6:9]
	v_mfma_f32_16x16x32_bf16 v[2:5], v[174:177], v[218:221], v[2:5]
	v_mfma_f32_16x16x32_bf16 v[54:57], v[170:173], v[186:189], v[54:57]
	v_mfma_f32_16x16x32_bf16 v[50:53], v[178:181], v[186:189], v[50:53]
	v_mfma_f32_16x16x32_bf16 v[38:41], v[170:173], v[206:209], v[38:41]
	v_mfma_f32_16x16x32_bf16 v[34:37], v[178:181], v[206:209], v[34:37]
	v_mfma_f32_16x16x32_bf16 v[22:25], v[170:173], v[214:217], v[22:25]
	v_mfma_f32_16x16x32_bf16 v[18:21], v[178:181], v[214:217], v[18:21]
	v_mfma_f32_16x16x32_bf16 v[6:9], v[170:173], v[222:225], v[6:9]
	v_mfma_f32_16x16x32_bf16 v[2:5], v[178:181], v[222:225], v[2:5]
	s_barrier
	s_add_i32 s25, s25, 2
	s_add_u32 s5, s5, 0x100
	s_addc_u32 s24, s24, 0
	s_cmpk_lt_u32 s25, 0x56
	s_mov_b64 s[18:19], s[20:21]
; #define PG8_STAGE(bufoff, gbase, voff) do { _Pragma("unroll") for (int _i = 0; _i < 2; ++_i) \
;         __builtin_amdgcn_global_load_lds((const unsigned*)((const char*)(gbase) + (voff)[_i]), (LAS unsigned*)(lds + (bufoff) + ldsw + _i * 8192), 16, 0, 0); } while (0)
; #define PG8_LDA(dst, b, h) do { _Pragma("unroll") for (int m = 0; m < 4; ++m) _Pragma("unroll") for (int k = 0; k < 2; ++k) dst[m][k] = *(const LAS bf16x8*)(lds + PG8_SA(b, h) + aoff + m * 2048 + k * 1024); } while (0)
; #define PG8_LDB(dst, b, h) do { _Pragma("unroll") for (int n = 0; n < 2; ++n) _Pragma("unroll") for (int k = 0; k < 2; ++k) dst[n][k] = *(const LAS bf16x8*)(lds + PG8_SB(b, h) + boff + n * 2048 + k * 1024); } while (0)
; #define PG8_MMA(ai, bj, At, Bt) do { __builtin_amdgcn_s_setprio(1); _Pragma("unroll") for (int m = 0; m < 4; ++m) _Pragma("unroll") for (int n = 0; n < 2; ++n) _Pragma("unroll") for (int k = 0; k < 2; ++k) \
;         acc[ai][bj][m][n] = __builtin_amdgcn_mfma_f32_16x16x32_bf16(Bt[n][k], At[m][k], acc[ai][bj][m][n], 0, 0, 0); __builtin_amdgcn_s_setprio(0); } while (0)
; #define PG8_WAIT_V(n) asm volatile("s_waitcnt vmcnt(" #n ")" ::: "memory")
; #define PG8_WAIT_L(n) asm volatile("s_waitcnt lgkmcnt(" #n ")" ::: "memory")
; #define PG8_BAR __builtin_amdgcn_s_barrier()
; template <class Epi, class Sched, bool ALIGN_EPI = false, bool SP2 = false>
; __device__ __forceinline__ void gemm_phase(LAS unsigned char* lds, const Gemm g, const Sched& S, const Epi& E) {
;     ...
;             const bool last = (t == nt - 2);
;             const char* a1 = cA + (size_t)(t + 1) * kstep;
;             const char* a2 = last ? nA : cA + (size_t)(t + 2) * kstep; const char* b2 = last ? nB : cB + (size_t)(t + 2) * kstep;
;             const char* a3 = a2 + kstep; const char* b3 = b2 + kstep;
;             if (last && has_next) S.a_ready(nxt);
;             if constexpr (SP2) {
;             PG8_LDB(B0, 0, 0); PG8_LDB(B1, 0, 1); PG8_SCHED; PG8_LDA(At, 0, 0); PG8_STAGE(PG8_SA(1, 1), a1 + hstep, voffA);
;             PG8_WAIT_V(8); PG8_WAIT_L(0); PG8_BAR; PG8_MMA(0, 0, At, B0); PG8_MMA(0, 1, At, B1); PG8_BAR; PG8_SCHED;
;             PG8_LDA(At, 0, 1); PG8_STAGE(PG8_SB(0, 0), b2, voffB); PG8_STAGE(PG8_SB(0, 1), b2 + hstepB, voffB); PG8_STAGE(PG8_SA(0, 0), a2, voffA);
;             PG8_WAIT_V(8); PG8_WAIT_L(0); PG8_BAR; PG8_MMA(1, 0, At, B0); PG8_MMA(1, 1, At, B1); PG8_BAR; PG8_SCHED;
.LBB0_1926:
	ds_read_b128 v[130:133], v196
	ds_read_b128 v[134:137], v196 offset:1024
	ds_read_b128 v[138:141], v196 offset:2048
	ds_read_b128 v[142:145], v196 offset:3072
	ds_read_b128 v[166:169], v197
	ds_read_b128 v[170:173], v197 offset:1024
	ds_read_b128 v[174:177], v197 offset:2048
	ds_read_b128 v[178:181], v197 offset:3072
	s_add_u32 s20, s18, 0x100
	s_addc_u32 s21, s19, 0
	s_cmpk_eq_i32 s25, 0x54
	s_cselect_b32 s47, s17, s21
	s_cselect_b32 s46, s16, s20
	s_cselect_b32 s23, s3, s24
	s_cselect_b32 s22, s2, s5
	v_lshl_add_u64 v[190:191], s[18:19], 0, v[160:161]
	s_add_i32 m0, s27, 0xc000
	ds_read_b128 v[182:185], v198
	ds_read_b128 v[186:189], v198 offset:1024
	ds_read_b128 v[202:205], v198 offset:2048
	ds_read_b128 v[206:209], v198 offset:3072
	ds_read_b128 v[210:213], v198 offset:4096
	ds_read_b128 v[214:217], v198 offset:5120
	ds_read_b128 v[218:221], v198 offset:6144
	ds_read_b128 v[222:225], v198 offset:7168
	global_load_lds_dwordx4 v[190:191], off
	v_lshl_add_u64 v[190:191], s[18:19], 0, v[158:159]
	s_add_i32 m0, s27, 0xe000
	s_nop 0
	global_load_lds_dwordx4 v[190:191], off
	s_waitcnt vmcnt(8)
	s_waitcnt lgkmcnt(0)
	s_barrier
	v_mfma_f32_16x16x32_bf16 v[126:129], v[130:133], v[182:185], v[126:129]
	v_mfma_f32_16x16x32_bf16 v[122:125], v[138:141], v[182:185], v[122:125]
	v_mfma_f32_16x16x32_bf16 v[110:113], v[130:133], v[202:205], v[110:113]
	v_mfma_f32_16x16x32_bf16 v[106:109], v[138:141], v[202:205], v[106:109]
	v_mfma_f32_16x16x32_bf16 v[94:97], v[130:133], v[210:213], v[94:97]
	v_mfma_f32_16x16x32_bf16 v[90:93], v[138:141], v[210:213], v[90:93]
	v_mfma_f32_16x16x32_bf16 v[78:81], v[130:133], v[218:221], v[78:81]
	v_mfma_f32_16x16x32_bf16 v[74:77], v[138:141], v[218:221], v[74:77]
	v_mfma_f32_16x16x32_bf16 v[126:129], v[134:137], v[186:189], v[126:129]
	v_mfma_f32_16x16x32_bf16 v[122:125], v[142:145], v[186:189], v[122:125]
	v_mfma_f32_16x16x32_bf16 v[110:113], v[134:137], v[206:209], v[110:113]
	v_mfma_f32_16x16x32_bf16 v[106:109], v[142:145], v[206:209], v[106:109]
	v_mfma_f32_16x16x32_bf16 v[94:97], v[134:137], v[214:217], v[94:97]
	v_mfma_f32_16x16x32_bf16 v[90:93], v[142:145], v[214:217], v[90:93]
	v_mfma_f32_16x16x32_bf16 v[78:81], v[134:137], v[222:225], v[78:81]
	v_mfma_f32_16x16x32_bf16 v[74:77], v[142:145], v[222:225], v[74:77]
	v_mfma_f32_16x16x32_bf16 v[118:121], v[166:169], v[182:185], v[118:121]
	v_mfma_f32_16x16x32_bf16 v[114:117], v[174:177], v[182:185], v[114:117]
	v_mfma_f32_16x16x32_bf16 v[102:105], v[166:169], v[202:205], v[102:105]
	v_mfma_f32_16x16x32_bf16 v[98:101], v[174:177], v[202:205], v[98:101]
	v_mfma_f32_16x16x32_bf16 v[86:89], v[166:169], v[210:213], v[86:89]
	v_mfma_f32_16x16x32_bf16 v[82:85], v[174:177], v[210:213], v[82:85]
	v_mfma_f32_16x16x32_bf16 v[70:73], v[166:169], v[218:221], v[70:73]
	v_mfma_f32_16x16x32_bf16 v[66:69], v[174:177], v[218:221], v[66:69]
	v_mfma_f32_16x16x32_bf16 v[118:121], v[170:173], v[186:189], v[118:121]
	v_mfma_f32_16x16x32_bf16 v[114:117], v[178:181], v[186:189], v[114:117]
	v_mfma_f32_16x16x32_bf16 v[102:105], v[170:173], v[206:209], v[102:105]
	v_mfma_f32_16x16x32_bf16 v[98:101], v[178:181], v[206:209], v[98:101]
	v_mfma_f32_16x16x32_bf16 v[86:89], v[170:173], v[214:217], v[86:89]
	v_mfma_f32_16x16x32_bf16 v[82:85], v[178:181], v[214:217], v[82:85]
	v_mfma_f32_16x16x32_bf16 v[70:73], v[170:173], v[222:225], v[70:73]
	v_mfma_f32_16x16x32_bf16 v[66:69], v[178:181], v[222:225], v[66:69]
	s_barrier
	s_add_i32 s18, s50, s26
	v_lshl_add_u64 v[190:191], s[22:23], 0, v[148:149]
	s_mov_b32 m0, s18
	ds_read_b128 v[182:185], v198 offset:16384
	ds_read_b128 v[186:189], v198 offset:17408
	ds_read_b128 v[202:205], v198 offset:18432
	ds_read_b128 v[206:209], v198 offset:19456
	ds_read_b128 v[210:213], v198 offset:20480
	ds_read_b128 v[214:217], v198 offset:21504
	ds_read_b128 v[218:221], v198 offset:22528
	ds_read_b128 v[222:225], v198 offset:23552
	global_load_lds_dwordx4 v[190:191], off
	s_add_i32 m0, s18, 0x2000
	s_add_u32 s18, s22, 0x58000
	v_lshl_add_u64 v[226:227], s[22:23], 0, v[152:153]
	s_addc_u32 s19, s23, 0
	s_add_i32 s54, s51, s26
	global_load_lds_dwordx4 v[226:227], off
	v_lshl_add_u64 v[228:229], s[18:19], 0, v[148:149]
	s_mov_b32 m0, s54
	v_lshl_add_u64 v[230:231], s[46:47], 0, v[150:151]
	global_load_lds_dwordx4 v[228:229], off
	v_lshl_add_u64 v[228:229], s[18:19], 0, v[152:153]
	s_add_i32 m0, s54, 0x2000
	s_nop 0
	global_load_lds_dwordx4 v[228:229], off
	v_lshl_add_u64 v[228:229], s[46:47], 0, v[146:147]
	s_mov_b32 m0, s27
	s_nop 0
	global_load_lds_dwordx4 v[228:229], off
	s_mov_b32 m0, s28
	s_nop 0
	global_load_lds_dwordx4 v[230:231], off
	s_waitcnt vmcnt(8)
	s_waitcnt lgkmcnt(0)
	s_barrier
; #define PG8_STAGE(bufoff, gbase, voff) do { _Pragma("unroll") for (int _i = 0; _i < 2; ++_i) \
;         __builtin_amdgcn_global_load_lds((const unsigned*)((const char*)(gbase) + (voff)[_i]), (LAS unsigned*)(lds + (bufoff) + ldsw + _i * 8192), 16, 0, 0); } while (0)
; #define PG8_LDA(dst, b, h) do { _Pragma("unroll") for (int m = 0; m < 4; ++m) _Pragma("unroll") for (int k = 0; k < 2; ++k) dst[m][k] = *(const LAS bf16x8*)(lds + PG8_SA(b, h) + aoff + m * 2048 + k * 1024); } while (0)
; #define PG8_LDB(dst, b, h) do { _Pragma("unroll") for (int n = 0; n < 2; ++n) _Pragma("unroll") for (int k = 0; k < 2; ++k) dst[n][k] = *(const LAS bf16x8*)(lds + PG8_SB(b, h) + boff + n * 2048 + k * 1024); } while (0)
; #define PG8_MMA(ai, bj, At, Bt) do { __builtin_amdgcn_s_setprio(1); _Pragma("unroll") for (int m = 0; m < 4; ++m) _Pragma("unroll") for (int n = 0; n < 2; ++n) _Pragma("unroll") for (int k = 0; k < 2; ++k) \
;         acc[ai][bj][m][n] = __builtin_amdgcn_mfma_f32_16x16x32_bf16(Bt[n][k], At[m][k], acc[ai][bj][m][n], 0, 0, 0); __builtin_amdgcn_s_setprio(0); } while (0)
; #define PG8_WAIT_V(n) asm volatile("s_waitcnt vmcnt(" #n ")" ::: "memory")
; #define PG8_WAIT_L(n) asm volatile("s_waitcnt lgkmcnt(" #n ")" ::: "memory")
; #define PG8_BAR __builtin_amdgcn_s_barrier()
; #define PG8_SCHED __builtin_amdgcn_sched_barrier(0)
; template <class Epi, class Sched, bool ALIGN_EPI = false, bool SP2 = false>
; __device__ __forceinline__ void gemm_phase(LAS unsigned char* lds, const Gemm g, const Sched& S, const Epi& E) {
;     ...
;             PG8_WAIT_V(8); PG8_WAIT_L(0); PG8_BAR; PG8_MMA(1, 0, At, B0); PG8_MMA(1, 1, At, B1); PG8_BAR; PG8_SCHED;
;             PG8_LDB(B0, 1, 0); PG8_LDB(B1, 1, 1); PG8_SCHED; PG8_LDA(At, 1, 0); PG8_STAGE(PG8_SA(0, 1), a2 + hstep, voffA);
;             PG8_WAIT_V(8); PG8_WAIT_L(0); PG8_BAR; PG8_MMA(0, 0, At, B0); PG8_MMA(0, 1, At, B1); PG8_BAR; PG8_SCHED;
	v_mfma_f32_16x16x32_bf16 v[62:65], v[130:133], v[182:185], v[62:65]
	v_mfma_f32_16x16x32_bf16 v[58:61], v[138:141], v[182:185], v[58:61]
	v_mfma_f32_16x16x32_bf16 v[46:49], v[130:133], v[202:205], v[46:49]
	v_mfma_f32_16x16x32_bf16 v[42:45], v[138:141], v[202:205], v[42:45]
	v_mfma_f32_16x16x32_bf16 v[30:33], v[130:133], v[210:213], v[30:33]
	v_mfma_f32_16x16x32_bf16 v[26:29], v[138:141], v[210:213], v[26:29]
	v_mfma_f32_16x16x32_bf16 v[14:17], v[130:133], v[218:221], v[14:17]
	v_mfma_f32_16x16x32_bf16 v[10:13], v[138:141], v[218:221], v[10:13]
	v_mfma_f32_16x16x32_bf16 v[62:65], v[134:137], v[186:189], v[62:65]
	v_mfma_f32_16x16x32_bf16 v[58:61], v[142:145], v[186:189], v[58:61]
	v_mfma_f32_16x16x32_bf16 v[46:49], v[134:137], v[206:209], v[46:49]
	v_mfma_f32_16x16x32_bf16 v[42:45], v[142:145], v[206:209], v[42:45]
	v_mfma_f32_16x16x32_bf16 v[30:33], v[134:137], v[214:217], v[30:33]
	v_mfma_f32_16x16x32_bf16 v[26:29], v[142:145], v[214:217], v[26:29]
	v_mfma_f32_16x16x32_bf16 v[14:17], v[134:137], v[222:225], v[14:17]
	v_mfma_f32_16x16x32_bf16 v[10:13], v[142:145], v[222:225], v[10:13]
	v_mfma_f32_16x16x32_bf16 v[54:57], v[166:169], v[182:185], v[54:57]
	v_mfma_f32_16x16x32_bf16 v[50:53], v[174:177], v[182:185], v[50:53]
	v_mfma_f32_16x16x32_bf16 v[38:41], v[166:169], v[202:205], v[38:41]
	v_mfma_f32_16x16x32_bf16 v[34:37], v[174:177], v[202:205], v[34:37]
	v_mfma_f32_16x16x32_bf16 v[22:25], v[166:169], v[210:213], v[22:25]
	v_mfma_f32_16x16x32_bf16 v[18:21], v[174:177], v[210:213], v[18:21]
	v_mfma_f32_16x16x32_bf16 v[6:9], v[166:169], v[218:221], v[6:9]
	v_mfma_f32_16x16x32_bf16 v[2:5], v[174:177], v[218:221], v[2:5]
	v_mfma_f32_16x16x32_bf16 v[54:57], v[170:173], v[186:189], v[54:57]
	v_mfma_f32_16x16x32_bf16 v[50:53], v[178:181], v[186:189], v[50:53]
	v_mfma_f32_16x16x32_bf16 v[38:41], v[170:173], v[206:209], v[38:41]
	v_mfma_f32_16x16x32_bf16 v[34:37], v[178:181], v[206:209], v[34:37]
	v_mfma_f32_16x16x32_bf16 v[22:25], v[170:173], v[214:217], v[22:25]
	v_mfma_f32_16x16x32_bf16 v[18:21], v[178:181], v[214:217], v[18:21]
	v_mfma_f32_16x16x32_bf16 v[6:9], v[170:173], v[222:225], v[6:9]
	v_mfma_f32_16x16x32_bf16 v[2:5], v[178:181], v[222:225], v[2:5]
	s_barrier
	s_add_i32 s54, 0, 0x18000
	s_add_i32 s55, 0, 0x1c000
	v_add_u32_e32 v142, s54, v1
	v_add_u32_e32 v154, s55, v1
	ds_read_b128 v[130:133], v142
	ds_read_b128 v[134:137], v142 offset:1024
	ds_read_b128 v[138:141], v142 offset:2048
	ds_read_b128 v[142:145], v142 offset:3072
	ds_read_b128 v[166:169], v154
	ds_read_b128 v[170:173], v154 offset:1024
	ds_read_b128 v[174:177], v154 offset:2048
	ds_read_b128 v[178:181], v154 offset:3072
	s_add_u32 s18, s46, 0x160000
	s_addc_u32 s19, s47, 0
	s_mov_b32 m0, s29
	v_lshl_add_u64 v[232:233], s[18:19], 0, v[146:147]
	ds_read_b128 v[182:185], v198 offset:32768
	ds_read_b128 v[186:189], v198 offset:33792
	ds_read_b128 v[202:205], v198 offset:34816
	ds_read_b128 v[206:209], v198 offset:35840
	ds_read_b128 v[210:213], v198 offset:36864
	ds_read_b128 v[214:217], v198 offset:37888
	ds_read_b128 v[218:221], v198 offset:38912
	ds_read_b128 v[222:225], v198 offset:39936
	global_load_lds_dwordx4 v[232:233], off
	v_lshl_add_u64 v[232:233], s[18:19], 0, v[150:151]
	s_mov_b32 m0, s30
	s_nop 0
	global_load_lds_dwordx4 v[232:233], off
	s_waitcnt vmcnt(8)
	s_waitcnt lgkmcnt(0)
	s_barrier
	v_mfma_f32_16x16x32_bf16 v[126:129], v[130:133], v[182:185], v[126:129]
	v_mfma_f32_16x16x32_bf16 v[122:125], v[138:141], v[182:185], v[122:125]
	v_mfma_f32_16x16x32_bf16 v[110:113], v[130:133], v[202:205], v[110:113]
	v_mfma_f32_16x16x32_bf16 v[106:109], v[138:141], v[202:205], v[106:109]
	v_mfma_f32_16x16x32_bf16 v[94:97], v[130:133], v[210:213], v[94:97]
	v_mfma_f32_16x16x32_bf16 v[90:93], v[138:141], v[210:213], v[90:93]
	v_mfma_f32_16x16x32_bf16 v[78:81], v[130:133], v[218:221], v[78:81]
	v_mfma_f32_16x16x32_bf16 v[74:77], v[138:141], v[218:221], v[74:77]
	v_mfma_f32_16x16x32_bf16 v[126:129], v[134:137], v[186:189], v[126:129]
	v_mfma_f32_16x16x32_bf16 v[122:125], v[142:145], v[186:189], v[122:125]
	v_mfma_f32_16x16x32_bf16 v[110:113], v[134:137], v[206:209], v[110:113]
	v_mfma_f32_16x16x32_bf16 v[106:109], v[142:145], v[206:209], v[106:109]
	v_mfma_f32_16x16x32_bf16 v[94:97], v[134:137], v[214:217], v[94:97]
	v_mfma_f32_16x16x32_bf16 v[90:93], v[142:145], v[214:217], v[90:93]
	v_mfma_f32_16x16x32_bf16 v[78:81], v[134:137], v[222:225], v[78:81]
	v_mfma_f32_16x16x32_bf16 v[74:77], v[142:145], v[222:225], v[74:77]
	v_mfma_f32_16x16x32_bf16 v[118:121], v[166:169], v[182:185], v[118:121]
	v_mfma_f32_16x16x32_bf16 v[114:117], v[174:177], v[182:185], v[114:117]
	v_mfma_f32_16x16x32_bf16 v[102:105], v[166:169], v[202:205], v[102:105]
	v_mfma_f32_16x16x32_bf16 v[98:101], v[174:177], v[202:205], v[98:101]
	v_mfma_f32_16x16x32_bf16 v[86:89], v[166:169], v[210:213], v[86:89]
	v_mfma_f32_16x16x32_bf16 v[82:85], v[174:177], v[210:213], v[82:85]
	v_mfma_f32_16x16x32_bf16 v[70:73], v[166:169], v[218:221], v[70:73]
	v_mfma_f32_16x16x32_bf16 v[66:69], v[174:177], v[218:221], v[66:69]
	v_mfma_f32_16x16x32_bf16 v[118:121], v[170:173], v[186:189], v[118:121]
	v_mfma_f32_16x16x32_bf16 v[114:117], v[178:181], v[186:189], v[114:117]
	v_mfma_f32_16x16x32_bf16 v[102:105], v[170:173], v[206:209], v[102:105]
	v_mfma_f32_16x16x32_bf16 v[98:101], v[178:181], v[206:209], v[98:101]
	v_mfma_f32_16x16x32_bf16 v[86:89], v[170:173], v[214:217], v[86:89]
	v_mfma_f32_16x16x32_bf16 v[82:85], v[178:181], v[214:217], v[82:85]
	v_mfma_f32_16x16x32_bf16 v[70:73], v[170:173], v[222:225], v[70:73]
	v_mfma_f32_16x16x32_bf16 v[66:69], v[178:181], v[222:225], v[66:69]
	s_barrier
; #define PG8_STAGE(bufoff, gbase, voff) do { _Pragma("unroll") for (int _i = 0; _i < 2; ++_i) \
;         __builtin_amdgcn_global_load_lds((const unsigned*)((const char*)(gbase) + (voff)[_i]), (LAS unsigned*)(lds + (bufoff) + ldsw + _i * 8192), 16, 0, 0); } while (0)
; #define PG8_LDA(dst, b, h) do { _Pragma("unroll") for (int m = 0; m < 4; ++m) _Pragma("unroll") for (int k = 0; k < 2; ++k) dst[m][k] = *(const LAS bf16x8*)(lds + PG8_SA(b, h) + aoff + m * 2048 + k * 1024); } while (0)
; #define PG8_MMA(ai, bj, At, Bt) do { __builtin_amdgcn_s_setprio(1); _Pragma("unroll") for (int m = 0; m < 4; ++m) _Pragma("unroll") for (int n = 0; n < 2; ++n) _Pragma("unroll") for (int k = 0; k < 2; ++k) \
;         acc[ai][bj][m][n] = __builtin_amdgcn_mfma_f32_16x16x32_bf16(Bt[n][k], At[m][k], acc[ai][bj][m][n], 0, 0, 0); __builtin_amdgcn_s_setprio(0); } while (0)
; #define PG8_WAIT_V(n) asm volatile("s_waitcnt vmcnt(" #n ")" ::: "memory")
; #define PG8_WAIT_L(n) asm volatile("s_waitcnt lgkmcnt(" #n ")" ::: "memory")
; #define PG8_BAR __builtin_amdgcn_s_barrier()
; #define PG8_SCHED __builtin_amdgcn_sched_barrier(0)
; template <class Epi, class Sched, bool ALIGN_EPI = false, bool SP2 = false>
; __device__ __forceinline__ void gemm_phase(LAS unsigned char* lds, const Gemm g, const Sched& S, const Epi& E) {
;     ...
;             PG8_LDA(At, 1, 1); PG8_STAGE(PG8_SB(1, 0), b3, voffB); PG8_STAGE(PG8_SB(1, 1), b3 + hstepB, voffB); PG8_STAGE(PG8_SA(1, 0), a3, voffA);
;             PG8_WAIT_V(8); PG8_WAIT_L(0); PG8_BAR; PG8_MMA(1, 0, At, B0); PG8_MMA(1, 1, At, B1); PG8_BAR; PG8_SCHED;
;     ...
;         if constexpr (ALIGN_EPI) { if (wr == 0) PG8_BAR; }
	s_add_i32 s18, s54, s26
	v_lshl_add_u64 v[190:191], v[190:191], 0, s[12:13]
	s_mov_b32 m0, s18
	ds_read_b128 v[182:185], v198 offset:49152
	ds_read_b128 v[186:189], v198 offset:50176
	ds_read_b128 v[202:205], v198 offset:51200
	ds_read_b128 v[206:209], v198 offset:52224
	ds_read_b128 v[210:213], v198 offset:53248
	ds_read_b128 v[214:217], v198 offset:54272
	ds_read_b128 v[218:221], v198 offset:55296
	ds_read_b128 v[222:225], v198 offset:56320
	global_load_lds_dwordx4 v[190:191], off
	s_add_i32 m0, s18, 0x2000
	s_add_u32 s18, s22, 0x58080
	v_lshl_add_u64 v[190:191], v[226:227], 0, s[12:13]
	s_addc_u32 s19, s23, 0
	s_add_i32 s22, s55, s26
	global_load_lds_dwordx4 v[190:191], off
	v_lshl_add_u64 v[190:191], s[18:19], 0, v[148:149]
	s_mov_b32 m0, s22
	s_nop 0
	global_load_lds_dwordx4 v[190:191], off
	v_lshl_add_u64 v[190:191], s[18:19], 0, v[152:153]
	s_add_i32 m0, s22, 0x2000
	s_nop 0
	global_load_lds_dwordx4 v[190:191], off
	v_lshl_add_u64 v[190:191], v[228:229], 0, s[12:13]
	s_mov_b32 m0, s37
	s_nop 0
	global_load_lds_dwordx4 v[190:191], off
	v_lshl_add_u64 v[190:191], v[230:231], 0, s[12:13]
	s_mov_b32 m0, s48
	s_nop 0
	global_load_lds_dwordx4 v[190:191], off
	s_waitcnt vmcnt(8)
	s_waitcnt lgkmcnt(0)
	s_barrier
	v_mfma_f32_16x16x32_bf16 v[62:65], v[130:133], v[182:185], v[62:65]
	v_mfma_f32_16x16x32_bf16 v[58:61], v[138:141], v[182:185], v[58:61]
	v_mfma_f32_16x16x32_bf16 v[46:49], v[130:133], v[202:205], v[46:49]
	v_mfma_f32_16x16x32_bf16 v[42:45], v[138:141], v[202:205], v[42:45]
	v_mfma_f32_16x16x32_bf16 v[30:33], v[130:133], v[210:213], v[30:33]
	v_mfma_f32_16x16x32_bf16 v[26:29], v[138:141], v[210:213], v[26:29]
	v_mfma_f32_16x16x32_bf16 v[14:17], v[130:133], v[218:221], v[14:17]
	v_mfma_f32_16x16x32_bf16 v[10:13], v[138:141], v[218:221], v[10:13]
	v_mfma_f32_16x16x32_bf16 v[62:65], v[134:137], v[186:189], v[62:65]
	v_mfma_f32_16x16x32_bf16 v[58:61], v[142:145], v[186:189], v[58:61]
	v_mfma_f32_16x16x32_bf16 v[46:49], v[134:137], v[206:209], v[46:49]
	v_mfma_f32_16x16x32_bf16 v[42:45], v[142:145], v[206:209], v[42:45]
	v_mfma_f32_16x16x32_bf16 v[30:33], v[134:137], v[214:217], v[30:33]
	v_mfma_f32_16x16x32_bf16 v[26:29], v[142:145], v[214:217], v[26:29]
	v_mfma_f32_16x16x32_bf16 v[14:17], v[134:137], v[222:225], v[14:17]
	v_mfma_f32_16x16x32_bf16 v[10:13], v[142:145], v[222:225], v[10:13]
	v_mfma_f32_16x16x32_bf16 v[54:57], v[166:169], v[182:185], v[54:57]
	v_mfma_f32_16x16x32_bf16 v[50:53], v[174:177], v[182:185], v[50:53]
	v_mfma_f32_16x16x32_bf16 v[38:41], v[166:169], v[202:205], v[38:41]
	v_mfma_f32_16x16x32_bf16 v[34:37], v[174:177], v[202:205], v[34:37]
	v_mfma_f32_16x16x32_bf16 v[22:25], v[166:169], v[210:213], v[22:25]
	v_mfma_f32_16x16x32_bf16 v[18:21], v[174:177], v[210:213], v[18:21]
	v_mfma_f32_16x16x32_bf16 v[6:9], v[166:169], v[218:221], v[6:9]
	v_mfma_f32_16x16x32_bf16 v[2:5], v[174:177], v[218:221], v[2:5]
	v_mfma_f32_16x16x32_bf16 v[54:57], v[170:173], v[186:189], v[54:57]
	v_mfma_f32_16x16x32_bf16 v[50:53], v[178:181], v[186:189], v[50:53]
	v_mfma_f32_16x16x32_bf16 v[38:41], v[170:173], v[206:209], v[38:41]
	v_mfma_f32_16x16x32_bf16 v[34:37], v[178:181], v[206:209], v[34:37]
	v_mfma_f32_16x16x32_bf16 v[22:25], v[170:173], v[214:217], v[22:25]
	v_mfma_f32_16x16x32_bf16 v[18:21], v[178:181], v[214:217], v[18:21]
	v_mfma_f32_16x16x32_bf16 v[6:9], v[170:173], v[222:225], v[6:9]
	v_mfma_f32_16x16x32_bf16 v[2:5], v[178:181], v[222:225], v[2:5]
	s_barrier
	s_add_i32 s25, s25, 2
	s_add_u32 s5, s5, 0x100
	s_addc_u32 s24, s24, 0
	s_cmpk_lt_u32 s25, 0x56
	s_mov_b64 s[18:19], s[20:21]
	s_cbranch_scc1 .LBB0_1926
	s_setprio 0
	s_andn2_b64 vcc, exec, s[14:15]
	s_cbranch_vccnz .LBB0_1929
	s_barrier

;     __device__ bool next(int i, Unit& u) const { if (i != 0 || c >= 128) return false; const int t = c >> 2; u.pm = t & 3; u.pn = t >> 2; u.koff = koff_bytes; u.q = c & 3; return true; }
; #define PG8_STAGE(bufoff, gbase, voff) do { _Pragma("unroll") for (int _i = 0; _i < 2; ++_i) \
;         __builtin_amdgcn_global_load_lds((const unsigned*)((const char*)(gbase) + (voff)[_i]), (LAS unsigned*)(lds + (bufoff) + ldsw + _i * 8192), 16, 0, 0); } while (0)
; #define PG8_LDA(dst, b, h) do { _Pragma("unroll") for (int m = 0; m < 4; ++m) _Pragma("unroll") for (int k = 0; k < 2; ++k) dst[m][k] = *(const LAS bf16x8*)(lds + PG8_SA(b, h) + aoff + m * 2048 + k * 1024); } while (0)
; #define PG8_LDB(dst, b, h) do { _Pragma("unroll") for (int n = 0; n < 2; ++n) _Pragma("unroll") for (int k = 0; k < 2; ++k) dst[n][k] = *(const LAS bf16x8*)(lds + PG8_SB(b, h) + boff + n * 2048 + k * 1024); } while (0)
; #define PG8_WAIT_V(n) asm volatile("s_waitcnt vmcnt(" #n ")" ::: "memory")
; template <class Epi, class Sched, bool ALIGN_EPI = false, bool SP2 = false>
; __device__ __forceinline__ void gemm_phase(LAS unsigned char* lds, const Gemm g, const Sched& S, const Epi& E) {
;     ...
;         const bool has_next = S.next(ui + 1, nxt);
;         const char* nA = has_next ? (const char*)g.A + (size_t)nxt.pm * tstep + nxt.koff : cA; const char* nB = has_next ? (const char*)g.Bt + (size_t)nxt.pn * tstep + nxt.koff : cB;
;         for (int t = 0; t < nt; t += 2) {
;             const bool last = (t == nt - 2);
;             const char* a1 = cA + (size_t)(t + 1) * kstep;
;             const char* a2 = last ? nA : cA + (size_t)(t + 2) * kstep; const char* b2 = last ? nB : cB + (size_t)(t + 2) * kstep;
;             const char* a3 = a2 + kstep; const char* b3 = b2 + kstep;
;             if (last && has_next) S.a_ready(nxt);
;             if constexpr (SP2) {
;             PG8_LDB(B0, 0, 0); PG8_LDB(B1, 0, 1); PG8_SCHED; PG8_LDA(At, 0, 0); PG8_STAGE(PG8_SA(1, 1), a1 + hstep, voffA);
;             PG8_WAIT_V(8); PG8_WAIT_L(0); PG8_BAR; PG8_MMA(0, 0, At, B0); PG8_MMA(0, 1, At, B1); PG8_BAR; PG8_SCHED;
;             PG8_LDA(At, 0, 1); PG8_STAGE(PG8_SB(0, 0), b2, voffB); PG8_STAGE(PG8_SB(0, 1), b2 + hstepB, voffB); PG8_STAGE(PG8_SA(0, 0), a2, voffA);
;             PG8_WAIT_V(8); PG8_WAIT_L(0); PG8_BAR; PG8_MMA(1, 0, At, B0); PG8_MMA(1, 1, At, B1); PG8_BAR; PG8_SCHED;
.Lprio_2143:
	ds_read_b128 v[34:37], v202
	ds_read_b128 v[38:41], v202 offset:1024
	ds_read_b128 v[42:45], v202 offset:2048
	ds_read_b128 v[46:49], v202 offset:3072
	ds_read_b128 v[98:101], v203
	ds_read_b128 v[102:105], v203 offset:1024
	ds_read_b128 v[106:109], v203 offset:2048
	ds_read_b128 v[110:113], v203 offset:3072
	s_add_u32 s22, s20, 0xfff80080
	s_addc_u32 s23, s21, -1
	s_cmp_eq_u32 s34, 28
	s_cselect_b32 s37, s3, s23
	s_cselect_b32 s36, s13, s22
	s_cselect_b32 s23, s11, s25
	s_cselect_b32 s22, s19, s24
	v_lshl_add_u64 v[182:183], s[20:21], 0, v[174:175]
	s_add_i32 m0, s28, 0xc000
	ds_read_b128 v[210:213], v204
	ds_read_b128 v[214:217], v204 offset:1024
	ds_read_b128 v[218:221], v204 offset:2048
	ds_read_b128 v[222:225], v204 offset:3072
	ds_read_b128 v[226:229], v204 offset:4096
	ds_read_b128 v[230:233], v204 offset:5120
	ds_read_b128 v[234:237], v204 offset:6144
	ds_read_b128 v[238:241], v204 offset:7168
	global_load_lds_dwordx4 v[182:183], off
	v_lshl_add_u64 v[182:183], s[20:21], 0, v[172:173]
	s_add_i32 m0, s28, 0xe000
	s_nop 0
	global_load_lds_dwordx4 v[182:183], off
	s_waitcnt lgkmcnt(0)
	s_barrier
	v_mfma_f32_16x16x32_bf16 v[158:161], v[34:37], v[210:213], 0
	v_mfma_f32_16x16x32_bf16 v[154:157], v[42:45], v[210:213], 0
	v_mfma_f32_16x16x32_bf16 v[142:145], v[34:37], v[218:221], 0
	v_mfma_f32_16x16x32_bf16 v[138:141], v[42:45], v[218:221], 0
	v_mfma_f32_16x16x32_bf16 v[126:129], v[34:37], v[226:229], 0
	v_mfma_f32_16x16x32_bf16 v[122:125], v[42:45], v[226:229], 0
	v_mfma_f32_16x16x32_bf16 v[94:97], v[34:37], v[234:237], 0
	v_mfma_f32_16x16x32_bf16 v[90:93], v[42:45], v[234:237], 0
	v_mfma_f32_16x16x32_bf16 v[158:161], v[38:41], v[214:217], v[158:161]
	v_mfma_f32_16x16x32_bf16 v[154:157], v[46:49], v[214:217], v[154:157]
	v_mfma_f32_16x16x32_bf16 v[142:145], v[38:41], v[222:225], v[142:145]
	v_mfma_f32_16x16x32_bf16 v[138:141], v[46:49], v[222:225], v[138:141]
	v_mfma_f32_16x16x32_bf16 v[126:129], v[38:41], v[230:233], v[126:129]
	v_mfma_f32_16x16x32_bf16 v[122:125], v[46:49], v[230:233], v[122:125]
	v_mfma_f32_16x16x32_bf16 v[94:97], v[38:41], v[238:241], v[94:97]
	v_mfma_f32_16x16x32_bf16 v[90:93], v[46:49], v[238:241], v[90:93]
	v_mfma_f32_16x16x32_bf16 v[150:153], v[98:101], v[210:213], 0
	v_mfma_f32_16x16x32_bf16 v[146:149], v[106:109], v[210:213], 0
	v_mfma_f32_16x16x32_bf16 v[134:137], v[98:101], v[218:221], 0
	v_mfma_f32_16x16x32_bf16 v[130:133], v[106:109], v[218:221], 0
	v_mfma_f32_16x16x32_bf16 v[118:121], v[98:101], v[226:229], 0
	v_mfma_f32_16x16x32_bf16 v[114:117], v[106:109], v[226:229], 0
	v_mfma_f32_16x16x32_bf16 v[86:89], v[98:101], v[234:237], 0
	v_mfma_f32_16x16x32_bf16 v[82:85], v[106:109], v[234:237], 0
	v_mfma_f32_16x16x32_bf16 v[150:153], v[102:105], v[214:217], v[150:153]
	v_mfma_f32_16x16x32_bf16 v[146:149], v[110:113], v[214:217], v[146:149]
	v_mfma_f32_16x16x32_bf16 v[134:137], v[102:105], v[222:225], v[134:137]
	v_mfma_f32_16x16x32_bf16 v[130:133], v[110:113], v[222:225], v[130:133]
	v_mfma_f32_16x16x32_bf16 v[118:121], v[102:105], v[230:233], v[118:121]
	v_mfma_f32_16x16x32_bf16 v[114:117], v[110:113], v[230:233], v[114:117]
	v_mfma_f32_16x16x32_bf16 v[86:89], v[102:105], v[238:241], v[86:89]
	v_mfma_f32_16x16x32_bf16 v[82:85], v[110:113], v[238:241], v[82:85]
	s_barrier
	s_add_i32 s35, s56, s27
	v_lshl_add_u64 v[182:183], s[22:23], 0, v[164:165]
	s_mov_b32 m0, s35
	ds_read_b128 v[210:213], v204 offset:16384
	ds_read_b128 v[214:217], v204 offset:17408
	ds_read_b128 v[218:221], v204 offset:18432
	ds_read_b128 v[222:225], v204 offset:19456
	ds_read_b128 v[226:229], v204 offset:20480
	ds_read_b128 v[230:233], v204 offset:21504
	ds_read_b128 v[234:237], v204 offset:22528
	ds_read_b128 v[238:241], v204 offset:23552
	global_load_lds_dwordx4 v[182:183], off
	s_add_i32 m0, s35, 0x2000
	s_add_u32 s46, s22, 0x20000
	v_lshl_add_u64 v[242:243], s[22:23], 0, v[168:169]
	s_addc_u32 s47, s23, 0
	s_add_i32 s35, s57, s27
	global_load_lds_dwordx4 v[242:243], off
	v_lshl_add_u64 v[244:245], s[46:47], 0, v[164:165]
	s_mov_b32 m0, s35
	v_lshl_add_u64 v[246:247], s[36:37], 0, v[166:167]
	global_load_lds_dwordx4 v[244:245], off
	v_lshl_add_u64 v[244:245], s[46:47], 0, v[168:169]
	s_add_i32 m0, s35, 0x2000
	s_nop 0
	global_load_lds_dwordx4 v[244:245], off
	v_lshl_add_u64 v[244:245], s[36:37], 0, v[162:163]
	s_mov_b32 m0, s28
	s_nop 0
	global_load_lds_dwordx4 v[244:245], off
	s_mov_b32 m0, s29
	s_nop 0
	global_load_lds_dwordx4 v[246:247], off
	s_waitcnt lgkmcnt(0)
	s_barrier
	v_mfma_f32_16x16x32_bf16 v[78:81], v[34:37], v[210:213], 0
	v_mfma_f32_16x16x32_bf16 v[74:77], v[42:45], v[210:213], 0
	v_mfma_f32_16x16x32_bf16 v[62:65], v[34:37], v[218:221], 0
	v_mfma_f32_16x16x32_bf16 v[58:61], v[42:45], v[218:221], 0
	v_mfma_f32_16x16x32_bf16 v[30:33], v[34:37], v[226:229], 0
	v_mfma_f32_16x16x32_bf16 v[26:29], v[42:45], v[226:229], 0
	v_mfma_f32_16x16x32_bf16 v[14:17], v[34:37], v[234:237], 0
	v_mfma_f32_16x16x32_bf16 v[10:13], v[42:45], v[234:237], 0
	v_mfma_f32_16x16x32_bf16 v[78:81], v[38:41], v[214:217], v[78:81]
	v_mfma_f32_16x16x32_bf16 v[74:77], v[46:49], v[214:217], v[74:77]
	v_mfma_f32_16x16x32_bf16 v[62:65], v[38:41], v[222:225], v[62:65]
	v_mfma_f32_16x16x32_bf16 v[58:61], v[46:49], v[222:225], v[58:61]
	v_mfma_f32_16x16x32_bf16 v[30:33], v[38:41], v[230:233], v[30:33]
	v_mfma_f32_16x16x32_bf16 v[26:29], v[46:49], v[230:233], v[26:29]
	v_mfma_f32_16x16x32_bf16 v[14:17], v[38:41], v[238:241], v[14:17]
	v_mfma_f32_16x16x32_bf16 v[10:13], v[46:49], v[238:241], v[10:13]
	v_mfma_f32_16x16x32_bf16 v[22:25], v[98:101], v[226:229], 0
	v_mfma_f32_16x16x32_bf16 v[18:21], v[106:109], v[226:229], 0
	v_mfma_f32_16x16x32_bf16 v[6:9], v[98:101], v[234:237], 0
	v_mfma_f32_16x16x32_bf16 v[2:5], v[106:109], v[234:237], 0
	v_mfma_f32_16x16x32_bf16 v[34:37], v[98:101], v[210:213], 0
	v_mfma_f32_16x16x32_bf16 v[38:41], v[106:109], v[210:213], 0
	v_mfma_f32_16x16x32_bf16 v[42:45], v[98:101], v[218:221], 0
	v_mfma_f32_16x16x32_bf16 v[46:49], v[106:109], v[218:221], 0
	v_mfma_f32_16x16x32_bf16 v[22:25], v[102:105], v[230:233], v[22:25]
	v_mfma_f32_16x16x32_bf16 v[18:21], v[110:113], v[230:233], v[18:21]
	v_mfma_f32_16x16x32_bf16 v[6:9], v[102:105], v[238:241], v[6:9]
	v_mfma_f32_16x16x32_bf16 v[2:5], v[110:113], v[238:241], v[2:5]
	v_mfma_f32_16x16x32_bf16 v[34:37], v[102:105], v[214:217], v[34:37]
	v_mfma_f32_16x16x32_bf16 v[38:41], v[110:113], v[214:217], v[38:41]
	v_mfma_f32_16x16x32_bf16 v[42:45], v[102:105], v[222:225], v[42:45]
	v_mfma_f32_16x16x32_bf16 v[46:49], v[110:113], v[222:225], v[46:49]
	s_barrier
; #define PG8_STAGE(bufoff, gbase, voff) do { _Pragma("unroll") for (int _i = 0; _i < 2; ++_i) \
;         __builtin_amdgcn_global_load_lds((const unsigned*)((const char*)(gbase) + (voff)[_i]), (LAS unsigned*)(lds + (bufoff) + ldsw + _i * 8192), 16, 0, 0); } while (0)
; #define PG8_LDA(dst, b, h) do { _Pragma("unroll") for (int m = 0; m < 4; ++m) _Pragma("unroll") for (int k = 0; k < 2; ++k) dst[m][k] = *(const LAS bf16x8*)(lds + PG8_SA(b, h) + aoff + m * 2048 + k * 1024); } while (0)
; #define PG8_LDB(dst, b, h) do { _Pragma("unroll") for (int n = 0; n < 2; ++n) _Pragma("unroll") for (int k = 0; k < 2; ++k) dst[n][k] = *(const LAS bf16x8*)(lds + PG8_SB(b, h) + boff + n * 2048 + k * 1024); } while (0)
; #define PG8_MMA(ai, bj, At, Bt) do { __builtin_amdgcn_s_setprio(1); _Pragma("unroll") for (int m = 0; m < 4; ++m) _Pragma("unroll") for (int n = 0; n < 2; ++n) _Pragma("unroll") for (int k = 0; k < 2; ++k) \
;         acc[ai][bj][m][n] = __builtin_amdgcn_mfma_f32_16x16x32_bf16(Bt[n][k], At[m][k], acc[ai][bj][m][n], 0, 0, 0); __builtin_amdgcn_s_setprio(0); } while (0)
; #define PG8_WAIT_V(n) asm volatile("s_waitcnt vmcnt(" #n ")" ::: "memory")
; #define PG8_WAIT_L(n) asm volatile("s_waitcnt lgkmcnt(" #n ")" ::: "memory")
; #define PG8_BAR __builtin_amdgcn_s_barrier()
; #define PG8_SCHED __builtin_amdgcn_sched_barrier(0)
; template <class Epi, class Sched, bool ALIGN_EPI = false, bool SP2 = false>
; __device__ __forceinline__ void gemm_phase(LAS unsigned char* lds, const Gemm g, const Sched& S, const Epi& E) {
;     ...
;             PG8_LDB(B0, 1, 0); PG8_LDB(B1, 1, 1); PG8_SCHED; PG8_LDA(At, 1, 0); PG8_STAGE(PG8_SA(0, 1), a2 + hstep, voffA);
;             PG8_WAIT_V(8); PG8_WAIT_L(0); PG8_BAR; PG8_MMA(0, 0, At, B0); PG8_MMA(0, 1, At, B1); PG8_BAR; PG8_SCHED;
;             PG8_LDA(At, 1, 1); PG8_STAGE(PG8_SB(1, 0), b3, voffB); PG8_STAGE(PG8_SB(1, 1), b3 + hstepB, voffB); PG8_STAGE(PG8_SA(1, 0), a3, voffA);
;             PG8_WAIT_V(8); PG8_WAIT_L(0); PG8_BAR; PG8_MMA(1, 0, At, B0); PG8_MMA(1, 1, At, B1); PG8_BAR; PG8_SCHED;
	s_add_i32 s35, 0, 0x18000
	s_add_i32 s46, 0, 0x1c000
	v_add_u32_e32 v70, s35, v185
	v_add_u32_e32 v110, s46, v185
	ds_read_b128 v[50:53], v70
	ds_read_b128 v[54:57], v70 offset:1024
	ds_read_b128 v[66:69], v70 offset:2048
	ds_read_b128 v[70:73], v70 offset:3072
	ds_read_b128 v[98:101], v110
	ds_read_b128 v[102:105], v110 offset:1024
	ds_read_b128 v[106:109], v110 offset:2048
	ds_read_b128 v[110:113], v110 offset:3072
	s_add_u32 s36, s36, 0x80000
	s_addc_u32 s37, s37, 0
	s_mov_b32 m0, s30
	v_lshl_add_u64 v[248:249], s[36:37], 0, v[162:163]
	ds_read_b128 v[210:213], v204 offset:32768
	ds_read_b128 v[214:217], v204 offset:33792
	ds_read_b128 v[218:221], v204 offset:34816
	ds_read_b128 v[222:225], v204 offset:35840
	ds_read_b128 v[226:229], v204 offset:36864
	ds_read_b128 v[230:233], v204 offset:37888
	ds_read_b128 v[234:237], v204 offset:38912
	ds_read_b128 v[238:241], v204 offset:39936
	global_load_lds_dwordx4 v[248:249], off
	v_lshl_add_u64 v[248:249], s[36:37], 0, v[166:167]
	s_mov_b32 m0, s31
	s_nop 0
	global_load_lds_dwordx4 v[248:249], off
	s_waitcnt vmcnt(8)
	s_waitcnt lgkmcnt(0)
	s_barrier
	v_mfma_f32_16x16x32_bf16 v[158:161], v[50:53], v[210:213], v[158:161]
	v_mfma_f32_16x16x32_bf16 v[154:157], v[66:69], v[210:213], v[154:157]
	v_mfma_f32_16x16x32_bf16 v[142:145], v[50:53], v[218:221], v[142:145]
	v_mfma_f32_16x16x32_bf16 v[138:141], v[66:69], v[218:221], v[138:141]
	v_mfma_f32_16x16x32_bf16 v[126:129], v[50:53], v[226:229], v[126:129]
	v_mfma_f32_16x16x32_bf16 v[122:125], v[66:69], v[226:229], v[122:125]
	v_mfma_f32_16x16x32_bf16 v[94:97], v[50:53], v[234:237], v[94:97]
	v_mfma_f32_16x16x32_bf16 v[90:93], v[66:69], v[234:237], v[90:93]
	v_mfma_f32_16x16x32_bf16 v[158:161], v[54:57], v[214:217], v[158:161]
	v_mfma_f32_16x16x32_bf16 v[154:157], v[70:73], v[214:217], v[154:157]
	v_mfma_f32_16x16x32_bf16 v[142:145], v[54:57], v[222:225], v[142:145]
	v_mfma_f32_16x16x32_bf16 v[138:141], v[70:73], v[222:225], v[138:141]
	v_mfma_f32_16x16x32_bf16 v[126:129], v[54:57], v[230:233], v[126:129]
	v_mfma_f32_16x16x32_bf16 v[122:125], v[70:73], v[230:233], v[122:125]
	v_mfma_f32_16x16x32_bf16 v[94:97], v[54:57], v[238:241], v[94:97]
	v_mfma_f32_16x16x32_bf16 v[90:93], v[70:73], v[238:241], v[90:93]
	v_mfma_f32_16x16x32_bf16 v[150:153], v[98:101], v[210:213], v[150:153]
	v_mfma_f32_16x16x32_bf16 v[146:149], v[106:109], v[210:213], v[146:149]
	v_mfma_f32_16x16x32_bf16 v[134:137], v[98:101], v[218:221], v[134:137]
	v_mfma_f32_16x16x32_bf16 v[130:133], v[106:109], v[218:221], v[130:133]
	v_mfma_f32_16x16x32_bf16 v[118:121], v[98:101], v[226:229], v[118:121]
	v_mfma_f32_16x16x32_bf16 v[114:117], v[106:109], v[226:229], v[114:117]
	v_mfma_f32_16x16x32_bf16 v[86:89], v[98:101], v[234:237], v[86:89]
	v_mfma_f32_16x16x32_bf16 v[82:85], v[106:109], v[234:237], v[82:85]
	v_mfma_f32_16x16x32_bf16 v[150:153], v[102:105], v[214:217], v[150:153]
	v_mfma_f32_16x16x32_bf16 v[146:149], v[110:113], v[214:217], v[146:149]
	v_mfma_f32_16x16x32_bf16 v[134:137], v[102:105], v[222:225], v[134:137]
	v_mfma_f32_16x16x32_bf16 v[130:133], v[110:113], v[222:225], v[130:133]
	v_mfma_f32_16x16x32_bf16 v[118:121], v[102:105], v[230:233], v[118:121]
	v_mfma_f32_16x16x32_bf16 v[114:117], v[110:113], v[230:233], v[114:117]
	v_mfma_f32_16x16x32_bf16 v[86:89], v[102:105], v[238:241], v[86:89]
	v_mfma_f32_16x16x32_bf16 v[82:85], v[110:113], v[238:241], v[82:85]
	s_barrier
	s_add_i32 s35, s35, s27
	v_lshl_add_u64 v[182:183], v[182:183], 0, s[4:5]
	s_mov_b32 m0, s35
	ds_read_b128 v[210:213], v204 offset:49152
	ds_read_b128 v[214:217], v204 offset:50176
	ds_read_b128 v[218:221], v204 offset:51200
	ds_read_b128 v[222:225], v204 offset:52224
	ds_read_b128 v[226:229], v204 offset:53248
	ds_read_b128 v[230:233], v204 offset:54272
	ds_read_b128 v[234:237], v204 offset:55296
	ds_read_b128 v[238:241], v204 offset:56320
	global_load_lds_dwordx4 v[182:183], off
	s_add_i32 m0, s35, 0x2000
	s_add_u32 s22, s22, 0x20080
	v_lshl_add_u64 v[182:183], v[242:243], 0, s[4:5]
	s_addc_u32 s23, s23, 0
	s_add_i32 s35, s46, s27
	global_load_lds_dwordx4 v[182:183], off
	v_lshl_add_u64 v[182:183], s[22:23], 0, v[164:165]
	s_mov_b32 m0, s35
	s_nop 0
	global_load_lds_dwordx4 v[182:183], off
	v_lshl_add_u64 v[182:183], s[22:23], 0, v[168:169]
	s_add_i32 m0, s35, 0x2000
	s_nop 0
	global_load_lds_dwordx4 v[182:183], off
	v_lshl_add_u64 v[182:183], v[244:245], 0, s[4:5]
	s_mov_b32 m0, s53
	s_nop 0
	global_load_lds_dwordx4 v[182:183], off
	v_lshl_add_u64 v[182:183], v[246:247], 0, s[4:5]
	s_mov_b32 m0, s54
	s_nop 0
	global_load_lds_dwordx4 v[182:183], off
	s_waitcnt vmcnt(8)
	s_waitcnt lgkmcnt(0)
	s_barrier
	v_mfma_f32_16x16x32_bf16 v[78:81], v[50:53], v[210:213], v[78:81]
	v_mfma_f32_16x16x32_bf16 v[74:77], v[66:69], v[210:213], v[74:77]
	v_mfma_f32_16x16x32_bf16 v[62:65], v[50:53], v[218:221], v[62:65]
	v_mfma_f32_16x16x32_bf16 v[58:61], v[66:69], v[218:221], v[58:61]
	v_mfma_f32_16x16x32_bf16 v[30:33], v[50:53], v[226:229], v[30:33]
	v_mfma_f32_16x16x32_bf16 v[26:29], v[66:69], v[226:229], v[26:29]
	v_mfma_f32_16x16x32_bf16 v[14:17], v[50:53], v[234:237], v[14:17]
	v_mfma_f32_16x16x32_bf16 v[10:13], v[66:69], v[234:237], v[10:13]
	v_mfma_f32_16x16x32_bf16 v[78:81], v[54:57], v[214:217], v[78:81]
	v_mfma_f32_16x16x32_bf16 v[74:77], v[70:73], v[214:217], v[74:77]
	v_mfma_f32_16x16x32_bf16 v[62:65], v[54:57], v[222:225], v[62:65]
	v_mfma_f32_16x16x32_bf16 v[58:61], v[70:73], v[222:225], v[58:61]
	v_mfma_f32_16x16x32_bf16 v[30:33], v[54:57], v[230:233], v[30:33]
	v_mfma_f32_16x16x32_bf16 v[26:29], v[70:73], v[230:233], v[26:29]
	v_mfma_f32_16x16x32_bf16 v[14:17], v[54:57], v[238:241], v[14:17]
	v_mfma_f32_16x16x32_bf16 v[10:13], v[70:73], v[238:241], v[10:13]
	v_mfma_f32_16x16x32_bf16 v[34:37], v[98:101], v[210:213], v[34:37]
	v_mfma_f32_16x16x32_bf16 v[70:73], v[102:105], v[214:217], v[34:37]
	v_mfma_f32_16x16x32_bf16 v[34:37], v[106:109], v[210:213], v[38:41]
	v_mfma_f32_16x16x32_bf16 v[66:69], v[110:113], v[214:217], v[34:37]
	v_mfma_f32_16x16x32_bf16 v[34:37], v[98:101], v[218:221], v[42:45]
	v_mfma_f32_16x16x32_bf16 v[54:57], v[102:105], v[222:225], v[34:37]
	v_mfma_f32_16x16x32_bf16 v[34:37], v[106:109], v[218:221], v[46:49]
	v_mfma_f32_16x16x32_bf16 v[22:25], v[98:101], v[226:229], v[22:25]
	v_mfma_f32_16x16x32_bf16 v[18:21], v[106:109], v[226:229], v[18:21]
	v_mfma_f32_16x16x32_bf16 v[6:9], v[98:101], v[234:237], v[6:9]
	v_mfma_f32_16x16x32_bf16 v[2:5], v[106:109], v[234:237], v[2:5]
	v_mfma_f32_16x16x32_bf16 v[50:53], v[110:113], v[222:225], v[34:37]
	v_mfma_f32_16x16x32_bf16 v[22:25], v[102:105], v[230:233], v[22:25]
	v_mfma_f32_16x16x32_bf16 v[18:21], v[110:113], v[230:233], v[18:21]
	v_mfma_f32_16x16x32_bf16 v[6:9], v[102:105], v[238:241], v[6:9]
	v_mfma_f32_16x16x32_bf16 v[2:5], v[110:113], v[238:241], v[2:5]
	s_barrier
	s_add_i32 s34, s34, 2
	s_add_u32 s24, s24, 0x100
	s_addc_u32 s25, s25, 0
	s_add_u32 s20, s20, 0x100
	s_addc_u32 s21, s21, 0
	s_cmp_lt_u32 s34, 30
; #define PG8_STAGE(bufoff, gbase, voff) do { _Pragma("unroll") for (int _i = 0; _i < 2; ++_i) \
;         __builtin_amdgcn_global_load_lds((const unsigned*)((const char*)(gbase) + (voff)[_i]), (LAS unsigned*)(lds + (bufoff) + ldsw + _i * 8192), 16, 0, 0); } while (0)
; #define PG8_LDA(dst, b, h) do { _Pragma("unroll") for (int m = 0; m < 4; ++m) _Pragma("unroll") for (int k = 0; k < 2; ++k) dst[m][k] = *(const LAS bf16x8*)(lds + PG8_SA(b, h) + aoff + m * 2048 + k * 1024); } while (0)
; #define PG8_LDB(dst, b, h) do { _Pragma("unroll") for (int n = 0; n < 2; ++n) _Pragma("unroll") for (int k = 0; k < 2; ++k) dst[n][k] = *(const LAS bf16x8*)(lds + PG8_SB(b, h) + boff + n * 2048 + k * 1024); } while (0)
; #define PG8_MMA(ai, bj, At, Bt) do { __builtin_amdgcn_s_setprio(1); _Pragma("unroll") for (int m = 0; m < 4; ++m) _Pragma("unroll") for (int n = 0; n < 2; ++n) _Pragma("unroll") for (int k = 0; k < 2; ++k) \
;         acc[ai][bj][m][n] = __builtin_amdgcn_mfma_f32_16x16x32_bf16(Bt[n][k], At[m][k], acc[ai][bj][m][n], 0, 0, 0); __builtin_amdgcn_s_setprio(0); } while (0)
; #define PG8_WAIT_V(n) asm volatile("s_waitcnt vmcnt(" #n ")" ::: "memory")
; #define PG8_WAIT_L(n) asm volatile("s_waitcnt lgkmcnt(" #n ")" ::: "memory")
; #define PG8_BAR __builtin_amdgcn_s_barrier()
; #define PG8_SCHED __builtin_amdgcn_sched_barrier(0)
; template <class Epi, class Sched, bool ALIGN_EPI = false, bool SP2 = false>
; __device__ __forceinline__ void gemm_phase(LAS unsigned char* lds, const Gemm g, const Sched& S, const Epi& E) {
;     ...
;         for (int t = 0; t < nt; t += 2) {
;             const bool last = (t == nt - 2);
;             const char* a1 = cA + (size_t)(t + 1) * kstep;
;             const char* a2 = last ? nA : cA + (size_t)(t + 2) * kstep; const char* b2 = last ? nB : cB + (size_t)(t + 2) * kstep;
;             const char* a3 = a2 + kstep; const char* b3 = b2 + kstep;
;             if (last && has_next) S.a_ready(nxt);
;             if constexpr (SP2) {
;             PG8_LDB(B0, 0, 0); PG8_LDB(B1, 0, 1); PG8_SCHED; PG8_LDA(At, 0, 0); PG8_STAGE(PG8_SA(1, 1), a1 + hstep, voffA);
;             PG8_WAIT_V(8); PG8_WAIT_L(0); PG8_BAR; PG8_MMA(0, 0, At, B0); PG8_MMA(0, 1, At, B1); PG8_BAR; PG8_SCHED;
;             PG8_LDA(At, 0, 1); PG8_STAGE(PG8_SB(0, 0), b2, voffB); PG8_STAGE(PG8_SB(0, 1), b2 + hstepB, voffB); PG8_STAGE(PG8_SA(0, 0), a2, voffA);
.LBB0_2143:
	ds_read_b128 v[34:37], v202
	ds_read_b128 v[38:41], v202 offset:1024
	ds_read_b128 v[42:45], v202 offset:2048
	ds_read_b128 v[46:49], v202 offset:3072
	ds_read_b128 v[98:101], v203
	ds_read_b128 v[102:105], v203 offset:1024
	ds_read_b128 v[106:109], v203 offset:2048
	ds_read_b128 v[110:113], v203 offset:3072
	s_add_u32 s22, s20, 0xfff80080
	s_addc_u32 s23, s21, -1
	s_cmp_eq_u32 s34, 28
	s_cselect_b32 s37, s3, s23
	s_cselect_b32 s36, s13, s22
	s_cselect_b32 s23, s11, s25
	s_cselect_b32 s22, s19, s24
	v_lshl_add_u64 v[182:183], s[20:21], 0, v[174:175]
	s_add_i32 m0, s28, 0xc000
	ds_read_b128 v[210:213], v204
	ds_read_b128 v[214:217], v204 offset:1024
	ds_read_b128 v[218:221], v204 offset:2048
	ds_read_b128 v[222:225], v204 offset:3072
	ds_read_b128 v[226:229], v204 offset:4096
	ds_read_b128 v[230:233], v204 offset:5120
	ds_read_b128 v[234:237], v204 offset:6144
	ds_read_b128 v[238:241], v204 offset:7168
	global_load_lds_dwordx4 v[182:183], off
	v_lshl_add_u64 v[182:183], s[20:21], 0, v[172:173]
	s_add_i32 m0, s28, 0xe000
	s_nop 0
	global_load_lds_dwordx4 v[182:183], off
	s_waitcnt vmcnt(8)
	s_waitcnt lgkmcnt(0)
	s_barrier
	v_mfma_f32_16x16x32_bf16 v[158:161], v[34:37], v[210:213], v[158:161]
	v_mfma_f32_16x16x32_bf16 v[154:157], v[42:45], v[210:213], v[154:157]
	v_mfma_f32_16x16x32_bf16 v[142:145], v[34:37], v[218:221], v[142:145]
	v_mfma_f32_16x16x32_bf16 v[138:141], v[42:45], v[218:221], v[138:141]
	v_mfma_f32_16x16x32_bf16 v[126:129], v[34:37], v[226:229], v[126:129]
	v_mfma_f32_16x16x32_bf16 v[122:125], v[42:45], v[226:229], v[122:125]
	v_mfma_f32_16x16x32_bf16 v[94:97], v[34:37], v[234:237], v[94:97]
	v_mfma_f32_16x16x32_bf16 v[90:93], v[42:45], v[234:237], v[90:93]
	v_mfma_f32_16x16x32_bf16 v[158:161], v[38:41], v[214:217], v[158:161]
	v_mfma_f32_16x16x32_bf16 v[154:157], v[46:49], v[214:217], v[154:157]
	v_mfma_f32_16x16x32_bf16 v[142:145], v[38:41], v[222:225], v[142:145]
	v_mfma_f32_16x16x32_bf16 v[138:141], v[46:49], v[222:225], v[138:141]
	v_mfma_f32_16x16x32_bf16 v[126:129], v[38:41], v[230:233], v[126:129]
	v_mfma_f32_16x16x32_bf16 v[122:125], v[46:49], v[230:233], v[122:125]
	v_mfma_f32_16x16x32_bf16 v[94:97], v[38:41], v[238:241], v[94:97]
	v_mfma_f32_16x16x32_bf16 v[90:93], v[46:49], v[238:241], v[90:93]
	v_mfma_f32_16x16x32_bf16 v[150:153], v[98:101], v[210:213], v[150:153]
	v_mfma_f32_16x16x32_bf16 v[146:149], v[106:109], v[210:213], v[146:149]
	v_mfma_f32_16x16x32_bf16 v[134:137], v[98:101], v[218:221], v[134:137]
	v_mfma_f32_16x16x32_bf16 v[130:133], v[106:109], v[218:221], v[130:133]
	v_mfma_f32_16x16x32_bf16 v[118:121], v[98:101], v[226:229], v[118:121]
	v_mfma_f32_16x16x32_bf16 v[114:117], v[106:109], v[226:229], v[114:117]
	v_mfma_f32_16x16x32_bf16 v[86:89], v[98:101], v[234:237], v[86:89]
	v_mfma_f32_16x16x32_bf16 v[82:85], v[106:109], v[234:237], v[82:85]
	v_mfma_f32_16x16x32_bf16 v[150:153], v[102:105], v[214:217], v[150:153]
	v_mfma_f32_16x16x32_bf16 v[146:149], v[110:113], v[214:217], v[146:149]
	v_mfma_f32_16x16x32_bf16 v[134:137], v[102:105], v[222:225], v[134:137]
	v_mfma_f32_16x16x32_bf16 v[130:133], v[110:113], v[222:225], v[130:133]
	v_mfma_f32_16x16x32_bf16 v[118:121], v[102:105], v[230:233], v[118:121]
	v_mfma_f32_16x16x32_bf16 v[114:117], v[110:113], v[230:233], v[114:117]
	v_mfma_f32_16x16x32_bf16 v[86:89], v[102:105], v[238:241], v[86:89]
	v_mfma_f32_16x16x32_bf16 v[82:85], v[110:113], v[238:241], v[82:85]
	s_barrier
	s_add_i32 s35, s56, s27
	v_lshl_add_u64 v[182:183], s[22:23], 0, v[164:165]
	s_mov_b32 m0, s35
	ds_read_b128 v[210:213], v204 offset:16384
	ds_read_b128 v[214:217], v204 offset:17408
	ds_read_b128 v[218:221], v204 offset:18432
	ds_read_b128 v[222:225], v204 offset:19456
	ds_read_b128 v[226:229], v204 offset:20480
	ds_read_b128 v[230:233], v204 offset:21504
	ds_read_b128 v[234:237], v204 offset:22528
	ds_read_b128 v[238:241], v204 offset:23552
	global_load_lds_dwordx4 v[182:183], off
	s_add_i32 m0, s35, 0x2000
	s_add_u32 s46, s22, 0x20000
	v_lshl_add_u64 v[242:243], s[22:23], 0, v[168:169]
	s_addc_u32 s47, s23, 0
	s_add_i32 s35, s57, s27
	global_load_lds_dwordx4 v[242:243], off
	v_lshl_add_u64 v[244:245], s[46:47], 0, v[164:165]
	s_mov_b32 m0, s35
	v_lshl_add_u64 v[246:247], s[36:37], 0, v[166:167]
	global_load_lds_dwordx4 v[244:245], off
	v_lshl_add_u64 v[244:245], s[46:47], 0, v[168:169]
	s_add_i32 m0, s35, 0x2000
	s_nop 0
	global_load_lds_dwordx4 v[244:245], off
	v_lshl_add_u64 v[244:245], s[36:37], 0, v[162:163]
	s_mov_b32 m0, s28
	s_nop 0
	global_load_lds_dwordx4 v[244:245], off
	s_mov_b32 m0, s29
	s_nop 0
	global_load_lds_dwordx4 v[246:247], off
	s_waitcnt vmcnt(8)
	s_waitcnt lgkmcnt(0)
	s_barrier
; #define PG8_STAGE(bufoff, gbase, voff) do { _Pragma("unroll") for (int _i = 0; _i < 2; ++_i) \
;         __builtin_amdgcn_global_load_lds((const unsigned*)((const char*)(gbase) + (voff)[_i]), (LAS unsigned*)(lds + (bufoff) + ldsw + _i * 8192), 16, 0, 0); } while (0)
; #define PG8_LDA(dst, b, h) do { _Pragma("unroll") for (int m = 0; m < 4; ++m) _Pragma("unroll") for (int k = 0; k < 2; ++k) dst[m][k] = *(const LAS bf16x8*)(lds + PG8_SA(b, h) + aoff + m * 2048 + k * 1024); } while (0)
; #define PG8_LDB(dst, b, h) do { _Pragma("unroll") for (int n = 0; n < 2; ++n) _Pragma("unroll") for (int k = 0; k < 2; ++k) dst[n][k] = *(const LAS bf16x8*)(lds + PG8_SB(b, h) + boff + n * 2048 + k * 1024); } while (0)
; #define PG8_MMA(ai, bj, At, Bt) do { __builtin_amdgcn_s_setprio(1); _Pragma("unroll") for (int m = 0; m < 4; ++m) _Pragma("unroll") for (int n = 0; n < 2; ++n) _Pragma("unroll") for (int k = 0; k < 2; ++k) \
;         acc[ai][bj][m][n] = __builtin_amdgcn_mfma_f32_16x16x32_bf16(Bt[n][k], At[m][k], acc[ai][bj][m][n], 0, 0, 0); __builtin_amdgcn_s_setprio(0); } while (0)
; #define PG8_WAIT_V(n) asm volatile("s_waitcnt vmcnt(" #n ")" ::: "memory")
; #define PG8_WAIT_L(n) asm volatile("s_waitcnt lgkmcnt(" #n ")" ::: "memory")
; #define PG8_BAR __builtin_amdgcn_s_barrier()
; #define PG8_SCHED __builtin_amdgcn_sched_barrier(0)
; template <class Epi, class Sched, bool ALIGN_EPI = false, bool SP2 = false>
; __device__ __forceinline__ void gemm_phase(LAS unsigned char* lds, const Gemm g, const Sched& S, const Epi& E) {
;     ...
;             PG8_WAIT_V(8); PG8_WAIT_L(0); PG8_BAR; PG8_MMA(1, 0, At, B0); PG8_MMA(1, 1, At, B1); PG8_BAR; PG8_SCHED;
;             PG8_LDB(B0, 1, 0); PG8_LDB(B1, 1, 1); PG8_SCHED; PG8_LDA(At, 1, 0); PG8_STAGE(PG8_SA(0, 1), a2 + hstep, voffA);
;             PG8_WAIT_V(8); PG8_WAIT_L(0); PG8_BAR; PG8_MMA(0, 0, At, B0); PG8_MMA(0, 1, At, B1); PG8_BAR; PG8_SCHED;
	v_mfma_f32_16x16x32_bf16 v[78:81], v[34:37], v[210:213], v[78:81]
	v_mfma_f32_16x16x32_bf16 v[74:77], v[42:45], v[210:213], v[74:77]
	v_mfma_f32_16x16x32_bf16 v[62:65], v[34:37], v[218:221], v[62:65]
	v_mfma_f32_16x16x32_bf16 v[58:61], v[42:45], v[218:221], v[58:61]
	v_mfma_f32_16x16x32_bf16 v[30:33], v[34:37], v[226:229], v[30:33]
	v_mfma_f32_16x16x32_bf16 v[26:29], v[42:45], v[226:229], v[26:29]
	v_mfma_f32_16x16x32_bf16 v[14:17], v[34:37], v[234:237], v[14:17]
	v_mfma_f32_16x16x32_bf16 v[10:13], v[42:45], v[234:237], v[10:13]
	v_mfma_f32_16x16x32_bf16 v[78:81], v[38:41], v[214:217], v[78:81]
	v_mfma_f32_16x16x32_bf16 v[74:77], v[46:49], v[214:217], v[74:77]
	v_mfma_f32_16x16x32_bf16 v[62:65], v[38:41], v[222:225], v[62:65]
	v_mfma_f32_16x16x32_bf16 v[58:61], v[46:49], v[222:225], v[58:61]
	v_mfma_f32_16x16x32_bf16 v[30:33], v[38:41], v[230:233], v[30:33]
	v_mfma_f32_16x16x32_bf16 v[26:29], v[46:49], v[230:233], v[26:29]
	v_mfma_f32_16x16x32_bf16 v[14:17], v[38:41], v[238:241], v[14:17]
	v_mfma_f32_16x16x32_bf16 v[10:13], v[46:49], v[238:241], v[10:13]
	v_mfma_f32_16x16x32_bf16 v[22:25], v[98:101], v[226:229], v[22:25]
	v_mfma_f32_16x16x32_bf16 v[18:21], v[106:109], v[226:229], v[18:21]
	v_mfma_f32_16x16x32_bf16 v[6:9], v[98:101], v[234:237], v[6:9]
	v_mfma_f32_16x16x32_bf16 v[2:5], v[106:109], v[234:237], v[2:5]
	v_mfma_f32_16x16x32_bf16 v[34:37], v[98:101], v[210:213], v[70:73]
	v_mfma_f32_16x16x32_bf16 v[38:41], v[106:109], v[210:213], v[66:69]
	v_mfma_f32_16x16x32_bf16 v[42:45], v[98:101], v[218:221], v[54:57]
	v_mfma_f32_16x16x32_bf16 v[46:49], v[106:109], v[218:221], v[50:53]
	v_mfma_f32_16x16x32_bf16 v[22:25], v[102:105], v[230:233], v[22:25]
	v_mfma_f32_16x16x32_bf16 v[18:21], v[110:113], v[230:233], v[18:21]
	v_mfma_f32_16x16x32_bf16 v[6:9], v[102:105], v[238:241], v[6:9]
	v_mfma_f32_16x16x32_bf16 v[2:5], v[110:113], v[238:241], v[2:5]
	v_mfma_f32_16x16x32_bf16 v[34:37], v[102:105], v[214:217], v[34:37]
	v_mfma_f32_16x16x32_bf16 v[38:41], v[110:113], v[214:217], v[38:41]
	v_mfma_f32_16x16x32_bf16 v[42:45], v[102:105], v[222:225], v[42:45]
	v_mfma_f32_16x16x32_bf16 v[46:49], v[110:113], v[222:225], v[46:49]
	s_barrier
	s_add_i32 s35, 0, 0x18000
	s_add_i32 s46, 0, 0x1c000
	v_add_u32_e32 v70, s35, v185
	v_add_u32_e32 v110, s46, v185
	ds_read_b128 v[50:53], v70
	ds_read_b128 v[54:57], v70 offset:1024
	ds_read_b128 v[66:69], v70 offset:2048
	ds_read_b128 v[70:73], v70 offset:3072
	ds_read_b128 v[98:101], v110
	ds_read_b128 v[102:105], v110 offset:1024
	ds_read_b128 v[106:109], v110 offset:2048
	ds_read_b128 v[110:113], v110 offset:3072
	s_add_u32 s36, s36, 0x80000
	s_addc_u32 s37, s37, 0
	s_mov_b32 m0, s30
	v_lshl_add_u64 v[248:249], s[36:37], 0, v[162:163]
	ds_read_b128 v[210:213], v204 offset:32768
	ds_read_b128 v[214:217], v204 offset:33792
	ds_read_b128 v[218:221], v204 offset:34816
	ds_read_b128 v[222:225], v204 offset:35840
	ds_read_b128 v[226:229], v204 offset:36864
	ds_read_b128 v[230:233], v204 offset:37888
	ds_read_b128 v[234:237], v204 offset:38912
	ds_read_b128 v[238:241], v204 offset:39936
	global_load_lds_dwordx4 v[248:249], off
	v_lshl_add_u64 v[248:249], s[36:37], 0, v[166:167]
	s_mov_b32 m0, s31
	s_nop 0
	global_load_lds_dwordx4 v[248:249], off
	s_waitcnt vmcnt(8)
	s_waitcnt lgkmcnt(0)
	s_barrier
	v_mfma_f32_16x16x32_bf16 v[158:161], v[50:53], v[210:213], v[158:161]
	v_mfma_f32_16x16x32_bf16 v[154:157], v[66:69], v[210:213], v[154:157]
	v_mfma_f32_16x16x32_bf16 v[142:145], v[50:53], v[218:221], v[142:145]
	v_mfma_f32_16x16x32_bf16 v[138:141], v[66:69], v[218:221], v[138:141]
	v_mfma_f32_16x16x32_bf16 v[126:129], v[50:53], v[226:229], v[126:129]
	v_mfma_f32_16x16x32_bf16 v[122:125], v[66:69], v[226:229], v[122:125]
	v_mfma_f32_16x16x32_bf16 v[94:97], v[50:53], v[234:237], v[94:97]
	v_mfma_f32_16x16x32_bf16 v[90:93], v[66:69], v[234:237], v[90:93]
	v_mfma_f32_16x16x32_bf16 v[158:161], v[54:57], v[214:217], v[158:161]
	v_mfma_f32_16x16x32_bf16 v[154:157], v[70:73], v[214:217], v[154:157]
	v_mfma_f32_16x16x32_bf16 v[142:145], v[54:57], v[222:225], v[142:145]
	v_mfma_f32_16x16x32_bf16 v[138:141], v[70:73], v[222:225], v[138:141]
	v_mfma_f32_16x16x32_bf16 v[126:129], v[54:57], v[230:233], v[126:129]
	v_mfma_f32_16x16x32_bf16 v[122:125], v[70:73], v[230:233], v[122:125]
	v_mfma_f32_16x16x32_bf16 v[94:97], v[54:57], v[238:241], v[94:97]
	v_mfma_f32_16x16x32_bf16 v[90:93], v[70:73], v[238:241], v[90:93]
	v_mfma_f32_16x16x32_bf16 v[150:153], v[98:101], v[210:213], v[150:153]
	v_mfma_f32_16x16x32_bf16 v[146:149], v[106:109], v[210:213], v[146:149]
	v_mfma_f32_16x16x32_bf16 v[134:137], v[98:101], v[218:221], v[134:137]
	v_mfma_f32_16x16x32_bf16 v[130:133], v[106:109], v[218:221], v[130:133]
	v_mfma_f32_16x16x32_bf16 v[118:121], v[98:101], v[226:229], v[118:121]
	v_mfma_f32_16x16x32_bf16 v[114:117], v[106:109], v[226:229], v[114:117]
	v_mfma_f32_16x16x32_bf16 v[86:89], v[98:101], v[234:237], v[86:89]
	v_mfma_f32_16x16x32_bf16 v[82:85], v[106:109], v[234:237], v[82:85]
	v_mfma_f32_16x16x32_bf16 v[150:153], v[102:105], v[214:217], v[150:153]
	v_mfma_f32_16x16x32_bf16 v[146:149], v[110:113], v[214:217], v[146:149]
	v_mfma_f32_16x16x32_bf16 v[134:137], v[102:105], v[222:225], v[134:137]
	v_mfma_f32_16x16x32_bf16 v[130:133], v[110:113], v[222:225], v[130:133]
	v_mfma_f32_16x16x32_bf16 v[118:121], v[102:105], v[230:233], v[118:121]
	v_mfma_f32_16x16x32_bf16 v[114:117], v[110:113], v[230:233], v[114:117]
	v_mfma_f32_16x16x32_bf16 v[86:89], v[102:105], v[238:241], v[86:89]
	v_mfma_f32_16x16x32_bf16 v[82:85], v[110:113], v[238:241], v[82:85]
	s_barrier
; #define PG8_STAGE(bufoff, gbase, voff) do { _Pragma("unroll") for (int _i = 0; _i < 2; ++_i) \
;         __builtin_amdgcn_global_load_lds((const unsigned*)((const char*)(gbase) + (voff)[_i]), (LAS unsigned*)(lds + (bufoff) + ldsw + _i * 8192), 16, 0, 0); } while (0)
; #define PG8_WAIT_V(n) asm volatile("s_waitcnt vmcnt(" #n ")" ::: "memory")
; #define PG8_WAIT_L(n) asm volatile("s_waitcnt lgkmcnt(" #n ")" ::: "memory")
; template <class Epi, class Sched, bool ALIGN_EPI = false, bool SP2 = false>
; __device__ __forceinline__ void gemm_phase(LAS unsigned char* lds, const Gemm g, const Sched& S, const Epi& E) {
;     ...
;             PG8_LDA(At, 1, 1); PG8_STAGE(PG8_SB(1, 0), b3, voffB); PG8_STAGE(PG8_SB(1, 1), b3 + hstepB, voffB); PG8_STAGE(PG8_SA(1, 0), a3, voffA);
;             PG8_WAIT_V(8); PG8_WAIT_L(0); PG8_BAR; PG8_MMA(1, 0, At, B0); PG8_MMA(1, 1, At, B1); PG8_BAR; PG8_SCHED;
;             } else {
;             PG8_LDB(B0, 0, 0); PG8_SCHED; PG8_LDA(At, 0, 0); PG8_STAGE(PG8_SA(1, 1), a1 + hstep, voffA);
;             PG8_WAIT_L(8); PG8_BAR; PG8_WAIT_L(0); PG8_MMA(0, 0, At, B0); PG8_BAR; PG8_SCHED;
;             PG8_LDB(B1, 0, 1); PG8_STAGE(PG8_SB(0, 0), b2, voffB);
;             PG8_BAR; PG8_WAIT_L(0); PG8_MMA(0, 1, At, B1); PG8_BAR;
;             PG8_LDA(At, 0, 1); PG8_STAGE(PG8_SA(0, 0), a2, voffA);
;             PG8_BAR; PG8_WAIT_L(0); PG8_MMA(1, 0, At, B0); PG8_BAR; PG8_SCHED;
;             PG8_STAGE(PG8_SB(0, 1), b2 + hstepB, voffB);
;             PG8_WAIT_V(6); PG8_BAR; PG8_MMA(1, 1, At, B1); PG8_BAR;
;             PG8_LDB(B0, 1, 0); PG8_SCHED; PG8_LDA(At, 1, 0); PG8_STAGE(PG8_SA(0, 1), a2 + hstep, voffA);
;             PG8_WAIT_L(8); PG8_BAR; PG8_WAIT_L(0); PG8_MMA(0, 0, At, B0); PG8_BAR; PG8_SCHED;
;             PG8_LDB(B1, 1, 1); PG8_STAGE(PG8_SB(1, 0), b3, voffB);
;             PG8_BAR; PG8_WAIT_L(0); PG8_MMA(0, 1, At, B1); PG8_BAR;
;             PG8_LDA(At, 1, 1); PG8_STAGE(PG8_SA(1, 0), a3, voffA);
;             PG8_BAR; PG8_WAIT_L(0); PG8_MMA(1, 0, At, B0); PG8_BAR; PG8_SCHED;
;             PG8_STAGE(PG8_SB(1, 1), b3 + hstepB, voffB);
;             PG8_WAIT_V(6); PG8_BAR; PG8_MMA(1, 1, At, B1); PG8_BAR;
;             }
;         }
;         if constexpr (ALIGN_EPI) { if (wr == 0) PG8_BAR; }
;         if constexpr (!Epi::AFTER_DRAIN) { E(acc, cur, wr, wc, fr, fq); S.done(cur); }
;         if (!has_next) break;
	s_add_i32 s35, s35, s27
	v_lshl_add_u64 v[182:183], v[182:183], 0, s[4:5]
	s_mov_b32 m0, s35
	ds_read_b128 v[210:213], v204 offset:49152
	ds_read_b128 v[214:217], v204 offset:50176
	ds_read_b128 v[218:221], v204 offset:51200
	ds_read_b128 v[222:225], v204 offset:52224
	ds_read_b128 v[226:229], v204 offset:53248
	ds_read_b128 v[230:233], v204 offset:54272
	ds_read_b128 v[234:237], v204 offset:55296
	ds_read_b128 v[238:241], v204 offset:56320
	global_load_lds_dwordx4 v[182:183], off
	s_add_i32 m0, s35, 0x2000
	s_add_u32 s22, s22, 0x20080
	v_lshl_add_u64 v[182:183], v[242:243], 0, s[4:5]
	s_addc_u32 s23, s23, 0
	s_add_i32 s35, s46, s27
	global_load_lds_dwordx4 v[182:183], off
	v_lshl_add_u64 v[182:183], s[22:23], 0, v[164:165]
	s_mov_b32 m0, s35
	s_nop 0
	global_load_lds_dwordx4 v[182:183], off
	v_lshl_add_u64 v[182:183], s[22:23], 0, v[168:169]
	s_add_i32 m0, s35, 0x2000
	s_nop 0
	global_load_lds_dwordx4 v[182:183], off
	v_lshl_add_u64 v[182:183], v[244:245], 0, s[4:5]
	s_mov_b32 m0, s53
	s_nop 0
	global_load_lds_dwordx4 v[182:183], off
	v_lshl_add_u64 v[182:183], v[246:247], 0, s[4:5]
	s_mov_b32 m0, s54
	s_nop 0
	global_load_lds_dwordx4 v[182:183], off
	s_waitcnt vmcnt(8)
	s_waitcnt lgkmcnt(0)
	s_barrier
	v_mfma_f32_16x16x32_bf16 v[78:81], v[50:53], v[210:213], v[78:81]
	v_mfma_f32_16x16x32_bf16 v[74:77], v[66:69], v[210:213], v[74:77]
	v_mfma_f32_16x16x32_bf16 v[62:65], v[50:53], v[218:221], v[62:65]
	v_mfma_f32_16x16x32_bf16 v[58:61], v[66:69], v[218:221], v[58:61]
	v_mfma_f32_16x16x32_bf16 v[30:33], v[50:53], v[226:229], v[30:33]
	v_mfma_f32_16x16x32_bf16 v[26:29], v[66:69], v[226:229], v[26:29]
	v_mfma_f32_16x16x32_bf16 v[14:17], v[50:53], v[234:237], v[14:17]
	v_mfma_f32_16x16x32_bf16 v[10:13], v[66:69], v[234:237], v[10:13]
	v_mfma_f32_16x16x32_bf16 v[78:81], v[54:57], v[214:217], v[78:81]
	v_mfma_f32_16x16x32_bf16 v[74:77], v[70:73], v[214:217], v[74:77]
	v_mfma_f32_16x16x32_bf16 v[62:65], v[54:57], v[222:225], v[62:65]
	v_mfma_f32_16x16x32_bf16 v[58:61], v[70:73], v[222:225], v[58:61]
	v_mfma_f32_16x16x32_bf16 v[30:33], v[54:57], v[230:233], v[30:33]
	v_mfma_f32_16x16x32_bf16 v[26:29], v[70:73], v[230:233], v[26:29]
	v_mfma_f32_16x16x32_bf16 v[14:17], v[54:57], v[238:241], v[14:17]
	v_mfma_f32_16x16x32_bf16 v[10:13], v[70:73], v[238:241], v[10:13]
	v_mfma_f32_16x16x32_bf16 v[34:37], v[98:101], v[210:213], v[34:37]
	v_mfma_f32_16x16x32_bf16 v[70:73], v[102:105], v[214:217], v[34:37]
	v_mfma_f32_16x16x32_bf16 v[34:37], v[106:109], v[210:213], v[38:41]
	v_mfma_f32_16x16x32_bf16 v[66:69], v[110:113], v[214:217], v[34:37]
	v_mfma_f32_16x16x32_bf16 v[34:37], v[98:101], v[218:221], v[42:45]
	v_mfma_f32_16x16x32_bf16 v[54:57], v[102:105], v[222:225], v[34:37]
	v_mfma_f32_16x16x32_bf16 v[34:37], v[106:109], v[218:221], v[46:49]
	v_mfma_f32_16x16x32_bf16 v[22:25], v[98:101], v[226:229], v[22:25]
	v_mfma_f32_16x16x32_bf16 v[18:21], v[106:109], v[226:229], v[18:21]
	v_mfma_f32_16x16x32_bf16 v[6:9], v[98:101], v[234:237], v[6:9]
	v_mfma_f32_16x16x32_bf16 v[2:5], v[106:109], v[234:237], v[2:5]
	v_mfma_f32_16x16x32_bf16 v[50:53], v[110:113], v[222:225], v[34:37]
	v_mfma_f32_16x16x32_bf16 v[22:25], v[102:105], v[230:233], v[22:25]
	v_mfma_f32_16x16x32_bf16 v[18:21], v[110:113], v[230:233], v[18:21]
	v_mfma_f32_16x16x32_bf16 v[6:9], v[102:105], v[238:241], v[6:9]
	v_mfma_f32_16x16x32_bf16 v[2:5], v[110:113], v[238:241], v[2:5]
	s_barrier
	s_add_i32 s34, s34, 2
	s_add_u32 s24, s24, 0x100
	s_addc_u32 s25, s25, 0
	s_add_u32 s20, s20, 0x100
	s_addc_u32 s21, s21, 0
	s_cmp_lt_u32 s34, 30
	s_cbranch_scc1 .LBB0_2143
	s_setprio 0
	s_andn2_b64 vcc, exec, s[8:9]
	s_cbranch_vccnz .LBB0_2146
	s_barrier

; #define PG8_STAGE(bufoff, gbase, voff) do { _Pragma("unroll") for (int _i = 0; _i < 2; ++_i) \
;         __builtin_amdgcn_global_load_lds((const unsigned*)((const char*)(gbase) + (voff)[_i]), (LAS unsigned*)(lds + (bufoff) + ldsw + _i * 8192), 16, 0, 0); } while (0)
; #define PG8_LDA(dst, b, h) do { _Pragma("unroll") for (int m = 0; m < 4; ++m) _Pragma("unroll") for (int k = 0; k < 2; ++k) dst[m][k] = *(const LAS bf16x8*)(lds + PG8_SA(b, h) + aoff + m * 2048 + k * 1024); } while (0)
; #define PG8_LDB(dst, b, h) do { _Pragma("unroll") for (int n = 0; n < 2; ++n) _Pragma("unroll") for (int k = 0; k < 2; ++k) dst[n][k] = *(const LAS bf16x8*)(lds + PG8_SB(b, h) + boff + n * 2048 + k * 1024); } while (0)
; #define PG8_MMA(ai, bj, At, Bt) do { __builtin_amdgcn_s_setprio(1); _Pragma("unroll") for (int m = 0; m < 4; ++m) _Pragma("unroll") for (int n = 0; n < 2; ++n) _Pragma("unroll") for (int k = 0; k < 2; ++k) \
;         acc[ai][bj][m][n] = __builtin_amdgcn_mfma_f32_16x16x32_bf16(Bt[n][k], At[m][k], acc[ai][bj][m][n], 0, 0, 0); __builtin_amdgcn_s_setprio(0); } while (0)
; #define PG8_WAIT_V(n) asm volatile("s_waitcnt vmcnt(" #n ")" ::: "memory")
; #define PG8_WAIT_L(n) asm volatile("s_waitcnt lgkmcnt(" #n ")" ::: "memory")
; #define PG8_BAR __builtin_amdgcn_s_barrier()
; #define PG8_SCHED __builtin_amdgcn_sched_barrier(0)
; template <class Epi, class Sched, bool ALIGN_EPI = false, bool SP2 = false>
; __device__ __forceinline__ void gemm_phase(LAS unsigned char* lds, const Gemm g, const Sched& S, const Epi& E) {
;     ...
;             if constexpr (SP2) {
;             PG8_LDB(B0, 0, 0); PG8_LDB(B1, 0, 1); PG8_SCHED; PG8_LDA(At, 0, 0); PG8_STAGE(PG8_SA(1, 1), a1 + hstep, voffA);
;             PG8_WAIT_V(8); PG8_WAIT_L(0); PG8_BAR; PG8_MMA(0, 0, At, B0); PG8_MMA(0, 1, At, B1); PG8_BAR; PG8_SCHED;
;             PG8_LDA(At, 0, 1); PG8_STAGE(PG8_SB(0, 0), b2, voffB); PG8_STAGE(PG8_SB(0, 1), b2 + hstepB, voffB); PG8_STAGE(PG8_SA(0, 0), a2, voffA);
;             PG8_WAIT_V(8); PG8_WAIT_L(0); PG8_BAR; PG8_MMA(1, 0, At, B0); PG8_MMA(1, 1, At, B1); PG8_BAR; PG8_SCHED;
.Lprio_2766:
	ds_read_b128 v[50:53], v196
	ds_read_b128 v[54:57], v196 offset:1024
	ds_read_b128 v[138:141], v196 offset:2048
	ds_read_b128 v[142:145], v196 offset:3072
	ds_read_b128 v[146:149], v197
	ds_read_b128 v[150:153], v197 offset:1024
	ds_read_b128 v[174:177], v197 offset:2048
	ds_read_b128 v[178:181], v197 offset:3072
	s_add_u32 s24, s22, 0xfff80080
	s_addc_u32 s25, s23, -1
	s_cmp_eq_u32 s55, 28
	s_cselect_b32 s35, s3, s25
	s_cselect_b32 s34, s15, s24
	s_cselect_b32 s25, s13, s54
	s_cselect_b32 s24, s21, s53
	v_lshl_add_u64 v[190:191], s[22:23], 0, v[168:169]
	s_add_i32 m0, s28, 0xc000
	ds_read_b128 v[182:185], v198
	ds_read_b128 v[186:189], v198 offset:1024
	ds_read_b128 v[202:205], v198 offset:2048
	ds_read_b128 v[206:209], v198 offset:3072
	ds_read_b128 v[210:213], v198 offset:4096
	ds_read_b128 v[214:217], v198 offset:5120
	ds_read_b128 v[218:221], v198 offset:6144
	ds_read_b128 v[222:225], v198 offset:7168
	global_load_lds_dwordx4 v[190:191], off
	v_lshl_add_u64 v[190:191], s[22:23], 0, v[166:167]
	s_add_i32 m0, s28, 0xe000
	s_nop 0
	global_load_lds_dwordx4 v[190:191], off
	s_waitcnt lgkmcnt(0)
	s_barrier
	v_mfma_f32_16x16x32_bf16 v[134:137], v[50:53], v[182:185], 0
	v_mfma_f32_16x16x32_bf16 v[130:133], v[138:141], v[182:185], 0
	v_mfma_f32_16x16x32_bf16 v[118:121], v[50:53], v[202:205], 0
	v_mfma_f32_16x16x32_bf16 v[114:117], v[138:141], v[202:205], 0
	v_mfma_f32_16x16x32_bf16 v[102:105], v[50:53], v[210:213], 0
	v_mfma_f32_16x16x32_bf16 v[98:101], v[138:141], v[210:213], 0
	v_mfma_f32_16x16x32_bf16 v[86:89], v[50:53], v[218:221], 0
	v_mfma_f32_16x16x32_bf16 v[82:85], v[138:141], v[218:221], 0
	v_mfma_f32_16x16x32_bf16 v[134:137], v[54:57], v[186:189], v[134:137]
	v_mfma_f32_16x16x32_bf16 v[130:133], v[142:145], v[186:189], v[130:133]
	v_mfma_f32_16x16x32_bf16 v[118:121], v[54:57], v[206:209], v[118:121]
	v_mfma_f32_16x16x32_bf16 v[114:117], v[142:145], v[206:209], v[114:117]
	v_mfma_f32_16x16x32_bf16 v[102:105], v[54:57], v[214:217], v[102:105]
	v_mfma_f32_16x16x32_bf16 v[98:101], v[142:145], v[214:217], v[98:101]
	v_mfma_f32_16x16x32_bf16 v[86:89], v[54:57], v[222:225], v[86:89]
	v_mfma_f32_16x16x32_bf16 v[82:85], v[142:145], v[222:225], v[82:85]
	v_mfma_f32_16x16x32_bf16 v[126:129], v[146:149], v[182:185], 0
	v_mfma_f32_16x16x32_bf16 v[122:125], v[174:177], v[182:185], 0
	v_mfma_f32_16x16x32_bf16 v[110:113], v[146:149], v[202:205], 0
	v_mfma_f32_16x16x32_bf16 v[106:109], v[174:177], v[202:205], 0
	v_mfma_f32_16x16x32_bf16 v[94:97], v[146:149], v[210:213], 0
	v_mfma_f32_16x16x32_bf16 v[90:93], v[174:177], v[210:213], 0
	v_mfma_f32_16x16x32_bf16 v[78:81], v[146:149], v[218:221], 0
	v_mfma_f32_16x16x32_bf16 v[74:77], v[174:177], v[218:221], 0
	v_mfma_f32_16x16x32_bf16 v[126:129], v[150:153], v[186:189], v[126:129]
	v_mfma_f32_16x16x32_bf16 v[122:125], v[178:181], v[186:189], v[122:125]
	v_mfma_f32_16x16x32_bf16 v[110:113], v[150:153], v[206:209], v[110:113]
	v_mfma_f32_16x16x32_bf16 v[106:109], v[178:181], v[206:209], v[106:109]
	v_mfma_f32_16x16x32_bf16 v[94:97], v[150:153], v[214:217], v[94:97]
	v_mfma_f32_16x16x32_bf16 v[90:93], v[178:181], v[214:217], v[90:93]
	v_mfma_f32_16x16x32_bf16 v[78:81], v[150:153], v[222:225], v[78:81]
	v_mfma_f32_16x16x32_bf16 v[74:77], v[178:181], v[222:225], v[74:77]
	s_barrier
	s_add_i32 s56, s51, s27
	v_lshl_add_u64 v[190:191], s[24:25], 0, v[156:157]
	s_mov_b32 m0, s56
	ds_read_b128 v[182:185], v198 offset:16384
	ds_read_b128 v[186:189], v198 offset:17408
	ds_read_b128 v[202:205], v198 offset:18432
	ds_read_b128 v[206:209], v198 offset:19456
	ds_read_b128 v[210:213], v198 offset:20480
	ds_read_b128 v[214:217], v198 offset:21504
	ds_read_b128 v[218:221], v198 offset:22528
	ds_read_b128 v[222:225], v198 offset:23552
	global_load_lds_dwordx4 v[190:191], off
	s_add_i32 m0, s56, 0x2000
	s_add_u32 s56, s24, 0x20000
	v_lshl_add_u64 v[226:227], s[24:25], 0, v[160:161]
	s_addc_u32 s57, s25, 0
	s_add_i32 s58, s52, s27
	global_load_lds_dwordx4 v[226:227], off
	v_lshl_add_u64 v[228:229], s[56:57], 0, v[156:157]
	s_mov_b32 m0, s58
	v_lshl_add_u64 v[230:231], s[34:35], 0, v[158:159]
	global_load_lds_dwordx4 v[228:229], off
	v_lshl_add_u64 v[228:229], s[56:57], 0, v[160:161]
	s_add_i32 m0, s58, 0x2000
	s_nop 0
	global_load_lds_dwordx4 v[228:229], off
	v_lshl_add_u64 v[228:229], s[34:35], 0, v[154:155]
	s_mov_b32 m0, s28
	s_nop 0
	global_load_lds_dwordx4 v[228:229], off
	s_mov_b32 m0, s29
	s_nop 0
	global_load_lds_dwordx4 v[230:231], off
	s_waitcnt lgkmcnt(0)
	s_barrier
	v_mfma_f32_16x16x32_bf16 v[70:73], v[50:53], v[182:185], 0
	v_mfma_f32_16x16x32_bf16 v[66:69], v[138:141], v[182:185], 0
	v_mfma_f32_16x16x32_bf16 v[46:49], v[50:53], v[202:205], 0
	v_mfma_f32_16x16x32_bf16 v[42:45], v[138:141], v[202:205], 0
	v_mfma_f32_16x16x32_bf16 v[30:33], v[50:53], v[210:213], 0
	v_mfma_f32_16x16x32_bf16 v[26:29], v[138:141], v[210:213], 0
	v_mfma_f32_16x16x32_bf16 v[14:17], v[50:53], v[218:221], 0
	v_mfma_f32_16x16x32_bf16 v[10:13], v[138:141], v[218:221], 0
	v_mfma_f32_16x16x32_bf16 v[70:73], v[54:57], v[186:189], v[70:73]
	v_mfma_f32_16x16x32_bf16 v[66:69], v[142:145], v[186:189], v[66:69]
	v_mfma_f32_16x16x32_bf16 v[46:49], v[54:57], v[206:209], v[46:49]
	v_mfma_f32_16x16x32_bf16 v[42:45], v[142:145], v[206:209], v[42:45]
	v_mfma_f32_16x16x32_bf16 v[30:33], v[54:57], v[214:217], v[30:33]
	v_mfma_f32_16x16x32_bf16 v[26:29], v[142:145], v[214:217], v[26:29]
	v_mfma_f32_16x16x32_bf16 v[14:17], v[54:57], v[222:225], v[14:17]
	v_mfma_f32_16x16x32_bf16 v[10:13], v[142:145], v[222:225], v[10:13]
	v_mfma_f32_16x16x32_bf16 v[38:41], v[146:149], v[202:205], 0
	v_mfma_f32_16x16x32_bf16 v[34:37], v[174:177], v[202:205], 0
	v_mfma_f32_16x16x32_bf16 v[22:25], v[146:149], v[210:213], 0
	v_mfma_f32_16x16x32_bf16 v[18:21], v[174:177], v[210:213], 0
	v_mfma_f32_16x16x32_bf16 v[6:9], v[146:149], v[218:221], 0
	v_mfma_f32_16x16x32_bf16 v[2:5], v[174:177], v[218:221], 0
	v_mfma_f32_16x16x32_bf16 v[50:53], v[146:149], v[182:185], 0
	v_mfma_f32_16x16x32_bf16 v[54:57], v[174:177], v[182:185], 0
	v_mfma_f32_16x16x32_bf16 v[38:41], v[150:153], v[206:209], v[38:41]
	v_mfma_f32_16x16x32_bf16 v[34:37], v[178:181], v[206:209], v[34:37]
	v_mfma_f32_16x16x32_bf16 v[22:25], v[150:153], v[214:217], v[22:25]
	v_mfma_f32_16x16x32_bf16 v[18:21], v[178:181], v[214:217], v[18:21]
	v_mfma_f32_16x16x32_bf16 v[6:9], v[150:153], v[222:225], v[6:9]
	v_mfma_f32_16x16x32_bf16 v[2:5], v[178:181], v[222:225], v[2:5]
	v_mfma_f32_16x16x32_bf16 v[50:53], v[150:153], v[186:189], v[50:53]
	v_mfma_f32_16x16x32_bf16 v[54:57], v[178:181], v[186:189], v[54:57]
	s_barrier
; #define PG8_STAGE(bufoff, gbase, voff) do { _Pragma("unroll") for (int _i = 0; _i < 2; ++_i) \
;         __builtin_amdgcn_global_load_lds((const unsigned*)((const char*)(gbase) + (voff)[_i]), (LAS unsigned*)(lds + (bufoff) + ldsw + _i * 8192), 16, 0, 0); } while (0)
; #define PG8_LDA(dst, b, h) do { _Pragma("unroll") for (int m = 0; m < 4; ++m) _Pragma("unroll") for (int k = 0; k < 2; ++k) dst[m][k] = *(const LAS bf16x8*)(lds + PG8_SA(b, h) + aoff + m * 2048 + k * 1024); } while (0)
; #define PG8_LDB(dst, b, h) do { _Pragma("unroll") for (int n = 0; n < 2; ++n) _Pragma("unroll") for (int k = 0; k < 2; ++k) dst[n][k] = *(const LAS bf16x8*)(lds + PG8_SB(b, h) + boff + n * 2048 + k * 1024); } while (0)
; #define PG8_MMA(ai, bj, At, Bt) do { __builtin_amdgcn_s_setprio(1); _Pragma("unroll") for (int m = 0; m < 4; ++m) _Pragma("unroll") for (int n = 0; n < 2; ++n) _Pragma("unroll") for (int k = 0; k < 2; ++k) \
;         acc[ai][bj][m][n] = __builtin_amdgcn_mfma_f32_16x16x32_bf16(Bt[n][k], At[m][k], acc[ai][bj][m][n], 0, 0, 0); __builtin_amdgcn_s_setprio(0); } while (0)
; #define PG8_WAIT_V(n) asm volatile("s_waitcnt vmcnt(" #n ")" ::: "memory")
; #define PG8_WAIT_L(n) asm volatile("s_waitcnt lgkmcnt(" #n ")" ::: "memory")
; #define PG8_BAR __builtin_amdgcn_s_barrier()
; #define PG8_SCHED __builtin_amdgcn_sched_barrier(0)
; template <class Epi, class Sched, bool ALIGN_EPI = false, bool SP2 = false>
; __device__ __forceinline__ void gemm_phase(LAS unsigned char* lds, const Gemm g, const Sched& S, const Epi& E) {
;     ...
;             PG8_LDB(B0, 1, 0); PG8_LDB(B1, 1, 1); PG8_SCHED; PG8_LDA(At, 1, 0); PG8_STAGE(PG8_SA(0, 1), a2 + hstep, voffA);
;             PG8_WAIT_V(8); PG8_WAIT_L(0); PG8_BAR; PG8_MMA(0, 0, At, B0); PG8_MMA(0, 1, At, B1); PG8_BAR; PG8_SCHED;
;             PG8_LDA(At, 1, 1); PG8_STAGE(PG8_SB(1, 0), b3, voffB); PG8_STAGE(PG8_SB(1, 1), b3 + hstepB, voffB); PG8_STAGE(PG8_SA(1, 0), a3, voffA);
;             PG8_WAIT_V(8); PG8_WAIT_L(0); PG8_BAR; PG8_MMA(1, 0, At, B0); PG8_MMA(1, 1, At, B1); PG8_BAR; PG8_SCHED;
	s_add_i32 s56, 0, 0x18000
	s_add_i32 s57, 0, 0x1c000
	v_add_u32_e32 v142, s56, v1
	v_add_u32_e32 v162, s57, v1
	ds_read_b128 v[58:61], v142
	ds_read_b128 v[62:65], v142 offset:1024
	ds_read_b128 v[138:141], v142 offset:2048
	ds_read_b128 v[142:145], v142 offset:3072
	ds_read_b128 v[146:149], v162
	ds_read_b128 v[150:153], v162 offset:1024
	ds_read_b128 v[174:177], v162 offset:2048
	ds_read_b128 v[178:181], v162 offset:3072
	s_add_u32 s34, s34, 0x80000
	s_addc_u32 s35, s35, 0
	s_mov_b32 m0, s30
	v_lshl_add_u64 v[232:233], s[34:35], 0, v[154:155]
	ds_read_b128 v[182:185], v198 offset:32768
	ds_read_b128 v[186:189], v198 offset:33792
	ds_read_b128 v[202:205], v198 offset:34816
	ds_read_b128 v[206:209], v198 offset:35840
	ds_read_b128 v[210:213], v198 offset:36864
	ds_read_b128 v[214:217], v198 offset:37888
	ds_read_b128 v[218:221], v198 offset:38912
	ds_read_b128 v[222:225], v198 offset:39936
	global_load_lds_dwordx4 v[232:233], off
	v_lshl_add_u64 v[232:233], s[34:35], 0, v[158:159]
	s_mov_b32 m0, s31
	s_nop 0
	global_load_lds_dwordx4 v[232:233], off
	s_waitcnt vmcnt(8)
	s_waitcnt lgkmcnt(0)
	s_barrier
	v_mfma_f32_16x16x32_bf16 v[134:137], v[58:61], v[182:185], v[134:137]
	v_mfma_f32_16x16x32_bf16 v[130:133], v[138:141], v[182:185], v[130:133]
	v_mfma_f32_16x16x32_bf16 v[118:121], v[58:61], v[202:205], v[118:121]
	v_mfma_f32_16x16x32_bf16 v[114:117], v[138:141], v[202:205], v[114:117]
	v_mfma_f32_16x16x32_bf16 v[102:105], v[58:61], v[210:213], v[102:105]
	v_mfma_f32_16x16x32_bf16 v[98:101], v[138:141], v[210:213], v[98:101]
	v_mfma_f32_16x16x32_bf16 v[86:89], v[58:61], v[218:221], v[86:89]
	v_mfma_f32_16x16x32_bf16 v[82:85], v[138:141], v[218:221], v[82:85]
	v_mfma_f32_16x16x32_bf16 v[134:137], v[62:65], v[186:189], v[134:137]
	v_mfma_f32_16x16x32_bf16 v[130:133], v[142:145], v[186:189], v[130:133]
	v_mfma_f32_16x16x32_bf16 v[118:121], v[62:65], v[206:209], v[118:121]
	v_mfma_f32_16x16x32_bf16 v[114:117], v[142:145], v[206:209], v[114:117]
	v_mfma_f32_16x16x32_bf16 v[102:105], v[62:65], v[214:217], v[102:105]
	v_mfma_f32_16x16x32_bf16 v[98:101], v[142:145], v[214:217], v[98:101]
	v_mfma_f32_16x16x32_bf16 v[86:89], v[62:65], v[222:225], v[86:89]
	v_mfma_f32_16x16x32_bf16 v[82:85], v[142:145], v[222:225], v[82:85]
	v_mfma_f32_16x16x32_bf16 v[126:129], v[146:149], v[182:185], v[126:129]
	v_mfma_f32_16x16x32_bf16 v[122:125], v[174:177], v[182:185], v[122:125]
	v_mfma_f32_16x16x32_bf16 v[110:113], v[146:149], v[202:205], v[110:113]
	v_mfma_f32_16x16x32_bf16 v[106:109], v[174:177], v[202:205], v[106:109]
	v_mfma_f32_16x16x32_bf16 v[94:97], v[146:149], v[210:213], v[94:97]
	v_mfma_f32_16x16x32_bf16 v[90:93], v[174:177], v[210:213], v[90:93]
	v_mfma_f32_16x16x32_bf16 v[78:81], v[146:149], v[218:221], v[78:81]
	v_mfma_f32_16x16x32_bf16 v[74:77], v[174:177], v[218:221], v[74:77]
	v_mfma_f32_16x16x32_bf16 v[126:129], v[150:153], v[186:189], v[126:129]
	v_mfma_f32_16x16x32_bf16 v[122:125], v[178:181], v[186:189], v[122:125]
	v_mfma_f32_16x16x32_bf16 v[110:113], v[150:153], v[206:209], v[110:113]
	v_mfma_f32_16x16x32_bf16 v[106:109], v[178:181], v[206:209], v[106:109]
	v_mfma_f32_16x16x32_bf16 v[94:97], v[150:153], v[214:217], v[94:97]
	v_mfma_f32_16x16x32_bf16 v[90:93], v[178:181], v[214:217], v[90:93]
	v_mfma_f32_16x16x32_bf16 v[78:81], v[150:153], v[222:225], v[78:81]
	v_mfma_f32_16x16x32_bf16 v[74:77], v[178:181], v[222:225], v[74:77]
	s_barrier
	s_add_i32 s34, s56, s27
	v_lshl_add_u64 v[190:191], v[190:191], 0, s[8:9]
	s_mov_b32 m0, s34
	ds_read_b128 v[182:185], v198 offset:49152
	ds_read_b128 v[186:189], v198 offset:50176
	ds_read_b128 v[202:205], v198 offset:51200
	ds_read_b128 v[206:209], v198 offset:52224
	ds_read_b128 v[210:213], v198 offset:53248
	ds_read_b128 v[214:217], v198 offset:54272
	ds_read_b128 v[218:221], v198 offset:55296
	ds_read_b128 v[222:225], v198 offset:56320
	global_load_lds_dwordx4 v[190:191], off
	s_add_i32 m0, s34, 0x2000
	s_add_u32 s24, s24, 0x20080
	v_lshl_add_u64 v[190:191], v[226:227], 0, s[8:9]
	s_addc_u32 s25, s25, 0
	s_add_i32 s34, s57, s27
	global_load_lds_dwordx4 v[190:191], off
	v_lshl_add_u64 v[190:191], s[24:25], 0, v[156:157]
	s_mov_b32 m0, s34
	s_nop 0
	global_load_lds_dwordx4 v[190:191], off
	v_lshl_add_u64 v[190:191], s[24:25], 0, v[160:161]
	s_add_i32 m0, s34, 0x2000
	s_nop 0
	global_load_lds_dwordx4 v[190:191], off
	v_lshl_add_u64 v[190:191], v[228:229], 0, s[8:9]
	s_mov_b32 m0, s48
	s_nop 0
	global_load_lds_dwordx4 v[190:191], off
	v_lshl_add_u64 v[190:191], v[230:231], 0, s[8:9]
	s_mov_b32 m0, s49
	s_nop 0
	global_load_lds_dwordx4 v[190:191], off
	s_waitcnt vmcnt(8)
	s_waitcnt lgkmcnt(0)
	s_barrier
	v_mfma_f32_16x16x32_bf16 v[70:73], v[58:61], v[182:185], v[70:73]
	v_mfma_f32_16x16x32_bf16 v[66:69], v[138:141], v[182:185], v[66:69]
	v_mfma_f32_16x16x32_bf16 v[46:49], v[58:61], v[202:205], v[46:49]
	v_mfma_f32_16x16x32_bf16 v[42:45], v[138:141], v[202:205], v[42:45]
	v_mfma_f32_16x16x32_bf16 v[30:33], v[58:61], v[210:213], v[30:33]
	v_mfma_f32_16x16x32_bf16 v[26:29], v[138:141], v[210:213], v[26:29]
	v_mfma_f32_16x16x32_bf16 v[14:17], v[58:61], v[218:221], v[14:17]
	v_mfma_f32_16x16x32_bf16 v[10:13], v[138:141], v[218:221], v[10:13]
	v_mfma_f32_16x16x32_bf16 v[70:73], v[62:65], v[186:189], v[70:73]
	v_mfma_f32_16x16x32_bf16 v[66:69], v[142:145], v[186:189], v[66:69]
	v_mfma_f32_16x16x32_bf16 v[46:49], v[62:65], v[206:209], v[46:49]
	v_mfma_f32_16x16x32_bf16 v[42:45], v[142:145], v[206:209], v[42:45]
	v_mfma_f32_16x16x32_bf16 v[30:33], v[62:65], v[214:217], v[30:33]
	v_mfma_f32_16x16x32_bf16 v[26:29], v[142:145], v[214:217], v[26:29]
	v_mfma_f32_16x16x32_bf16 v[14:17], v[62:65], v[222:225], v[14:17]
	v_mfma_f32_16x16x32_bf16 v[10:13], v[142:145], v[222:225], v[10:13]
	v_mfma_f32_16x16x32_bf16 v[50:53], v[146:149], v[182:185], v[50:53]
	v_mfma_f32_16x16x32_bf16 v[62:65], v[150:153], v[186:189], v[50:53]
	v_mfma_f32_16x16x32_bf16 v[50:53], v[174:177], v[182:185], v[54:57]
	v_mfma_f32_16x16x32_bf16 v[38:41], v[146:149], v[202:205], v[38:41]
	v_mfma_f32_16x16x32_bf16 v[34:37], v[174:177], v[202:205], v[34:37]
	v_mfma_f32_16x16x32_bf16 v[22:25], v[146:149], v[210:213], v[22:25]
	v_mfma_f32_16x16x32_bf16 v[18:21], v[174:177], v[210:213], v[18:21]
	v_mfma_f32_16x16x32_bf16 v[6:9], v[146:149], v[218:221], v[6:9]
	v_mfma_f32_16x16x32_bf16 v[2:5], v[174:177], v[218:221], v[2:5]
	v_mfma_f32_16x16x32_bf16 v[58:61], v[178:181], v[186:189], v[50:53]
	v_mfma_f32_16x16x32_bf16 v[38:41], v[150:153], v[206:209], v[38:41]
	v_mfma_f32_16x16x32_bf16 v[34:37], v[178:181], v[206:209], v[34:37]
	v_mfma_f32_16x16x32_bf16 v[22:25], v[150:153], v[214:217], v[22:25]
	v_mfma_f32_16x16x32_bf16 v[18:21], v[178:181], v[214:217], v[18:21]
	v_mfma_f32_16x16x32_bf16 v[6:9], v[150:153], v[222:225], v[6:9]
	v_mfma_f32_16x16x32_bf16 v[2:5], v[178:181], v[222:225], v[2:5]
	s_barrier
	s_add_i32 s55, s55, 2
	s_add_u32 s53, s53, 0x100
	s_addc_u32 s54, s54, 0
	s_add_u32 s22, s22, 0x100
	s_addc_u32 s23, s23, 0
	s_cmp_lt_u32 s55, 30
; #define PG8_STAGE(bufoff, gbase, voff) do { _Pragma("unroll") for (int _i = 0; _i < 2; ++_i) \
;         __builtin_amdgcn_global_load_lds((const unsigned*)((const char*)(gbase) + (voff)[_i]), (LAS unsigned*)(lds + (bufoff) + ldsw + _i * 8192), 16, 0, 0); } while (0)
; #define PG8_LDA(dst, b, h) do { _Pragma("unroll") for (int m = 0; m < 4; ++m) _Pragma("unroll") for (int k = 0; k < 2; ++k) dst[m][k] = *(const LAS bf16x8*)(lds + PG8_SA(b, h) + aoff + m * 2048 + k * 1024); } while (0)
; #define PG8_LDB(dst, b, h) do { _Pragma("unroll") for (int n = 0; n < 2; ++n) _Pragma("unroll") for (int k = 0; k < 2; ++k) dst[n][k] = *(const LAS bf16x8*)(lds + PG8_SB(b, h) + boff + n * 2048 + k * 1024); } while (0)
; #define PG8_MMA(ai, bj, At, Bt) do { __builtin_amdgcn_s_setprio(1); _Pragma("unroll") for (int m = 0; m < 4; ++m) _Pragma("unroll") for (int n = 0; n < 2; ++n) _Pragma("unroll") for (int k = 0; k < 2; ++k) \
;         acc[ai][bj][m][n] = __builtin_amdgcn_mfma_f32_16x16x32_bf16(Bt[n][k], At[m][k], acc[ai][bj][m][n], 0, 0, 0); __builtin_amdgcn_s_setprio(0); } while (0)
; #define PG8_WAIT_V(n) asm volatile("s_waitcnt vmcnt(" #n ")" ::: "memory")
; #define PG8_WAIT_L(n) asm volatile("s_waitcnt lgkmcnt(" #n ")" ::: "memory")
; #define PG8_BAR __builtin_amdgcn_s_barrier()
; #define PG8_SCHED __builtin_amdgcn_sched_barrier(0)
; template <class Epi, class Sched, bool ALIGN_EPI = false, bool SP2 = false>
; __device__ __forceinline__ void gemm_phase(LAS unsigned char* lds, const Gemm g, const Sched& S, const Epi& E) {
;     ...
;         for (int t = 0; t < nt; t += 2) {
;             const bool last = (t == nt - 2);
;             const char* a1 = cA + (size_t)(t + 1) * kstep;
;             const char* a2 = last ? nA : cA + (size_t)(t + 2) * kstep; const char* b2 = last ? nB : cB + (size_t)(t + 2) * kstep;
;             const char* a3 = a2 + kstep; const char* b3 = b2 + kstep;
;             if (last && has_next) S.a_ready(nxt);
;             if constexpr (SP2) {
;             PG8_LDB(B0, 0, 0); PG8_LDB(B1, 0, 1); PG8_SCHED; PG8_LDA(At, 0, 0); PG8_STAGE(PG8_SA(1, 1), a1 + hstep, voffA);
;             PG8_WAIT_V(8); PG8_WAIT_L(0); PG8_BAR; PG8_MMA(0, 0, At, B0); PG8_MMA(0, 1, At, B1); PG8_BAR; PG8_SCHED;
;             PG8_LDA(At, 0, 1); PG8_STAGE(PG8_SB(0, 0), b2, voffB); PG8_STAGE(PG8_SB(0, 1), b2 + hstepB, voffB); PG8_STAGE(PG8_SA(0, 0), a2, voffA);
.LBB0_2766:
	ds_read_b128 v[50:53], v196
	ds_read_b128 v[54:57], v196 offset:1024
	ds_read_b128 v[138:141], v196 offset:2048
	ds_read_b128 v[142:145], v196 offset:3072
	ds_read_b128 v[146:149], v197
	ds_read_b128 v[150:153], v197 offset:1024
	ds_read_b128 v[174:177], v197 offset:2048
	ds_read_b128 v[178:181], v197 offset:3072
	s_add_u32 s24, s22, 0xfff80080
	s_addc_u32 s25, s23, -1
	s_cmp_eq_u32 s55, 28
	s_cselect_b32 s35, s3, s25
	s_cselect_b32 s34, s15, s24
	s_cselect_b32 s25, s13, s54
	s_cselect_b32 s24, s21, s53
	v_lshl_add_u64 v[190:191], s[22:23], 0, v[168:169]
	s_add_i32 m0, s28, 0xc000
	ds_read_b128 v[182:185], v198
	ds_read_b128 v[186:189], v198 offset:1024
	ds_read_b128 v[202:205], v198 offset:2048
	ds_read_b128 v[206:209], v198 offset:3072
	ds_read_b128 v[210:213], v198 offset:4096
	ds_read_b128 v[214:217], v198 offset:5120
	ds_read_b128 v[218:221], v198 offset:6144
	ds_read_b128 v[222:225], v198 offset:7168
	global_load_lds_dwordx4 v[190:191], off
	v_lshl_add_u64 v[190:191], s[22:23], 0, v[166:167]
	s_add_i32 m0, s28, 0xe000
	s_nop 0
	global_load_lds_dwordx4 v[190:191], off
	s_waitcnt vmcnt(8)
	s_waitcnt lgkmcnt(0)
	s_barrier
	v_mfma_f32_16x16x32_bf16 v[134:137], v[50:53], v[182:185], v[134:137]
	v_mfma_f32_16x16x32_bf16 v[130:133], v[138:141], v[182:185], v[130:133]
	v_mfma_f32_16x16x32_bf16 v[118:121], v[50:53], v[202:205], v[118:121]
	v_mfma_f32_16x16x32_bf16 v[114:117], v[138:141], v[202:205], v[114:117]
	v_mfma_f32_16x16x32_bf16 v[102:105], v[50:53], v[210:213], v[102:105]
	v_mfma_f32_16x16x32_bf16 v[98:101], v[138:141], v[210:213], v[98:101]
	v_mfma_f32_16x16x32_bf16 v[86:89], v[50:53], v[218:221], v[86:89]
	v_mfma_f32_16x16x32_bf16 v[82:85], v[138:141], v[218:221], v[82:85]
	v_mfma_f32_16x16x32_bf16 v[134:137], v[54:57], v[186:189], v[134:137]
	v_mfma_f32_16x16x32_bf16 v[130:133], v[142:145], v[186:189], v[130:133]
	v_mfma_f32_16x16x32_bf16 v[118:121], v[54:57], v[206:209], v[118:121]
	v_mfma_f32_16x16x32_bf16 v[114:117], v[142:145], v[206:209], v[114:117]
	v_mfma_f32_16x16x32_bf16 v[102:105], v[54:57], v[214:217], v[102:105]
	v_mfma_f32_16x16x32_bf16 v[98:101], v[142:145], v[214:217], v[98:101]
	v_mfma_f32_16x16x32_bf16 v[86:89], v[54:57], v[222:225], v[86:89]
	v_mfma_f32_16x16x32_bf16 v[82:85], v[142:145], v[222:225], v[82:85]
	v_mfma_f32_16x16x32_bf16 v[126:129], v[146:149], v[182:185], v[126:129]
	v_mfma_f32_16x16x32_bf16 v[122:125], v[174:177], v[182:185], v[122:125]
	v_mfma_f32_16x16x32_bf16 v[110:113], v[146:149], v[202:205], v[110:113]
	v_mfma_f32_16x16x32_bf16 v[106:109], v[174:177], v[202:205], v[106:109]
	v_mfma_f32_16x16x32_bf16 v[94:97], v[146:149], v[210:213], v[94:97]
	v_mfma_f32_16x16x32_bf16 v[90:93], v[174:177], v[210:213], v[90:93]
	v_mfma_f32_16x16x32_bf16 v[78:81], v[146:149], v[218:221], v[78:81]
	v_mfma_f32_16x16x32_bf16 v[74:77], v[174:177], v[218:221], v[74:77]
	v_mfma_f32_16x16x32_bf16 v[126:129], v[150:153], v[186:189], v[126:129]
	v_mfma_f32_16x16x32_bf16 v[122:125], v[178:181], v[186:189], v[122:125]
	v_mfma_f32_16x16x32_bf16 v[110:113], v[150:153], v[206:209], v[110:113]
	v_mfma_f32_16x16x32_bf16 v[106:109], v[178:181], v[206:209], v[106:109]
	v_mfma_f32_16x16x32_bf16 v[94:97], v[150:153], v[214:217], v[94:97]
	v_mfma_f32_16x16x32_bf16 v[90:93], v[178:181], v[214:217], v[90:93]
	v_mfma_f32_16x16x32_bf16 v[78:81], v[150:153], v[222:225], v[78:81]
	v_mfma_f32_16x16x32_bf16 v[74:77], v[178:181], v[222:225], v[74:77]
	s_barrier
	s_add_i32 s56, s51, s27
	v_lshl_add_u64 v[190:191], s[24:25], 0, v[156:157]
	s_mov_b32 m0, s56
	ds_read_b128 v[182:185], v198 offset:16384
	ds_read_b128 v[186:189], v198 offset:17408
	ds_read_b128 v[202:205], v198 offset:18432
	ds_read_b128 v[206:209], v198 offset:19456
	ds_read_b128 v[210:213], v198 offset:20480
	ds_read_b128 v[214:217], v198 offset:21504
	ds_read_b128 v[218:221], v198 offset:22528
	ds_read_b128 v[222:225], v198 offset:23552
	global_load_lds_dwordx4 v[190:191], off
	s_add_i32 m0, s56, 0x2000
	s_add_u32 s56, s24, 0x20000
	v_lshl_add_u64 v[226:227], s[24:25], 0, v[160:161]
	s_addc_u32 s57, s25, 0
	s_add_i32 s58, s52, s27
	global_load_lds_dwordx4 v[226:227], off
	v_lshl_add_u64 v[228:229], s[56:57], 0, v[156:157]
	s_mov_b32 m0, s58
	v_lshl_add_u64 v[230:231], s[34:35], 0, v[158:159]
	global_load_lds_dwordx4 v[228:229], off
	v_lshl_add_u64 v[228:229], s[56:57], 0, v[160:161]
	s_add_i32 m0, s58, 0x2000
	s_nop 0
	global_load_lds_dwordx4 v[228:229], off
	v_lshl_add_u64 v[228:229], s[34:35], 0, v[154:155]
	s_mov_b32 m0, s28
	s_nop 0
	global_load_lds_dwordx4 v[228:229], off
	s_mov_b32 m0, s29
	s_nop 0
	global_load_lds_dwordx4 v[230:231], off
	s_waitcnt vmcnt(8)
	s_waitcnt lgkmcnt(0)
	s_barrier
; #define PG8_STAGE(bufoff, gbase, voff) do { _Pragma("unroll") for (int _i = 0; _i < 2; ++_i) \
;         __builtin_amdgcn_global_load_lds((const unsigned*)((const char*)(gbase) + (voff)[_i]), (LAS unsigned*)(lds + (bufoff) + ldsw + _i * 8192), 16, 0, 0); } while (0)
; #define PG8_LDA(dst, b, h) do { _Pragma("unroll") for (int m = 0; m < 4; ++m) _Pragma("unroll") for (int k = 0; k < 2; ++k) dst[m][k] = *(const LAS bf16x8*)(lds + PG8_SA(b, h) + aoff + m * 2048 + k * 1024); } while (0)
; #define PG8_LDB(dst, b, h) do { _Pragma("unroll") for (int n = 0; n < 2; ++n) _Pragma("unroll") for (int k = 0; k < 2; ++k) dst[n][k] = *(const LAS bf16x8*)(lds + PG8_SB(b, h) + boff + n * 2048 + k * 1024); } while (0)
; #define PG8_MMA(ai, bj, At, Bt) do { __builtin_amdgcn_s_setprio(1); _Pragma("unroll") for (int m = 0; m < 4; ++m) _Pragma("unroll") for (int n = 0; n < 2; ++n) _Pragma("unroll") for (int k = 0; k < 2; ++k) \
;         acc[ai][bj][m][n] = __builtin_amdgcn_mfma_f32_16x16x32_bf16(Bt[n][k], At[m][k], acc[ai][bj][m][n], 0, 0, 0); __builtin_amdgcn_s_setprio(0); } while (0)
; #define PG8_WAIT_V(n) asm volatile("s_waitcnt vmcnt(" #n ")" ::: "memory")
; #define PG8_WAIT_L(n) asm volatile("s_waitcnt lgkmcnt(" #n ")" ::: "memory")
; #define PG8_BAR __builtin_amdgcn_s_barrier()
; #define PG8_SCHED __builtin_amdgcn_sched_barrier(0)
; template <class Epi, class Sched, bool ALIGN_EPI = false, bool SP2 = false>
; __device__ __forceinline__ void gemm_phase(LAS unsigned char* lds, const Gemm g, const Sched& S, const Epi& E) {
;     ...
;             PG8_WAIT_V(8); PG8_WAIT_L(0); PG8_BAR; PG8_MMA(1, 0, At, B0); PG8_MMA(1, 1, At, B1); PG8_BAR; PG8_SCHED;
;             PG8_LDB(B0, 1, 0); PG8_LDB(B1, 1, 1); PG8_SCHED; PG8_LDA(At, 1, 0); PG8_STAGE(PG8_SA(0, 1), a2 + hstep, voffA);
;             PG8_WAIT_V(8); PG8_WAIT_L(0); PG8_BAR; PG8_MMA(0, 0, At, B0); PG8_MMA(0, 1, At, B1); PG8_BAR; PG8_SCHED;
	v_mfma_f32_16x16x32_bf16 v[70:73], v[50:53], v[182:185], v[70:73]
	v_mfma_f32_16x16x32_bf16 v[66:69], v[138:141], v[182:185], v[66:69]
	v_mfma_f32_16x16x32_bf16 v[46:49], v[50:53], v[202:205], v[46:49]
	v_mfma_f32_16x16x32_bf16 v[42:45], v[138:141], v[202:205], v[42:45]
	v_mfma_f32_16x16x32_bf16 v[30:33], v[50:53], v[210:213], v[30:33]
	v_mfma_f32_16x16x32_bf16 v[26:29], v[138:141], v[210:213], v[26:29]
	v_mfma_f32_16x16x32_bf16 v[14:17], v[50:53], v[218:221], v[14:17]
	v_mfma_f32_16x16x32_bf16 v[10:13], v[138:141], v[218:221], v[10:13]
	v_mfma_f32_16x16x32_bf16 v[70:73], v[54:57], v[186:189], v[70:73]
	v_mfma_f32_16x16x32_bf16 v[66:69], v[142:145], v[186:189], v[66:69]
	v_mfma_f32_16x16x32_bf16 v[46:49], v[54:57], v[206:209], v[46:49]
	v_mfma_f32_16x16x32_bf16 v[42:45], v[142:145], v[206:209], v[42:45]
	v_mfma_f32_16x16x32_bf16 v[30:33], v[54:57], v[214:217], v[30:33]
	v_mfma_f32_16x16x32_bf16 v[26:29], v[142:145], v[214:217], v[26:29]
	v_mfma_f32_16x16x32_bf16 v[14:17], v[54:57], v[222:225], v[14:17]
	v_mfma_f32_16x16x32_bf16 v[10:13], v[142:145], v[222:225], v[10:13]
	v_mfma_f32_16x16x32_bf16 v[38:41], v[146:149], v[202:205], v[38:41]
	v_mfma_f32_16x16x32_bf16 v[34:37], v[174:177], v[202:205], v[34:37]
	v_mfma_f32_16x16x32_bf16 v[22:25], v[146:149], v[210:213], v[22:25]
	v_mfma_f32_16x16x32_bf16 v[18:21], v[174:177], v[210:213], v[18:21]
	v_mfma_f32_16x16x32_bf16 v[6:9], v[146:149], v[218:221], v[6:9]
	v_mfma_f32_16x16x32_bf16 v[2:5], v[174:177], v[218:221], v[2:5]
	v_mfma_f32_16x16x32_bf16 v[50:53], v[146:149], v[182:185], v[62:65]
	v_mfma_f32_16x16x32_bf16 v[54:57], v[174:177], v[182:185], v[58:61]
	v_mfma_f32_16x16x32_bf16 v[38:41], v[150:153], v[206:209], v[38:41]
	v_mfma_f32_16x16x32_bf16 v[34:37], v[178:181], v[206:209], v[34:37]
	v_mfma_f32_16x16x32_bf16 v[22:25], v[150:153], v[214:217], v[22:25]
	v_mfma_f32_16x16x32_bf16 v[18:21], v[178:181], v[214:217], v[18:21]
	v_mfma_f32_16x16x32_bf16 v[6:9], v[150:153], v[222:225], v[6:9]
	v_mfma_f32_16x16x32_bf16 v[2:5], v[178:181], v[222:225], v[2:5]
	v_mfma_f32_16x16x32_bf16 v[50:53], v[150:153], v[186:189], v[50:53]
	v_mfma_f32_16x16x32_bf16 v[54:57], v[178:181], v[186:189], v[54:57]
	s_barrier
	s_add_i32 s56, 0, 0x18000
	s_add_i32 s57, 0, 0x1c000
	v_add_u32_e32 v142, s56, v1
	v_add_u32_e32 v162, s57, v1
	ds_read_b128 v[58:61], v142
	ds_read_b128 v[62:65], v142 offset:1024
	ds_read_b128 v[138:141], v142 offset:2048
	ds_read_b128 v[142:145], v142 offset:3072
	ds_read_b128 v[146:149], v162
	ds_read_b128 v[150:153], v162 offset:1024
	ds_read_b128 v[174:177], v162 offset:2048
	ds_read_b128 v[178:181], v162 offset:3072
	s_add_u32 s34, s34, 0x80000
	s_addc_u32 s35, s35, 0
	s_mov_b32 m0, s30
	v_lshl_add_u64 v[232:233], s[34:35], 0, v[154:155]
	ds_read_b128 v[182:185], v198 offset:32768
	ds_read_b128 v[186:189], v198 offset:33792
	ds_read_b128 v[202:205], v198 offset:34816
	ds_read_b128 v[206:209], v198 offset:35840
	ds_read_b128 v[210:213], v198 offset:36864
	ds_read_b128 v[214:217], v198 offset:37888
	ds_read_b128 v[218:221], v198 offset:38912
	ds_read_b128 v[222:225], v198 offset:39936
	global_load_lds_dwordx4 v[232:233], off
	v_lshl_add_u64 v[232:233], s[34:35], 0, v[158:159]
	s_mov_b32 m0, s31
	s_nop 0
	global_load_lds_dwordx4 v[232:233], off
	s_waitcnt vmcnt(8)
	s_waitcnt lgkmcnt(0)
	s_barrier
	v_mfma_f32_16x16x32_bf16 v[134:137], v[58:61], v[182:185], v[134:137]
	v_mfma_f32_16x16x32_bf16 v[130:133], v[138:141], v[182:185], v[130:133]
	v_mfma_f32_16x16x32_bf16 v[118:121], v[58:61], v[202:205], v[118:121]
	v_mfma_f32_16x16x32_bf16 v[114:117], v[138:141], v[202:205], v[114:117]
	v_mfma_f32_16x16x32_bf16 v[102:105], v[58:61], v[210:213], v[102:105]
	v_mfma_f32_16x16x32_bf16 v[98:101], v[138:141], v[210:213], v[98:101]
	v_mfma_f32_16x16x32_bf16 v[86:89], v[58:61], v[218:221], v[86:89]
	v_mfma_f32_16x16x32_bf16 v[82:85], v[138:141], v[218:221], v[82:85]
	v_mfma_f32_16x16x32_bf16 v[134:137], v[62:65], v[186:189], v[134:137]
	v_mfma_f32_16x16x32_bf16 v[130:133], v[142:145], v[186:189], v[130:133]
	v_mfma_f32_16x16x32_bf16 v[118:121], v[62:65], v[206:209], v[118:121]
	v_mfma_f32_16x16x32_bf16 v[114:117], v[142:145], v[206:209], v[114:117]
	v_mfma_f32_16x16x32_bf16 v[102:105], v[62:65], v[214:217], v[102:105]
	v_mfma_f32_16x16x32_bf16 v[98:101], v[142:145], v[214:217], v[98:101]
	v_mfma_f32_16x16x32_bf16 v[86:89], v[62:65], v[222:225], v[86:89]
	v_mfma_f32_16x16x32_bf16 v[82:85], v[142:145], v[222:225], v[82:85]
	v_mfma_f32_16x16x32_bf16 v[126:129], v[146:149], v[182:185], v[126:129]
	v_mfma_f32_16x16x32_bf16 v[122:125], v[174:177], v[182:185], v[122:125]
	v_mfma_f32_16x16x32_bf16 v[110:113], v[146:149], v[202:205], v[110:113]
	v_mfma_f32_16x16x32_bf16 v[106:109], v[174:177], v[202:205], v[106:109]
	v_mfma_f32_16x16x32_bf16 v[94:97], v[146:149], v[210:213], v[94:97]
	v_mfma_f32_16x16x32_bf16 v[90:93], v[174:177], v[210:213], v[90:93]
	v_mfma_f32_16x16x32_bf16 v[78:81], v[146:149], v[218:221], v[78:81]
	v_mfma_f32_16x16x32_bf16 v[74:77], v[174:177], v[218:221], v[74:77]
	v_mfma_f32_16x16x32_bf16 v[126:129], v[150:153], v[186:189], v[126:129]
	v_mfma_f32_16x16x32_bf16 v[122:125], v[178:181], v[186:189], v[122:125]
	v_mfma_f32_16x16x32_bf16 v[110:113], v[150:153], v[206:209], v[110:113]
	v_mfma_f32_16x16x32_bf16 v[106:109], v[178:181], v[206:209], v[106:109]
	v_mfma_f32_16x16x32_bf16 v[94:97], v[150:153], v[214:217], v[94:97]
	v_mfma_f32_16x16x32_bf16 v[90:93], v[178:181], v[214:217], v[90:93]
	v_mfma_f32_16x16x32_bf16 v[78:81], v[150:153], v[222:225], v[78:81]
	v_mfma_f32_16x16x32_bf16 v[74:77], v[178:181], v[222:225], v[74:77]
	s_barrier
; #define PG8_STAGE(bufoff, gbase, voff) do { _Pragma("unroll") for (int _i = 0; _i < 2; ++_i) \
;         __builtin_amdgcn_global_load_lds((const unsigned*)((const char*)(gbase) + (voff)[_i]), (LAS unsigned*)(lds + (bufoff) + ldsw + _i * 8192), 16, 0, 0); } while (0)
; #define PG8_WAIT_V(n) asm volatile("s_waitcnt vmcnt(" #n ")" ::: "memory")
; #define PG8_WAIT_L(n) asm volatile("s_waitcnt lgkmcnt(" #n ")" ::: "memory")
; template <class Epi, class Sched, bool ALIGN_EPI = false, bool SP2 = false>
; __device__ __forceinline__ void gemm_phase(LAS unsigned char* lds, const Gemm g, const Sched& S, const Epi& E) {
;     ...
;             PG8_LDA(At, 1, 1); PG8_STAGE(PG8_SB(1, 0), b3, voffB); PG8_STAGE(PG8_SB(1, 1), b3 + hstepB, voffB); PG8_STAGE(PG8_SA(1, 0), a3, voffA);
;             PG8_WAIT_V(8); PG8_WAIT_L(0); PG8_BAR; PG8_MMA(1, 0, At, B0); PG8_MMA(1, 1, At, B1); PG8_BAR; PG8_SCHED;
;             } else {
;             PG8_LDB(B0, 0, 0); PG8_SCHED; PG8_LDA(At, 0, 0); PG8_STAGE(PG8_SA(1, 1), a1 + hstep, voffA);
;             PG8_WAIT_L(8); PG8_BAR; PG8_WAIT_L(0); PG8_MMA(0, 0, At, B0); PG8_BAR; PG8_SCHED;
;             PG8_LDB(B1, 0, 1); PG8_STAGE(PG8_SB(0, 0), b2, voffB);
;             PG8_BAR; PG8_WAIT_L(0); PG8_MMA(0, 1, At, B1); PG8_BAR;
;             PG8_LDA(At, 0, 1); PG8_STAGE(PG8_SA(0, 0), a2, voffA);
;             PG8_BAR; PG8_WAIT_L(0); PG8_MMA(1, 0, At, B0); PG8_BAR; PG8_SCHED;
;             PG8_STAGE(PG8_SB(0, 1), b2 + hstepB, voffB);
;             PG8_WAIT_V(6); PG8_BAR; PG8_MMA(1, 1, At, B1); PG8_BAR;
;             PG8_LDB(B0, 1, 0); PG8_SCHED; PG8_LDA(At, 1, 0); PG8_STAGE(PG8_SA(0, 1), a2 + hstep, voffA);
;             PG8_WAIT_L(8); PG8_BAR; PG8_WAIT_L(0); PG8_MMA(0, 0, At, B0); PG8_BAR; PG8_SCHED;
;             PG8_LDB(B1, 1, 1); PG8_STAGE(PG8_SB(1, 0), b3, voffB);
;             PG8_BAR; PG8_WAIT_L(0); PG8_MMA(0, 1, At, B1); PG8_BAR;
;             PG8_LDA(At, 1, 1); PG8_STAGE(PG8_SA(1, 0), a3, voffA);
;             PG8_BAR; PG8_WAIT_L(0); PG8_MMA(1, 0, At, B0); PG8_BAR; PG8_SCHED;
;             PG8_STAGE(PG8_SB(1, 1), b3 + hstepB, voffB);
;             PG8_WAIT_V(6); PG8_BAR; PG8_MMA(1, 1, At, B1); PG8_BAR;
;             }
;         }
;         if constexpr (ALIGN_EPI) { if (wr == 0) PG8_BAR; }
;         if constexpr (!Epi::AFTER_DRAIN) { E(acc, cur, wr, wc, fr, fq); S.done(cur); }
;         if (!has_next) break;
	s_add_i32 s34, s56, s27
	v_lshl_add_u64 v[190:191], v[190:191], 0, s[8:9]
	s_mov_b32 m0, s34
	ds_read_b128 v[182:185], v198 offset:49152
	ds_read_b128 v[186:189], v198 offset:50176
	ds_read_b128 v[202:205], v198 offset:51200
	ds_read_b128 v[206:209], v198 offset:52224
	ds_read_b128 v[210:213], v198 offset:53248
	ds_read_b128 v[214:217], v198 offset:54272
	ds_read_b128 v[218:221], v198 offset:55296
	ds_read_b128 v[222:225], v198 offset:56320
	global_load_lds_dwordx4 v[190:191], off
	s_add_i32 m0, s34, 0x2000
	s_add_u32 s24, s24, 0x20080
	v_lshl_add_u64 v[190:191], v[226:227], 0, s[8:9]
	s_addc_u32 s25, s25, 0
	s_add_i32 s34, s57, s27
	global_load_lds_dwordx4 v[190:191], off
	v_lshl_add_u64 v[190:191], s[24:25], 0, v[156:157]
	s_mov_b32 m0, s34
	s_nop 0
	global_load_lds_dwordx4 v[190:191], off
	v_lshl_add_u64 v[190:191], s[24:25], 0, v[160:161]
	s_add_i32 m0, s34, 0x2000
	s_nop 0
	global_load_lds_dwordx4 v[190:191], off
	v_lshl_add_u64 v[190:191], v[228:229], 0, s[8:9]
	s_mov_b32 m0, s48
	s_nop 0
	global_load_lds_dwordx4 v[190:191], off
	v_lshl_add_u64 v[190:191], v[230:231], 0, s[8:9]
	s_mov_b32 m0, s49
	s_nop 0
	global_load_lds_dwordx4 v[190:191], off
	s_waitcnt vmcnt(8)
	s_waitcnt lgkmcnt(0)
	s_barrier
	v_mfma_f32_16x16x32_bf16 v[70:73], v[58:61], v[182:185], v[70:73]
	v_mfma_f32_16x16x32_bf16 v[66:69], v[138:141], v[182:185], v[66:69]
	v_mfma_f32_16x16x32_bf16 v[46:49], v[58:61], v[202:205], v[46:49]
	v_mfma_f32_16x16x32_bf16 v[42:45], v[138:141], v[202:205], v[42:45]
	v_mfma_f32_16x16x32_bf16 v[30:33], v[58:61], v[210:213], v[30:33]
	v_mfma_f32_16x16x32_bf16 v[26:29], v[138:141], v[210:213], v[26:29]
	v_mfma_f32_16x16x32_bf16 v[14:17], v[58:61], v[218:221], v[14:17]
	v_mfma_f32_16x16x32_bf16 v[10:13], v[138:141], v[218:221], v[10:13]
	v_mfma_f32_16x16x32_bf16 v[70:73], v[62:65], v[186:189], v[70:73]
	v_mfma_f32_16x16x32_bf16 v[66:69], v[142:145], v[186:189], v[66:69]
	v_mfma_f32_16x16x32_bf16 v[46:49], v[62:65], v[206:209], v[46:49]
	v_mfma_f32_16x16x32_bf16 v[42:45], v[142:145], v[206:209], v[42:45]
	v_mfma_f32_16x16x32_bf16 v[30:33], v[62:65], v[214:217], v[30:33]
	v_mfma_f32_16x16x32_bf16 v[26:29], v[142:145], v[214:217], v[26:29]
	v_mfma_f32_16x16x32_bf16 v[14:17], v[62:65], v[222:225], v[14:17]
	v_mfma_f32_16x16x32_bf16 v[10:13], v[142:145], v[222:225], v[10:13]
	v_mfma_f32_16x16x32_bf16 v[50:53], v[146:149], v[182:185], v[50:53]
	v_mfma_f32_16x16x32_bf16 v[62:65], v[150:153], v[186:189], v[50:53]
	v_mfma_f32_16x16x32_bf16 v[50:53], v[174:177], v[182:185], v[54:57]
	v_mfma_f32_16x16x32_bf16 v[38:41], v[146:149], v[202:205], v[38:41]
	v_mfma_f32_16x16x32_bf16 v[34:37], v[174:177], v[202:205], v[34:37]
	v_mfma_f32_16x16x32_bf16 v[22:25], v[146:149], v[210:213], v[22:25]
	v_mfma_f32_16x16x32_bf16 v[18:21], v[174:177], v[210:213], v[18:21]
	v_mfma_f32_16x16x32_bf16 v[6:9], v[146:149], v[218:221], v[6:9]
	v_mfma_f32_16x16x32_bf16 v[2:5], v[174:177], v[218:221], v[2:5]
	v_mfma_f32_16x16x32_bf16 v[58:61], v[178:181], v[186:189], v[50:53]
	v_mfma_f32_16x16x32_bf16 v[38:41], v[150:153], v[206:209], v[38:41]
	v_mfma_f32_16x16x32_bf16 v[34:37], v[178:181], v[206:209], v[34:37]
	v_mfma_f32_16x16x32_bf16 v[22:25], v[150:153], v[214:217], v[22:25]
	v_mfma_f32_16x16x32_bf16 v[18:21], v[178:181], v[214:217], v[18:21]
	v_mfma_f32_16x16x32_bf16 v[6:9], v[150:153], v[222:225], v[6:9]
	v_mfma_f32_16x16x32_bf16 v[2:5], v[178:181], v[222:225], v[2:5]
	s_barrier
	s_add_i32 s55, s55, 2
	s_add_u32 s53, s53, 0x100
	s_addc_u32 s54, s54, 0
	s_add_u32 s22, s22, 0x100
	s_addc_u32 s23, s23, 0
	s_cmp_lt_u32 s55, 30
	s_cbranch_scc1 .LBB0_2766
	s_setprio 0
	s_andn2_b64 vcc, exec, s[10:11]
	s_cbranch_vccnz .LBB0_2769
	s_barrier

; #define PG8_STAGE(bufoff, gbase, voff) do { _Pragma("unroll") for (int _i = 0; _i < 2; ++_i) \
;         __builtin_amdgcn_global_load_lds((const unsigned*)((const char*)(gbase) + (voff)[_i]), (LAS unsigned*)(lds + (bufoff) + ldsw + _i * 8192), 16, 0, 0); } while (0)
; #define PG8_LDA(dst, b, h) do { _Pragma("unroll") for (int m = 0; m < 4; ++m) _Pragma("unroll") for (int k = 0; k < 2; ++k) dst[m][k] = *(const LAS bf16x8*)(lds + PG8_SA(b, h) + aoff + m * 2048 + k * 1024); } while (0)
; #define PG8_LDB(dst, b, h) do { _Pragma("unroll") for (int n = 0; n < 2; ++n) _Pragma("unroll") for (int k = 0; k < 2; ++k) dst[n][k] = *(const LAS bf16x8*)(lds + PG8_SB(b, h) + boff + n * 2048 + k * 1024); } while (0)
; #define PG8_MMA(ai, bj, At, Bt) do { __builtin_amdgcn_s_setprio(1); _Pragma("unroll") for (int m = 0; m < 4; ++m) _Pragma("unroll") for (int n = 0; n < 2; ++n) _Pragma("unroll") for (int k = 0; k < 2; ++k) \
;         acc[ai][bj][m][n] = __builtin_amdgcn_mfma_f32_16x16x32_bf16(Bt[n][k], At[m][k], acc[ai][bj][m][n], 0, 0, 0); __builtin_amdgcn_s_setprio(0); } while (0)
; #define PG8_WAIT_V(n) asm volatile("s_waitcnt vmcnt(" #n ")" ::: "memory")
; #define PG8_WAIT_L(n) asm volatile("s_waitcnt lgkmcnt(" #n ")" ::: "memory")
; #define PG8_BAR __builtin_amdgcn_s_barrier()
; #define PG8_SCHED __builtin_amdgcn_sched_barrier(0)
; template <class Epi, class Sched, bool ALIGN_EPI = false, bool SP2 = false>
; __device__ __forceinline__ void gemm_phase(LAS unsigned char* lds, const Gemm g, const Sched& S, const Epi& E) {
;     ...
;             if constexpr (SP2) {
;             PG8_LDB(B0, 0, 0); PG8_LDB(B1, 0, 1); PG8_SCHED; PG8_LDA(At, 0, 0); PG8_STAGE(PG8_SA(1, 1), a1 + hstep, voffA);
;             PG8_WAIT_V(8); PG8_WAIT_L(0); PG8_BAR; PG8_MMA(0, 0, At, B0); PG8_MMA(0, 1, At, B1); PG8_BAR; PG8_SCHED;
;             PG8_LDA(At, 0, 1); PG8_STAGE(PG8_SB(0, 0), b2, voffB); PG8_STAGE(PG8_SB(0, 1), b2 + hstepB, voffB); PG8_STAGE(PG8_SA(0, 0), a2, voffA);
;             PG8_WAIT_V(8); PG8_WAIT_L(0); PG8_BAR; PG8_MMA(1, 0, At, B0); PG8_MMA(1, 1, At, B1); PG8_BAR; PG8_SCHED;
.Lprio_2916:
	ds_read_b128 v[66:69], v173
	ds_read_b128 v[70:73], v173 offset:1024
	ds_read_b128 v[74:77], v173 offset:2048
	ds_read_b128 v[78:81], v173 offset:3072
	ds_read_b128 v[162:165], v174
	ds_read_b128 v[180:183], v174 offset:1024
	ds_read_b128 v[184:187], v174 offset:2048
	ds_read_b128 v[188:191], v174 offset:3072
	s_add_u32 s20, s18, 0xfff80080
	s_addc_u32 s21, s19, -1
	s_cmp_eq_u32 s50, 28
	s_cselect_b32 s23, s13, s21
	s_cselect_b32 s22, s46, s20
	s_cselect_b32 s21, s11, s49
	s_cselect_b32 s20, s47, s48
	v_lshl_add_u64 v[166:167], s[18:19], 0, v[156:157]
	s_add_i32 m0, s28, 0xc000
	ds_read_b128 v[192:195], v175
	ds_read_b128 v[196:199], v175 offset:1024
	ds_read_b128 v[200:203], v175 offset:2048
	ds_read_b128 v[204:207], v175 offset:3072
	ds_read_b128 v[208:211], v175 offset:4096
	ds_read_b128 v[212:215], v175 offset:5120
	ds_read_b128 v[216:219], v175 offset:6144
	ds_read_b128 v[220:223], v175 offset:7168
	global_load_lds_dwordx4 v[166:167], off
	v_lshl_add_u64 v[166:167], s[18:19], 0, v[154:155]
	s_add_i32 m0, s28, 0xe000
	s_nop 0
	global_load_lds_dwordx4 v[166:167], off
	s_waitcnt lgkmcnt(0)
	s_barrier
	v_mfma_f32_16x16x32_bf16 v[142:145], v[66:69], v[192:195], 0
	v_mfma_f32_16x16x32_bf16 v[138:141], v[74:77], v[192:195], 0
	v_mfma_f32_16x16x32_bf16 v[126:129], v[66:69], v[200:203], 0
	v_mfma_f32_16x16x32_bf16 v[122:125], v[74:77], v[200:203], 0
	v_mfma_f32_16x16x32_bf16 v[110:113], v[66:69], v[208:211], 0
	v_mfma_f32_16x16x32_bf16 v[106:109], v[74:77], v[208:211], 0
	v_mfma_f32_16x16x32_bf16 v[94:97], v[66:69], v[216:219], 0
	v_mfma_f32_16x16x32_bf16 v[90:93], v[74:77], v[216:219], 0
	v_mfma_f32_16x16x32_bf16 v[142:145], v[70:73], v[196:199], v[142:145]
	v_mfma_f32_16x16x32_bf16 v[138:141], v[78:81], v[196:199], v[138:141]
	v_mfma_f32_16x16x32_bf16 v[126:129], v[70:73], v[204:207], v[126:129]
	v_mfma_f32_16x16x32_bf16 v[122:125], v[78:81], v[204:207], v[122:125]
	v_mfma_f32_16x16x32_bf16 v[110:113], v[70:73], v[212:215], v[110:113]
	v_mfma_f32_16x16x32_bf16 v[106:109], v[78:81], v[212:215], v[106:109]
	v_mfma_f32_16x16x32_bf16 v[94:97], v[70:73], v[220:223], v[94:97]
	v_mfma_f32_16x16x32_bf16 v[90:93], v[78:81], v[220:223], v[90:93]
	v_mfma_f32_16x16x32_bf16 v[134:137], v[162:165], v[192:195], 0
	v_mfma_f32_16x16x32_bf16 v[130:133], v[184:187], v[192:195], 0
	v_mfma_f32_16x16x32_bf16 v[118:121], v[162:165], v[200:203], 0
	v_mfma_f32_16x16x32_bf16 v[114:117], v[184:187], v[200:203], 0
	v_mfma_f32_16x16x32_bf16 v[102:105], v[162:165], v[208:211], 0
	v_mfma_f32_16x16x32_bf16 v[98:101], v[184:187], v[208:211], 0
	v_mfma_f32_16x16x32_bf16 v[86:89], v[162:165], v[216:219], 0
	v_mfma_f32_16x16x32_bf16 v[82:85], v[184:187], v[216:219], 0
	v_mfma_f32_16x16x32_bf16 v[134:137], v[180:183], v[196:199], v[134:137]
	v_mfma_f32_16x16x32_bf16 v[130:133], v[188:191], v[196:199], v[130:133]
	v_mfma_f32_16x16x32_bf16 v[118:121], v[180:183], v[204:207], v[118:121]
	v_mfma_f32_16x16x32_bf16 v[114:117], v[188:191], v[204:207], v[114:117]
	v_mfma_f32_16x16x32_bf16 v[102:105], v[180:183], v[212:215], v[102:105]
	v_mfma_f32_16x16x32_bf16 v[98:101], v[188:191], v[212:215], v[98:101]
	v_mfma_f32_16x16x32_bf16 v[86:89], v[180:183], v[220:223], v[86:89]
	v_mfma_f32_16x16x32_bf16 v[82:85], v[188:191], v[220:223], v[82:85]
	s_barrier
	s_add_i32 s51, s41, s25
	v_lshl_add_u64 v[166:167], s[20:21], 0, v[150:151]
	s_mov_b32 m0, s51
	ds_read_b128 v[192:195], v175 offset:16384
	ds_read_b128 v[196:199], v175 offset:17408
	ds_read_b128 v[200:203], v175 offset:18432
	ds_read_b128 v[204:207], v175 offset:19456
	ds_read_b128 v[208:211], v175 offset:20480
	ds_read_b128 v[212:215], v175 offset:21504
	ds_read_b128 v[216:219], v175 offset:22528
	ds_read_b128 v[220:223], v175 offset:23552
	global_load_lds_dwordx4 v[166:167], off
	s_add_i32 m0, s51, 0x2000
	s_add_u32 s52, s20, 0x80000
	v_lshl_add_u64 v[224:225], s[20:21], 0, v[146:147]
	s_addc_u32 s53, s21, 0
	s_add_i32 s51, s42, s25
	global_load_lds_dwordx4 v[224:225], off
	v_lshl_add_u64 v[226:227], s[52:53], 0, v[150:151]
	s_mov_b32 m0, s51
	v_lshl_add_u64 v[228:229], s[22:23], 0, v[148:149]
	global_load_lds_dwordx4 v[226:227], off
	v_lshl_add_u64 v[226:227], s[52:53], 0, v[146:147]
	s_add_i32 m0, s51, 0x2000
	s_nop 0
	global_load_lds_dwordx4 v[226:227], off
	v_lshl_add_u64 v[226:227], s[22:23], 0, v[152:153]
	s_mov_b32 m0, s28
	s_nop 0
	global_load_lds_dwordx4 v[226:227], off
	s_mov_b32 m0, s29
	s_nop 0
	global_load_lds_dwordx4 v[228:229], off
	s_waitcnt lgkmcnt(0)
	s_barrier
	v_mfma_f32_16x16x32_bf16 v[62:65], v[66:69], v[192:195], 0
	v_mfma_f32_16x16x32_bf16 v[58:61], v[74:77], v[192:195], 0
	v_mfma_f32_16x16x32_bf16 v[46:49], v[66:69], v[200:203], 0
	v_mfma_f32_16x16x32_bf16 v[42:45], v[74:77], v[200:203], 0
	v_mfma_f32_16x16x32_bf16 v[30:33], v[66:69], v[208:211], 0
	v_mfma_f32_16x16x32_bf16 v[26:29], v[74:77], v[208:211], 0
	v_mfma_f32_16x16x32_bf16 v[14:17], v[66:69], v[216:219], 0
	v_mfma_f32_16x16x32_bf16 v[10:13], v[74:77], v[216:219], 0
	v_mfma_f32_16x16x32_bf16 v[62:65], v[70:73], v[196:199], v[62:65]
	v_mfma_f32_16x16x32_bf16 v[58:61], v[78:81], v[196:199], v[58:61]
	v_mfma_f32_16x16x32_bf16 v[46:49], v[70:73], v[204:207], v[46:49]
	v_mfma_f32_16x16x32_bf16 v[42:45], v[78:81], v[204:207], v[42:45]
	v_mfma_f32_16x16x32_bf16 v[30:33], v[70:73], v[212:215], v[30:33]
	v_mfma_f32_16x16x32_bf16 v[26:29], v[78:81], v[212:215], v[26:29]
	v_mfma_f32_16x16x32_bf16 v[14:17], v[70:73], v[220:223], v[14:17]
	v_mfma_f32_16x16x32_bf16 v[10:13], v[78:81], v[220:223], v[10:13]
	v_mfma_f32_16x16x32_bf16 v[54:57], v[162:165], v[192:195], 0
	v_mfma_f32_16x16x32_bf16 v[50:53], v[184:187], v[192:195], 0
	v_mfma_f32_16x16x32_bf16 v[38:41], v[162:165], v[200:203], 0
	v_mfma_f32_16x16x32_bf16 v[34:37], v[184:187], v[200:203], 0
	v_mfma_f32_16x16x32_bf16 v[22:25], v[162:165], v[208:211], 0
	v_mfma_f32_16x16x32_bf16 v[18:21], v[184:187], v[208:211], 0
	v_mfma_f32_16x16x32_bf16 v[6:9], v[162:165], v[216:219], 0
	v_mfma_f32_16x16x32_bf16 v[2:5], v[184:187], v[216:219], 0
	v_mfma_f32_16x16x32_bf16 v[54:57], v[180:183], v[196:199], v[54:57]
	v_mfma_f32_16x16x32_bf16 v[50:53], v[188:191], v[196:199], v[50:53]
	v_mfma_f32_16x16x32_bf16 v[38:41], v[180:183], v[204:207], v[38:41]
	v_mfma_f32_16x16x32_bf16 v[34:37], v[188:191], v[204:207], v[34:37]
	v_mfma_f32_16x16x32_bf16 v[22:25], v[180:183], v[212:215], v[22:25]
	v_mfma_f32_16x16x32_bf16 v[18:21], v[188:191], v[212:215], v[18:21]
	v_mfma_f32_16x16x32_bf16 v[6:9], v[180:183], v[220:223], v[6:9]
	v_mfma_f32_16x16x32_bf16 v[2:5], v[188:191], v[220:223], v[2:5]
	s_barrier
; #define PG8_STAGE(bufoff, gbase, voff) do { _Pragma("unroll") for (int _i = 0; _i < 2; ++_i) \
;         __builtin_amdgcn_global_load_lds((const unsigned*)((const char*)(gbase) + (voff)[_i]), (LAS unsigned*)(lds + (bufoff) + ldsw + _i * 8192), 16, 0, 0); } while (0)
; #define PG8_LDA(dst, b, h) do { _Pragma("unroll") for (int m = 0; m < 4; ++m) _Pragma("unroll") for (int k = 0; k < 2; ++k) dst[m][k] = *(const LAS bf16x8*)(lds + PG8_SA(b, h) + aoff + m * 2048 + k * 1024); } while (0)
; #define PG8_LDB(dst, b, h) do { _Pragma("unroll") for (int n = 0; n < 2; ++n) _Pragma("unroll") for (int k = 0; k < 2; ++k) dst[n][k] = *(const LAS bf16x8*)(lds + PG8_SB(b, h) + boff + n * 2048 + k * 1024); } while (0)
; #define PG8_MMA(ai, bj, At, Bt) do { __builtin_amdgcn_s_setprio(1); _Pragma("unroll") for (int m = 0; m < 4; ++m) _Pragma("unroll") for (int n = 0; n < 2; ++n) _Pragma("unroll") for (int k = 0; k < 2; ++k) \
;         acc[ai][bj][m][n] = __builtin_amdgcn_mfma_f32_16x16x32_bf16(Bt[n][k], At[m][k], acc[ai][bj][m][n], 0, 0, 0); __builtin_amdgcn_s_setprio(0); } while (0)
; #define PG8_WAIT_V(n) asm volatile("s_waitcnt vmcnt(" #n ")" ::: "memory")
; #define PG8_WAIT_L(n) asm volatile("s_waitcnt lgkmcnt(" #n ")" ::: "memory")
; #define PG8_BAR __builtin_amdgcn_s_barrier()
; #define PG8_SCHED __builtin_amdgcn_sched_barrier(0)
; template <class Epi, class Sched, bool ALIGN_EPI = false, bool SP2 = false>
; __device__ __forceinline__ void gemm_phase(LAS unsigned char* lds, const Gemm g, const Sched& S, const Epi& E) {
;     ...
;             PG8_LDB(B0, 1, 0); PG8_LDB(B1, 1, 1); PG8_SCHED; PG8_LDA(At, 1, 0); PG8_STAGE(PG8_SA(0, 1), a2 + hstep, voffA);
;             PG8_WAIT_V(8); PG8_WAIT_L(0); PG8_BAR; PG8_MMA(0, 0, At, B0); PG8_MMA(0, 1, At, B1); PG8_BAR; PG8_SCHED;
;             PG8_LDA(At, 1, 1); PG8_STAGE(PG8_SB(1, 0), b3, voffB); PG8_STAGE(PG8_SB(1, 1), b3 + hstepB, voffB); PG8_STAGE(PG8_SA(1, 0), a3, voffA);
;             PG8_WAIT_V(8); PG8_WAIT_L(0); PG8_BAR; PG8_MMA(1, 0, At, B0); PG8_MMA(1, 1, At, B1); PG8_BAR; PG8_SCHED;
	s_add_i32 s51, 0, 0x18000
	s_add_i32 s52, 0, 0x1c000
	v_add_u32_e32 v78, s51, v169
	v_add_u32_e32 v168, s52, v169
	ds_read_b128 v[66:69], v78
	ds_read_b128 v[70:73], v78 offset:1024
	ds_read_b128 v[74:77], v78 offset:2048
	ds_read_b128 v[78:81], v78 offset:3072
	ds_read_b128 v[162:165], v168
	ds_read_b128 v[180:183], v168 offset:1024
	ds_read_b128 v[184:187], v168 offset:2048
	ds_read_b128 v[188:191], v168 offset:3072
	s_add_u32 s22, s22, 0x80000
	s_addc_u32 s23, s23, 0
	s_mov_b32 m0, s30
	v_lshl_add_u64 v[230:231], s[22:23], 0, v[152:153]
	ds_read_b128 v[192:195], v175 offset:32768
	ds_read_b128 v[196:199], v175 offset:33792
	ds_read_b128 v[200:203], v175 offset:34816
	ds_read_b128 v[204:207], v175 offset:35840
	ds_read_b128 v[208:211], v175 offset:36864
	ds_read_b128 v[212:215], v175 offset:37888
	ds_read_b128 v[216:219], v175 offset:38912
	ds_read_b128 v[220:223], v175 offset:39936
	global_load_lds_dwordx4 v[230:231], off
	v_lshl_add_u64 v[230:231], s[22:23], 0, v[148:149]
	s_mov_b32 m0, s31
	s_nop 0
	global_load_lds_dwordx4 v[230:231], off
	s_waitcnt vmcnt(8)
	s_waitcnt lgkmcnt(0)
	s_barrier
	v_mfma_f32_16x16x32_bf16 v[142:145], v[66:69], v[192:195], v[142:145]
	v_mfma_f32_16x16x32_bf16 v[138:141], v[74:77], v[192:195], v[138:141]
	v_mfma_f32_16x16x32_bf16 v[126:129], v[66:69], v[200:203], v[126:129]
	v_mfma_f32_16x16x32_bf16 v[122:125], v[74:77], v[200:203], v[122:125]
	v_mfma_f32_16x16x32_bf16 v[110:113], v[66:69], v[208:211], v[110:113]
	v_mfma_f32_16x16x32_bf16 v[106:109], v[74:77], v[208:211], v[106:109]
	v_mfma_f32_16x16x32_bf16 v[94:97], v[66:69], v[216:219], v[94:97]
	v_mfma_f32_16x16x32_bf16 v[90:93], v[74:77], v[216:219], v[90:93]
	v_mfma_f32_16x16x32_bf16 v[142:145], v[70:73], v[196:199], v[142:145]
	v_mfma_f32_16x16x32_bf16 v[138:141], v[78:81], v[196:199], v[138:141]
	v_mfma_f32_16x16x32_bf16 v[126:129], v[70:73], v[204:207], v[126:129]
	v_mfma_f32_16x16x32_bf16 v[122:125], v[78:81], v[204:207], v[122:125]
	v_mfma_f32_16x16x32_bf16 v[110:113], v[70:73], v[212:215], v[110:113]
	v_mfma_f32_16x16x32_bf16 v[106:109], v[78:81], v[212:215], v[106:109]
	v_mfma_f32_16x16x32_bf16 v[94:97], v[70:73], v[220:223], v[94:97]
	v_mfma_f32_16x16x32_bf16 v[90:93], v[78:81], v[220:223], v[90:93]
	v_mfma_f32_16x16x32_bf16 v[134:137], v[162:165], v[192:195], v[134:137]
	v_mfma_f32_16x16x32_bf16 v[130:133], v[184:187], v[192:195], v[130:133]
	v_mfma_f32_16x16x32_bf16 v[118:121], v[162:165], v[200:203], v[118:121]
	v_mfma_f32_16x16x32_bf16 v[114:117], v[184:187], v[200:203], v[114:117]
	v_mfma_f32_16x16x32_bf16 v[102:105], v[162:165], v[208:211], v[102:105]
	v_mfma_f32_16x16x32_bf16 v[98:101], v[184:187], v[208:211], v[98:101]
	v_mfma_f32_16x16x32_bf16 v[86:89], v[162:165], v[216:219], v[86:89]
	v_mfma_f32_16x16x32_bf16 v[82:85], v[184:187], v[216:219], v[82:85]
	v_mfma_f32_16x16x32_bf16 v[134:137], v[180:183], v[196:199], v[134:137]
	v_mfma_f32_16x16x32_bf16 v[130:133], v[188:191], v[196:199], v[130:133]
	v_mfma_f32_16x16x32_bf16 v[118:121], v[180:183], v[204:207], v[118:121]
	v_mfma_f32_16x16x32_bf16 v[114:117], v[188:191], v[204:207], v[114:117]
	v_mfma_f32_16x16x32_bf16 v[102:105], v[180:183], v[212:215], v[102:105]
	v_mfma_f32_16x16x32_bf16 v[98:101], v[188:191], v[212:215], v[98:101]
	v_mfma_f32_16x16x32_bf16 v[86:89], v[180:183], v[220:223], v[86:89]
	v_mfma_f32_16x16x32_bf16 v[82:85], v[188:191], v[220:223], v[82:85]
	s_barrier
	s_add_i32 s22, s51, s25
	v_lshl_add_u64 v[166:167], v[166:167], 0, s[6:7]
	s_mov_b32 m0, s22
	ds_read_b128 v[192:195], v175 offset:49152
	ds_read_b128 v[196:199], v175 offset:50176
	ds_read_b128 v[200:203], v175 offset:51200
	ds_read_b128 v[204:207], v175 offset:52224
	ds_read_b128 v[208:211], v175 offset:53248
	ds_read_b128 v[212:215], v175 offset:54272
	ds_read_b128 v[216:219], v175 offset:55296
	ds_read_b128 v[220:223], v175 offset:56320
	global_load_lds_dwordx4 v[166:167], off
	s_add_i32 m0, s22, 0x2000
	s_add_u32 s20, s20, 0x80080
	v_lshl_add_u64 v[166:167], v[224:225], 0, s[6:7]
	s_addc_u32 s21, s21, 0
	s_add_i32 s22, s52, s25
	global_load_lds_dwordx4 v[166:167], off
	v_lshl_add_u64 v[166:167], s[20:21], 0, v[150:151]
	s_mov_b32 m0, s22
	s_nop 0
	global_load_lds_dwordx4 v[166:167], off
	v_lshl_add_u64 v[166:167], s[20:21], 0, v[146:147]
	s_add_i32 m0, s22, 0x2000
	s_nop 0
	global_load_lds_dwordx4 v[166:167], off
	v_lshl_add_u64 v[166:167], v[226:227], 0, s[6:7]
	s_mov_b32 m0, s39
	s_nop 0
	global_load_lds_dwordx4 v[166:167], off
	v_lshl_add_u64 v[166:167], v[228:229], 0, s[6:7]
	s_mov_b32 m0, s40
	s_nop 0
	global_load_lds_dwordx4 v[166:167], off
	s_waitcnt vmcnt(8)
	s_waitcnt lgkmcnt(0)
	s_barrier
	v_mfma_f32_16x16x32_bf16 v[62:65], v[66:69], v[192:195], v[62:65]
	v_mfma_f32_16x16x32_bf16 v[58:61], v[74:77], v[192:195], v[58:61]
	v_mfma_f32_16x16x32_bf16 v[46:49], v[66:69], v[200:203], v[46:49]
	v_mfma_f32_16x16x32_bf16 v[42:45], v[74:77], v[200:203], v[42:45]
	v_mfma_f32_16x16x32_bf16 v[30:33], v[66:69], v[208:211], v[30:33]
	v_mfma_f32_16x16x32_bf16 v[26:29], v[74:77], v[208:211], v[26:29]
	v_mfma_f32_16x16x32_bf16 v[14:17], v[66:69], v[216:219], v[14:17]
	v_mfma_f32_16x16x32_bf16 v[10:13], v[74:77], v[216:219], v[10:13]
	v_mfma_f32_16x16x32_bf16 v[62:65], v[70:73], v[196:199], v[62:65]
	v_mfma_f32_16x16x32_bf16 v[58:61], v[78:81], v[196:199], v[58:61]
	v_mfma_f32_16x16x32_bf16 v[46:49], v[70:73], v[204:207], v[46:49]
	v_mfma_f32_16x16x32_bf16 v[42:45], v[78:81], v[204:207], v[42:45]
	v_mfma_f32_16x16x32_bf16 v[30:33], v[70:73], v[212:215], v[30:33]
	v_mfma_f32_16x16x32_bf16 v[26:29], v[78:81], v[212:215], v[26:29]
	v_mfma_f32_16x16x32_bf16 v[14:17], v[70:73], v[220:223], v[14:17]
	v_mfma_f32_16x16x32_bf16 v[10:13], v[78:81], v[220:223], v[10:13]
	v_mfma_f32_16x16x32_bf16 v[54:57], v[162:165], v[192:195], v[54:57]
	v_mfma_f32_16x16x32_bf16 v[50:53], v[184:187], v[192:195], v[50:53]
	v_mfma_f32_16x16x32_bf16 v[38:41], v[162:165], v[200:203], v[38:41]
	v_mfma_f32_16x16x32_bf16 v[34:37], v[184:187], v[200:203], v[34:37]
	v_mfma_f32_16x16x32_bf16 v[22:25], v[162:165], v[208:211], v[22:25]
	v_mfma_f32_16x16x32_bf16 v[18:21], v[184:187], v[208:211], v[18:21]
	v_mfma_f32_16x16x32_bf16 v[6:9], v[162:165], v[216:219], v[6:9]
	v_mfma_f32_16x16x32_bf16 v[2:5], v[184:187], v[216:219], v[2:5]
	v_mfma_f32_16x16x32_bf16 v[54:57], v[180:183], v[196:199], v[54:57]
	v_mfma_f32_16x16x32_bf16 v[50:53], v[188:191], v[196:199], v[50:53]
	v_mfma_f32_16x16x32_bf16 v[38:41], v[180:183], v[204:207], v[38:41]
	v_mfma_f32_16x16x32_bf16 v[34:37], v[188:191], v[204:207], v[34:37]
	v_mfma_f32_16x16x32_bf16 v[22:25], v[180:183], v[212:215], v[22:25]
	v_mfma_f32_16x16x32_bf16 v[18:21], v[188:191], v[212:215], v[18:21]
	v_mfma_f32_16x16x32_bf16 v[6:9], v[180:183], v[220:223], v[6:9]
	v_mfma_f32_16x16x32_bf16 v[2:5], v[188:191], v[220:223], v[2:5]
	s_barrier
	s_add_i32 s50, s50, 2
	s_add_u32 s48, s48, 0x100
	s_addc_u32 s49, s49, 0
	s_add_u32 s18, s18, 0x100
	s_addc_u32 s19, s19, 0
	s_cmp_lt_u32 s50, 30
; #define PG8_STAGE(bufoff, gbase, voff) do { _Pragma("unroll") for (int _i = 0; _i < 2; ++_i) \
;         __builtin_amdgcn_global_load_lds((const unsigned*)((const char*)(gbase) + (voff)[_i]), (LAS unsigned*)(lds + (bufoff) + ldsw + _i * 8192), 16, 0, 0); } while (0)
; #define PG8_LDA(dst, b, h) do { _Pragma("unroll") for (int m = 0; m < 4; ++m) _Pragma("unroll") for (int k = 0; k < 2; ++k) dst[m][k] = *(const LAS bf16x8*)(lds + PG8_SA(b, h) + aoff + m * 2048 + k * 1024); } while (0)
; #define PG8_LDB(dst, b, h) do { _Pragma("unroll") for (int n = 0; n < 2; ++n) _Pragma("unroll") for (int k = 0; k < 2; ++k) dst[n][k] = *(const LAS bf16x8*)(lds + PG8_SB(b, h) + boff + n * 2048 + k * 1024); } while (0)
; #define PG8_MMA(ai, bj, At, Bt) do { __builtin_amdgcn_s_setprio(1); _Pragma("unroll") for (int m = 0; m < 4; ++m) _Pragma("unroll") for (int n = 0; n < 2; ++n) _Pragma("unroll") for (int k = 0; k < 2; ++k) \
;         acc[ai][bj][m][n] = __builtin_amdgcn_mfma_f32_16x16x32_bf16(Bt[n][k], At[m][k], acc[ai][bj][m][n], 0, 0, 0); __builtin_amdgcn_s_setprio(0); } while (0)
; #define PG8_WAIT_V(n) asm volatile("s_waitcnt vmcnt(" #n ")" ::: "memory")
; #define PG8_WAIT_L(n) asm volatile("s_waitcnt lgkmcnt(" #n ")" ::: "memory")
; #define PG8_BAR __builtin_amdgcn_s_barrier()
; #define PG8_SCHED __builtin_amdgcn_sched_barrier(0)
; template <class Epi, class Sched, bool ALIGN_EPI = false, bool SP2 = false>
; __device__ __forceinline__ void gemm_phase(LAS unsigned char* lds, const Gemm g, const Sched& S, const Epi& E) {
;     ...
;         for (int t = 0; t < nt; t += 2) {
;             const bool last = (t == nt - 2);
;             const char* a1 = cA + (size_t)(t + 1) * kstep;
;             const char* a2 = last ? nA : cA + (size_t)(t + 2) * kstep; const char* b2 = last ? nB : cB + (size_t)(t + 2) * kstep;
;             const char* a3 = a2 + kstep; const char* b3 = b2 + kstep;
;             if (last && has_next) S.a_ready(nxt);
;             if constexpr (SP2) {
;             PG8_LDB(B0, 0, 0); PG8_LDB(B1, 0, 1); PG8_SCHED; PG8_LDA(At, 0, 0); PG8_STAGE(PG8_SA(1, 1), a1 + hstep, voffA);
;             PG8_WAIT_V(8); PG8_WAIT_L(0); PG8_BAR; PG8_MMA(0, 0, At, B0); PG8_MMA(0, 1, At, B1); PG8_BAR; PG8_SCHED;
;             PG8_LDA(At, 0, 1); PG8_STAGE(PG8_SB(0, 0), b2, voffB); PG8_STAGE(PG8_SB(0, 1), b2 + hstepB, voffB); PG8_STAGE(PG8_SA(0, 0), a2, voffA);
.LBB0_2916:
	ds_read_b128 v[66:69], v173
	ds_read_b128 v[70:73], v173 offset:1024
	ds_read_b128 v[74:77], v173 offset:2048
	ds_read_b128 v[78:81], v173 offset:3072
	ds_read_b128 v[162:165], v174
	ds_read_b128 v[180:183], v174 offset:1024
	ds_read_b128 v[184:187], v174 offset:2048
	ds_read_b128 v[188:191], v174 offset:3072
	s_add_u32 s20, s18, 0xfff80080
	s_addc_u32 s21, s19, -1
	s_cmp_eq_u32 s50, 28
	s_cselect_b32 s23, s13, s21
	s_cselect_b32 s22, s46, s20
	s_cselect_b32 s21, s11, s49
	s_cselect_b32 s20, s47, s48
	v_lshl_add_u64 v[166:167], s[18:19], 0, v[156:157]
	s_add_i32 m0, s28, 0xc000
	ds_read_b128 v[192:195], v175
	ds_read_b128 v[196:199], v175 offset:1024
	ds_read_b128 v[200:203], v175 offset:2048
	ds_read_b128 v[204:207], v175 offset:3072
	ds_read_b128 v[208:211], v175 offset:4096
	ds_read_b128 v[212:215], v175 offset:5120
	ds_read_b128 v[216:219], v175 offset:6144
	ds_read_b128 v[220:223], v175 offset:7168
	global_load_lds_dwordx4 v[166:167], off
	v_lshl_add_u64 v[166:167], s[18:19], 0, v[154:155]
	s_add_i32 m0, s28, 0xe000
	s_nop 0
	global_load_lds_dwordx4 v[166:167], off
	s_waitcnt vmcnt(8)
	s_waitcnt lgkmcnt(0)
	s_barrier
	v_mfma_f32_16x16x32_bf16 v[142:145], v[66:69], v[192:195], v[142:145]
	v_mfma_f32_16x16x32_bf16 v[138:141], v[74:77], v[192:195], v[138:141]
	v_mfma_f32_16x16x32_bf16 v[126:129], v[66:69], v[200:203], v[126:129]
	v_mfma_f32_16x16x32_bf16 v[122:125], v[74:77], v[200:203], v[122:125]
	v_mfma_f32_16x16x32_bf16 v[110:113], v[66:69], v[208:211], v[110:113]
	v_mfma_f32_16x16x32_bf16 v[106:109], v[74:77], v[208:211], v[106:109]
	v_mfma_f32_16x16x32_bf16 v[94:97], v[66:69], v[216:219], v[94:97]
	v_mfma_f32_16x16x32_bf16 v[90:93], v[74:77], v[216:219], v[90:93]
	v_mfma_f32_16x16x32_bf16 v[142:145], v[70:73], v[196:199], v[142:145]
	v_mfma_f32_16x16x32_bf16 v[138:141], v[78:81], v[196:199], v[138:141]
	v_mfma_f32_16x16x32_bf16 v[126:129], v[70:73], v[204:207], v[126:129]
	v_mfma_f32_16x16x32_bf16 v[122:125], v[78:81], v[204:207], v[122:125]
	v_mfma_f32_16x16x32_bf16 v[110:113], v[70:73], v[212:215], v[110:113]
	v_mfma_f32_16x16x32_bf16 v[106:109], v[78:81], v[212:215], v[106:109]
	v_mfma_f32_16x16x32_bf16 v[94:97], v[70:73], v[220:223], v[94:97]
	v_mfma_f32_16x16x32_bf16 v[90:93], v[78:81], v[220:223], v[90:93]
	v_mfma_f32_16x16x32_bf16 v[134:137], v[162:165], v[192:195], v[134:137]
	v_mfma_f32_16x16x32_bf16 v[130:133], v[184:187], v[192:195], v[130:133]
	v_mfma_f32_16x16x32_bf16 v[118:121], v[162:165], v[200:203], v[118:121]
	v_mfma_f32_16x16x32_bf16 v[114:117], v[184:187], v[200:203], v[114:117]
	v_mfma_f32_16x16x32_bf16 v[102:105], v[162:165], v[208:211], v[102:105]
	v_mfma_f32_16x16x32_bf16 v[98:101], v[184:187], v[208:211], v[98:101]
	v_mfma_f32_16x16x32_bf16 v[86:89], v[162:165], v[216:219], v[86:89]
	v_mfma_f32_16x16x32_bf16 v[82:85], v[184:187], v[216:219], v[82:85]
	v_mfma_f32_16x16x32_bf16 v[134:137], v[180:183], v[196:199], v[134:137]
	v_mfma_f32_16x16x32_bf16 v[130:133], v[188:191], v[196:199], v[130:133]
	v_mfma_f32_16x16x32_bf16 v[118:121], v[180:183], v[204:207], v[118:121]
	v_mfma_f32_16x16x32_bf16 v[114:117], v[188:191], v[204:207], v[114:117]
	v_mfma_f32_16x16x32_bf16 v[102:105], v[180:183], v[212:215], v[102:105]
	v_mfma_f32_16x16x32_bf16 v[98:101], v[188:191], v[212:215], v[98:101]
	v_mfma_f32_16x16x32_bf16 v[86:89], v[180:183], v[220:223], v[86:89]
	v_mfma_f32_16x16x32_bf16 v[82:85], v[188:191], v[220:223], v[82:85]
	s_barrier
	s_add_i32 s51, s41, s25
	v_lshl_add_u64 v[166:167], s[20:21], 0, v[150:151]
	s_mov_b32 m0, s51
	ds_read_b128 v[192:195], v175 offset:16384
	ds_read_b128 v[196:199], v175 offset:17408
	ds_read_b128 v[200:203], v175 offset:18432
	ds_read_b128 v[204:207], v175 offset:19456
	ds_read_b128 v[208:211], v175 offset:20480
	ds_read_b128 v[212:215], v175 offset:21504
	ds_read_b128 v[216:219], v175 offset:22528
	ds_read_b128 v[220:223], v175 offset:23552
	global_load_lds_dwordx4 v[166:167], off
	s_add_i32 m0, s51, 0x2000
	s_add_u32 s52, s20, 0x80000
	v_lshl_add_u64 v[224:225], s[20:21], 0, v[146:147]
	s_addc_u32 s53, s21, 0
	s_add_i32 s51, s42, s25
	global_load_lds_dwordx4 v[224:225], off
	v_lshl_add_u64 v[226:227], s[52:53], 0, v[150:151]
	s_mov_b32 m0, s51
	v_lshl_add_u64 v[228:229], s[22:23], 0, v[148:149]
	global_load_lds_dwordx4 v[226:227], off
	v_lshl_add_u64 v[226:227], s[52:53], 0, v[146:147]
	s_add_i32 m0, s51, 0x2000
	s_nop 0
	global_load_lds_dwordx4 v[226:227], off
	v_lshl_add_u64 v[226:227], s[22:23], 0, v[152:153]
	s_mov_b32 m0, s28
	s_nop 0
	global_load_lds_dwordx4 v[226:227], off
	s_mov_b32 m0, s29
	s_nop 0
	global_load_lds_dwordx4 v[228:229], off
	s_waitcnt vmcnt(8)
	s_waitcnt lgkmcnt(0)
	s_barrier
; #define PG8_STAGE(bufoff, gbase, voff) do { _Pragma("unroll") for (int _i = 0; _i < 2; ++_i) \
;         __builtin_amdgcn_global_load_lds((const unsigned*)((const char*)(gbase) + (voff)[_i]), (LAS unsigned*)(lds + (bufoff) + ldsw + _i * 8192), 16, 0, 0); } while (0)
; #define PG8_LDA(dst, b, h) do { _Pragma("unroll") for (int m = 0; m < 4; ++m) _Pragma("unroll") for (int k = 0; k < 2; ++k) dst[m][k] = *(const LAS bf16x8*)(lds + PG8_SA(b, h) + aoff + m * 2048 + k * 1024); } while (0)
; #define PG8_LDB(dst, b, h) do { _Pragma("unroll") for (int n = 0; n < 2; ++n) _Pragma("unroll") for (int k = 0; k < 2; ++k) dst[n][k] = *(const LAS bf16x8*)(lds + PG8_SB(b, h) + boff + n * 2048 + k * 1024); } while (0)
; #define PG8_MMA(ai, bj, At, Bt) do { __builtin_amdgcn_s_setprio(1); _Pragma("unroll") for (int m = 0; m < 4; ++m) _Pragma("unroll") for (int n = 0; n < 2; ++n) _Pragma("unroll") for (int k = 0; k < 2; ++k) \
;         acc[ai][bj][m][n] = __builtin_amdgcn_mfma_f32_16x16x32_bf16(Bt[n][k], At[m][k], acc[ai][bj][m][n], 0, 0, 0); __builtin_amdgcn_s_setprio(0); } while (0)
; #define PG8_WAIT_V(n) asm volatile("s_waitcnt vmcnt(" #n ")" ::: "memory")
; #define PG8_WAIT_L(n) asm volatile("s_waitcnt lgkmcnt(" #n ")" ::: "memory")
; #define PG8_BAR __builtin_amdgcn_s_barrier()
; #define PG8_SCHED __builtin_amdgcn_sched_barrier(0)
; template <class Epi, class Sched, bool ALIGN_EPI = false, bool SP2 = false>
; __device__ __forceinline__ void gemm_phase(LAS unsigned char* lds, const Gemm g, const Sched& S, const Epi& E) {
;     ...
;             PG8_WAIT_V(8); PG8_WAIT_L(0); PG8_BAR; PG8_MMA(1, 0, At, B0); PG8_MMA(1, 1, At, B1); PG8_BAR; PG8_SCHED;
;             PG8_LDB(B0, 1, 0); PG8_LDB(B1, 1, 1); PG8_SCHED; PG8_LDA(At, 1, 0); PG8_STAGE(PG8_SA(0, 1), a2 + hstep, voffA);
;             PG8_WAIT_V(8); PG8_WAIT_L(0); PG8_BAR; PG8_MMA(0, 0, At, B0); PG8_MMA(0, 1, At, B1); PG8_BAR; PG8_SCHED;
	v_mfma_f32_16x16x32_bf16 v[62:65], v[66:69], v[192:195], v[62:65]
	v_mfma_f32_16x16x32_bf16 v[58:61], v[74:77], v[192:195], v[58:61]
	v_mfma_f32_16x16x32_bf16 v[46:49], v[66:69], v[200:203], v[46:49]
	v_mfma_f32_16x16x32_bf16 v[42:45], v[74:77], v[200:203], v[42:45]
	v_mfma_f32_16x16x32_bf16 v[30:33], v[66:69], v[208:211], v[30:33]
	v_mfma_f32_16x16x32_bf16 v[26:29], v[74:77], v[208:211], v[26:29]
	v_mfma_f32_16x16x32_bf16 v[14:17], v[66:69], v[216:219], v[14:17]
	v_mfma_f32_16x16x32_bf16 v[10:13], v[74:77], v[216:219], v[10:13]
	v_mfma_f32_16x16x32_bf16 v[62:65], v[70:73], v[196:199], v[62:65]
	v_mfma_f32_16x16x32_bf16 v[58:61], v[78:81], v[196:199], v[58:61]
	v_mfma_f32_16x16x32_bf16 v[46:49], v[70:73], v[204:207], v[46:49]
	v_mfma_f32_16x16x32_bf16 v[42:45], v[78:81], v[204:207], v[42:45]
	v_mfma_f32_16x16x32_bf16 v[30:33], v[70:73], v[212:215], v[30:33]
	v_mfma_f32_16x16x32_bf16 v[26:29], v[78:81], v[212:215], v[26:29]
	v_mfma_f32_16x16x32_bf16 v[14:17], v[70:73], v[220:223], v[14:17]
	v_mfma_f32_16x16x32_bf16 v[10:13], v[78:81], v[220:223], v[10:13]
	v_mfma_f32_16x16x32_bf16 v[54:57], v[162:165], v[192:195], v[54:57]
	v_mfma_f32_16x16x32_bf16 v[50:53], v[184:187], v[192:195], v[50:53]
	v_mfma_f32_16x16x32_bf16 v[38:41], v[162:165], v[200:203], v[38:41]
	v_mfma_f32_16x16x32_bf16 v[34:37], v[184:187], v[200:203], v[34:37]
	v_mfma_f32_16x16x32_bf16 v[22:25], v[162:165], v[208:211], v[22:25]
	v_mfma_f32_16x16x32_bf16 v[18:21], v[184:187], v[208:211], v[18:21]
	v_mfma_f32_16x16x32_bf16 v[6:9], v[162:165], v[216:219], v[6:9]
	v_mfma_f32_16x16x32_bf16 v[2:5], v[184:187], v[216:219], v[2:5]
	v_mfma_f32_16x16x32_bf16 v[54:57], v[180:183], v[196:199], v[54:57]
	v_mfma_f32_16x16x32_bf16 v[50:53], v[188:191], v[196:199], v[50:53]
	v_mfma_f32_16x16x32_bf16 v[38:41], v[180:183], v[204:207], v[38:41]
	v_mfma_f32_16x16x32_bf16 v[34:37], v[188:191], v[204:207], v[34:37]
	v_mfma_f32_16x16x32_bf16 v[22:25], v[180:183], v[212:215], v[22:25]
	v_mfma_f32_16x16x32_bf16 v[18:21], v[188:191], v[212:215], v[18:21]
	v_mfma_f32_16x16x32_bf16 v[6:9], v[180:183], v[220:223], v[6:9]
	v_mfma_f32_16x16x32_bf16 v[2:5], v[188:191], v[220:223], v[2:5]
	s_barrier
	s_add_i32 s51, 0, 0x18000
	s_add_i32 s52, 0, 0x1c000
	v_add_u32_e32 v78, s51, v169
	v_add_u32_e32 v168, s52, v169
	ds_read_b128 v[66:69], v78
	ds_read_b128 v[70:73], v78 offset:1024
	ds_read_b128 v[74:77], v78 offset:2048
	ds_read_b128 v[78:81], v78 offset:3072
	ds_read_b128 v[162:165], v168
	ds_read_b128 v[180:183], v168 offset:1024
	ds_read_b128 v[184:187], v168 offset:2048
	ds_read_b128 v[188:191], v168 offset:3072
	s_add_u32 s22, s22, 0x80000
	s_addc_u32 s23, s23, 0
	s_mov_b32 m0, s30
	v_lshl_add_u64 v[230:231], s[22:23], 0, v[152:153]
	ds_read_b128 v[192:195], v175 offset:32768
	ds_read_b128 v[196:199], v175 offset:33792
	ds_read_b128 v[200:203], v175 offset:34816
	ds_read_b128 v[204:207], v175 offset:35840
	ds_read_b128 v[208:211], v175 offset:36864
	ds_read_b128 v[212:215], v175 offset:37888
	ds_read_b128 v[216:219], v175 offset:38912
	ds_read_b128 v[220:223], v175 offset:39936
	global_load_lds_dwordx4 v[230:231], off
	v_lshl_add_u64 v[230:231], s[22:23], 0, v[148:149]
	s_mov_b32 m0, s31
	s_nop 0
	global_load_lds_dwordx4 v[230:231], off
	s_waitcnt vmcnt(8)
	s_waitcnt lgkmcnt(0)
	s_barrier
	v_mfma_f32_16x16x32_bf16 v[142:145], v[66:69], v[192:195], v[142:145]
	v_mfma_f32_16x16x32_bf16 v[138:141], v[74:77], v[192:195], v[138:141]
	v_mfma_f32_16x16x32_bf16 v[126:129], v[66:69], v[200:203], v[126:129]
	v_mfma_f32_16x16x32_bf16 v[122:125], v[74:77], v[200:203], v[122:125]
	v_mfma_f32_16x16x32_bf16 v[110:113], v[66:69], v[208:211], v[110:113]
	v_mfma_f32_16x16x32_bf16 v[106:109], v[74:77], v[208:211], v[106:109]
	v_mfma_f32_16x16x32_bf16 v[94:97], v[66:69], v[216:219], v[94:97]
	v_mfma_f32_16x16x32_bf16 v[90:93], v[74:77], v[216:219], v[90:93]
	v_mfma_f32_16x16x32_bf16 v[142:145], v[70:73], v[196:199], v[142:145]
	v_mfma_f32_16x16x32_bf16 v[138:141], v[78:81], v[196:199], v[138:141]
	v_mfma_f32_16x16x32_bf16 v[126:129], v[70:73], v[204:207], v[126:129]
	v_mfma_f32_16x16x32_bf16 v[122:125], v[78:81], v[204:207], v[122:125]
	v_mfma_f32_16x16x32_bf16 v[110:113], v[70:73], v[212:215], v[110:113]
	v_mfma_f32_16x16x32_bf16 v[106:109], v[78:81], v[212:215], v[106:109]
	v_mfma_f32_16x16x32_bf16 v[94:97], v[70:73], v[220:223], v[94:97]
	v_mfma_f32_16x16x32_bf16 v[90:93], v[78:81], v[220:223], v[90:93]
	v_mfma_f32_16x16x32_bf16 v[134:137], v[162:165], v[192:195], v[134:137]
	v_mfma_f32_16x16x32_bf16 v[130:133], v[184:187], v[192:195], v[130:133]
	v_mfma_f32_16x16x32_bf16 v[118:121], v[162:165], v[200:203], v[118:121]
	v_mfma_f32_16x16x32_bf16 v[114:117], v[184:187], v[200:203], v[114:117]
	v_mfma_f32_16x16x32_bf16 v[102:105], v[162:165], v[208:211], v[102:105]
	v_mfma_f32_16x16x32_bf16 v[98:101], v[184:187], v[208:211], v[98:101]
	v_mfma_f32_16x16x32_bf16 v[86:89], v[162:165], v[216:219], v[86:89]
	v_mfma_f32_16x16x32_bf16 v[82:85], v[184:187], v[216:219], v[82:85]
	v_mfma_f32_16x16x32_bf16 v[134:137], v[180:183], v[196:199], v[134:137]
	v_mfma_f32_16x16x32_bf16 v[130:133], v[188:191], v[196:199], v[130:133]
	v_mfma_f32_16x16x32_bf16 v[118:121], v[180:183], v[204:207], v[118:121]
	v_mfma_f32_16x16x32_bf16 v[114:117], v[188:191], v[204:207], v[114:117]
	v_mfma_f32_16x16x32_bf16 v[102:105], v[180:183], v[212:215], v[102:105]
	v_mfma_f32_16x16x32_bf16 v[98:101], v[188:191], v[212:215], v[98:101]
	v_mfma_f32_16x16x32_bf16 v[86:89], v[180:183], v[220:223], v[86:89]
	v_mfma_f32_16x16x32_bf16 v[82:85], v[188:191], v[220:223], v[82:85]
	s_barrier
; #define PG8_STAGE(bufoff, gbase, voff) do { _Pragma("unroll") for (int _i = 0; _i < 2; ++_i) \
;         __builtin_amdgcn_global_load_lds((const unsigned*)((const char*)(gbase) + (voff)[_i]), (LAS unsigned*)(lds + (bufoff) + ldsw + _i * 8192), 16, 0, 0); } while (0)
; #define PG8_WAIT_V(n) asm volatile("s_waitcnt vmcnt(" #n ")" ::: "memory")
; #define PG8_WAIT_L(n) asm volatile("s_waitcnt lgkmcnt(" #n ")" ::: "memory")
; template <class Epi, class Sched, bool ALIGN_EPI = false, bool SP2 = false>
; __device__ __forceinline__ void gemm_phase(LAS unsigned char* lds, const Gemm g, const Sched& S, const Epi& E) {
;     ...
;             PG8_LDA(At, 1, 1); PG8_STAGE(PG8_SB(1, 0), b3, voffB); PG8_STAGE(PG8_SB(1, 1), b3 + hstepB, voffB); PG8_STAGE(PG8_SA(1, 0), a3, voffA);
;             PG8_WAIT_V(8); PG8_WAIT_L(0); PG8_BAR; PG8_MMA(1, 0, At, B0); PG8_MMA(1, 1, At, B1); PG8_BAR; PG8_SCHED;
;             } else {
;             PG8_LDB(B0, 0, 0); PG8_SCHED; PG8_LDA(At, 0, 0); PG8_STAGE(PG8_SA(1, 1), a1 + hstep, voffA);
;             PG8_WAIT_L(8); PG8_BAR; PG8_WAIT_L(0); PG8_MMA(0, 0, At, B0); PG8_BAR; PG8_SCHED;
;             PG8_LDB(B1, 0, 1); PG8_STAGE(PG8_SB(0, 0), b2, voffB);
;             PG8_BAR; PG8_WAIT_L(0); PG8_MMA(0, 1, At, B1); PG8_BAR;
;             PG8_LDA(At, 0, 1); PG8_STAGE(PG8_SA(0, 0), a2, voffA);
;             PG8_BAR; PG8_WAIT_L(0); PG8_MMA(1, 0, At, B0); PG8_BAR; PG8_SCHED;
;             PG8_STAGE(PG8_SB(0, 1), b2 + hstepB, voffB);
;             PG8_WAIT_V(6); PG8_BAR; PG8_MMA(1, 1, At, B1); PG8_BAR;
;             PG8_LDB(B0, 1, 0); PG8_SCHED; PG8_LDA(At, 1, 0); PG8_STAGE(PG8_SA(0, 1), a2 + hstep, voffA);
;             PG8_WAIT_L(8); PG8_BAR; PG8_WAIT_L(0); PG8_MMA(0, 0, At, B0); PG8_BAR; PG8_SCHED;
;             PG8_LDB(B1, 1, 1); PG8_STAGE(PG8_SB(1, 0), b3, voffB);
;             PG8_BAR; PG8_WAIT_L(0); PG8_MMA(0, 1, At, B1); PG8_BAR;
;             PG8_LDA(At, 1, 1); PG8_STAGE(PG8_SA(1, 0), a3, voffA);
;             PG8_BAR; PG8_WAIT_L(0); PG8_MMA(1, 0, At, B0); PG8_BAR; PG8_SCHED;
;             PG8_STAGE(PG8_SB(1, 1), b3 + hstepB, voffB);
;             PG8_WAIT_V(6); PG8_BAR; PG8_MMA(1, 1, At, B1); PG8_BAR;
;             }
;         }
;         if constexpr (ALIGN_EPI) { if (wr == 0) PG8_BAR; }
;         if constexpr (!Epi::AFTER_DRAIN) { E(acc, cur, wr, wc, fr, fq); S.done(cur); }
;         if (!has_next) break;
	s_add_i32 s22, s51, s25
	v_lshl_add_u64 v[166:167], v[166:167], 0, s[6:7]
	s_mov_b32 m0, s22
	ds_read_b128 v[192:195], v175 offset:49152
	ds_read_b128 v[196:199], v175 offset:50176
	ds_read_b128 v[200:203], v175 offset:51200
	ds_read_b128 v[204:207], v175 offset:52224
	ds_read_b128 v[208:211], v175 offset:53248
	ds_read_b128 v[212:215], v175 offset:54272
	ds_read_b128 v[216:219], v175 offset:55296
	ds_read_b128 v[220:223], v175 offset:56320
	global_load_lds_dwordx4 v[166:167], off
	s_add_i32 m0, s22, 0x2000
	s_add_u32 s20, s20, 0x80080
	v_lshl_add_u64 v[166:167], v[224:225], 0, s[6:7]
	s_addc_u32 s21, s21, 0
	s_add_i32 s22, s52, s25
	global_load_lds_dwordx4 v[166:167], off
	v_lshl_add_u64 v[166:167], s[20:21], 0, v[150:151]
	s_mov_b32 m0, s22
	s_nop 0
	global_load_lds_dwordx4 v[166:167], off
	v_lshl_add_u64 v[166:167], s[20:21], 0, v[146:147]
	s_add_i32 m0, s22, 0x2000
	s_nop 0
	global_load_lds_dwordx4 v[166:167], off
	v_lshl_add_u64 v[166:167], v[226:227], 0, s[6:7]
	s_mov_b32 m0, s39
	s_nop 0
	global_load_lds_dwordx4 v[166:167], off
	v_lshl_add_u64 v[166:167], v[228:229], 0, s[6:7]
	s_mov_b32 m0, s40
	s_nop 0
	global_load_lds_dwordx4 v[166:167], off
	s_waitcnt vmcnt(8)
	s_waitcnt lgkmcnt(0)
	s_barrier
	v_mfma_f32_16x16x32_bf16 v[62:65], v[66:69], v[192:195], v[62:65]
	v_mfma_f32_16x16x32_bf16 v[58:61], v[74:77], v[192:195], v[58:61]
	v_mfma_f32_16x16x32_bf16 v[46:49], v[66:69], v[200:203], v[46:49]
	v_mfma_f32_16x16x32_bf16 v[42:45], v[74:77], v[200:203], v[42:45]
	v_mfma_f32_16x16x32_bf16 v[30:33], v[66:69], v[208:211], v[30:33]
	v_mfma_f32_16x16x32_bf16 v[26:29], v[74:77], v[208:211], v[26:29]
	v_mfma_f32_16x16x32_bf16 v[14:17], v[66:69], v[216:219], v[14:17]
	v_mfma_f32_16x16x32_bf16 v[10:13], v[74:77], v[216:219], v[10:13]
	v_mfma_f32_16x16x32_bf16 v[62:65], v[70:73], v[196:199], v[62:65]
	v_mfma_f32_16x16x32_bf16 v[58:61], v[78:81], v[196:199], v[58:61]
	v_mfma_f32_16x16x32_bf16 v[46:49], v[70:73], v[204:207], v[46:49]
	v_mfma_f32_16x16x32_bf16 v[42:45], v[78:81], v[204:207], v[42:45]
	v_mfma_f32_16x16x32_bf16 v[30:33], v[70:73], v[212:215], v[30:33]
	v_mfma_f32_16x16x32_bf16 v[26:29], v[78:81], v[212:215], v[26:29]
	v_mfma_f32_16x16x32_bf16 v[14:17], v[70:73], v[220:223], v[14:17]
	v_mfma_f32_16x16x32_bf16 v[10:13], v[78:81], v[220:223], v[10:13]
	v_mfma_f32_16x16x32_bf16 v[54:57], v[162:165], v[192:195], v[54:57]
	v_mfma_f32_16x16x32_bf16 v[50:53], v[184:187], v[192:195], v[50:53]
	v_mfma_f32_16x16x32_bf16 v[38:41], v[162:165], v[200:203], v[38:41]
	v_mfma_f32_16x16x32_bf16 v[34:37], v[184:187], v[200:203], v[34:37]
	v_mfma_f32_16x16x32_bf16 v[22:25], v[162:165], v[208:211], v[22:25]
	v_mfma_f32_16x16x32_bf16 v[18:21], v[184:187], v[208:211], v[18:21]
	v_mfma_f32_16x16x32_bf16 v[6:9], v[162:165], v[216:219], v[6:9]
	v_mfma_f32_16x16x32_bf16 v[2:5], v[184:187], v[216:219], v[2:5]
	v_mfma_f32_16x16x32_bf16 v[54:57], v[180:183], v[196:199], v[54:57]
	v_mfma_f32_16x16x32_bf16 v[50:53], v[188:191], v[196:199], v[50:53]
	v_mfma_f32_16x16x32_bf16 v[38:41], v[180:183], v[204:207], v[38:41]
	v_mfma_f32_16x16x32_bf16 v[34:37], v[188:191], v[204:207], v[34:37]
	v_mfma_f32_16x16x32_bf16 v[22:25], v[180:183], v[212:215], v[22:25]
	v_mfma_f32_16x16x32_bf16 v[18:21], v[188:191], v[212:215], v[18:21]
	v_mfma_f32_16x16x32_bf16 v[6:9], v[180:183], v[220:223], v[6:9]
	v_mfma_f32_16x16x32_bf16 v[2:5], v[188:191], v[220:223], v[2:5]
	s_barrier
	s_add_i32 s50, s50, 2
	s_add_u32 s48, s48, 0x100
	s_addc_u32 s49, s49, 0
	s_add_u32 s18, s18, 0x100
	s_addc_u32 s19, s19, 0
	s_cmp_lt_u32 s50, 30
	s_cbranch_scc1 .LBB0_2916
	s_setprio 0
	s_andn2_b64 vcc, exec, s[8:9]
	s_cbranch_vccnz .LBB0_2919
	s_barrier

; #define PG8_STAGE(bufoff, gbase, voff) do { _Pragma("unroll") for (int _i = 0; _i < 2; ++_i) \
;         __builtin_amdgcn_global_load_lds((const unsigned*)((const char*)(gbase) + (voff)[_i]), (LAS unsigned*)(lds + (bufoff) + ldsw + _i * 8192), 16, 0, 0); } while (0)
; #define PG8_LDA(dst, b, h) do { _Pragma("unroll") for (int m = 0; m < 4; ++m) _Pragma("unroll") for (int k = 0; k < 2; ++k) dst[m][k] = *(const LAS bf16x8*)(lds + PG8_SA(b, h) + aoff + m * 2048 + k * 1024); } while (0)
; #define PG8_LDB(dst, b, h) do { _Pragma("unroll") for (int n = 0; n < 2; ++n) _Pragma("unroll") for (int k = 0; k < 2; ++k) dst[n][k] = *(const LAS bf16x8*)(lds + PG8_SB(b, h) + boff + n * 2048 + k * 1024); } while (0)
; #define PG8_MMA(ai, bj, At, Bt) do { __builtin_amdgcn_s_setprio(1); _Pragma("unroll") for (int m = 0; m < 4; ++m) _Pragma("unroll") for (int n = 0; n < 2; ++n) _Pragma("unroll") for (int k = 0; k < 2; ++k) \
;         acc[ai][bj][m][n] = __builtin_amdgcn_mfma_f32_16x16x32_bf16(Bt[n][k], At[m][k], acc[ai][bj][m][n], 0, 0, 0); __builtin_amdgcn_s_setprio(0); } while (0)
; #define PG8_WAIT_V(n) asm volatile("s_waitcnt vmcnt(" #n ")" ::: "memory")
; #define PG8_WAIT_L(n) asm volatile("s_waitcnt lgkmcnt(" #n ")" ::: "memory")
; #define PG8_BAR __builtin_amdgcn_s_barrier()
; #define PG8_SCHED __builtin_amdgcn_sched_barrier(0)
; template <class Epi, class Sched, bool ALIGN_EPI = false, bool SP2 = false>
; __device__ __forceinline__ void gemm_phase(LAS unsigned char* lds, const Gemm g, const Sched& S, const Epi& E) {
;     ...
;             if constexpr (SP2) {
;             PG8_LDB(B0, 0, 0); PG8_LDB(B1, 0, 1); PG8_SCHED; PG8_LDA(At, 0, 0); PG8_STAGE(PG8_SA(1, 1), a1 + hstep, voffA);
;             PG8_WAIT_V(8); PG8_WAIT_L(0); PG8_BAR; PG8_MMA(0, 0, At, B0); PG8_MMA(0, 1, At, B1); PG8_BAR; PG8_SCHED;
;             PG8_LDA(At, 0, 1); PG8_STAGE(PG8_SB(0, 0), b2, voffB); PG8_STAGE(PG8_SB(0, 1), b2 + hstepB, voffB); PG8_STAGE(PG8_SA(0, 0), a2, voffA);
;             PG8_WAIT_V(8); PG8_WAIT_L(0); PG8_BAR; PG8_MMA(1, 0, At, B0); PG8_MMA(1, 1, At, B1); PG8_BAR; PG8_SCHED;
.Lprio_3002:
	ds_read_b128 v[152:155], v147
	ds_read_b128 v[156:159], v147 offset:1024
	ds_read_b128 v[160:163], v147 offset:2048
	ds_read_b128 v[164:167], v147 offset:3072
	ds_read_b128 v[168:171], v148
	ds_read_b128 v[172:175], v148 offset:1024
	ds_read_b128 v[176:179], v148 offset:2048
	ds_read_b128 v[180:183], v148 offset:3072
	s_add_u32 s16, s14, 0x100
	s_addc_u32 s17, s15, 0
	s_cmpk_eq_i32 s40, 0x54
	s_cselect_b32 s21, s11, s17
	s_cselect_b32 s20, s10, s16
	s_cselect_b32 s19, s3, s39
	s_cselect_b32 s18, s2, s13
	v_lshl_add_u64 v[216:217], s[14:15], 0, v[138:139]
	s_add_i32 m0, s24, 0xc000
	ds_read_b128 v[184:187], v149
	ds_read_b128 v[188:191], v149 offset:1024
	ds_read_b128 v[192:195], v149 offset:2048
	ds_read_b128 v[196:199], v149 offset:3072
	ds_read_b128 v[200:203], v149 offset:4096
	ds_read_b128 v[204:207], v149 offset:5120
	ds_read_b128 v[208:211], v149 offset:6144
	ds_read_b128 v[212:215], v149 offset:7168
	global_load_lds_dwordx4 v[216:217], off
	v_lshl_add_u64 v[216:217], s[14:15], 0, v[136:137]
	s_add_i32 m0, s24, 0xe000
	s_nop 0
	global_load_lds_dwordx4 v[216:217], off
	s_waitcnt lgkmcnt(0)
	s_barrier
	v_mfma_f32_16x16x32_bf16 v[124:127], v[152:155], v[184:187], 0
	v_mfma_f32_16x16x32_bf16 v[120:123], v[160:163], v[184:187], 0
	v_mfma_f32_16x16x32_bf16 v[112:115], v[152:155], v[192:195], 0
	v_mfma_f32_16x16x32_bf16 v[104:107], v[160:163], v[192:195], 0
	v_mfma_f32_16x16x32_bf16 v[92:95], v[152:155], v[200:203], 0
	v_mfma_f32_16x16x32_bf16 v[88:91], v[160:163], v[200:203], 0
	v_mfma_f32_16x16x32_bf16 v[76:79], v[152:155], v[208:211], 0
	v_mfma_f32_16x16x32_bf16 v[72:75], v[160:163], v[208:211], 0
	v_mfma_f32_16x16x32_bf16 v[124:127], v[156:159], v[188:191], v[124:127]
	v_mfma_f32_16x16x32_bf16 v[120:123], v[164:167], v[188:191], v[120:123]
	v_mfma_f32_16x16x32_bf16 v[112:115], v[156:159], v[196:199], v[112:115]
	v_mfma_f32_16x16x32_bf16 v[104:107], v[164:167], v[196:199], v[104:107]
	v_mfma_f32_16x16x32_bf16 v[92:95], v[156:159], v[204:207], v[92:95]
	v_mfma_f32_16x16x32_bf16 v[88:91], v[164:167], v[204:207], v[88:91]
	v_mfma_f32_16x16x32_bf16 v[76:79], v[156:159], v[212:215], v[76:79]
	v_mfma_f32_16x16x32_bf16 v[72:75], v[164:167], v[212:215], v[72:75]
	v_mfma_f32_16x16x32_bf16 v[116:119], v[168:171], v[184:187], 0
	v_mfma_f32_16x16x32_bf16 v[108:111], v[176:179], v[184:187], 0
	v_mfma_f32_16x16x32_bf16 v[100:103], v[168:171], v[192:195], 0
	v_mfma_f32_16x16x32_bf16 v[96:99], v[176:179], v[192:195], 0
	v_mfma_f32_16x16x32_bf16 v[84:87], v[168:171], v[200:203], 0
	v_mfma_f32_16x16x32_bf16 v[80:83], v[176:179], v[200:203], 0
	v_mfma_f32_16x16x32_bf16 v[68:71], v[168:171], v[208:211], 0
	v_mfma_f32_16x16x32_bf16 v[64:67], v[176:179], v[208:211], 0
	v_mfma_f32_16x16x32_bf16 v[116:119], v[172:175], v[188:191], v[116:119]
	v_mfma_f32_16x16x32_bf16 v[108:111], v[180:183], v[188:191], v[108:111]
	v_mfma_f32_16x16x32_bf16 v[100:103], v[172:175], v[196:199], v[100:103]
	v_mfma_f32_16x16x32_bf16 v[96:99], v[180:183], v[196:199], v[96:99]
	v_mfma_f32_16x16x32_bf16 v[84:87], v[172:175], v[204:207], v[84:87]
	v_mfma_f32_16x16x32_bf16 v[80:83], v[180:183], v[204:207], v[80:83]
	v_mfma_f32_16x16x32_bf16 v[68:71], v[172:175], v[212:215], v[68:71]
	v_mfma_f32_16x16x32_bf16 v[64:67], v[180:183], v[212:215], v[64:67]
	s_barrier
	s_add_i32 s14, s34, s23
	v_lshl_add_u64 v[216:217], s[18:19], 0, v[130:131]
	s_mov_b32 m0, s14
	ds_read_b128 v[184:187], v149 offset:16384
	ds_read_b128 v[188:191], v149 offset:17408
	ds_read_b128 v[192:195], v149 offset:18432
	ds_read_b128 v[196:199], v149 offset:19456
	ds_read_b128 v[200:203], v149 offset:20480
	ds_read_b128 v[204:207], v149 offset:21504
	ds_read_b128 v[208:211], v149 offset:22528
	ds_read_b128 v[212:215], v149 offset:23552
	global_load_lds_dwordx4 v[216:217], off
	s_add_i32 m0, s14, 0x2000
	s_add_u32 s14, s18, 0x58000
	v_lshl_add_u64 v[218:219], s[18:19], 0, v[134:135]
	s_addc_u32 s15, s19, 0
	s_add_i32 s41, s35, s23
	global_load_lds_dwordx4 v[218:219], off
	v_lshl_add_u64 v[220:221], s[14:15], 0, v[130:131]
	s_mov_b32 m0, s41
	v_lshl_add_u64 v[222:223], s[20:21], 0, v[132:133]
	global_load_lds_dwordx4 v[220:221], off
	v_lshl_add_u64 v[220:221], s[14:15], 0, v[134:135]
	s_add_i32 m0, s41, 0x2000
	s_nop 0
	global_load_lds_dwordx4 v[220:221], off
	v_lshl_add_u64 v[220:221], s[20:21], 0, v[128:129]
	s_mov_b32 m0, s24
	s_nop 0
	global_load_lds_dwordx4 v[220:221], off
	s_mov_b32 m0, s25
	s_nop 0
	global_load_lds_dwordx4 v[222:223], off
	s_waitcnt lgkmcnt(0)
	s_barrier
	v_mfma_f32_16x16x32_bf16 v[60:63], v[152:155], v[184:187], 0
	v_mfma_f32_16x16x32_bf16 v[56:59], v[160:163], v[184:187], 0
	v_mfma_f32_16x16x32_bf16 v[44:47], v[152:155], v[192:195], 0
	v_mfma_f32_16x16x32_bf16 v[40:43], v[160:163], v[192:195], 0
	v_mfma_f32_16x16x32_bf16 v[28:31], v[152:155], v[200:203], 0
	v_mfma_f32_16x16x32_bf16 v[24:27], v[160:163], v[200:203], 0
	v_mfma_f32_16x16x32_bf16 v[12:15], v[152:155], v[208:211], 0
	v_mfma_f32_16x16x32_bf16 v[8:11], v[160:163], v[208:211], 0
	v_mfma_f32_16x16x32_bf16 v[60:63], v[156:159], v[188:191], v[60:63]
	v_mfma_f32_16x16x32_bf16 v[56:59], v[164:167], v[188:191], v[56:59]
	v_mfma_f32_16x16x32_bf16 v[44:47], v[156:159], v[196:199], v[44:47]
	v_mfma_f32_16x16x32_bf16 v[40:43], v[164:167], v[196:199], v[40:43]
	v_mfma_f32_16x16x32_bf16 v[28:31], v[156:159], v[204:207], v[28:31]
	v_mfma_f32_16x16x32_bf16 v[24:27], v[164:167], v[204:207], v[24:27]
	v_mfma_f32_16x16x32_bf16 v[12:15], v[156:159], v[212:215], v[12:15]
	v_mfma_f32_16x16x32_bf16 v[8:11], v[164:167], v[212:215], v[8:11]
	v_mfma_f32_16x16x32_bf16 v[52:55], v[168:171], v[184:187], 0
	v_mfma_f32_16x16x32_bf16 v[48:51], v[176:179], v[184:187], 0
	v_mfma_f32_16x16x32_bf16 v[36:39], v[168:171], v[192:195], 0
	v_mfma_f32_16x16x32_bf16 v[32:35], v[176:179], v[192:195], 0
	v_mfma_f32_16x16x32_bf16 v[20:23], v[168:171], v[200:203], 0
	v_mfma_f32_16x16x32_bf16 v[16:19], v[176:179], v[200:203], 0
	v_mfma_f32_16x16x32_bf16 v[4:7], v[168:171], v[208:211], 0
	v_mfma_f32_16x16x32_bf16 v[0:3], v[176:179], v[208:211], 0
	v_mfma_f32_16x16x32_bf16 v[52:55], v[172:175], v[188:191], v[52:55]
	v_mfma_f32_16x16x32_bf16 v[48:51], v[180:183], v[188:191], v[48:51]
	v_mfma_f32_16x16x32_bf16 v[36:39], v[172:175], v[196:199], v[36:39]
	v_mfma_f32_16x16x32_bf16 v[32:35], v[180:183], v[196:199], v[32:35]
	v_mfma_f32_16x16x32_bf16 v[20:23], v[172:175], v[204:207], v[20:23]
	v_mfma_f32_16x16x32_bf16 v[16:19], v[180:183], v[204:207], v[16:19]
	v_mfma_f32_16x16x32_bf16 v[4:7], v[172:175], v[212:215], v[4:7]
	v_mfma_f32_16x16x32_bf16 v[0:3], v[180:183], v[212:215], v[0:3]
	s_barrier
; #define PG8_STAGE(bufoff, gbase, voff) do { _Pragma("unroll") for (int _i = 0; _i < 2; ++_i) \
;         __builtin_amdgcn_global_load_lds((const unsigned*)((const char*)(gbase) + (voff)[_i]), (LAS unsigned*)(lds + (bufoff) + ldsw + _i * 8192), 16, 0, 0); } while (0)
; #define PG8_LDA(dst, b, h) do { _Pragma("unroll") for (int m = 0; m < 4; ++m) _Pragma("unroll") for (int k = 0; k < 2; ++k) dst[m][k] = *(const LAS bf16x8*)(lds + PG8_SA(b, h) + aoff + m * 2048 + k * 1024); } while (0)
; #define PG8_LDB(dst, b, h) do { _Pragma("unroll") for (int n = 0; n < 2; ++n) _Pragma("unroll") for (int k = 0; k < 2; ++k) dst[n][k] = *(const LAS bf16x8*)(lds + PG8_SB(b, h) + boff + n * 2048 + k * 1024); } while (0)
; #define PG8_MMA(ai, bj, At, Bt) do { __builtin_amdgcn_s_setprio(1); _Pragma("unroll") for (int m = 0; m < 4; ++m) _Pragma("unroll") for (int n = 0; n < 2; ++n) _Pragma("unroll") for (int k = 0; k < 2; ++k) \
;         acc[ai][bj][m][n] = __builtin_amdgcn_mfma_f32_16x16x32_bf16(Bt[n][k], At[m][k], acc[ai][bj][m][n], 0, 0, 0); __builtin_amdgcn_s_setprio(0); } while (0)
; #define PG8_WAIT_V(n) asm volatile("s_waitcnt vmcnt(" #n ")" ::: "memory")
; #define PG8_WAIT_L(n) asm volatile("s_waitcnt lgkmcnt(" #n ")" ::: "memory")
; #define PG8_BAR __builtin_amdgcn_s_barrier()
; #define PG8_SCHED __builtin_amdgcn_sched_barrier(0)
; template <class Epi, class Sched, bool ALIGN_EPI = false, bool SP2 = false>
; __device__ __forceinline__ void gemm_phase(LAS unsigned char* lds, const Gemm g, const Sched& S, const Epi& E) {
;     ...
;             PG8_LDB(B0, 1, 0); PG8_LDB(B1, 1, 1); PG8_SCHED; PG8_LDA(At, 1, 0); PG8_STAGE(PG8_SA(0, 1), a2 + hstep, voffA);
;             PG8_WAIT_V(8); PG8_WAIT_L(0); PG8_BAR; PG8_MMA(0, 0, At, B0); PG8_MMA(0, 1, At, B1); PG8_BAR; PG8_SCHED;
;             PG8_LDA(At, 1, 1); PG8_STAGE(PG8_SB(1, 0), b3, voffB); PG8_STAGE(PG8_SB(1, 1), b3 + hstepB, voffB); PG8_STAGE(PG8_SA(1, 0), a3, voffA);
;             PG8_WAIT_V(8); PG8_WAIT_L(0); PG8_BAR; PG8_MMA(1, 0, At, B0); PG8_MMA(1, 1, At, B1); PG8_BAR; PG8_SCHED;
	s_add_i32 s41, 0, 0x18000
	s_add_i32 s42, 0, 0x1c000
	v_add_u32_e32 v164, s41, v144
	v_add_u32_e32 v180, s42, v144
	ds_read_b128 v[152:155], v164
	ds_read_b128 v[156:159], v164 offset:1024
	ds_read_b128 v[160:163], v164 offset:2048
	ds_read_b128 v[164:167], v164 offset:3072
	ds_read_b128 v[168:171], v180
	ds_read_b128 v[172:175], v180 offset:1024
	ds_read_b128 v[176:179], v180 offset:2048
	ds_read_b128 v[180:183], v180 offset:3072
	s_add_u32 s14, s20, 0x160000
	s_addc_u32 s15, s21, 0
	s_mov_b32 m0, s26
	v_lshl_add_u64 v[224:225], s[14:15], 0, v[128:129]
	ds_read_b128 v[184:187], v149 offset:32768
	ds_read_b128 v[188:191], v149 offset:33792
	ds_read_b128 v[192:195], v149 offset:34816
	ds_read_b128 v[196:199], v149 offset:35840
	ds_read_b128 v[200:203], v149 offset:36864
	ds_read_b128 v[204:207], v149 offset:37888
	ds_read_b128 v[208:211], v149 offset:38912
	ds_read_b128 v[212:215], v149 offset:39936
	global_load_lds_dwordx4 v[224:225], off
	v_lshl_add_u64 v[224:225], s[14:15], 0, v[132:133]
	s_mov_b32 m0, s27
	s_nop 0
	global_load_lds_dwordx4 v[224:225], off
	s_waitcnt vmcnt(8)
	s_waitcnt lgkmcnt(0)
	s_barrier
	v_mfma_f32_16x16x32_bf16 v[124:127], v[152:155], v[184:187], v[124:127]
	v_mfma_f32_16x16x32_bf16 v[120:123], v[160:163], v[184:187], v[120:123]
	v_mfma_f32_16x16x32_bf16 v[112:115], v[152:155], v[192:195], v[112:115]
	v_mfma_f32_16x16x32_bf16 v[104:107], v[160:163], v[192:195], v[104:107]
	v_mfma_f32_16x16x32_bf16 v[92:95], v[152:155], v[200:203], v[92:95]
	v_mfma_f32_16x16x32_bf16 v[88:91], v[160:163], v[200:203], v[88:91]
	v_mfma_f32_16x16x32_bf16 v[76:79], v[152:155], v[208:211], v[76:79]
	v_mfma_f32_16x16x32_bf16 v[72:75], v[160:163], v[208:211], v[72:75]
	v_mfma_f32_16x16x32_bf16 v[124:127], v[156:159], v[188:191], v[124:127]
	v_mfma_f32_16x16x32_bf16 v[120:123], v[164:167], v[188:191], v[120:123]
	v_mfma_f32_16x16x32_bf16 v[112:115], v[156:159], v[196:199], v[112:115]
	v_mfma_f32_16x16x32_bf16 v[104:107], v[164:167], v[196:199], v[104:107]
	v_mfma_f32_16x16x32_bf16 v[92:95], v[156:159], v[204:207], v[92:95]
	v_mfma_f32_16x16x32_bf16 v[88:91], v[164:167], v[204:207], v[88:91]
	v_mfma_f32_16x16x32_bf16 v[76:79], v[156:159], v[212:215], v[76:79]
	v_mfma_f32_16x16x32_bf16 v[72:75], v[164:167], v[212:215], v[72:75]
	v_mfma_f32_16x16x32_bf16 v[116:119], v[168:171], v[184:187], v[116:119]
	v_mfma_f32_16x16x32_bf16 v[108:111], v[176:179], v[184:187], v[108:111]
	v_mfma_f32_16x16x32_bf16 v[100:103], v[168:171], v[192:195], v[100:103]
	v_mfma_f32_16x16x32_bf16 v[96:99], v[176:179], v[192:195], v[96:99]
	v_mfma_f32_16x16x32_bf16 v[84:87], v[168:171], v[200:203], v[84:87]
	v_mfma_f32_16x16x32_bf16 v[80:83], v[176:179], v[200:203], v[80:83]
	v_mfma_f32_16x16x32_bf16 v[68:71], v[168:171], v[208:211], v[68:71]
	v_mfma_f32_16x16x32_bf16 v[64:67], v[176:179], v[208:211], v[64:67]
	v_mfma_f32_16x16x32_bf16 v[116:119], v[172:175], v[188:191], v[116:119]
	v_mfma_f32_16x16x32_bf16 v[108:111], v[180:183], v[188:191], v[108:111]
	v_mfma_f32_16x16x32_bf16 v[100:103], v[172:175], v[196:199], v[100:103]
	v_mfma_f32_16x16x32_bf16 v[96:99], v[180:183], v[196:199], v[96:99]
	v_mfma_f32_16x16x32_bf16 v[84:87], v[172:175], v[204:207], v[84:87]
	v_mfma_f32_16x16x32_bf16 v[80:83], v[180:183], v[204:207], v[80:83]
	v_mfma_f32_16x16x32_bf16 v[68:71], v[172:175], v[212:215], v[68:71]
	v_mfma_f32_16x16x32_bf16 v[64:67], v[180:183], v[212:215], v[64:67]
	s_barrier
	s_add_i32 s14, s41, s23
	v_lshl_add_u64 v[216:217], v[216:217], 0, s[6:7]
	s_mov_b32 m0, s14
	ds_read_b128 v[184:187], v149 offset:49152
	ds_read_b128 v[188:191], v149 offset:50176
	ds_read_b128 v[192:195], v149 offset:51200
	ds_read_b128 v[196:199], v149 offset:52224
	ds_read_b128 v[200:203], v149 offset:53248
	ds_read_b128 v[204:207], v149 offset:54272
	ds_read_b128 v[208:211], v149 offset:55296
	ds_read_b128 v[212:215], v149 offset:56320
	global_load_lds_dwordx4 v[216:217], off
	s_add_i32 m0, s14, 0x2000
	s_add_u32 s14, s18, 0x58080
	v_lshl_add_u64 v[216:217], v[218:219], 0, s[6:7]
	s_addc_u32 s15, s19, 0
	s_add_i32 s18, s42, s23
	global_load_lds_dwordx4 v[216:217], off
	v_lshl_add_u64 v[216:217], s[14:15], 0, v[130:131]
	s_mov_b32 m0, s18
	s_nop 0
	global_load_lds_dwordx4 v[216:217], off
	v_lshl_add_u64 v[216:217], s[14:15], 0, v[134:135]
	s_add_i32 m0, s18, 0x2000
	s_nop 0
	global_load_lds_dwordx4 v[216:217], off
	v_lshl_add_u64 v[216:217], v[220:221], 0, s[6:7]
	s_mov_b32 m0, s31
	s_nop 0
	global_load_lds_dwordx4 v[216:217], off
	v_lshl_add_u64 v[216:217], v[222:223], 0, s[6:7]
	s_mov_b32 m0, s33
	s_nop 0
	global_load_lds_dwordx4 v[216:217], off
	s_waitcnt vmcnt(8)
	s_waitcnt lgkmcnt(0)
	s_barrier
	v_mfma_f32_16x16x32_bf16 v[60:63], v[152:155], v[184:187], v[60:63]
	v_mfma_f32_16x16x32_bf16 v[56:59], v[160:163], v[184:187], v[56:59]
	v_mfma_f32_16x16x32_bf16 v[44:47], v[152:155], v[192:195], v[44:47]
	v_mfma_f32_16x16x32_bf16 v[40:43], v[160:163], v[192:195], v[40:43]
	v_mfma_f32_16x16x32_bf16 v[28:31], v[152:155], v[200:203], v[28:31]
	v_mfma_f32_16x16x32_bf16 v[24:27], v[160:163], v[200:203], v[24:27]
	v_mfma_f32_16x16x32_bf16 v[12:15], v[152:155], v[208:211], v[12:15]
	v_mfma_f32_16x16x32_bf16 v[8:11], v[160:163], v[208:211], v[8:11]
	v_mfma_f32_16x16x32_bf16 v[60:63], v[156:159], v[188:191], v[60:63]
	v_mfma_f32_16x16x32_bf16 v[56:59], v[164:167], v[188:191], v[56:59]
	v_mfma_f32_16x16x32_bf16 v[44:47], v[156:159], v[196:199], v[44:47]
	v_mfma_f32_16x16x32_bf16 v[40:43], v[164:167], v[196:199], v[40:43]
	v_mfma_f32_16x16x32_bf16 v[28:31], v[156:159], v[204:207], v[28:31]
	v_mfma_f32_16x16x32_bf16 v[24:27], v[164:167], v[204:207], v[24:27]
	v_mfma_f32_16x16x32_bf16 v[12:15], v[156:159], v[212:215], v[12:15]
	v_mfma_f32_16x16x32_bf16 v[8:11], v[164:167], v[212:215], v[8:11]
	v_mfma_f32_16x16x32_bf16 v[52:55], v[168:171], v[184:187], v[52:55]
	v_mfma_f32_16x16x32_bf16 v[48:51], v[176:179], v[184:187], v[48:51]
	v_mfma_f32_16x16x32_bf16 v[36:39], v[168:171], v[192:195], v[36:39]
	v_mfma_f32_16x16x32_bf16 v[32:35], v[176:179], v[192:195], v[32:35]
	v_mfma_f32_16x16x32_bf16 v[20:23], v[168:171], v[200:203], v[20:23]
	v_mfma_f32_16x16x32_bf16 v[16:19], v[176:179], v[200:203], v[16:19]
	v_mfma_f32_16x16x32_bf16 v[4:7], v[168:171], v[208:211], v[4:7]
	v_mfma_f32_16x16x32_bf16 v[0:3], v[176:179], v[208:211], v[0:3]
	v_mfma_f32_16x16x32_bf16 v[52:55], v[172:175], v[188:191], v[52:55]
	v_mfma_f32_16x16x32_bf16 v[48:51], v[180:183], v[188:191], v[48:51]
	v_mfma_f32_16x16x32_bf16 v[36:39], v[172:175], v[196:199], v[36:39]
	v_mfma_f32_16x16x32_bf16 v[32:35], v[180:183], v[196:199], v[32:35]
	v_mfma_f32_16x16x32_bf16 v[20:23], v[172:175], v[204:207], v[20:23]
	v_mfma_f32_16x16x32_bf16 v[16:19], v[180:183], v[204:207], v[16:19]
	v_mfma_f32_16x16x32_bf16 v[4:7], v[172:175], v[212:215], v[4:7]
	v_mfma_f32_16x16x32_bf16 v[0:3], v[180:183], v[212:215], v[0:3]
	s_barrier
	s_add_i32 s40, s40, 2
	s_add_u32 s13, s13, 0x100
	s_addc_u32 s39, s39, 0
	s_cmpk_lt_u32 s40, 0x56
	s_mov_b64 s[14:15], s[16:17]
; #define PG8_STAGE(bufoff, gbase, voff) do { _Pragma("unroll") for (int _i = 0; _i < 2; ++_i) \
;         __builtin_amdgcn_global_load_lds((const unsigned*)((const char*)(gbase) + (voff)[_i]), (LAS unsigned*)(lds + (bufoff) + ldsw + _i * 8192), 16, 0, 0); } while (0)
; #define PG8_LDA(dst, b, h) do { _Pragma("unroll") for (int m = 0; m < 4; ++m) _Pragma("unroll") for (int k = 0; k < 2; ++k) dst[m][k] = *(const LAS bf16x8*)(lds + PG8_SA(b, h) + aoff + m * 2048 + k * 1024); } while (0)
; #define PG8_LDB(dst, b, h) do { _Pragma("unroll") for (int n = 0; n < 2; ++n) _Pragma("unroll") for (int k = 0; k < 2; ++k) dst[n][k] = *(const LAS bf16x8*)(lds + PG8_SB(b, h) + boff + n * 2048 + k * 1024); } while (0)
; #define PG8_MMA(ai, bj, At, Bt) do { __builtin_amdgcn_s_setprio(1); _Pragma("unroll") for (int m = 0; m < 4; ++m) _Pragma("unroll") for (int n = 0; n < 2; ++n) _Pragma("unroll") for (int k = 0; k < 2; ++k) \
;         acc[ai][bj][m][n] = __builtin_amdgcn_mfma_f32_16x16x32_bf16(Bt[n][k], At[m][k], acc[ai][bj][m][n], 0, 0, 0); __builtin_amdgcn_s_setprio(0); } while (0)
; #define PG8_WAIT_V(n) asm volatile("s_waitcnt vmcnt(" #n ")" ::: "memory")
; #define PG8_WAIT_L(n) asm volatile("s_waitcnt lgkmcnt(" #n ")" ::: "memory")
; #define PG8_BAR __builtin_amdgcn_s_barrier()
; #define PG8_SCHED __builtin_amdgcn_sched_barrier(0)
; template <class Epi, class Sched, bool ALIGN_EPI = false, bool SP2 = false>
; __device__ __forceinline__ void gemm_phase(LAS unsigned char* lds, const Gemm g, const Sched& S, const Epi& E) {
;     ...
;         for (int t = 0; t < nt; t += 2) {
;             const bool last = (t == nt - 2);
;             const char* a1 = cA + (size_t)(t + 1) * kstep;
;             const char* a2 = last ? nA : cA + (size_t)(t + 2) * kstep; const char* b2 = last ? nB : cB + (size_t)(t + 2) * kstep;
;             const char* a3 = a2 + kstep; const char* b3 = b2 + kstep;
;             if (last && has_next) S.a_ready(nxt);
;             if constexpr (SP2) {
;             PG8_LDB(B0, 0, 0); PG8_LDB(B1, 0, 1); PG8_SCHED; PG8_LDA(At, 0, 0); PG8_STAGE(PG8_SA(1, 1), a1 + hstep, voffA);
;             PG8_WAIT_V(8); PG8_WAIT_L(0); PG8_BAR; PG8_MMA(0, 0, At, B0); PG8_MMA(0, 1, At, B1); PG8_BAR; PG8_SCHED;
;             PG8_LDA(At, 0, 1); PG8_STAGE(PG8_SB(0, 0), b2, voffB); PG8_STAGE(PG8_SB(0, 1), b2 + hstepB, voffB); PG8_STAGE(PG8_SA(0, 0), a2, voffA);
.LBB0_3002:
	ds_read_b128 v[152:155], v147
	ds_read_b128 v[156:159], v147 offset:1024
	ds_read_b128 v[160:163], v147 offset:2048
	ds_read_b128 v[164:167], v147 offset:3072
	ds_read_b128 v[168:171], v148
	ds_read_b128 v[172:175], v148 offset:1024
	ds_read_b128 v[176:179], v148 offset:2048
	ds_read_b128 v[180:183], v148 offset:3072
	s_add_u32 s16, s14, 0x100
	s_addc_u32 s17, s15, 0
	s_cmpk_eq_i32 s40, 0x54
	s_cselect_b32 s21, s11, s17
	s_cselect_b32 s20, s10, s16
	s_cselect_b32 s19, s3, s39
	s_cselect_b32 s18, s2, s13
	v_lshl_add_u64 v[216:217], s[14:15], 0, v[138:139]
	s_add_i32 m0, s24, 0xc000
	ds_read_b128 v[184:187], v149
	ds_read_b128 v[188:191], v149 offset:1024
	ds_read_b128 v[192:195], v149 offset:2048
	ds_read_b128 v[196:199], v149 offset:3072
	ds_read_b128 v[200:203], v149 offset:4096
	ds_read_b128 v[204:207], v149 offset:5120
	ds_read_b128 v[208:211], v149 offset:6144
	ds_read_b128 v[212:215], v149 offset:7168
	global_load_lds_dwordx4 v[216:217], off
	v_lshl_add_u64 v[216:217], s[14:15], 0, v[136:137]
	s_add_i32 m0, s24, 0xe000
	s_nop 0
	global_load_lds_dwordx4 v[216:217], off
	s_waitcnt vmcnt(8)
	s_waitcnt lgkmcnt(0)
	s_barrier
	v_mfma_f32_16x16x32_bf16 v[124:127], v[152:155], v[184:187], v[124:127]
	v_mfma_f32_16x16x32_bf16 v[120:123], v[160:163], v[184:187], v[120:123]
	v_mfma_f32_16x16x32_bf16 v[112:115], v[152:155], v[192:195], v[112:115]
	v_mfma_f32_16x16x32_bf16 v[104:107], v[160:163], v[192:195], v[104:107]
	v_mfma_f32_16x16x32_bf16 v[92:95], v[152:155], v[200:203], v[92:95]
	v_mfma_f32_16x16x32_bf16 v[88:91], v[160:163], v[200:203], v[88:91]
	v_mfma_f32_16x16x32_bf16 v[76:79], v[152:155], v[208:211], v[76:79]
	v_mfma_f32_16x16x32_bf16 v[72:75], v[160:163], v[208:211], v[72:75]
	v_mfma_f32_16x16x32_bf16 v[124:127], v[156:159], v[188:191], v[124:127]
	v_mfma_f32_16x16x32_bf16 v[120:123], v[164:167], v[188:191], v[120:123]
	v_mfma_f32_16x16x32_bf16 v[112:115], v[156:159], v[196:199], v[112:115]
	v_mfma_f32_16x16x32_bf16 v[104:107], v[164:167], v[196:199], v[104:107]
	v_mfma_f32_16x16x32_bf16 v[92:95], v[156:159], v[204:207], v[92:95]
	v_mfma_f32_16x16x32_bf16 v[88:91], v[164:167], v[204:207], v[88:91]
	v_mfma_f32_16x16x32_bf16 v[76:79], v[156:159], v[212:215], v[76:79]
	v_mfma_f32_16x16x32_bf16 v[72:75], v[164:167], v[212:215], v[72:75]
	v_mfma_f32_16x16x32_bf16 v[116:119], v[168:171], v[184:187], v[116:119]
	v_mfma_f32_16x16x32_bf16 v[108:111], v[176:179], v[184:187], v[108:111]
	v_mfma_f32_16x16x32_bf16 v[100:103], v[168:171], v[192:195], v[100:103]
	v_mfma_f32_16x16x32_bf16 v[96:99], v[176:179], v[192:195], v[96:99]
	v_mfma_f32_16x16x32_bf16 v[84:87], v[168:171], v[200:203], v[84:87]
	v_mfma_f32_16x16x32_bf16 v[80:83], v[176:179], v[200:203], v[80:83]
	v_mfma_f32_16x16x32_bf16 v[68:71], v[168:171], v[208:211], v[68:71]
	v_mfma_f32_16x16x32_bf16 v[64:67], v[176:179], v[208:211], v[64:67]
	v_mfma_f32_16x16x32_bf16 v[116:119], v[172:175], v[188:191], v[116:119]
	v_mfma_f32_16x16x32_bf16 v[108:111], v[180:183], v[188:191], v[108:111]
	v_mfma_f32_16x16x32_bf16 v[100:103], v[172:175], v[196:199], v[100:103]
	v_mfma_f32_16x16x32_bf16 v[96:99], v[180:183], v[196:199], v[96:99]
	v_mfma_f32_16x16x32_bf16 v[84:87], v[172:175], v[204:207], v[84:87]
	v_mfma_f32_16x16x32_bf16 v[80:83], v[180:183], v[204:207], v[80:83]
	v_mfma_f32_16x16x32_bf16 v[68:71], v[172:175], v[212:215], v[68:71]
	v_mfma_f32_16x16x32_bf16 v[64:67], v[180:183], v[212:215], v[64:67]
	s_barrier
	s_add_i32 s14, s34, s23
	v_lshl_add_u64 v[216:217], s[18:19], 0, v[130:131]
	s_mov_b32 m0, s14
	ds_read_b128 v[184:187], v149 offset:16384
	ds_read_b128 v[188:191], v149 offset:17408
	ds_read_b128 v[192:195], v149 offset:18432
	ds_read_b128 v[196:199], v149 offset:19456
	ds_read_b128 v[200:203], v149 offset:20480
	ds_read_b128 v[204:207], v149 offset:21504
	ds_read_b128 v[208:211], v149 offset:22528
	ds_read_b128 v[212:215], v149 offset:23552
	global_load_lds_dwordx4 v[216:217], off
	s_add_i32 m0, s14, 0x2000
	s_add_u32 s14, s18, 0x58000
	v_lshl_add_u64 v[218:219], s[18:19], 0, v[134:135]
	s_addc_u32 s15, s19, 0
	s_add_i32 s41, s35, s23
	global_load_lds_dwordx4 v[218:219], off
	v_lshl_add_u64 v[220:221], s[14:15], 0, v[130:131]
	s_mov_b32 m0, s41
	v_lshl_add_u64 v[222:223], s[20:21], 0, v[132:133]
	global_load_lds_dwordx4 v[220:221], off
	v_lshl_add_u64 v[220:221], s[14:15], 0, v[134:135]
	s_add_i32 m0, s41, 0x2000
	s_nop 0
	global_load_lds_dwordx4 v[220:221], off
	v_lshl_add_u64 v[220:221], s[20:21], 0, v[128:129]
	s_mov_b32 m0, s24
	s_nop 0
	global_load_lds_dwordx4 v[220:221], off
	s_mov_b32 m0, s25
	s_nop 0
	global_load_lds_dwordx4 v[222:223], off
	s_waitcnt vmcnt(8)
	s_waitcnt lgkmcnt(0)
	s_barrier
; #define PG8_STAGE(bufoff, gbase, voff) do { _Pragma("unroll") for (int _i = 0; _i < 2; ++_i) \
;         __builtin_amdgcn_global_load_lds((const unsigned*)((const char*)(gbase) + (voff)[_i]), (LAS unsigned*)(lds + (bufoff) + ldsw + _i * 8192), 16, 0, 0); } while (0)
; #define PG8_LDA(dst, b, h) do { _Pragma("unroll") for (int m = 0; m < 4; ++m) _Pragma("unroll") for (int k = 0; k < 2; ++k) dst[m][k] = *(const LAS bf16x8*)(lds + PG8_SA(b, h) + aoff + m * 2048 + k * 1024); } while (0)
; #define PG8_LDB(dst, b, h) do { _Pragma("unroll") for (int n = 0; n < 2; ++n) _Pragma("unroll") for (int k = 0; k < 2; ++k) dst[n][k] = *(const LAS bf16x8*)(lds + PG8_SB(b, h) + boff + n * 2048 + k * 1024); } while (0)
; #define PG8_MMA(ai, bj, At, Bt) do { __builtin_amdgcn_s_setprio(1); _Pragma("unroll") for (int m = 0; m < 4; ++m) _Pragma("unroll") for (int n = 0; n < 2; ++n) _Pragma("unroll") for (int k = 0; k < 2; ++k) \
;         acc[ai][bj][m][n] = __builtin_amdgcn_mfma_f32_16x16x32_bf16(Bt[n][k], At[m][k], acc[ai][bj][m][n], 0, 0, 0); __builtin_amdgcn_s_setprio(0); } while (0)
; #define PG8_WAIT_V(n) asm volatile("s_waitcnt vmcnt(" #n ")" ::: "memory")
; #define PG8_WAIT_L(n) asm volatile("s_waitcnt lgkmcnt(" #n ")" ::: "memory")
; #define PG8_BAR __builtin_amdgcn_s_barrier()
; #define PG8_SCHED __builtin_amdgcn_sched_barrier(0)
; template <class Epi, class Sched, bool ALIGN_EPI = false, bool SP2 = false>
; __device__ __forceinline__ void gemm_phase(LAS unsigned char* lds, const Gemm g, const Sched& S, const Epi& E) {
;     ...
;             PG8_WAIT_V(8); PG8_WAIT_L(0); PG8_BAR; PG8_MMA(1, 0, At, B0); PG8_MMA(1, 1, At, B1); PG8_BAR; PG8_SCHED;
;             PG8_LDB(B0, 1, 0); PG8_LDB(B1, 1, 1); PG8_SCHED; PG8_LDA(At, 1, 0); PG8_STAGE(PG8_SA(0, 1), a2 + hstep, voffA);
;             PG8_WAIT_V(8); PG8_WAIT_L(0); PG8_BAR; PG8_MMA(0, 0, At, B0); PG8_MMA(0, 1, At, B1); PG8_BAR; PG8_SCHED;
	v_mfma_f32_16x16x32_bf16 v[60:63], v[152:155], v[184:187], v[60:63]
	v_mfma_f32_16x16x32_bf16 v[56:59], v[160:163], v[184:187], v[56:59]
	v_mfma_f32_16x16x32_bf16 v[44:47], v[152:155], v[192:195], v[44:47]
	v_mfma_f32_16x16x32_bf16 v[40:43], v[160:163], v[192:195], v[40:43]
	v_mfma_f32_16x16x32_bf16 v[28:31], v[152:155], v[200:203], v[28:31]
	v_mfma_f32_16x16x32_bf16 v[24:27], v[160:163], v[200:203], v[24:27]
	v_mfma_f32_16x16x32_bf16 v[12:15], v[152:155], v[208:211], v[12:15]
	v_mfma_f32_16x16x32_bf16 v[8:11], v[160:163], v[208:211], v[8:11]
	v_mfma_f32_16x16x32_bf16 v[60:63], v[156:159], v[188:191], v[60:63]
	v_mfma_f32_16x16x32_bf16 v[56:59], v[164:167], v[188:191], v[56:59]
	v_mfma_f32_16x16x32_bf16 v[44:47], v[156:159], v[196:199], v[44:47]
	v_mfma_f32_16x16x32_bf16 v[40:43], v[164:167], v[196:199], v[40:43]
	v_mfma_f32_16x16x32_bf16 v[28:31], v[156:159], v[204:207], v[28:31]
	v_mfma_f32_16x16x32_bf16 v[24:27], v[164:167], v[204:207], v[24:27]
	v_mfma_f32_16x16x32_bf16 v[12:15], v[156:159], v[212:215], v[12:15]
	v_mfma_f32_16x16x32_bf16 v[8:11], v[164:167], v[212:215], v[8:11]
	v_mfma_f32_16x16x32_bf16 v[52:55], v[168:171], v[184:187], v[52:55]
	v_mfma_f32_16x16x32_bf16 v[48:51], v[176:179], v[184:187], v[48:51]
	v_mfma_f32_16x16x32_bf16 v[36:39], v[168:171], v[192:195], v[36:39]
	v_mfma_f32_16x16x32_bf16 v[32:35], v[176:179], v[192:195], v[32:35]
	v_mfma_f32_16x16x32_bf16 v[20:23], v[168:171], v[200:203], v[20:23]
	v_mfma_f32_16x16x32_bf16 v[16:19], v[176:179], v[200:203], v[16:19]
	v_mfma_f32_16x16x32_bf16 v[4:7], v[168:171], v[208:211], v[4:7]
	v_mfma_f32_16x16x32_bf16 v[0:3], v[176:179], v[208:211], v[0:3]
	v_mfma_f32_16x16x32_bf16 v[52:55], v[172:175], v[188:191], v[52:55]
	v_mfma_f32_16x16x32_bf16 v[48:51], v[180:183], v[188:191], v[48:51]
	v_mfma_f32_16x16x32_bf16 v[36:39], v[172:175], v[196:199], v[36:39]
	v_mfma_f32_16x16x32_bf16 v[32:35], v[180:183], v[196:199], v[32:35]
	v_mfma_f32_16x16x32_bf16 v[20:23], v[172:175], v[204:207], v[20:23]
	v_mfma_f32_16x16x32_bf16 v[16:19], v[180:183], v[204:207], v[16:19]
	v_mfma_f32_16x16x32_bf16 v[4:7], v[172:175], v[212:215], v[4:7]
	v_mfma_f32_16x16x32_bf16 v[0:3], v[180:183], v[212:215], v[0:3]
	s_barrier
	s_add_i32 s41, 0, 0x18000
	s_add_i32 s42, 0, 0x1c000
	v_add_u32_e32 v164, s41, v144
	v_add_u32_e32 v180, s42, v144
	ds_read_b128 v[152:155], v164
	ds_read_b128 v[156:159], v164 offset:1024
	ds_read_b128 v[160:163], v164 offset:2048
	ds_read_b128 v[164:167], v164 offset:3072
	ds_read_b128 v[168:171], v180
	ds_read_b128 v[172:175], v180 offset:1024
	ds_read_b128 v[176:179], v180 offset:2048
	ds_read_b128 v[180:183], v180 offset:3072
	s_add_u32 s14, s20, 0x160000
	s_addc_u32 s15, s21, 0
	s_mov_b32 m0, s26
	v_lshl_add_u64 v[224:225], s[14:15], 0, v[128:129]
	ds_read_b128 v[184:187], v149 offset:32768
	ds_read_b128 v[188:191], v149 offset:33792
	ds_read_b128 v[192:195], v149 offset:34816
	ds_read_b128 v[196:199], v149 offset:35840
	ds_read_b128 v[200:203], v149 offset:36864
	ds_read_b128 v[204:207], v149 offset:37888
	ds_read_b128 v[208:211], v149 offset:38912
	ds_read_b128 v[212:215], v149 offset:39936
	global_load_lds_dwordx4 v[224:225], off
	v_lshl_add_u64 v[224:225], s[14:15], 0, v[132:133]
	s_mov_b32 m0, s27
	s_nop 0
	global_load_lds_dwordx4 v[224:225], off
	s_waitcnt vmcnt(8)
	s_waitcnt lgkmcnt(0)
	s_barrier
	v_mfma_f32_16x16x32_bf16 v[124:127], v[152:155], v[184:187], v[124:127]
	v_mfma_f32_16x16x32_bf16 v[120:123], v[160:163], v[184:187], v[120:123]
	v_mfma_f32_16x16x32_bf16 v[112:115], v[152:155], v[192:195], v[112:115]
	v_mfma_f32_16x16x32_bf16 v[104:107], v[160:163], v[192:195], v[104:107]
	v_mfma_f32_16x16x32_bf16 v[92:95], v[152:155], v[200:203], v[92:95]
	v_mfma_f32_16x16x32_bf16 v[88:91], v[160:163], v[200:203], v[88:91]
	v_mfma_f32_16x16x32_bf16 v[76:79], v[152:155], v[208:211], v[76:79]
	v_mfma_f32_16x16x32_bf16 v[72:75], v[160:163], v[208:211], v[72:75]
	v_mfma_f32_16x16x32_bf16 v[124:127], v[156:159], v[188:191], v[124:127]
	v_mfma_f32_16x16x32_bf16 v[120:123], v[164:167], v[188:191], v[120:123]
	v_mfma_f32_16x16x32_bf16 v[112:115], v[156:159], v[196:199], v[112:115]
	v_mfma_f32_16x16x32_bf16 v[104:107], v[164:167], v[196:199], v[104:107]
	v_mfma_f32_16x16x32_bf16 v[92:95], v[156:159], v[204:207], v[92:95]
	v_mfma_f32_16x16x32_bf16 v[88:91], v[164:167], v[204:207], v[88:91]
	v_mfma_f32_16x16x32_bf16 v[76:79], v[156:159], v[212:215], v[76:79]
	v_mfma_f32_16x16x32_bf16 v[72:75], v[164:167], v[212:215], v[72:75]
	v_mfma_f32_16x16x32_bf16 v[116:119], v[168:171], v[184:187], v[116:119]
	v_mfma_f32_16x16x32_bf16 v[108:111], v[176:179], v[184:187], v[108:111]
	v_mfma_f32_16x16x32_bf16 v[100:103], v[168:171], v[192:195], v[100:103]
	v_mfma_f32_16x16x32_bf16 v[96:99], v[176:179], v[192:195], v[96:99]
	v_mfma_f32_16x16x32_bf16 v[84:87], v[168:171], v[200:203], v[84:87]
	v_mfma_f32_16x16x32_bf16 v[80:83], v[176:179], v[200:203], v[80:83]
	v_mfma_f32_16x16x32_bf16 v[68:71], v[168:171], v[208:211], v[68:71]
	v_mfma_f32_16x16x32_bf16 v[64:67], v[176:179], v[208:211], v[64:67]
	v_mfma_f32_16x16x32_bf16 v[116:119], v[172:175], v[188:191], v[116:119]
	v_mfma_f32_16x16x32_bf16 v[108:111], v[180:183], v[188:191], v[108:111]
	v_mfma_f32_16x16x32_bf16 v[100:103], v[172:175], v[196:199], v[100:103]
	v_mfma_f32_16x16x32_bf16 v[96:99], v[180:183], v[196:199], v[96:99]
	v_mfma_f32_16x16x32_bf16 v[84:87], v[172:175], v[204:207], v[84:87]
	v_mfma_f32_16x16x32_bf16 v[80:83], v[180:183], v[204:207], v[80:83]
	v_mfma_f32_16x16x32_bf16 v[68:71], v[172:175], v[212:215], v[68:71]
	v_mfma_f32_16x16x32_bf16 v[64:67], v[180:183], v[212:215], v[64:67]
	s_barrier
; #define PG8_STAGE(bufoff, gbase, voff) do { _Pragma("unroll") for (int _i = 0; _i < 2; ++_i) \
;         __builtin_amdgcn_global_load_lds((const unsigned*)((const char*)(gbase) + (voff)[_i]), (LAS unsigned*)(lds + (bufoff) + ldsw + _i * 8192), 16, 0, 0); } while (0)
; #define PG8_WAIT_V(n) asm volatile("s_waitcnt vmcnt(" #n ")" ::: "memory")
; #define PG8_WAIT_L(n) asm volatile("s_waitcnt lgkmcnt(" #n ")" ::: "memory")
; template <class Epi, class Sched, bool ALIGN_EPI = false, bool SP2 = false>
; __device__ __forceinline__ void gemm_phase(LAS unsigned char* lds, const Gemm g, const Sched& S, const Epi& E) {
;     ...
;             PG8_LDA(At, 1, 1); PG8_STAGE(PG8_SB(1, 0), b3, voffB); PG8_STAGE(PG8_SB(1, 1), b3 + hstepB, voffB); PG8_STAGE(PG8_SA(1, 0), a3, voffA);
;             PG8_WAIT_V(8); PG8_WAIT_L(0); PG8_BAR; PG8_MMA(1, 0, At, B0); PG8_MMA(1, 1, At, B1); PG8_BAR; PG8_SCHED;
;             } else {
;             PG8_LDB(B0, 0, 0); PG8_SCHED; PG8_LDA(At, 0, 0); PG8_STAGE(PG8_SA(1, 1), a1 + hstep, voffA);
;             PG8_WAIT_L(8); PG8_BAR; PG8_WAIT_L(0); PG8_MMA(0, 0, At, B0); PG8_BAR; PG8_SCHED;
;             PG8_LDB(B1, 0, 1); PG8_STAGE(PG8_SB(0, 0), b2, voffB);
;             PG8_BAR; PG8_WAIT_L(0); PG8_MMA(0, 1, At, B1); PG8_BAR;
;             PG8_LDA(At, 0, 1); PG8_STAGE(PG8_SA(0, 0), a2, voffA);
;             PG8_BAR; PG8_WAIT_L(0); PG8_MMA(1, 0, At, B0); PG8_BAR; PG8_SCHED;
;             PG8_STAGE(PG8_SB(0, 1), b2 + hstepB, voffB);
;             PG8_WAIT_V(6); PG8_BAR; PG8_MMA(1, 1, At, B1); PG8_BAR;
;             PG8_LDB(B0, 1, 0); PG8_SCHED; PG8_LDA(At, 1, 0); PG8_STAGE(PG8_SA(0, 1), a2 + hstep, voffA);
;             PG8_WAIT_L(8); PG8_BAR; PG8_WAIT_L(0); PG8_MMA(0, 0, At, B0); PG8_BAR; PG8_SCHED;
;             PG8_LDB(B1, 1, 1); PG8_STAGE(PG8_SB(1, 0), b3, voffB);
;             PG8_BAR; PG8_WAIT_L(0); PG8_MMA(0, 1, At, B1); PG8_BAR;
;             PG8_LDA(At, 1, 1); PG8_STAGE(PG8_SA(1, 0), a3, voffA);
;             PG8_BAR; PG8_WAIT_L(0); PG8_MMA(1, 0, At, B0); PG8_BAR; PG8_SCHED;
;             PG8_STAGE(PG8_SB(1, 1), b3 + hstepB, voffB);
;             PG8_WAIT_V(6); PG8_BAR; PG8_MMA(1, 1, At, B1); PG8_BAR;
;             }
;         }
;         if constexpr (ALIGN_EPI) { if (wr == 0) PG8_BAR; }
;         if constexpr (!Epi::AFTER_DRAIN) { E(acc, cur, wr, wc, fr, fq); S.done(cur); }
;         if (!has_next) break;
	s_add_i32 s14, s41, s23
	v_lshl_add_u64 v[216:217], v[216:217], 0, s[6:7]
	s_mov_b32 m0, s14
	ds_read_b128 v[184:187], v149 offset:49152
	ds_read_b128 v[188:191], v149 offset:50176
	ds_read_b128 v[192:195], v149 offset:51200
	ds_read_b128 v[196:199], v149 offset:52224
	ds_read_b128 v[200:203], v149 offset:53248
	ds_read_b128 v[204:207], v149 offset:54272
	ds_read_b128 v[208:211], v149 offset:55296
	ds_read_b128 v[212:215], v149 offset:56320
	global_load_lds_dwordx4 v[216:217], off
	s_add_i32 m0, s14, 0x2000
	s_add_u32 s14, s18, 0x58080
	v_lshl_add_u64 v[216:217], v[218:219], 0, s[6:7]
	s_addc_u32 s15, s19, 0
	s_add_i32 s18, s42, s23
	global_load_lds_dwordx4 v[216:217], off
	v_lshl_add_u64 v[216:217], s[14:15], 0, v[130:131]
	s_mov_b32 m0, s18
	s_nop 0
	global_load_lds_dwordx4 v[216:217], off
	v_lshl_add_u64 v[216:217], s[14:15], 0, v[134:135]
	s_add_i32 m0, s18, 0x2000
	s_nop 0
	global_load_lds_dwordx4 v[216:217], off
	v_lshl_add_u64 v[216:217], v[220:221], 0, s[6:7]
	s_mov_b32 m0, s31
	s_nop 0
	global_load_lds_dwordx4 v[216:217], off
	v_lshl_add_u64 v[216:217], v[222:223], 0, s[6:7]
	s_mov_b32 m0, s33
	s_nop 0
	global_load_lds_dwordx4 v[216:217], off
	s_waitcnt vmcnt(8)
	s_waitcnt lgkmcnt(0)
	s_barrier
	v_mfma_f32_16x16x32_bf16 v[60:63], v[152:155], v[184:187], v[60:63]
	v_mfma_f32_16x16x32_bf16 v[56:59], v[160:163], v[184:187], v[56:59]
	v_mfma_f32_16x16x32_bf16 v[44:47], v[152:155], v[192:195], v[44:47]
	v_mfma_f32_16x16x32_bf16 v[40:43], v[160:163], v[192:195], v[40:43]
	v_mfma_f32_16x16x32_bf16 v[28:31], v[152:155], v[200:203], v[28:31]
	v_mfma_f32_16x16x32_bf16 v[24:27], v[160:163], v[200:203], v[24:27]
	v_mfma_f32_16x16x32_bf16 v[12:15], v[152:155], v[208:211], v[12:15]
	v_mfma_f32_16x16x32_bf16 v[8:11], v[160:163], v[208:211], v[8:11]
	v_mfma_f32_16x16x32_bf16 v[60:63], v[156:159], v[188:191], v[60:63]
	v_mfma_f32_16x16x32_bf16 v[56:59], v[164:167], v[188:191], v[56:59]
	v_mfma_f32_16x16x32_bf16 v[44:47], v[156:159], v[196:199], v[44:47]
	v_mfma_f32_16x16x32_bf16 v[40:43], v[164:167], v[196:199], v[40:43]
	v_mfma_f32_16x16x32_bf16 v[28:31], v[156:159], v[204:207], v[28:31]
	v_mfma_f32_16x16x32_bf16 v[24:27], v[164:167], v[204:207], v[24:27]
	v_mfma_f32_16x16x32_bf16 v[12:15], v[156:159], v[212:215], v[12:15]
	v_mfma_f32_16x16x32_bf16 v[8:11], v[164:167], v[212:215], v[8:11]
	v_mfma_f32_16x16x32_bf16 v[52:55], v[168:171], v[184:187], v[52:55]
	v_mfma_f32_16x16x32_bf16 v[48:51], v[176:179], v[184:187], v[48:51]
	v_mfma_f32_16x16x32_bf16 v[36:39], v[168:171], v[192:195], v[36:39]
	v_mfma_f32_16x16x32_bf16 v[32:35], v[176:179], v[192:195], v[32:35]
	v_mfma_f32_16x16x32_bf16 v[20:23], v[168:171], v[200:203], v[20:23]
	v_mfma_f32_16x16x32_bf16 v[16:19], v[176:179], v[200:203], v[16:19]
	v_mfma_f32_16x16x32_bf16 v[4:7], v[168:171], v[208:211], v[4:7]
	v_mfma_f32_16x16x32_bf16 v[0:3], v[176:179], v[208:211], v[0:3]
	v_mfma_f32_16x16x32_bf16 v[52:55], v[172:175], v[188:191], v[52:55]
	v_mfma_f32_16x16x32_bf16 v[48:51], v[180:183], v[188:191], v[48:51]
	v_mfma_f32_16x16x32_bf16 v[36:39], v[172:175], v[196:199], v[36:39]
	v_mfma_f32_16x16x32_bf16 v[32:35], v[180:183], v[196:199], v[32:35]
	v_mfma_f32_16x16x32_bf16 v[20:23], v[172:175], v[204:207], v[20:23]
	v_mfma_f32_16x16x32_bf16 v[16:19], v[180:183], v[204:207], v[16:19]
	v_mfma_f32_16x16x32_bf16 v[4:7], v[172:175], v[212:215], v[4:7]
	v_mfma_f32_16x16x32_bf16 v[0:3], v[180:183], v[212:215], v[0:3]
	s_barrier
	s_add_i32 s40, s40, 2
	s_add_u32 s13, s13, 0x100
	s_addc_u32 s39, s39, 0
	s_cmpk_lt_u32 s40, 0x56
	s_mov_b64 s[14:15], s[16:17]
	s_cbranch_scc1 .LBB0_3002
	s_setprio 0
	s_andn2_b64 vcc, exec, s[8:9]
	s_cbranch_vccnz .LBB0_3005
	s_barrier
